# flat_* to global_* for all global-memory accesses (no other change)
# speedup vs baseline: 1.0191x; 1.0191x over previous
; __device__ __forceinline__ int lane_asm() { int l; asm volatile("v_mbcnt_lo_u32_b32 %0, -1, 0\n\tv_mbcnt_hi_u32_b32 %0, -1, %0" : "=v"(l)); return l; }
; #define LAS __attribute__((address_space(3)))
; #define INP(k) ((const float*)ldptr(L, (k)))
; __device__ __forceinline__ void ssm_gen(int g, LAS float* S, const float* a_re, const float* a_im, const float* log_dt, const float* b_re, const float* b_im,
;                                         const float* c_re, const float* c_im, bf16* BY, bf16* BE, float* A16, int tid) {
;     ...
;     const float dt = expf(log_dt[g]);
;     for (int idx = tid; idx < 17 * 64; idx += NTHR) { const int j = idx >> 6, p = idx & 63;
;         const float re = fminf(a_re[g * 64 + p], -1e-4f), im = a_im[g * 64 + p];
;         const float mag = expf((float)j * re * dt), ang = (float)j * im * dt;
;         ljr[idx] = mag * cosf(ang); lji[idx] = mag * sinf(ang); }
; __global__ void __launch_bounds__(NTHR, 2) mk_fwd(Args args) {
;     ...
;     if (IN(0)) { const int lane = lane_asm(), tid = wave * 64 + lane; (void)tid;
;         if (bx < 64) ssm_gen(bx, (LAS float*)L, INP(18), INP(19), INP(20), INP(21), INP(22),
;                              INP(23), INP(24), p_BY, p_BE, p_A16, tid);
.LBB0_21:
	s_or_b64 exec, exec, s[4:5]
	s_lshr_b32 s93, s92, 6
	s_lshl_b32 s33, s2, 3
	s_add_i32 s72, s93, s33
	s_lshl_b32 s80, s70, 3
	s_cmp_lt_i32 s68, 1
	s_cselect_b64 s[0:1], -1, 0
	s_cmp_gt_i32 s69, 0
	s_cselect_b64 s[4:5], -1, 0
	s_and_b64 s[34:35], s[0:1], s[4:5]
	s_andn2_b64 vcc, exec, s[34:35]
	s_cbranch_vccnz .LBB0_212
	s_and_b32 s0, s92, 0xffffffc0
	v_mbcnt_lo_u32_b32 v88, -1, 0
	v_mbcnt_hi_u32_b32 v88, -1, v88
	s_cmp_gt_i32 s2, 63
	v_add_u32_e32 v0, s0, v88
	s_cbranch_scc1 .LBB0_74
	s_add_i32 s0, 0, 0x200a0
	v_mov_b32_e32 v1, s0
	ds_read_b128 v[2:5], v1
	s_ashr_i32 s3, s2, 31
	s_add_i32 s4, 0, 0x20090
	s_add_i32 s5, 0, 0x200b0
	s_add_i32 s6, 0, 0x200c0
	s_waitcnt lgkmcnt(0)
	v_readfirstlane_b32 s7, v2
	s_add_i32 s9, 0, 0x20118
	s_lshl_b64 s[0:1], s[2:3], 2
	v_readfirstlane_b32 s8, v3
	s_add_u32 s0, s7, s0
	s_addc_u32 s1, s8, s1
	v_mov_b64_e32 v[2:3], s[0:1]
	global_load_dword v16, v[2:3], off
	v_mov_b32_e32 v1, s4
	v_mov_b32_e32 v2, s5
	v_mov_b32_e32 v3, s6
	v_mov_b32_e32 v14, s9
	ds_read_b128 v[6:9], v1
	ds_read_b128 v[10:13], v2
	ds_read_b64 v[2:3], v3
	ds_read_b64 v[14:15], v14
	s_mov_b32 s24, 0x3fb8aa3b
	v_readfirstlane_b32 s22, v4
	v_readfirstlane_b32 s23, v5
	s_waitcnt lgkmcnt(0)
	v_readfirstlane_b32 s31, v2
	s_mov_b32 s29, 0xc2ce8ed0
	s_mov_b32 s30, 0x42b17218
	v_mov_b32_e32 v1, 0x7f800000
	s_movk_i32 s0, 0x440
	v_readfirstlane_b32 s12, v6
	v_readfirstlane_b32 s13, v7
	v_readfirstlane_b32 s14, v8
	v_readfirstlane_b32 s15, v9
	v_readfirstlane_b32 s25, v10
	v_readfirstlane_b32 s26, v11
	v_readfirstlane_b32 s27, v12
	v_readfirstlane_b32 s28, v13
	v_readfirstlane_b32 s36, v3
	v_readfirstlane_b32 s10, v14
	v_readfirstlane_b32 s11, v15
	s_waitcnt vmcnt(0)
	v_mul_f32_e32 v2, 0x3fb8aa3b, v16
	v_fma_f32 v4, v16, s24, -v2
	v_rndne_f32_e32 v5, v2
	v_fmac_f32_e32 v4, 0x32a5705f, v16
	v_sub_f32_e32 v2, v2, v5
	v_add_f32_e32 v2, v2, v4
	v_cvt_i32_f32_e32 v5, v5
	v_exp_f32_e32 v2, v2
	v_cmp_ngt_f32_e32 vcc, s29, v16
	v_ldexp_f32 v2, v2, v5
	s_nop 0
	v_cndmask_b32_e32 v2, 0, v2, vcc
	v_cmp_nlt_f32_e32 vcc, s30, v16
	s_nop 1
	v_cndmask_b32_e32 v8, v1, v2, vcc
	v_cmp_gt_i32_e32 vcc, s0, v0
	s_and_saveexec_b64 s[16:17], vcc
	s_cbranch_execz .LBB0_34
	s_lshl_b32 s0, s2, 6
	v_and_or_b32 v2, v88, 63, s0
	v_ashrrev_i32_e32 v3, 31, v2
	s_lshl_b32 s0, s93, 8
	v_lshlrev_b64 v[4:5], 2, v[2:3]
	s_add_i32 s0, s0, 0
	v_lshl_add_u64 v[2:3], s[12:13], 0, v[4:5]
	v_lshl_add_u64 v[4:5], s[14:15], 0, v[4:5]
	v_lshl_add_u32 v9, v88, 2, s0
	s_mov_b64 s[18:19], 0
	s_brev_b32 s37, 18
	s_mov_b32 s38, 0xfe5163ab
	v_mov_b32_e32 v7, 0
	s_mov_b32 s39, 0x3c439041
	s_mov_b32 s40, 0xdb629599
	s_mov_b32 s41, 0xf534ddc0
	s_mov_b32 s42, 0xfc2757d1
	s_mov_b32 s43, 0x4e441529
	s_mov_b32 s44, 0xa2f9836e
	s_mov_b32 s45, 0x3fc90fda
	s_mov_b32 s46, 0x3f22f983
	s_mov_b32 s47, 0xbfc90fda
	v_mov_b32_e32 v10, 0x3c0881c4
	v_mov_b32_e32 v11, 0xbab64f3b
	s_brev_b32 s48, 1
	s_movk_i32 s49, 0x1f8
	s_movk_i32 s50, 0x23f
	v_not_b32_e32 v12, 63
	v_not_b32_e32 v13, 31
	v_mov_b32_e32 v14, 0x7fc00000
	v_mov_b32_e32 v15, v0
	s_branch .LBB0_26

; __device__ __forceinline__ void ssm_gen(int g, LAS float* S, const float* a_re, const float* a_im, const float* log_dt, const float* b_re, const float* b_im,
;                                         const float* c_re, const float* c_im, bf16* BY, bf16* BE, float* A16, int tid) {
;     ...
;     for (int idx = tid; idx < 17 * 64; idx += NTHR) { const int j = idx >> 6, p = idx & 63;
;         const float re = fminf(a_re[g * 64 + p], -1e-4f), im = a_im[g * 64 + p];
;         const float mag = expf((float)j * re * dt), ang = (float)j * im * dt;
;         ljr[idx] = mag * cosf(ang); lji[idx] = mag * sinf(ang); }
.LBB0_26:
	global_load_dword v6, v[4:5], off
	global_load_dword v20, v[2:3], off
	v_ashrrev_i32_e32 v16, 6, v15
	v_cvt_f32_i32_e32 v21, v16
	s_waitcnt vmcnt(0) lgkmcnt(0)
	v_mul_f32_e32 v6, v6, v21
	v_mul_f32_e32 v16, v8, v6
	v_and_b32_e32 v17, 0x7fffffff, v16
	v_lshrrev_b32_e32 v6, 23, v17
	v_and_b32_e32 v18, 0x7fffff, v17
	v_cmp_nlt_f32_e64 s[8:9], |v16|, s37
	v_add_u32_e32 v19, 0xffffff88, v6
	v_or_b32_e32 v18, 0x800000, v18
	s_and_saveexec_b64 s[0:1], s[8:9]
	s_xor_b64 s[20:21], exec, s[0:1]
	s_cbranch_execz .LBB0_28
	v_cmp_lt_u32_e32 vcc, 63, v19
	s_nop 1
	v_cndmask_b32_e32 v6, 0, v12, vcc
	v_add_u32_e32 v6, v6, v19
	v_cmp_lt_u32_e64 s[0:1], 31, v6
	s_nop 1
	v_cndmask_b32_e64 v22, 0, v13, s[0:1]
	v_add_u32_e32 v6, v22, v6
	v_cmp_lt_u32_e64 s[4:5], 31, v6
	s_nop 1
	v_cndmask_b32_e64 v22, 0, v13, s[4:5]
	v_add_u32_e32 v36, v22, v6
	v_mad_u64_u32 v[22:23], s[6:7], v18, s38, 0
	v_mov_b32_e32 v6, v23
	v_mad_u64_u32 v[24:25], s[6:7], v18, s39, v[6:7]
	v_mov_b32_e32 v6, v25
	v_mad_u64_u32 v[26:27], s[6:7], v18, s40, v[6:7]
	v_mov_b32_e32 v6, v27
	v_mad_u64_u32 v[28:29], s[6:7], v18, s41, v[6:7]
	v_mov_b32_e32 v6, v29
	v_mad_u64_u32 v[30:31], s[6:7], v18, s42, v[6:7]
	v_mov_b32_e32 v6, v31
	v_mad_u64_u32 v[32:33], s[6:7], v18, s43, v[6:7]
	v_mov_b32_e32 v6, v33
	v_mad_u64_u32 v[34:35], s[6:7], v18, s44, v[6:7]
	v_cndmask_b32_e32 v23, v32, v28, vcc
	v_cndmask_b32_e32 v6, v34, v30, vcc
	v_cndmask_b32_e32 v27, v35, v32, vcc
	v_cndmask_b32_e64 v25, v6, v23, s[0:1]
	v_cndmask_b32_e64 v6, v27, v6, s[0:1]
	v_cndmask_b32_e32 v27, v30, v26, vcc
	v_cndmask_b32_e64 v23, v23, v27, s[0:1]
	v_cndmask_b32_e32 v24, v28, v24, vcc
	v_cndmask_b32_e64 v6, v6, v25, s[4:5]
	v_cndmask_b32_e64 v25, v25, v23, s[4:5]
	v_sub_u32_e32 v29, 32, v36
	v_cndmask_b32_e64 v27, v27, v24, s[0:1]
	v_alignbit_b32 v30, v6, v25, v29
	v_cmp_eq_u32_e64 s[6:7], 0, v36
	v_cndmask_b32_e64 v23, v23, v27, s[4:5]
	v_cndmask_b32_e32 v22, v26, v22, vcc
	v_cndmask_b32_e64 v6, v30, v6, s[6:7]
	v_alignbit_b32 v28, v25, v23, v29
	v_cndmask_b32_e64 v22, v24, v22, s[0:1]
	v_cndmask_b32_e64 v25, v28, v25, s[6:7]
	v_bfe_u32 v31, v6, 29, 1
	v_cndmask_b32_e64 v22, v27, v22, s[4:5]
	v_alignbit_b32 v28, v6, v25, 30
	v_sub_u32_e32 v32, 0, v31
	v_alignbit_b32 v24, v23, v22, v29
	v_xor_b32_e32 v28, v28, v32
	v_cndmask_b32_e64 v23, v24, v23, s[6:7]
	v_alignbit_b32 v24, v25, v23, 30
	v_ffbh_u32_e32 v25, v28
	v_min_u32_e32 v25, 32, v25
	v_alignbit_b32 v22, v23, v22, 30
	v_xor_b32_e32 v24, v24, v32
	v_sub_u32_e32 v26, 31, v25
	v_xor_b32_e32 v22, v22, v32
	v_alignbit_b32 v27, v28, v24, v26
	v_alignbit_b32 v22, v24, v22, v26
	v_alignbit_b32 v23, v27, v22, 9
	v_ffbh_u32_e32 v24, v23
	v_min_u32_e32 v24, 32, v24
	v_lshrrev_b32_e32 v30, 29, v6
	v_not_b32_e32 v26, v24
	v_alignbit_b32 v22, v23, v22, v26
	v_lshlrev_b32_e32 v23, 31, v30
	v_or_b32_e32 v26, 0x33000000, v23
	v_add_lshl_u32 v24, v24, v25, 23
	v_lshrrev_b32_e32 v22, 9, v22
	v_sub_u32_e32 v24, v26, v24
	v_or_b32_e32 v23, 0.5, v23
	v_lshlrev_b32_e32 v25, 23, v25
	v_or_b32_e32 v22, v24, v22
	v_lshrrev_b32_e32 v24, 9, v27
	v_sub_u32_e32 v23, v23, v25
	v_or_b32_e32 v23, v24, v23
	v_mul_f32_e32 v24, 0x3fc90fda, v23
	v_fma_f32 v25, v23, s45, -v24
	v_fmac_f32_e32 v25, 0x33a22168, v23
	v_fmac_f32_e32 v25, 0x3fc90fda, v22
	v_lshrrev_b32_e32 v6, 30, v6
	v_add_f32_e32 v23, v24, v25
	v_add_u32_e32 v22, v31, v6

; __device__ __forceinline__ void ssm_gen(int g, LAS float* S, const float* a_re, const float* a_im, const float* log_dt, const float* b_re, const float* b_im,
;                                         const float* c_re, const float* c_im, bf16* BY, bf16* BE, float* A16, int tid) {
;     ...
;     for (int idx = tid; idx < 1024; idx += NTHR) { const int p = idx >> 4;
;         const float re = fminf(a_re[g * 64 + p], -1e-4f), im = a_im[g * 64 + p];
;         const float mag = expf(re * dt), ang = im * dt; const float xr = mag * cosf(ang) - 1.0f, xi = mag * sinf(ang);
;         const float den = 1.0f / (re * re + im * im); const float qr = (xr * re + xi * im) * den, qi = (xi * re - xr * im) * den;
;         const float br = b_re[(size_t)g * 1024 + idx], bi = b_im[(size_t)g * 1024 + idx];
;         bbr[idx] = qr * br - qi * bi; bbi[idx] = qr * bi + qi * br;
;         ccr[idx] = c_re[(size_t)g * 1024 + idx]; cci[idx] = c_im[(size_t)g * 1024 + idx]; }
.LBB0_36:
	s_or_b64 exec, exec, s[0:1]
	v_lshl_add_u64 v[26:27], s[20:21], 0, v[2:3]
	v_lshl_add_u64 v[24:25], s[22:23], 0, v[2:3]
	global_load_dword v22, v[26:27], off
	global_load_dword v28, v[24:25], off
	v_max_f32_e32 v18, v18, v18
	v_mul_f32_e32 v24, v19, v19
	v_mul_f32_e32 v27, v4, v4
	v_and_b32_e32 v29, 1, v23
	v_lshlrev_b32_e32 v23, 30, v23
	v_mul_f32_e32 v30, v15, v15
	v_min_f32_e32 v18, 0xb8d1b717, v18
	v_fmamk_f32 v31, v24, 0xb94c1982, v7
	v_fmamk_f32 v32, v24, 0x37d75334, v9
	v_xor_b32_e32 v17, v17, v16
	v_fmamk_f32 v33, v27, 0xb94c1982, v7
	v_fmamk_f32 v34, v27, 0x37d75334, v9
	v_and_b32_e32 v23, 0x80000000, v23
	v_mul_f32_e32 v35, v8, v18
	v_fmaak_f32 v31, v24, v31, 0xbe2aaa9d
	v_fmaak_f32 v32, v24, v32, 0x3d2aabf7
	v_fmac_f32_e32 v30, v18, v18
	v_and_b32_e32 v25, 1, v20
	v_fmaak_f32 v33, v27, v33, 0xbe2aaa9d
	v_fmaak_f32 v34, v27, v34, 0x3d2aabf7
	v_xor_b32_e32 v17, v17, v23
	v_mul_f32_e32 v23, 0x3fb8aa3b, v35
	v_mul_f32_e32 v31, v24, v31
	v_fmaak_f32 v32, v24, v32, 0xbf000004
	v_div_scale_f32 v36, s[0:1], v30, v30, 1.0
	v_mul_f32_e32 v33, v27, v33
	v_fmaak_f32 v34, v27, v34, 0xbf000004
	v_fma_f32 v38, v35, s45, -v23
	v_rndne_f32_e32 v39, v23
	v_fmac_f32_e32 v19, v19, v31
	v_fma_f32 v24, v24, v32, 1.0
	v_cmp_eq_u32_e64 s[0:1], 0, v25
	v_fmac_f32_e32 v4, v4, v33
	v_fma_f32 v27, v27, v34, 1.0
	v_rcp_f32_e32 v31, v36
	v_fmac_f32_e32 v38, 0x32a5705f, v35
	v_sub_f32_e32 v23, v23, v39
	v_cndmask_b32_e64 v19, -v19, v24, s[0:1]
	v_cmp_eq_u32_e64 s[0:1], 0, v29
	v_add_f32_e32 v23, v23, v38
	v_lshlrev_b32_e32 v26, 30, v20
	v_cndmask_b32_e64 v4, v27, v4, s[0:1]
	v_cvt_i32_f32_e32 v32, v39
	v_xor_b32_e32 v4, v17, v4
	v_exp_f32_e32 v17, v23
	v_bitop3_b32 v19, v26, v19, s48 bitop3:0x6c
	v_cmp_class_f32_e64 s[0:1], v16, s49
	v_div_scale_f32 v37, vcc, 1.0, v30, 1.0
	s_nop 0
	v_cndmask_b32_e64 v16, v13, v19, s[0:1]
	v_fma_f32 v19, -v36, v31, 1.0
	v_fmac_f32_e32 v31, v19, v31
	v_cndmask_b32_e64 v4, v13, v4, s[0:1]
	v_mul_f32_e32 v19, v37, v31
	v_ldexp_f32 v17, v17, v32
	v_cmp_ngt_f32_e64 s[0:1], s46, v35
	v_fma_f32 v23, -v36, v19, v37
	v_fmac_f32_e32 v19, v23, v31
	v_cndmask_b32_e64 v17, 0, v17, s[0:1]
	v_cmp_nlt_f32_e64 s[0:1], s47, v35
	v_fma_f32 v23, -v36, v19, v37
	v_lshl_add_u64 v[20:21], s[18:19], 0, v[2:3]
	v_cndmask_b32_e64 v17, v12, v17, s[0:1]
	v_fma_f32 v16, v17, v16, -1.0
	v_mul_f32_e32 v4, v17, v4
	v_div_fmas_f32 v17, v23, v31, v19
	v_mul_f32_e32 v19, v15, v4
	v_mul_f32_e32 v15, v15, v16
	v_div_fixup_f32 v17, v17, v30, 1.0
	v_fma_f32 v4, v18, v4, -v15
	v_fmac_f32_e32 v19, v18, v16
	v_mul_f32_e32 v4, v17, v4
	v_mul_f32_e32 v15, v17, v19
	v_cmp_lt_i32_e32 vcc, s50, v14
	s_waitcnt vmcnt(0) lgkmcnt(0)
	v_mul_f32_e32 v16, v22, v4
	v_mul_f32_e32 v4, v28, v4
	v_fma_f32 v16, v28, v15, -v16
	v_fmac_f32_e32 v4, v22, v15
	ds_write2st64_b32 v6, v16, v4 offset1:16
	global_load_dword v4, v[20:21], off
	v_lshl_add_u64 v[16:17], s[16:17], 0, v[2:3]
	s_add_u32 s16, s16, 0x800
	s_addc_u32 s17, s17, 0
	s_add_u32 s18, s18, 0x800
	s_addc_u32 s19, s19, 0
	s_add_u32 s20, s20, 0x800
	s_addc_u32 s21, s21, 0
	s_add_u32 s22, s22, 0x800
	v_add_u32_e32 v15, 0x200, v14
	s_addc_u32 s23, s23, 0
	s_or_b64 s[24:25], vcc, s[24:25]
	v_mov_b32_e32 v14, v15
	s_waitcnt vmcnt(0) lgkmcnt(0)
	ds_write_b32 v6, v4 offset:8192
	global_load_dword v4, v[16:17], off
	s_waitcnt vmcnt(0) lgkmcnt(0)
	ds_write_b32 v6, v4 offset:12288
	v_add_u32_e32 v6, 0x800, v6
	s_andn2_b64 exec, exec, s[24:25]
	s_cbranch_execz .LBB0_45
.LBB0_37:
	v_ashrrev_i32_e32 v4, 4, v14
	v_add_u32_e32 v16, s30, v4
	v_ashrrev_i32_e32 v17, 31, v16
	v_lshlrev_b64 v[16:17], 2, v[16:17]
	v_lshl_add_u64 v[18:19], s[14:15], 0, v[16:17]
	global_load_dword v15, v[18:19], off
	v_lshl_add_u64 v[16:17], s[12:13], 0, v[16:17]
	global_load_dword v18, v[16:17], off
	s_waitcnt vmcnt(0) lgkmcnt(0)
	v_mul_f32_e32 v16, v8, v15
	v_and_b32_e32 v17, 0x7fffffff, v16
	v_lshrrev_b32_e32 v4, 23, v17
	v_and_b32_e32 v19, 0x7fffff, v17
	v_cmp_nlt_f32_e64 s[26:27], |v16|, s3
	v_add_u32_e32 v22, 0xffffff88, v4
	v_or_b32_e32 v21, 0x800000, v19
	s_and_saveexec_b64 s[0:1], s[26:27]
	s_xor_b64 s[28:29], exec, s[0:1]
	s_cbranch_execz .LBB0_39
	v_cmp_lt_u32_e32 vcc, 63, v22
	v_mad_u64_u32 v[24:25], s[6:7], v21, s31, 0
	s_nop 0
	v_cndmask_b32_e32 v4, 0, v10, vcc
	v_add_u32_e32 v4, v4, v22
	v_cmp_lt_u32_e64 s[0:1], 31, v4
	s_nop 1
	v_cndmask_b32_e64 v19, 0, v11, s[0:1]
	v_add_u32_e32 v4, v19, v4
	v_cmp_lt_u32_e64 s[4:5], 31, v4
	s_nop 1
	v_cndmask_b32_e64 v19, 0, v11, s[4:5]
	v_add_u32_e32 v19, v19, v4
	v_mov_b32_e32 v4, v25
	v_mad_u64_u32 v[26:27], s[6:7], v21, s36, v[4:5]
	v_mov_b32_e32 v4, v27
	v_mad_u64_u32 v[28:29], s[6:7], v21, s37, v[4:5]
	v_mov_b32_e32 v4, v29
	v_mad_u64_u32 v[30:31], s[6:7], v21, s38, v[4:5]
	v_mov_b32_e32 v4, v31
	v_mad_u64_u32 v[32:33], s[6:7], v21, s39, v[4:5]
	v_mov_b32_e32 v4, v33
	v_mad_u64_u32 v[34:35], s[6:7], v21, s40, v[4:5]
	v_mov_b32_e32 v4, v35
	v_mad_u64_u32 v[36:37], s[6:7], v21, s41, v[4:5]
	v_cndmask_b32_e32 v20, v34, v30, vcc
	v_cndmask_b32_e32 v4, v36, v32, vcc
	v_cndmask_b32_e32 v25, v37, v34, vcc
	v_cndmask_b32_e64 v23, v4, v20, s[0:1]
	v_cndmask_b32_e64 v4, v25, v4, s[0:1]
	v_cndmask_b32_e32 v25, v32, v28, vcc
	v_cndmask_b32_e64 v20, v20, v25, s[0:1]
	v_sub_u32_e32 v27, 32, v19
	v_cmp_eq_u32_e64 s[6:7], 0, v19
	v_cndmask_b32_e32 v19, v30, v26, vcc
	v_cndmask_b32_e64 v4, v4, v23, s[4:5]
	v_cndmask_b32_e64 v23, v23, v20, s[4:5]
	v_cndmask_b32_e64 v25, v25, v19, s[0:1]
	v_alignbit_b32 v29, v4, v23, v27
	v_cndmask_b32_e64 v20, v20, v25, s[4:5]
	v_cndmask_b32_e64 v4, v29, v4, s[6:7]
	v_alignbit_b32 v26, v23, v20, v27
	v_cndmask_b32_e32 v24, v28, v24, vcc
	v_cndmask_b32_e64 v23, v26, v23, s[6:7]
	v_bfe_u32 v30, v4, 29, 1
	v_cndmask_b32_e64 v19, v19, v24, s[0:1]
	v_alignbit_b32 v26, v4, v23, 30
	v_sub_u32_e32 v31, 0, v30
	v_cndmask_b32_e64 v19, v25, v19, s[4:5]
	v_xor_b32_e32 v26, v26, v31
	v_alignbit_b32 v24, v20, v19, v27
	v_cndmask_b32_e64 v20, v24, v20, s[6:7]
	v_ffbh_u32_e32 v24, v26
	v_alignbit_b32 v23, v23, v20, 30
	v_min_u32_e32 v24, 32, v24
	v_alignbit_b32 v19, v20, v19, 30
	v_xor_b32_e32 v23, v23, v31
	v_sub_u32_e32 v25, 31, v24
	v_xor_b32_e32 v19, v19, v31
	v_alignbit_b32 v26, v26, v23, v25
	v_alignbit_b32 v19, v23, v19, v25
	v_alignbit_b32 v20, v26, v19, 9
	v_ffbh_u32_e32 v23, v20
	v_min_u32_e32 v23, 32, v23
	v_lshrrev_b32_e32 v29, 29, v4
	v_not_b32_e32 v25, v23
	v_alignbit_b32 v19, v20, v19, v25
	v_lshlrev_b32_e32 v20, 31, v29
	v_or_b32_e32 v25, 0x33000000, v20
	v_add_lshl_u32 v23, v23, v24, 23
	v_lshrrev_b32_e32 v19, 9, v19
	v_sub_u32_e32 v23, v25, v23
	v_or_b32_e32 v20, 0.5, v20
	v_lshlrev_b32_e32 v24, 23, v24
	v_or_b32_e32 v19, v23, v19
	v_lshrrev_b32_e32 v23, 9, v26
	v_sub_u32_e32 v20, v20, v24
	v_or_b32_e32 v20, v23, v20
	v_mul_f32_e32 v23, 0x3fc90fda, v20
	v_fma_f32 v24, v20, s42, -v23
	v_fmac_f32_e32 v24, 0x33a22168, v20
	v_fmac_f32_e32 v24, 0x3fc90fda, v19
	v_lshrrev_b32_e32 v4, 30, v4
	v_add_f32_e32 v19, v23, v24
	v_add_u32_e32 v20, v30, v4

; __device__ __forceinline__ void ssm_gen(int g, LAS float* S, const float* a_re, const float* a_im, const float* log_dt, const float* b_re, const float* b_im,
;                                         const float* c_re, const float* c_im, bf16* BY, bf16* BE, float* A16, int tid) {
;     ...
;     __syncthreads();
;     if (tid < 64) { A16[(g * 64 + tid) * 2] = ljr[16 * 64 + tid]; A16[(g * 64 + tid) * 2 + 1] = lji[16 * 64 + tid]; }
.LBB0_45:
	s_or_b64 exec, exec, s[8:9]
	v_cmp_gt_i32_e32 vcc, 64, v0
	s_waitcnt lgkmcnt(0)
	s_barrier
	s_and_saveexec_b64 s[0:1], vcc
	s_cbranch_execz .LBB0_47
	v_lshl_add_u32 v6, v0, 2, 0
	s_lshl_b32 s3, s2, 7
	ds_read_b32 v7, v6 offset:4096
	v_lshl_add_u32 v2, v0, 1, s3
	v_ashrrev_i32_e32 v3, 31, v2
	v_lshl_add_u64 v[2:3], v[2:3], 2, s[10:11]
	v_add_co_u32_e32 v4, vcc, 0x500000, v2
	s_mov_b64 s[4:5], 0x500000
	s_nop 0
	v_addc_co_u32_e32 v5, vcc, 0, v3, vcc
	s_waitcnt lgkmcnt(0)
	global_store_dword v[4:5], v7, off
	ds_read_b32 v4, v6 offset:8448
	v_lshl_add_u64 v[2:3], v[2:3], 0, s[4:5]
	s_waitcnt lgkmcnt(0)
	global_store_dword v[2:3], v4, off offset:4

; __device__ __forceinline__ unsigned pk2(float lo, float hi) { return f2bf(lo) | (f2bf(hi) << 16); }
; __device__ __forceinline__ void ssm_gen(int g, LAS float* S, const float* a_re, const float* a_im, const float* log_dt, const float* b_re, const float* b_im,
;                                         const float* c_re, const float* c_im, bf16* BY, bf16* BE, float* A16, int tid) {
;     ...
;     unsigned* BYg = (unsigned*)(BY + (size_t)g * 256 * 384);
;     for (int i2 = tid; i2 < 256 * 192; i2 += NTHR) { const int row = i2 / 192, col = (i2 % 192) * 2, tl = row >> 4, co = row & 15; float v[2];
; #pragma unroll
;         for (int e = 0; e < 2; ++e) { const int cc = col + e;
;             if (cc < 256) { const int sl = cc >> 4, ci = cc & 15; v[e] = (tl >= sl) ? km[(tl - sl) * 256 + co * 16 + ci] : 0.f; }
;             else { const int q = cc - 256, p = q & 63; const float cr = ccr[co * 64 + p], cim = cci[co * 64 + p], lr = ljr[(tl + 1) * 64 + p], li = lji[(tl + 1) * 64 + p];
;                 v[e] = (q < 64) ? (cr * lr - cim * li) : -(cr * li + cim * lr); } }
;         BYg[i2] = pk2(v[0], v[1]); }
.LBB0_55:
	s_or_b64 exec, exec, s[0:1]
	s_waitcnt lgkmcnt(0)
	v_bfe_u32 v9, v1, 16, 1
	v_add3_u32 v1, v1, v9, s19
	v_bfe_u32 v9, v13, 16, 1
	v_lshrrev_b32_e32 v1, 16, v1
	v_add3_u32 v9, v13, v9, s19
	v_and_or_b32 v1, v9, s20, v1
	global_store_dword v[4:5], v1, off
	v_add_u32_e32 v1, 0x200, v8
	v_cmp_lt_i32_e32 vcc, s21, v8
	v_add_u32_e32 v6, 0x400, v6
	v_lshl_add_u64 v[4:5], v[4:5], 0, s[8:9]
	s_or_b64 s[6:7], vcc, s[6:7]
	v_mov_b32_e32 v8, v1
	s_andn2_b64 exec, exec, s[6:7]
	s_cbranch_execz .LBB0_67

; __device__ __forceinline__ unsigned pk2(float lo, float hi) { return f2bf(lo) | (f2bf(hi) << 16); }
; __device__ __forceinline__ void ssm_gen(int g, LAS float* S, const float* a_re, const float* a_im, const float* log_dt, const float* b_re, const float* b_im,
;                                         const float* c_re, const float* c_im, bf16* BY, bf16* BE, float* A16, int tid) {
;     ...
;     const int gi = g & 1; unsigned* BEg = (unsigned*)(BE + ((size_t)(g >> 1) * 256 + gi * 128) * 768);
;     for (int i2 = tid; i2 < 128 * 384; i2 += NTHR) { const int r = i2 / 384, col = (i2 % 384) * 2, part = r >> 6, p = r & 63; float v[2];
; #pragma unroll
;         for (int e = 0; e < 2; ++e) { const int c2 = col + e, gj = c2 >= 384 ? 1 : 0, cc = c2 - gj * 384;
;             if (gj == gi && cc < 256) { const int sl = cc >> 4, ci = cc & 15; const float lr = ljr[(15 - sl) * 64 + p], li = lji[(15 - sl) * 64 + p], br = bbr[p * 16 + ci], bi = bbi[p * 16 + ci];
;                 v[e] = part == 0 ? (lr * br - li * bi) : (lr * bi + li * br); }
;             else v[e] = 0.f; }
;         BEg[i2] = pk2(v[0], v[1]); }
.LBB0_68:
	s_or_b64 exec, exec, s[0:1]
	v_bfe_u32 v5, v10, 16, 1
	v_add3_u32 v5, v10, v5, s16
	v_bfe_u32 v8, v6, 16, 1
	v_lshrrev_b32_e32 v5, 16, v5
	v_add3_u32 v6, v6, v8, s16
	v_and_or_b32 v5, v6, s17, v5
	global_store_dword v[2:3], v5, off
	v_add_u32_e32 v5, 0x200, v4
	v_cmp_lt_i32_e32 vcc, s18, v4
	v_add_u32_e32 v7, 0x400, v7
	v_lshl_add_u64 v[2:3], v[2:3], 0, s[10:11]
	s_or_b64 s[8:9], vcc, s[8:9]
	v_mov_b32_e32 v4, v5
	s_andn2_b64 exec, exec, s[8:9]
	s_cbranch_execz .LBB0_73

; #define p_pos ((const int*)ldptr(L, 2))
; __global__ void __launch_bounds__(NTHR, 2) mk_fwd(Args args) {
;     ...
;         for (int t = bx * NTHR + tid; t < M; t += G * NTHR) { const int p = p_pos[t]; p_cid[t] = p >= 0 ? p / 64 : -((63 - p) / 64); }
.LBB0_76:
	ds_read_b64 v[6:7], v1
	ds_read_b64 v[8:9], v4
	v_add_u32_e32 v5, s4, v5
	v_cmp_lt_i32_e32 vcc, s3, v5
	s_or_b64 s[8:9], vcc, s[8:9]
	s_waitcnt lgkmcnt(0)
	v_readfirstlane_b32 s10, v6
	v_readfirstlane_b32 s11, v7
	s_nop 1
	v_lshl_add_u64 v[6:7], s[10:11], 0, v[2:3]
	global_load_dword v10, v[6:7], off
	v_readfirstlane_b32 s10, v8
	v_readfirstlane_b32 s11, v9
	s_waitcnt vmcnt(0) lgkmcnt(0)
	v_sub_u32_e32 v9, 63, v10
	v_lshl_add_u64 v[6:7], s[10:11], 0, v[2:3]
	v_add_co_u32_e32 v6, vcc, 0x480000, v6
	v_lshrrev_b32_e32 v9, 6, v9
	s_nop 0
	v_addc_co_u32_e32 v7, vcc, 0, v7, vcc
	v_lshrrev_b32_e32 v8, 6, v10
	v_sub_u32_e32 v9, 0, v9
	v_cmp_gt_i32_e32 vcc, 0, v10
	v_lshl_add_u64 v[2:3], v[2:3], 0, s[6:7]
	s_nop 0
	v_cndmask_b32_e32 v8, v8, v9, vcc
	global_store_dword v[6:7], v8, off
	s_andn2_b64 exec, exec, s[8:9]
	s_cbranch_execnz .LBB0_76

; #define p_pos ((const int*)ldptr(L, 2))
; __global__ void __launch_bounds__(NTHR, 2) mk_fwd(Args args) {
;     ...
;         for (int i = bx * NTHR + tid; i < M * 8; i += G * NTHR) { const int t = i >> 3, j = i & 7;
;             const float inv = (j == 0) ? 1.0f : (j == 1) ? 0.19392274474868576f : (j == 2) ? 0.03760603093086393f : (j == 3) ? 0.007292664737217109f : (j == 4) ? 0.001414213562373095f : (j == 5) ? 0.0002742481756762073f : (j == 6) ? 5.318295896944988e-05f : 1.031338537721246e-05f;
;             const float ang = (float)p_pos[t] * inv; p_CS[t * 16 + j] = cosf(ang); p_CS[t * 16 + 8 + j] = sinf(ang); }
.LBB0_79:
	s_or_b64 exec, exec, s[4:5]
	v_mul_f32_e32 v6, v21, v21
	v_fmamk_f32 v18, v6, 0xb94c1982, v11
	v_fmaak_f32 v18, v6, v18, 0xbe2aaa9d
	v_mul_f32_e32 v18, v6, v18
	v_fmac_f32_e32 v21, v21, v18
	v_fmamk_f32 v18, v6, 0x37d75334, v12
	v_fmaak_f32 v18, v6, v18, 0x3d2aabf7
	v_fmaak_f32 v18, v6, v18, 0xbf000004
	v_fma_f32 v6, v6, v18, 1.0
	v_and_b32_e32 v18, 1, v20
	v_cmp_eq_u32_e32 vcc, 0, v18
	v_lshlrev_b32_e32 v18, 30, v20
	v_and_b32_e32 v18, 0x80000000, v18
	v_xor_b32_e32 v16, v17, v16
	v_cndmask_b32_e32 v6, v6, v21, vcc
	v_xor_b32_e32 v16, v16, v18
	v_xor_b32_e32 v6, v16, v6
	v_cndmask_b32_e64 v6, v15, v6, s[0:1]
	v_readfirstlane_b32 s0, v4
	v_readfirstlane_b32 s1, v5
	v_add_u32_e32 v0, s3, v0
	v_mov_b32_e32 v16, s0
	v_mov_b32_e32 v17, s1
	v_lshl_add_u64 v[8:9], v[8:9], 2, v[16:17]
	v_add_co_u32_e32 v8, vcc, 0x600000, v8
	s_nop 1
	v_addc_co_u32_e32 v9, vcc, 0, v9, vcc
	v_cmp_lt_i32_e32 vcc, s29, v0
	s_or_b64 s[12:13], vcc, s[12:13]
	global_store_dword v[8:9], v6, off offset:32
	s_andn2_b64 exec, exec, s[12:13]
	s_cbranch_execz .LBB0_106

; #define p_pos ((const int*)ldptr(L, 2))
; __global__ void __launch_bounds__(NTHR, 2) mk_fwd(Args args) {
;     ...
;         for (int i = bx * NTHR + tid; i < M * 8; i += G * NTHR) { const int t = i >> 3, j = i & 7;
;             const float inv = (j == 0) ? 1.0f : (j == 1) ? 0.19392274474868576f : (j == 2) ? 0.03760603093086393f : (j == 3) ? 0.007292664737217109f : (j == 4) ? 0.001414213562373095f : (j == 5) ? 0.0002742481756762073f : (j == 6) ? 5.318295896944988e-05f : 1.031338537721246e-05f;
;             const float ang = (float)p_pos[t] * inv; p_CS[t * 16 + j] = cosf(ang); p_CS[t * 16 + 8 + j] = sinf(ang); }
.LBB0_98:
	s_or_b64 exec, exec, s[0:1]
	v_ashrrev_i32_e32 v8, 3, v0
	s_waitcnt lgkmcnt(0)
	v_readfirstlane_b32 s0, v2
	v_readfirstlane_b32 s1, v3
	v_ashrrev_i32_e32 v9, 31, v8
	v_mov_b32_e32 v16, s0
	v_mov_b32_e32 v17, s1
	v_lshl_add_u64 v[16:17], v[8:9], 2, v[16:17]
	global_load_dword v9, v[16:17], off
	s_waitcnt vmcnt(0) lgkmcnt(0)
	v_cvt_f32_i32_e32 v9, v9
	v_mul_f32_e32 v16, v6, v9
	v_and_b32_e32 v17, 0x7fffffff, v16
	v_lshrrev_b32_e32 v6, 23, v17
	v_and_b32_e32 v9, 0x7fffff, v17
	v_cmp_nlt_f32_e64 s[8:9], |v16|, s16
	v_add_u32_e32 v19, 0xffffff88, v6
	v_or_b32_e32 v18, 0x800000, v9
	s_and_saveexec_b64 s[0:1], s[8:9]
	s_xor_b64 s[14:15], exec, s[0:1]
	s_cbranch_execz .LBB0_100
	v_cmp_lt_u32_e32 vcc, 63, v19
	v_mad_u64_u32 v[20:21], s[6:7], v18, s17, 0
	s_nop 0
	v_cndmask_b32_e32 v6, 0, v13, vcc
	v_add_u32_e32 v6, v6, v19
	v_cmp_lt_u32_e64 s[0:1], 31, v6
	s_nop 1
	v_cndmask_b32_e64 v9, 0, v14, s[0:1]
	v_add_u32_e32 v6, v9, v6
	v_cmp_lt_u32_e64 s[4:5], 31, v6
	s_nop 1
	v_cndmask_b32_e64 v9, 0, v14, s[4:5]
	v_add_u32_e32 v9, v9, v6
	v_mov_b32_e32 v6, v21
	v_mad_u64_u32 v[22:23], s[6:7], v18, s18, v[6:7]
	v_mov_b32_e32 v6, v23
	v_mad_u64_u32 v[24:25], s[6:7], v18, s19, v[6:7]
	v_mov_b32_e32 v6, v25
	v_mad_u64_u32 v[26:27], s[6:7], v18, s20, v[6:7]
	v_mov_b32_e32 v6, v27
	v_mad_u64_u32 v[28:29], s[6:7], v18, s21, v[6:7]
	v_mov_b32_e32 v6, v29
	v_mad_u64_u32 v[30:31], s[6:7], v18, s22, v[6:7]
	v_mov_b32_e32 v6, v31
	v_mad_u64_u32 v[32:33], s[6:7], v18, s23, v[6:7]
	v_cndmask_b32_e32 v21, v30, v26, vcc
	v_cndmask_b32_e32 v6, v32, v28, vcc
	v_cndmask_b32_e32 v25, v33, v30, vcc
	v_cndmask_b32_e64 v23, v6, v21, s[0:1]
	v_cndmask_b32_e64 v6, v25, v6, s[0:1]
	v_cndmask_b32_e32 v25, v28, v24, vcc
	v_cndmask_b32_e64 v21, v21, v25, s[0:1]
	v_sub_u32_e32 v27, 32, v9
	v_cmp_eq_u32_e64 s[6:7], 0, v9
	v_cndmask_b32_e32 v9, v26, v22, vcc
	v_cndmask_b32_e64 v6, v6, v23, s[4:5]
	v_cndmask_b32_e64 v23, v23, v21, s[4:5]
	v_cndmask_b32_e64 v22, v25, v9, s[0:1]
	v_alignbit_b32 v28, v6, v23, v27
	v_cndmask_b32_e64 v21, v21, v22, s[4:5]
	v_cndmask_b32_e64 v6, v28, v6, s[6:7]
	v_alignbit_b32 v25, v23, v21, v27
	v_cndmask_b32_e32 v20, v24, v20, vcc
	v_cndmask_b32_e64 v23, v25, v23, s[6:7]
	v_bfe_u32 v28, v6, 29, 1
	v_cndmask_b32_e64 v9, v9, v20, s[0:1]
	v_alignbit_b32 v25, v6, v23, 30
	v_sub_u32_e32 v29, 0, v28
	v_cndmask_b32_e64 v9, v22, v9, s[4:5]
	v_xor_b32_e32 v25, v25, v29
	v_alignbit_b32 v20, v21, v9, v27
	v_cndmask_b32_e64 v20, v20, v21, s[6:7]
	v_ffbh_u32_e32 v22, v25
	v_alignbit_b32 v21, v23, v20, 30
	v_min_u32_e32 v22, 32, v22
	v_alignbit_b32 v9, v20, v9, 30
	v_xor_b32_e32 v21, v21, v29
	v_sub_u32_e32 v23, 31, v22
	v_xor_b32_e32 v9, v9, v29
	v_alignbit_b32 v24, v25, v21, v23
	v_alignbit_b32 v9, v21, v9, v23
	v_alignbit_b32 v20, v24, v9, 9
	v_ffbh_u32_e32 v21, v20
	v_min_u32_e32 v21, 32, v21
	v_lshrrev_b32_e32 v26, 29, v6
	v_not_b32_e32 v23, v21
	v_alignbit_b32 v9, v20, v9, v23
	v_lshlrev_b32_e32 v20, 31, v26
	v_or_b32_e32 v23, 0x33000000, v20
	v_add_lshl_u32 v21, v21, v22, 23
	v_lshrrev_b32_e32 v9, 9, v9
	v_sub_u32_e32 v21, v23, v21
	v_or_b32_e32 v20, 0.5, v20
	v_lshlrev_b32_e32 v22, 23, v22
	v_or_b32_e32 v9, v21, v9
	v_lshrrev_b32_e32 v21, 9, v24
	v_sub_u32_e32 v20, v20, v22
	v_or_b32_e32 v20, v21, v20
	v_mul_f32_e32 v21, 0x3fc90fda, v20
	v_fma_f32 v22, v20, s24, -v21
	v_fmac_f32_e32 v22, 0x33a22168, v20
	v_fmac_f32_e32 v22, 0x3fc90fda, v9
	v_lshrrev_b32_e32 v6, 30, v6
	v_add_f32_e32 v20, v21, v22
	v_add_u32_e32 v9, v28, v6
; #define p_pos ((const int*)ldptr(L, 2))
; __global__ void __launch_bounds__(NTHR, 2) mk_fwd(Args args) {
;     ...
;         for (int i = bx * NTHR + tid; i < M * 8; i += G * NTHR) { const int t = i >> 3, j = i & 7;
;             const float inv = (j == 0) ? 1.0f : (j == 1) ? 0.19392274474868576f : (j == 2) ? 0.03760603093086393f : (j == 3) ? 0.007292664737217109f : (j == 4) ? 0.001414213562373095f : (j == 5) ? 0.0002742481756762073f : (j == 6) ? 5.318295896944988e-05f : 1.031338537721246e-05f;
;             const float ang = (float)p_pos[t] * inv; p_CS[t * 16 + j] = cosf(ang); p_CS[t * 16 + 8 + j] = sinf(ang); }
.LBB0_100:
	s_or_saveexec_b64 s[0:1], s[14:15]
	v_mul_f32_e64 v6, |v16|, s25
	v_rndne_f32_e32 v6, v6
	s_xor_b64 exec, exec, s[0:1]
	v_cvt_i32_f32_e32 v9, v6
	v_fma_f32 v20, v6, s26, |v16|
	v_fmac_f32_e32 v20, 0xb3a22168, v6
	v_fmac_f32_e32 v20, 0xa7c234c4, v6
	s_or_b64 exec, exec, s[0:1]
	v_mul_f32_e32 v21, v20, v20
	v_fmamk_f32 v22, v21, 0xb94c1982, v11
	v_fmaak_f32 v22, v21, v22, 0xbe2aaa9d
	v_mul_f32_e32 v22, v21, v22
	v_fmac_f32_e32 v20, v20, v22
	v_fmamk_f32 v22, v21, 0x37d75334, v12
	v_fmaak_f32 v22, v21, v22, 0x3d2aabf7
	v_fmaak_f32 v22, v21, v22, 0xbf000004
	v_fma_f32 v21, v21, v22, 1.0
	v_and_b32_e32 v22, 1, v9
	v_cmp_eq_u32_e32 vcc, 0, v22
	v_lshlrev_b32_e32 v9, 30, v9
	v_cmp_class_f32_e64 s[0:1], v16, s28
	v_cndmask_b32_e64 v20, -v20, v21, vcc
	v_bitop3_b32 v9, v9, v20, s27 bitop3:0x6c
	v_readfirstlane_b32 s4, v4
	v_readfirstlane_b32 s5, v5
	v_lshl_or_b32 v8, v8, 4, v1
	v_cndmask_b32_e64 v22, v15, v9, s[0:1]
	v_mov_b32_e32 v20, s4
	v_mov_b32_e32 v21, s5
	v_ashrrev_i32_e32 v9, 31, v8
	v_lshl_add_u64 v[20:21], v[8:9], 2, v[20:21]
	v_add_co_u32_e32 v20, vcc, 0x600000, v20
	s_nop 1
	v_addc_co_u32_e32 v21, vcc, 0, v21, vcc
	global_store_dword v[20:21], v22, off
	s_and_saveexec_b64 s[4:5], s[8:9]
	s_xor_b64 s[14:15], exec, s[4:5]
	s_cbranch_execz .LBB0_104
	v_cmp_lt_u32_e32 vcc, 63, v19
	v_mad_u64_u32 v[20:21], s[8:9], v18, s17, 0
	s_nop 0
	v_cndmask_b32_e32 v6, 0, v13, vcc
	v_add_u32_e32 v6, v6, v19
	v_cmp_lt_u32_e64 s[4:5], 31, v6
	s_nop 1
	v_cndmask_b32_e64 v19, 0, v14, s[4:5]
	v_add_u32_e32 v6, v19, v6
	v_cmp_lt_u32_e64 s[6:7], 31, v6
	s_nop 1
	v_cndmask_b32_e64 v19, 0, v14, s[6:7]
	v_add_u32_e32 v32, v19, v6
	v_mov_b32_e32 v6, v21
	v_mad_u64_u32 v[22:23], s[8:9], v18, s18, v[6:7]
	v_mov_b32_e32 v6, v23
	v_mad_u64_u32 v[24:25], s[8:9], v18, s19, v[6:7]
	v_mov_b32_e32 v6, v25
	v_mad_u64_u32 v[26:27], s[8:9], v18, s20, v[6:7]
	v_mov_b32_e32 v6, v27
	v_mad_u64_u32 v[28:29], s[8:9], v18, s21, v[6:7]
	v_mov_b32_e32 v6, v29
	v_mad_u64_u32 v[30:31], s[8:9], v18, s22, v[6:7]
	v_mov_b32_e32 v6, v31
	v_mad_u64_u32 v[18:19], s[8:9], v18, s23, v[6:7]
	v_cndmask_b32_e32 v21, v30, v26, vcc
	v_cndmask_b32_e32 v6, v18, v28, vcc
	v_cndmask_b32_e32 v19, v19, v30, vcc
	v_cndmask_b32_e64 v18, v6, v21, s[4:5]
	v_cndmask_b32_e64 v6, v19, v6, s[4:5]
	v_cndmask_b32_e32 v19, v28, v24, vcc
	v_cndmask_b32_e64 v21, v21, v19, s[4:5]
	v_cndmask_b32_e32 v22, v26, v22, vcc
	v_cndmask_b32_e64 v6, v6, v18, s[6:7]
	v_cndmask_b32_e64 v18, v18, v21, s[6:7]
	v_sub_u32_e32 v23, 32, v32
	v_cndmask_b32_e64 v19, v19, v22, s[4:5]
	v_alignbit_b32 v25, v6, v18, v23
	v_cmp_eq_u32_e64 s[8:9], 0, v32
	v_cndmask_b32_e64 v21, v21, v19, s[6:7]
	v_cndmask_b32_e32 v20, v24, v20, vcc
	v_cndmask_b32_e64 v6, v25, v6, s[8:9]
	v_alignbit_b32 v25, v18, v21, v23
	v_cndmask_b32_e64 v18, v25, v18, s[8:9]
	v_bfe_u32 v27, v6, 29, 1
	v_cndmask_b32_e64 v20, v22, v20, s[4:5]
	v_alignbit_b32 v25, v6, v18, 30
	v_sub_u32_e32 v28, 0, v27
	v_cndmask_b32_e64 v19, v19, v20, s[6:7]
	v_xor_b32_e32 v25, v25, v28
	v_alignbit_b32 v20, v21, v19, v23
	v_cndmask_b32_e64 v20, v20, v21, s[8:9]
	v_ffbh_u32_e32 v21, v25
	v_alignbit_b32 v18, v18, v20, 30
	v_min_u32_e32 v21, 32, v21
	v_alignbit_b32 v19, v20, v19, 30
	v_xor_b32_e32 v18, v18, v28
	v_sub_u32_e32 v22, 31, v21
	v_xor_b32_e32 v19, v19, v28
	v_alignbit_b32 v23, v25, v18, v22
	v_alignbit_b32 v18, v18, v19, v22
	v_alignbit_b32 v19, v23, v18, 9
	v_ffbh_u32_e32 v20, v19
	v_min_u32_e32 v20, 32, v20
	v_lshrrev_b32_e32 v26, 29, v6
	v_not_b32_e32 v22, v20
	v_alignbit_b32 v18, v19, v18, v22
	v_lshlrev_b32_e32 v19, 31, v26
	v_or_b32_e32 v22, 0x33000000, v19
	v_add_lshl_u32 v20, v20, v21, 23
	v_lshrrev_b32_e32 v18, 9, v18
	v_sub_u32_e32 v20, v22, v20
	v_or_b32_e32 v19, 0.5, v19
	v_lshlrev_b32_e32 v21, 23, v21
	v_or_b32_e32 v18, v20, v18
	v_lshrrev_b32_e32 v20, 9, v23
	v_sub_u32_e32 v19, v19, v21
	v_or_b32_e32 v19, v20, v19
	v_mul_f32_e32 v20, 0x3fc90fda, v19
	v_fma_f32 v21, v19, s24, -v20
	v_fmac_f32_e32 v21, 0x33a22168, v19
	v_fmac_f32_e32 v21, 0x3fc90fda, v18
	v_lshrrev_b32_e32 v6, 30, v6
	v_add_f32_e32 v21, v20, v21
	v_add_u32_e32 v20, v27, v6

; #define p_cvec INP(1)
; #define p_w_ada INP(3)
; __global__ void __launch_bounds__(NTHR, 2) mk_fwd(Args args) {
;     ...
;             for (int r = g0; r < I_MOD; r += gn) { const int sl = r / 72, cb = r % 72, col = cb * 256 + lane * 4; f32x4 acc = {0.f, 0.f, 0.f, 0.f};
;                 const float* wp = p_w_ada + (size_t)(sl * 64) * NMOD + col; const float* cp = p_cvec + sl * 64;
; #pragma unroll 16
;                 for (int kk = 0; kk < 64; ++kk) { const float cv = cp[kk]; const float sv = cv / (1.0f + expf(-cv)); acc += *(const f32x4*)(wp + (size_t)kk * NMOD) * sv; }
;                 *(f32x4*)(p_modp + (size_t)sl * NMOD + col) = acc; } }
.LBB0_110:
	v_mov_b64_e32 v[4:5], s[36:37]
	global_load_dwordx4 v[28:31], v[4:5], off
	global_load_dwordx4 v[12:15], v[4:5], off offset:16
	global_load_dwordx4 v[8:11], v[4:5], off offset:32
	v_lshl_add_u64 v[36:37], v[86:87], 0, s[38:39]
	v_add_co_u32_e32 v38, vcc, s41, v36
	global_load_dwordx4 v[4:7], v[4:5], off offset:48
	s_nop 0
	v_addc_co_u32_e32 v39, vcc, 0, v37, vcc
	v_add_co_u32_e32 v94, vcc, s45, v36
	s_add_u32 s38, s38, 0x120000
	s_nop 0
	v_addc_co_u32_e32 v95, vcc, 0, v37, vcc
	v_add_co_u32_e32 v96, vcc, s46, v36
	s_addc_u32 s39, s39, 0
	s_nop 0
	v_addc_co_u32_e32 v97, vcc, 0, v37, vcc
	v_add_co_u32_e32 v98, vcc, s47, v36
	s_add_u32 s36, s36, 64
	s_nop 0
	v_addc_co_u32_e32 v99, vcc, 0, v37, vcc
	v_add_co_u32_e32 v100, vcc, s48, v36
	s_addc_u32 s37, s37, 0
	s_nop 0
	v_addc_co_u32_e32 v101, vcc, 0, v37, vcc
	v_add_co_u32_e32 v102, vcc, s49, v36
	s_cmp_eq_u32 s38, 0x480000
	s_nop 0
	v_addc_co_u32_e32 v103, vcc, 0, v37, vcc
	v_add_co_u32_e32 v104, vcc, s50, v36
	s_waitcnt vmcnt(0) lgkmcnt(0)
	v_mul_f32_e32 v93, 0xbfb8aa3b, v28
	v_addc_co_u32_e32 v105, vcc, 0, v37, vcc
	v_add_co_u32_e32 v106, vcc, s51, v36
	v_cmp_nlt_f32_e64 s[30:31], s43, v28
	s_nop 0
	v_addc_co_u32_e32 v107, vcc, 0, v37, vcc
	v_add_co_u32_e32 v108, vcc, s52, v36
	v_cmp_nlt_f32_e64 s[0:1], s43, v30
	s_nop 0
	v_addc_co_u32_e32 v109, vcc, 0, v37, vcc
	v_add_co_u32_e32 v110, vcc, s53, v36
	v_cmp_nlt_f32_e64 s[4:5], s43, v31
	s_nop 0
	v_addc_co_u32_e32 v111, vcc, 0, v37, vcc
	v_add_co_u32_e32 v112, vcc, s54, v36
	v_cmp_nlt_f32_e64 s[6:7], s43, v12
	s_nop 0
	v_addc_co_u32_e32 v113, vcc, 0, v37, vcc
	v_add_co_u32_e32 v114, vcc, s55, v36
	v_cmp_nlt_f32_e64 s[8:9], s43, v13
	s_nop 0
	v_addc_co_u32_e32 v115, vcc, 0, v37, vcc
	v_add_co_u32_e32 v116, vcc, s56, v36
	v_cmp_nlt_f32_e64 s[10:11], s43, v14
	s_nop 0
	v_addc_co_u32_e32 v117, vcc, 0, v37, vcc
	v_add_co_u32_e32 v118, vcc, s57, v36
	v_cmp_nlt_f32_e64 s[28:29], s43, v15
	s_nop 0
	v_addc_co_u32_e32 v119, vcc, 0, v37, vcc
	v_add_co_u32_e32 v120, vcc, s58, v36
	v_cmp_nlt_f32_e64 s[12:13], s43, v8
	s_nop 0
	v_addc_co_u32_e32 v121, vcc, 0, v37, vcc
	global_load_dwordx4 v[80:83], v[36:37], off
	global_load_dwordx4 v[76:79], v[38:39], off
	global_load_dwordx4 v[72:75], v[94:95], off
	global_load_dwordx4 v[68:71], v[96:97], off
	global_load_dwordx4 v[64:67], v[98:99], off
	global_load_dwordx4 v[60:63], v[100:101], off
	global_load_dwordx4 v[56:59], v[102:103], off
	global_load_dwordx4 v[52:55], v[104:105], off
	global_load_dwordx4 v[48:51], v[106:107], off
	global_load_dwordx4 v[44:47], v[108:109], off
	global_load_dwordx4 v[40:43], v[110:111], off
	global_load_dwordx4 v[32:35], v[112:113], off
	global_load_dwordx4 v[24:27], v[114:115], off
	global_load_dwordx4 v[20:23], v[116:117], off
	global_load_dwordx4 v[16:19], v[118:119], off
	global_load_dwordx4 v[36:39], v[120:121], off
	v_mul_f32_e32 v94, 0xbfb8aa3b, v29
	v_rndne_f32_e32 v109, v93
	v_fma_f32 v110, v28, s42, -v93
	v_mul_f32_e32 v95, 0xbfb8aa3b, v30
	v_rndne_f32_e32 v111, v94
	v_fma_f32 v112, v29, s42, -v94
	v_sub_f32_e32 v93, v93, v109
	v_fmac_f32_e32 v110, 0xb2a5705f, v28
	v_mul_f32_e32 v96, 0xbfb8aa3b, v31
	v_rndne_f32_e32 v113, v95
	v_fma_f32 v114, v30, s42, -v95
	v_sub_f32_e32 v94, v94, v111
	v_fmac_f32_e32 v112, 0xb2a5705f, v29
	v_add_f32_e32 v93, v93, v110
	v_mul_f32_e32 v97, 0xbfb8aa3b, v12
	v_rndne_f32_e32 v115, v96
	v_fma_f32 v116, v31, s42, -v96
	v_cvt_i32_f32_e32 v109, v109
	v_sub_f32_e32 v95, v95, v113
	v_fmac_f32_e32 v114, 0xb2a5705f, v30
	v_add_f32_e32 v94, v94, v112
	v_exp_f32_e32 v93, v93
	v_mul_f32_e32 v98, 0xbfb8aa3b, v13
	v_rndne_f32_e32 v117, v97
	v_fma_f32 v118, v12, s42, -v97
	v_cvt_i32_f32_e32 v111, v111
	v_sub_f32_e32 v96, v96, v115
	v_fmac_f32_e32 v116, 0xb2a5705f, v31
	v_add_f32_e32 v95, v95, v114
	v_exp_f32_e32 v94, v94
	v_mul_f32_e32 v99, 0xbfb8aa3b, v14
	v_rndne_f32_e32 v119, v98
	v_fma_f32 v120, v13, s42, -v98
	v_cvt_i32_f32_e32 v113, v113
	v_sub_f32_e32 v97, v97, v117
	v_fmac_f32_e32 v118, 0xb2a5705f, v12
	v_add_f32_e32 v96, v96, v116
	v_exp_f32_e32 v95, v95
	v_mul_f32_e32 v100, 0xbfb8aa3b, v15
	v_rndne_f32_e32 v121, v99
	v_fma_f32 v122, v14, s42, -v99
	v_cvt_i32_f32_e32 v115, v115
	v_sub_f32_e32 v98, v98, v119
	v_fmac_f32_e32 v120, 0xb2a5705f, v13
	v_add_f32_e32 v97, v97, v118
	v_exp_f32_e32 v96, v96
	v_mul_f32_e32 v101, 0xbfb8aa3b, v8
	v_rndne_f32_e32 v123, v100
	v_fma_f32 v124, v15, s42, -v100
	v_cvt_i32_f32_e32 v117, v117
	v_sub_f32_e32 v99, v99, v121
	v_fmac_f32_e32 v122, 0xb2a5705f, v14
	v_add_f32_e32 v98, v98, v120
	v_exp_f32_e32 v97, v97
	v_ldexp_f32 v93, v93, v109
	v_mul_f32_e32 v102, 0xbfb8aa3b, v9
	v_rndne_f32_e32 v125, v101
	v_fma_f32 v126, v8, s42, -v101
	v_cvt_i32_f32_e32 v119, v119
	v_sub_f32_e32 v100, v100, v123
	v_fmac_f32_e32 v124, 0xb2a5705f, v15
	v_add_f32_e32 v99, v99, v122
	v_exp_f32_e32 v98, v98
	v_ldexp_f32 v94, v94, v111
	v_cmp_nlt_f32_e32 vcc, s43, v29
	v_cndmask_b32_e64 v93, 0, v93, s[30:31]
	v_cmp_ngt_f32_e64 s[30:31], s44, v28
	v_mul_f32_e32 v103, 0xbfb8aa3b, v10
	v_rndne_f32_e32 v127, v102
	v_fma_f32 v128, v9, s42, -v102
	v_sub_f32_e32 v101, v101, v125
	v_fmac_f32_e32 v126, 0xb2a5705f, v8
	v_cvt_i32_f32_e32 v121, v121
	v_add_f32_e32 v100, v100, v124
	v_exp_f32_e32 v99, v99
	v_ldexp_f32 v95, v95, v113
	v_cndmask_b32_e32 v94, 0, v94, vcc
	v_cmp_ngt_f32_e32 vcc, s44, v29
	v_cndmask_b32_e64 v93, v92, v93, s[30:31]
	v_mul_f32_e32 v104, 0xbfb8aa3b, v11
	v_mul_f32_e32 v108, 0xbfb8aa3b, v7
	v_rndne_f32_e32 v129, v103
	v_fma_f32 v130, v10, s42, -v103
	v_sub_f32_e32 v102, v102, v127
	v_fmac_f32_e32 v128, 0xb2a5705f, v9
	v_cvt_i32_f32_e32 v123, v123
	v_add_f32_e32 v101, v101, v126
	v_exp_f32_e32 v100, v100
; __global__ void __launch_bounds__(NTHR, 2) mk_fwd(Args args) {
;     ...
;                 for (int kk = 0; kk < 64; ++kk) { const float cv = cp[kk]; const float sv = cv / (1.0f + expf(-cv)); acc += *(const f32x4*)(wp + (size_t)kk * NMOD) * sv; }
	v_ldexp_f32 v96, v96, v115
	v_cndmask_b32_e64 v95, 0, v95, s[0:1]
	v_cmp_ngt_f32_e64 s[0:1], s44, v30
	v_cndmask_b32_e32 v94, v92, v94, vcc
	v_add_f32_e32 v93, 1.0, v93
	v_mul_f32_e32 v105, 0xbfb8aa3b, v4
	v_mul_f32_e32 v107, 0xbfb8aa3b, v6
	v_rndne_f32_e32 v131, v104
	v_fma_f32 v132, v11, s42, -v104
	v_rndne_f32_e32 v139, v108
	v_fma_f32 v140, v7, s42, -v108
	v_sub_f32_e32 v103, v103, v129
	v_fmac_f32_e32 v130, 0xb2a5705f, v10
	v_cvt_i32_f32_e32 v125, v125
	v_add_f32_e32 v102, v102, v128
	v_exp_f32_e32 v101, v101
	v_ldexp_f32 v97, v97, v117
	v_cndmask_b32_e64 v96, 0, v96, s[4:5]
	v_cmp_ngt_f32_e64 s[4:5], s44, v31
	v_cndmask_b32_e64 v95, v92, v95, s[0:1]
	v_add_f32_e32 v94, 1.0, v94
	v_div_scale_f32 v109, s[0:1], v93, v93, v28
	v_mul_f32_e32 v106, 0xbfb8aa3b, v5
	v_rndne_f32_e32 v133, v105
	v_fma_f32 v134, v4, s42, -v105
	v_rndne_f32_e32 v137, v107
	v_fma_f32 v138, v6, s42, -v107
	v_sub_f32_e32 v104, v104, v131
	v_fmac_f32_e32 v132, 0xb2a5705f, v11
	v_sub_f32_e32 v108, v108, v139
	v_fmac_f32_e32 v140, 0xb2a5705f, v7
	v_cvt_i32_f32_e32 v127, v127
	v_add_f32_e32 v103, v103, v130
	v_exp_f32_e32 v102, v102
	v_ldexp_f32 v98, v98, v119
	v_cndmask_b32_e64 v97, 0, v97, s[6:7]
	v_cmp_ngt_f32_e64 s[6:7], s44, v12
	v_cndmask_b32_e64 v96, v92, v96, s[4:5]
	v_add_f32_e32 v95, 1.0, v95
	v_div_scale_f32 v111, s[0:1], v94, v94, v29
	v_rcp_f32_e32 v141, v109
	v_rndne_f32_e32 v135, v106
	v_fma_f32 v136, v5, s42, -v106
	v_sub_f32_e32 v105, v105, v133
	v_fmac_f32_e32 v134, 0xb2a5705f, v4
	v_sub_f32_e32 v107, v107, v137
	v_fmac_f32_e32 v138, 0xb2a5705f, v6
	v_cvt_i32_f32_e32 v129, v129
	v_add_f32_e32 v104, v104, v132
	v_add_f32_e32 v108, v108, v140
	v_exp_f32_e32 v103, v103
	v_ldexp_f32 v99, v99, v121
	v_cndmask_b32_e64 v98, 0, v98, s[8:9]
	v_cmp_ngt_f32_e64 s[8:9], s44, v13
	v_cndmask_b32_e64 v97, v92, v97, s[6:7]
	v_add_f32_e32 v96, 1.0, v96
	v_div_scale_f32 v113, s[0:1], v95, v95, v30
	v_rcp_f32_e32 v142, v111
	v_sub_f32_e32 v106, v106, v135
	v_fmac_f32_e32 v136, 0xb2a5705f, v5
	v_cvt_i32_f32_e32 v131, v131
	v_cvt_i32_f32_e32 v139, v139
	v_add_f32_e32 v105, v105, v134
	v_add_f32_e32 v107, v107, v138
	v_exp_f32_e32 v104, v104
	v_exp_f32_e32 v108, v108
	v_ldexp_f32 v100, v100, v123
	v_cndmask_b32_e64 v99, 0, v99, s[10:11]
	v_cmp_ngt_f32_e64 s[10:11], s44, v14
	v_cndmask_b32_e64 v98, v92, v98, s[8:9]
	v_add_f32_e32 v97, 1.0, v97
	v_div_scale_f32 v115, s[0:1], v96, v96, v31
	v_rcp_f32_e32 v143, v113
	v_cvt_i32_f32_e32 v133, v133
	v_cvt_i32_f32_e32 v137, v137
	v_add_f32_e32 v106, v106, v136
	v_exp_f32_e32 v105, v105
	v_exp_f32_e32 v107, v107
	v_ldexp_f32 v101, v101, v125
	v_cndmask_b32_e64 v100, 0, v100, s[28:29]
	v_cmp_ngt_f32_e64 s[28:29], s44, v15
	v_cndmask_b32_e64 v99, v92, v99, s[10:11]
	v_add_f32_e32 v98, 1.0, v98
	v_div_scale_f32 v117, s[0:1], v97, v97, v12
	v_rcp_f32_e32 v144, v115
	v_cvt_i32_f32_e32 v135, v135
	v_exp_f32_e32 v106, v106
	v_ldexp_f32 v102, v102, v127
	v_cmp_nlt_f32_e64 s[14:15], s43, v9
	v_cndmask_b32_e64 v101, 0, v101, s[12:13]
	v_cmp_ngt_f32_e64 s[12:13], s44, v8
	v_cndmask_b32_e64 v100, v92, v100, s[28:29]
	v_add_f32_e32 v99, 1.0, v99
	v_div_scale_f32 v119, s[0:1], v98, v98, v13
	v_rcp_f32_e32 v145, v117
	v_fma_f32 v157, -v109, v141, 1.0
	v_ldexp_f32 v103, v103, v129
	v_cmp_nlt_f32_e64 s[16:17], s43, v10
	v_cndmask_b32_e64 v102, 0, v102, s[14:15]
	v_cmp_ngt_f32_e64 s[14:15], s44, v9
	v_cndmask_b32_e64 v101, v92, v101, s[12:13]
	v_add_f32_e32 v100, 1.0, v100
	v_div_scale_f32 v110, vcc, v28, v93, v28
	v_div_scale_f32 v121, s[0:1], v99, v99, v14
	v_rcp_f32_e32 v146, v119
	v_fma_f32 v158, -v111, v142, 1.0
	v_fmac_f32_e32 v141, v157, v141
	v_ldexp_f32 v104, v104, v131
	v_ldexp_f32 v108, v108, v139
	v_cmp_nlt_f32_e64 s[18:19], s43, v11
	v_cmp_nlt_f32_e64 s[26:27], s43, v7
	v_cndmask_b32_e64 v103, 0, v103, s[16:17]
	v_cmp_ngt_f32_e64 s[16:17], s44, v10
	v_cndmask_b32_e64 v102, v92, v102, s[14:15]
	v_add_f32_e32 v101, 1.0, v101
	v_div_scale_f32 v112, s[30:31], v29, v94, v29
	v_div_scale_f32 v123, s[0:1], v100, v100, v15
	v_rcp_f32_e32 v147, v121
	v_fma_f32 v159, -v113, v143, 1.0
	v_fmac_f32_e32 v142, v158, v142
	v_mul_f32_e32 v157, v110, v141
	v_ldexp_f32 v105, v105, v133
	v_ldexp_f32 v107, v107, v137
	v_cmp_nlt_f32_e64 s[20:21], s43, v4
	v_cmp_nlt_f32_e64 s[24:25], s43, v6
	v_cndmask_b32_e64 v104, 0, v104, s[18:19]
	v_cmp_ngt_f32_e64 s[18:19], s44, v11
	v_cndmask_b32_e64 v108, 0, v108, s[26:27]
	v_cmp_ngt_f32_e64 s[26:27], s44, v7
	v_cndmask_b32_e64 v103, v92, v103, s[16:17]
	v_add_f32_e32 v102, 1.0, v102
	v_div_scale_f32 v114, s[28:29], v30, v95, v30
	v_div_scale_f32 v125, s[0:1], v101, v101, v8
	v_rcp_f32_e32 v148, v123
	v_fma_f32 v160, -v115, v144, 1.0
	v_fmac_f32_e32 v143, v159, v143
	v_mul_f32_e32 v158, v112, v142
	v_fma_f32 v173, -v109, v157, v110
	v_ldexp_f32 v106, v106, v135
	v_cmp_nlt_f32_e64 s[22:23], s43, v5
	v_cndmask_b32_e64 v105, 0, v105, s[20:21]
	v_cmp_ngt_f32_e64 s[20:21], s44, v4
	v_cndmask_b32_e64 v107, 0, v107, s[24:25]
	v_cmp_ngt_f32_e64 s[24:25], s44, v6
	v_cndmask_b32_e64 v104, v92, v104, s[18:19]
	v_cndmask_b32_e64 v108, v92, v108, s[26:27]
	v_add_f32_e32 v103, 1.0, v103
	v_div_scale_f32 v116, s[26:27], v31, v96, v31
	v_div_scale_f32 v127, s[0:1], v102, v102, v9
	v_rcp_f32_e32 v149, v125
	v_fma_f32 v161, -v117, v145, 1.0
	v_fmac_f32_e32 v144, v160, v144
	v_mul_f32_e32 v159, v114, v143
	v_fma_f32 v174, -v111, v158, v112
	v_fmac_f32_e32 v157, v173, v141
	v_cndmask_b32_e64 v106, 0, v106, s[22:23]
	v_cmp_ngt_f32_e64 s[22:23], s44, v5
	v_cndmask_b32_e64 v105, v92, v105, s[20:21]
	v_cndmask_b32_e64 v107, v92, v107, s[24:25]
	v_add_f32_e32 v104, 1.0, v104
	v_div_scale_f32 v118, s[24:25], v12, v97, v12
; __global__ void __launch_bounds__(NTHR, 2) mk_fwd(Args args) {
;     ...
;                 for (int kk = 0; kk < 64; ++kk) { const float cv = cp[kk]; const float sv = cv / (1.0f + expf(-cv)); acc += *(const f32x4*)(wp + (size_t)kk * NMOD) * sv; }
	v_div_scale_f32 v129, s[0:1], v103, v103, v10
	v_rcp_f32_e32 v150, v127
	v_fma_f32 v162, -v119, v146, 1.0
	v_fmac_f32_e32 v145, v161, v145
	v_mul_f32_e32 v160, v116, v144
	v_fma_f32 v175, -v113, v159, v114
	v_fmac_f32_e32 v158, v174, v142
	v_fma_f32 v109, -v109, v157, v110
	v_cndmask_b32_e64 v106, v92, v106, s[22:23]
	v_add_f32_e32 v105, 1.0, v105
	v_div_scale_f32 v120, s[22:23], v13, v98, v13
	v_div_scale_f32 v131, s[0:1], v104, v104, v11
	v_rcp_f32_e32 v151, v129
	v_fma_f32 v163, -v121, v147, 1.0
	v_fmac_f32_e32 v146, v162, v146
	v_mul_f32_e32 v161, v118, v145
	v_fma_f32 v176, -v115, v160, v116
	v_fmac_f32_e32 v159, v175, v143
	v_fma_f32 v110, -v111, v158, v112
	v_div_fmas_f32 v109, v109, v141, v157
	s_mov_b64 vcc, s[30:31]
	v_add_f32_e32 v106, 1.0, v106
	v_div_scale_f32 v122, s[20:21], v14, v99, v14
	v_div_scale_f32 v133, s[0:1], v105, v105, v4
	v_rcp_f32_e32 v152, v131
	v_fma_f32 v164, -v123, v148, 1.0
	v_fmac_f32_e32 v147, v163, v147
	v_mul_f32_e32 v162, v120, v146
	v_fma_f32 v177, -v117, v161, v118
	v_fmac_f32_e32 v160, v176, v144
	v_fma_f32 v111, -v113, v159, v114
	v_div_fixup_f32 v28, v109, v93, v28
	v_div_fmas_f32 v93, v110, v142, v158
	s_mov_b64 vcc, s[28:29]
	v_add_f32_e32 v107, 1.0, v107
	v_div_scale_f32 v124, s[18:19], v15, v100, v15
	v_div_scale_f32 v135, s[0:1], v106, v106, v5
	v_rcp_f32_e32 v153, v133
	v_fma_f32 v165, -v125, v149, 1.0
	v_fmac_f32_e32 v148, v164, v148
	v_mul_f32_e32 v163, v122, v147
	v_fma_f32 v178, -v119, v162, v120
	v_fmac_f32_e32 v161, v177, v145
	v_fma_f32 v112, -v115, v160, v116
	s_waitcnt vmcnt(0) lgkmcnt(0)
; __global__ void __launch_bounds__(NTHR, 2) mk_fwd(Args args) {
;     ...
;                 for (int kk = 0; kk < 64; ++kk) { const float cv = cp[kk]; const float sv = cv / (1.0f + expf(-cv)); acc += *(const f32x4*)(wp + (size_t)kk * NMOD) * sv; }
;                 *(f32x4*)(p_modp + (size_t)sl * NMOD + col) = acc; } }
	v_pk_fma_f32 v[0:1], v[80:81], v[28:29], v[0:1] op_sel_hi:[1,0,1]
	v_pk_fma_f32 v[2:3], v[82:83], v[28:29], v[2:3] op_sel_hi:[1,0,1]
	v_div_fixup_f32 v28, v93, v94, v29
	v_div_fmas_f32 v29, v111, v143, v159
	s_mov_b64 vcc, s[26:27]
	v_add_f32_e32 v108, 1.0, v108
	v_div_scale_f32 v126, s[16:17], v8, v101, v8
	v_div_scale_f32 v137, s[0:1], v107, v107, v6
	v_rcp_f32_e32 v154, v135
	v_fma_f32 v166, -v127, v150, 1.0
	v_fmac_f32_e32 v149, v165, v149
	v_mul_f32_e32 v164, v124, v148
	v_fma_f32 v179, -v121, v163, v122
	v_fmac_f32_e32 v162, v178, v146
	v_fma_f32 v113, -v117, v161, v118
	v_pk_fma_f32 v[2:3], v[78:79], v[28:29], v[2:3] op_sel_hi:[1,0,1]
	v_pk_fma_f32 v[0:1], v[76:77], v[28:29], v[0:1] op_sel_hi:[1,0,1]
	v_div_fixup_f32 v28, v29, v95, v30
	v_div_fmas_f32 v29, v112, v144, v160
	s_mov_b64 vcc, s[24:25]
	v_div_scale_f32 v128, s[14:15], v9, v102, v9
	v_div_scale_f32 v139, s[0:1], v108, v108, v7
	v_rcp_f32_e32 v155, v137
	v_fma_f32 v167, -v129, v151, 1.0
	v_fmac_f32_e32 v150, v166, v150
	v_mul_f32_e32 v165, v126, v149
	v_fma_f32 v180, -v123, v164, v124
	v_fmac_f32_e32 v163, v179, v147
	v_fma_f32 v114, -v119, v162, v120
	v_pk_fma_f32 v[0:1], v[72:73], v[28:29], v[0:1] op_sel_hi:[1,0,1]
	v_pk_fma_f32 v[2:3], v[74:75], v[28:29], v[2:3] op_sel_hi:[1,0,1]
	v_div_fixup_f32 v28, v29, v96, v31
	v_div_fmas_f32 v29, v113, v145, v161
	s_mov_b64 vcc, s[22:23]
	v_div_scale_f32 v130, s[12:13], v10, v103, v10
	v_rcp_f32_e32 v156, v139
	v_fma_f32 v168, -v131, v152, 1.0
	v_fmac_f32_e32 v151, v167, v151
	v_mul_f32_e32 v166, v128, v150
	v_fma_f32 v181, -v125, v165, v126
	v_fmac_f32_e32 v164, v180, v148
	v_fma_f32 v115, -v121, v163, v122
	v_pk_fma_f32 v[2:3], v[70:71], v[28:29], v[2:3] op_sel_hi:[1,0,1]
	v_pk_fma_f32 v[0:1], v[68:69], v[28:29], v[0:1] op_sel_hi:[1,0,1]
	v_div_fixup_f32 v12, v29, v97, v12
	v_div_fmas_f32 v28, v114, v146, v162
	s_mov_b64 vcc, s[20:21]
	v_div_scale_f32 v132, s[10:11], v11, v104, v11
	v_fma_f32 v169, -v133, v153, 1.0
	v_fmac_f32_e32 v152, v168, v152
	v_mul_f32_e32 v167, v130, v151
	v_fma_f32 v182, -v127, v166, v128
	v_fmac_f32_e32 v165, v181, v149
	v_fma_f32 v116, -v123, v164, v124
	v_pk_fma_f32 v[0:1], v[64:65], v[12:13], v[0:1] op_sel_hi:[1,0,1]
	v_pk_fma_f32 v[2:3], v[66:67], v[12:13], v[2:3] op_sel_hi:[1,0,1]
	v_div_fixup_f32 v12, v28, v98, v13
	v_div_fmas_f32 v13, v115, v147, v163
	s_mov_b64 vcc, s[18:19]
	v_div_scale_f32 v134, s[8:9], v4, v105, v4
	v_fma_f32 v170, -v135, v154, 1.0
	v_fmac_f32_e32 v153, v169, v153
	v_mul_f32_e32 v168, v132, v152
	v_fma_f32 v183, -v129, v167, v130
	v_fmac_f32_e32 v166, v182, v150
	v_fma_f32 v117, -v125, v165, v126
	v_pk_fma_f32 v[2:3], v[62:63], v[12:13], v[2:3] op_sel_hi:[1,0,1]
	v_pk_fma_f32 v[0:1], v[60:61], v[12:13], v[0:1] op_sel_hi:[1,0,1]
	v_div_fixup_f32 v12, v13, v99, v14
	v_div_fmas_f32 v13, v116, v148, v164
	s_mov_b64 vcc, s[16:17]
	v_div_scale_f32 v136, s[6:7], v5, v106, v5
	v_fma_f32 v171, -v137, v155, 1.0
	v_fmac_f32_e32 v154, v170, v154
	v_mul_f32_e32 v169, v134, v153
	v_fma_f32 v184, -v131, v168, v132
	v_fmac_f32_e32 v167, v183, v151
	v_fma_f32 v118, -v127, v166, v128
	v_pk_fma_f32 v[0:1], v[56:57], v[12:13], v[0:1] op_sel_hi:[1,0,1]
	v_pk_fma_f32 v[2:3], v[58:59], v[12:13], v[2:3] op_sel_hi:[1,0,1]
	v_div_fixup_f32 v12, v13, v100, v15
	v_div_fmas_f32 v13, v117, v149, v165
	s_mov_b64 vcc, s[14:15]
	v_div_scale_f32 v138, s[4:5], v6, v107, v6
	v_fma_f32 v172, -v139, v156, 1.0
	v_fmac_f32_e32 v155, v171, v155
	v_mul_f32_e32 v170, v136, v154
	v_fma_f32 v185, -v133, v169, v134
	v_fmac_f32_e32 v168, v184, v152
	v_fma_f32 v119, -v129, v167, v130
	v_pk_fma_f32 v[2:3], v[54:55], v[12:13], v[2:3] op_sel_hi:[1,0,1]
	v_pk_fma_f32 v[0:1], v[52:53], v[12:13], v[0:1] op_sel_hi:[1,0,1]
	v_div_fixup_f32 v8, v13, v101, v8
	v_div_fmas_f32 v12, v118, v150, v166
	s_mov_b64 vcc, s[12:13]
	v_div_scale_f32 v140, s[0:1], v7, v108, v7
	v_fmac_f32_e32 v156, v172, v156
	v_mul_f32_e32 v171, v138, v155
	v_fma_f32 v186, -v135, v170, v136
	v_fmac_f32_e32 v169, v185, v153
	v_fma_f32 v120, -v131, v168, v132
	v_pk_fma_f32 v[0:1], v[48:49], v[8:9], v[0:1] op_sel_hi:[1,0,1]
	v_pk_fma_f32 v[2:3], v[50:51], v[8:9], v[2:3] op_sel_hi:[1,0,1]
	v_div_fixup_f32 v8, v12, v102, v9
	v_div_fmas_f32 v9, v119, v151, v167
	s_mov_b64 vcc, s[10:11]
	v_mul_f32_e32 v172, v140, v156
	v_fma_f32 v187, -v137, v171, v138
	v_fmac_f32_e32 v170, v186, v154
	v_fma_f32 v121, -v133, v169, v134
	v_pk_fma_f32 v[2:3], v[46:47], v[8:9], v[2:3] op_sel_hi:[1,0,1]
	v_pk_fma_f32 v[0:1], v[44:45], v[8:9], v[0:1] op_sel_hi:[1,0,1]
	v_div_fmas_f32 v12, v120, v152, v168
	v_div_fixup_f32 v8, v9, v103, v10
	s_mov_b64 vcc, s[8:9]
	v_fma_f32 v188, -v139, v172, v140
	v_fmac_f32_e32 v171, v187, v155
	v_fma_f32 v122, -v135, v170, v136
	v_pk_fma_f32 v[0:1], v[40:41], v[8:9], v[0:1] op_sel_hi:[1,0,1]
	v_pk_fma_f32 v[2:3], v[42:43], v[8:9], v[2:3] op_sel_hi:[1,0,1]
	v_div_fixup_f32 v8, v12, v104, v11
	v_div_fmas_f32 v9, v121, v153, v169
	s_mov_b64 vcc, s[6:7]
	v_fmac_f32_e32 v172, v188, v156
	v_fma_f32 v123, -v137, v171, v138
	v_pk_fma_f32 v[2:3], v[34:35], v[8:9], v[2:3] op_sel_hi:[1,0,1]
	v_pk_fma_f32 v[0:1], v[32:33], v[8:9], v[0:1] op_sel_hi:[1,0,1]
	v_div_fixup_f32 v4, v9, v105, v4
	v_div_fmas_f32 v8, v122, v154, v170
	s_mov_b64 vcc, s[4:5]
	v_fma_f32 v124, -v139, v172, v140
	v_pk_fma_f32 v[0:1], v[24:25], v[4:5], v[0:1] op_sel_hi:[1,0,1]
	v_pk_fma_f32 v[2:3], v[26:27], v[4:5], v[2:3] op_sel_hi:[1,0,1]
	v_div_fixup_f32 v4, v8, v106, v5
	v_div_fmas_f32 v5, v123, v155, v171
	s_mov_b64 vcc, s[0:1]
	v_pk_fma_f32 v[2:3], v[22:23], v[4:5], v[2:3] op_sel_hi:[1,0,1]
	v_pk_fma_f32 v[0:1], v[20:21], v[4:5], v[0:1] op_sel_hi:[1,0,1]
	v_div_fixup_f32 v4, v5, v107, v6
	v_div_fmas_f32 v5, v124, v156, v172
	v_pk_fma_f32 v[0:1], v[16:17], v[4:5], v[0:1] op_sel_hi:[1,0,1]
	v_pk_fma_f32 v[2:3], v[18:19], v[4:5], v[2:3] op_sel_hi:[1,0,1]
	v_div_fixup_f32 v4, v5, v108, v7
	v_pk_fma_f32 v[2:3], v[38:39], v[4:5], v[2:3] op_sel_hi:[1,0,1]
	v_pk_fma_f32 v[0:1], v[36:37], v[4:5], v[0:1] op_sel_hi:[1,0,1]
	s_cbranch_scc0 .LBB0_110
	v_mov_b32_e32 v4, s59
	ds_read_b64 v[4:5], v4
	s_mul_hi_i32 s1, s60, 0x12000
	s_mul_i32 s60, s60, 0x12000
	s_waitcnt lgkmcnt(0)
	v_readfirstlane_b32 s0, v4
	v_readfirstlane_b32 s4, v5
	s_add_u32 s0, s0, s60
	s_addc_u32 s1, s4, s1
	v_lshl_add_u64 v[4:5], v[84:85], 2, s[0:1]
	v_add_co_u32_e32 v4, vcc, 0x100000, v4
	s_add_i32 s3, s3, s40
	s_nop 0
	v_addc_co_u32_e32 v5, vcc, 0, v5, vcc
	s_cmpk_gt_i32 s3, 0x8ff
	global_store_dwordx4 v[4:5], v[0:3], off
	s_cbranch_scc0 .LBB0_109

; __device__ __forceinline__ void tr_load(const TrItem& t, int lane, f32x4 (&r)[8]) {
;     const int nblk = t.N / 32, kb = t.item / nblk, nb = t.item % nblk;
;     const float* p = t.W + (size_t)(64 * kb + (lane >> 3)) * t.N + 32 * nb + (lane & 7) * 4;
; #pragma unroll
;     for (int i = 0; i < 8; ++i) r[i] = *(const f32x4*)(p + (size_t)(8 * i) * t.N);
; }
; __global__ void __launch_bounds__(NTHR, 2) mk_fwd(Args args) {
;     ...
;         if (gw < NTR) { TrItem cur, nxt; f32x4 ra[8], rb[8]; int it = gw; P0_DECODE(it, cur); tr_load(cur, lane, ra);
.LBB0_152:
	s_lshl_b32 s8, s93, 14
	s_add_i32 s11, s8, 0
	s_add_u32 s8, s7, s4
	s_addc_u32 s9, s10, s5
	s_lshr_b32 s4, s6, 5
	s_waitcnt lgkmcnt(0)
	v_cvt_f32_u32_e32 v0, s4
	s_sub_i32 s12, 0, s4
	s_abs_i32 s10, s3
	s_ashr_i32 s5, s3, 31
	v_rcp_iflag_f32_e32 v0, v0
	v_ashrrev_i32_e32 v76, 3, v88
	s_mov_b32 s7, 0
	v_mov_b32_e32 v65, 0
	v_mul_f32_e32 v0, 0x4f7ffffe, v0
	v_cvt_u32_f32_e32 v0, v0
	v_add_u32_e32 v77, 8, v76
	v_add_u32_e32 v78, 16, v76
	v_add_u32_e32 v79, 24, v76
	v_readfirstlane_b32 s13, v0
	s_mul_i32 s12, s12, s13
	s_mul_hi_u32 s12, s13, s12
	s_add_i32 s13, s13, s12
	s_mul_hi_u32 s12, s10, s13
	s_mul_i32 s13, s12, s4
	s_sub_i32 s10, s10, s13
	s_add_i32 s14, s12, 1
	s_sub_i32 s13, s10, s4
	s_cmp_ge_u32 s10, s4
	s_cselect_b32 s12, s14, s12
	s_cselect_b32 s10, s13, s10
	s_add_i32 s13, s12, 1
	s_cmp_ge_u32 s10, s4
	s_cselect_b32 s10, s13, s12
	s_xor_b32 s10, s10, s5
	s_sub_i32 s5, s10, s5
	s_mul_i32 s4, s5, s4
	v_lshl_add_u32 v0, s5, 6, v76
	s_sub_i32 s10, s3, s4
	v_ashrrev_i32_e32 v3, 31, v0
	v_mad_u64_u32 v[0:1], s[4:5], v0, s6, 0
	v_mov_b32_e32 v2, v1
	v_mad_u64_u32 v[2:3], s[4:5], v3, s6, v[2:3]
	v_mov_b32_e32 v1, v2
	v_lshl_add_u64 v[0:1], v[0:1], 2, s[0:1]
	s_lshl_b32 s0, s10, 5
	v_lshlrev_b32_e32 v2, 2, v88
	s_ashr_i32 s1, s0, 31
	v_and_b32_e32 v32, 28, v2
	v_lshl_add_u64 v[0:1], s[0:1], 2, v[0:1]
	v_lshlrev_b32_e32 v64, 2, v32
	v_lshl_add_u64 v[8:9], v[0:1], 0, v[64:65]
	s_lshl_b64 s[0:1], s[6:7], 5
	v_lshl_add_u64 v[10:11], v[8:9], 0, s[0:1]
	v_lshl_add_u64 v[16:17], v[10:11], 0, s[0:1]
	v_lshl_add_u64 v[18:19], v[16:17], 0, s[0:1]
	v_lshl_add_u64 v[24:25], v[18:19], 0, s[0:1]
	v_lshl_add_u64 v[26:27], v[24:25], 0, s[0:1]
	v_lshl_add_u64 v[34:35], v[26:27], 0, s[0:1]
	global_load_dwordx4 v[0:3], v[8:9], off
	global_load_dwordx4 v[4:7], v[10:11], off
	s_nop 0
	global_load_dwordx4 v[8:11], v[16:17], off
	global_load_dwordx4 v[12:15], v[18:19], off
	s_nop 0
	global_load_dwordx4 v[16:19], v[24:25], off
	global_load_dwordx4 v[20:23], v[26:27], off
	v_lshl_add_u64 v[36:37], v[34:35], 0, s[0:1]
	global_load_dwordx4 v[24:27], v[34:35], off
	global_load_dwordx4 v[28:31], v[36:37], off
	v_lshlrev_b32_e32 v34, 3, v88
	s_movk_i32 s0, 0x84
	v_and_b32_e32 v34, 56, v34
	v_add_u32_e32 v33, s11, v64
	v_mul_lo_u32 v35, v76, s0
	v_mul_u32_u24_e32 v36, 0x84, v34
	v_lshlrev_b32_e32 v37, 2, v76
	v_add3_u32 v80, s11, v36, v37
	v_and_b32_e32 v81, 31, v76
	v_and_b32_e32 v82, 31, v77
	v_and_b32_e32 v83, 31, v78
	v_and_b32_e32 v84, 31, v79
	s_add_i32 s22, 0, 0x20118
	s_add_i32 s23, 0, 0x20108
	s_add_i32 s24, 0, 0x20100
	s_add_i32 s25, 0, 0x200f8
	s_add_i32 s26, 0, 0x200e8
	s_add_i32 s27, 0, 0x200d0
	s_add_i32 s28, 0, 0x20050
	s_add_i32 s29, 0, 0x20040
	s_add_i32 s30, 0, 0x20038
	s_add_i32 s31, 0, 0x20030
	v_lshlrev_b32_e32 v66, 2, v32
	v_add_u32_e32 v85, v33, v35
	s_movk_i32 s36, 0xff00
	s_movk_i32 s37, 0x800
	s_movk_i32 s38, 0x7fff
	s_mov_b32 s39, 0xffff0000
	v_lshlrev_b32_e32 v64, 1, v34
	s_mov_b32 s40, s6
	s_mov_b32 s41, s72
	s_branch .LBB0_154

; __device__ __forceinline__ void tr_load(const TrItem& t, int lane, f32x4 (&r)[8]) {
;     const int nblk = t.N / 32, kb = t.item / nblk, nb = t.item % nblk;
;     const float* p = t.W + (size_t)(64 * kb + (lane >> 3)) * t.N + 32 * nb + (lane & 7) * 4;
; #pragma unroll
;     for (int i = 0; i < 8; ++i) r[i] = *(const f32x4*)(p + (size_t)(8 * i) * t.N);
; }
; __global__ void __launch_bounds__(NTHR, 2) mk_fwd(Args args) {
;     ...
;             for (;;) { const int itn = it + NGW; const bool has = itn < NTR;
;                 if (has) { P0_DECODE(itn, nxt); tr_load(nxt, lane, rb); }
.LBB0_188:
	s_add_u32 s14, s16, s4
	s_addc_u32 s15, s17, s5
	s_lshr_b32 s4, s6, 5
	s_waitcnt lgkmcnt(0)
	v_cvt_f32_u32_e32 v32, s4
	s_sub_i32 s17, 0, s4
	s_abs_i32 s16, s43
	s_ashr_i32 s5, s43, 31
	v_rcp_iflag_f32_e32 v32, v32
	v_mov_b32_e32 v67, v65
	v_mul_f32_e32 v32, 0x4f7ffffe, v32
	v_cvt_u32_f32_e32 v32, v32
	s_nop 0
	v_readfirstlane_b32 s18, v32
	s_mul_i32 s17, s17, s18
	s_mul_hi_u32 s17, s18, s17
	s_add_i32 s18, s18, s17
	s_mul_hi_u32 s17, s16, s18
	s_mul_i32 s18, s17, s4
	s_sub_i32 s16, s16, s18
	s_add_i32 s19, s17, 1
	s_sub_i32 s18, s16, s4
	s_cmp_ge_u32 s16, s4
	s_cselect_b32 s17, s19, s17
	s_cselect_b32 s16, s18, s16
	s_add_i32 s18, s17, 1
	s_cmp_ge_u32 s16, s4
	s_cselect_b32 s16, s18, s17
	s_xor_b32 s16, s16, s5
	s_sub_i32 s5, s16, s5
	s_mul_i32 s4, s5, s4
	v_lshl_add_u32 v32, s5, 6, v76
	s_sub_i32 s16, s43, s4
	v_ashrrev_i32_e32 v35, 31, v32
	v_mad_u64_u32 v[32:33], s[4:5], v32, s6, 0
	v_mov_b32_e32 v34, v33
	v_mad_u64_u32 v[34:35], s[4:5], v35, s6, v[34:35]
	v_mov_b32_e32 v33, v34
	v_lshl_add_u64 v[32:33], v[32:33], 2, s[0:1]
	s_lshl_b32 s0, s16, 5
	s_ashr_i32 s1, s0, 31
	v_lshl_add_u64 v[32:33], s[0:1], 2, v[32:33]
	v_lshl_add_u64 v[40:41], v[32:33], 0, v[66:67]
	s_lshl_b64 s[0:1], s[6:7], 5
	v_lshl_add_u64 v[42:43], v[40:41], 0, s[0:1]
	v_lshl_add_u64 v[48:49], v[42:43], 0, s[0:1]
	v_lshl_add_u64 v[50:51], v[48:49], 0, s[0:1]
	v_lshl_add_u64 v[56:57], v[50:51], 0, s[0:1]
	v_lshl_add_u64 v[58:59], v[56:57], 0, s[0:1]
	v_lshl_add_u64 v[68:69], v[58:59], 0, s[0:1]
	global_load_dwordx4 v[32:35], v[40:41], off
	global_load_dwordx4 v[36:39], v[42:43], off
	s_nop 0
	global_load_dwordx4 v[40:43], v[48:49], off
	global_load_dwordx4 v[44:47], v[50:51], off
	s_nop 0
	global_load_dwordx4 v[48:51], v[56:57], off
	global_load_dwordx4 v[52:55], v[58:59], off
	v_lshl_add_u64 v[70:71], v[68:69], 0, s[0:1]
	global_load_dwordx4 v[56:59], v[68:69], off
	global_load_dwordx4 v[60:63], v[70:71], off

; #define LAS __attribute__((address_space(3)))
; __device__ __forceinline__ unsigned pk2(float lo, float hi) { return f2bf(lo) | (f2bf(hi) << 16); }
; __device__ __forceinline__ void tr_store(const TrItem& t, int lane, const f32x4 (&r)[8], LAS float* scr) {
;     ...
;     for (int j = 0; j < 4; ++j) { const int n = (lane >> 3) + 8 * j; const LAS float* s = scr + (8 * c) * 33 + n;
;         v4u o; o.x = pk2(s[0 * 33], s[1 * 33]); o.y = pk2(s[2 * 33], s[3 * 33]); o.z = pk2(s[4 * 33], s[5 * 33]); o.w = pk2(s[6 * 33], s[7 * 33]);
;         const int nn = n0 + n; int drow = t.mode == 0 ? nn : ((nn >> 7) * 256 + (t.mode == 2 ? 128 : 0) + (nn & 127));
;         if (t.mode == 3) drow = nn < 2048 ? ((nn >> 8) * 256 + ((nn >> 5) & 1) * 128 + ((nn >> 6) & 3) * 32 + (nn & 31)) : nn;
;         *(v4u*)(t.WT + (size_t)drow * t.K + k0 + 8 * c) = o; }
.LBB0_194:
	s_waitcnt lgkmcnt(3)
	v_bfe_u32 v86, v74, 16, 1
	v_add3_u32 v74, v74, v86, s38
	v_bfe_u32 v86, v75, 16, 1
	v_lshrrev_b32_e32 v74, 16, v74
	v_add3_u32 v75, v75, v86, s38
	v_and_or_b32 v86, v75, s39, v74
	s_waitcnt lgkmcnt(2)
	v_bfe_u32 v74, v72, 16, 1
	v_add3_u32 v72, v72, v74, s38
	v_bfe_u32 v74, v73, 16, 1
	v_lshrrev_b32_e32 v72, 16, v72
	v_add3_u32 v73, v73, v74, s38
	v_and_or_b32 v87, v73, s39, v72
	s_waitcnt lgkmcnt(1)
	v_bfe_u32 v72, v70, 16, 1
	v_add3_u32 v70, v70, v72, s38
	v_bfe_u32 v72, v71, 16, 1
	v_lshrrev_b32_e32 v70, 16, v70
	v_add3_u32 v71, v71, v72, s38
	v_and_or_b32 v88, v71, s39, v70
	s_waitcnt lgkmcnt(0)
	v_bfe_u32 v70, v68, 16, 1
	v_add3_u32 v68, v68, v70, s38
	v_bfe_u32 v70, v69, 16, 1
	v_lshrrev_b32_e32 v68, 16, v68
	v_add3_u32 v69, v69, v70, s38
	s_lshl_b32 s16, s16, 6
	v_and_or_b32 v89, v69, s39, v68
	v_mad_i64_i32 v[68:69], s[4:5], v67, s21, 0
	s_ashr_i32 s17, s16, 31
	v_lshl_add_u64 v[68:69], v[68:69], 1, s[8:9]
	v_lshl_add_u64 v[68:69], s[16:17], 1, v[68:69]
	v_lshl_add_u64 v[68:69], v[68:69], 0, v[64:65]
	global_store_dwordx4 v[68:69], v[86:89], off
	ds_read2_b32 v[74:75], v80 offset0:8 offset1:41
	ds_read2_b32 v[72:73], v80 offset0:74 offset1:107
	ds_read2_b32 v[70:71], v80 offset0:140 offset1:173
	ds_read2_b32 v[68:69], v80 offset0:206 offset1:239
	v_cndmask_b32_e64 v67, 0, 1, s[18:19]
	v_cmp_ne_u32_e64 s[4:5], 1, v67
	s_andn2_b64 vcc, exec, s[18:19]
	v_add_u32_e32 v67, s46, v77
	s_cbranch_vccnz .LBB0_198
	v_cmp_gt_i32_e32 vcc, s37, v67
	s_and_saveexec_b64 s[18:19], vcc
	v_lshlrev_b32_e32 v86, 2, v67
	v_lshrrev_b32_e32 v87, 1, v67
	v_and_b32_e32 v86, 0x80, v86
	v_and_b32_e32 v87, 0x60, v87
	v_and_or_b32 v67, v67, s36, v82
	v_or3_b32 v67, v67, v86, v87
	s_or_b64 exec, exec, s[18:19]
	s_branch .LBB0_199

; #define LAS __attribute__((address_space(3)))
; __device__ __forceinline__ unsigned pk2(float lo, float hi) { return f2bf(lo) | (f2bf(hi) << 16); }
; __device__ __forceinline__ void tr_store(const TrItem& t, int lane, const f32x4 (&r)[8], LAS float* scr) {
;     ...
;     for (int j = 0; j < 4; ++j) { const int n = (lane >> 3) + 8 * j; const LAS float* s = scr + (8 * c) * 33 + n;
;         v4u o; o.x = pk2(s[0 * 33], s[1 * 33]); o.y = pk2(s[2 * 33], s[3 * 33]); o.z = pk2(s[4 * 33], s[5 * 33]); o.w = pk2(s[6 * 33], s[7 * 33]);
;         const int nn = n0 + n; int drow = t.mode == 0 ? nn : ((nn >> 7) * 256 + (t.mode == 2 ? 128 : 0) + (nn & 127));
;         if (t.mode == 3) drow = nn < 2048 ? ((nn >> 8) * 256 + ((nn >> 5) & 1) * 128 + ((nn >> 6) & 3) * 32 + (nn & 31)) : nn;
;         *(v4u*)(t.WT + (size_t)drow * t.K + k0 + 8 * c) = o; }
.LBB0_199:
	s_waitcnt lgkmcnt(0)
	v_bfe_u32 v86, v74, 16, 1
	v_add3_u32 v74, v74, v86, s38
	v_bfe_u32 v86, v75, 16, 1
	v_lshrrev_b32_e32 v74, 16, v74
	v_add3_u32 v75, v75, v86, s38
	v_and_or_b32 v86, v75, s39, v74
	v_bfe_u32 v74, v72, 16, 1
	v_add3_u32 v72, v72, v74, s38
	v_bfe_u32 v74, v73, 16, 1
	v_lshrrev_b32_e32 v72, 16, v72
	v_add3_u32 v73, v73, v74, s38
	v_and_or_b32 v87, v73, s39, v72
	v_bfe_u32 v72, v70, 16, 1
	v_add3_u32 v70, v70, v72, s38
	v_bfe_u32 v72, v71, 16, 1
	v_lshrrev_b32_e32 v70, 16, v70
	v_add3_u32 v71, v71, v72, s38
	v_and_or_b32 v88, v71, s39, v70
	v_bfe_u32 v70, v68, 16, 1
	v_add3_u32 v68, v68, v70, s38
	v_bfe_u32 v70, v69, 16, 1
	v_lshrrev_b32_e32 v68, 16, v68
	v_add3_u32 v69, v69, v70, s38
	v_and_or_b32 v89, v69, s39, v68
	v_mad_i64_i32 v[68:69], s[18:19], v67, s21, 0
	v_lshl_add_u64 v[68:69], v[68:69], 1, s[8:9]
	v_lshl_add_u64 v[68:69], s[16:17], 1, v[68:69]
	v_lshl_add_u64 v[68:69], v[68:69], 0, v[64:65]
	global_store_dwordx4 v[68:69], v[86:89], off
	ds_read2_b32 v[74:75], v80 offset0:16 offset1:49
	ds_read2_b32 v[72:73], v80 offset0:82 offset1:115
	ds_read2_b32 v[70:71], v80 offset0:148 offset1:181
	ds_read2_b32 v[68:69], v80 offset0:214 offset1:247
	s_and_b64 vcc, exec, s[4:5]
	v_add_u32_e32 v67, s46, v78
	s_cbranch_vccnz .LBB0_203
	v_cmp_gt_i32_e32 vcc, s37, v67
	s_and_saveexec_b64 s[18:19], vcc
	v_lshlrev_b32_e32 v86, 2, v67
	v_lshrrev_b32_e32 v87, 1, v67
	v_and_b32_e32 v86, 0x80, v86
	v_and_b32_e32 v87, 0x60, v87
	v_and_or_b32 v67, v67, s36, v83
	v_or3_b32 v67, v67, v86, v87
	s_or_b64 exec, exec, s[18:19]
	s_branch .LBB0_204

; #define LAS __attribute__((address_space(3)))
; __device__ __forceinline__ unsigned pk2(float lo, float hi) { return f2bf(lo) | (f2bf(hi) << 16); }
; __device__ __forceinline__ void tr_store(const TrItem& t, int lane, const f32x4 (&r)[8], LAS float* scr) {
;     ...
;     for (int j = 0; j < 4; ++j) { const int n = (lane >> 3) + 8 * j; const LAS float* s = scr + (8 * c) * 33 + n;
;         v4u o; o.x = pk2(s[0 * 33], s[1 * 33]); o.y = pk2(s[2 * 33], s[3 * 33]); o.z = pk2(s[4 * 33], s[5 * 33]); o.w = pk2(s[6 * 33], s[7 * 33]);
;         const int nn = n0 + n; int drow = t.mode == 0 ? nn : ((nn >> 7) * 256 + (t.mode == 2 ? 128 : 0) + (nn & 127));
;         if (t.mode == 3) drow = nn < 2048 ? ((nn >> 8) * 256 + ((nn >> 5) & 1) * 128 + ((nn >> 6) & 3) * 32 + (nn & 31)) : nn;
;         *(v4u*)(t.WT + (size_t)drow * t.K + k0 + 8 * c) = o; }
.LBB0_204:
	s_waitcnt lgkmcnt(0)
	v_bfe_u32 v86, v74, 16, 1
	v_add3_u32 v74, v74, v86, s38
	v_bfe_u32 v86, v75, 16, 1
	v_lshrrev_b32_e32 v74, 16, v74
	v_add3_u32 v75, v75, v86, s38
	v_and_or_b32 v86, v75, s39, v74
	v_bfe_u32 v74, v72, 16, 1
	v_add3_u32 v72, v72, v74, s38
	v_bfe_u32 v74, v73, 16, 1
	v_lshrrev_b32_e32 v72, 16, v72
	v_add3_u32 v73, v73, v74, s38
	v_and_or_b32 v87, v73, s39, v72
	v_bfe_u32 v72, v70, 16, 1
	v_add3_u32 v70, v70, v72, s38
	v_bfe_u32 v72, v71, 16, 1
	v_lshrrev_b32_e32 v70, 16, v70
	v_add3_u32 v71, v71, v72, s38
	v_and_or_b32 v88, v71, s39, v70
	v_bfe_u32 v70, v68, 16, 1
	v_add3_u32 v68, v68, v70, s38
	v_bfe_u32 v70, v69, 16, 1
	v_lshrrev_b32_e32 v68, 16, v68
	v_add3_u32 v69, v69, v70, s38
	v_and_or_b32 v89, v69, s39, v68
	v_mad_i64_i32 v[68:69], s[18:19], v67, s21, 0
	v_lshl_add_u64 v[68:69], v[68:69], 1, s[8:9]
	v_lshl_add_u64 v[68:69], s[16:17], 1, v[68:69]
	v_lshl_add_u64 v[68:69], v[68:69], 0, v[64:65]
	global_store_dwordx4 v[68:69], v[86:89], off
	ds_read2_b32 v[74:75], v80 offset0:24 offset1:57
	ds_read2_b32 v[72:73], v80 offset0:90 offset1:123
	ds_read2_b32 v[70:71], v80 offset0:156 offset1:189
	ds_read2_b32 v[68:69], v80 offset0:222 offset1:255
	s_and_b64 vcc, exec, s[4:5]
	v_add_u32_e32 v67, s46, v79
	s_cbranch_vccnz .LBB0_208
	v_cmp_gt_i32_e32 vcc, s37, v67
	s_and_saveexec_b64 s[0:1], vcc
	v_lshlrev_b32_e32 v86, 2, v67
	v_lshrrev_b32_e32 v87, 1, v67
	v_and_b32_e32 v86, 0x80, v86
	v_and_b32_e32 v87, 0x60, v87
	v_and_or_b32 v67, v67, s36, v84
	v_or3_b32 v67, v67, v86, v87
	s_or_b64 exec, exec, s[0:1]
	s_branch .LBB0_209

; #define LAS __attribute__((address_space(3)))
; #define LDS_WAIT() asm volatile("s_waitcnt lgkmcnt(0)" ::: "memory")
; __device__ __forceinline__ unsigned pk2(float lo, float hi) { return f2bf(lo) | (f2bf(hi) << 16); }
; __device__ __forceinline__ void tr_store(const TrItem& t, int lane, const f32x4 (&r)[8], LAS float* scr) {
;     ...
;     for (int j = 0; j < 4; ++j) { const int n = (lane >> 3) + 8 * j; const LAS float* s = scr + (8 * c) * 33 + n;
;         v4u o; o.x = pk2(s[0 * 33], s[1 * 33]); o.y = pk2(s[2 * 33], s[3 * 33]); o.z = pk2(s[4 * 33], s[5 * 33]); o.w = pk2(s[6 * 33], s[7 * 33]);
;         const int nn = n0 + n; int drow = t.mode == 0 ? nn : ((nn >> 7) * 256 + (t.mode == 2 ? 128 : 0) + (nn & 127));
;         if (t.mode == 3) drow = nn < 2048 ? ((nn >> 8) * 256 + ((nn >> 5) & 1) * 128 + ((nn >> 6) & 3) * 32 + (nn & 31)) : nn;
;         *(v4u*)(t.WT + (size_t)drow * t.K + k0 + 8 * c) = o; }
;     LDS_WAIT(); asm volatile("" ::: "memory");
; __global__ void __launch_bounds__(NTHR, 2) mk_fwd(Args args) {
;     ...
;                 if (!has) break;
;                 it = itn; cur = nxt;
; #pragma unroll
;                 for (int i = 0; i < 8; ++i) ra[i] = rb[i]; } }
.LBB0_209:
	s_waitcnt lgkmcnt(0)
	v_bfe_u32 v86, v75, 16, 1
	v_add3_u32 v75, v75, v86, s38
	v_bfe_u32 v86, v74, 16, 1
	v_add3_u32 v74, v74, v86, s38
	v_lshrrev_b32_e32 v74, 16, v74
	v_and_or_b32 v86, v75, s39, v74
	v_bfe_u32 v74, v73, 16, 1
	v_add3_u32 v73, v73, v74, s38
	v_bfe_u32 v74, v72, 16, 1
	v_add3_u32 v72, v72, v74, s38
	v_lshrrev_b32_e32 v72, 16, v72
	v_and_or_b32 v87, v73, s39, v72
	v_bfe_u32 v72, v71, 16, 1
	v_add3_u32 v71, v71, v72, s38
	v_bfe_u32 v72, v70, 16, 1
	v_add3_u32 v70, v70, v72, s38
	v_lshrrev_b32_e32 v70, 16, v70
	v_and_or_b32 v88, v71, s39, v70
	v_bfe_u32 v70, v69, 16, 1
	v_add3_u32 v69, v69, v70, s38
	v_bfe_u32 v70, v68, 16, 1
	v_add3_u32 v68, v68, v70, s38
	v_lshrrev_b32_e32 v68, 16, v68
	v_and_or_b32 v89, v69, s39, v68
	v_mad_i64_i32 v[68:69], s[0:1], v67, s21, 0
	v_lshl_add_u64 v[68:69], v[68:69], 1, s[8:9]
	v_lshl_add_u64 v[68:69], s[16:17], 1, v[68:69]
	v_lshl_add_u64 v[68:69], v[68:69], 0, v[64:65]
	global_store_dwordx4 v[68:69], v[86:89], off
	s_waitcnt lgkmcnt(0)
	s_andn2_b64 vcc, exec, s[12:13]
	s_cbranch_vccnz .LBB0_153
	v_mov_b64_e32 v[0:1], v[32:33]
	v_mov_b64_e32 v[4:5], v[36:37]
	v_mov_b64_e32 v[8:9], v[40:41]
	v_mov_b64_e32 v[12:13], v[44:45]
	v_mov_b64_e32 v[16:17], v[48:49]
	v_mov_b64_e32 v[20:21], v[52:53]
	v_mov_b64_e32 v[24:25], v[56:57]
	v_mov_b64_e32 v[28:29], v[60:61]
	v_mov_b64_e32 v[2:3], v[34:35]
	v_mov_b64_e32 v[6:7], v[38:39]
	v_mov_b64_e32 v[10:11], v[42:43]
	v_mov_b64_e32 v[14:15], v[46:47]
	v_mov_b64_e32 v[18:19], v[50:51]
	v_mov_b64_e32 v[22:23], v[54:55]
	v_mov_b64_e32 v[26:27], v[58:59]
	v_mov_b64_e32 v[30:31], v[62:63]
	s_mov_b64 s[8:9], s[14:15]
	s_mov_b32 s21, s45
	s_mov_b32 s40, s6
	s_mov_b32 s20, s44
	s_mov_b32 s3, s43
	s_mov_b32 s41, s42
	s_branch .LBB0_153

; __device__ __forceinline__ unsigned xb_ld(unsigned* p)              { return __hip_atomic_load(p, __ATOMIC_RELAXED, __HIP_MEMORY_SCOPE_AGENT); }
; __device__ __forceinline__ void xcd_barrier_complete(unsigned* bar, unsigned x, unsigned& nloc, unsigned& nx) {
;     const unsigned G = gridDim.x * gridDim.y * gridDim.z;
;     unsigned sum, cnt, mine, sp = 0u;
;     for (;;) {
;         sum = 0u; cnt = 0u; mine = 0u;
; #pragma unroll
;         for (unsigned j = 0; j < 16; ++j) { const unsigned c = xb_ld(&bar[XB_XCNT(j)]); sum += c; cnt += (c > 0u) ? 1u : 0u; mine = (j == x) ? c : mine; }
;         if (sum == G) break;
;         __builtin_amdgcn_s_sleep(1);
;         if ((++sp & 255u) == 0u) { if (xb_ld(&bar[XB_TMO])) break; if (sp > XB_SPIN_CAP) { atomicAdd(&bar[XB_TMO], 1u); break; } }
;     }
;     nloc = mine > 0u ? mine : 1u; nx = cnt > 0u ? cnt : 1u;
; }
.LBB0_220:
	global_load_dword v25, v[0:1], off offset:1024 sc1
	global_load_dword v10, v[0:1], off offset:1280 sc1
	global_load_dword v11, v[0:1], off offset:1536 sc1
	global_load_dword v12, v[0:1], off offset:1792 sc1
	global_load_dword v13, v[0:1], off offset:2048 sc1
	global_load_dword v14, v[0:1], off offset:2304 sc1
	global_load_dword v15, v[0:1], off offset:2560 sc1
	global_load_dword v16, v[0:1], off offset:2816 sc1
	global_load_dword v17, v[0:1], off offset:3072 sc1
	global_load_dword v18, v[0:1], off offset:3328 sc1
	global_load_dword v19, v[0:1], off offset:3584 sc1
	global_load_dword v20, v[0:1], off offset:3840 sc1
	global_load_dword v21, v[2:3], off sc1
	global_load_dword v22, v[4:5], off sc1
	global_load_dword v23, v[6:7], off sc1
	global_load_dword v24, v[8:9], off sc1
	s_or_b64 s[8:9], s[8:9], exec
	s_or_b64 s[6:7], s[6:7], exec
	s_waitcnt vmcnt(0) lgkmcnt(0)
	v_add_u32_e32 v26, v10, v25
	v_add_u32_e32 v26, v26, v11
	v_add_u32_e32 v26, v26, v12
	v_add_u32_e32 v26, v26, v13
	v_add_u32_e32 v26, v26, v14
	v_add_u32_e32 v26, v26, v15
	v_add_u32_e32 v26, v26, v16
	v_add_u32_e32 v26, v26, v17
	v_add_u32_e32 v26, v26, v18
	v_add_u32_e32 v26, v26, v19
	v_add_u32_e32 v26, v26, v20
	v_add_u32_e32 v26, v26, v21
	v_add_u32_e32 v26, v26, v22
	v_add_u32_e32 v26, v26, v23
	v_add_u32_e32 v26, v26, v24
	v_cmp_ne_u32_e32 vcc, s20, v26
	s_and_saveexec_b64 s[10:11], vcc
	s_cbranch_execz .LBB0_219
	s_and_b32 s14, s21, 0xff
	s_mov_b64 s[12:13], -1
	s_cmp_eq_u32 s14, 0
	s_mov_b64 s[16:17], -1
	s_mov_b64 s[14:15], -1
	s_sleep 1
	s_cbranch_scc1 .LBB0_223
	s_and_saveexec_b64 s[18:19], s[16:17]
	s_cbranch_execz .LBB0_218
	s_branch .LBB0_226
.LBB0_223:
	global_load_dword v26, v[0:1], off offset:512 sc1
	s_mov_b64 s[16:17], 0
	s_waitcnt vmcnt(0) lgkmcnt(0)
	v_cmp_eq_u32_e32 vcc, 0, v26
	s_and_saveexec_b64 s[18:19], vcc
	s_cmp_lt_u32 s21, 0x400001
	s_cselect_b64 s[16:17], -1, 0
	s_xor_b64 s[14:15], exec, -1
	s_and_b64 s[16:17], s[16:17], exec
	s_or_b64 exec, exec, s[18:19]
	s_and_saveexec_b64 s[18:19], s[16:17]
	s_cbranch_execz .LBB0_218

; __device__ __forceinline__ unsigned xb_ld(unsigned* p)              { return __hip_atomic_load(p, __ATOMIC_RELAXED, __HIP_MEMORY_SCOPE_AGENT); }
; __device__ __forceinline__ void xcd_barrier_complete(unsigned* bar, unsigned x, unsigned& nloc, unsigned& nx) {
;     ...
;         if ((++sp & 255u) == 0u) { if (xb_ld(&bar[XB_TMO])) break; if (sp > XB_SPIN_CAP) { atomicAdd(&bar[XB_TMO], 1u); break; } }
.LBB0_227:
	s_or_b64 exec, exec, s[0:1]
	s_xor_b64 s[0:1], s[4:5], -1
	s_and_saveexec_b64 s[4:5], s[0:1]
	s_xor_b64 s[0:1], exec, s[4:5]
	s_cbranch_execz .LBB0_229
	v_mov_b32_e32 v2, 1
	v_mov_b64_e32 v[0:1], s[38:39]
	global_atomic_add v[0:1], v2, off offset:512

; __device__ __forceinline__ unsigned xb_ld(unsigned* p)              { return __hip_atomic_load(p, __ATOMIC_RELAXED, __HIP_MEMORY_SCOPE_AGENT); }
; __device__ __forceinline__ unsigned xb_add(unsigned* p, unsigned v) { return __hip_atomic_fetch_add(p, v, __ATOMIC_RELAXED, __HIP_MEMORY_SCOPE_AGENT); }
; #define XB_SPIN(cond, bar) do { unsigned _sp = 0; while (cond) { __builtin_amdgcn_s_sleep(1); \
;     if ((++_sp & 255u) == 0u) { if (xb_ld(&(bar)[XB_TMO])) break; if (_sp > XB_SPIN_CAP) { atomicAdd(&(bar)[XB_TMO], 1u); break; } } } } while (0)
; __device__ __forceinline__ void xcd_barrier(unsigned* bar, volatile LAS unsigned* st, bool lead) {
;     ...
;         const unsigned old = xb_add(&bar[XB_XSUB(x)], 1u);
;         const unsigned gen = old / nloc;
;         if (old + 1u == (gen + 1u) * nloc) {
;             __builtin_amdgcn_fence(__ATOMIC_RELEASE, "agent");
;             asm volatile("s_waitcnt vmcnt(0)" ::: "memory");
;             const unsigned og = xb_add(&bar[XB_TOP], 1u);
;             const unsigned tg = og / nx;
;             if (og + 1u == (tg + 1u) * nx) xb_add(&bar[XB_TOPGEN], 1u);
;             else XB_SPIN(xb_ld(&bar[XB_TOPGEN]) == tg, bar);
;             __builtin_amdgcn_fence(__ATOMIC_ACQUIRE, "agent");
;             xb_add(&bar[XB_XGEN(x)], 1u);
;             asm volatile("s_waitcnt vmcnt(0)" ::: "memory");
;         } else {
;             XB_SPIN(xb_ld(&bar[XB_XGEN(x)]) == gen, bar);
.LBB0_230:
	s_lshl_b32 s0, s3, 8
	s_add_u32 s22, s38, s0
	s_addc_u32 s3, s39, 0
	v_mov_b32_e32 v1, s22
	v_add_co_u32_e32 v4, vcc, 0x1000, v1
	v_mov_b32_e32 v1, s3
	s_nop 0
	v_addc_co_u32_e32 v5, vcc, 0, v1, vcc
	v_mov_b32_e32 v1, 1
	global_atomic_add v1, v[4:5], v1, off offset:1024 sc0
	v_cvt_f32_u32_e32 v3, v2
	v_sub_u32_e32 v4, 0, v2
	v_rcp_iflag_f32_e32 v3, v3
	s_nop 0
	v_mul_f32_e32 v3, 0x4f7ffffe, v3
	v_cvt_u32_f32_e32 v3, v3
	v_mul_lo_u32 v4, v4, v3
	v_mul_hi_u32 v4, v3, v4
	v_add_u32_e32 v3, v3, v4
	s_waitcnt vmcnt(0) lgkmcnt(0)
	v_mul_hi_u32 v3, v1, v3
	v_mul_lo_u32 v5, v3, v2
	v_add_u32_e32 v4, 1, v1
	v_sub_u32_e32 v1, v1, v5
	v_add_u32_e32 v6, 1, v3
	v_cmp_ge_u32_e32 vcc, v1, v2
	v_sub_u32_e32 v5, v1, v2
	s_nop 0
	v_cndmask_b32_e32 v3, v3, v6, vcc
	v_cndmask_b32_e32 v1, v1, v5, vcc
	v_add_u32_e32 v5, 1, v3
	v_cmp_ge_u32_e32 vcc, v1, v2
	s_nop 1
	v_cndmask_b32_e32 v1, v3, v5, vcc
	v_mad_u64_u32 v[2:3], s[0:1], v2, v1, v[2:3]
	v_cmp_ne_u32_e32 vcc, v4, v2
	s_and_saveexec_b64 s[0:1], vcc
	s_xor_b64 s[0:1], exec, s[0:1]
	s_cbranch_execz .LBB0_243
	v_mov_b32_e32 v0, s22
	v_add_co_u32_e32 v2, vcc, 0x2000, v0
	v_mov_b32_e32 v0, s3
	s_nop 0
	v_addc_co_u32_e32 v3, vcc, 0, v0, vcc
	global_load_dword v0, v[2:3], off offset:1024 sc1
	s_add_u32 s6, s22, 0x2400
	s_addc_u32 s7, s3, 0
	s_waitcnt vmcnt(0) lgkmcnt(0)
	v_cmp_eq_u32_e32 vcc, v0, v1
	s_and_saveexec_b64 s[4:5], vcc
	s_cbranch_execz .LBB0_242
	s_mov_b32 s23, 1
	s_mov_b64 s[8:9], 0
	s_branch .LBB0_234

; __device__ __forceinline__ unsigned xb_ld(unsigned* p)              { return __hip_atomic_load(p, __ATOMIC_RELAXED, __HIP_MEMORY_SCOPE_AGENT); }
; #define XB_SPIN(cond, bar) do { unsigned _sp = 0; while (cond) { __builtin_amdgcn_s_sleep(1); \
;     if ((++_sp & 255u) == 0u) { if (xb_ld(&(bar)[XB_TMO])) break; if (_sp > XB_SPIN_CAP) { atomicAdd(&(bar)[XB_TMO], 1u); break; } } } } while (0)
; __device__ __forceinline__ void xcd_barrier(unsigned* bar, volatile LAS unsigned* st, bool lead) {
;     ...
;             XB_SPIN(xb_ld(&bar[XB_XGEN(x)]) == gen, bar);
.LBB0_234:
	s_and_b32 s16, s23, 0xff
	s_mov_b64 s[14:15], -1
	s_cmp_lg_u32 s16, 0
	s_mov_b64 s[16:17], -1
	s_sleep 1
	s_cbranch_scc1 .LBB0_238
	v_mov_b64_e32 v[2:3], s[38:39]
	global_load_dword v0, v[2:3], off offset:512 sc1
	s_mov_b64 s[16:17], 0
	s_mov_b64 s[18:19], -1
	s_waitcnt vmcnt(0) lgkmcnt(0)
	v_cmp_eq_u32_e32 vcc, 0, v0
	s_and_saveexec_b64 s[20:21], vcc
	s_cmp_lt_u32 s23, 0x400001
	s_cselect_b64 s[16:17], -1, 0
	s_xor_b64 s[18:19], exec, -1
	s_and_b64 s[16:17], s[16:17], exec
	s_or_b64 exec, exec, s[20:21]
.LBB0_238:
	s_andn2_b64 s[12:13], s[12:13], exec
	s_and_b64 s[18:19], s[18:19], exec
	s_or_b64 s[12:13], s[12:13], s[18:19]
	s_and_saveexec_b64 s[18:19], s[16:17]
	s_cbranch_execz .LBB0_233
	v_mov_b64_e32 v[2:3], s[6:7]
	global_load_dword v0, v[2:3], off sc1
	s_add_i32 s23, s23, 1
	s_or_b64 s[12:13], s[12:13], exec
	s_waitcnt vmcnt(0) lgkmcnt(0)
	v_cmp_ne_u32_e32 vcc, v0, v1
	s_orn2_b64 s[14:15], vcc, exec
	s_branch .LBB0_233
.LBB0_240:
	s_or_b64 exec, exec, s[8:9]
	s_xor_b64 s[6:7], s[10:11], -1
	s_and_saveexec_b64 s[8:9], s[6:7]
	s_xor_b64 s[8:9], exec, s[8:9]
	s_cbranch_execz .LBB0_242
	v_mov_b32_e32 v2, 1
	v_mov_b64_e32 v[0:1], s[38:39]
	global_atomic_add v[0:1], v2, off offset:512

; __device__ __forceinline__ unsigned xb_ld(unsigned* p)              { return __hip_atomic_load(p, __ATOMIC_RELAXED, __HIP_MEMORY_SCOPE_AGENT); }
; __device__ __forceinline__ unsigned xb_add(unsigned* p, unsigned v) { return __hip_atomic_fetch_add(p, v, __ATOMIC_RELAXED, __HIP_MEMORY_SCOPE_AGENT); }
; #define XB_SPIN(cond, bar) do { unsigned _sp = 0; while (cond) { __builtin_amdgcn_s_sleep(1); \
;     if ((++_sp & 255u) == 0u) { if (xb_ld(&(bar)[XB_TMO])) break; if (_sp > XB_SPIN_CAP) { atomicAdd(&(bar)[XB_TMO], 1u); break; } } } } while (0)
; __device__ __forceinline__ void xcd_barrier(unsigned* bar, volatile LAS unsigned* st, bool lead) {
;     ...
;         if (old + 1u == (gen + 1u) * nloc) {
;             __builtin_amdgcn_fence(__ATOMIC_RELEASE, "agent");
;             asm volatile("s_waitcnt vmcnt(0)" ::: "memory");
;             const unsigned og = xb_add(&bar[XB_TOP], 1u);
;             const unsigned tg = og / nx;
;             if (og + 1u == (tg + 1u) * nx) xb_add(&bar[XB_TOPGEN], 1u);
;             else XB_SPIN(xb_ld(&bar[XB_TOPGEN]) == tg, bar);
.LBB0_243:
	s_andn2_saveexec_b64 s[0:1], s[0:1]
	s_cbranch_execz .LBB0_259
	v_mov_b32_e32 v1, s38
	v_add_co_u32_e32 v2, vcc, 0x3000, v1
	v_mov_b32_e32 v1, s39
	buffer_wbl2 sc1
	s_waitcnt vmcnt(0)
	v_addc_co_u32_e32 v3, vcc, 0, v1, vcc
	v_mov_b32_e32 v1, 1
	global_atomic_add v1, v[2:3], v1, off offset:1024 sc0
	v_cvt_f32_u32_e32 v2, v0
	v_sub_u32_e32 v3, 0, v0
	s_add_u32 s0, s38, 0x3500
	s_addc_u32 s1, s39, 0
	v_rcp_iflag_f32_e32 v2, v2
	s_mov_b64 s[6:7], -1
	v_mul_f32_e32 v2, 0x4f7ffffe, v2
	v_cvt_u32_f32_e32 v2, v2
	v_mul_lo_u32 v3, v3, v2
	v_mul_hi_u32 v3, v2, v3
	v_add_u32_e32 v2, v2, v3
	s_waitcnt vmcnt(0) lgkmcnt(0)
	v_mul_hi_u32 v2, v1, v2
	v_mul_lo_u32 v4, v2, v0
	v_add_u32_e32 v3, 1, v1
	v_sub_u32_e32 v1, v1, v4
	v_add_u32_e32 v5, 1, v2
	v_cmp_ge_u32_e32 vcc, v1, v0
	v_sub_u32_e32 v4, v1, v0
	s_nop 0
	v_cndmask_b32_e32 v2, v2, v5, vcc
	v_cndmask_b32_e32 v1, v1, v4, vcc
	v_add_u32_e32 v4, 1, v2
	v_cmp_ge_u32_e32 vcc, v1, v0
	s_nop 1
	v_cndmask_b32_e32 v2, v2, v4, vcc
	v_mad_u64_u32 v[0:1], s[4:5], v0, v2, v[0:1]
	v_cmp_ne_u32_e32 vcc, v3, v0
	v_mov_b64_e32 v[0:1], s[0:1]
	s_and_saveexec_b64 s[4:5], vcc
	s_cbranch_execz .LBB0_256
	v_mov_b64_e32 v[0:1], s[0:1]
	global_load_dword v0, v[0:1], off sc1
	s_mov_b64 s[10:11], 0
	s_waitcnt vmcnt(0) lgkmcnt(0)
	v_cmp_eq_u32_e32 vcc, v0, v2
	s_and_saveexec_b64 s[8:9], vcc
	s_cbranch_execz .LBB0_255
	s_add_u32 s6, s38, 0x200
	s_addc_u32 s7, s39, 0
	s_mov_b32 s23, 1
	s_branch .LBB0_248

; __device__ __forceinline__ unsigned xb_ld(unsigned* p)              { return __hip_atomic_load(p, __ATOMIC_RELAXED, __HIP_MEMORY_SCOPE_AGENT); }
; #define XB_SPIN(cond, bar) do { unsigned _sp = 0; while (cond) { __builtin_amdgcn_s_sleep(1); \
;     if ((++_sp & 255u) == 0u) { if (xb_ld(&(bar)[XB_TMO])) break; if (_sp > XB_SPIN_CAP) { atomicAdd(&(bar)[XB_TMO], 1u); break; } } } } while (0)
; __device__ __forceinline__ void xcd_barrier(unsigned* bar, volatile LAS unsigned* st, bool lead) {
;     ...
;             else XB_SPIN(xb_ld(&bar[XB_TOPGEN]) == tg, bar);
.LBB0_250:
	v_mov_b64_e32 v[0:1], s[6:7]
	global_load_dword v0, v[0:1], off sc1
	s_mov_b64 s[16:17], 0
	s_mov_b64 s[14:15], -1
	s_waitcnt vmcnt(0) lgkmcnt(0)
	v_cmp_eq_u32_e32 vcc, 0, v0
	s_and_saveexec_b64 s[18:19], vcc
	s_cmp_lt_u32 s23, 0x400001
	s_cselect_b64 s[16:17], -1, 0
	s_xor_b64 s[14:15], exec, -1
	s_and_b64 s[16:17], s[16:17], exec
	s_or_b64 exec, exec, s[18:19]
	s_mov_b64 s[18:19], -1
	s_and_saveexec_b64 s[20:21], s[16:17]
	s_cbranch_execz .LBB0_247
.LBB0_253:
	v_mov_b64_e32 v[0:1], s[0:1]
	global_load_dword v0, v[0:1], off sc1
	s_add_i32 s23, s23, 1
	s_or_b64 s[14:15], s[14:15], exec
	s_waitcnt vmcnt(0) lgkmcnt(0)
	v_cmp_ne_u32_e32 vcc, v0, v2
	s_orn2_b64 s[18:19], vcc, exec
	s_branch .LBB0_247

; __device__ __forceinline__ unsigned xb_ld(unsigned* p)              { return __hip_atomic_load(p, __ATOMIC_RELAXED, __HIP_MEMORY_SCOPE_AGENT); }
; __device__ __forceinline__ unsigned xb_add(unsigned* p, unsigned v) { return __hip_atomic_fetch_add(p, v, __ATOMIC_RELAXED, __HIP_MEMORY_SCOPE_AGENT); }
; #define XB_SPIN(cond, bar) do { unsigned _sp = 0; while (cond) { __builtin_amdgcn_s_sleep(1); \
;     if ((++_sp & 255u) == 0u) { if (xb_ld(&(bar)[XB_TMO])) break; if (_sp > XB_SPIN_CAP) { atomicAdd(&(bar)[XB_TMO], 1u); break; } } } } while (0)
; __device__ __forceinline__ void xcd_barrier(unsigned* bar, volatile LAS unsigned* st, bool lead) {
;     ...
;             if (og + 1u == (tg + 1u) * nx) xb_add(&bar[XB_TOPGEN], 1u);
;             else XB_SPIN(xb_ld(&bar[XB_TOPGEN]) == tg, bar);
;             __builtin_amdgcn_fence(__ATOMIC_ACQUIRE, "agent");
;             xb_add(&bar[XB_XGEN(x)], 1u);
;             asm volatile("s_waitcnt vmcnt(0)" ::: "memory");
.LBB0_256:
	s_or_b64 exec, exec, s[4:5]
	s_and_saveexec_b64 s[0:1], s[6:7]
	s_cbranch_execz .LBB0_258
	v_mov_b32_e32 v2, 1
	global_atomic_add v[0:1], v2, off
.LBB0_258:
	s_or_b64 exec, exec, s[0:1]
	v_mov_b32_e32 v0, s22
	v_add_co_u32_e32 v0, vcc, 0x2000, v0
	v_mov_b32_e32 v1, s3
	s_nop 0
	v_addc_co_u32_e32 v1, vcc, 0, v1, vcc
	v_mov_b32_e32 v2, 1
	s_waitcnt vmcnt(0) lgkmcnt(0)
	buffer_inv sc1
	global_atomic_add v[0:1], v2, off offset:1024
	s_waitcnt vmcnt(0)

; #define INP(k) ((const float*)ldptr(L, (k)))
; #define p_b_ada INP(4)
; __global__ void __launch_bounds__(NTHR, 2) mk_fwd(Args args) {
;     ...
;         for (int j = bx * NTHR + tid; j < NMOD; j += G * NTHR) { float s = p_b_ada[j];
; #pragma unroll
;             for (int sl = 0; sl < 32; ++sl) s += p_modp[(size_t)sl * NMOD + j];
;             const int seg = j / DMODEL; p_mod[j] = (seg == 2 || seg == 8) ? 0.5f * s : s;
;             if (seg == 4) p_GM[j - 4 * DMODEL] = INP(9)[j - 4 * DMODEL] * (1.0f + s);
.LBB0_265:
	s_waitcnt lgkmcnt(0)
	v_readfirstlane_b32 s0, v2
	v_readfirstlane_b32 s1, v3
	s_nop 1
	v_lshl_add_u64 v[10:11], s[0:1], 0, v[6:7]
	v_add_co_u32_e32 v10, vcc, 0xffdf2000, v10
	v_readfirstlane_b32 s0, v4
	s_nop 0
	v_addc_co_u32_e32 v11, vcc, -1, v11, vcc
	v_readfirstlane_b32 s1, v5
	global_load_dword v1, v[10:11], off
	s_nop 0
	v_lshl_add_u64 v[10:11], s[0:1], 0, v[6:7]
	v_add_co_u32_e32 v12, vcc, 0xffef2000, v10
	s_nop 1
	v_addc_co_u32_e32 v13, vcc, -1, v11, vcc
	v_add_co_u32_e32 v14, vcc, 0xfff04000, v10
	s_nop 1
	v_addc_co_u32_e32 v15, vcc, -1, v11, vcc
	v_add_co_u32_e32 v16, vcc, 0xfff16000, v10
	s_nop 1
	v_addc_co_u32_e32 v17, vcc, -1, v11, vcc
	v_add_co_u32_e32 v18, vcc, 0xfff28000, v10
	s_nop 1
	v_addc_co_u32_e32 v19, vcc, -1, v11, vcc
	v_add_co_u32_e32 v20, vcc, 0xfff3a000, v10
	s_nop 1
	v_addc_co_u32_e32 v21, vcc, -1, v11, vcc
	v_add_co_u32_e32 v22, vcc, 0xfff4c000, v10
	s_nop 1
	v_addc_co_u32_e32 v23, vcc, -1, v11, vcc
	v_add_co_u32_e32 v24, vcc, 0xfff5e000, v10
	s_nop 1
	v_addc_co_u32_e32 v25, vcc, -1, v11, vcc
	v_add_co_u32_e32 v26, vcc, 0xfff70000, v10
	s_nop 1
	v_addc_co_u32_e32 v27, vcc, -1, v11, vcc
	v_add_co_u32_e32 v28, vcc, 0xfff82000, v10
	s_nop 1
	v_addc_co_u32_e32 v29, vcc, -1, v11, vcc
	v_add_co_u32_e32 v30, vcc, 0xfff94000, v10
	s_nop 1
	v_addc_co_u32_e32 v31, vcc, -1, v11, vcc
	v_add_co_u32_e32 v32, vcc, 0xfffa6000, v10
	s_nop 1
	v_addc_co_u32_e32 v33, vcc, -1, v11, vcc
	v_add_co_u32_e32 v34, vcc, 0xfffb8000, v10
	s_nop 1
	v_addc_co_u32_e32 v35, vcc, -1, v11, vcc
	v_add_co_u32_e32 v36, vcc, 0xfffca000, v10
	s_nop 1
	v_addc_co_u32_e32 v37, vcc, -1, v11, vcc
	v_add_co_u32_e32 v38, vcc, 0xfffdc000, v10
	s_nop 1
	v_addc_co_u32_e32 v39, vcc, -1, v11, vcc
	v_add_co_u32_e32 v40, vcc, 0xfffee000, v10
	s_nop 1
	v_addc_co_u32_e32 v41, vcc, -1, v11, vcc
	global_load_dword v8, v[26:27], off
	global_load_dword v42, v[28:29], off
	global_load_dword v43, v[30:31], off
	global_load_dword v44, v[32:33], off
	global_load_dword v45, v[34:35], off
	global_load_dword v46, v[36:37], off
	global_load_dword v47, v[38:39], off
	global_load_dword v48, v[40:41], off
	global_load_dword v49, v[12:13], off
	global_load_dword v50, v[14:15], off
	global_load_dword v51, v[16:17], off
	global_load_dword v52, v[18:19], off
	global_load_dword v53, v[20:21], off
	global_load_dword v54, v[22:23], off
	global_load_dword v55, v[24:25], off
	global_load_dword v28, v[10:11], off
	v_add_co_u32_e32 v12, vcc, 0x12000, v10
	s_waitcnt vmcnt(0) lgkmcnt(0)
	v_add_f32_e32 v1, v1, v49
	v_addc_co_u32_e32 v13, vcc, 0, v11, vcc
	v_add_co_u32_e32 v14, vcc, 0x24000, v10
	v_add_f32_e32 v1, v1, v50
	s_nop 0
	v_addc_co_u32_e32 v15, vcc, 0, v11, vcc
	v_add_co_u32_e32 v16, vcc, 0x36000, v10
	v_add_f32_e32 v1, v1, v51
	s_nop 0
	v_addc_co_u32_e32 v17, vcc, 0, v11, vcc
	v_add_co_u32_e32 v18, vcc, 0x48000, v10
	v_add_f32_e32 v1, v1, v52
	s_nop 0
	v_addc_co_u32_e32 v19, vcc, 0, v11, vcc
	v_add_co_u32_e32 v20, vcc, 0x5a000, v10
	v_add_f32_e32 v1, v1, v53
	s_nop 0
	v_addc_co_u32_e32 v21, vcc, 0, v11, vcc
	v_add_co_u32_e32 v22, vcc, 0x6c000, v10
	v_add_f32_e32 v1, v1, v54
	s_nop 0
	v_addc_co_u32_e32 v23, vcc, 0, v11, vcc
	v_add_co_u32_e32 v24, vcc, 0x7e000, v10
	v_add_f32_e32 v1, v1, v55
	s_nop 0
	v_addc_co_u32_e32 v25, vcc, 0, v11, vcc
	v_add_co_u32_e32 v26, vcc, 0x90000, v10
	v_add_f32_e32 v1, v1, v8
	s_nop 0
	v_addc_co_u32_e32 v27, vcc, 0, v11, vcc
	global_load_dword v29, v[12:13], off
	global_load_dword v30, v[14:15], off
	global_load_dword v31, v[16:17], off
	global_load_dword v32, v[18:19], off
	global_load_dword v33, v[20:21], off
	global_load_dword v34, v[22:23], off
	global_load_dword v35, v[24:25], off
	global_load_dword v36, v[26:27], off
	v_add_co_u32_e32 v12, vcc, 0xa2000, v10
	v_add_f32_e32 v1, v1, v42
	s_nop 0
	v_addc_co_u32_e32 v13, vcc, 0, v11, vcc
	v_add_co_u32_e32 v14, vcc, 0xb4000, v10
	v_add_f32_e32 v1, v1, v43
	s_nop 0
	v_addc_co_u32_e32 v15, vcc, 0, v11, vcc
	v_add_co_u32_e32 v16, vcc, 0xc6000, v10
	v_add_f32_e32 v1, v1, v44
	s_nop 0
	v_addc_co_u32_e32 v17, vcc, 0, v11, vcc
	v_add_co_u32_e32 v18, vcc, 0xd8000, v10
	v_add_f32_e32 v1, v1, v45
	s_nop 0
	v_addc_co_u32_e32 v19, vcc, 0, v11, vcc
	v_add_co_u32_e32 v20, vcc, 0xea000, v10
	v_add_f32_e32 v1, v1, v46
	s_nop 0
	v_addc_co_u32_e32 v21, vcc, 0, v11, vcc
	v_add_co_u32_e32 v22, vcc, 0xfc000, v10
	v_add_f32_e32 v1, v1, v47
	s_nop 0
	v_addc_co_u32_e32 v23, vcc, 0, v11, vcc
	v_add_co_u32_e32 v24, vcc, 0x10e000, v10
	v_add_f32_e32 v1, v1, v48
	s_nop 0
	v_addc_co_u32_e32 v25, vcc, 0, v11, vcc
	v_add_co_u32_e32 v26, vcc, 0x120000, v10
	v_add_f32_e32 v1, v1, v28
	s_nop 0
	v_addc_co_u32_e32 v27, vcc, 0, v11, vcc
	global_load_dword v37, v[12:13], off
	global_load_dword v38, v[14:15], off
	global_load_dword v39, v[16:17], off
	global_load_dword v40, v[18:19], off
	global_load_dword v41, v[20:21], off
	global_load_dword v56, v[22:23], off
	global_load_dword v57, v[24:25], off
	global_load_dword v58, v[26:27], off
	s_waitcnt vmcnt(0) lgkmcnt(0)
	v_add_f32_e32 v1, v1, v29
	v_add_f32_e32 v1, v1, v30
	v_add_f32_e32 v1, v1, v31
	v_add_f32_e32 v1, v1, v32
	v_add_f32_e32 v1, v1, v33
	v_add_f32_e32 v1, v1, v34
	v_add_f32_e32 v1, v1, v35
	v_add_f32_e32 v1, v1, v36
	v_add_f32_e32 v1, v1, v37
	v_add_f32_e32 v1, v1, v38
	v_add_f32_e32 v1, v1, v39
	v_add_f32_e32 v1, v1, v40
	v_add_f32_e32 v1, v1, v41
	v_add_f32_e32 v1, v1, v56
	v_add_f32_e32 v1, v1, v57
	v_add_f32_e32 v12, v1, v58
	v_and_b32_e32 v1, 0xfffff800, v0
	v_cmp_eq_u32_e32 vcc, s3, v1
	v_cmp_eq_u32_e64 s[0:1], s9, v1
	v_mul_f32_e32 v8, 0.5, v12
	s_or_b64 vcc, vcc, s[0:1]
	v_cndmask_b32_e32 v8, v12, v8, vcc
	v_add_co_u32_e32 v10, vcc, 0x1f2000, v10
	s_nop 1
	v_addc_co_u32_e32 v11, vcc, 0, v11, vcc
	v_cmp_lt_i32_e32 vcc, s16, v1
	global_store_dword v[10:11], v8, off
	s_and_saveexec_b64 s[0:1], vcc
	s_xor_b64 s[0:1], exec, s[0:1]
	s_cbranch_execz .LBB0_269
	v_cmp_eq_u32_e32 vcc, s17, v1
	s_and_saveexec_b64 s[14:15], vcc
	s_cbranch_execz .LBB0_268
	v_mov_b32_e32 v1, s18
	ds_read_b64 v[10:11], v1
	v_mov_b32_e32 v1, v9
	v_lshlrev_b64 v[14:15], 2, v[0:1]
	v_add_f32_e32 v8, 1.0, v12
	s_waitcnt lgkmcnt(0)
	v_readfirstlane_b32 s22, v10
	v_readfirstlane_b32 s23, v11
	s_nop 1
	v_lshl_add_u64 v[10:11], s[22:23], 0, v[14:15]
	v_add_co_u32_e32 v10, vcc, 0xffff2000, v10
	v_readfirstlane_b32 s22, v4
	s_nop 0
	v_addc_co_u32_e32 v11, vcc, -1, v11, vcc
	global_load_dword v1, v[10:11], off
	v_readfirstlane_b32 s23, v5
	s_waitcnt vmcnt(0) lgkmcnt(0)
	v_mul_f32_e32 v1, v8, v1
	v_lshl_add_u64 v[10:11], s[22:23], 0, v[14:15]
	v_add_co_u32_e32 v10, vcc, 0x8f4000, v10
	s_nop 1
	v_addc_co_u32_e32 v11, vcc, 0, v11, vcc
	global_store_dword v[10:11], v1, off

; #define INP(k) ((const float*)ldptr(L, (k)))
; __global__ void __launch_bounds__(NTHR, 2) mk_fwd(Args args) {
;     ...
;             if (seg == 7) p_GM[DMODEL + j - 7 * DMODEL] = INP(30)[j - 7 * DMODEL] * (1.0f + s); }
.LBB0_269:
	s_andn2_saveexec_b64 s[0:1], s[0:1]
	s_cbranch_execz .LBB0_264
	v_cmp_eq_u32_e32 vcc, s19, v1
	s_and_saveexec_b64 s[14:15], vcc
	s_cbranch_execz .LBB0_263
	v_mov_b32_e32 v1, s20
	ds_read_b64 v[10:11], v1
	v_add_u32_e32 v8, 0xffffe000, v0
	v_lshlrev_b64 v[14:15], 2, v[8:9]
	v_add_f32_e32 v8, 1.0, v12
	s_waitcnt lgkmcnt(0)
	v_readfirstlane_b32 s22, v10
	v_readfirstlane_b32 s23, v11
	s_nop 1
	v_lshl_add_u64 v[10:11], s[22:23], 0, v[14:15]
	global_load_dword v1, v[10:11], off
	v_readfirstlane_b32 s22, v4
	v_readfirstlane_b32 s23, v5
	s_waitcnt vmcnt(0) lgkmcnt(0)
	v_mul_f32_e32 v1, v8, v1
	v_lshl_add_u64 v[10:11], s[22:23], 0, v[14:15]
	v_add_co_u32_e32 v10, vcc, 0x900000, v10
	s_nop 1
	v_addc_co_u32_e32 v11, vcc, 0, v11, vcc
	global_store_dword v[10:11], v1, off
	s_branch .LBB0_263

; __device__ __forceinline__ int lane_asm() { int l; asm volatile("v_mbcnt_lo_u32_b32 %0, -1, 0\n\tv_mbcnt_hi_u32_b32 %0, -1, %0" : "=v"(l)); return l; }
; __device__ __forceinline__ unsigned pk2(float lo, float hi) { return f2bf(lo) | (f2bf(hi) << 16); }
; #define INP(k) ((const float*)ldptr(L, (k)))
; #define p_x INP(0)
; __device__ __forceinline__ void norm_load2(const float* X, int r0, int r1, int lane, f32x4 (&v)[2][8]) {
;     const f32x4* x0 = (const f32x4*)(X + (size_t)(r0 < M ? r0 : 0) * DMODEL) + lane; const f32x4* x1 = (const f32x4*)(X + (size_t)(r1 < M ? r1 : 0) * DMODEL) + lane;
; #pragma unroll
;     for (int j = 0; j < 8; ++j) { v[0][j] = x0[64 * j]; v[1][j] = x1[64 * j]; }
; }
; __device__ __forceinline__ void norm_store2(bf16* O, int r0, int r1, int lane, const f32x4 (&v)[2][8], const f32x4 (&gm)[8], const f32x4 (&hs)[8]) {
; #pragma unroll
;     for (int q = 0; q < 2; ++q) { const int r = q == 0 ? r0 : r1; float s = 0.f;
; #pragma unroll
;         for (int j = 0; j < 8; ++j) s += (v[q][j].x * v[q][j].x + v[q][j].y * v[q][j].y) + (v[q][j].z * v[q][j].z + v[q][j].w * v[q][j].w);
;         const float rstd = 1.0f / sqrtf(wave_sum(s) * (1.0f / DMODEL) + 1e-6f);
;         if (r < M) { bf16* orow = O + (size_t)r * DMODEL;
; #pragma unroll
;             for (int j = 0; j < 8; ++j) { const f32x4 y = (v[q][j] * rstd) * gm[j] + hs[j]; v2u o; o.x = pk2(y.x, y.y); o.y = pk2(y.z, y.w); *(v2u*)(orow + 4 * (lane + 64 * j)) = o; } } }
; }
; __device__ __forceinline__ void norm_mod_pass(const float* X, const float* gam, const float* sc, const float* sh, bf16* O, int gw, int NGW, int lane) {
;     f32x4 va[2][8], vb[2][8];
;     norm_load2(X, gw, gw + NGW, lane, va);
;     f32x4 gm[8], hs[8];
; #pragma unroll
;     for (int j = 0; j < 8; ++j) { const int col = 4 * (lane + 64 * j); gm[j] = *(const f32x4*)(gam + col) * (*(const f32x4*)(sc + col) + 1.0f); hs[j] = *(const f32x4*)(sh + col); }
; __global__ void __launch_bounds__(NTHR, 2) mk_fwd(Args args) {
;     ...
;     if (IN(2)) { const int lane = lane_asm(), tid = wave * 64 + lane; (void)tid; norm_mod_pass(p_x, INP(5), p_mod + 1 * DMODEL, p_mod + 0 * DMODEL, p_HB, gw, NGW, lane);
.LBB0_321:
	s_cmp_lt_i32 s68, 3
	s_cselect_b64 s[0:1], -1, 0
	s_and_b64 s[6:7], s[0:1], s[34:35]
	s_andn2_b64 vcc, exec, s[6:7]
	s_cbranch_vccnz .LBB0_360
	s_add_i32 s0, 0, 0x20000
	v_mov_b32_e32 v0, s0
	s_add_i32 s0, 0, 0x20028
	v_mov_b32_e32 v2, s0
	s_add_i32 s0, 0, 0x20118
	v_mov_b32_e32 v4, s0
	v_mbcnt_lo_u32_b32 v160, -1, 0
	v_mbcnt_hi_u32_b32 v160, -1, v160
	ds_read_b64 v[0:1], v0
	ds_read_b64 v[2:3], v2
	ds_read_b64 v[4:5], v4
	s_cmpk_gt_i32 s72, 0x3fff
	v_ashrrev_i32_e32 v161, 31, v160
	s_waitcnt lgkmcnt(0)
	v_readfirstlane_b32 s4, v0
	v_readfirstlane_b32 s5, v1
	v_readfirstlane_b32 s8, v2
	v_readfirstlane_b32 s9, v3
	v_readfirstlane_b32 s0, v4
	v_readfirstlane_b32 s1, v5
	s_mul_i32 s3, s70, 24
	s_cbranch_scc1 .LBB0_331
	v_lshlrev_b32_e32 v96, 2, v160
	s_add_u32 s10, s0, 0x402000
	v_ashrrev_i32_e32 v97, 31, v96
	s_addc_u32 s11, s1, 0
	v_lshlrev_b64 v[0:1], 2, v[96:97]
	v_lshl_add_u64 v[4:5], s[10:11], 0, v[0:1]
	global_load_dwordx4 v[36:39], v[4:5], off
	v_add_u32_e32 v4, 0x100, v96
	v_ashrrev_i32_e32 v5, 31, v4
	v_lshlrev_b64 v[4:5], 2, v[4:5]
	v_lshl_add_u64 v[6:7], s[10:11], 0, v[4:5]
	global_load_dwordx4 v[40:43], v[6:7], off
	v_add_u32_e32 v6, 0x200, v96
	v_ashrrev_i32_e32 v7, 31, v6
	v_lshlrev_b64 v[6:7], 2, v[6:7]
	v_lshl_add_u64 v[8:9], s[10:11], 0, v[6:7]
	global_load_dwordx4 v[44:47], v[8:9], off
	v_add_u32_e32 v8, 0x300, v96
	v_ashrrev_i32_e32 v9, 31, v8
	v_lshlrev_b64 v[8:9], 2, v[8:9]
	v_lshl_add_u64 v[10:11], s[10:11], 0, v[8:9]
	global_load_dwordx4 v[48:51], v[10:11], off
	v_add_u32_e32 v10, 0x400, v96
	v_ashrrev_i32_e32 v11, 31, v10
	v_lshl_add_u64 v[2:3], s[8:9], 0, v[0:1]
	v_lshlrev_b64 v[10:11], 2, v[10:11]
	global_load_dwordx4 v[32:35], v[2:3], off
	v_lshl_add_u64 v[12:13], s[10:11], 0, v[10:11]
	global_load_dwordx4 v[52:55], v[12:13], off
	global_load_dwordx4 v[88:91], v[2:3], off offset:1024
	v_add_u32_e32 v12, 0x500, v96
	v_add_u32_e32 v14, 0x600, v96
	v_ashrrev_i32_e32 v13, 31, v12
	v_add_u32_e32 v16, 0x700, v96
	v_ashrrev_i32_e32 v15, 31, v14
	v_lshlrev_b64 v[12:13], 2, v[12:13]
	v_ashrrev_i32_e32 v17, 31, v16
	v_lshlrev_b64 v[14:15], 2, v[14:15]
	v_lshl_add_u64 v[20:21], s[10:11], 0, v[12:13]
	v_lshlrev_b64 v[16:17], 2, v[16:17]
	global_load_dwordx4 v[98:101], v[2:3], off offset:2048
	global_load_dwordx4 v[108:111], v[2:3], off offset:3072
	v_lshl_add_u64 v[2:3], s[8:9], 0, v[10:11]
	v_lshl_add_u64 v[18:19], s[8:9], 0, v[12:13]
	v_lshl_add_u64 v[24:25], s[10:11], 0, v[14:15]
	global_load_dwordx4 v[116:119], v[20:21], off
	v_lshl_add_u64 v[22:23], s[8:9], 0, v[14:15]
	v_lshl_add_u64 v[26:27], s[10:11], 0, v[16:17]
	global_load_dwordx4 v[112:115], v[2:3], off
	global_load_dwordx4 v[120:123], v[18:19], off
	global_load_dwordx4 v[124:127], v[24:25], off
	global_load_dwordx4 v[132:135], v[26:27], off
	v_lshl_add_u64 v[2:3], s[8:9], 0, v[16:17]
	global_load_dwordx4 v[128:131], v[22:23], off
	global_load_dwordx4 v[136:139], v[2:3], off
	s_add_u32 s12, s0, 0x400000
	s_addc_u32 s13, s1, 0
	s_add_i32 s8, s80, s72
	s_cmpk_lt_i32 s8, 0x4000
	s_cselect_b32 s8, s8, 0
	s_ashr_i32 s9, s8, 31
	s_lshl_b64 s[8:9], s[8:9], 13
	s_add_u32 s8, s4, s8
	v_lshlrev_b64 v[102:103], 4, v[160:161]
	v_lshl_add_u64 v[56:57], s[12:13], 0, v[0:1]
	v_lshl_add_u64 v[60:61], s[12:13], 0, v[6:7]
	s_addc_u32 s9, s5, s9
	s_ashr_i32 s73, s72, 31
	v_lshl_add_u64 v[58:59], s[12:13], 0, v[4:5]
	v_lshl_add_u64 v[62:63], s[12:13], 0, v[8:9]
	v_lshl_add_u64 v[64:65], s[12:13], 0, v[10:11]
	v_lshl_add_u64 v[66:67], s[12:13], 0, v[12:13]
	v_lshl_add_u64 v[68:69], s[12:13], 0, v[14:15]
	v_lshl_add_u64 v[70:71], s[12:13], 0, v[16:17]
	global_load_dwordx4 v[0:3], v[56:57], off
	global_load_dwordx4 v[4:7], v[58:59], off
	global_load_dwordx4 v[8:11], v[60:61], off
	global_load_dwordx4 v[12:15], v[62:63], off
	global_load_dwordx4 v[16:19], v[64:65], off
	global_load_dwordx4 v[20:23], v[66:67], off
	global_load_dwordx4 v[24:27], v[68:69], off
	global_load_dwordx4 v[28:31], v[70:71], off
	v_lshl_add_u64 v[60:61], s[8:9], 0, v[102:103]
	s_lshl_b64 s[8:9], s[72:73], 13
	s_movk_i32 s22, 0x1000
	s_add_u32 s8, s4, s8
	s_addc_u32 s9, s5, s9
	v_lshlrev_b64 v[196:197], 1, v[96:97]
	v_lshl_add_u64 v[194:195], s[4:5], 0, v[102:103]
	s_lshl_b32 s4, s70, 5
	s_mul_i32 s23, s70, 40
	s_lshl_b32 s26, s70, 4
	s_add_i32 s23, s23, s33
	s_add_i32 s24, s4, s33
	v_mov_b32_e32 v206, 0x358637bd
	s_waitcnt vmcnt(0) lgkmcnt(0)
; __device__ __forceinline__ float wave_sum(float v) {
; #pragma unroll
;     for (int o = 1; o < 64; o <<= 1) v += __shfl_xor(v, o);
;     return v;
; }
; __device__ __forceinline__ void norm_load2(const float* X, int r0, int r1, int lane, f32x4 (&v)[2][8]) {
;     const f32x4* x0 = (const f32x4*)(X + (size_t)(r0 < M ? r0 : 0) * DMODEL) + lane; const f32x4* x1 = (const f32x4*)(X + (size_t)(r1 < M ? r1 : 0) * DMODEL) + lane;
; #pragma unroll
;     for (int j = 0; j < 8; ++j) { v[0][j] = x0[64 * j]; v[1][j] = x1[64 * j]; }
; }
; __device__ __forceinline__ void norm_mod_pass(const float* X, const float* gam, const float* sc, const float* sh, bf16* O, int gw, int NGW, int lane) {
;     f32x4 va[2][8], vb[2][8];
;     norm_load2(X, gw, gw + NGW, lane, va);
;     f32x4 gm[8], hs[8];
; #pragma unroll
;     for (int j = 0; j < 8; ++j) { const int col = 4 * (lane + 64 * j); gm[j] = *(const f32x4*)(gam + col) * (*(const f32x4*)(sc + col) + 1.0f); hs[j] = *(const f32x4*)(sh + col); }
	v_pk_add_f32 v[36:37], v[36:37], 1.0 op_sel_hi:[1,0]
	v_pk_add_f32 v[38:39], v[38:39], 1.0 op_sel_hi:[1,0]
	s_mov_b32 s27, 0xf800000
	v_mov_b32_e32 v207, 0x260
	s_movk_i32 s28, 0x7fff
	v_pk_add_f32 v[140:141], v[40:41], 1.0 op_sel_hi:[1,0]
	s_mov_b32 s29, 0xffff0000
	s_mov_b32 s30, 0xc600000
	s_mov_b32 s31, s93
	v_pk_add_f32 v[142:143], v[46:47], 1.0 op_sel_hi:[1,0]
	v_pk_add_f32 v[144:145], v[44:45], 1.0 op_sel_hi:[1,0]
	v_pk_add_f32 v[148:149], v[48:49], 1.0 op_sel_hi:[1,0]
	v_add_co_u32_e32 v48, vcc, s22, v60
	v_pk_add_f32 v[146:147], v[50:51], 1.0 op_sel_hi:[1,0]
	s_nop 0
	v_addc_co_u32_e32 v49, vcc, 0, v61, vcc
	v_pk_mul_f32 v[164:165], v[32:33], v[36:37]
	v_pk_add_f32 v[32:33], v[42:43], 1.0 op_sel_hi:[1,0]
	v_pk_mul_f32 v[162:163], v[34:35], v[38:39]
	v_pk_mul_f32 v[166:167], v[90:91], v[32:33]
	v_lshl_add_u64 v[90:91], s[8:9], 0, v[102:103]
	v_add_co_u32_e32 v50, vcc, s22, v90
	v_pk_add_f32 v[150:151], v[54:55], 1.0 op_sel_hi:[1,0]
	s_nop 0
	v_addc_co_u32_e32 v51, vcc, 0, v91, vcc
	v_pk_add_f32 v[152:153], v[52:53], 1.0 op_sel_hi:[1,0]
	global_load_dwordx4 v[32:35], v[48:49], off offset:3072
	global_load_dwordx4 v[36:39], v[48:49], off offset:2048
	global_load_dwordx4 v[40:43], v[48:49], off offset:1024
	global_load_dwordx4 v[44:47], v[48:49], off
	global_load_dwordx4 v[64:67], v[50:51], off offset:3072
	global_load_dwordx4 v[68:71], v[50:51], off offset:2048
	global_load_dwordx4 v[72:75], v[50:51], off offset:1024
	global_load_dwordx4 v[76:79], v[50:51], off
	s_nop 0
	global_load_dwordx4 v[48:51], v[60:61], off offset:3072
	global_load_dwordx4 v[52:55], v[60:61], off offset:2048
	global_load_dwordx4 v[56:59], v[60:61], off offset:1024
	s_nop 0
	global_load_dwordx4 v[60:63], v[60:61], off
	s_nop 0
	global_load_dwordx4 v[80:83], v[90:91], off offset:3072
	global_load_dwordx4 v[84:87], v[90:91], off offset:2048
	global_load_dwordx4 v[92:95], v[90:91], off offset:1024
	global_load_dwordx4 v[104:107], v[90:91], off
	v_pk_mul_f32 v[168:169], v[88:89], v[140:141]
	s_mov_b64 s[8:9], 0xc600000
	v_pk_mul_f32 v[170:171], v[100:101], v[142:143]
	v_pk_mul_f32 v[172:173], v[98:99], v[144:145]
	v_pk_add_f32 v[88:89], v[118:119], 1.0 op_sel_hi:[1,0]
	v_pk_add_f32 v[90:91], v[116:117], 1.0 op_sel_hi:[1,0]
	v_pk_mul_f32 v[174:175], v[110:111], v[146:147]
	v_pk_mul_f32 v[176:177], v[108:109], v[148:149]
	v_pk_mul_f32 v[182:183], v[122:123], v[88:89]
	v_pk_add_f32 v[88:89], v[126:127], 1.0 op_sel_hi:[1,0]
	v_pk_mul_f32 v[184:185], v[120:121], v[90:91]
	v_pk_add_f32 v[90:91], v[124:125], 1.0 op_sel_hi:[1,0]
	v_pk_mul_f32 v[186:187], v[130:131], v[88:89]
	v_pk_add_f32 v[88:89], v[134:135], 1.0 op_sel_hi:[1,0]
	v_pk_mul_f32 v[188:189], v[128:129], v[90:91]
	v_pk_mul_f32 v[190:191], v[138:139], v[88:89]
	v_mbcnt_lo_u32_b32 v88, -1, 0
	v_mbcnt_hi_u32_b32 v88, -1, v88
	v_pk_add_f32 v[90:91], v[132:133], 1.0 op_sel_hi:[1,0]
	v_and_b32_e32 v89, 64, v88
	v_pk_mul_f32 v[192:193], v[136:137], v[90:91]
	v_add_u32_e32 v89, 64, v89
	v_xor_b32_e32 v90, 1, v88
	v_cmp_lt_i32_e32 vcc, v90, v89
	v_pk_mul_f32 v[178:179], v[114:115], v[150:151]
	v_pk_mul_f32 v[180:181], v[112:113], v[152:153]
	v_cndmask_b32_e32 v90, v88, v90, vcc
	v_lshlrev_b32_e32 v200, 2, v90
	v_xor_b32_e32 v90, 2, v88
	v_cmp_lt_i32_e32 vcc, v90, v89
	s_nop 1
	v_cndmask_b32_e32 v90, v88, v90, vcc
	v_lshlrev_b32_e32 v201, 2, v90
	v_xor_b32_e32 v90, 4, v88
	v_cmp_lt_i32_e32 vcc, v90, v89
	s_nop 1
	v_cndmask_b32_e32 v90, v88, v90, vcc
	v_lshlrev_b32_e32 v202, 2, v90
	v_xor_b32_e32 v90, 8, v88
	v_cmp_lt_i32_e32 vcc, v90, v89
	s_nop 1
	v_cndmask_b32_e32 v90, v88, v90, vcc
	v_lshlrev_b32_e32 v203, 2, v90
	v_xor_b32_e32 v90, 16, v88
	v_cmp_lt_i32_e32 vcc, v90, v89
	s_nop 1
	v_cndmask_b32_e32 v90, v88, v90, vcc
	v_lshlrev_b32_e32 v204, 2, v90
	v_xor_b32_e32 v90, 32, v88
	v_cmp_lt_i32_e32 vcc, v90, v89
	s_nop 1
	v_cndmask_b32_e32 v88, v88, v90, vcc
	v_lshlrev_b32_e32 v205, 2, v88
	v_lshl_add_u64 v[88:89], s[0:1], 0, v[196:197]
	v_lshl_add_u64 v[198:199], v[88:89], 0, s[8:9]
	s_lshl_b64 s[8:9], s[72:73], 12
	s_add_u32 s8, s0, s8
	s_addc_u32 s9, s1, s9
	s_add_i32 s12, s2, s70
	s_add_i32 s26, s26, s33
	s_lshl_b32 s25, s12, 3
	s_add_i32 s12, s26, s93
	s_ashr_i32 s5, s4, 31
	s_ashr_i32 s13, s12, 31
	s_lshl_b64 s[10:11], s[4:5], 12
	s_add_i32 s5, s3, s33
	s_lshl_b64 s[12:13], s[12:13], 12
	s_add_u32 s12, s0, s12
	s_addc_u32 s13, s1, s13
	s_branch .LBB0_325

; __device__ __forceinline__ unsigned pk2(float lo, float hi) { return f2bf(lo) | (f2bf(hi) << 16); }
; __device__ __forceinline__ void norm_store2(bf16* O, int r0, int r1, int lane, const f32x4 (&v)[2][8], const f32x4 (&gm)[8], const f32x4 (&hs)[8]) {
; #pragma unroll
;     for (int q = 0; q < 2; ++q) { const int r = q == 0 ? r0 : r1; float s = 0.f;
; #pragma unroll
;         for (int j = 0; j < 8; ++j) s += (v[q][j].x * v[q][j].x + v[q][j].y * v[q][j].y) + (v[q][j].z * v[q][j].z + v[q][j].w * v[q][j].w);
;         const float rstd = 1.0f / sqrtf(wave_sum(s) * (1.0f / DMODEL) + 1e-6f);
;         if (r < M) { bf16* orow = O + (size_t)r * DMODEL;
; #pragma unroll
;             for (int j = 0; j < 8; ++j) { const f32x4 y = (v[q][j] * rstd) * gm[j] + hs[j]; v2u o; o.x = pk2(y.x, y.y); o.y = pk2(y.z, y.w); *(v2u*)(orow + 4 * (lane + 64 * j)) = o; } } }
; }
; __device__ __forceinline__ void norm_mod_pass(const float* X, const float* gam, const float* sc, const float* sh, bf16* O, int gw, int NGW, int lane) {
;     f32x4 va[2][8], vb[2][8];
;     norm_load2(X, gw, gw + NGW, lane, va);
;     f32x4 gm[8], hs[8];
; #pragma unroll
;     for (int j = 0; j < 8; ++j) { const int col = 4 * (lane + 64 * j); gm[j] = *(const f32x4*)(gam + col) * (*(const f32x4*)(sc + col) + 1.0f); hs[j] = *(const f32x4*)(sh + col); }
;     for (int row = gw; row < M; row += 4 * NGW) {
;         norm_load2(X, row + 2 * NGW, row + 3 * NGW, lane, vb);
;         norm_store2(O, row, row + NGW, lane, va, gm, hs);
;         norm_load2(X, row + 4 * NGW, row + 5 * NGW, lane, va);
;         norm_store2(O, row + 2 * NGW, row + 3 * NGW, lane, vb, gm, hs);
;     }
.LBB0_325:
	s_waitcnt vmcnt(0) lgkmcnt(0)
	v_mov_b32_e32 v90, v93
	v_mov_b32_e32 v91, v105
	v_mov_b32_e32 v88, v92
	v_mov_b32_e32 v89, v104
	v_pk_mul_f32 v[90:91], v[90:91], v[90:91]
	v_mov_b32_e32 v96, v95
	v_mov_b32_e32 v97, v107
	v_pk_fma_f32 v[88:89], v[88:89], v[88:89], v[90:91]
	v_mov_b32_e32 v90, v94
	v_mov_b32_e32 v91, v106
	v_pk_mul_f32 v[96:97], v[96:97], v[96:97]
	s_add_i32 s15, s26, s31
	v_pk_fma_f32 v[90:91], v[90:91], v[90:91], v[96:97]
	v_pk_mul_f32 v[96:97], v[84:85], v[84:85]
	v_pk_add_f32 v[88:89], v[88:89], v[90:91]
	v_pk_mul_f32 v[90:91], v[86:87], v[86:87]
	v_pk_add_f32 v[88:89], v[88:89], v[88:89] op_sel_hi:[0,1]
	v_pk_mov_b32 v[98:99], v[96:97], v[90:91] op_sel:[1,0]
	v_mov_b32_e32 v97, v91
	v_mul_f32_e32 v88, v80, v80
	v_pk_add_f32 v[90:91], v[98:99], v[96:97]
	v_pk_fma_f32 v[96:97], v[80:81], v[80:81], v[88:89] op_sel_hi:[1,1,0]
	v_mul_f32_e32 v88, v82, v82
	v_pk_add_f32 v[90:91], v[90:91], v[90:91] op_sel_hi:[0,1]
	v_pk_fma_f32 v[98:99], v[82:83], v[82:83], v[88:89] op_sel_hi:[1,1,0]
	v_mul_f32_e32 v96, v76, v76
	v_mul_f32_e32 v98, v77, v77
	v_mul_f32_e32 v90, v78, v78
	v_mul_f32_e32 v88, v79, v79
	v_pk_add_f32 v[96:97], v[96:97], v[98:99]
	v_pk_add_f32 v[88:89], v[90:91], v[88:89]
	v_pk_mul_f32 v[90:91], v[74:75], v[74:75]
	v_pk_add_f32 v[88:89], v[96:97], v[88:89]
	v_pk_mul_f32 v[96:97], v[72:73], v[72:73]
	v_pk_add_f32 v[88:89], v[88:89], v[88:89] op_sel_hi:[0,1]
	v_pk_mov_b32 v[98:99], v[96:97], v[90:91] op_sel:[1,0]
	v_mov_b32_e32 v97, v91
	v_mul_f32_e32 v88, v68, v68
	v_pk_add_f32 v[90:91], v[98:99], v[96:97]
	v_pk_fma_f32 v[96:97], v[68:69], v[68:69], v[88:89] op_sel_hi:[1,1,0]
	v_mul_f32_e32 v88, v70, v70
	v_pk_add_f32 v[90:91], v[90:91], v[90:91] op_sel_hi:[0,1]
	v_pk_fma_f32 v[98:99], v[70:71], v[70:71], v[88:89] op_sel_hi:[1,1,0]
	v_mul_f32_e32 v96, v64, v64
	v_mul_f32_e32 v98, v65, v65
	v_mul_f32_e32 v90, v66, v66
	v_mul_f32_e32 v88, v67, v67
	v_pk_add_f32 v[96:97], v[96:97], v[98:99]
	v_pk_add_f32 v[88:89], v[90:91], v[88:89]
	s_add_i32 s14, s5, s31
	v_pk_add_f32 v[88:89], v[96:97], v[88:89]
	s_cmpk_lt_i32 s15, 0x4000
	v_add_f32_e32 v88, v88, v89
	ds_bpermute_b32 v89, v200, v88
	s_cselect_b64 s[18:19], -1, 0
	s_and_b64 s[0:1], s[18:19], exec
	s_cselect_b32 s0, s15, 0
	s_ashr_i32 s1, s0, 31
	s_waitcnt lgkmcnt(0)
	v_add_f32_e32 v88, v88, v89
	ds_bpermute_b32 v89, v201, v88
	s_lshl_b64 s[0:1], s[0:1], 13
	s_cmpk_lt_i32 s14, 0x4000
	s_cselect_b64 s[16:17], -1, 0
	s_waitcnt lgkmcnt(0)
	v_add_f32_e32 v88, v88, v89
	ds_bpermute_b32 v89, v202, v88
	s_waitcnt lgkmcnt(0)
	v_add_f32_e32 v88, v88, v89
	ds_bpermute_b32 v89, v203, v88
	s_waitcnt lgkmcnt(0)
	v_add_f32_e32 v88, v88, v89
	ds_bpermute_b32 v89, v204, v88
	s_waitcnt lgkmcnt(0)
	v_add_f32_e32 v90, v88, v89
	ds_bpermute_b32 v91, v205, v90
	v_lshl_add_u64 v[88:89], v[194:195], 0, s[0:1]
	s_and_b64 s[0:1], s[16:17], exec
	s_cselect_b32 s20, s14, 0
	s_ashr_i32 s21, s20, 31
	s_waitcnt lgkmcnt(0)
	v_add_f32_e32 v90, v90, v91
	v_fmamk_f32 v90, v90, 0x3a000000, v206
	v_mul_f32_e32 v91, 0x4f800000, v90
	v_cmp_gt_f32_e32 vcc, s27, v90
	global_load_dwordx4 v[132:135], v[88:89], off
	global_load_dwordx4 v[128:131], v[88:89], off offset:1024
	v_cndmask_b32_e32 v90, v90, v91, vcc
	v_sqrt_f32_e32 v91, v90
	s_nop 0
	v_add_u32_e32 v96, -1, v91
	v_fma_f32 v97, -v96, v91, v90
	v_cmp_ge_f32_e64 s[0:1], 0, v97
	v_add_u32_e32 v97, 1, v91
	s_nop 0
	v_cndmask_b32_e64 v96, v91, v96, s[0:1]
	v_fma_f32 v91, -v97, v91, v90
	v_cmp_lt_f32_e64 s[0:1], 0, v91
	s_nop 1
	v_cndmask_b32_e64 v91, v96, v97, s[0:1]
	v_mul_f32_e32 v96, 0x37800000, v91
	v_cndmask_b32_e32 v91, v91, v96, vcc
	v_cmp_class_f32_e32 vcc, v90, v207
	s_nop 1
	v_cndmask_b32_e32 v96, v91, v90, vcc
	v_div_scale_f32 v97, s[0:1], v96, v96, 1.0
	v_rcp_f32_e32 v98, v97
	s_lshl_b64 s[0:1], s[20:21], 13
	v_lshl_add_u64 v[90:91], v[194:195], 0, s[0:1]
	s_add_i32 s20, s25, s31
	v_fma_f32 v99, -v97, v98, 1.0
	v_fmac_f32_e32 v98, v99, v98
	v_div_scale_f32 v99, vcc, 1.0, v96, 1.0
	v_mul_f32_e32 v100, v99, v98
	v_fma_f32 v101, -v97, v100, v99
	v_fmac_f32_e32 v100, v101, v98
	v_fma_f32 v97, -v97, v100, v99
	v_div_fmas_f32 v97, v97, v98, v100
	v_div_fixup_f32 v96, v97, v96, 1.0
	v_pk_mul_f32 v[98:99], v[104:105], v[96:97] op_sel_hi:[1,0]
	v_pk_mul_f32 v[100:101], v[106:107], v[96:97] op_sel_hi:[1,0]
	v_pk_fma_f32 v[98:99], v[164:165], v[98:99], v[0:1]
	v_pk_fma_f32 v[100:101], v[162:163], v[100:101], v[2:3]
	v_bfe_u32 v97, v98, 16, 1
	v_add3_u32 v97, v98, v97, s28
	v_bfe_u32 v98, v99, 16, 1
	v_add3_u32 v102, v99, v98, s28
	v_bfe_u32 v98, v100, 16, 1
	v_add3_u32 v100, v100, v98, s28
	v_bfe_u32 v98, v101, 16, 1
	v_lshrrev_b32_e32 v97, 16, v97
	v_add3_u32 v101, v101, v98, s28
	v_add_co_u32_e32 v98, vcc, s22, v88
	v_and_or_b32 v104, v102, s29, v97
	v_lshrrev_b32_e32 v97, 16, v100
	v_addc_co_u32_e32 v99, vcc, 0, v89, vcc
	v_and_or_b32 v105, v101, s29, v97
	v_pk_mul_f32 v[92:93], v[92:93], v[96:97] op_sel_hi:[1,0]
	v_pk_mul_f32 v[94:95], v[94:95], v[96:97] op_sel_hi:[1,0]
	v_pk_mul_f32 v[84:85], v[84:85], v[96:97] op_sel_hi:[1,0]
	v_pk_mul_f32 v[86:87], v[86:87], v[96:97] op_sel_hi:[1,0]
	v_pk_mul_f32 v[80:81], v[80:81], v[96:97] op_sel_hi:[1,0]
	v_pk_mul_f32 v[82:83], v[82:83], v[96:97] op_sel_hi:[1,0]
	v_pk_mul_f32 v[76:77], v[76:77], v[96:97] op_sel_hi:[1,0]
	v_pk_mul_f32 v[78:79], v[78:79], v[96:97] op_sel_hi:[1,0]
	v_pk_mul_f32 v[72:73], v[72:73], v[96:97] op_sel_hi:[1,0]
	v_pk_mul_f32 v[74:75], v[74:75], v[96:97] op_sel_hi:[1,0]
	v_pk_mul_f32 v[68:69], v[68:69], v[96:97] op_sel_hi:[1,0]
	v_pk_mul_f32 v[70:71], v[70:71], v[96:97] op_sel_hi:[1,0]
	v_pk_mul_f32 v[64:65], v[64:65], v[96:97] op_sel_hi:[1,0]
; __device__ __forceinline__ unsigned pk2(float lo, float hi) { return f2bf(lo) | (f2bf(hi) << 16); }
; __device__ __forceinline__ void norm_store2(bf16* O, int r0, int r1, int lane, const f32x4 (&v)[2][8], const f32x4 (&gm)[8], const f32x4 (&hs)[8]) {
; #pragma unroll
;     for (int q = 0; q < 2; ++q) { const int r = q == 0 ? r0 : r1; float s = 0.f;
; #pragma unroll
;         for (int j = 0; j < 8; ++j) s += (v[q][j].x * v[q][j].x + v[q][j].y * v[q][j].y) + (v[q][j].z * v[q][j].z + v[q][j].w * v[q][j].w);
;         const float rstd = 1.0f / sqrtf(wave_sum(s) * (1.0f / DMODEL) + 1e-6f);
;         if (r < M) { bf16* orow = O + (size_t)r * DMODEL;
; #pragma unroll
;             for (int j = 0; j < 8; ++j) { const f32x4 y = (v[q][j] * rstd) * gm[j] + hs[j]; v2u o; o.x = pk2(y.x, y.y); o.y = pk2(y.z, y.w); *(v2u*)(orow + 4 * (lane + 64 * j)) = o; } } }
; }
; __device__ __forceinline__ void norm_mod_pass(const float* X, const float* gam, const float* sc, const float* sh, bf16* O, int gw, int NGW, int lane) {
;     f32x4 va[2][8], vb[2][8];
;     norm_load2(X, gw, gw + NGW, lane, va);
;     f32x4 gm[8], hs[8];
; #pragma unroll
;     for (int j = 0; j < 8; ++j) { const int col = 4 * (lane + 64 * j); gm[j] = *(const f32x4*)(gam + col) * (*(const f32x4*)(sc + col) + 1.0f); hs[j] = *(const f32x4*)(sh + col); }
;     for (int row = gw; row < M; row += 4 * NGW) {
;         norm_load2(X, row + 2 * NGW, row + 3 * NGW, lane, vb);
;         norm_store2(O, row, row + NGW, lane, va, gm, hs);
;         norm_load2(X, row + 4 * NGW, row + 5 * NGW, lane, va);
;         norm_store2(O, row + 2 * NGW, row + 3 * NGW, lane, vb, gm, hs);
	v_pk_mul_f32 v[66:67], v[66:67], v[96:97] op_sel_hi:[1,0]
	v_lshl_add_u64 v[96:97], s[8:9], 0, v[196:197]
	v_add_co_u32_e32 v106, vcc, s30, v96
	v_pk_fma_f32 v[92:93], v[168:169], v[92:93], v[4:5]
	s_nop 0
	v_addc_co_u32_e32 v107, vcc, 0, v97, vcc
	v_add_co_u32_e32 v208, vcc, s22, v90
	v_pk_fma_f32 v[84:85], v[172:173], v[84:85], v[8:9]
	s_nop 0
	v_addc_co_u32_e32 v209, vcc, 0, v91, vcc
	global_load_dwordx4 v[156:159], v[88:89], off offset:2048
	global_load_dwordx4 v[152:155], v[88:89], off offset:3072
	global_load_dwordx4 v[124:127], v[90:91], off
	global_load_dwordx4 v[120:123], v[90:91], off offset:1024
	global_load_dwordx4 v[116:119], v[90:91], off offset:2048
	global_load_dwordx4 v[112:115], v[90:91], off offset:3072
	global_load_dwordx4 v[148:151], v[98:99], off
	global_load_dwordx4 v[144:147], v[98:99], off offset:1024
	global_load_dwordx4 v[140:143], v[98:99], off offset:2048
	global_load_dwordx4 v[136:139], v[98:99], off offset:3072
	global_load_dwordx4 v[108:111], v[208:209], off
	global_load_dwordx4 v[100:103], v[208:209], off offset:1024
	s_nop 0
	global_load_dwordx4 v[96:99], v[208:209], off offset:2048
	global_load_dwordx4 v[88:91], v[208:209], off offset:3072
	v_pk_fma_f32 v[80:81], v[176:177], v[80:81], v[12:13]
	global_store_dwordx2 v[106:107], v[104:105], off
	v_bfe_u32 v104, v92, 16, 1
	v_add3_u32 v104, v92, v104, s28
	v_bfe_u32 v92, v93, 16, 1
	v_add3_u32 v105, v93, v92, s28
	v_pk_fma_f32 v[92:93], v[166:167], v[94:95], v[6:7]
	v_pk_fma_f32 v[76:77], v[180:181], v[76:77], v[16:17]
	v_bfe_u32 v94, v92, 16, 1
	v_add3_u32 v94, v92, v94, s28
	v_bfe_u32 v92, v93, 16, 1
	v_add3_u32 v93, v93, v92, s28
	v_lshrrev_b32_e32 v92, 16, v104
	v_lshrrev_b32_e32 v94, 16, v94
	v_and_or_b32 v92, v105, s29, v92
	v_and_or_b32 v93, v93, s29, v94
	global_store_dwordx2 v[106:107], v[92:93], off offset:512
	v_bfe_u32 v92, v84, 16, 1
	v_add3_u32 v92, v84, v92, s28
	v_bfe_u32 v84, v85, 16, 1
	v_add3_u32 v93, v85, v84, s28
	v_pk_fma_f32 v[84:85], v[170:171], v[86:87], v[10:11]
	v_pk_fma_f32 v[72:73], v[184:185], v[72:73], v[20:21]
	v_bfe_u32 v86, v84, 16, 1
	v_add3_u32 v86, v84, v86, s28
	v_bfe_u32 v84, v85, 16, 1
	v_add3_u32 v85, v85, v84, s28
	v_lshrrev_b32_e32 v84, 16, v92
	v_lshrrev_b32_e32 v86, 16, v86
	v_and_or_b32 v84, v93, s29, v84
	v_and_or_b32 v85, v85, s29, v86
	global_store_dwordx2 v[106:107], v[84:85], off offset:1024
	v_bfe_u32 v84, v80, 16, 1
	v_add3_u32 v84, v80, v84, s28
	v_bfe_u32 v80, v81, 16, 1
	v_add3_u32 v85, v81, v80, s28
	v_pk_fma_f32 v[80:81], v[174:175], v[82:83], v[14:15]
	v_pk_fma_f32 v[68:69], v[188:189], v[68:69], v[24:25]
	v_bfe_u32 v82, v80, 16, 1
	v_add3_u32 v82, v80, v82, s28
	v_bfe_u32 v80, v81, 16, 1
	v_add3_u32 v81, v81, v80, s28
	v_lshrrev_b32_e32 v80, 16, v84
	v_lshrrev_b32_e32 v82, 16, v82
	v_and_or_b32 v80, v85, s29, v80
	v_and_or_b32 v81, v81, s29, v82
	global_store_dwordx2 v[106:107], v[80:81], off offset:1536
	v_bfe_u32 v80, v76, 16, 1
	v_add3_u32 v80, v76, v80, s28
	v_bfe_u32 v76, v77, 16, 1
	v_add3_u32 v81, v77, v76, s28
	v_pk_fma_f32 v[76:77], v[178:179], v[78:79], v[18:19]
	v_pk_fma_f32 v[64:65], v[192:193], v[64:65], v[28:29]
	v_bfe_u32 v78, v76, 16, 1
	v_add3_u32 v78, v76, v78, s28
	v_bfe_u32 v76, v77, 16, 1
	v_add3_u32 v77, v77, v76, s28
	v_lshrrev_b32_e32 v76, 16, v80
	v_lshrrev_b32_e32 v78, 16, v78
	v_and_or_b32 v76, v81, s29, v76
	v_and_or_b32 v77, v77, s29, v78
	global_store_dwordx2 v[106:107], v[76:77], off offset:2048
	v_bfe_u32 v76, v72, 16, 1
	v_add3_u32 v76, v72, v76, s28
	v_bfe_u32 v72, v73, 16, 1
	v_add3_u32 v77, v73, v72, s28
	v_pk_fma_f32 v[72:73], v[182:183], v[74:75], v[22:23]
	s_cmpk_gt_i32 s20, 0x3fff
	v_bfe_u32 v74, v72, 16, 1
	v_add3_u32 v74, v72, v74, s28
	v_bfe_u32 v72, v73, 16, 1
	v_add3_u32 v73, v73, v72, s28
	v_lshrrev_b32_e32 v72, 16, v76
	v_lshrrev_b32_e32 v74, 16, v74
	v_and_or_b32 v72, v77, s29, v72
	v_and_or_b32 v73, v73, s29, v74
	global_store_dwordx2 v[106:107], v[72:73], off offset:2560
	v_bfe_u32 v72, v68, 16, 1
	v_add3_u32 v72, v68, v72, s28
	v_bfe_u32 v68, v69, 16, 1
	v_add3_u32 v73, v69, v68, s28
	v_pk_fma_f32 v[68:69], v[186:187], v[70:71], v[26:27]
	v_mul_f32_e32 v71, v63, v63
	v_bfe_u32 v70, v68, 16, 1
	v_add3_u32 v70, v68, v70, s28
	v_mul_f32_e32 v68, v61, v61
	v_fmac_f32_e32 v68, v60, v60
	v_fmac_f32_e32 v71, v62, v62
	v_add_f32_e32 v68, v68, v71
	v_mul_f32_e32 v71, v57, v57
	v_mul_f32_e32 v74, v59, v59
	v_fmac_f32_e32 v71, v56, v56
	v_fmac_f32_e32 v74, v58, v58
	v_add_f32_e32 v71, v71, v74
	v_add_f32_e32 v68, v71, v68
	v_mul_f32_e32 v71, v53, v53
	v_mul_f32_e32 v74, v55, v55
	v_fmac_f32_e32 v71, v52, v52
	v_fmac_f32_e32 v74, v54, v54
	v_add_f32_e32 v71, v71, v74
	v_add_f32_e32 v68, v71, v68
	v_mul_f32_e32 v71, v49, v49
	v_mul_f32_e32 v74, v51, v51
	v_fmac_f32_e32 v71, v48, v48
	v_fmac_f32_e32 v74, v50, v50
	v_add_f32_e32 v71, v71, v74
	v_add_f32_e32 v68, v71, v68
	v_mul_f32_e32 v71, v45, v45
	v_mul_f32_e32 v74, v47, v47
	v_fmac_f32_e32 v71, v44, v44
	v_fmac_f32_e32 v74, v46, v46
	v_add_f32_e32 v71, v71, v74
	v_add_f32_e32 v68, v71, v68
	v_mul_f32_e32 v71, v41, v41
	v_mul_f32_e32 v74, v43, v43
	v_fmac_f32_e32 v71, v40, v40
	v_fmac_f32_e32 v74, v42, v42
	v_add_f32_e32 v71, v71, v74
	v_add_f32_e32 v68, v71, v68
	v_mul_f32_e32 v71, v37, v37
	v_mul_f32_e32 v74, v39, v39
	v_fmac_f32_e32 v71, v36, v36
	v_fmac_f32_e32 v74, v38, v38
	v_add_f32_e32 v71, v71, v74
	v_add_f32_e32 v68, v71, v68
	v_mul_f32_e32 v71, v33, v33
	v_mul_f32_e32 v74, v35, v35
	v_fmac_f32_e32 v71, v32, v32
	v_fmac_f32_e32 v74, v34, v34
	v_add_f32_e32 v71, v71, v74
	v_add_f32_e32 v71, v71, v68
	ds_bpermute_b32 v74, v200, v71
	v_bfe_u32 v68, v69, 16, 1
	v_add3_u32 v69, v69, v68, s28
	v_lshrrev_b32_e32 v68, 16, v72
	v_lshrrev_b32_e32 v70, 16, v70
	s_waitcnt lgkmcnt(0)
	v_add_f32_e32 v71, v71, v74
	ds_bpermute_b32 v72, v201, v71
	v_and_or_b32 v68, v73, s29, v68
	v_and_or_b32 v69, v69, s29, v70
	global_store_dwordx2 v[106:107], v[68:69], off offset:3072
	v_bfe_u32 v70, v64, 16, 1
	s_waitcnt lgkmcnt(0)
	v_add_f32_e32 v68, v71, v72
	ds_bpermute_b32 v69, v202, v68
	v_add3_u32 v70, v64, v70, s28
	v_bfe_u32 v64, v65, 16, 1
	v_add3_u32 v71, v65, v64, s28
	v_pk_fma_f32 v[64:65], v[190:191], v[66:67], v[30:31]
	s_waitcnt lgkmcnt(0)
	v_add_f32_e32 v68, v68, v69
	ds_bpermute_b32 v69, v203, v68
	v_bfe_u32 v66, v64, 16, 1
	v_add3_u32 v64, v64, v66, s28
	v_bfe_u32 v66, v65, 16, 1
	s_waitcnt lgkmcnt(0)
	v_add_f32_e32 v67, v68, v69
	ds_bpermute_b32 v68, v204, v67
	v_add3_u32 v69, v65, v66, s28
	v_lshrrev_b32_e32 v65, 16, v70
	v_lshrrev_b32_e32 v70, 16, v64
	v_and_or_b32 v66, v71, s29, v65
	s_waitcnt lgkmcnt(0)
	v_add_f32_e32 v64, v67, v68
	ds_bpermute_b32 v65, v205, v64
	v_and_or_b32 v67, v69, s29, v70
	global_store_dwordx2 v[106:107], v[66:67], off offset:3584
	s_cbranch_scc1 .LBB0_327
; __device__ __forceinline__ unsigned pk2(float lo, float hi) { return f2bf(lo) | (f2bf(hi) << 16); }
; __device__ __forceinline__ void norm_store2(bf16* O, int r0, int r1, int lane, const f32x4 (&v)[2][8], const f32x4 (&gm)[8], const f32x4 (&hs)[8]) {
; #pragma unroll
;     for (int q = 0; q < 2; ++q) { const int r = q == 0 ? r0 : r1; float s = 0.f;
; #pragma unroll
;         for (int j = 0; j < 8; ++j) s += (v[q][j].x * v[q][j].x + v[q][j].y * v[q][j].y) + (v[q][j].z * v[q][j].z + v[q][j].w * v[q][j].w);
;         const float rstd = 1.0f / sqrtf(wave_sum(s) * (1.0f / DMODEL) + 1e-6f);
;         if (r < M) { bf16* orow = O + (size_t)r * DMODEL;
; #pragma unroll
;             for (int j = 0; j < 8; ++j) { const f32x4 y = (v[q][j] * rstd) * gm[j] + hs[j]; v2u o; o.x = pk2(y.x, y.y); o.y = pk2(y.z, y.w); *(v2u*)(orow + 4 * (lane + 64 * j)) = o; } } }
	s_waitcnt lgkmcnt(0)
	v_add_f32_e32 v64, v64, v65
	v_fmamk_f32 v64, v64, 0x3a000000, v206
	v_mul_f32_e32 v65, 0x4f800000, v64
	v_cmp_gt_f32_e32 vcc, s27, v64
	s_ashr_i32 s21, s20, 31
	s_nop 0
	v_cndmask_b32_e32 v64, v64, v65, vcc
	v_sqrt_f32_e32 v65, v64
	s_nop 0
	v_add_u32_e32 v66, -1, v65
	v_fma_f32 v68, -v66, v65, v64
	v_add_u32_e32 v67, 1, v65
	v_cmp_ge_f32_e64 s[0:1], 0, v68
	s_nop 1
	v_cndmask_b32_e64 v66, v65, v66, s[0:1]
	v_fma_f32 v65, -v67, v65, v64
	v_cmp_lt_f32_e64 s[0:1], 0, v65
	s_nop 1
	v_cndmask_b32_e64 v65, v66, v67, s[0:1]
	v_mul_f32_e32 v66, 0x37800000, v65
	v_cndmask_b32_e32 v65, v65, v66, vcc
	v_cmp_class_f32_e32 vcc, v64, v207
	s_nop 1
	v_cndmask_b32_e32 v64, v65, v64, vcc
	v_div_scale_f32 v65, s[0:1], v64, v64, 1.0
	v_rcp_f32_e32 v66, v65
	s_lshl_b64 s[0:1], s[20:21], 12
	v_fma_f32 v67, -v65, v66, 1.0
	v_fmac_f32_e32 v66, v67, v66
	v_div_scale_f32 v67, vcc, 1.0, v64, 1.0
	v_mul_f32_e32 v68, v67, v66
	v_fma_f32 v69, -v65, v68, v67
	v_fmac_f32_e32 v68, v69, v66
	v_fma_f32 v65, -v65, v68, v67
	v_div_fmas_f32 v65, v65, v66, v68
	v_div_fixup_f32 v64, v65, v64, 1.0
	v_pk_mul_f32 v[60:61], v[60:61], v[64:65] op_sel_hi:[1,0]
	v_pk_mul_f32 v[62:63], v[62:63], v[64:65] op_sel_hi:[1,0]
	v_pk_fma_f32 v[60:61], v[164:165], v[60:61], v[0:1]
	v_pk_fma_f32 v[62:63], v[162:163], v[62:63], v[2:3]
	v_bfe_u32 v65, v60, 16, 1
	v_add3_u32 v60, v60, v65, s28
	v_bfe_u32 v65, v61, 16, 1
	v_lshrrev_b32_e32 v60, 16, v60
	v_add3_u32 v61, v61, v65, s28
	v_and_or_b32 v60, v61, s29, v60
	v_bfe_u32 v61, v62, 16, 1
	v_add3_u32 v61, v62, v61, s28
	v_bfe_u32 v62, v63, 16, 1
	v_lshrrev_b32_e32 v61, 16, v61
	v_add3_u32 v62, v63, v62, s28
	v_pk_mul_f32 v[56:57], v[56:57], v[64:65] op_sel_hi:[1,0]
	v_and_or_b32 v61, v62, s29, v61
	v_lshl_add_u64 v[62:63], v[198:199], 0, s[0:1]
	v_pk_fma_f32 v[56:57], v[168:169], v[56:57], v[4:5]
	global_store_dwordx2 v[62:63], v[60:61], off
	v_bfe_u32 v60, v56, 16, 1
	v_pk_mul_f32 v[58:59], v[58:59], v[64:65] op_sel_hi:[1,0]
	v_add3_u32 v56, v56, v60, s28
	v_bfe_u32 v60, v57, 16, 1
	v_pk_fma_f32 v[58:59], v[166:167], v[58:59], v[6:7]
	v_lshrrev_b32_e32 v56, 16, v56
	v_add3_u32 v57, v57, v60, s28
	v_and_or_b32 v56, v57, s29, v56
	v_bfe_u32 v57, v58, 16, 1
	v_add3_u32 v57, v58, v57, s28
	v_bfe_u32 v58, v59, 16, 1
	v_lshrrev_b32_e32 v57, 16, v57
	v_add3_u32 v58, v59, v58, s28
	v_pk_mul_f32 v[52:53], v[52:53], v[64:65] op_sel_hi:[1,0]
	v_and_or_b32 v57, v58, s29, v57
	v_pk_fma_f32 v[52:53], v[172:173], v[52:53], v[8:9]
	global_store_dwordx2 v[62:63], v[56:57], off offset:512
	v_bfe_u32 v56, v52, 16, 1
	v_pk_mul_f32 v[54:55], v[54:55], v[64:65] op_sel_hi:[1,0]
	v_add3_u32 v52, v52, v56, s28
	v_bfe_u32 v56, v53, 16, 1
	v_pk_fma_f32 v[54:55], v[170:171], v[54:55], v[10:11]
	v_lshrrev_b32_e32 v52, 16, v52
	v_add3_u32 v53, v53, v56, s28
	v_and_or_b32 v52, v53, s29, v52
	v_bfe_u32 v53, v54, 16, 1
	v_add3_u32 v53, v54, v53, s28
	v_bfe_u32 v54, v55, 16, 1
	v_lshrrev_b32_e32 v53, 16, v53
	v_add3_u32 v54, v55, v54, s28
	v_pk_mul_f32 v[48:49], v[48:49], v[64:65] op_sel_hi:[1,0]
	v_and_or_b32 v53, v54, s29, v53
	v_pk_fma_f32 v[48:49], v[176:177], v[48:49], v[12:13]
	global_store_dwordx2 v[62:63], v[52:53], off offset:1024
	v_bfe_u32 v52, v48, 16, 1
	v_pk_mul_f32 v[50:51], v[50:51], v[64:65] op_sel_hi:[1,0]
	v_add3_u32 v48, v48, v52, s28
	v_bfe_u32 v52, v49, 16, 1
	v_pk_fma_f32 v[50:51], v[174:175], v[50:51], v[14:15]
	v_lshrrev_b32_e32 v48, 16, v48
	v_add3_u32 v49, v49, v52, s28
	v_and_or_b32 v48, v49, s29, v48
	v_bfe_u32 v49, v50, 16, 1
	v_add3_u32 v49, v50, v49, s28
	v_bfe_u32 v50, v51, 16, 1
	v_lshrrev_b32_e32 v49, 16, v49
	v_add3_u32 v50, v51, v50, s28
	v_pk_mul_f32 v[44:45], v[44:45], v[64:65] op_sel_hi:[1,0]
	v_and_or_b32 v49, v50, s29, v49
	v_pk_fma_f32 v[44:45], v[180:181], v[44:45], v[16:17]
	global_store_dwordx2 v[62:63], v[48:49], off offset:1536
	v_bfe_u32 v48, v44, 16, 1
	v_pk_mul_f32 v[46:47], v[46:47], v[64:65] op_sel_hi:[1,0]
	v_add3_u32 v44, v44, v48, s28
	v_bfe_u32 v48, v45, 16, 1
	v_pk_fma_f32 v[46:47], v[178:179], v[46:47], v[18:19]
	v_lshrrev_b32_e32 v44, 16, v44
	v_add3_u32 v45, v45, v48, s28
	v_and_or_b32 v44, v45, s29, v44
	v_bfe_u32 v45, v46, 16, 1
	v_add3_u32 v45, v46, v45, s28
	v_bfe_u32 v46, v47, 16, 1
	v_lshrrev_b32_e32 v45, 16, v45
	v_add3_u32 v46, v47, v46, s28
	v_pk_mul_f32 v[40:41], v[40:41], v[64:65] op_sel_hi:[1,0]
	v_and_or_b32 v45, v46, s29, v45
	v_pk_fma_f32 v[40:41], v[184:185], v[40:41], v[20:21]
	global_store_dwordx2 v[62:63], v[44:45], off offset:2048
	v_bfe_u32 v44, v40, 16, 1
	v_pk_mul_f32 v[42:43], v[42:43], v[64:65] op_sel_hi:[1,0]
	v_add3_u32 v40, v40, v44, s28
	v_bfe_u32 v44, v41, 16, 1
	v_pk_fma_f32 v[42:43], v[182:183], v[42:43], v[22:23]
	v_lshrrev_b32_e32 v40, 16, v40
	v_add3_u32 v41, v41, v44, s28
	v_and_or_b32 v40, v41, s29, v40
	v_bfe_u32 v41, v42, 16, 1
	v_add3_u32 v41, v42, v41, s28
	v_bfe_u32 v42, v43, 16, 1
	v_lshrrev_b32_e32 v41, 16, v41
	v_add3_u32 v42, v43, v42, s28
	v_pk_mul_f32 v[36:37], v[36:37], v[64:65] op_sel_hi:[1,0]
	v_and_or_b32 v41, v42, s29, v41
	v_pk_fma_f32 v[36:37], v[188:189], v[36:37], v[24:25]
	global_store_dwordx2 v[62:63], v[40:41], off offset:2560
	v_bfe_u32 v40, v36, 16, 1
	v_pk_mul_f32 v[38:39], v[38:39], v[64:65] op_sel_hi:[1,0]
	v_add3_u32 v36, v36, v40, s28
	v_bfe_u32 v40, v37, 16, 1
	v_pk_fma_f32 v[38:39], v[186:187], v[38:39], v[26:27]
	v_lshrrev_b32_e32 v36, 16, v36
	v_add3_u32 v37, v37, v40, s28
	v_and_or_b32 v36, v37, s29, v36
	v_bfe_u32 v37, v38, 16, 1
	v_add3_u32 v37, v38, v37, s28
	v_bfe_u32 v38, v39, 16, 1
	v_lshrrev_b32_e32 v37, 16, v37
	v_add3_u32 v38, v39, v38, s28
	v_pk_mul_f32 v[32:33], v[32:33], v[64:65] op_sel_hi:[1,0]
	v_and_or_b32 v37, v38, s29, v37
	v_pk_fma_f32 v[32:33], v[192:193], v[32:33], v[28:29]
	global_store_dwordx2 v[62:63], v[36:37], off offset:3072
	v_bfe_u32 v36, v32, 16, 1
	v_pk_mul_f32 v[34:35], v[34:35], v[64:65] op_sel_hi:[1,0]
	v_add3_u32 v32, v32, v36, s28
	v_bfe_u32 v36, v33, 16, 1
	v_pk_fma_f32 v[34:35], v[190:191], v[34:35], v[30:31]
	v_lshrrev_b32_e32 v32, 16, v32
	v_add3_u32 v33, v33, v36, s28
	v_and_or_b32 v32, v33, s29, v32
	v_bfe_u32 v33, v34, 16, 1
	v_add3_u32 v33, v34, v33, s28
	v_bfe_u32 v34, v35, 16, 1
	v_lshrrev_b32_e32 v33, 16, v33
	v_add3_u32 v34, v35, v34, s28
	v_and_or_b32 v33, v34, s29, v33
	global_store_dwordx2 v[62:63], v[32:33], off offset:3584
; __device__ __forceinline__ unsigned pk2(float lo, float hi) { return f2bf(lo) | (f2bf(hi) << 16); }
; __device__ __forceinline__ void norm_load2(const float* X, int r0, int r1, int lane, f32x4 (&v)[2][8]) {
;     const f32x4* x0 = (const f32x4*)(X + (size_t)(r0 < M ? r0 : 0) * DMODEL) + lane; const f32x4* x1 = (const f32x4*)(X + (size_t)(r1 < M ? r1 : 0) * DMODEL) + lane;
; #pragma unroll
;     for (int j = 0; j < 8; ++j) { v[0][j] = x0[64 * j]; v[1][j] = x1[64 * j]; }
; }
; __device__ __forceinline__ void norm_store2(bf16* O, int r0, int r1, int lane, const f32x4 (&v)[2][8], const f32x4 (&gm)[8], const f32x4 (&hs)[8]) {
; #pragma unroll
;     for (int q = 0; q < 2; ++q) { const int r = q == 0 ? r0 : r1; float s = 0.f;
; #pragma unroll
;         for (int j = 0; j < 8; ++j) s += (v[q][j].x * v[q][j].x + v[q][j].y * v[q][j].y) + (v[q][j].z * v[q][j].z + v[q][j].w * v[q][j].w);
;         const float rstd = 1.0f / sqrtf(wave_sum(s) * (1.0f / DMODEL) + 1e-6f);
;         if (r < M) { bf16* orow = O + (size_t)r * DMODEL;
; #pragma unroll
;             for (int j = 0; j < 8; ++j) { const f32x4 y = (v[q][j] * rstd) * gm[j] + hs[j]; v2u o; o.x = pk2(y.x, y.y); o.y = pk2(y.z, y.w); *(v2u*)(orow + 4 * (lane + 64 * j)) = o; } } }
; __device__ __forceinline__ void norm_mod_pass(const float* X, const float* gam, const float* sc, const float* sh, bf16* O, int gw, int NGW, int lane) {
;     ...
;     for (int row = gw; row < M; row += 4 * NGW) {
;         norm_load2(X, row + 2 * NGW, row + 3 * NGW, lane, vb);
;         norm_store2(O, row, row + NGW, lane, va, gm, hs);
;         norm_load2(X, row + 4 * NGW, row + 5 * NGW, lane, va);
;         norm_store2(O, row + 2 * NGW, row + 3 * NGW, lane, vb, gm, hs);
;     }
.LBB0_327:
	s_add_i32 s0, s24, s31
	s_add_i32 s15, s23, s31
	s_cmpk_lt_i32 s0, 0x4000
	s_cselect_b32 s0, s0, 0
	s_ashr_i32 s1, s0, 31
	s_lshl_b64 s[0:1], s[0:1], 13
	s_cmpk_lt_i32 s15, 0x4000
	v_lshl_add_u64 v[32:33], v[194:195], 0, s[0:1]
	s_cselect_b32 s0, s15, 0
	s_ashr_i32 s1, s0, 31
	s_lshl_b64 s[0:1], s[0:1], 13
	v_lshl_add_u64 v[34:35], v[194:195], 0, s[0:1]
	global_load_dwordx4 v[104:107], v[32:33], off
	global_load_dwordx4 v[92:95], v[32:33], off offset:1024
	global_load_dwordx4 v[60:63], v[34:35], off
	global_load_dwordx4 v[56:59], v[34:35], off offset:1024
	global_load_dwordx4 v[84:87], v[32:33], off offset:2048
	global_load_dwordx4 v[80:83], v[32:33], off offset:3072
	global_load_dwordx4 v[52:55], v[34:35], off offset:2048
	global_load_dwordx4 v[48:51], v[34:35], off offset:3072
	v_add_co_u32_e32 v32, vcc, s22, v32
	s_waitcnt vmcnt(0)
	v_mul_f32_e32 v208, v133, v133
	v_addc_co_u32_e32 v33, vcc, 0, v33, vcc
	v_add_co_u32_e32 v34, vcc, s22, v34
	v_mul_f32_e32 v209, v135, v135
	s_nop 0
	v_addc_co_u32_e32 v35, vcc, 0, v35, vcc
	global_load_dwordx4 v[76:79], v[32:33], off
	global_load_dwordx4 v[72:75], v[32:33], off offset:1024
	global_load_dwordx4 v[44:47], v[34:35], off
	global_load_dwordx4 v[40:43], v[34:35], off offset:1024
	global_load_dwordx4 v[68:71], v[32:33], off offset:2048
	s_waitcnt lgkmcnt(0)
	global_load_dwordx4 v[64:67], v[32:33], off offset:3072
	global_load_dwordx4 v[36:39], v[34:35], off offset:2048
	s_nop 0
	global_load_dwordx4 v[32:35], v[34:35], off offset:3072
	v_fmac_f32_e32 v208, v132, v132
	v_fmac_f32_e32 v209, v134, v134
	v_add_f32_e32 v208, v208, v209
	v_mul_f32_e32 v209, v129, v129
	v_mul_f32_e32 v210, v131, v131
	v_fmac_f32_e32 v209, v128, v128
	v_fmac_f32_e32 v210, v130, v130
	v_add_f32_e32 v209, v209, v210
	v_add_f32_e32 v208, v208, v209
	v_mul_f32_e32 v209, v157, v157
	v_mul_f32_e32 v210, v159, v159
	v_fmac_f32_e32 v209, v156, v156
	v_fmac_f32_e32 v210, v158, v158
	v_add_f32_e32 v209, v209, v210
	v_add_f32_e32 v208, v208, v209
	v_mul_f32_e32 v209, v153, v153
	v_mul_f32_e32 v210, v155, v155
	v_fmac_f32_e32 v209, v152, v152
	v_fmac_f32_e32 v210, v154, v154
	v_add_f32_e32 v209, v209, v210
	v_add_f32_e32 v208, v208, v209
	v_mul_f32_e32 v209, v149, v149
	v_mul_f32_e32 v210, v151, v151
	v_fmac_f32_e32 v209, v148, v148
	v_fmac_f32_e32 v210, v150, v150
	v_add_f32_e32 v209, v209, v210
	v_add_f32_e32 v208, v208, v209
	v_mul_f32_e32 v209, v145, v145
	v_mul_f32_e32 v210, v147, v147
	v_fmac_f32_e32 v209, v144, v144
	v_fmac_f32_e32 v210, v146, v146
	v_add_f32_e32 v209, v209, v210
	v_add_f32_e32 v208, v208, v209
	v_mul_f32_e32 v209, v141, v141
	v_mul_f32_e32 v210, v143, v143
	v_fmac_f32_e32 v209, v140, v140
	v_fmac_f32_e32 v210, v142, v142
	v_add_f32_e32 v209, v209, v210
	v_add_f32_e32 v208, v208, v209
	v_mul_f32_e32 v209, v137, v137
	v_mul_f32_e32 v210, v139, v139
	v_fmac_f32_e32 v209, v136, v136
	v_fmac_f32_e32 v210, v138, v138
	v_add_f32_e32 v209, v209, v210
	v_add_f32_e32 v208, v208, v209
	ds_bpermute_b32 v209, v200, v208
	s_andn2_b64 vcc, exec, s[18:19]
	s_waitcnt lgkmcnt(0)
	v_add_f32_e32 v208, v208, v209
	ds_bpermute_b32 v209, v201, v208
	s_waitcnt lgkmcnt(0)
	v_add_f32_e32 v208, v208, v209
	ds_bpermute_b32 v209, v202, v208
	s_waitcnt lgkmcnt(0)
	v_add_f32_e32 v208, v208, v209
	ds_bpermute_b32 v209, v203, v208
	s_waitcnt lgkmcnt(0)
	v_add_f32_e32 v208, v208, v209
	ds_bpermute_b32 v209, v204, v208
	s_waitcnt lgkmcnt(0)
	v_add_f32_e32 v208, v208, v209
	ds_bpermute_b32 v209, v205, v208
	s_cbranch_vccnz .LBB0_329
	s_waitcnt lgkmcnt(0)
	v_add_f32_e32 v208, v208, v209
	v_fmamk_f32 v208, v208, 0x3a000000, v206
	v_mul_f32_e32 v209, 0x4f800000, v208
	v_cmp_gt_f32_e32 vcc, s27, v208
	s_nop 1
	v_cndmask_b32_e32 v208, v208, v209, vcc
	v_sqrt_f32_e32 v209, v208
	s_nop 0
	v_add_u32_e32 v210, -1, v209
	v_fma_f32 v212, -v210, v209, v208
	v_add_u32_e32 v211, 1, v209
	v_cmp_ge_f32_e64 s[0:1], 0, v212
	s_nop 1
	v_cndmask_b32_e64 v210, v209, v210, s[0:1]
	v_fma_f32 v209, -v211, v209, v208
	v_cmp_lt_f32_e64 s[0:1], 0, v209
	s_nop 1
	v_cndmask_b32_e64 v209, v210, v211, s[0:1]
	v_mul_f32_e32 v210, 0x37800000, v209
	v_cndmask_b32_e32 v209, v209, v210, vcc
	v_cmp_class_f32_e32 vcc, v208, v207
	s_nop 1
	v_cndmask_b32_e32 v208, v209, v208, vcc
	v_div_scale_f32 v209, s[0:1], v208, v208, 1.0
	v_rcp_f32_e32 v210, v209
	s_nop 0
	v_fma_f32 v211, -v209, v210, 1.0
	v_fmac_f32_e32 v210, v211, v210
	v_div_scale_f32 v211, vcc, 1.0, v208, 1.0
	v_mul_f32_e32 v212, v211, v210
	v_fma_f32 v213, -v209, v212, v211
	v_fmac_f32_e32 v212, v213, v210
	v_fma_f32 v209, -v209, v212, v211
	v_div_fmas_f32 v209, v209, v210, v212
	v_div_fixup_f32 v208, v209, v208, 1.0
	v_pk_mul_f32 v[132:133], v[132:133], v[208:209] op_sel_hi:[1,0]
	v_pk_mul_f32 v[134:135], v[134:135], v[208:209] op_sel_hi:[1,0]
	v_pk_fma_f32 v[132:133], v[164:165], v[132:133], v[0:1]
	v_pk_fma_f32 v[134:135], v[162:163], v[134:135], v[2:3]
	v_bfe_u32 v209, v132, 16, 1
	v_add3_u32 v132, v132, v209, s28
	v_bfe_u32 v209, v133, 16, 1
	v_lshrrev_b32_e32 v132, 16, v132
	v_add3_u32 v133, v133, v209, s28
	v_and_or_b32 v132, v133, s29, v132
	v_bfe_u32 v133, v134, 16, 1
	v_add3_u32 v133, v134, v133, s28
	v_bfe_u32 v134, v135, 16, 1
	v_lshrrev_b32_e32 v133, 16, v133
	v_add3_u32 v134, v135, v134, s28
	v_and_or_b32 v133, v134, s29, v133
	v_lshl_add_u64 v[134:135], s[12:13], 0, v[196:197]
	v_add_co_u32_e32 v134, vcc, s30, v134
	v_pk_mul_f32 v[128:129], v[128:129], v[208:209] op_sel_hi:[1,0]
	s_nop 0
	v_addc_co_u32_e32 v135, vcc, 0, v135, vcc
	v_pk_fma_f32 v[128:129], v[168:169], v[128:129], v[4:5]
	global_store_dwordx2 v[134:135], v[132:133], off
	v_bfe_u32 v132, v128, 16, 1
; __device__ __forceinline__ unsigned pk2(float lo, float hi) { return f2bf(lo) | (f2bf(hi) << 16); }
; __device__ __forceinline__ void norm_store2(bf16* O, int r0, int r1, int lane, const f32x4 (&v)[2][8], const f32x4 (&gm)[8], const f32x4 (&hs)[8]) {
;     ...
;         if (r < M) { bf16* orow = O + (size_t)r * DMODEL;
; #pragma unroll
;             for (int j = 0; j < 8; ++j) { const f32x4 y = (v[q][j] * rstd) * gm[j] + hs[j]; v2u o; o.x = pk2(y.x, y.y); o.y = pk2(y.z, y.w); *(v2u*)(orow + 4 * (lane + 64 * j)) = o; } } }
	v_pk_mul_f32 v[130:131], v[130:131], v[208:209] op_sel_hi:[1,0]
	v_add3_u32 v128, v128, v132, s28
	v_bfe_u32 v132, v129, 16, 1
	v_pk_fma_f32 v[130:131], v[166:167], v[130:131], v[6:7]
	v_lshrrev_b32_e32 v128, 16, v128
	v_add3_u32 v129, v129, v132, s28
	v_and_or_b32 v128, v129, s29, v128
	v_bfe_u32 v129, v130, 16, 1
	v_add3_u32 v129, v130, v129, s28
	v_bfe_u32 v130, v131, 16, 1
	v_lshrrev_b32_e32 v129, 16, v129
	v_add3_u32 v130, v131, v130, s28
	v_and_or_b32 v129, v130, s29, v129
	global_store_dwordx2 v[134:135], v[128:129], off offset:512
	v_pk_mul_f32 v[128:129], v[156:157], v[208:209] op_sel_hi:[1,0]
	v_pk_mul_f32 v[130:131], v[158:159], v[208:209] op_sel_hi:[1,0]
	v_pk_fma_f32 v[128:129], v[172:173], v[128:129], v[8:9]
	v_pk_fma_f32 v[130:131], v[170:171], v[130:131], v[10:11]
	v_bfe_u32 v132, v128, 16, 1
	v_add3_u32 v128, v128, v132, s28
	v_bfe_u32 v132, v129, 16, 1
	v_lshrrev_b32_e32 v128, 16, v128
	v_add3_u32 v129, v129, v132, s28
	v_and_or_b32 v128, v129, s29, v128
	v_bfe_u32 v129, v130, 16, 1
	v_add3_u32 v129, v130, v129, s28
	v_bfe_u32 v130, v131, 16, 1
	v_lshrrev_b32_e32 v129, 16, v129
	v_add3_u32 v130, v131, v130, s28
	v_and_or_b32 v129, v130, s29, v129
	global_store_dwordx2 v[134:135], v[128:129], off offset:1024
	v_pk_mul_f32 v[128:129], v[152:153], v[208:209] op_sel_hi:[1,0]
	v_pk_mul_f32 v[130:131], v[154:155], v[208:209] op_sel_hi:[1,0]
	v_pk_fma_f32 v[128:129], v[176:177], v[128:129], v[12:13]
	v_pk_fma_f32 v[130:131], v[174:175], v[130:131], v[14:15]
	v_bfe_u32 v132, v128, 16, 1
	v_add3_u32 v128, v128, v132, s28
	v_bfe_u32 v132, v129, 16, 1
	v_lshrrev_b32_e32 v128, 16, v128
	v_add3_u32 v129, v129, v132, s28
	v_and_or_b32 v128, v129, s29, v128
	v_bfe_u32 v129, v130, 16, 1
	v_add3_u32 v129, v130, v129, s28
	v_bfe_u32 v130, v131, 16, 1
	v_lshrrev_b32_e32 v129, 16, v129
	v_add3_u32 v130, v131, v130, s28
	v_and_or_b32 v129, v130, s29, v129
	global_store_dwordx2 v[134:135], v[128:129], off offset:1536
	v_pk_mul_f32 v[128:129], v[148:149], v[208:209] op_sel_hi:[1,0]
	v_pk_mul_f32 v[130:131], v[150:151], v[208:209] op_sel_hi:[1,0]
	v_pk_fma_f32 v[128:129], v[180:181], v[128:129], v[16:17]
	v_pk_fma_f32 v[130:131], v[178:179], v[130:131], v[18:19]
	v_bfe_u32 v132, v128, 16, 1
	v_add3_u32 v128, v128, v132, s28
	v_bfe_u32 v132, v129, 16, 1
	v_lshrrev_b32_e32 v128, 16, v128
	v_add3_u32 v129, v129, v132, s28
	v_and_or_b32 v128, v129, s29, v128
	v_bfe_u32 v129, v130, 16, 1
	v_add3_u32 v129, v130, v129, s28
	v_bfe_u32 v130, v131, 16, 1
	v_lshrrev_b32_e32 v129, 16, v129
	v_add3_u32 v130, v131, v130, s28
	v_and_or_b32 v129, v130, s29, v129
	global_store_dwordx2 v[134:135], v[128:129], off offset:2048
	v_pk_mul_f32 v[128:129], v[144:145], v[208:209] op_sel_hi:[1,0]
	v_pk_mul_f32 v[130:131], v[146:147], v[208:209] op_sel_hi:[1,0]
	v_pk_fma_f32 v[128:129], v[184:185], v[128:129], v[20:21]
	v_pk_fma_f32 v[130:131], v[182:183], v[130:131], v[22:23]
	v_bfe_u32 v132, v128, 16, 1
	v_add3_u32 v128, v128, v132, s28
	v_bfe_u32 v132, v129, 16, 1
	v_lshrrev_b32_e32 v128, 16, v128
	v_add3_u32 v129, v129, v132, s28
	v_and_or_b32 v128, v129, s29, v128
	v_bfe_u32 v129, v130, 16, 1
	v_add3_u32 v129, v130, v129, s28
	v_bfe_u32 v130, v131, 16, 1
	v_lshrrev_b32_e32 v129, 16, v129
	v_add3_u32 v130, v131, v130, s28
	v_and_or_b32 v129, v130, s29, v129
	global_store_dwordx2 v[134:135], v[128:129], off offset:2560
	v_pk_mul_f32 v[128:129], v[140:141], v[208:209] op_sel_hi:[1,0]
	v_pk_mul_f32 v[130:131], v[142:143], v[208:209] op_sel_hi:[1,0]
	v_pk_fma_f32 v[128:129], v[188:189], v[128:129], v[24:25]
	v_pk_fma_f32 v[130:131], v[186:187], v[130:131], v[26:27]
	v_bfe_u32 v132, v128, 16, 1
	v_add3_u32 v128, v128, v132, s28
	v_bfe_u32 v132, v129, 16, 1
	v_lshrrev_b32_e32 v128, 16, v128
	v_add3_u32 v129, v129, v132, s28
	v_and_or_b32 v128, v129, s29, v128
	v_bfe_u32 v129, v130, 16, 1
	v_add3_u32 v129, v130, v129, s28
	v_bfe_u32 v130, v131, 16, 1
	v_lshrrev_b32_e32 v129, 16, v129
	v_add3_u32 v130, v131, v130, s28
	v_and_or_b32 v129, v130, s29, v129
	global_store_dwordx2 v[134:135], v[128:129], off offset:3072
	v_pk_mul_f32 v[128:129], v[136:137], v[208:209] op_sel_hi:[1,0]
	v_pk_mul_f32 v[130:131], v[138:139], v[208:209] op_sel_hi:[1,0]
	v_pk_fma_f32 v[128:129], v[192:193], v[128:129], v[28:29]
	v_pk_fma_f32 v[130:131], v[190:191], v[130:131], v[30:31]
	v_bfe_u32 v132, v128, 16, 1
	v_add3_u32 v128, v128, v132, s28
	v_bfe_u32 v132, v129, 16, 1
	v_lshrrev_b32_e32 v128, 16, v128
	v_add3_u32 v129, v129, v132, s28
	v_and_or_b32 v128, v129, s29, v128
	v_bfe_u32 v129, v130, 16, 1
	v_add3_u32 v129, v130, v129, s28
	v_bfe_u32 v130, v131, 16, 1
	v_lshrrev_b32_e32 v129, 16, v129
	v_add3_u32 v130, v131, v130, s28
	v_and_or_b32 v129, v130, s29, v129
	global_store_dwordx2 v[134:135], v[128:129], off offset:3584
; __device__ __forceinline__ void norm_store2(bf16* O, int r0, int r1, int lane, const f32x4 (&v)[2][8], const f32x4 (&gm)[8], const f32x4 (&hs)[8]) {
;     ...
;     for (int q = 0; q < 2; ++q) { const int r = q == 0 ? r0 : r1; float s = 0.f;
; #pragma unroll
;         for (int j = 0; j < 8; ++j) s += (v[q][j].x * v[q][j].x + v[q][j].y * v[q][j].y) + (v[q][j].z * v[q][j].z + v[q][j].w * v[q][j].w);
;         const float rstd = 1.0f / sqrtf(wave_sum(s) * (1.0f / DMODEL) + 1e-6f);
.LBB0_329:
	v_mul_f32_e32 v128, v125, v125
	v_mul_f32_e32 v129, v127, v127
	v_fmac_f32_e32 v128, v124, v124
	v_fmac_f32_e32 v129, v126, v126
	v_add_f32_e32 v128, v128, v129
	v_mul_f32_e32 v129, v121, v121
	v_mul_f32_e32 v130, v123, v123
	v_fmac_f32_e32 v129, v120, v120
	v_fmac_f32_e32 v130, v122, v122
	v_add_f32_e32 v129, v129, v130
	v_add_f32_e32 v128, v128, v129
	v_mul_f32_e32 v129, v117, v117
	v_mul_f32_e32 v130, v119, v119
	v_fmac_f32_e32 v129, v116, v116
	v_fmac_f32_e32 v130, v118, v118
	v_add_f32_e32 v129, v129, v130
	v_add_f32_e32 v128, v128, v129
	v_mul_f32_e32 v129, v113, v113
	v_mul_f32_e32 v130, v115, v115
	v_fmac_f32_e32 v129, v112, v112
	v_fmac_f32_e32 v130, v114, v114
	v_add_f32_e32 v129, v129, v130
	v_add_f32_e32 v128, v128, v129
	v_mul_f32_e32 v129, v109, v109
	v_mul_f32_e32 v130, v111, v111
	v_fmac_f32_e32 v129, v108, v108
	v_fmac_f32_e32 v130, v110, v110
	v_add_f32_e32 v129, v129, v130
	v_add_f32_e32 v128, v128, v129
	v_mul_f32_e32 v129, v101, v101
	v_mul_f32_e32 v130, v103, v103
	v_fmac_f32_e32 v129, v100, v100
	v_fmac_f32_e32 v130, v102, v102
	v_add_f32_e32 v129, v129, v130
	v_add_f32_e32 v128, v128, v129
	v_mul_f32_e32 v129, v97, v97
	v_mul_f32_e32 v130, v99, v99
	v_fmac_f32_e32 v129, v96, v96
	v_fmac_f32_e32 v130, v98, v98
	v_add_f32_e32 v129, v129, v130
	v_add_f32_e32 v128, v128, v129
	v_mul_f32_e32 v129, v89, v89
	v_mul_f32_e32 v130, v91, v91
	v_fmac_f32_e32 v129, v88, v88
	v_fmac_f32_e32 v130, v90, v90
	v_add_f32_e32 v129, v129, v130
	v_add_f32_e32 v128, v128, v129
	ds_bpermute_b32 v129, v200, v128
	s_andn2_b64 vcc, exec, s[16:17]
	s_waitcnt lgkmcnt(0)
	v_add_f32_e32 v128, v128, v129
	ds_bpermute_b32 v129, v201, v128
	s_waitcnt lgkmcnt(0)
	v_add_f32_e32 v128, v128, v129
	ds_bpermute_b32 v129, v202, v128
	s_waitcnt lgkmcnt(0)
	v_add_f32_e32 v128, v128, v129
	ds_bpermute_b32 v129, v203, v128
	s_waitcnt lgkmcnt(0)
	v_add_f32_e32 v128, v128, v129
	ds_bpermute_b32 v129, v204, v128
	s_waitcnt lgkmcnt(0)
	v_add_f32_e32 v128, v128, v129
	ds_bpermute_b32 v129, v205, v128
	s_cbranch_vccnz .LBB0_324
; __device__ __forceinline__ unsigned pk2(float lo, float hi) { return f2bf(lo) | (f2bf(hi) << 16); }
; __device__ __forceinline__ void norm_store2(bf16* O, int r0, int r1, int lane, const f32x4 (&v)[2][8], const f32x4 (&gm)[8], const f32x4 (&hs)[8]) {
;     ...
;         const float rstd = 1.0f / sqrtf(wave_sum(s) * (1.0f / DMODEL) + 1e-6f);
;         if (r < M) { bf16* orow = O + (size_t)r * DMODEL;
; #pragma unroll
;             for (int j = 0; j < 8; ++j) { const f32x4 y = (v[q][j] * rstd) * gm[j] + hs[j]; v2u o; o.x = pk2(y.x, y.y); o.y = pk2(y.z, y.w); *(v2u*)(orow + 4 * (lane + 64 * j)) = o; } } }
	s_waitcnt lgkmcnt(0)
	v_add_f32_e32 v128, v128, v129
	v_fmamk_f32 v128, v128, 0x3a000000, v206
	v_mul_f32_e32 v129, 0x4f800000, v128
	v_cmp_gt_f32_e32 vcc, s27, v128
	s_ashr_i32 s15, s14, 31
	s_nop 0
	v_cndmask_b32_e32 v128, v128, v129, vcc
	v_sqrt_f32_e32 v129, v128
	s_nop 0
	v_add_u32_e32 v130, -1, v129
	v_fma_f32 v132, -v130, v129, v128
	v_add_u32_e32 v131, 1, v129
	v_cmp_ge_f32_e64 s[0:1], 0, v132
	s_nop 1
	v_cndmask_b32_e64 v130, v129, v130, s[0:1]
	v_fma_f32 v129, -v131, v129, v128
	v_cmp_lt_f32_e64 s[0:1], 0, v129
	s_nop 1
	v_cndmask_b32_e64 v129, v130, v131, s[0:1]
	v_mul_f32_e32 v130, 0x37800000, v129
	v_cndmask_b32_e32 v129, v129, v130, vcc
	v_cmp_class_f32_e32 vcc, v128, v207
	s_nop 1
	v_cndmask_b32_e32 v128, v129, v128, vcc
	v_div_scale_f32 v129, s[0:1], v128, v128, 1.0
	v_rcp_f32_e32 v130, v129
	s_lshl_b64 s[0:1], s[14:15], 12
	v_fma_f32 v131, -v129, v130, 1.0
	v_fmac_f32_e32 v130, v131, v130
	v_div_scale_f32 v131, vcc, 1.0, v128, 1.0
	v_mul_f32_e32 v132, v131, v130
	v_fma_f32 v133, -v129, v132, v131
	v_fmac_f32_e32 v132, v133, v130
	v_fma_f32 v129, -v129, v132, v131
	v_div_fmas_f32 v129, v129, v130, v132
	v_div_fixup_f32 v128, v129, v128, 1.0
	v_pk_mul_f32 v[124:125], v[124:125], v[128:129] op_sel_hi:[1,0]
	v_pk_mul_f32 v[126:127], v[126:127], v[128:129] op_sel_hi:[1,0]
	v_pk_fma_f32 v[124:125], v[164:165], v[124:125], v[0:1]
	v_pk_fma_f32 v[126:127], v[162:163], v[126:127], v[2:3]
	v_bfe_u32 v129, v124, 16, 1
	v_add3_u32 v124, v124, v129, s28
	v_bfe_u32 v129, v125, 16, 1
	v_lshrrev_b32_e32 v124, 16, v124
	v_add3_u32 v125, v125, v129, s28
	v_and_or_b32 v124, v125, s29, v124
	v_bfe_u32 v125, v126, 16, 1
	v_add3_u32 v125, v126, v125, s28
	v_bfe_u32 v126, v127, 16, 1
	v_lshrrev_b32_e32 v125, 16, v125
	v_add3_u32 v126, v127, v126, s28
	v_pk_mul_f32 v[120:121], v[120:121], v[128:129] op_sel_hi:[1,0]
	v_and_or_b32 v125, v126, s29, v125
	v_lshl_add_u64 v[126:127], v[198:199], 0, s[0:1]
	v_pk_fma_f32 v[120:121], v[168:169], v[120:121], v[4:5]
	global_store_dwordx2 v[126:127], v[124:125], off
	v_bfe_u32 v124, v120, 16, 1
	v_pk_mul_f32 v[122:123], v[122:123], v[128:129] op_sel_hi:[1,0]
	v_add3_u32 v120, v120, v124, s28
	v_bfe_u32 v124, v121, 16, 1
	v_pk_fma_f32 v[122:123], v[166:167], v[122:123], v[6:7]
	v_lshrrev_b32_e32 v120, 16, v120
	v_add3_u32 v121, v121, v124, s28
	v_and_or_b32 v120, v121, s29, v120
	v_bfe_u32 v121, v122, 16, 1
	v_add3_u32 v121, v122, v121, s28
	v_bfe_u32 v122, v123, 16, 1
	v_lshrrev_b32_e32 v121, 16, v121
	v_add3_u32 v122, v123, v122, s28
	v_pk_mul_f32 v[116:117], v[116:117], v[128:129] op_sel_hi:[1,0]
	v_and_or_b32 v121, v122, s29, v121
	v_pk_fma_f32 v[116:117], v[172:173], v[116:117], v[8:9]
	global_store_dwordx2 v[126:127], v[120:121], off offset:512
	v_bfe_u32 v120, v116, 16, 1
	v_pk_mul_f32 v[118:119], v[118:119], v[128:129] op_sel_hi:[1,0]
	v_add3_u32 v116, v116, v120, s28
	v_bfe_u32 v120, v117, 16, 1
	v_pk_fma_f32 v[118:119], v[170:171], v[118:119], v[10:11]
	v_lshrrev_b32_e32 v116, 16, v116
	v_add3_u32 v117, v117, v120, s28
	v_and_or_b32 v116, v117, s29, v116
	v_bfe_u32 v117, v118, 16, 1
	v_add3_u32 v117, v118, v117, s28
	v_bfe_u32 v118, v119, 16, 1
	v_lshrrev_b32_e32 v117, 16, v117
	v_add3_u32 v118, v119, v118, s28
	v_pk_mul_f32 v[112:113], v[112:113], v[128:129] op_sel_hi:[1,0]
	v_and_or_b32 v117, v118, s29, v117
	v_pk_fma_f32 v[112:113], v[176:177], v[112:113], v[12:13]
	global_store_dwordx2 v[126:127], v[116:117], off offset:1024
	v_bfe_u32 v116, v112, 16, 1
	v_pk_mul_f32 v[114:115], v[114:115], v[128:129] op_sel_hi:[1,0]
	v_add3_u32 v112, v112, v116, s28
	v_bfe_u32 v116, v113, 16, 1
	v_pk_fma_f32 v[114:115], v[174:175], v[114:115], v[14:15]
	v_lshrrev_b32_e32 v112, 16, v112
	v_add3_u32 v113, v113, v116, s28
	v_and_or_b32 v112, v113, s29, v112
	v_bfe_u32 v113, v114, 16, 1
	v_add3_u32 v113, v114, v113, s28
	v_bfe_u32 v114, v115, 16, 1
	v_lshrrev_b32_e32 v113, 16, v113
	v_add3_u32 v114, v115, v114, s28
	v_pk_mul_f32 v[108:109], v[108:109], v[128:129] op_sel_hi:[1,0]
	v_and_or_b32 v113, v114, s29, v113
	v_pk_fma_f32 v[108:109], v[180:181], v[108:109], v[16:17]
	global_store_dwordx2 v[126:127], v[112:113], off offset:1536
	v_bfe_u32 v112, v108, 16, 1
	v_pk_mul_f32 v[110:111], v[110:111], v[128:129] op_sel_hi:[1,0]
	v_add3_u32 v108, v108, v112, s28
	v_bfe_u32 v112, v109, 16, 1
	v_pk_fma_f32 v[110:111], v[178:179], v[110:111], v[18:19]
	v_lshrrev_b32_e32 v108, 16, v108
	v_add3_u32 v109, v109, v112, s28
	v_and_or_b32 v108, v109, s29, v108
	v_bfe_u32 v109, v110, 16, 1
	v_add3_u32 v109, v110, v109, s28
	v_bfe_u32 v110, v111, 16, 1
	v_lshrrev_b32_e32 v109, 16, v109
	v_add3_u32 v110, v111, v110, s28
	v_pk_mul_f32 v[100:101], v[100:101], v[128:129] op_sel_hi:[1,0]
	v_and_or_b32 v109, v110, s29, v109
	v_pk_fma_f32 v[100:101], v[184:185], v[100:101], v[20:21]
	global_store_dwordx2 v[126:127], v[108:109], off offset:2048
	v_bfe_u32 v108, v100, 16, 1
	v_pk_mul_f32 v[102:103], v[102:103], v[128:129] op_sel_hi:[1,0]
	v_add3_u32 v100, v100, v108, s28
	v_bfe_u32 v108, v101, 16, 1
	v_pk_fma_f32 v[102:103], v[182:183], v[102:103], v[22:23]
	v_lshrrev_b32_e32 v100, 16, v100
	v_add3_u32 v101, v101, v108, s28
	v_and_or_b32 v100, v101, s29, v100
	v_bfe_u32 v101, v102, 16, 1
	v_add3_u32 v101, v102, v101, s28
	v_bfe_u32 v102, v103, 16, 1
	v_lshrrev_b32_e32 v101, 16, v101
	v_add3_u32 v102, v103, v102, s28
	v_pk_mul_f32 v[96:97], v[96:97], v[128:129] op_sel_hi:[1,0]
	v_and_or_b32 v101, v102, s29, v101
	v_pk_fma_f32 v[96:97], v[188:189], v[96:97], v[24:25]
	global_store_dwordx2 v[126:127], v[100:101], off offset:2560
	v_bfe_u32 v100, v96, 16, 1
	v_pk_mul_f32 v[98:99], v[98:99], v[128:129] op_sel_hi:[1,0]
	v_add3_u32 v96, v96, v100, s28
	v_bfe_u32 v100, v97, 16, 1
	v_pk_fma_f32 v[98:99], v[186:187], v[98:99], v[26:27]
	v_lshrrev_b32_e32 v96, 16, v96
	v_add3_u32 v97, v97, v100, s28
	v_and_or_b32 v96, v97, s29, v96
	v_bfe_u32 v97, v98, 16, 1
	v_add3_u32 v97, v98, v97, s28
	v_bfe_u32 v98, v99, 16, 1
	v_lshrrev_b32_e32 v97, 16, v97
	v_add3_u32 v98, v99, v98, s28
	v_pk_mul_f32 v[88:89], v[88:89], v[128:129] op_sel_hi:[1,0]
	v_and_or_b32 v97, v98, s29, v97
	v_pk_fma_f32 v[88:89], v[192:193], v[88:89], v[28:29]
	global_store_dwordx2 v[126:127], v[96:97], off offset:3072
	v_bfe_u32 v96, v88, 16, 1
	v_pk_mul_f32 v[90:91], v[90:91], v[128:129] op_sel_hi:[1,0]
	v_add3_u32 v88, v88, v96, s28
	v_bfe_u32 v96, v89, 16, 1
	v_pk_fma_f32 v[90:91], v[190:191], v[90:91], v[30:31]
	v_lshrrev_b32_e32 v88, 16, v88
	v_add3_u32 v89, v89, v96, s28
	v_and_or_b32 v88, v89, s29, v88
	v_bfe_u32 v89, v90, 16, 1
	v_add3_u32 v89, v90, v89, s28
	v_bfe_u32 v90, v91, 16, 1
	v_lshrrev_b32_e32 v89, 16, v89
	v_add3_u32 v90, v91, v90, s28
	v_and_or_b32 v89, v90, s29, v89
	global_store_dwordx2 v[126:127], v[88:89], off offset:3584
	s_branch .LBB0_324

; __global__ void __launch_bounds__(NTHR, 2) mk_fwd(Args args) {
;     ...
;         for (int i = bx * NTHR + tid; i < 2 * M; i += G * NTHR) p_SSQ[i] = 0ull;
.LBB0_333:
	v_add_u32_e32 v0, s4, v0
	s_waitcnt lgkmcnt(0)
	v_readfirstlane_b32 s12, v2
	v_readfirstlane_b32 s13, v3
	v_cmp_lt_i32_e32 vcc, s5, v0
	s_or_b64 s[10:11], vcc, s[10:11]
	v_lshl_add_u64 v[8:9], s[12:13], 0, v[4:5]
	v_lshl_add_u64 v[4:5], v[4:5], 0, s[8:9]
	global_store_dwordx2 v[8:9], v[6:7], off
	s_andn2_b64 exec, exec, s[10:11]
	s_cbranch_execnz .LBB0_333

; __global__ void __launch_bounds__(NTHR, 2) mk_fwd(Args args) {
;     ...
;         for (int p = gw; p < 65536; p += NGW) ((unsigned*)(p_UGS + (size_t)p * 384 + 256))[lane] = 0u;
; #pragma unroll
;         for (int which = 0; which < 2; ++which) { const bf16* Wt = which == 0 ? p_WIN : p_W2U; const float* shv = p_mod + (which == 0 ? 3 : 6) * DMODEL; float* bvo = p_BV + (which == 0 ? 0 : NIN); const int nrows = which == 0 ? NIN : NUP;
;             float shr[32];
; #pragma unroll
;             for (int j = 0; j < 4; ++j)
; #pragma unroll
;                 for (int e = 0; e < 8; ++e) shr[j * 8 + e] = shv[j * 512 + lane * 8 + e];
.LBB0_336:
	ds_read_b64 v[4:5], v2
	s_add_i32 s4, s4, s80
	s_cmp_gt_i32 s4, 0xffff
	s_waitcnt lgkmcnt(0)
	v_readfirstlane_b32 s8, v4
	v_readfirstlane_b32 s9, v5
	s_nop 1
	v_lshl_add_u64 v[4:5], s[8:9], 0, v[0:1]
	v_lshl_add_u64 v[0:1], v[0:1], 0, s[0:1]
	global_store_dword v[4:5], v3, off
	s_cbranch_scc0 .LBB0_336
.LBB0_337:
	s_add_i32 s0, 0, 0x20118
	v_mov_b32_e32 v0, s0
	ds_read_b64 v[82:83], v0
	v_lshlrev_b32_e32 v80, 3, v160
	v_or_b32_e32 v84, 4, v80
	v_cmp_ne_u32_e64 s[0:1], 0, v160
	v_cmp_eq_u32_e64 s[4:5], 0, v160
	v_ashrrev_i32_e32 v81, 31, v80
	s_waitcnt lgkmcnt(0)
	v_readfirstlane_b32 s8, v82
	v_readfirstlane_b32 s9, v83
	v_ashrrev_i32_e32 v85, 31, v84
	s_movk_i32 s10, 0x1000
	s_cmpk_lt_i32 s72, 0x1000
	v_mov_b32_e32 v0, v82
	v_mov_b32_e32 v1, v83
	s_cbranch_scc0 .LBB0_349
	s_add_u32 s12, s8, 0x406000
	s_addc_u32 s13, s9, 0
	v_lshl_add_u64 v[16:17], v[80:81], 2, s[12:13]
	s_waitcnt vmcnt(0)
	v_add_co_u32_e32 v32, vcc, s10, v16
	v_lshl_add_u64 v[18:19], v[84:85], 2, s[12:13]
	s_nop 0
	v_addc_co_u32_e32 v33, vcc, 0, v17, vcc
	global_load_dwordx4 v[0:3], v[16:17], off
	global_load_dwordx4 v[4:7], v[16:17], off offset:2048
	global_load_dwordx4 v[8:11], v[18:19], off
	global_load_dwordx4 v[12:15], v[16:17], off offset:2064
	s_nop 0
	global_load_dwordx4 v[16:19], v[32:33], off
	global_load_dwordx4 v[20:23], v[32:33], off offset:16
	global_load_dwordx4 v[24:27], v[32:33], off offset:2048
	global_load_dwordx4 v[28:31], v[32:33], off offset:2064
	s_add_u32 s24, s8, 0x800000
	s_addc_u32 s25, s9, 0
	v_lshl_add_u64 v[32:33], v[80:81], 1, s[8:9]
	s_mov_b64 s[8:9], 0x9400000
	v_lshl_add_u64 v[86:87], v[32:33], 0, s[8:9]
	v_mbcnt_lo_u32_b32 v32, -1, 0
	v_mbcnt_hi_u32_b32 v32, -1, v32
	v_and_b32_e32 v33, 64, v32
	v_add_u32_e32 v33, 64, v33
	v_xor_b32_e32 v34, 1, v32
	v_cmp_lt_i32_e32 vcc, v34, v33
	s_lshl_b32 s26, s70, 5
	s_lshl_b32 s27, s70, 4
	v_cndmask_b32_e32 v34, v32, v34, vcc
	v_lshlrev_b32_e32 v88, 2, v34
	v_xor_b32_e32 v34, 2, v32
	v_cmp_lt_i32_e32 vcc, v34, v33
	s_mov_b32 s8, s72
	s_nop 0
	v_cndmask_b32_e32 v34, v32, v34, vcc
	v_lshlrev_b32_e32 v89, 2, v34
	v_xor_b32_e32 v34, 4, v32
	v_cmp_lt_i32_e32 vcc, v34, v33
	s_nop 1
	v_cndmask_b32_e32 v34, v32, v34, vcc
	v_lshlrev_b32_e32 v90, 2, v34
	v_xor_b32_e32 v34, 8, v32
	v_cmp_lt_i32_e32 vcc, v34, v33
	s_nop 1
	v_cndmask_b32_e32 v34, v32, v34, vcc
	v_lshlrev_b32_e32 v91, 2, v34
	v_xor_b32_e32 v34, 16, v32
	v_cmp_lt_i32_e32 vcc, v34, v33
	s_nop 1
	v_cndmask_b32_e32 v34, v32, v34, vcc
	v_lshlrev_b32_e32 v92, 2, v34
	v_xor_b32_e32 v34, 32, v32
	v_cmp_lt_i32_e32 vcc, v34, v33
	s_nop 1
	v_cndmask_b32_e32 v32, v32, v34, vcc
	v_lshlrev_b32_e32 v93, 2, v32
	s_branch .LBB0_340

; __device__ __forceinline__ float blo(unsigned w) { return __uint_as_float(w << 16); }
; __device__ __forceinline__ float bhi(unsigned w) { return __uint_as_float(w & 0xffff0000u); }
; __global__ void __launch_bounds__(NTHR, 2) mk_fwd(Args args) {
;     ...
;             for (int r = gw; r < nrows; r += 4 * NGW) {
;                 v4u w[4][4];
; #pragma unroll
;                 for (int q = 0; q < 4; ++q) { const int rq = (r + q * NGW < nrows) ? r + q * NGW : r; const bf16* wr_ = Wt + (size_t)rq * DMODEL + lane * 8;
; #pragma unroll
;                     for (int j = 0; j < 4; ++j) w[q][j] = *(const v4u*)(wr_ + j * 512); }
; #pragma unroll
;                 for (int q = 0; q < 4; ++q) { float acc = 0.f;
; #pragma unroll
;                     for (int j = 0; j < 4; ++j) { const v4u x = w[q][j];
;                         acc += blo(x.x) * shr[j * 8 + 0] + bhi(x.x) * shr[j * 8 + 1] + blo(x.y) * shr[j * 8 + 2] + bhi(x.y) * shr[j * 8 + 3] + blo(x.z) * shr[j * 8 + 4] + bhi(x.z) * shr[j * 8 + 5] + blo(x.w) * shr[j * 8 + 6] + bhi(x.w) * shr[j * 8 + 7]; }
;                     acc = wave_sum(acc); if (lane == 0 && r + q * NGW < nrows) bvo[r + q * NGW] = acc; } } }
.LBB0_340:
	s_ashr_i32 s9, s8, 31
	s_lshl_b64 s[10:11], s[8:9], 12
	s_waitcnt lgkmcnt(0)
	v_lshl_add_u64 v[32:33], v[86:87], 0, s[10:11]
	global_load_dwordx4 v[94:97], v[32:33], off
	global_load_dwordx4 v[98:101], v[32:33], off offset:1024
	global_load_dwordx4 v[102:105], v[32:33], off offset:2048
	global_load_dwordx4 v[106:109], v[32:33], off offset:3072
	s_add_i32 s18, s80, s8
	s_cmpk_gt_i32 s18, 0xfff
	s_cselect_b64 s[20:21], -1, 0
	s_and_b64 s[10:11], s[20:21], exec
	s_cselect_b32 s10, s8, s18
	s_ashr_i32 s11, s10, 31
	s_add_i32 s14, s27, s8
	s_lshl_b64 s[10:11], s[10:11], 12
	s_cmpk_gt_i32 s14, 0xfff
	s_cselect_b64 s[16:17], -1, 0
	v_lshl_add_u64 v[32:33], v[86:87], 0, s[10:11]
	s_and_b64 s[10:11], s[16:17], exec
	s_cselect_b32 s12, s8, s14
	s_ashr_i32 s13, s12, 31
	s_add_i32 s10, s3, s8
	s_lshl_b64 s[12:13], s[12:13], 12
	s_cmpk_gt_i32 s10, 0xfff
	global_load_dwordx4 v[76:79], v[32:33], off
	global_load_dwordx4 v[72:75], v[32:33], off offset:1024
	global_load_dwordx4 v[68:71], v[32:33], off offset:2048
	global_load_dwordx4 v[64:67], v[32:33], off offset:3072
	v_lshl_add_u64 v[32:33], v[86:87], 0, s[12:13]
	s_cselect_b64 s[12:13], -1, 0
	s_and_b64 s[22:23], s[12:13], exec
	s_cselect_b32 s22, s8, s10
	s_ashr_i32 s23, s22, 31
	s_lshl_b64 s[22:23], s[22:23], 12
	v_lshl_add_u64 v[110:111], v[86:87], 0, s[22:23]
	global_load_dwordx4 v[60:63], v[32:33], off
	global_load_dwordx4 v[56:59], v[32:33], off offset:1024
	global_load_dwordx4 v[52:55], v[32:33], off offset:2048
	global_load_dwordx4 v[48:51], v[32:33], off offset:3072
	global_load_dwordx4 v[44:47], v[110:111], off
	global_load_dwordx4 v[40:43], v[110:111], off offset:1024
	global_load_dwordx4 v[36:39], v[110:111], off offset:2048
	s_nop 0
	global_load_dwordx4 v[32:35], v[110:111], off offset:3072
	s_waitcnt vmcnt(0) lgkmcnt(0)
	v_lshlrev_b32_e32 v110, 16, v94
	v_and_b32_e32 v94, 0xffff0000, v94
	v_mul_f32_e32 v94, v1, v94
	v_lshlrev_b32_e32 v111, 16, v95
	v_lshlrev_b32_e32 v114, 16, v98
	v_and_b32_e32 v98, 0xffff0000, v98
	v_fmac_f32_e32 v94, v0, v110
	v_and_b32_e32 v95, 0xffff0000, v95
	v_lshlrev_b32_e32 v118, 16, v102
	v_and_b32_e32 v102, 0xffff0000, v102
	v_mul_f32_e32 v98, v5, v98
	v_fmac_f32_e32 v94, v2, v111
	v_lshlrev_b32_e32 v112, 16, v96
	v_lshlrev_b32_e32 v115, 16, v99
	v_mul_f32_e32 v102, v17, v102
	v_fmac_f32_e32 v98, v4, v114
	v_fmac_f32_e32 v94, v3, v95
	v_and_b32_e32 v95, 0xffff0000, v106
	v_and_b32_e32 v96, 0xffff0000, v96
	v_and_b32_e32 v99, 0xffff0000, v99
	v_lshlrev_b32_e32 v119, 16, v103
	v_lshlrev_b32_e32 v122, 16, v106
	v_fmac_f32_e32 v102, v16, v118
	v_fmac_f32_e32 v98, v6, v115
	v_fmac_f32_e32 v94, v8, v112
	v_mul_f32_e32 v95, v25, v95
	v_lshlrev_b32_e32 v116, 16, v100
	v_and_b32_e32 v103, 0xffff0000, v103
	v_fmac_f32_e32 v102, v18, v119
	v_fmac_f32_e32 v98, v7, v99
	v_fmac_f32_e32 v94, v9, v96
	v_fmac_f32_e32 v95, v24, v122
	v_lshlrev_b32_e32 v96, 16, v107
	v_lshlrev_b32_e32 v113, 16, v97
	v_and_b32_e32 v100, 0xffff0000, v100
	v_lshlrev_b32_e32 v120, 16, v104
	v_fmac_f32_e32 v102, v19, v103
	v_fmac_f32_e32 v98, v12, v116
	v_fmac_f32_e32 v95, v26, v96
	v_and_b32_e32 v96, 0xffff0000, v107
	v_and_b32_e32 v97, 0xffff0000, v97
	v_lshlrev_b32_e32 v117, 16, v101
	v_and_b32_e32 v104, 0xffff0000, v104
	v_fmac_f32_e32 v102, v20, v120
	v_fmac_f32_e32 v98, v13, v100
	v_fmac_f32_e32 v94, v10, v113
	v_fmac_f32_e32 v95, v27, v96
	v_lshlrev_b32_e32 v96, 16, v108
	v_and_b32_e32 v101, 0xffff0000, v101
	v_lshlrev_b32_e32 v121, 16, v105
	v_fmac_f32_e32 v102, v21, v104
	v_fmac_f32_e32 v98, v14, v117
	v_fmac_f32_e32 v94, v11, v97
	v_fmac_f32_e32 v95, v28, v96
	v_and_b32_e32 v96, 0xffff0000, v108
	v_and_b32_e32 v105, 0xffff0000, v105
	v_fmac_f32_e32 v102, v22, v121
	v_fmac_f32_e32 v98, v15, v101
	v_add_f32_e32 v94, 0, v94
	v_fmac_f32_e32 v95, v29, v96
	v_lshlrev_b32_e32 v96, 16, v109
	v_fmac_f32_e32 v102, v23, v105
	v_add_f32_e32 v94, v94, v98
	v_fmac_f32_e32 v95, v30, v96
	v_and_b32_e32 v96, 0xffff0000, v109
	v_add_f32_e32 v94, v94, v102
	v_fmac_f32_e32 v95, v31, v96
	v_add_f32_e32 v94, v94, v95
	ds_bpermute_b32 v95, v88, v94
	s_waitcnt lgkmcnt(0)
	v_add_f32_e32 v94, v94, v95
	ds_bpermute_b32 v95, v89, v94
	s_waitcnt lgkmcnt(0)
	v_add_f32_e32 v94, v94, v95
	ds_bpermute_b32 v95, v90, v94
	s_waitcnt lgkmcnt(0)
	v_add_f32_e32 v94, v94, v95
	ds_bpermute_b32 v95, v91, v94
	s_waitcnt lgkmcnt(0)
	v_add_f32_e32 v94, v94, v95
	ds_bpermute_b32 v95, v92, v94
	s_waitcnt lgkmcnt(0)
	v_add_f32_e32 v94, v94, v95
	ds_bpermute_b32 v95, v93, v94
	s_and_saveexec_b64 s[22:23], s[4:5]
	s_cbranch_execz .LBB0_342
	s_lshl_b64 s[28:29], s[8:9], 2
	s_add_u32 s28, s24, s28
	s_addc_u32 s29, s25, s29
	s_waitcnt lgkmcnt(0)
	v_add_f32_e32 v96, v94, v95
	v_mov_b64_e32 v[94:95], s[28:29]
	global_store_dword v[94:95], v96, off
; __device__ __forceinline__ float blo(unsigned w) { return __uint_as_float(w << 16); }
; __device__ __forceinline__ float bhi(unsigned w) { return __uint_as_float(w & 0xffff0000u); }
; __global__ void __launch_bounds__(NTHR, 2) mk_fwd(Args args) {
;     ...
;                 for (int q = 0; q < 4; ++q) { float acc = 0.f;
; #pragma unroll
;                     for (int j = 0; j < 4; ++j) { const v4u x = w[q][j];
;                         acc += blo(x.x) * shr[j * 8 + 0] + bhi(x.x) * shr[j * 8 + 1] + blo(x.y) * shr[j * 8 + 2] + bhi(x.y) * shr[j * 8 + 3] + blo(x.z) * shr[j * 8 + 4] + bhi(x.z) * shr[j * 8 + 5] + blo(x.w) * shr[j * 8 + 6] + bhi(x.w) * shr[j * 8 + 7]; }
;                     acc = wave_sum(acc); if (lane == 0 && r + q * NGW < nrows) bvo[r + q * NGW] = acc; } } }
.LBB0_342:
	s_or_b64 exec, exec, s[22:23]
	v_lshlrev_b32_e32 v94, 16, v76
	v_and_b32_e32 v76, 0xffff0000, v76
	v_mul_f32_e32 v76, v1, v76
	v_fmac_f32_e32 v76, v0, v94
	v_lshlrev_b32_e32 v94, 16, v77
	v_fmac_f32_e32 v76, v2, v94
	v_and_b32_e32 v77, 0xffff0000, v77
	v_fmac_f32_e32 v76, v3, v77
	v_lshlrev_b32_e32 v77, 16, v78
	v_fmac_f32_e32 v76, v8, v77
	v_and_b32_e32 v77, 0xffff0000, v78
	v_fmac_f32_e32 v76, v9, v77
	v_lshlrev_b32_e32 v77, 16, v79
	v_fmac_f32_e32 v76, v10, v77
	v_and_b32_e32 v77, 0xffff0000, v79
	v_fmac_f32_e32 v76, v11, v77
	v_lshlrev_b32_e32 v77, 16, v72
	v_and_b32_e32 v72, 0xffff0000, v72
	v_mul_f32_e32 v72, v5, v72
	v_fmac_f32_e32 v72, v4, v77
	v_lshlrev_b32_e32 v77, 16, v73
	v_fmac_f32_e32 v72, v6, v77
	v_and_b32_e32 v73, 0xffff0000, v73
	v_fmac_f32_e32 v72, v7, v73
	v_lshlrev_b32_e32 v73, 16, v74
	v_fmac_f32_e32 v72, v12, v73
	v_and_b32_e32 v73, 0xffff0000, v74
	v_fmac_f32_e32 v72, v13, v73
	v_lshlrev_b32_e32 v73, 16, v75
	v_fmac_f32_e32 v72, v14, v73
	v_and_b32_e32 v73, 0xffff0000, v75
	v_fmac_f32_e32 v72, v15, v73
	v_lshlrev_b32_e32 v73, 16, v68
	v_and_b32_e32 v68, 0xffff0000, v68
	v_mul_f32_e32 v68, v17, v68
	v_fmac_f32_e32 v68, v16, v73
	v_lshlrev_b32_e32 v73, 16, v69
	v_fmac_f32_e32 v68, v18, v73
	v_and_b32_e32 v69, 0xffff0000, v69
	v_fmac_f32_e32 v68, v19, v69
	v_lshlrev_b32_e32 v69, 16, v70
	v_fmac_f32_e32 v68, v20, v69
	v_and_b32_e32 v69, 0xffff0000, v70
	v_fmac_f32_e32 v68, v21, v69
	v_lshlrev_b32_e32 v69, 16, v71
	v_fmac_f32_e32 v68, v22, v69
	v_and_b32_e32 v69, 0xffff0000, v71
	v_fmac_f32_e32 v68, v23, v69
	v_lshlrev_b32_e32 v69, 16, v64
	v_and_b32_e32 v64, 0xffff0000, v64
	v_mul_f32_e32 v64, v25, v64
	v_fmac_f32_e32 v64, v24, v69
	v_lshlrev_b32_e32 v69, 16, v65
	v_fmac_f32_e32 v64, v26, v69
	v_and_b32_e32 v65, 0xffff0000, v65
	v_fmac_f32_e32 v64, v27, v65
	v_lshlrev_b32_e32 v65, 16, v66
	v_fmac_f32_e32 v64, v28, v65
	v_and_b32_e32 v65, 0xffff0000, v66
	v_add_f32_e32 v76, 0, v76
	v_fmac_f32_e32 v64, v29, v65
	v_lshlrev_b32_e32 v65, 16, v67
	v_add_f32_e32 v72, v76, v72
	v_fmac_f32_e32 v64, v30, v65
	v_and_b32_e32 v65, 0xffff0000, v67
	v_add_f32_e32 v68, v72, v68
	v_fmac_f32_e32 v64, v31, v65
	v_add_f32_e32 v64, v68, v64
	ds_bpermute_b32 v65, v88, v64
	s_nor_b64 s[22:23], s[0:1], s[20:21]
	s_waitcnt lgkmcnt(0)
	v_add_f32_e32 v64, v64, v65
	ds_bpermute_b32 v65, v89, v64
	s_waitcnt lgkmcnt(0)
	v_add_f32_e32 v64, v64, v65
	ds_bpermute_b32 v65, v90, v64
	s_waitcnt lgkmcnt(0)
	v_add_f32_e32 v64, v64, v65
	ds_bpermute_b32 v65, v91, v64
	s_waitcnt lgkmcnt(0)
	v_add_f32_e32 v64, v64, v65
	ds_bpermute_b32 v65, v92, v64
	s_waitcnt lgkmcnt(0)
	v_add_f32_e32 v64, v64, v65
	ds_bpermute_b32 v65, v93, v64
	s_and_saveexec_b64 s[20:21], s[22:23]
	s_cbranch_execz .LBB0_344
	s_ashr_i32 s19, s18, 31
	s_lshl_b64 s[18:19], s[18:19], 2
	s_add_u32 s18, s24, s18
	s_addc_u32 s19, s25, s19
	s_waitcnt lgkmcnt(0)
	v_add_f32_e32 v66, v64, v65
	v_mov_b64_e32 v[64:65], s[18:19]
	global_store_dword v[64:65], v66, off
.LBB0_344:
	s_or_b64 exec, exec, s[20:21]
	v_lshlrev_b32_e32 v64, 16, v60
	v_and_b32_e32 v60, 0xffff0000, v60
	v_mul_f32_e32 v60, v1, v60
	v_fmac_f32_e32 v60, v0, v64
	v_lshlrev_b32_e32 v64, 16, v61
	v_fmac_f32_e32 v60, v2, v64
	v_and_b32_e32 v61, 0xffff0000, v61
	v_fmac_f32_e32 v60, v3, v61
	v_lshlrev_b32_e32 v61, 16, v62
	v_fmac_f32_e32 v60, v8, v61
	v_and_b32_e32 v61, 0xffff0000, v62
	v_fmac_f32_e32 v60, v9, v61
	v_lshlrev_b32_e32 v61, 16, v63
	v_fmac_f32_e32 v60, v10, v61
	v_and_b32_e32 v61, 0xffff0000, v63
	v_fmac_f32_e32 v60, v11, v61
	v_lshlrev_b32_e32 v61, 16, v56
	v_and_b32_e32 v56, 0xffff0000, v56
	v_mul_f32_e32 v56, v5, v56
	v_fmac_f32_e32 v56, v4, v61
	v_lshlrev_b32_e32 v61, 16, v57
	v_fmac_f32_e32 v56, v6, v61
	v_and_b32_e32 v57, 0xffff0000, v57
	v_fmac_f32_e32 v56, v7, v57
	v_lshlrev_b32_e32 v57, 16, v58
	v_fmac_f32_e32 v56, v12, v57
	v_and_b32_e32 v57, 0xffff0000, v58
	v_fmac_f32_e32 v56, v13, v57
	v_lshlrev_b32_e32 v57, 16, v59
	v_fmac_f32_e32 v56, v14, v57
	v_and_b32_e32 v57, 0xffff0000, v59
	v_fmac_f32_e32 v56, v15, v57
	v_lshlrev_b32_e32 v57, 16, v52
	v_and_b32_e32 v52, 0xffff0000, v52
	v_mul_f32_e32 v52, v17, v52
	v_fmac_f32_e32 v52, v16, v57
	v_lshlrev_b32_e32 v57, 16, v53
	v_fmac_f32_e32 v52, v18, v57
	v_and_b32_e32 v53, 0xffff0000, v53
	v_fmac_f32_e32 v52, v19, v53
	v_lshlrev_b32_e32 v53, 16, v54
	v_fmac_f32_e32 v52, v20, v53
	v_and_b32_e32 v53, 0xffff0000, v54
	v_fmac_f32_e32 v52, v21, v53
	v_lshlrev_b32_e32 v53, 16, v55
	v_fmac_f32_e32 v52, v22, v53
	v_and_b32_e32 v53, 0xffff0000, v55
	v_fmac_f32_e32 v52, v23, v53
	v_lshlrev_b32_e32 v53, 16, v48
	v_and_b32_e32 v48, 0xffff0000, v48
	v_mul_f32_e32 v48, v25, v48
	v_fmac_f32_e32 v48, v24, v53
	v_lshlrev_b32_e32 v53, 16, v49
	v_fmac_f32_e32 v48, v26, v53
	v_and_b32_e32 v49, 0xffff0000, v49
	v_fmac_f32_e32 v48, v27, v49
	v_lshlrev_b32_e32 v49, 16, v50
	v_fmac_f32_e32 v48, v28, v49
	v_and_b32_e32 v49, 0xffff0000, v50
	v_add_f32_e32 v60, 0, v60
	v_fmac_f32_e32 v48, v29, v49
	v_lshlrev_b32_e32 v49, 16, v51
	v_add_f32_e32 v56, v60, v56
	v_fmac_f32_e32 v48, v30, v49
	v_and_b32_e32 v49, 0xffff0000, v51
	v_add_f32_e32 v52, v56, v52
	v_fmac_f32_e32 v48, v31, v49
	v_add_f32_e32 v48, v52, v48
	ds_bpermute_b32 v49, v88, v48
	s_nor_b64 s[18:19], s[0:1], s[16:17]
	s_waitcnt lgkmcnt(0)
	v_add_f32_e32 v48, v48, v49
	ds_bpermute_b32 v49, v89, v48
	s_waitcnt lgkmcnt(0)
	v_add_f32_e32 v48, v48, v49
	ds_bpermute_b32 v49, v90, v48
	s_waitcnt lgkmcnt(0)
	v_add_f32_e32 v48, v48, v49
	ds_bpermute_b32 v49, v91, v48
	s_waitcnt lgkmcnt(0)
	v_add_f32_e32 v48, v48, v49
	ds_bpermute_b32 v49, v92, v48
	s_waitcnt lgkmcnt(0)
	v_add_f32_e32 v48, v48, v49
	ds_bpermute_b32 v49, v93, v48
	s_and_saveexec_b64 s[16:17], s[18:19]
	s_cbranch_execz .LBB0_346
	s_ashr_i32 s15, s14, 31
	s_lshl_b64 s[14:15], s[14:15], 2
	s_add_u32 s14, s24, s14
	s_addc_u32 s15, s25, s15
	s_waitcnt lgkmcnt(0)
	v_add_f32_e32 v50, v48, v49
	v_mov_b64_e32 v[48:49], s[14:15]
	global_store_dword v[48:49], v50, off
; __device__ __forceinline__ float blo(unsigned w) { return __uint_as_float(w << 16); }
; __device__ __forceinline__ float bhi(unsigned w) { return __uint_as_float(w & 0xffff0000u); }
; __global__ void __launch_bounds__(NTHR, 2) mk_fwd(Args args) {
;     ...
;                 for (int q = 0; q < 4; ++q) { float acc = 0.f;
; #pragma unroll
;                     for (int j = 0; j < 4; ++j) { const v4u x = w[q][j];
;                         acc += blo(x.x) * shr[j * 8 + 0] + bhi(x.x) * shr[j * 8 + 1] + blo(x.y) * shr[j * 8 + 2] + bhi(x.y) * shr[j * 8 + 3] + blo(x.z) * shr[j * 8 + 4] + bhi(x.z) * shr[j * 8 + 5] + blo(x.w) * shr[j * 8 + 6] + bhi(x.w) * shr[j * 8 + 7]; }
;                     acc = wave_sum(acc); if (lane == 0 && r + q * NGW < nrows) bvo[r + q * NGW] = acc; } } }
.LBB0_346:
	s_or_b64 exec, exec, s[16:17]
	v_lshlrev_b32_e32 v48, 16, v44
	v_and_b32_e32 v44, 0xffff0000, v44
	v_mul_f32_e32 v44, v1, v44
	v_fmac_f32_e32 v44, v0, v48
	v_lshlrev_b32_e32 v48, 16, v45
	v_fmac_f32_e32 v44, v2, v48
	v_and_b32_e32 v45, 0xffff0000, v45
	v_fmac_f32_e32 v44, v3, v45
	v_lshlrev_b32_e32 v45, 16, v46
	v_fmac_f32_e32 v44, v8, v45
	v_and_b32_e32 v45, 0xffff0000, v46
	v_fmac_f32_e32 v44, v9, v45
	v_lshlrev_b32_e32 v45, 16, v47
	v_fmac_f32_e32 v44, v10, v45
	v_and_b32_e32 v45, 0xffff0000, v47
	v_fmac_f32_e32 v44, v11, v45
	v_lshlrev_b32_e32 v45, 16, v40
	v_and_b32_e32 v40, 0xffff0000, v40
	v_mul_f32_e32 v40, v5, v40
	v_fmac_f32_e32 v40, v4, v45
	v_lshlrev_b32_e32 v45, 16, v41
	v_fmac_f32_e32 v40, v6, v45
	v_and_b32_e32 v41, 0xffff0000, v41
	v_fmac_f32_e32 v40, v7, v41
	v_lshlrev_b32_e32 v41, 16, v42
	v_fmac_f32_e32 v40, v12, v41
	v_and_b32_e32 v41, 0xffff0000, v42
	v_fmac_f32_e32 v40, v13, v41
	v_lshlrev_b32_e32 v41, 16, v43
	v_fmac_f32_e32 v40, v14, v41
	v_and_b32_e32 v41, 0xffff0000, v43
	v_fmac_f32_e32 v40, v15, v41
	v_lshlrev_b32_e32 v41, 16, v36
	v_and_b32_e32 v36, 0xffff0000, v36
	v_mul_f32_e32 v36, v17, v36
	v_fmac_f32_e32 v36, v16, v41
	v_lshlrev_b32_e32 v41, 16, v37
	v_fmac_f32_e32 v36, v18, v41
	v_and_b32_e32 v37, 0xffff0000, v37
	v_fmac_f32_e32 v36, v19, v37
	v_lshlrev_b32_e32 v37, 16, v38
	v_fmac_f32_e32 v36, v20, v37
	v_and_b32_e32 v37, 0xffff0000, v38
	v_fmac_f32_e32 v36, v21, v37
	v_lshlrev_b32_e32 v37, 16, v39
	v_fmac_f32_e32 v36, v22, v37
	v_and_b32_e32 v37, 0xffff0000, v39
	v_fmac_f32_e32 v36, v23, v37
	v_lshlrev_b32_e32 v37, 16, v32
	v_and_b32_e32 v32, 0xffff0000, v32
	v_mul_f32_e32 v32, v25, v32
	v_fmac_f32_e32 v32, v24, v37
	v_lshlrev_b32_e32 v37, 16, v33
	v_fmac_f32_e32 v32, v26, v37
	v_and_b32_e32 v33, 0xffff0000, v33
	v_fmac_f32_e32 v32, v27, v33
	v_lshlrev_b32_e32 v33, 16, v34
	v_fmac_f32_e32 v32, v28, v33
	v_and_b32_e32 v33, 0xffff0000, v34
	v_add_f32_e32 v44, 0, v44
	v_fmac_f32_e32 v32, v29, v33
	v_lshlrev_b32_e32 v33, 16, v35
	v_add_f32_e32 v40, v44, v40
	v_fmac_f32_e32 v32, v30, v33
	v_and_b32_e32 v33, 0xffff0000, v35
	v_add_f32_e32 v36, v40, v36
	v_fmac_f32_e32 v32, v31, v33
	v_add_f32_e32 v32, v36, v32
	ds_bpermute_b32 v33, v88, v32
	s_nor_b64 s[14:15], s[0:1], s[12:13]
	s_waitcnt lgkmcnt(0)
	v_add_f32_e32 v32, v32, v33
	ds_bpermute_b32 v33, v89, v32
	s_waitcnt lgkmcnt(0)
	v_add_f32_e32 v32, v32, v33
	ds_bpermute_b32 v33, v90, v32
	s_waitcnt lgkmcnt(0)
	v_add_f32_e32 v32, v32, v33
	ds_bpermute_b32 v33, v91, v32
	s_waitcnt lgkmcnt(0)
	v_add_f32_e32 v32, v32, v33
	ds_bpermute_b32 v33, v92, v32
	s_waitcnt lgkmcnt(0)
	v_add_f32_e32 v32, v32, v33
	ds_bpermute_b32 v33, v93, v32
	s_and_saveexec_b64 s[12:13], s[14:15]
	s_cbranch_execz .LBB0_339
	s_ashr_i32 s11, s10, 31
	s_lshl_b64 s[10:11], s[10:11], 2
	s_add_u32 s10, s24, s10
	s_addc_u32 s11, s25, s11
	s_waitcnt lgkmcnt(0)
	v_add_f32_e32 v34, v32, v33
	v_mov_b64_e32 v[32:33], s[10:11]
	global_store_dword v[32:33], v34, off
	s_branch .LBB0_339

; __global__ void __launch_bounds__(NTHR, 2) mk_fwd(Args args) {
;     ...
;         for (int which = 0; which < 2; ++which) { const bf16* Wt = which == 0 ? p_WIN : p_W2U; const float* shv = p_mod + (which == 0 ? 3 : 6) * DMODEL; float* bvo = p_BV + (which == 0 ? 0 : NIN); const int nrows = which == 0 ? NIN : NUP;
;             float shr[32];
; #pragma unroll
;             for (int j = 0; j < 4; ++j)
; #pragma unroll
;                 for (int e = 0; e < 8; ++e) shr[j * 8 + e] = shv[j * 512 + lane * 8 + e];
.LBB0_349:
	s_waitcnt lgkmcnt(0)
	v_readfirstlane_b32 s8, v0
	v_readfirstlane_b32 s9, v1
	v_readfirstlane_b32 s10, v82
	s_cmpk_gt_i32 s72, 0x2bff
	v_readfirstlane_b32 s11, v83
	s_cbranch_scc1 .LBB0_360
	s_add_u32 s12, s10, 0x40c000
	s_addc_u32 s13, s11, 0
	v_lshl_add_u64 v[16:17], v[80:81], 2, s[12:13]
	s_waitcnt vmcnt(0)
	v_add_co_u32_e32 v32, vcc, 0x1000, v16
	v_lshl_add_u64 v[18:19], v[84:85], 2, s[12:13]
	s_nop 0
	v_addc_co_u32_e32 v33, vcc, 0, v17, vcc
	global_load_dwordx4 v[0:3], v[16:17], off
	global_load_dwordx4 v[4:7], v[16:17], off offset:2048
	global_load_dwordx4 v[8:11], v[18:19], off
	global_load_dwordx4 v[12:15], v[16:17], off offset:2064
	s_nop 0
	global_load_dwordx4 v[16:19], v[32:33], off
	global_load_dwordx4 v[20:23], v[32:33], off offset:16
	global_load_dwordx4 v[24:27], v[32:33], off offset:2048
	global_load_dwordx4 v[28:31], v[32:33], off offset:2064
	v_mov_b32_e32 v32, s8
	v_mov_b32_e32 v33, s9
	v_lshl_add_u64 v[32:33], v[80:81], 1, v[32:33]
	s_mov_b64 s[8:9], 0x5200000
	v_lshl_add_u64 v[80:81], v[32:33], 0, s[8:9]
	v_mbcnt_lo_u32_b32 v32, -1, 0
	v_mbcnt_hi_u32_b32 v32, -1, v32
	v_and_b32_e32 v33, 64, v32
	v_add_u32_e32 v33, 64, v33
	v_xor_b32_e32 v34, 1, v32
	v_cmp_lt_i32_e32 vcc, v34, v33
	s_add_u32 s24, s10, 0x804000
	s_addc_u32 s25, s11, 0
	v_cndmask_b32_e32 v34, v32, v34, vcc
	v_lshlrev_b32_e32 v82, 2, v34
	v_xor_b32_e32 v34, 2, v32
	v_cmp_lt_i32_e32 vcc, v34, v33
	s_lshl_b32 s26, s70, 5
	s_lshl_b32 s27, s70, 4
	v_cndmask_b32_e32 v34, v32, v34, vcc
	v_lshlrev_b32_e32 v83, 2, v34
	v_xor_b32_e32 v34, 4, v32
	v_cmp_lt_i32_e32 vcc, v34, v33
	s_mov_b32 s8, s72
	s_nop 0
	v_cndmask_b32_e32 v34, v32, v34, vcc
	v_lshlrev_b32_e32 v84, 2, v34
	v_xor_b32_e32 v34, 8, v32
	v_cmp_lt_i32_e32 vcc, v34, v33
	s_nop 1
	v_cndmask_b32_e32 v34, v32, v34, vcc
	v_lshlrev_b32_e32 v85, 2, v34
	v_xor_b32_e32 v34, 16, v32
	v_cmp_lt_i32_e32 vcc, v34, v33
	s_nop 1
	v_cndmask_b32_e32 v34, v32, v34, vcc
	v_lshlrev_b32_e32 v86, 2, v34
	v_xor_b32_e32 v34, 32, v32
	v_cmp_lt_i32_e32 vcc, v34, v33
	s_nop 1
	v_cndmask_b32_e32 v32, v32, v34, vcc
	v_lshlrev_b32_e32 v87, 2, v32
	s_branch .LBB0_352

; __device__ __forceinline__ float blo(unsigned w) { return __uint_as_float(w << 16); }
; __device__ __forceinline__ float bhi(unsigned w) { return __uint_as_float(w & 0xffff0000u); }
; __global__ void __launch_bounds__(NTHR, 2) mk_fwd(Args args) {
;     ...
;             for (int r = gw; r < nrows; r += 4 * NGW) {
;                 v4u w[4][4];
; #pragma unroll
;                 for (int q = 0; q < 4; ++q) { const int rq = (r + q * NGW < nrows) ? r + q * NGW : r; const bf16* wr_ = Wt + (size_t)rq * DMODEL + lane * 8;
; #pragma unroll
;                     for (int j = 0; j < 4; ++j) w[q][j] = *(const v4u*)(wr_ + j * 512); }
; #pragma unroll
;                 for (int q = 0; q < 4; ++q) { float acc = 0.f;
; #pragma unroll
;                     for (int j = 0; j < 4; ++j) { const v4u x = w[q][j];
;                         acc += blo(x.x) * shr[j * 8 + 0] + bhi(x.x) * shr[j * 8 + 1] + blo(x.y) * shr[j * 8 + 2] + bhi(x.y) * shr[j * 8 + 3] + blo(x.z) * shr[j * 8 + 4] + bhi(x.z) * shr[j * 8 + 5] + blo(x.w) * shr[j * 8 + 6] + bhi(x.w) * shr[j * 8 + 7]; }
;                     acc = wave_sum(acc); if (lane == 0 && r + q * NGW < nrows) bvo[r + q * NGW] = acc; } } }
.LBB0_352:
	s_ashr_i32 s9, s8, 31
	s_lshl_b64 s[10:11], s[8:9], 12
	s_waitcnt lgkmcnt(0)
	v_lshl_add_u64 v[32:33], v[80:81], 0, s[10:11]
	global_load_dwordx4 v[88:91], v[32:33], off
	global_load_dwordx4 v[92:95], v[32:33], off offset:1024
	global_load_dwordx4 v[96:99], v[32:33], off offset:2048
	global_load_dwordx4 v[100:103], v[32:33], off offset:3072
	s_add_i32 s18, s80, s8
	s_cmpk_gt_i32 s18, 0x2bff
	s_cselect_b64 s[20:21], -1, 0
	s_and_b64 s[10:11], s[20:21], exec
	s_cselect_b32 s10, s8, s18
	s_ashr_i32 s11, s10, 31
	s_add_i32 s14, s27, s8
	s_lshl_b64 s[10:11], s[10:11], 12
	s_cmpk_gt_i32 s14, 0x2bff
	s_cselect_b64 s[16:17], -1, 0
	v_lshl_add_u64 v[32:33], v[80:81], 0, s[10:11]
	s_and_b64 s[10:11], s[16:17], exec
	s_cselect_b32 s12, s8, s14
	s_ashr_i32 s13, s12, 31
	s_add_i32 s10, s3, s8
	s_lshl_b64 s[12:13], s[12:13], 12
	s_cmpk_gt_i32 s10, 0x2bff
	global_load_dwordx4 v[76:79], v[32:33], off
	global_load_dwordx4 v[72:75], v[32:33], off offset:1024
	global_load_dwordx4 v[68:71], v[32:33], off offset:2048
	global_load_dwordx4 v[64:67], v[32:33], off offset:3072
	v_lshl_add_u64 v[32:33], v[80:81], 0, s[12:13]
	s_cselect_b64 s[12:13], -1, 0
	s_and_b64 s[22:23], s[12:13], exec
	s_cselect_b32 s22, s8, s10
	s_ashr_i32 s23, s22, 31
	s_lshl_b64 s[22:23], s[22:23], 12
	v_lshl_add_u64 v[104:105], v[80:81], 0, s[22:23]
	global_load_dwordx4 v[60:63], v[32:33], off
	global_load_dwordx4 v[56:59], v[32:33], off offset:1024
	global_load_dwordx4 v[52:55], v[32:33], off offset:2048
	global_load_dwordx4 v[48:51], v[32:33], off offset:3072
	global_load_dwordx4 v[44:47], v[104:105], off
	global_load_dwordx4 v[40:43], v[104:105], off offset:1024
	global_load_dwordx4 v[36:39], v[104:105], off offset:2048
	s_nop 0
	global_load_dwordx4 v[32:35], v[104:105], off offset:3072
	s_waitcnt vmcnt(0) lgkmcnt(0)
	v_lshlrev_b32_e32 v104, 16, v88
	v_and_b32_e32 v88, 0xffff0000, v88
	v_mul_f32_e32 v88, v1, v88
	v_lshlrev_b32_e32 v105, 16, v89
	v_lshlrev_b32_e32 v108, 16, v92
	v_and_b32_e32 v92, 0xffff0000, v92
	v_fmac_f32_e32 v88, v0, v104
	v_and_b32_e32 v89, 0xffff0000, v89
	v_lshlrev_b32_e32 v112, 16, v96
	v_and_b32_e32 v96, 0xffff0000, v96
	v_mul_f32_e32 v92, v5, v92
	v_fmac_f32_e32 v88, v2, v105
	v_lshlrev_b32_e32 v106, 16, v90
	v_lshlrev_b32_e32 v109, 16, v93
	v_mul_f32_e32 v96, v17, v96
	v_fmac_f32_e32 v92, v4, v108
	v_fmac_f32_e32 v88, v3, v89
	v_and_b32_e32 v89, 0xffff0000, v100
	v_and_b32_e32 v90, 0xffff0000, v90
	v_and_b32_e32 v93, 0xffff0000, v93
	v_lshlrev_b32_e32 v113, 16, v97
	v_lshlrev_b32_e32 v116, 16, v100
	v_fmac_f32_e32 v96, v16, v112
	v_fmac_f32_e32 v92, v6, v109
	v_fmac_f32_e32 v88, v8, v106
	v_mul_f32_e32 v89, v25, v89
	v_lshlrev_b32_e32 v110, 16, v94
	v_and_b32_e32 v97, 0xffff0000, v97
	v_fmac_f32_e32 v96, v18, v113
	v_fmac_f32_e32 v92, v7, v93
	v_fmac_f32_e32 v88, v9, v90
	v_fmac_f32_e32 v89, v24, v116
	v_lshlrev_b32_e32 v90, 16, v101
	v_lshlrev_b32_e32 v107, 16, v91
	v_and_b32_e32 v94, 0xffff0000, v94
	v_lshlrev_b32_e32 v114, 16, v98
	v_fmac_f32_e32 v96, v19, v97
	v_fmac_f32_e32 v92, v12, v110
	v_fmac_f32_e32 v89, v26, v90
	v_and_b32_e32 v90, 0xffff0000, v101
	v_and_b32_e32 v91, 0xffff0000, v91
	v_lshlrev_b32_e32 v111, 16, v95
	v_and_b32_e32 v98, 0xffff0000, v98
	v_fmac_f32_e32 v96, v20, v114
	v_fmac_f32_e32 v92, v13, v94
	v_fmac_f32_e32 v88, v10, v107
	v_fmac_f32_e32 v89, v27, v90
	v_lshlrev_b32_e32 v90, 16, v102
	v_and_b32_e32 v95, 0xffff0000, v95
	v_lshlrev_b32_e32 v115, 16, v99
	v_fmac_f32_e32 v96, v21, v98
	v_fmac_f32_e32 v92, v14, v111
	v_fmac_f32_e32 v88, v11, v91
	v_fmac_f32_e32 v89, v28, v90
	v_and_b32_e32 v90, 0xffff0000, v102
	v_and_b32_e32 v99, 0xffff0000, v99
	v_fmac_f32_e32 v96, v22, v115
	v_fmac_f32_e32 v92, v15, v95
	v_add_f32_e32 v88, 0, v88
	v_fmac_f32_e32 v89, v29, v90
	v_lshlrev_b32_e32 v90, 16, v103
	v_fmac_f32_e32 v96, v23, v99
	v_add_f32_e32 v88, v88, v92
	v_fmac_f32_e32 v89, v30, v90
	v_and_b32_e32 v90, 0xffff0000, v103
	v_add_f32_e32 v88, v88, v96
	v_fmac_f32_e32 v89, v31, v90
	v_add_f32_e32 v88, v88, v89
	ds_bpermute_b32 v89, v82, v88
	s_waitcnt lgkmcnt(0)
	v_add_f32_e32 v88, v88, v89
	ds_bpermute_b32 v89, v83, v88
	s_waitcnt lgkmcnt(0)
	v_add_f32_e32 v88, v88, v89
	ds_bpermute_b32 v89, v84, v88
	s_waitcnt lgkmcnt(0)
	v_add_f32_e32 v88, v88, v89
	ds_bpermute_b32 v89, v85, v88
	s_waitcnt lgkmcnt(0)
	v_add_f32_e32 v88, v88, v89
	ds_bpermute_b32 v89, v86, v88
	s_waitcnt lgkmcnt(0)
	v_add_f32_e32 v88, v88, v89
	ds_bpermute_b32 v89, v87, v88
	s_and_saveexec_b64 s[22:23], s[4:5]
	s_cbranch_execz .LBB0_354
	s_lshl_b64 s[28:29], s[8:9], 2
	s_add_u32 s28, s24, s28
	s_addc_u32 s29, s25, s29
	s_waitcnt lgkmcnt(0)
	v_add_f32_e32 v90, v88, v89
	v_mov_b64_e32 v[88:89], s[28:29]
	global_store_dword v[88:89], v90, off
; __device__ __forceinline__ float blo(unsigned w) { return __uint_as_float(w << 16); }
; __device__ __forceinline__ float bhi(unsigned w) { return __uint_as_float(w & 0xffff0000u); }
; __global__ void __launch_bounds__(NTHR, 2) mk_fwd(Args args) {
;     ...
;                 for (int q = 0; q < 4; ++q) { float acc = 0.f;
; #pragma unroll
;                     for (int j = 0; j < 4; ++j) { const v4u x = w[q][j];
;                         acc += blo(x.x) * shr[j * 8 + 0] + bhi(x.x) * shr[j * 8 + 1] + blo(x.y) * shr[j * 8 + 2] + bhi(x.y) * shr[j * 8 + 3] + blo(x.z) * shr[j * 8 + 4] + bhi(x.z) * shr[j * 8 + 5] + blo(x.w) * shr[j * 8 + 6] + bhi(x.w) * shr[j * 8 + 7]; }
;                     acc = wave_sum(acc); if (lane == 0 && r + q * NGW < nrows) bvo[r + q * NGW] = acc; } } }
.LBB0_354:
	s_or_b64 exec, exec, s[22:23]
	v_lshlrev_b32_e32 v88, 16, v76
	v_and_b32_e32 v76, 0xffff0000, v76
	v_mul_f32_e32 v76, v1, v76
	v_fmac_f32_e32 v76, v0, v88
	v_lshlrev_b32_e32 v88, 16, v77
	v_fmac_f32_e32 v76, v2, v88
	v_and_b32_e32 v77, 0xffff0000, v77
	v_fmac_f32_e32 v76, v3, v77
	v_lshlrev_b32_e32 v77, 16, v78
	v_fmac_f32_e32 v76, v8, v77
	v_and_b32_e32 v77, 0xffff0000, v78
	v_fmac_f32_e32 v76, v9, v77
	v_lshlrev_b32_e32 v77, 16, v79
	v_fmac_f32_e32 v76, v10, v77
	v_and_b32_e32 v77, 0xffff0000, v79
	v_fmac_f32_e32 v76, v11, v77
	v_lshlrev_b32_e32 v77, 16, v72
	v_and_b32_e32 v72, 0xffff0000, v72
	v_mul_f32_e32 v72, v5, v72
	v_fmac_f32_e32 v72, v4, v77
	v_lshlrev_b32_e32 v77, 16, v73
	v_fmac_f32_e32 v72, v6, v77
	v_and_b32_e32 v73, 0xffff0000, v73
	v_fmac_f32_e32 v72, v7, v73
	v_lshlrev_b32_e32 v73, 16, v74
	v_fmac_f32_e32 v72, v12, v73
	v_and_b32_e32 v73, 0xffff0000, v74
	v_fmac_f32_e32 v72, v13, v73
	v_lshlrev_b32_e32 v73, 16, v75
	v_fmac_f32_e32 v72, v14, v73
	v_and_b32_e32 v73, 0xffff0000, v75
	v_fmac_f32_e32 v72, v15, v73
	v_lshlrev_b32_e32 v73, 16, v68
	v_and_b32_e32 v68, 0xffff0000, v68
	v_mul_f32_e32 v68, v17, v68
	v_fmac_f32_e32 v68, v16, v73
	v_lshlrev_b32_e32 v73, 16, v69
	v_fmac_f32_e32 v68, v18, v73
	v_and_b32_e32 v69, 0xffff0000, v69
	v_fmac_f32_e32 v68, v19, v69
	v_lshlrev_b32_e32 v69, 16, v70
	v_fmac_f32_e32 v68, v20, v69
	v_and_b32_e32 v69, 0xffff0000, v70
	v_fmac_f32_e32 v68, v21, v69
	v_lshlrev_b32_e32 v69, 16, v71
	v_fmac_f32_e32 v68, v22, v69
	v_and_b32_e32 v69, 0xffff0000, v71
	v_fmac_f32_e32 v68, v23, v69
	v_lshlrev_b32_e32 v69, 16, v64
	v_and_b32_e32 v64, 0xffff0000, v64
	v_mul_f32_e32 v64, v25, v64
	v_fmac_f32_e32 v64, v24, v69
	v_lshlrev_b32_e32 v69, 16, v65
	v_fmac_f32_e32 v64, v26, v69
	v_and_b32_e32 v65, 0xffff0000, v65
	v_fmac_f32_e32 v64, v27, v65
	v_lshlrev_b32_e32 v65, 16, v66
	v_fmac_f32_e32 v64, v28, v65
	v_and_b32_e32 v65, 0xffff0000, v66
	v_add_f32_e32 v76, 0, v76
	v_fmac_f32_e32 v64, v29, v65
	v_lshlrev_b32_e32 v65, 16, v67
	v_add_f32_e32 v72, v76, v72
	v_fmac_f32_e32 v64, v30, v65
	v_and_b32_e32 v65, 0xffff0000, v67
	v_add_f32_e32 v68, v72, v68
	v_fmac_f32_e32 v64, v31, v65
	v_add_f32_e32 v64, v68, v64
	ds_bpermute_b32 v65, v82, v64
	s_nor_b64 s[22:23], s[0:1], s[20:21]
	s_waitcnt lgkmcnt(0)
	v_add_f32_e32 v64, v64, v65
	ds_bpermute_b32 v65, v83, v64
	s_waitcnt lgkmcnt(0)
	v_add_f32_e32 v64, v64, v65
	ds_bpermute_b32 v65, v84, v64
	s_waitcnt lgkmcnt(0)
	v_add_f32_e32 v64, v64, v65
	ds_bpermute_b32 v65, v85, v64
	s_waitcnt lgkmcnt(0)
	v_add_f32_e32 v64, v64, v65
	ds_bpermute_b32 v65, v86, v64
	s_waitcnt lgkmcnt(0)
	v_add_f32_e32 v64, v64, v65
	ds_bpermute_b32 v65, v87, v64
	s_and_saveexec_b64 s[20:21], s[22:23]
	s_cbranch_execz .LBB0_356
	s_ashr_i32 s19, s18, 31
	s_lshl_b64 s[18:19], s[18:19], 2
	s_add_u32 s18, s24, s18
	s_addc_u32 s19, s25, s19
	s_waitcnt lgkmcnt(0)
	v_add_f32_e32 v66, v64, v65
	v_mov_b64_e32 v[64:65], s[18:19]
	global_store_dword v[64:65], v66, off
.LBB0_356:
	s_or_b64 exec, exec, s[20:21]
	v_lshlrev_b32_e32 v64, 16, v60
	v_and_b32_e32 v60, 0xffff0000, v60
	v_mul_f32_e32 v60, v1, v60
	v_fmac_f32_e32 v60, v0, v64
	v_lshlrev_b32_e32 v64, 16, v61
	v_fmac_f32_e32 v60, v2, v64
	v_and_b32_e32 v61, 0xffff0000, v61
	v_fmac_f32_e32 v60, v3, v61
	v_lshlrev_b32_e32 v61, 16, v62
	v_fmac_f32_e32 v60, v8, v61
	v_and_b32_e32 v61, 0xffff0000, v62
	v_fmac_f32_e32 v60, v9, v61
	v_lshlrev_b32_e32 v61, 16, v63
	v_fmac_f32_e32 v60, v10, v61
	v_and_b32_e32 v61, 0xffff0000, v63
	v_fmac_f32_e32 v60, v11, v61
	v_lshlrev_b32_e32 v61, 16, v56
	v_and_b32_e32 v56, 0xffff0000, v56
	v_mul_f32_e32 v56, v5, v56
	v_fmac_f32_e32 v56, v4, v61
	v_lshlrev_b32_e32 v61, 16, v57
	v_fmac_f32_e32 v56, v6, v61
	v_and_b32_e32 v57, 0xffff0000, v57
	v_fmac_f32_e32 v56, v7, v57
	v_lshlrev_b32_e32 v57, 16, v58
	v_fmac_f32_e32 v56, v12, v57
	v_and_b32_e32 v57, 0xffff0000, v58
	v_fmac_f32_e32 v56, v13, v57
	v_lshlrev_b32_e32 v57, 16, v59
	v_fmac_f32_e32 v56, v14, v57
	v_and_b32_e32 v57, 0xffff0000, v59
	v_fmac_f32_e32 v56, v15, v57
	v_lshlrev_b32_e32 v57, 16, v52
	v_and_b32_e32 v52, 0xffff0000, v52
	v_mul_f32_e32 v52, v17, v52
	v_fmac_f32_e32 v52, v16, v57
	v_lshlrev_b32_e32 v57, 16, v53
	v_fmac_f32_e32 v52, v18, v57
	v_and_b32_e32 v53, 0xffff0000, v53
	v_fmac_f32_e32 v52, v19, v53
	v_lshlrev_b32_e32 v53, 16, v54
	v_fmac_f32_e32 v52, v20, v53
	v_and_b32_e32 v53, 0xffff0000, v54
	v_fmac_f32_e32 v52, v21, v53
	v_lshlrev_b32_e32 v53, 16, v55
	v_fmac_f32_e32 v52, v22, v53
	v_and_b32_e32 v53, 0xffff0000, v55
	v_fmac_f32_e32 v52, v23, v53
	v_lshlrev_b32_e32 v53, 16, v48
	v_and_b32_e32 v48, 0xffff0000, v48
	v_mul_f32_e32 v48, v25, v48
	v_fmac_f32_e32 v48, v24, v53
	v_lshlrev_b32_e32 v53, 16, v49
	v_fmac_f32_e32 v48, v26, v53
	v_and_b32_e32 v49, 0xffff0000, v49
	v_fmac_f32_e32 v48, v27, v49
	v_lshlrev_b32_e32 v49, 16, v50
	v_fmac_f32_e32 v48, v28, v49
	v_and_b32_e32 v49, 0xffff0000, v50
	v_add_f32_e32 v60, 0, v60
	v_fmac_f32_e32 v48, v29, v49
	v_lshlrev_b32_e32 v49, 16, v51
	v_add_f32_e32 v56, v60, v56
	v_fmac_f32_e32 v48, v30, v49
	v_and_b32_e32 v49, 0xffff0000, v51
	v_add_f32_e32 v52, v56, v52
	v_fmac_f32_e32 v48, v31, v49
	v_add_f32_e32 v48, v52, v48
	ds_bpermute_b32 v49, v82, v48
	s_nor_b64 s[18:19], s[0:1], s[16:17]
	s_waitcnt lgkmcnt(0)
	v_add_f32_e32 v48, v48, v49
	ds_bpermute_b32 v49, v83, v48
	s_waitcnt lgkmcnt(0)
	v_add_f32_e32 v48, v48, v49
	ds_bpermute_b32 v49, v84, v48
	s_waitcnt lgkmcnt(0)
	v_add_f32_e32 v48, v48, v49
	ds_bpermute_b32 v49, v85, v48
	s_waitcnt lgkmcnt(0)
	v_add_f32_e32 v48, v48, v49
	ds_bpermute_b32 v49, v86, v48
	s_waitcnt lgkmcnt(0)
	v_add_f32_e32 v48, v48, v49
	ds_bpermute_b32 v49, v87, v48
	s_and_saveexec_b64 s[16:17], s[18:19]
	s_cbranch_execz .LBB0_358
	s_ashr_i32 s15, s14, 31
	s_lshl_b64 s[14:15], s[14:15], 2
	s_add_u32 s14, s24, s14
	s_addc_u32 s15, s25, s15
	s_waitcnt lgkmcnt(0)
	v_add_f32_e32 v50, v48, v49
	v_mov_b64_e32 v[48:49], s[14:15]
	global_store_dword v[48:49], v50, off
; __device__ __forceinline__ float blo(unsigned w) { return __uint_as_float(w << 16); }
; __device__ __forceinline__ float bhi(unsigned w) { return __uint_as_float(w & 0xffff0000u); }
; __global__ void __launch_bounds__(NTHR, 2) mk_fwd(Args args) {
;     ...
;                 for (int q = 0; q < 4; ++q) { float acc = 0.f;
; #pragma unroll
;                     for (int j = 0; j < 4; ++j) { const v4u x = w[q][j];
;                         acc += blo(x.x) * shr[j * 8 + 0] + bhi(x.x) * shr[j * 8 + 1] + blo(x.y) * shr[j * 8 + 2] + bhi(x.y) * shr[j * 8 + 3] + blo(x.z) * shr[j * 8 + 4] + bhi(x.z) * shr[j * 8 + 5] + blo(x.w) * shr[j * 8 + 6] + bhi(x.w) * shr[j * 8 + 7]; }
;                     acc = wave_sum(acc); if (lane == 0 && r + q * NGW < nrows) bvo[r + q * NGW] = acc; } } }
.LBB0_358:
	s_or_b64 exec, exec, s[16:17]
	v_lshlrev_b32_e32 v48, 16, v44
	v_and_b32_e32 v44, 0xffff0000, v44
	v_mul_f32_e32 v44, v1, v44
	v_fmac_f32_e32 v44, v0, v48
	v_lshlrev_b32_e32 v48, 16, v45
	v_fmac_f32_e32 v44, v2, v48
	v_and_b32_e32 v45, 0xffff0000, v45
	v_fmac_f32_e32 v44, v3, v45
	v_lshlrev_b32_e32 v45, 16, v46
	v_fmac_f32_e32 v44, v8, v45
	v_and_b32_e32 v45, 0xffff0000, v46
	v_fmac_f32_e32 v44, v9, v45
	v_lshlrev_b32_e32 v45, 16, v47
	v_fmac_f32_e32 v44, v10, v45
	v_and_b32_e32 v45, 0xffff0000, v47
	v_fmac_f32_e32 v44, v11, v45
	v_lshlrev_b32_e32 v45, 16, v40
	v_and_b32_e32 v40, 0xffff0000, v40
	v_mul_f32_e32 v40, v5, v40
	v_fmac_f32_e32 v40, v4, v45
	v_lshlrev_b32_e32 v45, 16, v41
	v_fmac_f32_e32 v40, v6, v45
	v_and_b32_e32 v41, 0xffff0000, v41
	v_fmac_f32_e32 v40, v7, v41
	v_lshlrev_b32_e32 v41, 16, v42
	v_fmac_f32_e32 v40, v12, v41
	v_and_b32_e32 v41, 0xffff0000, v42
	v_fmac_f32_e32 v40, v13, v41
	v_lshlrev_b32_e32 v41, 16, v43
	v_fmac_f32_e32 v40, v14, v41
	v_and_b32_e32 v41, 0xffff0000, v43
	v_fmac_f32_e32 v40, v15, v41
	v_lshlrev_b32_e32 v41, 16, v36
	v_and_b32_e32 v36, 0xffff0000, v36
	v_mul_f32_e32 v36, v17, v36
	v_fmac_f32_e32 v36, v16, v41
	v_lshlrev_b32_e32 v41, 16, v37
	v_fmac_f32_e32 v36, v18, v41
	v_and_b32_e32 v37, 0xffff0000, v37
	v_fmac_f32_e32 v36, v19, v37
	v_lshlrev_b32_e32 v37, 16, v38
	v_fmac_f32_e32 v36, v20, v37
	v_and_b32_e32 v37, 0xffff0000, v38
	v_fmac_f32_e32 v36, v21, v37
	v_lshlrev_b32_e32 v37, 16, v39
	v_fmac_f32_e32 v36, v22, v37
	v_and_b32_e32 v37, 0xffff0000, v39
	v_fmac_f32_e32 v36, v23, v37
	v_lshlrev_b32_e32 v37, 16, v32
	v_and_b32_e32 v32, 0xffff0000, v32
	v_mul_f32_e32 v32, v25, v32
	v_fmac_f32_e32 v32, v24, v37
	v_lshlrev_b32_e32 v37, 16, v33
	v_fmac_f32_e32 v32, v26, v37
	v_and_b32_e32 v33, 0xffff0000, v33
	v_fmac_f32_e32 v32, v27, v33
	v_lshlrev_b32_e32 v33, 16, v34
	v_fmac_f32_e32 v32, v28, v33
	v_and_b32_e32 v33, 0xffff0000, v34
	v_add_f32_e32 v44, 0, v44
	v_fmac_f32_e32 v32, v29, v33
	v_lshlrev_b32_e32 v33, 16, v35
	v_add_f32_e32 v40, v44, v40
	v_fmac_f32_e32 v32, v30, v33
	v_and_b32_e32 v33, 0xffff0000, v35
	v_add_f32_e32 v36, v40, v36
	v_fmac_f32_e32 v32, v31, v33
	v_add_f32_e32 v32, v36, v32
	ds_bpermute_b32 v33, v82, v32
	s_nor_b64 s[14:15], s[0:1], s[12:13]
	s_waitcnt lgkmcnt(0)
	v_add_f32_e32 v32, v32, v33
	ds_bpermute_b32 v33, v83, v32
	s_waitcnt lgkmcnt(0)
	v_add_f32_e32 v32, v32, v33
	ds_bpermute_b32 v33, v84, v32
	s_waitcnt lgkmcnt(0)
	v_add_f32_e32 v32, v32, v33
	ds_bpermute_b32 v33, v85, v32
	s_waitcnt lgkmcnt(0)
	v_add_f32_e32 v32, v32, v33
	ds_bpermute_b32 v33, v86, v32
	s_waitcnt lgkmcnt(0)
	v_add_f32_e32 v32, v32, v33
	ds_bpermute_b32 v33, v87, v32
	s_and_saveexec_b64 s[12:13], s[14:15]
	s_cbranch_execz .LBB0_351
	s_ashr_i32 s11, s10, 31
	s_lshl_b64 s[10:11], s[10:11], 2
	s_add_u32 s10, s24, s10
	s_addc_u32 s11, s25, s11
	s_waitcnt lgkmcnt(0)
	v_add_f32_e32 v34, v32, v33
	v_mov_b64_e32 v[32:33], s[10:11]
	global_store_dword v[32:33], v34, off
	s_branch .LBB0_351

; __device__ __forceinline__ u32x4 pack8(const f32x4& v0, const f32x4& v1) { u32x4 w; w.x = cvt_pk_bf16(v0[0], v0[1]); w.y = cvt_pk_bf16(v0[2], v0[3]); w.z = cvt_pk_bf16(v1[0], v1[1]); w.w = cvt_pk_bf16(v1[2], v1[3]); return w; }
; __device__ __forceinline__ f32x4 swiglu4(const f32x4 a, const f32x4 b) {
;     const f32x4 t = a * (-1.4426950408889634f); f32x4 e;
; #pragma unroll
;     for (int k = 0; k < 4; ++k) e[k] = __builtin_amdgcn_exp2f(t[k]);
;     e = e + 1.0f;
; #pragma unroll
;     for (int k = 0; k < 4; ++k) e[k] = __builtin_amdgcn_rcpf(e[k]);
;     return (a * e) * b;
; }
;     __device__ __forceinline__ void operator()(const f32x4 (&acc)[2][2][4][2], const Unit& u, int wr, int wc, int fr_, int fq_) const {
;     ...
;             for (int m = 0; m < 4; ++m) { const int row = row0 + ai * HALF + m * 16; bf16_t* rowp = O + (size_t)row * ldc + col0;
;                 f32x4 v0, v1;
;                 if constexpr (DEFER) { const float rs = rsv[ai * 4 + m];
;                     v0 = swiglu4(acc[ai][0][m][0] * rs + ba0, acc[ai][1][m][0] * rs + bb0); v1 = swiglu4(acc[ai][0][m][1] * rs + ba1, acc[ai][1][m][1] * rs + bb1); }
;                 else { v0 = swiglu4(acc[ai][0][m][0], acc[ai][1][m][0]); v1 = swiglu4(acc[ai][0][m][1], acc[ai][1][m][1]); }
;                 *(u32x4*)rowp = pack8(v0, v1); }
.LBB0_421:
	v_mul_f32_e32 v153, 0xbfb8aa3b, v124
	v_mul_f32_e32 v157, 0xbfb8aa3b, v126
	v_exp_f32_e32 v156, v153
	v_mul_f32_e32 v153, 0xbfb8aa3b, v125
	v_exp_f32_e32 v158, v157
	v_mul_f32_e32 v157, 0xbfb8aa3b, v127
	v_exp_f32_e32 v159, v157
	v_exp_f32_e32 v157, v153
	v_mul_f32_e32 v153, 0xbfb8aa3b, v120
	v_mul_f32_e32 v161, 0xbfb8aa3b, v122
	v_pk_add_f32 v[158:159], v[158:159], 1.0 op_sel_hi:[1,0]
	v_pk_add_f32 v[156:157], v[156:157], 1.0 op_sel_hi:[1,0]
	v_exp_f32_e32 v160, v153
	v_mul_f32_e32 v153, 0xbfb8aa3b, v121
	v_exp_f32_e32 v162, v161
	v_mul_f32_e32 v161, 0xbfb8aa3b, v123
	v_rcp_f32_e32 v156, v156
	v_rcp_f32_e32 v157, v157
	v_rcp_f32_e32 v158, v158
	v_rcp_f32_e32 v159, v159
	v_exp_f32_e32 v163, v161
	v_exp_f32_e32 v161, v153
	s_lshl_b32 s15, s22, 8
	v_pk_mul_f32 v[124:125], v[124:125], v[156:157]
	v_pk_mul_f32 v[126:127], v[126:127], v[158:159]
	v_pk_add_f32 v[156:157], v[162:163], 1.0 op_sel_hi:[1,0]
	v_pk_add_f32 v[158:159], v[160:161], 1.0 op_sel_hi:[1,0]
	v_mbcnt_lo_u32_b32 v144, -1, 0
	v_mbcnt_hi_u32_b32 v144, -1, v144
	s_add_i32 s15, s15, s40
	v_rcp_f32_e32 v158, v158
	v_rcp_f32_e32 v159, v159
	v_rcp_f32_e32 v156, v156
	v_rcp_f32_e32 v157, v157
	v_and_or_b32 v152, v144, 15, s15
	s_lshl_b32 s15, s50, 7
	v_ashrrev_i32_e32 v144, 1, v144
	s_or_b32 s15, s15, s41
	v_and_b32_e32 v144, -8, v144
	v_add_u32_e32 v146, s15, v144
	v_ashrrev_i32_e32 v147, 31, v146
	v_mov_b64_e32 v[144:145], s[8:9]
	v_pk_mul_f32 v[120:121], v[120:121], v[158:159]
	v_pk_mul_f32 v[122:123], v[122:123], v[156:157]
	v_mad_i64_i32 v[154:155], s[24:25], v152, s49, v[144:145]
	v_lshlrev_b64 v[146:147], 1, v[146:147]
	v_pk_mul_f32 v[122:123], v[122:123], v[114:115]
	v_pk_mul_f32 v[114:115], v[120:121], v[112:113]
	v_lshl_add_u64 v[154:155], v[154:155], 0, v[146:147]
	v_pk_mul_f32 v[118:119], v[126:127], v[118:119]
	v_pk_mul_f32 v[116:117], v[124:125], v[116:117]
	v_mul_f32_e32 v120, 0xbfb8aa3b, v106
	v_cvt_pk_bf16_f32 v112, v116, v117
	v_cvt_pk_bf16_f32 v113, v118, v119
	v_cvt_pk_bf16_f32 v114, v114, v115
	v_cvt_pk_bf16_f32 v115, v122, v123
	global_store_dwordx4 v[154:155], v[112:115], off
	v_mul_f32_e32 v118, 0xbfb8aa3b, v104
	v_mul_f32_e32 v119, 0xbfb8aa3b, v105
	v_mul_f32_e32 v112, 0xbfb8aa3b, v108
	v_mul_f32_e32 v113, 0xbfb8aa3b, v109
	v_mul_f32_e32 v114, 0xbfb8aa3b, v110
	v_mul_f32_e32 v115, 0xbfb8aa3b, v111
	v_exp_f32_e32 v112, v112
	v_exp_f32_e32 v113, v113
	v_exp_f32_e32 v114, v114
	v_exp_f32_e32 v115, v115
	v_mul_f32_e32 v121, 0xbfb8aa3b, v107
	v_pk_add_f32 v[112:113], v[112:113], 1.0 op_sel_hi:[1,0]
	v_exp_f32_e32 v118, v118
	v_pk_add_f32 v[114:115], v[114:115], 1.0 op_sel_hi:[1,0]
	v_rcp_f32_e32 v112, v112
	v_rcp_f32_e32 v113, v113
	v_rcp_f32_e32 v114, v114
	v_rcp_f32_e32 v115, v115
	v_exp_f32_e32 v120, v120
	v_exp_f32_e32 v121, v121
	v_exp_f32_e32 v119, v119
	v_pk_mul_f32 v[108:109], v[108:109], v[112:113]
	v_pk_mul_f32 v[110:111], v[110:111], v[114:115]
	v_pk_add_f32 v[112:113], v[120:121], 1.0 op_sel_hi:[1,0]
	v_pk_add_f32 v[114:115], v[118:119], 1.0 op_sel_hi:[1,0]
	v_rcp_f32_e32 v112, v112
	v_rcp_f32_e32 v114, v114
	v_rcp_f32_e32 v115, v115
	v_rcp_f32_e32 v113, v113
	v_or_b32_e32 v116, 16, v152
	v_mad_i64_i32 v[116:117], s[24:25], v116, s49, v[144:145]
	v_pk_mul_f32 v[104:105], v[104:105], v[114:115]
	v_pk_mul_f32 v[106:107], v[106:107], v[112:113]
	v_lshl_add_u64 v[116:117], v[116:117], 0, v[146:147]
	v_pk_mul_f32 v[106:107], v[106:107], v[98:99]
	v_pk_mul_f32 v[98:99], v[104:105], v[96:97]
	v_pk_mul_f32 v[102:103], v[110:111], v[102:103]
	v_pk_mul_f32 v[100:101], v[108:109], v[100:101]
	v_mul_f32_e32 v104, 0xbfb8aa3b, v90
	v_cvt_pk_bf16_f32 v96, v100, v101
	v_cvt_pk_bf16_f32 v97, v102, v103
	v_cvt_pk_bf16_f32 v98, v98, v99
	v_cvt_pk_bf16_f32 v99, v106, v107
	global_store_dwordx4 v[116:117], v[96:99], off
	v_mul_f32_e32 v102, 0xbfb8aa3b, v88
	v_mul_f32_e32 v103, 0xbfb8aa3b, v89
	v_mul_f32_e32 v96, 0xbfb8aa3b, v92
	v_mul_f32_e32 v97, 0xbfb8aa3b, v93
	v_mul_f32_e32 v98, 0xbfb8aa3b, v94
	v_mul_f32_e32 v99, 0xbfb8aa3b, v95
	v_exp_f32_e32 v96, v96
	v_exp_f32_e32 v97, v97
	v_exp_f32_e32 v98, v98
	v_exp_f32_e32 v99, v99
	v_mul_f32_e32 v105, 0xbfb8aa3b, v91
	v_pk_add_f32 v[96:97], v[96:97], 1.0 op_sel_hi:[1,0]
	v_exp_f32_e32 v102, v102
	v_pk_add_f32 v[98:99], v[98:99], 1.0 op_sel_hi:[1,0]
	v_rcp_f32_e32 v96, v96
	v_rcp_f32_e32 v97, v97
	v_rcp_f32_e32 v98, v98
	v_rcp_f32_e32 v99, v99
	v_exp_f32_e32 v104, v104
	v_exp_f32_e32 v105, v105
	v_exp_f32_e32 v103, v103
	v_pk_mul_f32 v[92:93], v[92:93], v[96:97]
	v_pk_mul_f32 v[94:95], v[94:95], v[98:99]
	v_pk_add_f32 v[96:97], v[104:105], 1.0 op_sel_hi:[1,0]
	v_pk_add_f32 v[98:99], v[102:103], 1.0 op_sel_hi:[1,0]
	v_rcp_f32_e32 v96, v96
	v_rcp_f32_e32 v98, v98
	v_rcp_f32_e32 v99, v99
	v_rcp_f32_e32 v97, v97
	v_or_b32_e32 v100, 32, v152
	v_mad_i64_i32 v[100:101], s[24:25], v100, s49, v[144:145]
	v_pk_mul_f32 v[88:89], v[88:89], v[98:99]
	v_pk_mul_f32 v[90:91], v[90:91], v[96:97]
	v_lshl_add_u64 v[100:101], v[100:101], 0, v[146:147]
	v_pk_mul_f32 v[90:91], v[90:91], v[82:83]
	v_pk_mul_f32 v[82:83], v[88:89], v[80:81]
	v_pk_mul_f32 v[86:87], v[94:95], v[86:87]
	v_pk_mul_f32 v[84:85], v[92:93], v[84:85]
	v_mul_f32_e32 v88, 0xbfb8aa3b, v74
	v_cvt_pk_bf16_f32 v80, v84, v85
	v_cvt_pk_bf16_f32 v81, v86, v87
	v_cvt_pk_bf16_f32 v82, v82, v83
	v_cvt_pk_bf16_f32 v83, v90, v91
	global_store_dwordx4 v[100:101], v[80:83], off
	v_mul_f32_e32 v86, 0xbfb8aa3b, v72
	v_mul_f32_e32 v87, 0xbfb8aa3b, v73
	v_mul_f32_e32 v80, 0xbfb8aa3b, v76
	v_mul_f32_e32 v81, 0xbfb8aa3b, v77
	v_mul_f32_e32 v82, 0xbfb8aa3b, v78
	v_mul_f32_e32 v83, 0xbfb8aa3b, v79
	v_exp_f32_e32 v80, v80
	v_exp_f32_e32 v81, v81
	v_exp_f32_e32 v82, v82
	v_exp_f32_e32 v83, v83
; __device__ __forceinline__ u32x4 pack8(const f32x4& v0, const f32x4& v1) { u32x4 w; w.x = cvt_pk_bf16(v0[0], v0[1]); w.y = cvt_pk_bf16(v0[2], v0[3]); w.z = cvt_pk_bf16(v1[0], v1[1]); w.w = cvt_pk_bf16(v1[2], v1[3]); return w; }
; __device__ __forceinline__ f32x4 swiglu4(const f32x4 a, const f32x4 b) {
;     const f32x4 t = a * (-1.4426950408889634f); f32x4 e;
; #pragma unroll
;     for (int k = 0; k < 4; ++k) e[k] = __builtin_amdgcn_exp2f(t[k]);
;     e = e + 1.0f;
; #pragma unroll
;     for (int k = 0; k < 4; ++k) e[k] = __builtin_amdgcn_rcpf(e[k]);
;     return (a * e) * b;
; }
;     __device__ __forceinline__ void operator()(const f32x4 (&acc)[2][2][4][2], const Unit& u, int wr, int wc, int fr_, int fq_) const {
;     ...
;             for (int m = 0; m < 4; ++m) { const int row = row0 + ai * HALF + m * 16; bf16_t* rowp = O + (size_t)row * ldc + col0;
;                 f32x4 v0, v1;
;                 if constexpr (DEFER) { const float rs = rsv[ai * 4 + m];
;                     v0 = swiglu4(acc[ai][0][m][0] * rs + ba0, acc[ai][1][m][0] * rs + bb0); v1 = swiglu4(acc[ai][0][m][1] * rs + ba1, acc[ai][1][m][1] * rs + bb1); }
;                 else { v0 = swiglu4(acc[ai][0][m][0], acc[ai][1][m][0]); v1 = swiglu4(acc[ai][0][m][1], acc[ai][1][m][1]); }
;                 *(u32x4*)rowp = pack8(v0, v1); }
	v_mul_f32_e32 v89, 0xbfb8aa3b, v75
	v_pk_add_f32 v[80:81], v[80:81], 1.0 op_sel_hi:[1,0]
	v_exp_f32_e32 v86, v86
	v_pk_add_f32 v[82:83], v[82:83], 1.0 op_sel_hi:[1,0]
	v_rcp_f32_e32 v80, v80
	v_rcp_f32_e32 v81, v81
	v_rcp_f32_e32 v82, v82
	v_rcp_f32_e32 v83, v83
	v_exp_f32_e32 v88, v88
	v_exp_f32_e32 v89, v89
	v_exp_f32_e32 v87, v87
	v_pk_mul_f32 v[76:77], v[76:77], v[80:81]
	v_pk_mul_f32 v[78:79], v[78:79], v[82:83]
	v_pk_add_f32 v[80:81], v[88:89], 1.0 op_sel_hi:[1,0]
	v_pk_add_f32 v[82:83], v[86:87], 1.0 op_sel_hi:[1,0]
	v_rcp_f32_e32 v80, v80
	v_rcp_f32_e32 v82, v82
	v_rcp_f32_e32 v83, v83
	v_rcp_f32_e32 v81, v81
	v_or_b32_e32 v84, 48, v152
	v_mad_i64_i32 v[84:85], s[24:25], v84, s49, v[144:145]
	v_pk_mul_f32 v[72:73], v[72:73], v[82:83]
	v_pk_mul_f32 v[74:75], v[74:75], v[80:81]
	v_lshl_add_u64 v[84:85], v[84:85], 0, v[146:147]
	v_pk_mul_f32 v[74:75], v[74:75], v[66:67]
	v_pk_mul_f32 v[66:67], v[72:73], v[64:65]
	v_pk_mul_f32 v[70:71], v[78:79], v[70:71]
	v_pk_mul_f32 v[68:69], v[76:77], v[68:69]
	v_mul_f32_e32 v72, 0xbfb8aa3b, v58
	v_cvt_pk_bf16_f32 v64, v68, v69
	v_cvt_pk_bf16_f32 v65, v70, v71
	v_cvt_pk_bf16_f32 v66, v66, v67
	v_cvt_pk_bf16_f32 v67, v74, v75
	global_store_dwordx4 v[84:85], v[64:67], off
	v_mul_f32_e32 v70, 0xbfb8aa3b, v56
	v_mul_f32_e32 v71, 0xbfb8aa3b, v57
	v_mul_f32_e32 v64, 0xbfb8aa3b, v60
	v_mul_f32_e32 v65, 0xbfb8aa3b, v61
	v_mul_f32_e32 v66, 0xbfb8aa3b, v62
	v_mul_f32_e32 v67, 0xbfb8aa3b, v63
	v_exp_f32_e32 v64, v64
	v_exp_f32_e32 v65, v65
	v_exp_f32_e32 v66, v66
	v_exp_f32_e32 v67, v67
	v_mul_f32_e32 v73, 0xbfb8aa3b, v59
	v_pk_add_f32 v[64:65], v[64:65], 1.0 op_sel_hi:[1,0]
	v_exp_f32_e32 v70, v70
	v_pk_add_f32 v[66:67], v[66:67], 1.0 op_sel_hi:[1,0]
	v_rcp_f32_e32 v64, v64
	v_rcp_f32_e32 v65, v65
	v_rcp_f32_e32 v66, v66
	v_rcp_f32_e32 v67, v67
	v_exp_f32_e32 v72, v72
	v_exp_f32_e32 v73, v73
	v_exp_f32_e32 v71, v71
	v_pk_mul_f32 v[60:61], v[60:61], v[64:65]
	v_pk_mul_f32 v[62:63], v[62:63], v[66:67]
	v_pk_add_f32 v[64:65], v[72:73], 1.0 op_sel_hi:[1,0]
	v_pk_add_f32 v[66:67], v[70:71], 1.0 op_sel_hi:[1,0]
	v_rcp_f32_e32 v64, v64
	v_rcp_f32_e32 v66, v66
	v_rcp_f32_e32 v67, v67
	v_rcp_f32_e32 v65, v65
	v_add_u32_e32 v68, 0x80, v152
	v_mad_i64_i32 v[68:69], s[24:25], v68, s49, v[144:145]
	v_pk_mul_f32 v[56:57], v[56:57], v[66:67]
	v_pk_mul_f32 v[58:59], v[58:59], v[64:65]
	v_lshl_add_u64 v[68:69], v[68:69], 0, v[146:147]
	v_pk_mul_f32 v[58:59], v[58:59], v[50:51]
	v_pk_mul_f32 v[50:51], v[56:57], v[48:49]
	v_pk_mul_f32 v[54:55], v[62:63], v[54:55]
	v_pk_mul_f32 v[52:53], v[60:61], v[52:53]
	v_mul_f32_e32 v56, 0xbfb8aa3b, v42
	v_cvt_pk_bf16_f32 v48, v52, v53
	v_cvt_pk_bf16_f32 v49, v54, v55
	v_cvt_pk_bf16_f32 v50, v50, v51
	v_cvt_pk_bf16_f32 v51, v58, v59
	global_store_dwordx4 v[68:69], v[48:51], off
	v_mul_f32_e32 v54, 0xbfb8aa3b, v40
	v_mul_f32_e32 v55, 0xbfb8aa3b, v41
	v_mul_f32_e32 v48, 0xbfb8aa3b, v44
	v_mul_f32_e32 v49, 0xbfb8aa3b, v45
	v_mul_f32_e32 v50, 0xbfb8aa3b, v46
	v_mul_f32_e32 v51, 0xbfb8aa3b, v47
	v_exp_f32_e32 v48, v48
	v_exp_f32_e32 v49, v49
	v_exp_f32_e32 v50, v50
	v_exp_f32_e32 v51, v51
	v_mul_f32_e32 v57, 0xbfb8aa3b, v43
	v_pk_add_f32 v[48:49], v[48:49], 1.0 op_sel_hi:[1,0]
	v_exp_f32_e32 v54, v54
	v_pk_add_f32 v[50:51], v[50:51], 1.0 op_sel_hi:[1,0]
	v_rcp_f32_e32 v48, v48
	v_rcp_f32_e32 v49, v49
	v_rcp_f32_e32 v50, v50
	v_rcp_f32_e32 v51, v51
	v_exp_f32_e32 v56, v56
	v_exp_f32_e32 v57, v57
	v_exp_f32_e32 v55, v55
	v_pk_mul_f32 v[44:45], v[44:45], v[48:49]
	v_pk_mul_f32 v[46:47], v[46:47], v[50:51]
	v_pk_add_f32 v[48:49], v[56:57], 1.0 op_sel_hi:[1,0]
	v_pk_add_f32 v[50:51], v[54:55], 1.0 op_sel_hi:[1,0]
	v_rcp_f32_e32 v48, v48
	v_rcp_f32_e32 v50, v50
	v_rcp_f32_e32 v51, v51
	v_rcp_f32_e32 v49, v49
	v_add_u32_e32 v52, 0x90, v152
; __device__ __forceinline__ u32x4 pack8(const f32x4& v0, const f32x4& v1) { u32x4 w; w.x = cvt_pk_bf16(v0[0], v0[1]); w.y = cvt_pk_bf16(v0[2], v0[3]); w.z = cvt_pk_bf16(v1[0], v1[1]); w.w = cvt_pk_bf16(v1[2], v1[3]); return w; }
; __device__ __forceinline__ f32x4 swiglu4(const f32x4 a, const f32x4 b) {
;     const f32x4 t = a * (-1.4426950408889634f); f32x4 e;
; #pragma unroll
;     for (int k = 0; k < 4; ++k) e[k] = __builtin_amdgcn_exp2f(t[k]);
;     e = e + 1.0f;
; #pragma unroll
;     for (int k = 0; k < 4; ++k) e[k] = __builtin_amdgcn_rcpf(e[k]);
;     return (a * e) * b;
; }
;     __device__ __forceinline__ void operator()(const f32x4 (&acc)[2][2][4][2], const Unit& u, int wr, int wc, int fr_, int fq_) const {
;     ...
;             for (int m = 0; m < 4; ++m) { const int row = row0 + ai * HALF + m * 16; bf16_t* rowp = O + (size_t)row * ldc + col0;
;                 f32x4 v0, v1;
;                 if constexpr (DEFER) { const float rs = rsv[ai * 4 + m];
;                     v0 = swiglu4(acc[ai][0][m][0] * rs + ba0, acc[ai][1][m][0] * rs + bb0); v1 = swiglu4(acc[ai][0][m][1] * rs + ba1, acc[ai][1][m][1] * rs + bb1); }
;                 else { v0 = swiglu4(acc[ai][0][m][0], acc[ai][1][m][0]); v1 = swiglu4(acc[ai][0][m][1], acc[ai][1][m][1]); }
;                 *(u32x4*)rowp = pack8(v0, v1); }
	v_mad_i64_i32 v[52:53], s[24:25], v52, s49, v[144:145]
	v_pk_mul_f32 v[40:41], v[40:41], v[50:51]
	v_pk_mul_f32 v[42:43], v[42:43], v[48:49]
	v_lshl_add_u64 v[52:53], v[52:53], 0, v[146:147]
	v_pk_mul_f32 v[42:43], v[42:43], v[34:35]
	v_pk_mul_f32 v[34:35], v[40:41], v[32:33]
	v_pk_mul_f32 v[38:39], v[46:47], v[38:39]
	v_pk_mul_f32 v[36:37], v[44:45], v[36:37]
	v_mul_f32_e32 v40, 0xbfb8aa3b, v26
	v_cvt_pk_bf16_f32 v32, v36, v37
	v_cvt_pk_bf16_f32 v33, v38, v39
	v_cvt_pk_bf16_f32 v34, v34, v35
	v_cvt_pk_bf16_f32 v35, v42, v43
	global_store_dwordx4 v[52:53], v[32:35], off
	v_mul_f32_e32 v38, 0xbfb8aa3b, v24
	v_mul_f32_e32 v39, 0xbfb8aa3b, v25
	v_mul_f32_e32 v32, 0xbfb8aa3b, v28
	v_mul_f32_e32 v33, 0xbfb8aa3b, v29
	v_mul_f32_e32 v34, 0xbfb8aa3b, v30
	v_mul_f32_e32 v35, 0xbfb8aa3b, v31
	v_exp_f32_e32 v32, v32
	v_exp_f32_e32 v33, v33
	v_exp_f32_e32 v34, v34
	v_exp_f32_e32 v35, v35
	v_mul_f32_e32 v41, 0xbfb8aa3b, v27
	v_pk_add_f32 v[32:33], v[32:33], 1.0 op_sel_hi:[1,0]
	v_exp_f32_e32 v38, v38
	v_pk_add_f32 v[34:35], v[34:35], 1.0 op_sel_hi:[1,0]
	v_rcp_f32_e32 v32, v32
	v_rcp_f32_e32 v33, v33
	v_rcp_f32_e32 v34, v34
	v_rcp_f32_e32 v35, v35
	v_exp_f32_e32 v40, v40
	v_exp_f32_e32 v41, v41
	v_exp_f32_e32 v39, v39
	v_pk_mul_f32 v[28:29], v[28:29], v[32:33]
	v_pk_mul_f32 v[30:31], v[30:31], v[34:35]
	v_pk_add_f32 v[32:33], v[40:41], 1.0 op_sel_hi:[1,0]
	v_pk_add_f32 v[34:35], v[38:39], 1.0 op_sel_hi:[1,0]
	v_rcp_f32_e32 v32, v32
	v_rcp_f32_e32 v34, v34
	v_rcp_f32_e32 v35, v35
	v_rcp_f32_e32 v33, v33
	v_add_u32_e32 v36, 0xa0, v152
	v_mad_i64_i32 v[36:37], s[24:25], v36, s49, v[144:145]
	v_pk_mul_f32 v[24:25], v[24:25], v[34:35]
	v_pk_mul_f32 v[26:27], v[26:27], v[32:33]
	v_lshl_add_u64 v[36:37], v[36:37], 0, v[146:147]
	v_pk_mul_f32 v[26:27], v[26:27], v[18:19]
	v_pk_mul_f32 v[18:19], v[24:25], v[16:17]
	v_pk_mul_f32 v[22:23], v[30:31], v[22:23]
	v_pk_mul_f32 v[20:21], v[28:29], v[20:21]
	v_mul_f32_e32 v24, 0xbfb8aa3b, v10
	v_cvt_pk_bf16_f32 v16, v20, v21
	v_cvt_pk_bf16_f32 v17, v22, v23
	v_cvt_pk_bf16_f32 v18, v18, v19
	v_cvt_pk_bf16_f32 v19, v26, v27
	global_store_dwordx4 v[36:37], v[16:19], off
	v_mul_f32_e32 v22, 0xbfb8aa3b, v8
	v_mul_f32_e32 v23, 0xbfb8aa3b, v9
	v_mul_f32_e32 v16, 0xbfb8aa3b, v12
	v_mul_f32_e32 v17, 0xbfb8aa3b, v13
	v_mul_f32_e32 v18, 0xbfb8aa3b, v14
	v_mul_f32_e32 v19, 0xbfb8aa3b, v15
	v_exp_f32_e32 v16, v16
	v_exp_f32_e32 v17, v17
	v_exp_f32_e32 v18, v18
	v_exp_f32_e32 v19, v19
	v_mul_f32_e32 v25, 0xbfb8aa3b, v11
	v_pk_add_f32 v[16:17], v[16:17], 1.0 op_sel_hi:[1,0]
	v_exp_f32_e32 v22, v22
	v_pk_add_f32 v[18:19], v[18:19], 1.0 op_sel_hi:[1,0]
	v_rcp_f32_e32 v16, v16
	v_rcp_f32_e32 v17, v17
	v_rcp_f32_e32 v18, v18
	v_rcp_f32_e32 v19, v19
	v_exp_f32_e32 v24, v24
	v_exp_f32_e32 v25, v25
	v_exp_f32_e32 v23, v23
	v_pk_mul_f32 v[12:13], v[12:13], v[16:17]
	v_pk_mul_f32 v[14:15], v[14:15], v[18:19]
	v_pk_add_f32 v[16:17], v[24:25], 1.0 op_sel_hi:[1,0]
	v_pk_add_f32 v[18:19], v[22:23], 1.0 op_sel_hi:[1,0]
	v_rcp_f32_e32 v16, v16
	v_rcp_f32_e32 v18, v18
	v_rcp_f32_e32 v19, v19
	v_rcp_f32_e32 v17, v17
	v_add_u32_e32 v20, 0xb0, v152
	v_mad_i64_i32 v[20:21], s[24:25], v20, s49, v[144:145]
	v_pk_mul_f32 v[8:9], v[8:9], v[18:19]
	v_pk_mul_f32 v[10:11], v[10:11], v[16:17]
	v_lshl_add_u64 v[20:21], v[20:21], 0, v[146:147]
	v_pk_mul_f32 v[10:11], v[10:11], v[2:3]
	v_pk_mul_f32 v[2:3], v[8:9], v[0:1]
	s_andn2_b64 vcc, exec, s[0:1]
	s_mov_b64 s[0:1], -1
	v_pk_mul_f32 v[6:7], v[14:15], v[6:7]
	v_pk_mul_f32 v[4:5], v[12:13], v[4:5]
	s_nop 0
	v_cvt_pk_bf16_f32 v0, v4, v5
	v_cvt_pk_bf16_f32 v1, v6, v7
	v_cvt_pk_bf16_f32 v2, v2, v3
	v_cvt_pk_bf16_f32 v3, v10, v11
	global_store_dwordx4 v[20:21], v[0:3], off
	s_cbranch_vccnz .LBB0_414
	s_andn2_b64 vcc, exec, s[6:7]
	s_cbranch_vccnz .LBB0_413
	s_barrier
	s_branch .LBB0_413

; __device__ __forceinline__ unsigned cvt_pk_bf16(float lo, float hi) { unsigned r; asm volatile("v_cvt_pk_bf16_f32 %0, %1, %2" : "=v"(r) : "v"(lo), "v"(hi)); return r; }
;     __device__ __forceinline__ void operator()(const f32x4 (&acc)[2][2][4][2], const Unit& u, int wr, int wc, int fr_, int fq_) const {
;     ...
;         f32x4 gv[2][2], gm[2][2];
; #pragma unroll
;         for (int bj = 0; bj < 2; ++bj)
; #pragma unroll
;             for (int n = 0; n < 2; ++n) { gv[bj][n] = *(const f32x4*)(gate + col0 + bj * HALF + n * 16);
;                 if constexpr (EMIT) gm[bj][n] = *(const f32x4*)(gmv + col0 + bj * HALF + n * 16); else gm[bj][n] = gv[bj][n]; }
; #pragma unroll
;         for (int ai = 0; ai < 2; ++ai)
; #pragma unroll
;         for (int mh = 0; mh < 2; ++mh) {
;             f32x4 bs[2][2][2];
; #pragma unroll
;             for (int m = 0; m < 2; ++m) { const size_t off = (size_t)(row0 + ai * HALF + (2 * mh + m) * 16) * ldc + col0;
; #pragma unroll
;                 for (int bj = 0; bj < 2; ++bj)
; #pragma unroll
;                     for (int n = 0; n < 2; ++n) bs[m][bj][n] = *(const f32x4*)(base + off + bj * HALF + n * 16); }
;             asm volatile("" ::: "memory");
; #pragma unroll
;             for (int m = 0; m < 2; ++m) { const int row = row0 + ai * HALF + (2 * mh + m) * 16; const size_t off = (size_t)row * ldc + col0; float ss = 0.f;
; #pragma unroll
;                 for (int bj = 0; bj < 2; ++bj)
; #pragma unroll
;                     for (int n = 0; n < 2; ++n) { const f32x4 o = bs[m][bj][n] + gv[bj][n] * acc[ai][bj][2 * mh + m][n]; *(f32x4*)(out + off + bj * HALF + n * 16) = o;
;                         if constexpr (EMIT) { ss += (o[0] * o[0] + o[1] * o[1]) + (o[2] * o[2] + o[3] * o[3]); const f32x4 y = o * gm[bj][n];
;                             typedef unsigned u32x2_t __attribute__((ext_vector_type(2))); u32x2_t w; w.x = cvt_pk_bf16(y[0], y[1]); w.y = cvt_pk_bf16(y[2], y[3]); *(u32x2_t*)(A2 + off + bj * HALF + n * 16) = w; } }
;                 if constexpr (EMIT) { ss += __shfl_xor(ss, 16); ss += __shfl_xor(ss, 32); if (fq == 0) atomicAdd(ssq + row, (unsigned long long)(ss * 16777216.0f)); } }
.LBB0_500:
	v_mbcnt_lo_u32_b32 v201, -1, 0
	v_mbcnt_hi_u32_b32 v201, -1, v201
	s_lshl_b32 s5, s57, 8
	v_ashrrev_i32_e32 v64, 2, v201
	s_lshl_b32 s4, s58, 8
	s_or_b32 s5, s5, s47
	v_and_b32_e32 v64, -4, v64
	s_add_i32 s4, s4, s46
	v_add_u32_e32 v188, s5, v64
	v_ashrrev_i32_e32 v189, 31, v188
	v_and_or_b32 v192, v201, 15, s4
	v_lshlrev_b64 v[64:65], 2, v[188:189]
	v_ashrrev_i32_e32 v193, 31, v192
	v_lshl_add_u64 v[190:191], s[8:9], 0, v[64:65]
	v_lshlrev_b64 v[72:73], 13, v[192:193]
	v_lshl_add_u64 v[80:81], v[190:191], 0, v[72:73]
	v_lshl_add_u64 v[66:67], s[14:15], 0, v[64:65]
	global_load_dwordx4 v[202:205], v[80:81], off
	global_load_dwordx4 v[104:107], v[66:67], off
	global_load_dwordx4 v[92:95], v[66:67], off offset:64
	global_load_dwordx4 v[206:209], v[80:81], off offset:64
	global_load_dwordx4 v[210:213], v[80:81], off offset:512
	global_load_dwordx4 v[84:87], v[66:67], off offset:512
	global_load_dwordx4 v[72:75], v[66:67], off offset:576
	global_load_dwordx4 v[214:217], v[80:81], off offset:576
	v_lshl_add_u64 v[64:65], s[18:19], 0, v[64:65]
	global_load_dwordx4 v[100:103], v[64:65], off
	global_load_dwordx4 v[88:91], v[64:65], off offset:64
	global_load_dwordx4 v[80:83], v[64:65], off offset:512
	s_nop 0
	global_load_dwordx4 v[64:67], v[64:65], off offset:576
	v_or_b32_e32 v194, 16, v192
	v_ashrrev_i32_e32 v195, 31, v194
	v_lshlrev_b64 v[160:161], 13, v[194:195]
	v_lshl_add_u64 v[160:161], v[190:191], 0, v[160:161]
	global_load_dwordx4 v[172:175], v[160:161], off
	global_load_dwordx4 v[168:171], v[160:161], off offset:64
	global_load_dwordx4 v[164:167], v[160:161], off offset:512
	s_nop 0
	global_load_dwordx4 v[160:163], v[160:161], off offset:576
	v_and_b32_e32 v219, 64, v200
	v_xor_b32_e32 v218, 16, v200
	v_cmp_gt_u32_e32 vcc, 16, v201
	v_add_u32_e32 v201, 64, v219
	v_cmp_lt_i32_e64 s[4:5], v218, v201
	s_waitcnt vmcnt(0) lgkmcnt(0)
	v_pk_fma_f32 v[158:159], v[158:159], v[106:107], v[204:205]
	v_cndmask_b32_e64 v222, v200, v218, s[4:5]
	v_lshlrev_b64 v[218:219], 11, v[192:193]
	v_lshl_add_u64 v[218:219], v[218:219], 0, v[188:189]
	v_lshl_add_u64 v[220:221], v[218:219], 2, s[10:11]
	v_pk_fma_f32 v[156:157], v[156:157], v[104:105], v[202:203]
	v_pk_fma_f32 v[154:155], v[154:155], v[94:95], v[208:209]
	v_pk_fma_f32 v[152:153], v[152:153], v[92:93], v[206:207]
	v_pk_fma_f32 v[150:151], v[150:151], v[86:87], v[212:213]
	v_pk_fma_f32 v[148:149], v[148:149], v[84:85], v[210:211]
	v_pk_fma_f32 v[204:205], v[146:147], v[74:75], v[216:217]
	v_pk_fma_f32 v[202:203], v[144:145], v[72:73], v[214:215]
	global_store_dwordx4 v[220:221], v[156:159], off
	v_mul_f32_e32 v214, v157, v157
	v_mul_f32_e32 v215, v159, v159
	v_pk_mul_f32 v[144:145], v[102:103], v[158:159]
	v_pk_mul_f32 v[146:147], v[100:101], v[156:157]
	v_mul_f32_e32 v157, v153, v153
	v_mul_f32_e32 v159, v155, v155
	v_lshl_add_u64 v[218:219], v[218:219], 1, s[16:17]
	v_mul_f32_e32 v216, v149, v149
	v_mul_f32_e32 v217, v151, v151
	v_fmac_f32_e32 v214, v156, v156
	v_fmac_f32_e32 v215, v158, v158
	v_cvt_pk_bf16_f32 v146, v146, v147
	v_cvt_pk_bf16_f32 v147, v144, v145
	v_fmac_f32_e32 v157, v152, v152
	v_fmac_f32_e32 v159, v154, v154
	v_mul_f32_e32 v223, v203, v203
	v_mul_f32_e32 v224, v205, v205
	v_fmac_f32_e32 v216, v148, v148
	v_fmac_f32_e32 v217, v150, v150
	v_add_f32_e32 v156, v214, v215
	global_store_dwordx2 v[218:219], v[146:147], off
	global_store_dwordx4 v[220:221], v[152:155], off offset:64
	v_add_f32_e32 v146, v157, v159
	v_pk_mul_f32 v[206:207], v[90:91], v[154:155]
	v_pk_mul_f32 v[208:209], v[88:89], v[152:153]
	v_fmac_f32_e32 v223, v202, v202
	v_fmac_f32_e32 v224, v204, v204
	v_cvt_pk_bf16_f32 v144, v208, v209
	v_cvt_pk_bf16_f32 v145, v206, v207
	v_add_f32_e32 v147, v216, v217
	v_add_f32_e32 v146, v156, v146
	v_add_f32_e32 v152, v223, v224
	global_store_dwordx2 v[218:219], v[144:145], off offset:32
	global_store_dwordx4 v[220:221], v[148:151], off offset:512
	v_add_f32_e32 v145, v146, v147
	v_pk_mul_f32 v[212:213], v[80:81], v[148:149]
	v_add_f32_e32 v149, v145, v152
	v_lshlrev_b32_e32 v148, 2, v222
	v_pk_mul_f32 v[210:211], v[82:83], v[150:151]
	ds_bpermute_b32 v150, v148, v149
	v_cvt_pk_bf16_f32 v144, v212, v213
	v_cvt_pk_bf16_f32 v145, v210, v211
	global_store_dwordx2 v[218:219], v[144:145], off offset:256
	global_store_dwordx4 v[220:221], v[202:205], off offset:576
	v_xor_b32_e32 v145, 32, v200
	v_cmp_lt_i32_e64 s[4:5], v145, v201
	s_waitcnt lgkmcnt(0)
	v_add_f32_e32 v144, v149, v150
	v_pk_mul_f32 v[150:151], v[64:65], v[202:203]
	v_cndmask_b32_e64 v145, v200, v145, s[4:5]
	v_lshlrev_b32_e32 v149, 2, v145
	ds_bpermute_b32 v145, v149, v144
	v_pk_mul_f32 v[146:147], v[66:67], v[204:205]
	v_cvt_pk_bf16_f32 v150, v150, v151
	s_nop 0
	v_cvt_pk_bf16_f32 v151, v146, v147
	global_store_dwordx2 v[218:219], v[150:151], off offset:288
	s_and_saveexec_b64 s[4:5], vcc
	s_cbranch_execz .LBB0_502
	s_waitcnt lgkmcnt(0)
	v_add_f32_e32 v144, v144, v145
	v_mul_f32_e32 v144, 0x4b800000, v144
	v_trunc_f32_e32 v144, v144
	v_mul_f32_e32 v145, 0x2f800000, v144
	v_floor_f32_e32 v145, v145
	v_fmac_f32_e32 v144, 0xcf800000, v145
	v_cvt_u32_f32_e32 v144, v144
	v_cvt_u32_f32_e32 v145, v145
	v_lshl_add_u64 v[146:147], v[192:193], 3, s[20:21]
	global_atomic_add_x2 v[146:147], v[144:145], off
; __device__ __forceinline__ unsigned cvt_pk_bf16(float lo, float hi) { unsigned r; asm volatile("v_cvt_pk_bf16_f32 %0, %1, %2" : "=v"(r) : "v"(lo), "v"(hi)); return r; }
;     __device__ __forceinline__ void operator()(const f32x4 (&acc)[2][2][4][2], const Unit& u, int wr, int wc, int fr_, int fq_) const {
;     ...
;         for (int mh = 0; mh < 2; ++mh) {
;             f32x4 bs[2][2][2];
; #pragma unroll
;             for (int m = 0; m < 2; ++m) { const size_t off = (size_t)(row0 + ai * HALF + (2 * mh + m) * 16) * ldc + col0;
; #pragma unroll
;                 for (int bj = 0; bj < 2; ++bj)
; #pragma unroll
;                     for (int n = 0; n < 2; ++n) bs[m][bj][n] = *(const f32x4*)(base + off + bj * HALF + n * 16); }
;             asm volatile("" ::: "memory");
; #pragma unroll
;             for (int m = 0; m < 2; ++m) { const int row = row0 + ai * HALF + (2 * mh + m) * 16; const size_t off = (size_t)row * ldc + col0; float ss = 0.f;
; #pragma unroll
;                 for (int bj = 0; bj < 2; ++bj)
; #pragma unroll
;                     for (int n = 0; n < 2; ++n) { const f32x4 o = bs[m][bj][n] + gv[bj][n] * acc[ai][bj][2 * mh + m][n]; *(f32x4*)(out + off + bj * HALF + n * 16) = o;
;                         if constexpr (EMIT) { ss += (o[0] * o[0] + o[1] * o[1]) + (o[2] * o[2] + o[3] * o[3]); const f32x4 y = o * gm[bj][n];
;                             typedef unsigned u32x2_t __attribute__((ext_vector_type(2))); u32x2_t w; w.x = cvt_pk_bf16(y[0], y[1]); w.y = cvt_pk_bf16(y[2], y[3]); *(u32x2_t*)(A2 + off + bj * HALF + n * 16) = w; } }
;                 if constexpr (EMIT) { ss += __shfl_xor(ss, 16); ss += __shfl_xor(ss, 32); if (fq == 0) atomicAdd(ssq + row, (unsigned long long)(ss * 16777216.0f)); } }
.LBB0_502:
	s_or_b64 exec, exec, s[4:5]
	s_waitcnt lgkmcnt(0)
	v_lshlrev_b64 v[144:145], 11, v[194:195]
	v_lshl_add_u64 v[144:145], v[144:145], 0, v[188:189]
	v_pk_fma_f32 v[142:143], v[142:143], v[106:107], v[174:175]
	v_pk_fma_f32 v[140:141], v[140:141], v[104:105], v[172:173]
	v_lshl_add_u64 v[146:147], v[144:145], 2, s[10:11]
	v_mul_f32_e32 v150, v141, v141
	v_mul_f32_e32 v151, v143, v143
	global_store_dwordx4 v[146:147], v[140:143], off
	v_fmac_f32_e32 v150, v140, v140
	v_fmac_f32_e32 v151, v142, v142
	v_pk_mul_f32 v[142:143], v[102:103], v[142:143]
	v_pk_mul_f32 v[140:141], v[100:101], v[140:141]
	v_pk_fma_f32 v[136:137], v[136:137], v[92:93], v[168:169]
	v_cvt_pk_bf16_f32 v140, v140, v141
	v_cvt_pk_bf16_f32 v141, v142, v143
	v_lshl_add_u64 v[142:143], v[144:145], 1, s[16:17]
	global_store_dwordx2 v[142:143], v[140:141], off
	v_pk_fma_f32 v[138:139], v[138:139], v[94:95], v[170:171]
	v_mul_f32_e32 v140, v137, v137
	global_store_dwordx4 v[146:147], v[136:139], off offset:64
	v_fmac_f32_e32 v140, v136, v136
	v_mul_f32_e32 v141, v139, v139
	v_pk_mul_f32 v[136:137], v[88:89], v[136:137]
	v_fmac_f32_e32 v141, v138, v138
	v_pk_mul_f32 v[138:139], v[90:91], v[138:139]
	v_cvt_pk_bf16_f32 v136, v136, v137
	v_pk_fma_f32 v[134:135], v[134:135], v[86:87], v[166:167]
	v_cvt_pk_bf16_f32 v137, v138, v139
	v_pk_fma_f32 v[132:133], v[132:133], v[84:85], v[164:165]
	global_store_dwordx2 v[142:143], v[136:137], off offset:32
	v_mul_f32_e32 v136, v133, v133
	v_mul_f32_e32 v137, v135, v135
	v_add_f32_e32 v150, v150, v151
	v_add_f32_e32 v140, v140, v141
	v_fmac_f32_e32 v136, v132, v132
	v_fmac_f32_e32 v137, v134, v134
	v_add_f32_e32 v140, v150, v140
	global_store_dwordx4 v[146:147], v[132:135], off offset:512
	v_add_f32_e32 v136, v136, v137
	v_add_f32_e32 v137, v140, v136
	v_pk_mul_f32 v[132:133], v[80:81], v[132:133]
	v_pk_mul_f32 v[134:135], v[82:83], v[134:135]
	v_cvt_pk_bf16_f32 v136, v132, v133
	v_pk_fma_f32 v[132:133], v[130:131], v[74:75], v[162:163]
	v_pk_fma_f32 v[130:131], v[128:129], v[72:73], v[160:161]
	v_mul_f32_e32 v129, v133, v133
	v_mul_f32_e32 v128, v131, v131
	v_fmac_f32_e32 v128, v130, v130
	v_fmac_f32_e32 v129, v132, v132
	v_add_f32_e32 v128, v128, v129
	v_add_f32_e32 v128, v137, v128
	ds_bpermute_b32 v129, v148, v128
	v_cvt_pk_bf16_f32 v137, v134, v135
	global_store_dwordx2 v[142:143], v[136:137], off offset:256
	global_store_dwordx4 v[146:147], v[130:133], off offset:576
	s_waitcnt lgkmcnt(0)
	v_add_f32_e32 v128, v128, v129
	ds_bpermute_b32 v129, v149, v128
	v_pk_mul_f32 v[130:131], v[64:65], v[130:131]
	v_pk_mul_f32 v[132:133], v[66:67], v[132:133]
	v_cvt_pk_bf16_f32 v130, v130, v131
	s_nop 0
	v_cvt_pk_bf16_f32 v131, v132, v133
	global_store_dwordx2 v[142:143], v[130:131], off offset:288
	s_and_saveexec_b64 s[4:5], vcc
	s_cbranch_execz .LBB0_504
	s_waitcnt lgkmcnt(0)
	v_add_f32_e32 v128, v128, v129
	v_mul_f32_e32 v128, 0x4b800000, v128
	v_trunc_f32_e32 v128, v128
	v_mul_f32_e32 v129, 0x2f800000, v128
	v_floor_f32_e32 v129, v129
	v_fmac_f32_e32 v128, 0xcf800000, v129
	v_cvt_u32_f32_e32 v128, v128
	v_cvt_u32_f32_e32 v129, v129
	v_lshl_add_u64 v[130:131], v[194:195], 3, s[20:21]
	global_atomic_add_x2 v[130:131], v[128:129], off
.LBB0_504:
	s_or_b64 exec, exec, s[4:5]
	v_or_b32_e32 v146, 32, v192
	v_ashrrev_i32_e32 v147, 31, v146
	s_waitcnt lgkmcnt(0)
	v_lshlrev_b64 v[128:129], 13, v[146:147]
	v_lshl_add_u64 v[128:129], v[190:191], 0, v[128:129]
	global_load_dwordx4 v[150:153], v[128:129], off
	global_load_dwordx4 v[154:157], v[128:129], off offset:64
	global_load_dwordx4 v[158:161], v[128:129], off offset:512
	global_load_dwordx4 v[162:165], v[128:129], off offset:576
	v_or_b32_e32 v144, 48, v192
	v_ashrrev_i32_e32 v145, 31, v144
	v_lshlrev_b64 v[128:129], 13, v[144:145]
	v_lshl_add_u64 v[128:129], v[190:191], 0, v[128:129]
	global_load_dwordx4 v[140:143], v[128:129], off
	global_load_dwordx4 v[136:139], v[128:129], off offset:64
	global_load_dwordx4 v[132:135], v[128:129], off offset:512
	s_nop 0
	global_load_dwordx4 v[128:131], v[128:129], off offset:576
	v_lshlrev_b64 v[166:167], 11, v[146:147]
	v_lshl_add_u64 v[166:167], v[166:167], 0, v[188:189]
	v_lshl_add_u64 v[168:169], v[166:167], 2, s[10:11]
	v_lshl_add_u64 v[166:167], v[166:167], 1, s[16:17]
	s_waitcnt vmcnt(0) lgkmcnt(0)
	v_pk_fma_f32 v[126:127], v[126:127], v[106:107], v[152:153]
	v_pk_fma_f32 v[124:125], v[124:125], v[104:105], v[150:151]
	v_pk_fma_f32 v[122:123], v[122:123], v[94:95], v[156:157]
	v_pk_fma_f32 v[120:121], v[120:121], v[92:93], v[154:155]
	v_pk_fma_f32 v[118:119], v[118:119], v[86:87], v[160:161]
	v_pk_fma_f32 v[116:117], v[116:117], v[84:85], v[158:159]
	v_pk_fma_f32 v[152:153], v[114:115], v[74:75], v[164:165]
	v_pk_fma_f32 v[150:151], v[112:113], v[72:73], v[162:163]
	global_store_dwordx4 v[168:169], v[124:127], off
	v_mul_f32_e32 v162, v125, v125
	v_mul_f32_e32 v163, v127, v127
	v_pk_mul_f32 v[112:113], v[102:103], v[126:127]
	v_pk_mul_f32 v[114:115], v[100:101], v[124:125]
	v_mul_f32_e32 v125, v121, v121
	v_mul_f32_e32 v127, v123, v123
	v_mul_f32_e32 v164, v117, v117
	v_mul_f32_e32 v165, v119, v119
	v_fmac_f32_e32 v162, v124, v124
	v_fmac_f32_e32 v163, v126, v126
	v_cvt_pk_bf16_f32 v114, v114, v115
	v_cvt_pk_bf16_f32 v115, v112, v113
	v_fmac_f32_e32 v125, v120, v120
	v_fmac_f32_e32 v127, v122, v122
	v_mul_f32_e32 v170, v151, v151
	v_mul_f32_e32 v171, v153, v153
	v_fmac_f32_e32 v164, v116, v116
	v_fmac_f32_e32 v165, v118, v118
	v_add_f32_e32 v124, v162, v163
	global_store_dwordx2 v[166:167], v[114:115], off
	global_store_dwordx4 v[168:169], v[120:123], off offset:64
	v_add_f32_e32 v114, v125, v127
	v_pk_mul_f32 v[154:155], v[90:91], v[122:123]
	v_pk_mul_f32 v[156:157], v[88:89], v[120:121]
	v_fmac_f32_e32 v170, v150, v150
	v_fmac_f32_e32 v171, v152, v152
	v_cvt_pk_bf16_f32 v112, v156, v157
	v_cvt_pk_bf16_f32 v113, v154, v155
	v_add_f32_e32 v115, v164, v165
	v_add_f32_e32 v114, v124, v114
	global_store_dwordx2 v[166:167], v[112:113], off offset:32
	global_store_dwordx4 v[168:169], v[116:119], off offset:512
	v_add_f32_e32 v113, v114, v115
	v_add_f32_e32 v114, v170, v171
	v_pk_mul_f32 v[160:161], v[80:81], v[116:117]
	v_add_f32_e32 v116, v113, v114
	ds_bpermute_b32 v117, v148, v116
	v_pk_mul_f32 v[158:159], v[82:83], v[118:119]
	v_cvt_pk_bf16_f32 v112, v160, v161
	v_pk_mul_f32 v[114:115], v[66:67], v[152:153]
	v_cvt_pk_bf16_f32 v113, v158, v159
	global_store_dwordx2 v[166:167], v[112:113], off offset:256
	global_store_dwordx4 v[168:169], v[150:153], off offset:576
	s_waitcnt lgkmcnt(0)
	v_add_f32_e32 v112, v116, v117
	ds_bpermute_b32 v113, v149, v112
	v_pk_mul_f32 v[116:117], v[64:65], v[150:151]
	s_nop 0
	v_cvt_pk_bf16_f32 v116, v116, v117
	v_cvt_pk_bf16_f32 v117, v114, v115
	global_store_dwordx2 v[166:167], v[116:117], off offset:288
	s_and_saveexec_b64 s[4:5], vcc
	s_cbranch_execz .LBB0_506
; __device__ __forceinline__ unsigned cvt_pk_bf16(float lo, float hi) { unsigned r; asm volatile("v_cvt_pk_bf16_f32 %0, %1, %2" : "=v"(r) : "v"(lo), "v"(hi)); return r; }
;     __device__ __forceinline__ void operator()(const f32x4 (&acc)[2][2][4][2], const Unit& u, int wr, int wc, int fr_, int fq_) const {
;     ...
;         for (int mh = 0; mh < 2; ++mh) {
;             f32x4 bs[2][2][2];
; #pragma unroll
;             for (int m = 0; m < 2; ++m) { const size_t off = (size_t)(row0 + ai * HALF + (2 * mh + m) * 16) * ldc + col0;
; #pragma unroll
;                 for (int bj = 0; bj < 2; ++bj)
; #pragma unroll
;                     for (int n = 0; n < 2; ++n) bs[m][bj][n] = *(const f32x4*)(base + off + bj * HALF + n * 16); }
;             asm volatile("" ::: "memory");
; #pragma unroll
;             for (int m = 0; m < 2; ++m) { const int row = row0 + ai * HALF + (2 * mh + m) * 16; const size_t off = (size_t)row * ldc + col0; float ss = 0.f;
; #pragma unroll
;                 for (int bj = 0; bj < 2; ++bj)
; #pragma unroll
;                     for (int n = 0; n < 2; ++n) { const f32x4 o = bs[m][bj][n] + gv[bj][n] * acc[ai][bj][2 * mh + m][n]; *(f32x4*)(out + off + bj * HALF + n * 16) = o;
;                         if constexpr (EMIT) { ss += (o[0] * o[0] + o[1] * o[1]) + (o[2] * o[2] + o[3] * o[3]); const f32x4 y = o * gm[bj][n];
;                             typedef unsigned u32x2_t __attribute__((ext_vector_type(2))); u32x2_t w; w.x = cvt_pk_bf16(y[0], y[1]); w.y = cvt_pk_bf16(y[2], y[3]); *(u32x2_t*)(A2 + off + bj * HALF + n * 16) = w; } }
;                 if constexpr (EMIT) { ss += __shfl_xor(ss, 16); ss += __shfl_xor(ss, 32); if (fq == 0) atomicAdd(ssq + row, (unsigned long long)(ss * 16777216.0f)); } }
	s_waitcnt lgkmcnt(0)
	v_add_f32_e32 v112, v112, v113
	v_mul_f32_e32 v112, 0x4b800000, v112
	v_trunc_f32_e32 v112, v112
	v_mul_f32_e32 v113, 0x2f800000, v112
	v_floor_f32_e32 v113, v113
	v_fmac_f32_e32 v112, 0xcf800000, v113
	v_cvt_u32_f32_e32 v112, v112
	v_cvt_u32_f32_e32 v113, v113
	v_lshl_add_u64 v[114:115], v[146:147], 3, s[20:21]
	global_atomic_add_x2 v[114:115], v[112:113], off
.LBB0_506:
	s_or_b64 exec, exec, s[4:5]
	s_waitcnt lgkmcnt(0)
	v_lshlrev_b64 v[112:113], 11, v[144:145]
	v_lshl_add_u64 v[112:113], v[112:113], 0, v[188:189]
	v_pk_fma_f32 v[110:111], v[110:111], v[106:107], v[142:143]
	v_pk_fma_f32 v[108:109], v[108:109], v[104:105], v[140:141]
	v_lshl_add_u64 v[114:115], v[112:113], 2, s[10:11]
	v_mul_f32_e32 v116, v109, v109
	v_mul_f32_e32 v117, v111, v111
	global_store_dwordx4 v[114:115], v[108:111], off
	v_fmac_f32_e32 v116, v108, v108
	v_fmac_f32_e32 v117, v110, v110
	v_pk_mul_f32 v[110:111], v[102:103], v[110:111]
	v_pk_mul_f32 v[108:109], v[100:101], v[108:109]
	v_pk_fma_f32 v[96:97], v[96:97], v[92:93], v[136:137]
	v_cvt_pk_bf16_f32 v108, v108, v109
	v_cvt_pk_bf16_f32 v109, v110, v111
	v_lshl_add_u64 v[110:111], v[112:113], 1, s[16:17]
	global_store_dwordx2 v[110:111], v[108:109], off
	v_pk_fma_f32 v[98:99], v[98:99], v[94:95], v[138:139]
	v_mul_f32_e32 v108, v97, v97
	global_store_dwordx4 v[114:115], v[96:99], off offset:64
	v_fmac_f32_e32 v108, v96, v96
	v_mul_f32_e32 v109, v99, v99
	v_pk_mul_f32 v[96:97], v[88:89], v[96:97]
	v_fmac_f32_e32 v109, v98, v98
	v_pk_mul_f32 v[98:99], v[90:91], v[98:99]
	v_cvt_pk_bf16_f32 v96, v96, v97
	v_pk_fma_f32 v[78:79], v[78:79], v[86:87], v[134:135]
	v_cvt_pk_bf16_f32 v97, v98, v99
	v_pk_fma_f32 v[76:77], v[76:77], v[84:85], v[132:133]
	global_store_dwordx2 v[110:111], v[96:97], off offset:32
	v_mul_f32_e32 v96, v77, v77
	v_mul_f32_e32 v97, v79, v79
	v_add_f32_e32 v116, v116, v117
	v_add_f32_e32 v108, v108, v109
	v_fmac_f32_e32 v96, v76, v76
	v_fmac_f32_e32 v97, v78, v78
	v_add_f32_e32 v108, v116, v108
	global_store_dwordx4 v[114:115], v[76:79], off offset:512
	v_add_f32_e32 v96, v96, v97
	v_add_f32_e32 v99, v108, v96
	v_pk_mul_f32 v[76:77], v[80:81], v[76:77]
	v_pk_mul_f32 v[96:97], v[82:83], v[78:79]
	v_cvt_pk_bf16_f32 v98, v76, v77
	v_pk_fma_f32 v[78:79], v[70:71], v[74:75], v[130:131]
	v_pk_fma_f32 v[76:77], v[68:69], v[72:73], v[128:129]
	v_mul_f32_e32 v69, v79, v79
	v_mul_f32_e32 v68, v77, v77
	v_fmac_f32_e32 v68, v76, v76
	v_fmac_f32_e32 v69, v78, v78
	v_add_f32_e32 v68, v68, v69
	v_add_f32_e32 v68, v99, v68
	ds_bpermute_b32 v69, v148, v68
	v_cvt_pk_bf16_f32 v99, v96, v97
	global_store_dwordx2 v[110:111], v[98:99], off offset:256
	global_store_dwordx4 v[114:115], v[76:79], off offset:576
	v_pk_mul_f32 v[70:71], v[66:67], v[78:79]
	s_waitcnt lgkmcnt(0)
	v_add_f32_e32 v68, v68, v69
	ds_bpermute_b32 v69, v149, v68
	v_pk_mul_f32 v[76:77], v[64:65], v[76:77]
	s_nop 0
	v_cvt_pk_bf16_f32 v76, v76, v77
	v_cvt_pk_bf16_f32 v77, v70, v71
	global_store_dwordx2 v[110:111], v[76:77], off offset:288
	s_and_saveexec_b64 s[4:5], vcc
	s_cbranch_execz .LBB0_508
	s_waitcnt lgkmcnt(0)
	v_add_f32_e32 v68, v68, v69
	v_mul_f32_e32 v68, 0x4b800000, v68
	v_trunc_f32_e32 v68, v68
	v_mul_f32_e32 v69, 0x2f800000, v68
	v_floor_f32_e32 v69, v69
	v_fmac_f32_e32 v68, 0xcf800000, v69
	v_cvt_u32_f32_e32 v68, v68
	v_cvt_u32_f32_e32 v69, v69
	v_lshl_add_u64 v[70:71], v[144:145], 3, s[20:21]
	global_atomic_add_x2 v[70:71], v[68:69], off
.LBB0_508:
	s_or_b64 exec, exec, s[4:5]
	v_add_u32_e32 v114, 0x80, v192
	v_ashrrev_i32_e32 v115, 31, v114
	s_waitcnt lgkmcnt(0)
	v_lshlrev_b64 v[68:69], 13, v[114:115]
	v_lshl_add_u64 v[68:69], v[190:191], 0, v[68:69]
	global_load_dwordx4 v[116:119], v[68:69], off
	global_load_dwordx4 v[120:123], v[68:69], off offset:64
	global_load_dwordx4 v[124:127], v[68:69], off offset:512
	global_load_dwordx4 v[128:131], v[68:69], off offset:576
	v_add_u32_e32 v112, 0x90, v192
	v_ashrrev_i32_e32 v113, 31, v112
	v_lshlrev_b64 v[68:69], 13, v[112:113]
	v_lshl_add_u64 v[68:69], v[190:191], 0, v[68:69]
	global_load_dwordx4 v[108:111], v[68:69], off
	global_load_dwordx4 v[96:99], v[68:69], off offset:64
	global_load_dwordx4 v[76:79], v[68:69], off offset:512
	s_nop 0
	global_load_dwordx4 v[68:71], v[68:69], off offset:576
	v_lshlrev_b64 v[132:133], 11, v[114:115]
	v_lshl_add_u64 v[132:133], v[132:133], 0, v[188:189]
	v_lshl_add_u64 v[134:135], v[132:133], 2, s[10:11]
	v_lshl_add_u64 v[132:133], v[132:133], 1, s[16:17]
	s_waitcnt vmcnt(0) lgkmcnt(0)
	v_pk_fma_f32 v[62:63], v[62:63], v[106:107], v[118:119]
	v_pk_fma_f32 v[60:61], v[60:61], v[104:105], v[116:117]
	v_pk_fma_f32 v[58:59], v[58:59], v[94:95], v[122:123]
	v_pk_fma_f32 v[56:57], v[56:57], v[92:93], v[120:121]
	v_pk_fma_f32 v[54:55], v[54:55], v[86:87], v[126:127]
	v_pk_fma_f32 v[52:53], v[52:53], v[84:85], v[124:125]
	v_pk_fma_f32 v[118:119], v[50:51], v[74:75], v[130:131]
	v_pk_fma_f32 v[116:117], v[48:49], v[72:73], v[128:129]
	global_store_dwordx4 v[134:135], v[60:63], off
	v_mul_f32_e32 v128, v61, v61
	v_mul_f32_e32 v129, v63, v63
	v_pk_mul_f32 v[48:49], v[102:103], v[62:63]
	v_pk_mul_f32 v[50:51], v[100:101], v[60:61]
	v_mul_f32_e32 v61, v57, v57
	v_mul_f32_e32 v63, v59, v59
	v_mul_f32_e32 v130, v53, v53
	v_mul_f32_e32 v131, v55, v55
	v_fmac_f32_e32 v128, v60, v60
	v_fmac_f32_e32 v129, v62, v62
	v_cvt_pk_bf16_f32 v50, v50, v51
	v_cvt_pk_bf16_f32 v51, v48, v49
	v_fmac_f32_e32 v61, v56, v56
	v_fmac_f32_e32 v63, v58, v58
	v_mul_f32_e32 v136, v117, v117
	v_mul_f32_e32 v137, v119, v119
	v_fmac_f32_e32 v130, v52, v52
	v_fmac_f32_e32 v131, v54, v54
	v_add_f32_e32 v60, v128, v129
	global_store_dwordx2 v[132:133], v[50:51], off
	global_store_dwordx4 v[134:135], v[56:59], off offset:64
	v_add_f32_e32 v50, v61, v63
	v_pk_mul_f32 v[120:121], v[90:91], v[58:59]
	v_pk_mul_f32 v[122:123], v[88:89], v[56:57]
	v_fmac_f32_e32 v136, v116, v116
	v_fmac_f32_e32 v137, v118, v118
	v_cvt_pk_bf16_f32 v48, v122, v123
	v_cvt_pk_bf16_f32 v49, v120, v121
	v_add_f32_e32 v51, v130, v131
	v_add_f32_e32 v50, v60, v50
	global_store_dwordx2 v[132:133], v[48:49], off offset:32
	global_store_dwordx4 v[134:135], v[52:55], off offset:512
	v_add_f32_e32 v49, v50, v51
	v_add_f32_e32 v50, v136, v137
	v_pk_mul_f32 v[126:127], v[80:81], v[52:53]
	v_add_f32_e32 v52, v49, v50
	ds_bpermute_b32 v53, v148, v52
	v_pk_mul_f32 v[124:125], v[82:83], v[54:55]
	v_cvt_pk_bf16_f32 v48, v126, v127
	v_pk_mul_f32 v[50:51], v[66:67], v[118:119]
	v_cvt_pk_bf16_f32 v49, v124, v125
	global_store_dwordx2 v[132:133], v[48:49], off offset:256
	global_store_dwordx4 v[134:135], v[116:119], off offset:576
	s_waitcnt lgkmcnt(0)
	v_add_f32_e32 v48, v52, v53
	ds_bpermute_b32 v49, v149, v48
	v_pk_mul_f32 v[52:53], v[64:65], v[116:117]
	s_nop 0
	v_cvt_pk_bf16_f32 v52, v52, v53
	v_cvt_pk_bf16_f32 v53, v50, v51
	global_store_dwordx2 v[132:133], v[52:53], off offset:288
	s_and_saveexec_b64 s[4:5], vcc
	s_cbranch_execz .LBB0_510
; __device__ __forceinline__ unsigned cvt_pk_bf16(float lo, float hi) { unsigned r; asm volatile("v_cvt_pk_bf16_f32 %0, %1, %2" : "=v"(r) : "v"(lo), "v"(hi)); return r; }
;     __device__ __forceinline__ void operator()(const f32x4 (&acc)[2][2][4][2], const Unit& u, int wr, int wc, int fr_, int fq_) const {
;     ...
;             for (int m = 0; m < 2; ++m) { const int row = row0 + ai * HALF + (2 * mh + m) * 16; const size_t off = (size_t)row * ldc + col0; float ss = 0.f;
; #pragma unroll
;                 for (int bj = 0; bj < 2; ++bj)
; #pragma unroll
;                     for (int n = 0; n < 2; ++n) { const f32x4 o = bs[m][bj][n] + gv[bj][n] * acc[ai][bj][2 * mh + m][n]; *(f32x4*)(out + off + bj * HALF + n * 16) = o;
;                         if constexpr (EMIT) { ss += (o[0] * o[0] + o[1] * o[1]) + (o[2] * o[2] + o[3] * o[3]); const f32x4 y = o * gm[bj][n];
;                             typedef unsigned u32x2_t __attribute__((ext_vector_type(2))); u32x2_t w; w.x = cvt_pk_bf16(y[0], y[1]); w.y = cvt_pk_bf16(y[2], y[3]); *(u32x2_t*)(A2 + off + bj * HALF + n * 16) = w; } }
;                 if constexpr (EMIT) { ss += __shfl_xor(ss, 16); ss += __shfl_xor(ss, 32); if (fq == 0) atomicAdd(ssq + row, (unsigned long long)(ss * 16777216.0f)); } }
	s_waitcnt lgkmcnt(0)
	v_add_f32_e32 v48, v48, v49
	v_mul_f32_e32 v48, 0x4b800000, v48
	v_trunc_f32_e32 v48, v48
	v_mul_f32_e32 v49, 0x2f800000, v48
	v_floor_f32_e32 v49, v49
	v_fmac_f32_e32 v48, 0xcf800000, v49
	v_cvt_u32_f32_e32 v48, v48
	v_cvt_u32_f32_e32 v49, v49
	v_lshl_add_u64 v[50:51], v[114:115], 3, s[20:21]
	global_atomic_add_x2 v[50:51], v[48:49], off
.LBB0_510:
	s_or_b64 exec, exec, s[4:5]
	s_waitcnt lgkmcnt(0)
	v_lshlrev_b64 v[48:49], 11, v[112:113]
	v_lshl_add_u64 v[48:49], v[48:49], 0, v[188:189]
	v_pk_fma_f32 v[46:47], v[46:47], v[106:107], v[110:111]
	v_pk_fma_f32 v[44:45], v[44:45], v[104:105], v[108:109]
	v_lshl_add_u64 v[50:51], v[48:49], 2, s[10:11]
	v_mul_f32_e32 v52, v45, v45
	v_mul_f32_e32 v53, v47, v47
	global_store_dwordx4 v[50:51], v[44:47], off
	v_fmac_f32_e32 v52, v44, v44
	v_fmac_f32_e32 v53, v46, v46
	v_pk_mul_f32 v[46:47], v[102:103], v[46:47]
	v_pk_mul_f32 v[44:45], v[100:101], v[44:45]
	v_pk_fma_f32 v[40:41], v[40:41], v[92:93], v[96:97]
	v_cvt_pk_bf16_f32 v44, v44, v45
	v_cvt_pk_bf16_f32 v45, v46, v47
	v_lshl_add_u64 v[46:47], v[48:49], 1, s[16:17]
	global_store_dwordx2 v[46:47], v[44:45], off
	v_pk_fma_f32 v[42:43], v[42:43], v[94:95], v[98:99]
	v_mul_f32_e32 v44, v41, v41
	global_store_dwordx4 v[50:51], v[40:43], off offset:64
	v_fmac_f32_e32 v44, v40, v40
	v_mul_f32_e32 v45, v43, v43
	v_pk_mul_f32 v[40:41], v[88:89], v[40:41]
	v_fmac_f32_e32 v45, v42, v42
	v_pk_mul_f32 v[42:43], v[90:91], v[42:43]
	v_cvt_pk_bf16_f32 v40, v40, v41
	v_pk_fma_f32 v[38:39], v[38:39], v[86:87], v[78:79]
	v_cvt_pk_bf16_f32 v41, v42, v43
	v_pk_fma_f32 v[36:37], v[36:37], v[84:85], v[76:77]
	global_store_dwordx2 v[46:47], v[40:41], off offset:32
	v_mul_f32_e32 v40, v37, v37
	v_mul_f32_e32 v41, v39, v39
	v_add_f32_e32 v52, v52, v53
	v_add_f32_e32 v44, v44, v45
	v_fmac_f32_e32 v40, v36, v36
	v_fmac_f32_e32 v41, v38, v38
	v_add_f32_e32 v44, v52, v44
	global_store_dwordx4 v[50:51], v[36:39], off offset:512
	v_add_f32_e32 v40, v40, v41
	v_add_f32_e32 v41, v44, v40
	v_pk_mul_f32 v[36:37], v[80:81], v[36:37]
	v_pk_mul_f32 v[38:39], v[82:83], v[38:39]
	v_cvt_pk_bf16_f32 v40, v36, v37
	v_pk_fma_f32 v[36:37], v[34:35], v[74:75], v[70:71]
	v_pk_fma_f32 v[34:35], v[32:33], v[72:73], v[68:69]
	v_mul_f32_e32 v33, v37, v37
	v_mul_f32_e32 v32, v35, v35
	v_fmac_f32_e32 v32, v34, v34
	v_fmac_f32_e32 v33, v36, v36
	v_add_f32_e32 v32, v32, v33
	v_add_f32_e32 v32, v41, v32
	ds_bpermute_b32 v33, v148, v32
	v_cvt_pk_bf16_f32 v41, v38, v39
	global_store_dwordx2 v[46:47], v[40:41], off offset:256
	global_store_dwordx4 v[50:51], v[34:37], off offset:576
	s_waitcnt lgkmcnt(0)
	v_add_f32_e32 v32, v32, v33
	ds_bpermute_b32 v33, v149, v32
	v_pk_mul_f32 v[34:35], v[64:65], v[34:35]
	v_pk_mul_f32 v[36:37], v[66:67], v[36:37]
	v_cvt_pk_bf16_f32 v34, v34, v35
	s_nop 0
	v_cvt_pk_bf16_f32 v35, v36, v37
	global_store_dwordx2 v[46:47], v[34:35], off offset:288
	s_and_saveexec_b64 s[4:5], vcc
	s_cbranch_execz .LBB0_512
	s_waitcnt lgkmcnt(0)
	v_add_f32_e32 v32, v32, v33
	v_mul_f32_e32 v32, 0x4b800000, v32
	v_trunc_f32_e32 v32, v32
	v_mul_f32_e32 v33, 0x2f800000, v32
	v_floor_f32_e32 v33, v33
	v_fmac_f32_e32 v32, 0xcf800000, v33
	v_cvt_u32_f32_e32 v32, v32
	v_cvt_u32_f32_e32 v33, v33
	v_lshl_add_u64 v[34:35], v[112:113], 3, s[20:21]
	global_atomic_add_x2 v[34:35], v[32:33], off
; __device__ __forceinline__ unsigned cvt_pk_bf16(float lo, float hi) { unsigned r; asm volatile("v_cvt_pk_bf16_f32 %0, %1, %2" : "=v"(r) : "v"(lo), "v"(hi)); return r; }
;     __device__ __forceinline__ void operator()(const f32x4 (&acc)[2][2][4][2], const Unit& u, int wr, int wc, int fr_, int fq_) const {
;     ...
;         for (int mh = 0; mh < 2; ++mh) {
;             f32x4 bs[2][2][2];
; #pragma unroll
;             for (int m = 0; m < 2; ++m) { const size_t off = (size_t)(row0 + ai * HALF + (2 * mh + m) * 16) * ldc + col0;
; #pragma unroll
;                 for (int bj = 0; bj < 2; ++bj)
; #pragma unroll
;                     for (int n = 0; n < 2; ++n) bs[m][bj][n] = *(const f32x4*)(base + off + bj * HALF + n * 16); }
;             asm volatile("" ::: "memory");
; #pragma unroll
;             for (int m = 0; m < 2; ++m) { const int row = row0 + ai * HALF + (2 * mh + m) * 16; const size_t off = (size_t)row * ldc + col0; float ss = 0.f;
; #pragma unroll
;                 for (int bj = 0; bj < 2; ++bj)
; #pragma unroll
;                     for (int n = 0; n < 2; ++n) { const f32x4 o = bs[m][bj][n] + gv[bj][n] * acc[ai][bj][2 * mh + m][n]; *(f32x4*)(out + off + bj * HALF + n * 16) = o;
;                         if constexpr (EMIT) { ss += (o[0] * o[0] + o[1] * o[1]) + (o[2] * o[2] + o[3] * o[3]); const f32x4 y = o * gm[bj][n];
;                             typedef unsigned u32x2_t __attribute__((ext_vector_type(2))); u32x2_t w; w.x = cvt_pk_bf16(y[0], y[1]); w.y = cvt_pk_bf16(y[2], y[3]); *(u32x2_t*)(A2 + off + bj * HALF + n * 16) = w; } }
;                 if constexpr (EMIT) { ss += __shfl_xor(ss, 16); ss += __shfl_xor(ss, 32); if (fq == 0) atomicAdd(ssq + row, (unsigned long long)(ss * 16777216.0f)); } }
.LBB0_512:
	s_or_b64 exec, exec, s[4:5]
	v_add_u32_e32 v50, 0xa0, v192
	v_ashrrev_i32_e32 v51, 31, v50
	s_waitcnt lgkmcnt(0)
	v_lshlrev_b64 v[32:33], 13, v[50:51]
	v_lshl_add_u64 v[32:33], v[190:191], 0, v[32:33]
	global_load_dwordx4 v[52:55], v[32:33], off
	global_load_dwordx4 v[56:59], v[32:33], off offset:64
	global_load_dwordx4 v[60:63], v[32:33], off offset:512
	global_load_dwordx4 v[68:71], v[32:33], off offset:576
	v_add_u32_e32 v48, 0xb0, v192
	v_ashrrev_i32_e32 v49, 31, v48
	v_lshlrev_b64 v[32:33], 13, v[48:49]
	v_lshl_add_u64 v[32:33], v[190:191], 0, v[32:33]
	global_load_dwordx4 v[44:47], v[32:33], off
	global_load_dwordx4 v[40:43], v[32:33], off offset:64
	global_load_dwordx4 v[36:39], v[32:33], off offset:512
	s_nop 0
	global_load_dwordx4 v[32:35], v[32:33], off offset:576
	v_lshlrev_b64 v[76:77], 11, v[50:51]
	v_lshl_add_u64 v[76:77], v[76:77], 0, v[188:189]
	v_lshl_add_u64 v[78:79], v[76:77], 2, s[10:11]
	v_lshl_add_u64 v[76:77], v[76:77], 1, s[16:17]
	s_waitcnt vmcnt(0) lgkmcnt(0)
	v_pk_fma_f32 v[30:31], v[30:31], v[106:107], v[54:55]
	v_pk_fma_f32 v[28:29], v[28:29], v[104:105], v[52:53]
	v_pk_fma_f32 v[26:27], v[26:27], v[94:95], v[58:59]
	v_pk_fma_f32 v[24:25], v[24:25], v[92:93], v[56:57]
	v_pk_fma_f32 v[22:23], v[22:23], v[86:87], v[62:63]
	v_pk_fma_f32 v[20:21], v[20:21], v[84:85], v[60:61]
	v_pk_fma_f32 v[54:55], v[18:19], v[74:75], v[70:71]
	v_pk_fma_f32 v[52:53], v[16:17], v[72:73], v[68:69]
	global_store_dwordx4 v[78:79], v[28:31], off
	v_mul_f32_e32 v68, v29, v29
	v_mul_f32_e32 v69, v31, v31
	v_pk_mul_f32 v[16:17], v[102:103], v[30:31]
	v_pk_mul_f32 v[18:19], v[100:101], v[28:29]
	v_mul_f32_e32 v29, v25, v25
	v_mul_f32_e32 v31, v27, v27
	v_mul_f32_e32 v70, v21, v21
	v_mul_f32_e32 v71, v23, v23
	v_fmac_f32_e32 v68, v28, v28
	v_fmac_f32_e32 v69, v30, v30
	v_cvt_pk_bf16_f32 v18, v18, v19
	v_cvt_pk_bf16_f32 v19, v16, v17
	v_fmac_f32_e32 v29, v24, v24
	v_fmac_f32_e32 v31, v26, v26
	v_mul_f32_e32 v96, v53, v53
	v_mul_f32_e32 v97, v55, v55
	v_fmac_f32_e32 v70, v20, v20
	v_fmac_f32_e32 v71, v22, v22
	v_add_f32_e32 v28, v68, v69
	global_store_dwordx2 v[76:77], v[18:19], off
	global_store_dwordx4 v[78:79], v[24:27], off offset:64
	v_add_f32_e32 v18, v29, v31
	v_pk_mul_f32 v[56:57], v[90:91], v[26:27]
	v_pk_mul_f32 v[58:59], v[88:89], v[24:25]
	v_fmac_f32_e32 v96, v52, v52
	v_fmac_f32_e32 v97, v54, v54
	v_cvt_pk_bf16_f32 v16, v58, v59
	v_cvt_pk_bf16_f32 v17, v56, v57
	v_add_f32_e32 v19, v70, v71
	v_add_f32_e32 v18, v28, v18
	global_store_dwordx2 v[76:77], v[16:17], off offset:32
	global_store_dwordx4 v[78:79], v[20:23], off offset:512
	v_add_f32_e32 v17, v18, v19
	v_add_f32_e32 v18, v96, v97
	v_pk_mul_f32 v[62:63], v[80:81], v[20:21]
	v_add_f32_e32 v20, v17, v18
	ds_bpermute_b32 v21, v148, v20
	v_pk_mul_f32 v[60:61], v[82:83], v[22:23]
	v_cvt_pk_bf16_f32 v16, v62, v63
	v_pk_mul_f32 v[18:19], v[66:67], v[54:55]
	v_cvt_pk_bf16_f32 v17, v60, v61
	global_store_dwordx2 v[76:77], v[16:17], off offset:256
	global_store_dwordx4 v[78:79], v[52:55], off offset:576
	s_waitcnt lgkmcnt(0)
	v_add_f32_e32 v16, v20, v21
	ds_bpermute_b32 v17, v149, v16
	v_pk_mul_f32 v[20:21], v[64:65], v[52:53]
	s_nop 0
	v_cvt_pk_bf16_f32 v20, v20, v21
	v_cvt_pk_bf16_f32 v21, v18, v19
	global_store_dwordx2 v[76:77], v[20:21], off offset:288
	s_and_saveexec_b64 s[4:5], vcc
	s_cbranch_execz .LBB0_514
	s_waitcnt lgkmcnt(0)
	v_add_f32_e32 v16, v16, v17
	v_mul_f32_e32 v16, 0x4b800000, v16
	v_trunc_f32_e32 v16, v16
	v_mul_f32_e32 v17, 0x2f800000, v16
	v_floor_f32_e32 v17, v17
	v_fmac_f32_e32 v16, 0xcf800000, v17
	v_cvt_u32_f32_e32 v16, v16
	v_cvt_u32_f32_e32 v17, v17
	v_lshl_add_u64 v[18:19], v[50:51], 3, s[20:21]
	global_atomic_add_x2 v[18:19], v[16:17], off
.LBB0_514:
	s_or_b64 exec, exec, s[4:5]
	s_waitcnt lgkmcnt(0)
	v_lshlrev_b64 v[16:17], 11, v[48:49]
	v_lshl_add_u64 v[16:17], v[16:17], 0, v[188:189]
	v_pk_fma_f32 v[14:15], v[14:15], v[106:107], v[46:47]
	v_pk_fma_f32 v[12:13], v[12:13], v[104:105], v[44:45]
	v_lshl_add_u64 v[18:19], v[16:17], 2, s[10:11]
	v_mul_f32_e32 v20, v13, v13
	v_mul_f32_e32 v21, v15, v15
	global_store_dwordx4 v[18:19], v[12:15], off
	v_fmac_f32_e32 v20, v12, v12
	v_fmac_f32_e32 v21, v14, v14
	v_pk_mul_f32 v[14:15], v[102:103], v[14:15]
	v_pk_mul_f32 v[12:13], v[100:101], v[12:13]
	v_pk_fma_f32 v[8:9], v[8:9], v[92:93], v[40:41]
	v_cvt_pk_bf16_f32 v12, v12, v13
	v_cvt_pk_bf16_f32 v13, v14, v15
	v_lshl_add_u64 v[14:15], v[16:17], 1, s[16:17]
	global_store_dwordx2 v[14:15], v[12:13], off
	v_pk_fma_f32 v[10:11], v[10:11], v[94:95], v[42:43]
	v_mul_f32_e32 v12, v9, v9
	global_store_dwordx4 v[18:19], v[8:11], off offset:64
	v_fmac_f32_e32 v12, v8, v8
	v_mul_f32_e32 v13, v11, v11
	v_pk_mul_f32 v[8:9], v[88:89], v[8:9]
	v_fmac_f32_e32 v13, v10, v10
	v_pk_mul_f32 v[10:11], v[90:91], v[10:11]
	v_cvt_pk_bf16_f32 v8, v8, v9
	v_pk_fma_f32 v[6:7], v[6:7], v[86:87], v[38:39]
	v_cvt_pk_bf16_f32 v9, v10, v11
	v_pk_fma_f32 v[4:5], v[4:5], v[84:85], v[36:37]
	global_store_dwordx2 v[14:15], v[8:9], off offset:32
	v_mul_f32_e32 v8, v5, v5
	v_mul_f32_e32 v9, v7, v7
	v_add_f32_e32 v20, v20, v21
	v_add_f32_e32 v12, v12, v13
	v_fmac_f32_e32 v8, v4, v4
	v_fmac_f32_e32 v9, v6, v6
	v_add_f32_e32 v12, v20, v12
	global_store_dwordx4 v[18:19], v[4:7], off offset:512
	v_add_f32_e32 v8, v8, v9
	v_add_f32_e32 v9, v12, v8
	v_pk_mul_f32 v[4:5], v[80:81], v[4:5]
	v_pk_mul_f32 v[6:7], v[82:83], v[6:7]
	v_cvt_pk_bf16_f32 v8, v4, v5
	v_pk_fma_f32 v[4:5], v[2:3], v[74:75], v[34:35]
	v_pk_fma_f32 v[2:3], v[0:1], v[72:73], v[32:33]
	v_mul_f32_e32 v1, v5, v5
	v_mul_f32_e32 v0, v3, v3
	v_fmac_f32_e32 v0, v2, v2
	v_fmac_f32_e32 v1, v4, v4
	v_add_f32_e32 v0, v0, v1
	v_add_f32_e32 v0, v9, v0
	ds_bpermute_b32 v1, v148, v0
	v_cvt_pk_bf16_f32 v9, v6, v7
	global_store_dwordx2 v[14:15], v[8:9], off offset:256
	global_store_dwordx4 v[18:19], v[2:5], off offset:576
	s_waitcnt lgkmcnt(0)
	v_add_f32_e32 v0, v0, v1
	ds_bpermute_b32 v1, v149, v0
	v_pk_mul_f32 v[2:3], v[64:65], v[2:3]
	v_pk_mul_f32 v[4:5], v[66:67], v[4:5]
	v_cvt_pk_bf16_f32 v2, v2, v3
	s_nop 0
	v_cvt_pk_bf16_f32 v3, v4, v5
	global_store_dwordx2 v[14:15], v[2:3], off offset:288
	s_and_saveexec_b64 s[4:5], vcc
	s_cbranch_execz .LBB0_516
	s_waitcnt lgkmcnt(0)
	v_add_f32_e32 v0, v0, v1
	v_mul_f32_e32 v0, 0x4b800000, v0
	v_trunc_f32_e32 v0, v0
	v_mul_f32_e32 v1, 0x2f800000, v0
	v_floor_f32_e32 v1, v1
	v_fmac_f32_e32 v0, 0xcf800000, v1
	v_cvt_u32_f32_e32 v0, v0
	v_cvt_u32_f32_e32 v1, v1
	v_lshl_add_u64 v[2:3], v[48:49], 3, s[20:21]
	global_atomic_add_x2 v[2:3], v[0:1], off

.LBB0_535:
	s_or_b64 exec, exec, s[0:1]
	s_xor_b64 s[0:1], s[4:5], -1
	s_and_saveexec_b64 s[4:5], s[0:1]
	s_xor_b64 s[0:1], exec, s[4:5]
	s_cbranch_execz .LBB0_537
	v_mov_b32_e32 v2, 1
	v_mov_b64_e32 v[0:1], s[36:37]
	global_atomic_add v[0:1], v2, off offset:512

; __device__ __forceinline__ unsigned xb_ld(unsigned* p)              { return __hip_atomic_load(p, __ATOMIC_RELAXED, __HIP_MEMORY_SCOPE_AGENT); }
; __device__ __forceinline__ unsigned xb_add(unsigned* p, unsigned v) { return __hip_atomic_fetch_add(p, v, __ATOMIC_RELAXED, __HIP_MEMORY_SCOPE_AGENT); }
; #define XB_SPIN(cond, bar) do { unsigned _sp = 0; while (cond) { __builtin_amdgcn_s_sleep(1); \
;     if ((++_sp & 255u) == 0u) { if (xb_ld(&(bar)[XB_TMO])) break; if (_sp > XB_SPIN_CAP) { atomicAdd(&(bar)[XB_TMO], 1u); break; } } } } while (0)
; __device__ __forceinline__ void xcd_barrier(unsigned* bar, volatile LAS unsigned* st, bool lead) {
;     ...
;         const unsigned old = xb_add(&bar[XB_XSUB(x)], 1u);
;         const unsigned gen = old / nloc;
;         if (old + 1u == (gen + 1u) * nloc) {
;             __builtin_amdgcn_fence(__ATOMIC_RELEASE, "agent");
;             asm volatile("s_waitcnt vmcnt(0)" ::: "memory");
;             const unsigned og = xb_add(&bar[XB_TOP], 1u);
;             const unsigned tg = og / nx;
;             if (og + 1u == (tg + 1u) * nx) xb_add(&bar[XB_TOPGEN], 1u);
;             else XB_SPIN(xb_ld(&bar[XB_TOPGEN]) == tg, bar);
;             __builtin_amdgcn_fence(__ATOMIC_ACQUIRE, "agent");
;             xb_add(&bar[XB_XGEN(x)], 1u);
;             asm volatile("s_waitcnt vmcnt(0)" ::: "memory");
;         } else {
;             XB_SPIN(xb_ld(&bar[XB_XGEN(x)]) == gen, bar);
.LBB0_538:
	s_lshl_b32 s0, s3, 8
	s_add_u32 s22, s36, s0
	s_addc_u32 s3, s37, 0
	v_mov_b32_e32 v1, s22
	v_add_co_u32_e32 v4, vcc, 0x1000, v1
	v_mov_b32_e32 v1, s3
	s_nop 0
	v_addc_co_u32_e32 v5, vcc, 0, v1, vcc
	v_mov_b32_e32 v1, 1
	global_atomic_add v1, v[4:5], v1, off offset:1024 sc0
	v_cvt_f32_u32_e32 v3, v2
	v_sub_u32_e32 v4, 0, v2
	v_rcp_iflag_f32_e32 v3, v3
	s_nop 0
	v_mul_f32_e32 v3, 0x4f7ffffe, v3
	v_cvt_u32_f32_e32 v3, v3
	v_mul_lo_u32 v4, v4, v3
	v_mul_hi_u32 v4, v3, v4
	v_add_u32_e32 v3, v3, v4
	s_waitcnt vmcnt(0) lgkmcnt(0)
	v_mul_hi_u32 v3, v1, v3
	v_mul_lo_u32 v5, v3, v2
	v_add_u32_e32 v4, 1, v1
	v_sub_u32_e32 v1, v1, v5
	v_add_u32_e32 v6, 1, v3
	v_cmp_ge_u32_e32 vcc, v1, v2
	v_sub_u32_e32 v5, v1, v2
	s_nop 0
	v_cndmask_b32_e32 v3, v3, v6, vcc
	v_cndmask_b32_e32 v1, v1, v5, vcc
	v_add_u32_e32 v5, 1, v3
	v_cmp_ge_u32_e32 vcc, v1, v2
	s_nop 1
	v_cndmask_b32_e32 v1, v3, v5, vcc
	v_mad_u64_u32 v[2:3], s[0:1], v2, v1, v[2:3]
	v_cmp_ne_u32_e32 vcc, v4, v2
	s_and_saveexec_b64 s[0:1], vcc
	s_xor_b64 s[0:1], exec, s[0:1]
	s_cbranch_execz .LBB0_551
	v_mov_b32_e32 v0, s22
	v_add_co_u32_e32 v2, vcc, 0x2000, v0
	v_mov_b32_e32 v0, s3
	s_nop 0
	v_addc_co_u32_e32 v3, vcc, 0, v0, vcc
	global_load_dword v0, v[2:3], off offset:1024 sc1
	s_add_u32 s6, s22, 0x2400
	s_addc_u32 s7, s3, 0
	s_waitcnt vmcnt(0) lgkmcnt(0)
	v_cmp_eq_u32_e32 vcc, v0, v1
	s_and_saveexec_b64 s[4:5], vcc
	s_cbranch_execz .LBB0_550
	s_mov_b32 s23, 1
	s_mov_b64 s[8:9], 0
	s_branch .LBB0_542

.LBB0_542:
	s_and_b32 s16, s23, 0xff
	s_mov_b64 s[14:15], -1
	s_cmp_lg_u32 s16, 0
	s_mov_b64 s[16:17], -1
	s_sleep 1
	s_cbranch_scc1 .LBB0_546
	v_mov_b64_e32 v[2:3], s[36:37]
	global_load_dword v0, v[2:3], off offset:512 sc1
	s_mov_b64 s[16:17], 0
	s_mov_b64 s[18:19], -1
	s_waitcnt vmcnt(0) lgkmcnt(0)
	v_cmp_eq_u32_e32 vcc, 0, v0
	s_and_saveexec_b64 s[20:21], vcc
	s_cmp_lt_u32 s23, 0x400001
	s_cselect_b64 s[16:17], -1, 0
	s_xor_b64 s[18:19], exec, -1
	s_and_b64 s[16:17], s[16:17], exec
	s_or_b64 exec, exec, s[20:21]

.LBB0_548:
	s_or_b64 exec, exec, s[8:9]
	s_xor_b64 s[6:7], s[10:11], -1
	s_and_saveexec_b64 s[8:9], s[6:7]
	s_xor_b64 s[8:9], exec, s[8:9]
	s_cbranch_execz .LBB0_550
	v_mov_b32_e32 v2, 1
	v_mov_b64_e32 v[0:1], s[36:37]
	global_atomic_add v[0:1], v2, off offset:512

; __device__ __forceinline__ unsigned xb_ld(unsigned* p)              { return __hip_atomic_load(p, __ATOMIC_RELAXED, __HIP_MEMORY_SCOPE_AGENT); }
; __device__ __forceinline__ unsigned xb_add(unsigned* p, unsigned v) { return __hip_atomic_fetch_add(p, v, __ATOMIC_RELAXED, __HIP_MEMORY_SCOPE_AGENT); }
; #define XB_SPIN(cond, bar) do { unsigned _sp = 0; while (cond) { __builtin_amdgcn_s_sleep(1); \
;     if ((++_sp & 255u) == 0u) { if (xb_ld(&(bar)[XB_TMO])) break; if (_sp > XB_SPIN_CAP) { atomicAdd(&(bar)[XB_TMO], 1u); break; } } } } while (0)
; __device__ __forceinline__ void xcd_barrier(unsigned* bar, volatile LAS unsigned* st, bool lead) {
;     ...
;         if (old + 1u == (gen + 1u) * nloc) {
;             __builtin_amdgcn_fence(__ATOMIC_RELEASE, "agent");
;             asm volatile("s_waitcnt vmcnt(0)" ::: "memory");
;             const unsigned og = xb_add(&bar[XB_TOP], 1u);
;             const unsigned tg = og / nx;
;             if (og + 1u == (tg + 1u) * nx) xb_add(&bar[XB_TOPGEN], 1u);
;             else XB_SPIN(xb_ld(&bar[XB_TOPGEN]) == tg, bar);
.LBB0_551:
	s_andn2_saveexec_b64 s[0:1], s[0:1]
	s_cbranch_execz .LBB0_567
	v_mov_b32_e32 v1, s36
	v_add_co_u32_e32 v2, vcc, 0x3000, v1
	v_mov_b32_e32 v1, s37
	buffer_wbl2 sc1
	s_waitcnt vmcnt(0)
	v_addc_co_u32_e32 v3, vcc, 0, v1, vcc
	v_mov_b32_e32 v1, 1
	global_atomic_add v1, v[2:3], v1, off offset:1024 sc0
	v_cvt_f32_u32_e32 v2, v0
	v_sub_u32_e32 v3, 0, v0
	s_add_u32 s0, s36, 0x3500
	s_addc_u32 s1, s37, 0
	v_rcp_iflag_f32_e32 v2, v2
	s_mov_b64 s[6:7], -1
	v_mul_f32_e32 v2, 0x4f7ffffe, v2
	v_cvt_u32_f32_e32 v2, v2
	v_mul_lo_u32 v3, v3, v2
	v_mul_hi_u32 v3, v2, v3
	v_add_u32_e32 v2, v2, v3
	s_waitcnt vmcnt(0) lgkmcnt(0)
	v_mul_hi_u32 v2, v1, v2
	v_mul_lo_u32 v4, v2, v0
	v_add_u32_e32 v3, 1, v1
	v_sub_u32_e32 v1, v1, v4
	v_add_u32_e32 v5, 1, v2
	v_cmp_ge_u32_e32 vcc, v1, v0
	v_sub_u32_e32 v4, v1, v0
	s_nop 0
	v_cndmask_b32_e32 v2, v2, v5, vcc
	v_cndmask_b32_e32 v1, v1, v4, vcc
	v_add_u32_e32 v4, 1, v2
	v_cmp_ge_u32_e32 vcc, v1, v0
	s_nop 1
	v_cndmask_b32_e32 v2, v2, v4, vcc
	v_mad_u64_u32 v[0:1], s[4:5], v0, v2, v[0:1]
	v_cmp_ne_u32_e32 vcc, v3, v0
	v_mov_b64_e32 v[0:1], s[0:1]
	s_and_saveexec_b64 s[4:5], vcc
	s_cbranch_execz .LBB0_564
	v_mov_b64_e32 v[0:1], s[0:1]
	global_load_dword v0, v[0:1], off sc1
	s_mov_b64 s[10:11], 0
	s_waitcnt vmcnt(0) lgkmcnt(0)
	v_cmp_eq_u32_e32 vcc, v0, v2
	s_and_saveexec_b64 s[8:9], vcc
	s_cbranch_execz .LBB0_563
	s_add_u32 s6, s36, 0x200
	s_addc_u32 s7, s37, 0
	s_mov_b32 s23, 1
	s_branch .LBB0_556

; __device__ __forceinline__ float rstd_from_ssq(const unsigned long long* ssq, int row) {
;     return 1.0f / sqrtf((float)ssq[row] * (1.0f / 16777216.0f) * (1.0f / 2048.0f) + 1e-6f);
; }
;     __device__ __forceinline__ void operator()(const f32x4 (&acc)[2][2][4][2], const Unit& u, int wr, int wc, int fr_, int fq_) const {
;     ...
;         const int row0 = u.pm * BM + wr * 64 + fr, t = u.pn >> 2;
;         float rsv[8];
; #pragma unroll
;         for (int i = 0; i < 8; ++i) rsv[i] = rstd_from_ssq(ssq, row0 + (i >> 2) * HALF + (i & 3) * 16);
;         asm volatile("" ::: "memory");
.LBB0_591:
	s_lshl_b32 s45, s4, 8
	v_mbcnt_lo_u32_b32 v166, -1, 0
	v_mbcnt_hi_u32_b32 v166, -1, v166
	s_add_i32 s45, s45, s66
	v_and_b32_e32 v130, 15, v166
	v_or_b32_e32 v144, s45, v130
	v_ashrrev_i32_e32 v145, 31, v144
	v_lshl_add_u64 v[196:197], v[144:145], 3, s[24:25]
	global_load_dwordx2 v[132:133], v[196:197], off
	global_load_dwordx2 v[134:135], v[196:197], off offset:128
	global_load_dwordx2 v[136:137], v[196:197], off offset:256
	global_load_dwordx2 v[138:139], v[196:197], off offset:384
	global_load_dwordx2 v[128:129], v[196:197], off offset:1024
	v_ashrrev_i32_e32 v167, 4, v166
	v_lshlrev_b32_e32 v162, 3, v167
	v_lshlrev_b64 v[164:165], 11, v[144:145]
	v_ashrrev_i32_e32 v163, 31, v162
	s_waitcnt vmcnt(0) lgkmcnt(0)
	v_ffbh_u32_e32 v131, v133
	v_ffbh_u32_e32 v140, v135
	v_min_u32_e32 v131, 32, v131
	v_ffbh_u32_e32 v141, v137
	v_min_u32_e32 v140, 32, v140
	v_lshlrev_b64 v[132:133], v131, v[132:133]
	v_min_u32_e32 v141, 32, v141
	v_lshlrev_b64 v[134:135], v140, v[134:135]
	v_min_u32_e32 v132, 1, v132
	v_lshlrev_b64 v[136:137], v141, v[136:137]
	v_min_u32_e32 v134, 1, v134
	v_or_b32_e32 v132, v133, v132
	v_min_u32_e32 v136, 1, v136
	v_or_b32_e32 v133, v135, v134
	v_cvt_f32_u32_e32 v132, v132
	v_or_b32_e32 v134, v137, v136
	v_cvt_f32_u32_e32 v133, v133
	v_cvt_f32_u32_e32 v134, v134
	v_sub_u32_e32 v131, 32, v131
	v_sub_u32_e32 v140, 32, v140
	v_ldexp_f32 v131, v132, v131
	v_sub_u32_e32 v135, 32, v141
	v_ldexp_f32 v132, v133, v140
	v_mul_f32_e32 v131, 0x33800000, v131
	v_ldexp_f32 v133, v134, v135
	v_mul_f32_e32 v132, 0x33800000, v132
	v_fmamk_f32 v131, v131, 0x3a000000, v240
	v_mul_f32_e32 v133, 0x33800000, v133
	v_fmamk_f32 v132, v132, 0x3a000000, v240
	v_mul_f32_e32 v134, 0x4f800000, v131
	v_cmp_gt_f32_e32 vcc, s83, v131
	v_fmamk_f32 v133, v133, 0x3a000000, v240
	v_mul_f32_e32 v135, 0x4f800000, v132
	v_cndmask_b32_e32 v131, v131, v134, vcc
	v_cmp_gt_f32_e64 s[4:5], s83, v132
	v_mul_f32_e32 v136, 0x4f800000, v133
	v_sqrt_f32_e32 v134, v131
	v_cndmask_b32_e64 v132, v132, v135, s[4:5]
	v_cmp_gt_f32_e64 s[6:7], s83, v133
	v_sqrt_f32_e32 v135, v132
	v_add_u32_e32 v137, -1, v134
	v_cndmask_b32_e64 v133, v133, v136, s[6:7]
	v_sqrt_f32_e32 v136, v133
	v_add_u32_e32 v141, -1, v135
	v_fma_f32 v148, -v137, v134, v131
	v_add_u32_e32 v140, 1, v134
	v_add_u32_e32 v146, -1, v136
	v_fma_f32 v150, -v141, v135, v132
	v_cmp_ge_f32_e64 s[8:9], 0, v148
	v_add_u32_e32 v143, 1, v135
	v_fma_f32 v149, -v140, v134, v131
	v_fma_f32 v152, -v146, v136, v133
	v_cndmask_b32_e64 v134, v134, v137, s[8:9]
	v_cmp_ge_f32_e64 s[8:9], 0, v150
	v_add_u32_e32 v147, 1, v136
	v_fma_f32 v151, -v143, v135, v132
	v_cndmask_b32_e64 v135, v135, v141, s[8:9]
	v_cmp_ge_f32_e64 s[8:9], 0, v152
	v_fma_f32 v153, -v147, v136, v133
	v_ffbh_u32_e32 v142, v139
	v_cndmask_b32_e64 v136, v136, v146, s[8:9]
	v_cmp_lt_f32_e64 s[8:9], 0, v149
	s_nop 1
	v_cndmask_b32_e64 v134, v134, v140, s[8:9]
	v_cmp_lt_f32_e64 s[8:9], 0, v151
	v_mul_f32_e32 v137, 0x37800000, v134
	v_cndmask_b32_e32 v134, v134, v137, vcc
	v_cndmask_b32_e64 v135, v135, v143, s[8:9]
	v_cmp_lt_f32_e64 s[8:9], 0, v153
	v_mul_f32_e32 v140, 0x37800000, v135
	v_cmp_class_f32_e32 vcc, v131, v241
	v_cndmask_b32_e64 v136, v136, v147, s[8:9]
	v_mul_f32_e32 v141, 0x37800000, v136
	v_cndmask_b32_e64 v135, v135, v140, s[4:5]
	v_cndmask_b32_e32 v131, v134, v131, vcc
	v_cmp_class_f32_e32 vcc, v132, v241
	v_cndmask_b32_e64 v136, v136, v141, s[6:7]
	s_nop 0
	v_cndmask_b32_e32 v132, v135, v132, vcc
	v_cmp_class_f32_e32 vcc, v133, v241
	v_div_scale_f32 v135, s[4:5], v132, v132, 1.0
	s_nop 0
	v_cndmask_b32_e32 v136, v136, v133, vcc
	v_div_scale_f32 v133, s[4:5], v131, v131, 1.0
	v_rcp_f32_e32 v140, v133
	v_div_scale_f32 v137, s[4:5], v136, v136, 1.0
	v_rcp_f32_e32 v141, v135
	v_rcp_f32_e32 v143, v137
	v_fma_f32 v147, -v133, v140, 1.0
	v_div_scale_f32 v134, vcc, 1.0, v131, 1.0
	v_fma_f32 v148, -v135, v141, 1.0
	v_fmac_f32_e32 v140, v147, v140
	v_div_scale_f32 v146, s[4:5], 1.0, v132, 1.0
	v_fma_f32 v149, -v137, v143, 1.0
	v_fmac_f32_e32 v141, v148, v141
	v_mul_f32_e32 v147, v134, v140
	v_fmac_f32_e32 v143, v149, v143
	v_mul_f32_e32 v148, v146, v141
	v_fma_f32 v149, -v133, v147, v134
	v_fma_f32 v150, -v135, v148, v146
	v_fmac_f32_e32 v147, v149, v140
	v_fmac_f32_e32 v148, v150, v141
	v_fma_f32 v133, -v133, v147, v134
	v_fma_f32 v134, -v135, v148, v146
	v_div_fmas_f32 v133, v133, v140, v147
	s_mov_b64 vcc, s[4:5]
	v_div_fixup_f32 v160, v133, v131, 1.0
	v_div_fmas_f32 v131, v134, v141, v148
	global_load_dwordx2 v[134:135], v[196:197], off offset:1152
	v_div_fixup_f32 v208, v131, v132, 1.0
	v_min_u32_e32 v131, 32, v142
	v_lshlrev_b64 v[132:133], v131, v[138:139]
	v_min_u32_e32 v132, 1, v132
	v_or_b32_e32 v132, v133, v132
	v_cvt_f32_u32_e32 v132, v132
	v_sub_u32_e32 v131, 32, v131
	v_div_scale_f32 v133, vcc, 1.0, v136, 1.0
	v_ldexp_f32 v131, v132, v131
	v_mul_f32_e32 v131, 0x33800000, v131
	v_fmamk_f32 v131, v131, 0x3a000000, v240
	v_mul_f32_e32 v132, 0x4f800000, v131
	v_cmp_gt_f32_e64 s[4:5], s83, v131
	v_mul_f32_e32 v138, v133, v143
	v_fma_f32 v139, -v137, v138, v133
	v_cndmask_b32_e64 v131, v131, v132, s[4:5]
	v_sqrt_f32_e32 v132, v131
	v_fmac_f32_e32 v138, v139, v143
	v_fma_f32 v133, -v137, v138, v133
	v_add_u32_e32 v137, -1, v132
	v_fma_f32 v139, -v137, v132, v131
	v_cmp_ge_f32_e64 s[6:7], 0, v139
	v_add_u32_e32 v139, 1, v132
	s_nop 0
	v_cndmask_b32_e64 v137, v132, v137, s[6:7]
	v_fma_f32 v132, -v139, v132, v131
	v_cmp_lt_f32_e64 s[6:7], 0, v132
	s_nop 1
	v_cndmask_b32_e64 v132, v137, v139, s[6:7]
	v_mul_f32_e32 v137, 0x37800000, v132
	v_cndmask_b32_e64 v132, v132, v137, s[4:5]
	v_cmp_class_f32_e64 s[4:5], v131, v241
	s_nop 1
; __device__ __forceinline__ float rstd_from_ssq(const unsigned long long* ssq, int row) {
;     return 1.0f / sqrtf((float)ssq[row] * (1.0f / 16777216.0f) * (1.0f / 2048.0f) + 1e-6f);
; }
;     __device__ __forceinline__ void operator()(const f32x4 (&acc)[2][2][4][2], const Unit& u, int wr, int wc, int fr_, int fq_) const {
;     ...
;         for (int i = 0; i < 8; ++i) rsv[i] = rstd_from_ssq(ssq, row0 + (i >> 2) * HALF + (i & 3) * 16);
;         asm volatile("" ::: "memory");
;         if (t < 2) {
	v_cndmask_b32_e64 v131, v132, v131, s[4:5]
	v_div_scale_f32 v139, s[4:5], v131, v131, 1.0
	v_rcp_f32_e32 v140, v139
	v_div_fmas_f32 v132, v133, v143, v138
	v_div_fixup_f32 v206, v132, v136, 1.0
	v_ffbh_u32_e32 v138, v129
	v_fma_f32 v132, -v139, v140, 1.0
	v_fmac_f32_e32 v140, v132, v140
	global_load_dwordx2 v[132:133], v[196:197], off offset:1280
	global_load_dwordx2 v[136:137], v[196:197], off offset:1408
	v_min_u32_e32 v138, 32, v138
	v_lshlrev_b64 v[128:129], v138, v[128:129]
	v_min_u32_e32 v128, 1, v128
	v_or_b32_e32 v128, v129, v128
	v_cvt_f32_u32_e32 v128, v128
	v_sub_u32_e32 v138, 32, v138
	v_div_scale_f32 v129, vcc, 1.0, v131, 1.0
	v_ldexp_f32 v128, v128, v138
	v_mul_f32_e32 v128, 0x33800000, v128
	v_fmamk_f32 v128, v128, 0x3a000000, v240
	v_mul_f32_e32 v138, 0x4f800000, v128
	v_cmp_gt_f32_e64 s[4:5], s83, v128
	v_mul_f32_e32 v141, v129, v140
	v_fma_f32 v142, -v139, v141, v129
	v_cndmask_b32_e64 v128, v128, v138, s[4:5]
	v_sqrt_f32_e32 v138, v128
	v_fmac_f32_e32 v141, v142, v140
	v_fma_f32 v129, -v139, v141, v129
	v_add_u32_e32 v139, -1, v138
	v_fma_f32 v142, -v139, v138, v128
	v_cmp_ge_f32_e64 s[6:7], 0, v142
	v_add_u32_e32 v142, 1, v138
	s_nop 0
	v_cndmask_b32_e64 v139, v138, v139, s[6:7]
	v_fma_f32 v138, -v142, v138, v128
	v_cmp_lt_f32_e64 s[6:7], 0, v138
	s_nop 1
	v_cndmask_b32_e64 v138, v139, v142, s[6:7]
	v_mul_f32_e32 v139, 0x37800000, v138
	v_cndmask_b32_e64 v138, v138, v139, s[4:5]
	v_cmp_class_f32_e64 s[4:5], v128, v241
	s_nop 1
	v_cndmask_b32_e64 v138, v138, v128, s[4:5]
	v_div_scale_f32 v139, s[4:5], v138, v138, 1.0
	v_rcp_f32_e32 v142, v139
	v_div_fmas_f32 v128, v129, v140, v141
	v_div_fixup_f32 v194, v128, v131, 1.0
	v_fma_f32 v128, -v139, v142, 1.0
	v_fmac_f32_e32 v142, v128, v142
	s_waitcnt vmcnt(0) lgkmcnt(0)
	v_ffbh_u32_e32 v128, v135
	v_min_u32_e32 v131, 32, v128
	v_lshlrev_b64 v[128:129], v131, v[134:135]
	v_min_u32_e32 v128, 1, v128
	v_or_b32_e32 v128, v129, v128
	v_cvt_f32_u32_e32 v128, v128
	v_sub_u32_e32 v131, 32, v131
	v_div_scale_f32 v129, vcc, 1.0, v138, 1.0
	v_ldexp_f32 v128, v128, v131
	v_mul_f32_e32 v128, 0x33800000, v128
	v_fmamk_f32 v128, v128, 0x3a000000, v240
	v_mul_f32_e32 v131, 0x4f800000, v128
	v_cmp_gt_f32_e64 s[4:5], s83, v128
	v_mul_f32_e32 v134, v129, v142
	v_fma_f32 v135, -v139, v134, v129
	v_cndmask_b32_e64 v128, v128, v131, s[4:5]
	v_sqrt_f32_e32 v131, v128
	v_fmac_f32_e32 v134, v135, v142
	v_fma_f32 v129, -v139, v134, v129
	v_add_u32_e32 v135, -1, v131
	v_fma_f32 v139, -v135, v131, v128
	v_cmp_ge_f32_e64 s[6:7], 0, v139
	v_add_u32_e32 v139, 1, v131
	s_nop 0
	v_cndmask_b32_e64 v135, v131, v135, s[6:7]
	v_fma_f32 v131, -v139, v131, v128
	v_cmp_lt_f32_e64 s[6:7], 0, v131
	s_nop 1
	v_cndmask_b32_e64 v131, v135, v139, s[6:7]
	v_mul_f32_e32 v135, 0x37800000, v131
	v_cndmask_b32_e64 v131, v131, v135, s[4:5]
	v_cmp_class_f32_e64 s[4:5], v128, v241
	s_nop 1
	v_cndmask_b32_e64 v131, v131, v128, s[4:5]
	v_div_scale_f32 v135, s[4:5], v131, v131, 1.0
	v_rcp_f32_e32 v139, v135
	v_div_fmas_f32 v128, v129, v142, v134
	v_div_fixup_f32 v192, v128, v138, 1.0
	v_fma_f32 v128, -v135, v139, 1.0
	v_fmac_f32_e32 v139, v128, v139
	v_ffbh_u32_e32 v128, v133
	v_min_u32_e32 v134, 32, v128
	v_lshlrev_b64 v[128:129], v134, v[132:133]
	v_min_u32_e32 v128, 1, v128
	v_or_b32_e32 v128, v129, v128
	v_cvt_f32_u32_e32 v128, v128
	v_sub_u32_e32 v133, 32, v134
	v_div_scale_f32 v129, vcc, 1.0, v131, 1.0
	v_ldexp_f32 v128, v128, v133
	v_mul_f32_e32 v128, 0x33800000, v128
	v_fmamk_f32 v128, v128, 0x3a000000, v240
	v_mul_f32_e32 v133, 0x4f800000, v128
	v_cmp_gt_f32_e64 s[4:5], s83, v128
	v_mul_f32_e32 v132, v129, v139
	v_fma_f32 v134, -v135, v132, v129
	v_cndmask_b32_e64 v128, v128, v133, s[4:5]
	v_sqrt_f32_e32 v133, v128
	v_fmac_f32_e32 v132, v134, v139
	v_fma_f32 v129, -v135, v132, v129
	v_add_u32_e32 v134, -1, v133
	v_fma_f32 v135, -v134, v133, v128
	v_cmp_ge_f32_e64 s[6:7], 0, v135
	v_add_u32_e32 v135, 1, v133
	s_nop 0
	v_cndmask_b32_e64 v134, v133, v134, s[6:7]
	v_fma_f32 v133, -v135, v133, v128
	v_cmp_lt_f32_e64 s[6:7], 0, v133
	s_nop 1
	v_cndmask_b32_e64 v133, v134, v135, s[6:7]
	v_mul_f32_e32 v134, 0x37800000, v133
	v_cndmask_b32_e64 v133, v133, v134, s[4:5]
	v_cmp_class_f32_e64 s[4:5], v128, v241
	s_nop 1
	v_cndmask_b32_e64 v133, v133, v128, s[4:5]
	v_div_scale_f32 v134, s[4:5], v133, v133, 1.0
	v_rcp_f32_e32 v135, v134
	v_div_fmas_f32 v128, v129, v139, v132
	v_div_fixup_f32 v190, v128, v131, 1.0
	v_fma_f32 v128, -v134, v135, 1.0
	v_fmac_f32_e32 v135, v128, v135
	v_ffbh_u32_e32 v128, v137
	v_min_u32_e32 v131, 32, v128
	v_lshlrev_b64 v[128:129], v131, v[136:137]
	v_min_u32_e32 v128, 1, v128
	v_or_b32_e32 v128, v129, v128
	v_cvt_f32_u32_e32 v128, v128
	v_sub_u32_e32 v131, 32, v131
	v_div_scale_f32 v129, vcc, 1.0, v133, 1.0
	v_ldexp_f32 v128, v128, v131
	v_mul_f32_e32 v128, 0x33800000, v128
	v_fmamk_f32 v128, v128, 0x3a000000, v240
	v_mul_f32_e32 v131, 0x4f800000, v128
	v_cmp_gt_f32_e64 s[4:5], s83, v128
	v_mul_f32_e32 v132, v129, v135
	v_fma_f32 v136, -v134, v132, v129
	v_cndmask_b32_e64 v128, v128, v131, s[4:5]
	v_sqrt_f32_e32 v131, v128
	v_fmac_f32_e32 v132, v136, v135
	v_fma_f32 v129, -v134, v132, v129
	v_div_fmas_f32 v129, v129, v135, v132
	v_add_u32_e32 v134, -1, v131
	v_fma_f32 v136, -v134, v131, v128
	v_cmp_ge_f32_e64 s[6:7], 0, v136
	v_add_u32_e32 v136, 1, v131
	v_div_fixup_f32 v188, v129, v133, 1.0
	v_cndmask_b32_e64 v134, v131, v134, s[6:7]
	v_fma_f32 v131, -v136, v131, v128
	v_cmp_lt_f32_e64 s[6:7], 0, v131
	s_nop 1
	v_cndmask_b32_e64 v131, v134, v136, s[6:7]
	v_mul_f32_e32 v134, 0x37800000, v131
	v_cndmask_b32_e64 v131, v131, v134, s[4:5]
	v_cmp_class_f32_e64 s[4:5], v128, v241
	s_ashr_i32 s6, s16, 2
	s_cmp_gt_i32 s6, 1
	v_cndmask_b32_e64 v128, v131, v128, s[4:5]
	v_div_scale_f32 v131, s[4:5], v128, v128, 1.0
	v_rcp_f32_e32 v134, v131
	s_mov_b64 s[4:5], -1
	v_fma_f32 v129, -v131, v134, 1.0
	v_fmac_f32_e32 v134, v129, v134
	v_div_scale_f32 v129, vcc, 1.0, v128, 1.0
	v_mul_f32_e32 v132, v129, v134
	v_fma_f32 v133, -v131, v132, v129
	v_fmac_f32_e32 v132, v133, v134
	v_fma_f32 v129, -v131, v132, v129
	v_div_fmas_f32 v129, v129, v134, v132
	v_div_fixup_f32 v186, v129, v128, 1.0
	s_cbranch_scc0 .LBB0_658
; __device__ __forceinline__ u32x4 pack8(const f32x4& v0, const f32x4& v1) { u32x4 w; w.x = cvt_pk_bf16(v0[0], v0[1]); w.y = cvt_pk_bf16(v0[2], v0[3]); w.z = cvt_pk_bf16(v1[0], v1[1]); w.w = cvt_pk_bf16(v1[2], v1[3]); return w; }
;     __device__ __forceinline__ void operator()(const f32x4 (&acc)[2][2][4][2], const Unit& u, int wr, int wc, int fr_, int fq_) const {
;     ...
;         const int col0 = (u.pn & 3) * BM + wc * 32 + 8 * fq;
;         bf16_t* base = Q + (size_t)2 * qkv_stride;
;         const float* bp2 = bv + u.pn * BM + wc * 32 + 8 * fq;
; #pragma unroll
;         for (int ai = 0; ai < 2; ++ai)
; #pragma unroll
;             for (int m = 0; m < 4; ++m) { const int row = row0 + ai * HALF + m * 16;
; #pragma unroll
;                 for (int bj = 0; bj < 2; ++bj) { const int col = col0 + bj * HALF; const float rs = rsv[ai * 4 + m];
;                     const u32x4 w = pack8(acc[ai][bj][m][0] * rs + *(const f32x4*)(bp2 + bj * HALF), acc[ai][bj][m][1] * rs + *(const f32x4*)(bp2 + bj * HALF + 4));
;                     if (t < 3) *(u32x4*)(base + (size_t)row * 1024 + col) = w;
;                     else *(u32x4*)(U + ((size_t)((row >> 4) * 64 + (col >> 4)) * 384 + (row & 15) * 16 + (col & 15))) = w; } }
	s_lshl_b32 s4, s16, 8
	s_and_b32 s5, s4, 0x300
	s_or_b32 s7, s5, s67
	s_ashr_i32 s5, s4, 31
	s_lshl_b64 s[4:5], s[4:5], 2
	s_add_u32 s4, s78, s4
	s_addc_u32 s5, s79, s5
	v_lshl_add_u64 v[136:137], v[162:163], 2, s[4:5]
	global_load_dwordx4 v[146:149], v[136:137], off
	global_load_dwordx4 v[150:153], v[136:137], off offset:16
	s_cmp_lg_u32 s6, 2
	v_lshlrev_b32_e32 v128, 4, v130
	v_and_b32_e32 v129, 8, v162
	v_add_u32_e32 v132, s7, v162
	s_cselect_b64 s[8:9], -1, 0
	s_mov_b64 s[4:5], -1
	v_lshlrev_b32_e32 v176, 1, v128
	v_lshlrev_b32_e32 v134, 1, v129
	v_ashrrev_i32_e32 v140, 4, v132
	s_lshl_b32 s7, s45, 2
	s_and_b64 vcc, exec, s[8:9]
	s_waitcnt vmcnt(0) lgkmcnt(0)
	v_pk_fma_f32 v[130:131], v[126:127], v[160:161], v[148:149] op_sel_hi:[1,0,1]
	v_pk_fma_f32 v[128:129], v[124:125], v[160:161], v[146:147] op_sel_hi:[1,0,1]
	v_pk_fma_f32 v[138:139], v[122:123], v[160:161], v[152:153] op_sel_hi:[1,0,1]
	v_pk_fma_f32 v[142:143], v[120:121], v[160:161], v[150:151] op_sel_hi:[1,0,1]
	v_cvt_pk_bf16_f32 v128, v128, v129
	v_cvt_pk_bf16_f32 v129, v130, v131
	s_nop 0
	v_cvt_pk_bf16_f32 v130, v142, v143
	v_cvt_pk_bf16_f32 v131, v138, v139
	s_cbranch_vccz .LBB0_594
	v_add_u32_e32 v133, s7, v140
	v_mov_b64_e32 v[138:139], s[20:21]
	v_mad_i64_i32 v[138:139], s[4:5], v133, s84, v[138:139]
	v_lshl_add_u64 v[138:139], v[138:139], 0, v[176:177]
	v_mov_b32_e32 v135, v177
	v_lshl_add_u64 v[138:139], v[138:139], 0, v[134:135]
	global_store_dwordx4 v[138:139], v[128:131], off
	s_mov_b64 s[4:5], 0
.LBB0_594:
	v_lshl_add_u64 v[138:139], s[30:31], 0, v[164:165]
	s_andn2_b64 vcc, exec, s[4:5]
	v_ashrrev_i32_e32 v133, 31, v132
	s_cbranch_vccnz .LBB0_596
	v_lshl_add_u64 v[142:143], v[132:133], 1, v[138:139]
	global_store_dwordx4 v[142:143], v[128:131], off
.LBB0_596:
	global_load_dwordx4 v[128:131], v[136:137], off offset:512
	s_nop 0
	global_load_dwordx4 v[146:149], v[136:137], off offset:528
	v_mov_b32_e32 v161, v160
	v_add_u32_e32 v135, 0x80, v132
	v_mov_b32_e32 v142, v160
	v_mov_b32_e32 v143, v160
	v_cndmask_b32_e64 v141, 0, 1, s[8:9]
	s_mov_b64 s[52:53], -1
	v_cmp_ne_u32_e64 s[4:5], 1, v141
	s_andn2_b64 vcc, exec, s[8:9]
	v_ashrrev_i32_e32 v141, 4, v135
	s_waitcnt vmcnt(0) lgkmcnt(0)
	v_pk_fma_f32 v[130:131], v[118:119], v[142:143], v[130:131]
	v_pk_fma_f32 v[128:129], v[116:117], v[160:161], v[128:129]
	v_pk_fma_f32 v[142:143], v[114:115], v[142:143], v[148:149]
	v_pk_fma_f32 v[146:147], v[112:113], v[160:161], v[146:147]
	v_cvt_pk_bf16_f32 v128, v128, v129
	v_cvt_pk_bf16_f32 v129, v130, v131
	s_nop 0
	v_cvt_pk_bf16_f32 v130, v146, v147
	v_cvt_pk_bf16_f32 v131, v142, v143
	s_cbranch_vccnz .LBB0_598
	v_add_u32_e32 v135, s7, v141
	v_mov_b64_e32 v[142:143], s[20:21]
	v_mad_i64_i32 v[142:143], s[8:9], v135, s84, v[142:143]
	v_lshl_add_u64 v[142:143], v[142:143], 0, v[176:177]
	v_mov_b32_e32 v135, v177
	v_lshl_add_u64 v[142:143], v[142:143], 0, v[134:135]
	s_mov_b64 s[52:53], 0
	global_store_dwordx4 v[142:143], v[128:131], off
.LBB0_598:
	s_andn2_b64 vcc, exec, s[52:53]
	s_cbranch_vccnz .LBB0_600
	v_lshl_add_u64 v[138:139], v[132:133], 1, v[138:139]
	global_store_dwordx4 v[138:139], v[128:131], off offset:256
.LBB0_600:
	global_load_dwordx4 v[128:131], v[136:137], off
	s_nop 0
	global_load_dwordx4 v[146:149], v[136:137], off offset:16
	v_or_b32_e32 v138, 16, v144
	v_lshlrev_b32_e32 v135, 2, v138
	s_and_b64 vcc, exec, s[4:5]
	v_and_b32_e32 v142, 0xffffff40, v135
	s_mov_b64 s[8:9], -1
	s_waitcnt vmcnt(0) lgkmcnt(0)
	v_pk_fma_f32 v[130:131], v[110:111], v[208:209], v[130:131] op_sel_hi:[1,0,1]
	v_pk_fma_f32 v[128:129], v[108:109], v[208:209], v[128:129] op_sel_hi:[1,0,1]
	v_pk_fma_f32 v[148:149], v[106:107], v[208:209], v[148:149] op_sel_hi:[1,0,1]
	v_pk_fma_f32 v[146:147], v[104:105], v[208:209], v[146:147] op_sel_hi:[1,0,1]
	v_cvt_pk_bf16_f32 v128, v128, v129
	v_cvt_pk_bf16_f32 v129, v130, v131
	s_nop 0
	v_cvt_pk_bf16_f32 v130, v146, v147
	v_cvt_pk_bf16_f32 v131, v148, v149
	s_cbranch_vccnz .LBB0_602
	v_add_u32_e32 v135, v142, v140
	v_mov_b64_e32 v[146:147], s[20:21]
	v_mad_i64_i32 v[146:147], s[8:9], v135, s84, v[146:147]
	v_lshl_add_u64 v[146:147], v[146:147], 0, v[176:177]
	v_mov_b32_e32 v135, v177
	v_lshl_add_u64 v[146:147], v[146:147], 0, v[134:135]
	s_mov_b64 s[8:9], 0
	global_store_dwordx4 v[146:147], v[128:131], off
.LBB0_602:
	v_ashrrev_i32_e32 v139, 31, v138
	v_lshlrev_b64 v[138:139], 11, v[138:139]
	s_andn2_b64 vcc, exec, s[8:9]
	v_lshl_add_u64 v[138:139], s[30:31], 0, v[138:139]
	s_cbranch_vccnz .LBB0_604
	v_lshl_add_u64 v[146:147], v[132:133], 1, v[138:139]
	global_store_dwordx4 v[146:147], v[128:131], off
.LBB0_604:
	global_load_dwordx4 v[128:131], v[136:137], off offset:512
	s_nop 0
	global_load_dwordx4 v[146:149], v[136:137], off offset:528
	v_mov_b32_e32 v209, v208
	v_mov_b32_e32 v150, v208
	v_mov_b32_e32 v151, v208
	s_and_b64 vcc, exec, s[4:5]
	s_mov_b64 s[8:9], -1
	s_waitcnt vmcnt(0) lgkmcnt(0)
	v_pk_fma_f32 v[130:131], v[102:103], v[150:151], v[130:131]
	v_pk_fma_f32 v[128:129], v[100:101], v[208:209], v[128:129]
	v_pk_fma_f32 v[148:149], v[98:99], v[150:151], v[148:149]
	v_pk_fma_f32 v[146:147], v[96:97], v[208:209], v[146:147]
	v_cvt_pk_bf16_f32 v128, v128, v129
	v_cvt_pk_bf16_f32 v129, v130, v131
	s_nop 0
	v_cvt_pk_bf16_f32 v130, v146, v147
	v_cvt_pk_bf16_f32 v131, v148, v149
	s_cbranch_vccnz .LBB0_606
	v_add_u32_e32 v135, v141, v142
	v_mov_b64_e32 v[142:143], s[20:21]
	v_mad_i64_i32 v[142:143], s[8:9], v135, s84, v[142:143]
	v_lshl_add_u64 v[142:143], v[142:143], 0, v[176:177]
	v_mov_b32_e32 v135, v177
	v_lshl_add_u64 v[142:143], v[142:143], 0, v[134:135]
	s_mov_b64 s[8:9], 0
	global_store_dwordx4 v[142:143], v[128:131], off
.LBB0_606:
	s_andn2_b64 vcc, exec, s[8:9]
	s_cbranch_vccnz .LBB0_608
	v_lshl_add_u64 v[138:139], v[132:133], 1, v[138:139]
	global_store_dwordx4 v[138:139], v[128:131], off offset:256
.LBB0_608:
	global_load_dwordx4 v[128:131], v[136:137], off
	s_nop 0
	global_load_dwordx4 v[146:149], v[136:137], off offset:16
	v_or_b32_e32 v138, 32, v144
	v_lshlrev_b32_e32 v135, 2, v138
	s_and_b64 vcc, exec, s[4:5]
	v_and_b32_e32 v142, 0xffffff80, v135
	s_mov_b64 s[8:9], -1
	s_waitcnt vmcnt(0) lgkmcnt(0)
	v_pk_fma_f32 v[130:131], v[94:95], v[206:207], v[130:131] op_sel_hi:[1,0,1]
	v_pk_fma_f32 v[128:129], v[92:93], v[206:207], v[128:129] op_sel_hi:[1,0,1]
	v_pk_fma_f32 v[148:149], v[90:91], v[206:207], v[148:149] op_sel_hi:[1,0,1]
	v_pk_fma_f32 v[146:147], v[88:89], v[206:207], v[146:147] op_sel_hi:[1,0,1]
	v_cvt_pk_bf16_f32 v128, v128, v129
	v_cvt_pk_bf16_f32 v129, v130, v131
	s_nop 0
	v_cvt_pk_bf16_f32 v130, v146, v147
	v_cvt_pk_bf16_f32 v131, v148, v149
	s_cbranch_vccnz .LBB0_610
	v_add_u32_e32 v135, v142, v140
	v_mov_b64_e32 v[146:147], s[20:21]
	v_mad_i64_i32 v[146:147], s[8:9], v135, s84, v[146:147]
	v_lshl_add_u64 v[146:147], v[146:147], 0, v[176:177]
	v_mov_b32_e32 v135, v177
	v_lshl_add_u64 v[146:147], v[146:147], 0, v[134:135]
	s_mov_b64 s[8:9], 0
	global_store_dwordx4 v[146:147], v[128:131], off

; __device__ __forceinline__ u32x4 pack8(const f32x4& v0, const f32x4& v1) { u32x4 w; w.x = cvt_pk_bf16(v0[0], v0[1]); w.y = cvt_pk_bf16(v0[2], v0[3]); w.z = cvt_pk_bf16(v1[0], v1[1]); w.w = cvt_pk_bf16(v1[2], v1[3]); return w; }
;     __device__ __forceinline__ void operator()(const f32x4 (&acc)[2][2][4][2], const Unit& u, int wr, int wc, int fr_, int fq_) const {
;     ...
;             for (int m = 0; m < 4; ++m) { const int row = row0 + ai * HALF + m * 16;
; #pragma unroll
;                 for (int bj = 0; bj < 2; ++bj) { const int col = col0 + bj * HALF; const float rs = rsv[ai * 4 + m];
;                     const u32x4 w = pack8(acc[ai][bj][m][0] * rs + *(const f32x4*)(bp2 + bj * HALF), acc[ai][bj][m][1] * rs + *(const f32x4*)(bp2 + bj * HALF + 4));
;                     if (t < 3) *(u32x4*)(base + (size_t)row * 1024 + col) = w;
;                     else *(u32x4*)(U + ((size_t)((row >> 4) * 64 + (col >> 4)) * 384 + (row & 15) * 16 + (col & 15))) = w; } }
.LBB0_612:
	global_load_dwordx4 v[128:131], v[136:137], off offset:512
	s_nop 0
	global_load_dwordx4 v[146:149], v[136:137], off offset:528
	v_mov_b32_e32 v207, v206
	v_mov_b32_e32 v150, v206
	v_mov_b32_e32 v151, v206
	s_and_b64 vcc, exec, s[4:5]
	s_mov_b64 s[8:9], -1
	s_waitcnt vmcnt(0) lgkmcnt(0)
	v_pk_fma_f32 v[130:131], v[86:87], v[150:151], v[130:131]
	v_pk_fma_f32 v[128:129], v[84:85], v[206:207], v[128:129]
	v_pk_fma_f32 v[148:149], v[82:83], v[150:151], v[148:149]
	v_pk_fma_f32 v[146:147], v[80:81], v[206:207], v[146:147]
	v_cvt_pk_bf16_f32 v128, v128, v129
	v_cvt_pk_bf16_f32 v129, v130, v131
	s_nop 0
	v_cvt_pk_bf16_f32 v130, v146, v147
	v_cvt_pk_bf16_f32 v131, v148, v149
	s_cbranch_vccnz .LBB0_614
	v_add_u32_e32 v135, v141, v142
	v_mov_b64_e32 v[142:143], s[20:21]
	v_mad_i64_i32 v[142:143], s[8:9], v135, s84, v[142:143]
	v_lshl_add_u64 v[142:143], v[142:143], 0, v[176:177]
	v_mov_b32_e32 v135, v177
	v_lshl_add_u64 v[142:143], v[142:143], 0, v[134:135]
	s_mov_b64 s[8:9], 0
	global_store_dwordx4 v[142:143], v[128:131], off

; __device__ __forceinline__ u32x4 pack8(const f32x4& v0, const f32x4& v1) { u32x4 w; w.x = cvt_pk_bf16(v0[0], v0[1]); w.y = cvt_pk_bf16(v0[2], v0[3]); w.z = cvt_pk_bf16(v1[0], v1[1]); w.w = cvt_pk_bf16(v1[2], v1[3]); return w; }
;     __device__ __forceinline__ void operator()(const f32x4 (&acc)[2][2][4][2], const Unit& u, int wr, int wc, int fr_, int fq_) const {
;     ...
;             for (int m = 0; m < 4; ++m) { const int row = row0 + ai * HALF + m * 16;
; #pragma unroll
;                 for (int bj = 0; bj < 2; ++bj) { const int col = col0 + bj * HALF; const float rs = rsv[ai * 4 + m];
;                     const u32x4 w = pack8(acc[ai][bj][m][0] * rs + *(const f32x4*)(bp2 + bj * HALF), acc[ai][bj][m][1] * rs + *(const f32x4*)(bp2 + bj * HALF + 4));
;                     if (t < 3) *(u32x4*)(base + (size_t)row * 1024 + col) = w;
;                     else *(u32x4*)(U + ((size_t)((row >> 4) * 64 + (col >> 4)) * 384 + (row & 15) * 16 + (col & 15))) = w; } }
.LBB0_616:
	global_load_dwordx4 v[128:131], v[136:137], off
	s_nop 0
	global_load_dwordx4 v[146:149], v[136:137], off offset:16
	v_or_b32_e32 v138, 48, v144
	v_lshlrev_b32_e32 v135, 2, v138
	s_and_b64 vcc, exec, s[4:5]
	v_and_b32_e32 v142, 0xffffffc0, v135
	s_mov_b64 s[8:9], -1
	s_waitcnt vmcnt(0) lgkmcnt(0)
	v_pk_fma_f32 v[130:131], v[78:79], v[194:195], v[130:131] op_sel_hi:[1,0,1]
	v_pk_fma_f32 v[128:129], v[76:77], v[194:195], v[128:129] op_sel_hi:[1,0,1]
	v_pk_fma_f32 v[148:149], v[74:75], v[194:195], v[148:149] op_sel_hi:[1,0,1]
	v_pk_fma_f32 v[146:147], v[72:73], v[194:195], v[146:147] op_sel_hi:[1,0,1]
	v_cvt_pk_bf16_f32 v128, v128, v129
	v_cvt_pk_bf16_f32 v129, v130, v131
	s_nop 0
	v_cvt_pk_bf16_f32 v130, v146, v147
	v_cvt_pk_bf16_f32 v131, v148, v149
	s_cbranch_vccnz .LBB0_618
	v_add_u32_e32 v135, v142, v140
	v_mov_b64_e32 v[146:147], s[20:21]
	v_mad_i64_i32 v[146:147], s[8:9], v135, s84, v[146:147]
	v_lshl_add_u64 v[146:147], v[146:147], 0, v[176:177]
	v_mov_b32_e32 v135, v177
	v_lshl_add_u64 v[146:147], v[146:147], 0, v[134:135]
	s_mov_b64 s[8:9], 0
	global_store_dwordx4 v[146:147], v[128:131], off

; __device__ __forceinline__ u32x4 pack8(const f32x4& v0, const f32x4& v1) { u32x4 w; w.x = cvt_pk_bf16(v0[0], v0[1]); w.y = cvt_pk_bf16(v0[2], v0[3]); w.z = cvt_pk_bf16(v1[0], v1[1]); w.w = cvt_pk_bf16(v1[2], v1[3]); return w; }
;     __device__ __forceinline__ void operator()(const f32x4 (&acc)[2][2][4][2], const Unit& u, int wr, int wc, int fr_, int fq_) const {
;     ...
;             for (int m = 0; m < 4; ++m) { const int row = row0 + ai * HALF + m * 16;
; #pragma unroll
;                 for (int bj = 0; bj < 2; ++bj) { const int col = col0 + bj * HALF; const float rs = rsv[ai * 4 + m];
;                     const u32x4 w = pack8(acc[ai][bj][m][0] * rs + *(const f32x4*)(bp2 + bj * HALF), acc[ai][bj][m][1] * rs + *(const f32x4*)(bp2 + bj * HALF + 4));
;                     if (t < 3) *(u32x4*)(base + (size_t)row * 1024 + col) = w;
;                     else *(u32x4*)(U + ((size_t)((row >> 4) * 64 + (col >> 4)) * 384 + (row & 15) * 16 + (col & 15))) = w; } }
.LBB0_620:
	global_load_dwordx4 v[128:131], v[136:137], off offset:512
	s_nop 0
	global_load_dwordx4 v[146:149], v[136:137], off offset:528
	v_mov_b32_e32 v195, v194
	v_mov_b32_e32 v150, v194
	v_mov_b32_e32 v151, v194
	s_and_b64 vcc, exec, s[4:5]
	s_mov_b64 s[8:9], -1
	s_waitcnt vmcnt(0) lgkmcnt(0)
	v_pk_fma_f32 v[130:131], v[70:71], v[150:151], v[130:131]
	v_pk_fma_f32 v[128:129], v[68:69], v[194:195], v[128:129]
	v_pk_fma_f32 v[148:149], v[66:67], v[150:151], v[148:149]
	v_pk_fma_f32 v[146:147], v[64:65], v[194:195], v[146:147]
	v_cvt_pk_bf16_f32 v128, v128, v129
	v_cvt_pk_bf16_f32 v129, v130, v131
	s_nop 0
	v_cvt_pk_bf16_f32 v130, v146, v147
	v_cvt_pk_bf16_f32 v131, v148, v149
	s_cbranch_vccnz .LBB0_622
	v_add_u32_e32 v135, v141, v142
	v_mov_b64_e32 v[142:143], s[20:21]
	v_mad_i64_i32 v[142:143], s[8:9], v135, s84, v[142:143]
	v_lshl_add_u64 v[142:143], v[142:143], 0, v[176:177]
	v_mov_b32_e32 v135, v177
	v_lshl_add_u64 v[142:143], v[142:143], 0, v[134:135]
	s_mov_b64 s[8:9], 0
	global_store_dwordx4 v[142:143], v[128:131], off

; __device__ __forceinline__ u32x4 pack8(const f32x4& v0, const f32x4& v1) { u32x4 w; w.x = cvt_pk_bf16(v0[0], v0[1]); w.y = cvt_pk_bf16(v0[2], v0[3]); w.z = cvt_pk_bf16(v1[0], v1[1]); w.w = cvt_pk_bf16(v1[2], v1[3]); return w; }
;     __device__ __forceinline__ void operator()(const f32x4 (&acc)[2][2][4][2], const Unit& u, int wr, int wc, int fr_, int fq_) const {
;     ...
;             for (int m = 0; m < 4; ++m) { const int row = row0 + ai * HALF + m * 16;
; #pragma unroll
;                 for (int bj = 0; bj < 2; ++bj) { const int col = col0 + bj * HALF; const float rs = rsv[ai * 4 + m];
;                     const u32x4 w = pack8(acc[ai][bj][m][0] * rs + *(const f32x4*)(bp2 + bj * HALF), acc[ai][bj][m][1] * rs + *(const f32x4*)(bp2 + bj * HALF + 4));
;                     if (t < 3) *(u32x4*)(base + (size_t)row * 1024 + col) = w;
;                     else *(u32x4*)(U + ((size_t)((row >> 4) * 64 + (col >> 4)) * 384 + (row & 15) * 16 + (col & 15))) = w; } }
.LBB0_624:
	global_load_dwordx4 v[128:131], v[136:137], off
	s_nop 0
	global_load_dwordx4 v[146:149], v[136:137], off offset:16
	v_add_u32_e32 v138, 0x80, v144
	v_lshlrev_b32_e32 v135, 2, v138
	s_and_b64 vcc, exec, s[4:5]
	v_and_b32_e32 v142, 0xffffff00, v135
	s_mov_b64 s[8:9], -1
	s_waitcnt vmcnt(0) lgkmcnt(0)
	v_pk_fma_f32 v[130:131], v[62:63], v[192:193], v[130:131] op_sel_hi:[1,0,1]
	v_pk_fma_f32 v[128:129], v[60:61], v[192:193], v[128:129] op_sel_hi:[1,0,1]
	v_pk_fma_f32 v[148:149], v[58:59], v[192:193], v[148:149] op_sel_hi:[1,0,1]
	v_pk_fma_f32 v[146:147], v[56:57], v[192:193], v[146:147] op_sel_hi:[1,0,1]
	v_cvt_pk_bf16_f32 v128, v128, v129
	v_cvt_pk_bf16_f32 v129, v130, v131
	s_nop 0
	v_cvt_pk_bf16_f32 v130, v146, v147
	v_cvt_pk_bf16_f32 v131, v148, v149
	s_cbranch_vccnz .LBB0_626
	v_add_u32_e32 v135, v142, v140
	v_mov_b64_e32 v[146:147], s[20:21]
	v_mad_i64_i32 v[146:147], s[8:9], v135, s84, v[146:147]
	v_lshl_add_u64 v[146:147], v[146:147], 0, v[176:177]
	v_mov_b32_e32 v135, v177
	v_lshl_add_u64 v[146:147], v[146:147], 0, v[134:135]
	s_mov_b64 s[8:9], 0
	global_store_dwordx4 v[146:147], v[128:131], off

; __device__ __forceinline__ u32x4 pack8(const f32x4& v0, const f32x4& v1) { u32x4 w; w.x = cvt_pk_bf16(v0[0], v0[1]); w.y = cvt_pk_bf16(v0[2], v0[3]); w.z = cvt_pk_bf16(v1[0], v1[1]); w.w = cvt_pk_bf16(v1[2], v1[3]); return w; }
;     __device__ __forceinline__ void operator()(const f32x4 (&acc)[2][2][4][2], const Unit& u, int wr, int wc, int fr_, int fq_) const {
;     ...
;             for (int m = 0; m < 4; ++m) { const int row = row0 + ai * HALF + m * 16;
; #pragma unroll
;                 for (int bj = 0; bj < 2; ++bj) { const int col = col0 + bj * HALF; const float rs = rsv[ai * 4 + m];
;                     const u32x4 w = pack8(acc[ai][bj][m][0] * rs + *(const f32x4*)(bp2 + bj * HALF), acc[ai][bj][m][1] * rs + *(const f32x4*)(bp2 + bj * HALF + 4));
;                     if (t < 3) *(u32x4*)(base + (size_t)row * 1024 + col) = w;
;                     else *(u32x4*)(U + ((size_t)((row >> 4) * 64 + (col >> 4)) * 384 + (row & 15) * 16 + (col & 15))) = w; } }
.LBB0_628:
	global_load_dwordx4 v[128:131], v[136:137], off offset:512
	s_nop 0
	global_load_dwordx4 v[146:149], v[136:137], off offset:528
	v_mov_b32_e32 v193, v192
	v_mov_b32_e32 v150, v192
	v_mov_b32_e32 v151, v192
	s_and_b64 vcc, exec, s[4:5]
	s_mov_b64 s[8:9], -1
	s_waitcnt vmcnt(0) lgkmcnt(0)
	v_pk_fma_f32 v[130:131], v[54:55], v[150:151], v[130:131]
	v_pk_fma_f32 v[128:129], v[52:53], v[192:193], v[128:129]
	v_pk_fma_f32 v[148:149], v[50:51], v[150:151], v[148:149]
	v_pk_fma_f32 v[146:147], v[48:49], v[192:193], v[146:147]
	v_cvt_pk_bf16_f32 v128, v128, v129
	v_cvt_pk_bf16_f32 v129, v130, v131
	s_nop 0
	v_cvt_pk_bf16_f32 v130, v146, v147
	v_cvt_pk_bf16_f32 v131, v148, v149
	s_cbranch_vccnz .LBB0_630
	v_add_u32_e32 v135, v141, v142
	v_mov_b64_e32 v[142:143], s[20:21]
	v_mad_i64_i32 v[142:143], s[8:9], v135, s84, v[142:143]
	v_lshl_add_u64 v[142:143], v[142:143], 0, v[176:177]
	v_mov_b32_e32 v135, v177
	v_lshl_add_u64 v[142:143], v[142:143], 0, v[134:135]
	s_mov_b64 s[8:9], 0
	global_store_dwordx4 v[142:143], v[128:131], off

; __device__ __forceinline__ u32x4 pack8(const f32x4& v0, const f32x4& v1) { u32x4 w; w.x = cvt_pk_bf16(v0[0], v0[1]); w.y = cvt_pk_bf16(v0[2], v0[3]); w.z = cvt_pk_bf16(v1[0], v1[1]); w.w = cvt_pk_bf16(v1[2], v1[3]); return w; }
;     __device__ __forceinline__ void operator()(const f32x4 (&acc)[2][2][4][2], const Unit& u, int wr, int wc, int fr_, int fq_) const {
;     ...
;             for (int m = 0; m < 4; ++m) { const int row = row0 + ai * HALF + m * 16;
; #pragma unroll
;                 for (int bj = 0; bj < 2; ++bj) { const int col = col0 + bj * HALF; const float rs = rsv[ai * 4 + m];
;                     const u32x4 w = pack8(acc[ai][bj][m][0] * rs + *(const f32x4*)(bp2 + bj * HALF), acc[ai][bj][m][1] * rs + *(const f32x4*)(bp2 + bj * HALF + 4));
;                     if (t < 3) *(u32x4*)(base + (size_t)row * 1024 + col) = w;
;                     else *(u32x4*)(U + ((size_t)((row >> 4) * 64 + (col >> 4)) * 384 + (row & 15) * 16 + (col & 15))) = w; } }
.LBB0_632:
	global_load_dwordx4 v[128:131], v[136:137], off
	s_nop 0
	global_load_dwordx4 v[146:149], v[136:137], off offset:16
	v_add_u32_e32 v138, 0x90, v144
	v_lshlrev_b32_e32 v135, 2, v138
	s_and_b64 vcc, exec, s[4:5]
	v_and_b32_e32 v142, 0xffffff40, v135
	s_mov_b64 s[8:9], -1
	s_waitcnt vmcnt(0) lgkmcnt(0)
	v_pk_fma_f32 v[130:131], v[46:47], v[190:191], v[130:131] op_sel_hi:[1,0,1]
	v_pk_fma_f32 v[128:129], v[44:45], v[190:191], v[128:129] op_sel_hi:[1,0,1]
	v_pk_fma_f32 v[148:149], v[42:43], v[190:191], v[148:149] op_sel_hi:[1,0,1]
	v_pk_fma_f32 v[146:147], v[40:41], v[190:191], v[146:147] op_sel_hi:[1,0,1]
	v_cvt_pk_bf16_f32 v128, v128, v129
	v_cvt_pk_bf16_f32 v129, v130, v131
	s_nop 0
	v_cvt_pk_bf16_f32 v130, v146, v147
	v_cvt_pk_bf16_f32 v131, v148, v149
	s_cbranch_vccnz .LBB0_634
	v_add_u32_e32 v135, v142, v140
	v_mov_b64_e32 v[146:147], s[20:21]
	v_mad_i64_i32 v[146:147], s[8:9], v135, s84, v[146:147]
	v_lshl_add_u64 v[146:147], v[146:147], 0, v[176:177]
	v_mov_b32_e32 v135, v177
	v_lshl_add_u64 v[146:147], v[146:147], 0, v[134:135]
	s_mov_b64 s[8:9], 0
	global_store_dwordx4 v[146:147], v[128:131], off

; __device__ __forceinline__ u32x4 pack8(const f32x4& v0, const f32x4& v1) { u32x4 w; w.x = cvt_pk_bf16(v0[0], v0[1]); w.y = cvt_pk_bf16(v0[2], v0[3]); w.z = cvt_pk_bf16(v1[0], v1[1]); w.w = cvt_pk_bf16(v1[2], v1[3]); return w; }
;     __device__ __forceinline__ void operator()(const f32x4 (&acc)[2][2][4][2], const Unit& u, int wr, int wc, int fr_, int fq_) const {
;     ...
;             for (int m = 0; m < 4; ++m) { const int row = row0 + ai * HALF + m * 16;
; #pragma unroll
;                 for (int bj = 0; bj < 2; ++bj) { const int col = col0 + bj * HALF; const float rs = rsv[ai * 4 + m];
;                     const u32x4 w = pack8(acc[ai][bj][m][0] * rs + *(const f32x4*)(bp2 + bj * HALF), acc[ai][bj][m][1] * rs + *(const f32x4*)(bp2 + bj * HALF + 4));
;                     if (t < 3) *(u32x4*)(base + (size_t)row * 1024 + col) = w;
;                     else *(u32x4*)(U + ((size_t)((row >> 4) * 64 + (col >> 4)) * 384 + (row & 15) * 16 + (col & 15))) = w; } }
.LBB0_636:
	global_load_dwordx4 v[128:131], v[136:137], off offset:512
	s_nop 0
	global_load_dwordx4 v[146:149], v[136:137], off offset:528
	v_mov_b32_e32 v191, v190
	v_mov_b32_e32 v150, v190
	v_mov_b32_e32 v151, v190
	s_and_b64 vcc, exec, s[4:5]
	s_mov_b64 s[8:9], -1
	s_waitcnt vmcnt(0) lgkmcnt(0)
	v_pk_fma_f32 v[130:131], v[38:39], v[150:151], v[130:131]
	v_pk_fma_f32 v[128:129], v[36:37], v[190:191], v[128:129]
	v_pk_fma_f32 v[148:149], v[34:35], v[150:151], v[148:149]
	v_pk_fma_f32 v[146:147], v[32:33], v[190:191], v[146:147]
	v_cvt_pk_bf16_f32 v128, v128, v129
	v_cvt_pk_bf16_f32 v129, v130, v131
	s_nop 0
	v_cvt_pk_bf16_f32 v130, v146, v147
	v_cvt_pk_bf16_f32 v131, v148, v149
	s_cbranch_vccnz .LBB0_638
	v_add_u32_e32 v135, v141, v142
	v_mov_b64_e32 v[142:143], s[20:21]
	v_mad_i64_i32 v[142:143], s[8:9], v135, s84, v[142:143]
	v_lshl_add_u64 v[142:143], v[142:143], 0, v[176:177]
	v_mov_b32_e32 v135, v177
	v_lshl_add_u64 v[142:143], v[142:143], 0, v[134:135]
	s_mov_b64 s[8:9], 0
	global_store_dwordx4 v[142:143], v[128:131], off

; __device__ __forceinline__ u32x4 pack8(const f32x4& v0, const f32x4& v1) { u32x4 w; w.x = cvt_pk_bf16(v0[0], v0[1]); w.y = cvt_pk_bf16(v0[2], v0[3]); w.z = cvt_pk_bf16(v1[0], v1[1]); w.w = cvt_pk_bf16(v1[2], v1[3]); return w; }
;     __device__ __forceinline__ void operator()(const f32x4 (&acc)[2][2][4][2], const Unit& u, int wr, int wc, int fr_, int fq_) const {
;     ...
;         const int col0 = (u.pn & 3) * BM + wc * 32 + 8 * fq;
;         bf16_t* base = Q + (size_t)2 * qkv_stride;
;         const float* bp2 = bv + u.pn * BM + wc * 32 + 8 * fq;
; #pragma unroll
;         for (int ai = 0; ai < 2; ++ai)
; #pragma unroll
;             for (int m = 0; m < 4; ++m) { const int row = row0 + ai * HALF + m * 16;
; #pragma unroll
;                 for (int bj = 0; bj < 2; ++bj) { const int col = col0 + bj * HALF; const float rs = rsv[ai * 4 + m];
;                     const u32x4 w = pack8(acc[ai][bj][m][0] * rs + *(const f32x4*)(bp2 + bj * HALF), acc[ai][bj][m][1] * rs + *(const f32x4*)(bp2 + bj * HALF + 4));
;                     if (t < 3) *(u32x4*)(base + (size_t)row * 1024 + col) = w;
;                     else *(u32x4*)(U + ((size_t)((row >> 4) * 64 + (col >> 4)) * 384 + (row & 15) * 16 + (col & 15))) = w; } }
.LBB0_640:
	global_load_dwordx4 v[128:131], v[136:137], off
	s_nop 0
	global_load_dwordx4 v[146:149], v[136:137], off offset:16
	v_add_u32_e32 v138, 0xa0, v144
	v_lshlrev_b32_e32 v135, 2, v138
	s_and_b64 vcc, exec, s[4:5]
	v_and_b32_e32 v142, 0xffffff80, v135
	s_mov_b64 s[8:9], -1
	s_waitcnt vmcnt(0) lgkmcnt(0)
	v_pk_fma_f32 v[130:131], v[30:31], v[188:189], v[130:131] op_sel_hi:[1,0,1]
	v_pk_fma_f32 v[128:129], v[28:29], v[188:189], v[128:129] op_sel_hi:[1,0,1]
	v_pk_fma_f32 v[148:149], v[26:27], v[188:189], v[148:149] op_sel_hi:[1,0,1]
	v_pk_fma_f32 v[146:147], v[24:25], v[188:189], v[146:147] op_sel_hi:[1,0,1]
	v_cvt_pk_bf16_f32 v128, v128, v129
	v_cvt_pk_bf16_f32 v129, v130, v131
	s_nop 0
	v_cvt_pk_bf16_f32 v130, v146, v147
	v_cvt_pk_bf16_f32 v131, v148, v149
	s_cbranch_vccnz .LBB0_642
	v_add_u32_e32 v135, v142, v140
	v_mov_b64_e32 v[146:147], s[20:21]
	v_mad_i64_i32 v[146:147], s[8:9], v135, s84, v[146:147]
	v_lshl_add_u64 v[146:147], v[146:147], 0, v[176:177]
	v_mov_b32_e32 v135, v177
	v_lshl_add_u64 v[146:147], v[146:147], 0, v[134:135]
	s_mov_b64 s[8:9], 0
	global_store_dwordx4 v[146:147], v[128:131], off

; __device__ __forceinline__ u32x4 pack8(const f32x4& v0, const f32x4& v1) { u32x4 w; w.x = cvt_pk_bf16(v0[0], v0[1]); w.y = cvt_pk_bf16(v0[2], v0[3]); w.z = cvt_pk_bf16(v1[0], v1[1]); w.w = cvt_pk_bf16(v1[2], v1[3]); return w; }
;     __device__ __forceinline__ void operator()(const f32x4 (&acc)[2][2][4][2], const Unit& u, int wr, int wc, int fr_, int fq_) const {
;     ...
;         const int col0 = (u.pn & 3) * BM + wc * 32 + 8 * fq;
;         bf16_t* base = Q + (size_t)2 * qkv_stride;
;         const float* bp2 = bv + u.pn * BM + wc * 32 + 8 * fq;
; #pragma unroll
;         for (int ai = 0; ai < 2; ++ai)
; #pragma unroll
;             for (int m = 0; m < 4; ++m) { const int row = row0 + ai * HALF + m * 16;
; #pragma unroll
;                 for (int bj = 0; bj < 2; ++bj) { const int col = col0 + bj * HALF; const float rs = rsv[ai * 4 + m];
;                     const u32x4 w = pack8(acc[ai][bj][m][0] * rs + *(const f32x4*)(bp2 + bj * HALF), acc[ai][bj][m][1] * rs + *(const f32x4*)(bp2 + bj * HALF + 4));
;                     if (t < 3) *(u32x4*)(base + (size_t)row * 1024 + col) = w;
;                     else *(u32x4*)(U + ((size_t)((row >> 4) * 64 + (col >> 4)) * 384 + (row & 15) * 16 + (col & 15))) = w; } }
.LBB0_644:
	global_load_dwordx4 v[128:131], v[136:137], off offset:512
	s_nop 0
	global_load_dwordx4 v[146:149], v[136:137], off offset:528
	v_mov_b32_e32 v189, v188
	v_mov_b32_e32 v150, v188
	v_mov_b32_e32 v151, v188
	s_and_b64 vcc, exec, s[4:5]
	s_mov_b64 s[8:9], -1
	s_waitcnt vmcnt(0) lgkmcnt(0)
	v_pk_fma_f32 v[130:131], v[22:23], v[150:151], v[130:131]
	v_pk_fma_f32 v[128:129], v[20:21], v[188:189], v[128:129]
	v_pk_fma_f32 v[148:149], v[18:19], v[150:151], v[148:149]
	v_pk_fma_f32 v[146:147], v[16:17], v[188:189], v[146:147]
	v_cvt_pk_bf16_f32 v128, v128, v129
	v_cvt_pk_bf16_f32 v129, v130, v131
	s_nop 0
	v_cvt_pk_bf16_f32 v130, v146, v147
	v_cvt_pk_bf16_f32 v131, v148, v149
	s_cbranch_vccnz .LBB0_646
	v_add_u32_e32 v135, v141, v142
	v_mov_b64_e32 v[142:143], s[20:21]
	v_mad_i64_i32 v[142:143], s[8:9], v135, s84, v[142:143]
	v_lshl_add_u64 v[142:143], v[142:143], 0, v[176:177]
	v_mov_b32_e32 v135, v177
	v_lshl_add_u64 v[142:143], v[142:143], 0, v[134:135]
	s_mov_b64 s[8:9], 0
	global_store_dwordx4 v[142:143], v[128:131], off

; __device__ __forceinline__ u32x4 pack8(const f32x4& v0, const f32x4& v1) { u32x4 w; w.x = cvt_pk_bf16(v0[0], v0[1]); w.y = cvt_pk_bf16(v0[2], v0[3]); w.z = cvt_pk_bf16(v1[0], v1[1]); w.w = cvt_pk_bf16(v1[2], v1[3]); return w; }
;     __device__ __forceinline__ void operator()(const f32x4 (&acc)[2][2][4][2], const Unit& u, int wr, int wc, int fr_, int fq_) const {
;     ...
;         const int col0 = (u.pn & 3) * BM + wc * 32 + 8 * fq;
;         bf16_t* base = Q + (size_t)2 * qkv_stride;
;         const float* bp2 = bv + u.pn * BM + wc * 32 + 8 * fq;
; #pragma unroll
;         for (int ai = 0; ai < 2; ++ai)
; #pragma unroll
;             for (int m = 0; m < 4; ++m) { const int row = row0 + ai * HALF + m * 16;
; #pragma unroll
;                 for (int bj = 0; bj < 2; ++bj) { const int col = col0 + bj * HALF; const float rs = rsv[ai * 4 + m];
;                     const u32x4 w = pack8(acc[ai][bj][m][0] * rs + *(const f32x4*)(bp2 + bj * HALF), acc[ai][bj][m][1] * rs + *(const f32x4*)(bp2 + bj * HALF + 4));
;                     if (t < 3) *(u32x4*)(base + (size_t)row * 1024 + col) = w;
;                     else *(u32x4*)(U + ((size_t)((row >> 4) * 64 + (col >> 4)) * 384 + (row & 15) * 16 + (col & 15))) = w; } }
.LBB0_648:
	global_load_dwordx4 v[128:131], v[136:137], off
	s_nop 0
	global_load_dwordx4 v[146:149], v[136:137], off offset:16
	v_add_u32_e32 v138, 0xb0, v144
	v_lshlrev_b32_e32 v135, 2, v138
	s_and_b64 vcc, exec, s[4:5]
	v_and_b32_e32 v142, 0xffffffc0, v135
	s_mov_b64 s[8:9], -1
	s_waitcnt vmcnt(0) lgkmcnt(0)
	v_pk_fma_f32 v[130:131], v[14:15], v[186:187], v[130:131] op_sel_hi:[1,0,1]
	v_pk_fma_f32 v[128:129], v[12:13], v[186:187], v[128:129] op_sel_hi:[1,0,1]
	v_pk_fma_f32 v[148:149], v[10:11], v[186:187], v[148:149] op_sel_hi:[1,0,1]
	v_pk_fma_f32 v[146:147], v[8:9], v[186:187], v[146:147] op_sel_hi:[1,0,1]
	v_cvt_pk_bf16_f32 v128, v128, v129
	v_cvt_pk_bf16_f32 v129, v130, v131
	s_nop 0
	v_cvt_pk_bf16_f32 v130, v146, v147
	v_cvt_pk_bf16_f32 v131, v148, v149
	s_cbranch_vccnz .LBB0_650
	v_add_u32_e32 v135, v142, v140
	v_mov_b64_e32 v[146:147], s[20:21]
	v_mad_i64_i32 v[146:147], s[8:9], v135, s84, v[146:147]
	v_lshl_add_u64 v[146:147], v[146:147], 0, v[176:177]
	v_mov_b32_e32 v135, v177
	v_lshl_add_u64 v[146:147], v[146:147], 0, v[134:135]
	s_mov_b64 s[8:9], 0
	global_store_dwordx4 v[146:147], v[128:131], off

; __device__ __forceinline__ u32x4 pack8(const f32x4& v0, const f32x4& v1) { u32x4 w; w.x = cvt_pk_bf16(v0[0], v0[1]); w.y = cvt_pk_bf16(v0[2], v0[3]); w.z = cvt_pk_bf16(v1[0], v1[1]); w.w = cvt_pk_bf16(v1[2], v1[3]); return w; }
;     __device__ __forceinline__ void operator()(const f32x4 (&acc)[2][2][4][2], const Unit& u, int wr, int wc, int fr_, int fq_) const {
;     ...
;         const int col0 = (u.pn & 3) * BM + wc * 32 + 8 * fq;
;         bf16_t* base = Q + (size_t)2 * qkv_stride;
;         const float* bp2 = bv + u.pn * BM + wc * 32 + 8 * fq;
; #pragma unroll
;         for (int ai = 0; ai < 2; ++ai)
; #pragma unroll
;             for (int m = 0; m < 4; ++m) { const int row = row0 + ai * HALF + m * 16;
; #pragma unroll
;                 for (int bj = 0; bj < 2; ++bj) { const int col = col0 + bj * HALF; const float rs = rsv[ai * 4 + m];
;                     const u32x4 w = pack8(acc[ai][bj][m][0] * rs + *(const f32x4*)(bp2 + bj * HALF), acc[ai][bj][m][1] * rs + *(const f32x4*)(bp2 + bj * HALF + 4));
;                     if (t < 3) *(u32x4*)(base + (size_t)row * 1024 + col) = w;
;                     else *(u32x4*)(U + ((size_t)((row >> 4) * 64 + (col >> 4)) * 384 + (row & 15) * 16 + (col & 15))) = w; } }
.LBB0_652:
	global_load_dwordx4 v[128:131], v[136:137], off offset:512
	s_nop 0
	global_load_dwordx4 v[146:149], v[136:137], off offset:528
	v_mov_b32_e32 v187, v186
	v_mov_b32_e32 v136, v186
	v_mov_b32_e32 v137, v186
	s_and_b64 vcc, exec, s[4:5]
	s_mov_b64 s[4:5], -1
	s_waitcnt vmcnt(0) lgkmcnt(0)
	v_pk_fma_f32 v[130:131], v[6:7], v[136:137], v[130:131]
	v_pk_fma_f32 v[128:129], v[4:5], v[186:187], v[128:129]
	v_pk_fma_f32 v[136:137], v[2:3], v[136:137], v[148:149]
	v_pk_fma_f32 v[146:147], v[0:1], v[186:187], v[146:147]
	v_cvt_pk_bf16_f32 v128, v128, v129
	v_cvt_pk_bf16_f32 v129, v130, v131
	s_nop 0
	v_cvt_pk_bf16_f32 v130, v146, v147
	v_cvt_pk_bf16_f32 v131, v136, v137
	s_cbranch_vccnz .LBB0_654
	v_add_u32_e32 v135, v141, v142
	v_mov_b64_e32 v[136:137], s[20:21]
	v_mad_i64_i32 v[136:137], s[4:5], v135, s84, v[136:137]
	v_lshl_add_u64 v[136:137], v[136:137], 0, v[176:177]
	v_mov_b32_e32 v135, v177
	v_lshl_add_u64 v[134:135], v[136:137], 0, v[134:135]
	s_mov_b64 s[4:5], 0
	global_store_dwordx4 v[134:135], v[128:131], off
.LBB0_654:
	s_andn2_b64 vcc, exec, s[4:5]
	s_cbranch_vccnz .LBB0_656
	v_lshl_add_u64 v[132:133], v[132:133], 1, v[138:139]
	global_store_dwordx4 v[132:133], v[128:131], off offset:256

;     __device__ __forceinline__ void operator()(const f32x4 (&acc)[2][2][4][2], const Unit& u, int wr, int wc, int fr_, int fq_) const {
;     ...
;         if (t < 2) {
;             f32x4 g[2][2];
; #pragma unroll
;             for (int bj = 0; bj < 2; ++bj)
; #pragma unroll
;                 for (int n = 0; n < 2; ++n) { const f32x4 a = *(const f32x4*)(qn + bj * 32 + 8 * fq + 4 * n), b = *(const f32x4*)(kn + bj * 32 + 8 * fq + 4 * n); g[bj][n] = t == 0 ? a : b; }
;             const float sc = t == 0 ? c2 : 1.0f;
;             const float* bp = bv + u.pn * BM + wc * 32 + 8 * fq; const f32x4 b00 = *(const f32x4*)bp, b01 = *(const f32x4*)(bp + 4), b10 = *(const f32x4*)(bp + HALF), b11 = *(const f32x4*)(bp + HALF + 4);
;             const unsigned long long* sp = ssq + row0;
;             bf16_t* rp = Q + (size_t)t * qkv_stride + (size_t)row0 * 1024 + ((u.pn & 3) * 4 + wc) * 64 + 8 * fq;
;             const float* cp = cs + (size_t)row0 * 16;
; #pragma unroll
;             for (int ai = 0; ai < 2; ++ai)
; #pragma unroll
;                 for (int m = 0; m < 4; ++m) {
;                     asm volatile("" : "+v"(rp), "+v"(cp), "+v"(sp));
;                     const float rs = rsv[ai * 4 + m];
;                     f32x4 v00 = acc[ai][0][m][0] * rs + b00, v01 = acc[ai][0][m][1] * rs + b01, v10 = acc[ai][1][m][0] * rs + b10, v11 = acc[ai][1][m][1] * rs + b11;
;                     float ss = 0.f;
; #pragma unroll
;                     for (int k = 0; k < 4; ++k) ss += v00[k] * v00[k] + v01[k] * v01[k] + v10[k] * v10[k] + v11[k] * v11[k];
;                     ss += __shfl_xor(ss, 16); ss += __shfl_xor(ss, 32);
;                     const float rstd = 1.0f / sqrtf(ss * (1.0f / 64.0f) + 1e-6f);
;                     v00 = v00 * rstd * g[0][0]; v01 = v01 * rstd * g[0][1]; v10 = v10 * rstd * g[1][0]; v11 = v11 * rstd * g[1][1];
;                     f32x4 p0, p1;
; #pragma unroll
;                     for (int k = 0; k < 4; ++k) { p0[k] = __shfl_xor(v00[k], 16); p1[k] = __shfl_xor(v01[k], 16); }
;                     const f32x4 c0 = *(const f32x4*)(cp), c1 = *(const f32x4*)(cp + 4), s0 = *(const f32x4*)(cp + 8), s1 = *(const f32x4*)(cp + 12);
;                     if (fq < 2) {
;                         if (fq == 0) { v00 = v00 * c0 - p0 * s0; v01 = v01 * c1 - p1 * s1; } else { v00 = p0 * s0 + v00 * c0; v01 = p1 * s1 + v01 * c1; } }
.LBB0_658:
	s_and_b64 vcc, exec, s[4:5]
	s_cbranch_vccz .LBB0_657
	s_cmp_lt_u32 s16, 4
	s_cselect_b64 s[8:9], -1, 0
	s_lshl_b32 s4, s16, 8
	s_ashr_i32 s5, s4, 31
	s_lshl_b64 s[4:5], s[4:5], 2
	s_add_u32 s4, s78, s4
	v_lshlrev_b64 v[128:129], 2, v[162:163]
	s_addc_u32 s5, s79, s5
	v_lshl_add_u64 v[146:147], s[12:13], 0, v[128:129]
	v_lshl_add_u64 v[148:149], s[14:15], 0, v[128:129]
	v_lshl_add_u64 v[128:129], s[4:5], 0, v[128:129]
	global_load_dwordx4 v[200:203], v[146:147], off
	global_load_dwordx4 v[222:225], v[146:147], off offset:16
	global_load_dwordx4 v[226:229], v[148:149], off
	global_load_dwordx4 v[230:233], v[148:149], off offset:16
	global_load_dwordx4 v[140:143], v[128:129], off
	global_load_dwordx4 v[136:139], v[128:129], off offset:16
	global_load_dwordx4 v[132:135], v[128:129], off offset:512
	s_nop 0
	global_load_dwordx4 v[128:131], v[128:129], off offset:528
	v_lshlrev_b64 v[212:213], 6, v[144:145]
	v_and_b32_e32 v144, 64, v242
	v_add_u32_e32 v187, 64, v144
	global_load_dwordx4 v[152:155], v[146:147], off offset:128
	s_nop 0
	global_load_dwordx4 v[144:147], v[146:147], off offset:144
	s_nop 0
	global_load_dwordx4 v[156:159], v[148:149], off offset:128
	s_nop 0
	global_load_dwordx4 v[148:151], v[148:149], off offset:144
	v_xor_b32_e32 v161, 16, v242
	v_cmp_lt_i32_e32 vcc, v161, v187
	v_xor_b32_e32 v176, 32, v242
	s_ashr_i32 s7, s6, 31
	v_cndmask_b32_e32 v161, v242, v161, vcc
	v_cmp_lt_i32_e32 vcc, v176, v187
	s_lshl_b64 s[4:5], s[6:7], 25
	s_add_u32 s4, s63, s4
	v_cndmask_b32_e32 v187, v242, v176, vcc
	v_lshlrev_b32_e32 v176, 2, v161
	s_addc_u32 s5, s64, s5
	s_lshl_b32 s6, s16, 2
	v_lshl_add_u64 v[164:165], s[4:5], 0, v[164:165]
	s_and_b32 s4, s6, 12
	s_or_b32 s4, s4, s65
	s_lshl_b32 s16, s4, 7
	v_lshlrev_b32_e32 v187, 2, v187
	v_lshl_add_u64 v[212:213], s[22:23], 0, v[212:213]
	v_cmp_gt_i32_e64 s[6:7], 2, v167
	s_waitcnt vmcnt(0) lgkmcnt(0)
	v_pk_fma_f32 v[124:125], v[124:125], v[160:161], v[140:141] op_sel_hi:[1,0,1]
	v_pk_fma_f32 v[120:121], v[120:121], v[160:161], v[136:137] op_sel_hi:[1,0,1]
	v_pk_fma_f32 v[122:123], v[122:123], v[160:161], v[138:139] op_sel_hi:[1,0,1]
	v_pk_fma_f32 v[214:215], v[114:115], v[160:161], v[130:131] op_sel_hi:[1,0,1]
	v_pk_mul_f32 v[114:115], v[120:121], v[120:121]
	v_pk_fma_f32 v[126:127], v[126:127], v[160:161], v[142:143] op_sel_hi:[1,0,1]
	v_pk_fma_f32 v[220:221], v[116:117], v[160:161], v[132:133] op_sel_hi:[1,0,1]
	v_pk_fma_f32 v[216:217], v[112:113], v[160:161], v[128:129] op_sel_hi:[1,0,1]
	v_pk_mul_f32 v[112:113], v[122:123], v[122:123]
	v_pk_fma_f32 v[114:115], v[124:125], v[124:125], v[114:115]
	v_pk_fma_f32 v[218:219], v[118:119], v[160:161], v[134:135] op_sel_hi:[1,0,1]
	v_pk_fma_f32 v[112:113], v[126:127], v[126:127], v[112:113]
	v_pk_fma_f32 v[114:115], v[220:221], v[220:221], v[114:115]
	v_pk_fma_f32 v[112:113], v[218:219], v[218:219], v[112:113]
	v_pk_fma_f32 v[114:115], v[216:217], v[216:217], v[114:115]
	v_pk_fma_f32 v[112:113], v[214:215], v[214:215], v[112:113]
	v_add_f32_e32 v114, v114, v115
	v_add_f32_e32 v112, v112, v114
	v_add_f32_e32 v114, v113, v112
	ds_bpermute_b32 v115, v176, v114
	v_lshl_add_u64 v[112:113], v[164:165], 0, s[16:17]
	v_lshl_add_u64 v[210:211], v[162:163], 1, v[112:113]
	v_cndmask_b32_e64 v204, v230, v222, s[8:9]
	v_cndmask_b32_e64 v199, v229, v203, s[8:9]
	s_waitcnt lgkmcnt(0)
	v_add_f32_e32 v112, v114, v115
	ds_bpermute_b32 v113, v187, v112
	v_cndmask_b32_e64 v198, v228, v202, s[8:9]
	v_cndmask_b32_e64 v201, v227, v201, s[8:9]
	v_cndmask_b32_e64 v200, v226, v200, s[8:9]
	v_cndmask_b32_e64 v203, v233, v225, s[8:9]
	s_waitcnt lgkmcnt(0)
	v_add_f32_e32 v112, v112, v113
	v_fmamk_f32 v112, v112, 0x3c800000, v240
	v_mul_f32_e32 v113, 0x4f800000, v112
	v_cmp_gt_f32_e32 vcc, s83, v112
	v_cndmask_b32_e64 v202, v232, v224, s[8:9]
	v_cndmask_b32_e64 v205, v231, v223, s[8:9]
	v_cndmask_b32_e32 v112, v112, v113, vcc
	v_sqrt_f32_e32 v113, v112
	s_nop 0
	v_add_u32_e32 v114, -1, v113
	v_add_u32_e32 v115, 1, v113
	v_fma_f32 v116, -v114, v113, v112
	v_fma_f32 v117, -v115, v113, v112
	v_cmp_ge_f32_e64 s[4:5], 0, v116
	s_nop 1
	v_cndmask_b32_e64 v113, v113, v114, s[4:5]
	v_cmp_lt_f32_e64 s[4:5], 0, v117
	s_nop 1
	v_cndmask_b32_e64 v113, v113, v115, s[4:5]
	v_mul_f32_e32 v114, 0x37800000, v113
	v_cndmask_b32_e32 v113, v113, v114, vcc
	v_cmp_class_f32_e32 vcc, v112, v241
	s_nop 1
	v_cndmask_b32_e32 v112, v113, v112, vcc
	v_div_scale_f32 v113, s[4:5], v112, v112, 1.0
	v_rcp_f32_e32 v114, v113
	v_div_scale_f32 v115, vcc, 1.0, v112, 1.0
	v_cmp_lt_u32_e64 s[4:5], 15, v166
	v_fma_f32 v116, -v113, v114, 1.0
	v_fmac_f32_e32 v114, v116, v114
	v_mul_f32_e32 v116, v115, v114
	v_fma_f32 v117, -v113, v116, v115
	v_fmac_f32_e32 v116, v117, v114
	v_fma_f32 v113, -v113, v116, v115
	v_div_fmas_f32 v113, v113, v114, v116
	v_div_fixup_f32 v222, v113, v112, 1.0
	v_pk_mul_f32 v[112:113], v[124:125], v[222:223] op_sel_hi:[1,0]
	v_pk_mul_f32 v[114:115], v[126:127], v[222:223] op_sel_hi:[1,0]
	v_pk_mul_f32 v[116:117], v[120:121], v[222:223] op_sel_hi:[1,0]
	v_pk_mul_f32 v[118:119], v[122:123], v[222:223] op_sel_hi:[1,0]
	v_pk_mul_f32 v[228:229], v[198:199], v[114:115]
	v_pk_mul_f32 v[224:225], v[200:201], v[112:113]
	v_pk_mul_f32 v[226:227], v[202:203], v[118:119]
	v_pk_mul_f32 v[230:231], v[204:205], v[116:117]
	ds_bpermute_b32 v124, v176, v224
	ds_bpermute_b32 v112, v176, v230
	ds_bpermute_b32 v125, v176, v225
	ds_bpermute_b32 v113, v176, v231
	ds_bpermute_b32 v234, v176, v228
	ds_bpermute_b32 v232, v176, v226
	ds_bpermute_b32 v235, v176, v229
	ds_bpermute_b32 v233, v176, v227
	s_and_saveexec_b64 s[52:53], s[6:7]
	s_cbranch_execz .LBB0_665
	global_load_dwordx4 v[160:163], v[212:213], off
	global_load_dwordx4 v[116:119], v[212:213], off offset:16
	global_load_dwordx4 v[164:167], v[212:213], off offset:32
	global_load_dwordx4 v[120:123], v[212:213], off offset:48
	s_and_saveexec_b64 s[54:55], s[4:5]
	s_xor_b64 s[54:55], exec, s[54:55]
	s_cbranch_execz .LBB0_662
	s_waitcnt vmcnt(0) lgkmcnt(0)
	v_pk_mul_f32 v[114:115], v[162:163], v[228:229]
	v_pk_mul_f32 v[126:127], v[160:161], v[224:225]
	v_pk_fma_f32 v[228:229], v[166:167], v[234:235], v[114:115]
	v_pk_mul_f32 v[114:115], v[118:119], v[226:227]
	v_pk_mul_f32 v[116:117], v[116:117], v[230:231]
	v_pk_fma_f32 v[224:225], v[164:165], v[124:125], v[126:127]
	v_pk_fma_f32 v[226:227], v[122:123], v[232:233], v[114:115]
	v_pk_fma_f32 v[230:231], v[120:121], v[112:113], v[116:117]

; __device__ __forceinline__ u32x4 pack8(const f32x4& v0, const f32x4& v1) { u32x4 w; w.x = cvt_pk_bf16(v0[0], v0[1]); w.y = cvt_pk_bf16(v0[2], v0[3]); w.z = cvt_pk_bf16(v1[0], v1[1]); w.w = cvt_pk_bf16(v1[2], v1[3]); return w; }
;     __device__ __forceinline__ void operator()(const f32x4 (&acc)[2][2][4][2], const Unit& u, int wr, int wc, int fr_, int fq_) const {
;     ...
;                     asm volatile("" : "+v"(rp), "+v"(cp), "+v"(sp));
;                     const float rs = rsv[ai * 4 + m];
;                     f32x4 v00 = acc[ai][0][m][0] * rs + b00, v01 = acc[ai][0][m][1] * rs + b01, v10 = acc[ai][1][m][0] * rs + b10, v11 = acc[ai][1][m][1] * rs + b11;
;                     float ss = 0.f;
; #pragma unroll
;                     for (int k = 0; k < 4; ++k) ss += v00[k] * v00[k] + v01[k] * v01[k] + v10[k] * v10[k] + v11[k] * v11[k];
;                     ss += __shfl_xor(ss, 16); ss += __shfl_xor(ss, 32);
;                     const float rstd = 1.0f / sqrtf(ss * (1.0f / 64.0f) + 1e-6f);
;                     v00 = v00 * rstd * g[0][0]; v01 = v01 * rstd * g[0][1]; v10 = v10 * rstd * g[1][0]; v11 = v11 * rstd * g[1][1];
;                     f32x4 p0, p1;
; #pragma unroll
;                     for (int k = 0; k < 4; ++k) { p0[k] = __shfl_xor(v00[k], 16); p1[k] = __shfl_xor(v01[k], 16); }
;                     const f32x4 c0 = *(const f32x4*)(cp), c1 = *(const f32x4*)(cp + 4), s0 = *(const f32x4*)(cp + 8), s1 = *(const f32x4*)(cp + 12);
;                     if (fq < 2) {
;                         if (fq == 0) { v00 = v00 * c0 - p0 * s0; v01 = v01 * c1 - p1 * s1; } else { v00 = p0 * s0 + v00 * c0; v01 = p1 * s1 + v01 * c1; } }
;                     v00 = v00 * sc; v01 = v01 * sc; v10 = v10 * sc; v11 = v11 * sc;
;                     *(u32x4*)rp = pack8(v00, v01); *(u32x4*)(rp + 32) = pack8(v10, v11);
;                     const int adv = (m == 3) ? (128 - 48) : 16; rp += (size_t)adv * 1024; cp += (size_t)adv * 16; sp += adv; }
.LBB0_665:
	s_or_b64 exec, exec, s[52:53]
	v_mov_b32_e32 v223, v222
	s_waitcnt vmcnt(0) lgkmcnt(0)
	v_cndmask_b32_e64 v121, v149, v145, s[8:9]
	v_cndmask_b32_e64 v120, v148, v144, s[8:9]
	v_pk_mul_f32 v[144:145], v[216:217], v[222:223]
	v_pk_fma_f32 v[104:105], v[104:105], v[208:209], v[136:137] op_sel_hi:[1,0,1]
	v_cndmask_b32_e64 v117, v157, v153, s[8:9]
	v_cndmask_b32_e64 v116, v156, v152, s[8:9]
	v_pk_mul_f32 v[152:153], v[120:121], v[144:145]
	v_pk_fma_f32 v[108:109], v[108:109], v[208:209], v[140:141] op_sel_hi:[1,0,1]
	v_pk_fma_f32 v[106:107], v[106:107], v[208:209], v[138:139] op_sel_hi:[1,0,1]
	v_pk_fma_f32 v[144:145], v[98:99], v[208:209], v[130:131] op_sel_hi:[1,0,1]
	v_pk_mul_f32 v[98:99], v[104:105], v[104:105]
	v_cndmask_b32_e64 v119, v151, v147, s[8:9]
	v_cndmask_b32_e64 v118, v150, v146, s[8:9]
	v_pk_fma_f32 v[110:111], v[110:111], v[208:209], v[142:143] op_sel_hi:[1,0,1]
	v_pk_fma_f32 v[150:151], v[100:101], v[208:209], v[132:133] op_sel_hi:[1,0,1]
	v_pk_fma_f32 v[148:149], v[96:97], v[208:209], v[128:129] op_sel_hi:[1,0,1]
	v_pk_mul_f32 v[96:97], v[106:107], v[106:107]
	v_pk_fma_f32 v[98:99], v[108:109], v[108:109], v[98:99]
	v_pk_fma_f32 v[146:147], v[102:103], v[208:209], v[134:135] op_sel_hi:[1,0,1]
	v_pk_fma_f32 v[96:97], v[110:111], v[110:111], v[96:97]
	v_pk_fma_f32 v[98:99], v[150:151], v[150:151], v[98:99]
	v_pk_fma_f32 v[96:97], v[146:147], v[146:147], v[96:97]
	v_pk_fma_f32 v[98:99], v[148:149], v[148:149], v[98:99]
	v_pk_fma_f32 v[96:97], v[144:145], v[144:145], v[96:97]
	v_add_f32_e32 v98, v98, v99
	v_add_f32_e32 v96, v96, v98
	v_add_f32_e32 v96, v97, v96
	ds_bpermute_b32 v97, v176, v96
	v_mov_b32_e32 v122, v222
	v_mov_b32_e32 v123, v222
	v_cndmask_b32_e64 v115, v159, v155, s[8:9]
	v_cndmask_b32_e64 v114, v158, v154, s[8:9]
	v_pk_mul_f32 v[124:125], v[218:219], v[122:123]
	v_pk_mul_f32 v[126:127], v[220:221], v[222:223]
	v_pk_mul_f32 v[122:123], v[214:215], v[122:123]
	v_cndmask_b32_e64 v112, 1.0, v243, s[8:9]
	v_pk_mul_f32 v[126:127], v[116:117], v[126:127]
	v_pk_mul_f32 v[124:125], v[114:115], v[124:125]
	v_pk_mul_f32 v[122:123], v[118:119], v[122:123]
	v_pk_mul_f32 v[154:155], v[112:113], v[228:229] op_sel_hi:[0,1]
	v_pk_mul_f32 v[156:157], v[112:113], v[224:225] op_sel_hi:[0,1]
	v_pk_mul_f32 v[158:159], v[112:113], v[226:227] op_sel_hi:[0,1]
	v_pk_mul_f32 v[160:161], v[112:113], v[230:231] op_sel_hi:[0,1]
	v_pk_mul_f32 v[100:101], v[112:113], v[124:125] op_sel_hi:[0,1]
	v_pk_mul_f32 v[102:103], v[112:113], v[126:127] op_sel_hi:[0,1]
	v_pk_mul_f32 v[122:123], v[112:113], v[122:123] op_sel_hi:[0,1]
	v_pk_mul_f32 v[124:125], v[112:113], v[152:153] op_sel_hi:[0,1]
	s_waitcnt lgkmcnt(0)
	v_add_f32_e32 v113, v96, v97
	ds_bpermute_b32 v126, v187, v113
	v_cvt_pk_bf16_f32 v96, v156, v157
	v_cvt_pk_bf16_f32 v97, v154, v155
	v_cvt_pk_bf16_f32 v98, v160, v161
	v_cvt_pk_bf16_f32 v99, v158, v159
	s_waitcnt lgkmcnt(0)
	v_add_f32_e32 v113, v113, v126
	v_fmamk_f32 v113, v113, 0x3c800000, v240
	v_mul_f32_e32 v126, 0x4f800000, v113
	v_cmp_gt_f32_e32 vcc, s83, v113
	global_store_dwordx4 v[210:211], v[96:99], off
	s_nop 0
	v_cndmask_b32_e32 v113, v113, v126, vcc
	v_sqrt_f32_e32 v126, v113
	v_cvt_pk_bf16_f32 v96, v102, v103
	v_cvt_pk_bf16_f32 v97, v100, v101
	s_nop 0
	v_add_u32_e32 v98, -1, v126
	v_fma_f32 v99, -v98, v126, v113
	v_cmp_ge_f32_e64 s[8:9], 0, v99
	v_add_u32_e32 v99, 1, v126
	v_fma_f32 v100, -v99, v126, v113
	v_cndmask_b32_e64 v98, v126, v98, s[8:9]
	v_cmp_lt_f32_e64 s[8:9], 0, v100
	v_lshl_add_u64 v[126:127], v[196:197], 0, s[26:27]
	s_nop 0
	v_cndmask_b32_e64 v98, v98, v99, s[8:9]
	v_mul_f32_e32 v99, 0x37800000, v98
	v_cndmask_b32_e32 v98, v98, v99, vcc
	v_cmp_class_f32_e32 vcc, v113, v241
	s_nop 1
	v_cndmask_b32_e32 v100, v98, v113, vcc
	v_div_scale_f32 v101, s[8:9], v100, v100, 1.0
	v_rcp_f32_e32 v102, v101
	v_cvt_pk_bf16_f32 v98, v124, v125
	v_cvt_pk_bf16_f32 v99, v122, v123
	global_store_dwordx4 v[210:211], v[96:99], off offset:64
	v_lshl_add_u64 v[122:123], v[210:211], 0, s[36:37]
	v_lshl_add_u64 v[124:125], v[212:213], 0, s[34:35]
	v_fma_f32 v96, -v101, v102, 1.0
	v_fmac_f32_e32 v102, v96, v102
	v_div_scale_f32 v96, vcc, 1.0, v100, 1.0
	v_mul_f32_e32 v97, v96, v102
	v_fma_f32 v98, -v101, v97, v96
	v_fmac_f32_e32 v97, v98, v102
	v_fma_f32 v96, -v101, v97, v96
	v_div_fmas_f32 v96, v96, v102, v97
	v_div_fixup_f32 v160, v96, v100, 1.0
	v_pk_mul_f32 v[96:97], v[108:109], v[160:161] op_sel_hi:[1,0]
	v_pk_mul_f32 v[98:99], v[110:111], v[160:161] op_sel_hi:[1,0]
	v_pk_mul_f32 v[154:155], v[200:201], v[96:97]
	v_pk_mul_f32 v[152:153], v[198:199], v[98:99]
	v_pk_mul_f32 v[96:97], v[104:105], v[160:161] op_sel_hi:[1,0]
	v_pk_mul_f32 v[98:99], v[106:107], v[160:161] op_sel_hi:[1,0]
	v_pk_mul_f32 v[158:159], v[204:205], v[96:97]
	v_pk_mul_f32 v[156:157], v[202:203], v[98:99]
	ds_bpermute_b32 v208, v176, v154
	ds_bpermute_b32 v166, v176, v158
	ds_bpermute_b32 v209, v176, v155
	ds_bpermute_b32 v167, v176, v159
	ds_bpermute_b32 v164, v176, v152
	ds_bpermute_b32 v162, v176, v156
	ds_bpermute_b32 v165, v176, v153
	ds_bpermute_b32 v163, v176, v157
	s_and_saveexec_b64 s[8:9], s[6:7]
	s_cbranch_execz .LBB0_671
	global_load_dwordx4 v[108:111], v[124:125], off offset:32
	global_load_dwordx4 v[100:103], v[124:125], off offset:48
	global_load_dwordx4 v[104:107], v[124:125], off
	global_load_dwordx4 v[96:99], v[124:125], off offset:16
	s_waitcnt vmcnt(0) lgkmcnt(0)
	v_pk_mul_f32 v[108:109], v[108:109], v[208:209]
	v_pk_mul_f32 v[100:101], v[100:101], v[166:167]
	s_and_saveexec_b64 s[52:53], s[4:5]
	s_xor_b64 s[52:53], exec, s[52:53]
	v_pk_mul_f32 v[110:111], v[110:111], v[164:165]
	v_pk_mul_f32 v[102:103], v[102:103], v[162:163]
	v_pk_fma_f32 v[152:153], v[106:107], v[152:153], v[110:111]
	v_pk_fma_f32 v[154:155], v[104:105], v[154:155], v[108:109]
	v_pk_fma_f32 v[156:157], v[98:99], v[156:157], v[102:103]
	v_pk_fma_f32 v[158:159], v[96:97], v[158:159], v[100:101]
	s_andn2_saveexec_b64 s[52:53], s[52:53]
	v_pk_mul_f32 v[110:111], v[110:111], v[164:165]
	v_pk_mul_f32 v[102:103], v[102:103], v[162:163]
	v_pk_fma_f32 v[152:153], v[106:107], v[152:153], v[110:111] neg_lo:[0,0,1] neg_hi:[0,0,1]
	v_pk_fma_f32 v[154:155], v[104:105], v[154:155], v[108:109] neg_lo:[0,0,1] neg_hi:[0,0,1]
	v_pk_fma_f32 v[156:157], v[98:99], v[156:157], v[102:103] neg_lo:[0,0,1] neg_hi:[0,0,1]
	v_pk_fma_f32 v[158:159], v[96:97], v[158:159], v[100:101] neg_lo:[0,0,1] neg_hi:[0,0,1]
	s_or_b64 exec, exec, s[52:53]
; __device__ __forceinline__ u32x4 pack8(const f32x4& v0, const f32x4& v1) { u32x4 w; w.x = cvt_pk_bf16(v0[0], v0[1]); w.y = cvt_pk_bf16(v0[2], v0[3]); w.z = cvt_pk_bf16(v1[0], v1[1]); w.w = cvt_pk_bf16(v1[2], v1[3]); return w; }
;     __device__ __forceinline__ void operator()(const f32x4 (&acc)[2][2][4][2], const Unit& u, int wr, int wc, int fr_, int fq_) const {
;     ...
;                     asm volatile("" : "+v"(rp), "+v"(cp), "+v"(sp));
;                     const float rs = rsv[ai * 4 + m];
;                     f32x4 v00 = acc[ai][0][m][0] * rs + b00, v01 = acc[ai][0][m][1] * rs + b01, v10 = acc[ai][1][m][0] * rs + b10, v11 = acc[ai][1][m][1] * rs + b11;
;                     float ss = 0.f;
; #pragma unroll
;                     for (int k = 0; k < 4; ++k) ss += v00[k] * v00[k] + v01[k] * v01[k] + v10[k] * v10[k] + v11[k] * v11[k];
;                     ss += __shfl_xor(ss, 16); ss += __shfl_xor(ss, 32);
;                     const float rstd = 1.0f / sqrtf(ss * (1.0f / 64.0f) + 1e-6f);
;                     v00 = v00 * rstd * g[0][0]; v01 = v01 * rstd * g[0][1]; v10 = v10 * rstd * g[1][0]; v11 = v11 * rstd * g[1][1];
;                     f32x4 p0, p1;
; #pragma unroll
;                     for (int k = 0; k < 4; ++k) { p0[k] = __shfl_xor(v00[k], 16); p1[k] = __shfl_xor(v01[k], 16); }
;                     const f32x4 c0 = *(const f32x4*)(cp), c1 = *(const f32x4*)(cp + 4), s0 = *(const f32x4*)(cp + 8), s1 = *(const f32x4*)(cp + 12);
;                     if (fq < 2) {
;                         if (fq == 0) { v00 = v00 * c0 - p0 * s0; v01 = v01 * c1 - p1 * s1; } else { v00 = p0 * s0 + v00 * c0; v01 = p1 * s1 + v01 * c1; } }
;                     v00 = v00 * sc; v01 = v01 * sc; v10 = v10 * sc; v11 = v11 * sc;
;                     *(u32x4*)rp = pack8(v00, v01); *(u32x4*)(rp + 32) = pack8(v10, v11);
;                     const int adv = (m == 3) ? (128 - 48) : 16; rp += (size_t)adv * 1024; cp += (size_t)adv * 16; sp += adv; }
.LBB0_671:
	s_or_b64 exec, exec, s[8:9]
	v_pk_fma_f32 v[88:89], v[88:89], v[206:207], v[136:137] op_sel_hi:[1,0,1]
	v_pk_fma_f32 v[92:93], v[92:93], v[206:207], v[140:141] op_sel_hi:[1,0,1]
	v_pk_fma_f32 v[90:91], v[90:91], v[206:207], v[138:139] op_sel_hi:[1,0,1]
	v_pk_fma_f32 v[108:109], v[82:83], v[206:207], v[130:131] op_sel_hi:[1,0,1]
	v_pk_mul_f32 v[82:83], v[88:89], v[88:89]
	v_pk_fma_f32 v[94:95], v[94:95], v[206:207], v[142:143] op_sel_hi:[1,0,1]
	v_pk_fma_f32 v[106:107], v[84:85], v[206:207], v[132:133] op_sel_hi:[1,0,1]
	v_pk_fma_f32 v[110:111], v[80:81], v[206:207], v[128:129] op_sel_hi:[1,0,1]
	v_pk_mul_f32 v[80:81], v[90:91], v[90:91]
	v_pk_fma_f32 v[82:83], v[92:93], v[92:93], v[82:83]
	v_pk_fma_f32 v[104:105], v[86:87], v[206:207], v[134:135] op_sel_hi:[1,0,1]
	v_pk_fma_f32 v[80:81], v[94:95], v[94:95], v[80:81]
	v_pk_fma_f32 v[82:83], v[106:107], v[106:107], v[82:83]
	v_pk_fma_f32 v[80:81], v[104:105], v[104:105], v[80:81]
	v_pk_fma_f32 v[82:83], v[110:111], v[110:111], v[82:83]
	v_pk_fma_f32 v[80:81], v[108:109], v[108:109], v[80:81]
	v_add_f32_e32 v82, v82, v83
	v_add_f32_e32 v80, v80, v82
	v_add_f32_e32 v80, v81, v80
	ds_bpermute_b32 v81, v176, v80
	v_mov_b32_e32 v161, v160
	v_pk_mul_f32 v[100:101], v[150:151], v[160:161]
	v_pk_mul_f32 v[102:103], v[148:149], v[160:161]
	v_mov_b32_e32 v113, v112
	v_pk_mul_f32 v[100:101], v[116:117], v[100:101]
	v_pk_mul_f32 v[102:103], v[120:121], v[102:103]
	v_pk_mul_f32 v[86:87], v[112:113], v[100:101]
	v_pk_mul_f32 v[100:101], v[112:113], v[102:103]
	s_waitcnt lgkmcnt(0)
	v_add_f32_e32 v102, v80, v81
	ds_bpermute_b32 v103, v187, v102
	v_mov_b32_e32 v96, v160
	v_mov_b32_e32 v97, v160
	v_pk_mul_f32 v[98:99], v[146:147], v[96:97]
	v_pk_mul_f32 v[96:97], v[144:145], v[96:97]
	s_waitcnt lgkmcnt(0)
	v_add_f32_e32 v102, v102, v103
	v_fmamk_f32 v102, v102, 0x3c800000, v240
	v_mul_f32_e32 v103, 0x4f800000, v102
	v_cmp_gt_f32_e32 vcc, s83, v102
	v_pk_mul_f32 v[144:145], v[118:119], v[96:97]
	v_mov_b32_e32 v96, v112
	v_cndmask_b32_e32 v102, v102, v103, vcc
	v_sqrt_f32_e32 v103, v102
	v_mov_b32_e32 v97, v112
	v_pk_mul_f32 v[146:147], v[96:97], v[152:153]
	v_pk_mul_f32 v[148:149], v[112:113], v[154:155]
	v_pk_mul_f32 v[152:153], v[112:113], v[158:159]
	v_cvt_pk_bf16_f32 v80, v148, v149
	v_cvt_pk_bf16_f32 v81, v146, v147
	v_pk_mul_f32 v[150:151], v[96:97], v[156:157]
	v_cvt_pk_bf16_f32 v82, v152, v153
	v_pk_mul_f32 v[98:99], v[114:115], v[98:99]
	v_cvt_pk_bf16_f32 v83, v150, v151
	global_store_dwordx4 v[122:123], v[80:83], off
	v_pk_mul_f32 v[84:85], v[96:97], v[98:99]
	v_pk_mul_f32 v[98:99], v[96:97], v[144:145]
	v_add_u32_e32 v82, -1, v103
	v_fma_f32 v83, -v82, v103, v102
	v_cmp_ge_f32_e64 s[8:9], 0, v83
	v_add_u32_e32 v83, 1, v103
	v_cvt_pk_bf16_f32 v80, v86, v87
	v_cvt_pk_bf16_f32 v81, v84, v85
	v_fma_f32 v84, -v83, v103, v102
	v_cndmask_b32_e64 v82, v103, v82, s[8:9]
	v_cmp_lt_f32_e64 s[8:9], 0, v84
	s_nop 1
	v_cndmask_b32_e64 v82, v82, v83, s[8:9]
	v_mul_f32_e32 v83, 0x37800000, v82
	v_cndmask_b32_e32 v82, v82, v83, vcc
	v_cmp_class_f32_e32 vcc, v102, v241
	s_nop 1
	v_cndmask_b32_e32 v84, v82, v102, vcc
	v_div_scale_f32 v85, s[8:9], v84, v84, 1.0
	v_rcp_f32_e32 v86, v85
	v_cvt_pk_bf16_f32 v82, v100, v101
	v_cvt_pk_bf16_f32 v83, v98, v99
	global_store_dwordx4 v[122:123], v[80:83], off offset:64
	v_lshl_add_u64 v[98:99], v[122:123], 0, s[36:37]
	v_lshl_add_u64 v[100:101], v[124:125], 0, s[34:35]
	v_fma_f32 v80, -v85, v86, 1.0
	v_fmac_f32_e32 v86, v80, v86
	v_div_scale_f32 v80, vcc, 1.0, v84, 1.0
	v_mul_f32_e32 v81, v80, v86
	v_fma_f32 v82, -v85, v81, v80
	v_fmac_f32_e32 v81, v82, v86
	v_fma_f32 v80, -v85, v81, v80
	v_div_fmas_f32 v80, v80, v86, v81
	v_div_fixup_f32 v148, v80, v84, 1.0
	v_pk_mul_f32 v[80:81], v[92:93], v[148:149] op_sel_hi:[1,0]
	v_pk_mul_f32 v[82:83], v[94:95], v[148:149] op_sel_hi:[1,0]
	v_pk_mul_f32 v[146:147], v[200:201], v[80:81]
	v_pk_mul_f32 v[144:145], v[198:199], v[82:83]
	v_pk_mul_f32 v[80:81], v[88:89], v[148:149] op_sel_hi:[1,0]
	v_pk_mul_f32 v[82:83], v[90:91], v[148:149] op_sel_hi:[1,0]
	v_pk_mul_f32 v[152:153], v[204:205], v[80:81]
	v_pk_mul_f32 v[150:151], v[202:203], v[82:83]
	ds_bpermute_b32 v160, v176, v146
	ds_bpermute_b32 v158, v176, v152
	ds_bpermute_b32 v161, v176, v147
	ds_bpermute_b32 v159, v176, v153
	ds_bpermute_b32 v156, v176, v144
	ds_bpermute_b32 v154, v176, v150
	ds_bpermute_b32 v157, v176, v145
	ds_bpermute_b32 v155, v176, v151
	v_lshl_add_u64 v[102:103], v[126:127], 0, s[26:27]
	s_and_saveexec_b64 s[8:9], s[6:7]
	s_cbranch_execz .LBB0_677
	global_load_dwordx4 v[92:95], v[100:101], off offset:32
	global_load_dwordx4 v[84:87], v[100:101], off offset:48
	global_load_dwordx4 v[88:91], v[100:101], off
	global_load_dwordx4 v[80:83], v[100:101], off offset:16
	s_waitcnt vmcnt(0) lgkmcnt(0)
	v_pk_mul_f32 v[92:93], v[92:93], v[160:161]
	v_pk_mul_f32 v[84:85], v[84:85], v[158:159]
	s_and_saveexec_b64 s[52:53], s[4:5]
	s_xor_b64 s[52:53], exec, s[52:53]
	v_pk_mul_f32 v[94:95], v[94:95], v[156:157]
	v_pk_mul_f32 v[86:87], v[86:87], v[154:155]
	v_pk_fma_f32 v[144:145], v[90:91], v[144:145], v[94:95]
	v_pk_fma_f32 v[146:147], v[88:89], v[146:147], v[92:93]
	v_pk_fma_f32 v[150:151], v[82:83], v[150:151], v[86:87]
	v_pk_fma_f32 v[152:153], v[80:81], v[152:153], v[84:85]
	s_andn2_saveexec_b64 s[52:53], s[52:53]
	v_pk_mul_f32 v[94:95], v[94:95], v[156:157]
	v_pk_mul_f32 v[86:87], v[86:87], v[154:155]
	v_pk_fma_f32 v[144:145], v[90:91], v[144:145], v[94:95] neg_lo:[0,0,1] neg_hi:[0,0,1]
	v_pk_fma_f32 v[146:147], v[88:89], v[146:147], v[92:93] neg_lo:[0,0,1] neg_hi:[0,0,1]
	v_pk_fma_f32 v[150:151], v[82:83], v[150:151], v[86:87] neg_lo:[0,0,1] neg_hi:[0,0,1]
	v_pk_fma_f32 v[152:153], v[80:81], v[152:153], v[84:85] neg_lo:[0,0,1] neg_hi:[0,0,1]
	s_or_b64 exec, exec, s[52:53]
; __device__ __forceinline__ u32x4 pack8(const f32x4& v0, const f32x4& v1) { u32x4 w; w.x = cvt_pk_bf16(v0[0], v0[1]); w.y = cvt_pk_bf16(v0[2], v0[3]); w.z = cvt_pk_bf16(v1[0], v1[1]); w.w = cvt_pk_bf16(v1[2], v1[3]); return w; }
;     __device__ __forceinline__ void operator()(const f32x4 (&acc)[2][2][4][2], const Unit& u, int wr, int wc, int fr_, int fq_) const {
;     ...
;                     asm volatile("" : "+v"(rp), "+v"(cp), "+v"(sp));
;                     const float rs = rsv[ai * 4 + m];
;                     f32x4 v00 = acc[ai][0][m][0] * rs + b00, v01 = acc[ai][0][m][1] * rs + b01, v10 = acc[ai][1][m][0] * rs + b10, v11 = acc[ai][1][m][1] * rs + b11;
;                     float ss = 0.f;
; #pragma unroll
;                     for (int k = 0; k < 4; ++k) ss += v00[k] * v00[k] + v01[k] * v01[k] + v10[k] * v10[k] + v11[k] * v11[k];
;                     ss += __shfl_xor(ss, 16); ss += __shfl_xor(ss, 32);
;                     const float rstd = 1.0f / sqrtf(ss * (1.0f / 64.0f) + 1e-6f);
;                     v00 = v00 * rstd * g[0][0]; v01 = v01 * rstd * g[0][1]; v10 = v10 * rstd * g[1][0]; v11 = v11 * rstd * g[1][1];
;                     f32x4 p0, p1;
; #pragma unroll
;                     for (int k = 0; k < 4; ++k) { p0[k] = __shfl_xor(v00[k], 16); p1[k] = __shfl_xor(v01[k], 16); }
;                     const f32x4 c0 = *(const f32x4*)(cp), c1 = *(const f32x4*)(cp + 4), s0 = *(const f32x4*)(cp + 8), s1 = *(const f32x4*)(cp + 12);
;                     if (fq < 2) {
;                         if (fq == 0) { v00 = v00 * c0 - p0 * s0; v01 = v01 * c1 - p1 * s1; } else { v00 = p0 * s0 + v00 * c0; v01 = p1 * s1 + v01 * c1; } }
;                     v00 = v00 * sc; v01 = v01 * sc; v10 = v10 * sc; v11 = v11 * sc;
;                     *(u32x4*)rp = pack8(v00, v01); *(u32x4*)(rp + 32) = pack8(v10, v11);
;                     const int adv = (m == 3) ? (128 - 48) : 16; rp += (size_t)adv * 1024; cp += (size_t)adv * 16; sp += adv; }
.LBB0_677:
	s_or_b64 exec, exec, s[8:9]
	v_mov_b32_e32 v149, v148
	v_pk_mul_f32 v[86:87], v[110:111], v[148:149]
	v_pk_fma_f32 v[72:73], v[72:73], v[194:195], v[136:137] op_sel_hi:[1,0,1]
	v_pk_mul_f32 v[94:95], v[120:121], v[86:87]
	v_pk_fma_f32 v[76:77], v[76:77], v[194:195], v[140:141] op_sel_hi:[1,0,1]
	v_pk_fma_f32 v[74:75], v[74:75], v[194:195], v[138:139] op_sel_hi:[1,0,1]
	v_pk_fma_f32 v[86:87], v[66:67], v[194:195], v[130:131] op_sel_hi:[1,0,1]
	v_pk_mul_f32 v[66:67], v[72:73], v[72:73]
	v_pk_fma_f32 v[78:79], v[78:79], v[194:195], v[142:143] op_sel_hi:[1,0,1]
	v_pk_fma_f32 v[92:93], v[68:69], v[194:195], v[132:133] op_sel_hi:[1,0,1]
	v_pk_fma_f32 v[90:91], v[64:65], v[194:195], v[128:129] op_sel_hi:[1,0,1]
	v_pk_mul_f32 v[64:65], v[74:75], v[74:75]
	v_pk_fma_f32 v[66:67], v[76:77], v[76:77], v[66:67]
	v_pk_fma_f32 v[88:89], v[70:71], v[194:195], v[134:135] op_sel_hi:[1,0,1]
	v_pk_fma_f32 v[64:65], v[78:79], v[78:79], v[64:65]
	v_pk_fma_f32 v[66:67], v[92:93], v[92:93], v[66:67]
	v_pk_fma_f32 v[64:65], v[88:89], v[88:89], v[64:65]
	v_pk_fma_f32 v[66:67], v[90:91], v[90:91], v[66:67]
	v_pk_fma_f32 v[64:65], v[86:87], v[86:87], v[64:65]
	v_add_f32_e32 v66, v66, v67
	v_add_f32_e32 v64, v64, v66
	v_add_f32_e32 v64, v65, v64
	ds_bpermute_b32 v65, v176, v64
	v_pk_mul_f32 v[84:85], v[106:107], v[148:149]
	v_mov_b32_e32 v80, v148
	v_pk_mul_f32 v[84:85], v[116:117], v[84:85]
	v_mov_b32_e32 v81, v148
	v_pk_mul_f32 v[70:71], v[112:113], v[84:85]
	s_waitcnt lgkmcnt(0)
	v_add_f32_e32 v84, v64, v65
	ds_bpermute_b32 v85, v187, v84
	v_pk_mul_f32 v[82:83], v[104:105], v[80:81]
	v_pk_mul_f32 v[104:105], v[96:97], v[144:145]
	v_pk_mul_f32 v[106:107], v[112:113], v[146:147]
	v_pk_mul_f32 v[110:111], v[112:113], v[152:153]
	s_waitcnt lgkmcnt(0)
	v_add_f32_e32 v84, v84, v85
	v_fmamk_f32 v84, v84, 0x3c800000, v240
	v_mul_f32_e32 v85, 0x4f800000, v84
	v_cmp_gt_f32_e32 vcc, s83, v84
	v_cvt_pk_bf16_f32 v64, v106, v107
	v_cvt_pk_bf16_f32 v65, v104, v105
	v_cvt_pk_bf16_f32 v66, v110, v111
	v_pk_mul_f32 v[80:81], v[108:109], v[80:81]
	v_pk_mul_f32 v[108:109], v[96:97], v[150:151]
	v_cndmask_b32_e32 v84, v84, v85, vcc
	v_sqrt_f32_e32 v85, v84
	v_cvt_pk_bf16_f32 v67, v108, v109
	global_store_dwordx4 v[98:99], v[64:67], off
	v_pk_mul_f32 v[82:83], v[114:115], v[82:83]
	v_pk_mul_f32 v[80:81], v[118:119], v[80:81]
	v_add_u32_e32 v66, -1, v85
	v_fma_f32 v67, -v66, v85, v84
	v_pk_mul_f32 v[68:69], v[96:97], v[82:83]
	v_cmp_ge_f32_e64 s[8:9], 0, v67
	v_add_u32_e32 v67, 1, v85
	v_cvt_pk_bf16_f32 v64, v70, v71
	v_cvt_pk_bf16_f32 v65, v68, v69
	v_fma_f32 v68, -v67, v85, v84
	v_cndmask_b32_e64 v66, v85, v66, s[8:9]
	v_cmp_lt_f32_e64 s[8:9], 0, v68
	v_pk_mul_f32 v[80:81], v[96:97], v[80:81]
	v_pk_mul_f32 v[82:83], v[112:113], v[94:95]
	v_cndmask_b32_e64 v66, v66, v67, s[8:9]
	v_mul_f32_e32 v67, 0x37800000, v66
	v_cndmask_b32_e32 v66, v66, v67, vcc
	v_cmp_class_f32_e32 vcc, v84, v241
	s_nop 1
	v_cndmask_b32_e32 v68, v66, v84, vcc
	v_div_scale_f32 v69, s[8:9], v68, v68, 1.0
	v_rcp_f32_e32 v70, v69
	v_cvt_pk_bf16_f32 v66, v82, v83
	v_cvt_pk_bf16_f32 v67, v80, v81
	global_store_dwordx4 v[98:99], v[64:67], off offset:64
	v_lshl_add_u64 v[80:81], v[98:99], 0, s[36:37]
	v_lshl_add_u64 v[82:83], v[100:101], 0, s[34:35]
	v_fma_f32 v64, -v69, v70, 1.0
	v_fmac_f32_e32 v70, v64, v70
	v_div_scale_f32 v64, vcc, 1.0, v68, 1.0
	v_mul_f32_e32 v65, v64, v70
	v_fma_f32 v66, -v69, v65, v64
	v_fmac_f32_e32 v65, v66, v70
	v_fma_f32 v64, -v69, v65, v64
	v_div_fmas_f32 v64, v64, v70, v65
	v_div_fixup_f32 v108, v64, v68, 1.0
	v_pk_mul_f32 v[64:65], v[76:77], v[108:109] op_sel_hi:[1,0]
	v_pk_mul_f32 v[66:67], v[78:79], v[108:109] op_sel_hi:[1,0]
	v_pk_mul_f32 v[96:97], v[200:201], v[64:65]
	v_pk_mul_f32 v[94:95], v[198:199], v[66:67]
	v_pk_mul_f32 v[64:65], v[72:73], v[108:109] op_sel_hi:[1,0]
	v_pk_mul_f32 v[66:67], v[74:75], v[108:109] op_sel_hi:[1,0]
	v_pk_mul_f32 v[106:107], v[204:205], v[64:65]
	v_pk_mul_f32 v[104:105], v[202:203], v[66:67]
	ds_bpermute_b32 v126, v176, v96
	ds_bpermute_b32 v124, v176, v106
	ds_bpermute_b32 v127, v176, v97
	ds_bpermute_b32 v125, v176, v107
	ds_bpermute_b32 v122, v176, v94
	ds_bpermute_b32 v110, v176, v104
	ds_bpermute_b32 v123, v176, v95
	ds_bpermute_b32 v111, v176, v105
	v_lshl_add_u64 v[84:85], v[102:103], 0, s[26:27]
	s_and_saveexec_b64 s[8:9], s[6:7]
	s_cbranch_execz .LBB0_683
	global_load_dwordx4 v[76:79], v[82:83], off offset:32
	global_load_dwordx4 v[68:71], v[82:83], off offset:48
	global_load_dwordx4 v[72:75], v[82:83], off
	global_load_dwordx4 v[64:67], v[82:83], off offset:16
	s_waitcnt vmcnt(0) lgkmcnt(0)
	v_pk_mul_f32 v[76:77], v[76:77], v[126:127]
	v_pk_mul_f32 v[68:69], v[68:69], v[124:125]
	s_and_saveexec_b64 s[52:53], s[4:5]
	s_xor_b64 s[52:53], exec, s[52:53]
	v_pk_mul_f32 v[78:79], v[78:79], v[122:123]
	v_pk_mul_f32 v[70:71], v[70:71], v[110:111]
	v_pk_fma_f32 v[94:95], v[74:75], v[94:95], v[78:79]
	v_pk_fma_f32 v[96:97], v[72:73], v[96:97], v[76:77]
	v_pk_fma_f32 v[104:105], v[66:67], v[104:105], v[70:71]
	v_pk_fma_f32 v[106:107], v[64:65], v[106:107], v[68:69]
	s_andn2_saveexec_b64 s[52:53], s[52:53]
	v_pk_mul_f32 v[78:79], v[78:79], v[122:123]
	v_pk_mul_f32 v[70:71], v[70:71], v[110:111]
	v_pk_fma_f32 v[94:95], v[74:75], v[94:95], v[78:79] neg_lo:[0,0,1] neg_hi:[0,0,1]
	v_pk_fma_f32 v[96:97], v[72:73], v[96:97], v[76:77] neg_lo:[0,0,1] neg_hi:[0,0,1]
	v_pk_fma_f32 v[104:105], v[66:67], v[104:105], v[70:71] neg_lo:[0,0,1] neg_hi:[0,0,1]
	v_pk_fma_f32 v[106:107], v[64:65], v[106:107], v[68:69] neg_lo:[0,0,1] neg_hi:[0,0,1]
	s_or_b64 exec, exec, s[52:53]
; __device__ __forceinline__ u32x4 pack8(const f32x4& v0, const f32x4& v1) { u32x4 w; w.x = cvt_pk_bf16(v0[0], v0[1]); w.y = cvt_pk_bf16(v0[2], v0[3]); w.z = cvt_pk_bf16(v1[0], v1[1]); w.w = cvt_pk_bf16(v1[2], v1[3]); return w; }
;     __device__ __forceinline__ void operator()(const f32x4 (&acc)[2][2][4][2], const Unit& u, int wr, int wc, int fr_, int fq_) const {
;     ...
;                     asm volatile("" : "+v"(rp), "+v"(cp), "+v"(sp));
;                     const float rs = rsv[ai * 4 + m];
;                     f32x4 v00 = acc[ai][0][m][0] * rs + b00, v01 = acc[ai][0][m][1] * rs + b01, v10 = acc[ai][1][m][0] * rs + b10, v11 = acc[ai][1][m][1] * rs + b11;
;                     float ss = 0.f;
; #pragma unroll
;                     for (int k = 0; k < 4; ++k) ss += v00[k] * v00[k] + v01[k] * v01[k] + v10[k] * v10[k] + v11[k] * v11[k];
;                     ss += __shfl_xor(ss, 16); ss += __shfl_xor(ss, 32);
;                     const float rstd = 1.0f / sqrtf(ss * (1.0f / 64.0f) + 1e-6f);
;                     v00 = v00 * rstd * g[0][0]; v01 = v01 * rstd * g[0][1]; v10 = v10 * rstd * g[1][0]; v11 = v11 * rstd * g[1][1];
;                     f32x4 p0, p1;
; #pragma unroll
;                     for (int k = 0; k < 4; ++k) { p0[k] = __shfl_xor(v00[k], 16); p1[k] = __shfl_xor(v01[k], 16); }
;                     const f32x4 c0 = *(const f32x4*)(cp), c1 = *(const f32x4*)(cp + 4), s0 = *(const f32x4*)(cp + 8), s1 = *(const f32x4*)(cp + 12);
;                     if (fq < 2) {
;                         if (fq == 0) { v00 = v00 * c0 - p0 * s0; v01 = v01 * c1 - p1 * s1; } else { v00 = p0 * s0 + v00 * c0; v01 = p1 * s1 + v01 * c1; } }
;                     v00 = v00 * sc; v01 = v01 * sc; v10 = v10 * sc; v11 = v11 * sc;
;                     *(u32x4*)rp = pack8(v00, v01); *(u32x4*)(rp + 32) = pack8(v10, v11);
;                     const int adv = (m == 3) ? (128 - 48) : 16; rp += (size_t)adv * 1024; cp += (size_t)adv * 16; sp += adv; }
.LBB0_683:
	s_or_b64 exec, exec, s[8:9]
	v_pk_fma_f32 v[56:57], v[56:57], v[192:193], v[136:137] op_sel_hi:[1,0,1]
	v_pk_fma_f32 v[60:61], v[60:61], v[192:193], v[140:141] op_sel_hi:[1,0,1]
	v_pk_fma_f32 v[58:59], v[58:59], v[192:193], v[138:139] op_sel_hi:[1,0,1]
	v_pk_fma_f32 v[76:77], v[50:51], v[192:193], v[130:131] op_sel_hi:[1,0,1]
	v_pk_mul_f32 v[50:51], v[56:57], v[56:57]
	v_pk_fma_f32 v[62:63], v[62:63], v[192:193], v[142:143] op_sel_hi:[1,0,1]
	v_pk_fma_f32 v[74:75], v[52:53], v[192:193], v[132:133] op_sel_hi:[1,0,1]
	v_pk_fma_f32 v[78:79], v[48:49], v[192:193], v[128:129] op_sel_hi:[1,0,1]
	v_pk_mul_f32 v[48:49], v[58:59], v[58:59]
	v_pk_fma_f32 v[50:51], v[60:61], v[60:61], v[50:51]
	v_pk_fma_f32 v[72:73], v[54:55], v[192:193], v[134:135] op_sel_hi:[1,0,1]
	v_pk_fma_f32 v[48:49], v[62:63], v[62:63], v[48:49]
	v_pk_fma_f32 v[50:51], v[74:75], v[74:75], v[50:51]
	v_pk_fma_f32 v[48:49], v[72:73], v[72:73], v[48:49]
	v_pk_fma_f32 v[50:51], v[78:79], v[78:79], v[50:51]
	v_pk_fma_f32 v[48:49], v[76:77], v[76:77], v[48:49]
	v_add_f32_e32 v50, v50, v51
	v_add_f32_e32 v48, v48, v50
	v_add_f32_e32 v48, v49, v48
	ds_bpermute_b32 v49, v176, v48
	v_mov_b32_e32 v109, v108
	v_pk_mul_f32 v[68:69], v[92:93], v[108:109]
	v_pk_mul_f32 v[70:71], v[90:91], v[108:109]
	v_pk_mul_f32 v[68:69], v[116:117], v[68:69]
	v_pk_mul_f32 v[70:71], v[120:121], v[70:71]
	v_pk_mul_f32 v[54:55], v[112:113], v[68:69]
	v_pk_mul_f32 v[68:69], v[112:113], v[70:71]
	s_waitcnt lgkmcnt(0)
	v_add_f32_e32 v70, v48, v49
	ds_bpermute_b32 v71, v187, v70
	v_mov_b32_e32 v64, v108
	v_mov_b32_e32 v65, v108
	v_pk_mul_f32 v[66:67], v[88:89], v[64:65]
	v_pk_mul_f32 v[64:65], v[86:87], v[64:65]
	s_waitcnt lgkmcnt(0)
	v_add_f32_e32 v70, v70, v71
	v_fmamk_f32 v70, v70, 0x3c800000, v240
	v_mul_f32_e32 v71, 0x4f800000, v70
	v_cmp_gt_f32_e32 vcc, s83, v70
	v_pk_mul_f32 v[86:87], v[118:119], v[64:65]
	v_mov_b32_e32 v64, v112
	v_cndmask_b32_e32 v70, v70, v71, vcc
	v_sqrt_f32_e32 v71, v70
	v_mov_b32_e32 v65, v112
	v_pk_mul_f32 v[88:89], v[64:65], v[94:95]
	v_pk_mul_f32 v[90:91], v[112:113], v[96:97]
	v_pk_mul_f32 v[94:95], v[112:113], v[106:107]
	v_cvt_pk_bf16_f32 v48, v90, v91
	v_cvt_pk_bf16_f32 v49, v88, v89
	v_pk_mul_f32 v[92:93], v[64:65], v[104:105]
	v_cvt_pk_bf16_f32 v50, v94, v95
	v_pk_mul_f32 v[66:67], v[114:115], v[66:67]
	v_cvt_pk_bf16_f32 v51, v92, v93
	global_store_dwordx4 v[80:81], v[48:51], off
	v_pk_mul_f32 v[52:53], v[64:65], v[66:67]
	v_pk_mul_f32 v[66:67], v[64:65], v[86:87]
	v_add_u32_e32 v50, -1, v71
	v_fma_f32 v51, -v50, v71, v70
	v_cmp_ge_f32_e64 s[8:9], 0, v51
	v_add_u32_e32 v51, 1, v71
	v_cvt_pk_bf16_f32 v48, v54, v55
	v_cvt_pk_bf16_f32 v49, v52, v53
	v_fma_f32 v52, -v51, v71, v70
	v_cndmask_b32_e64 v50, v71, v50, s[8:9]
	v_cmp_lt_f32_e64 s[8:9], 0, v52
	s_nop 1
	v_cndmask_b32_e64 v50, v50, v51, s[8:9]
	v_mul_f32_e32 v51, 0x37800000, v50
	v_cndmask_b32_e32 v50, v50, v51, vcc
	v_cmp_class_f32_e32 vcc, v70, v241
	s_nop 1
	v_cndmask_b32_e32 v52, v50, v70, vcc
	v_div_scale_f32 v53, s[8:9], v52, v52, 1.0
	v_rcp_f32_e32 v54, v53
	v_cvt_pk_bf16_f32 v50, v68, v69
	v_cvt_pk_bf16_f32 v51, v66, v67
	global_store_dwordx4 v[80:81], v[48:51], off offset:64
	v_lshl_add_u64 v[66:67], v[80:81], 0, s[38:39]
	v_lshl_add_u64 v[68:69], v[82:83], 0, s[40:41]
	v_fma_f32 v48, -v53, v54, 1.0
	v_fmac_f32_e32 v54, v48, v54
	v_div_scale_f32 v48, vcc, 1.0, v52, 1.0
	v_mul_f32_e32 v49, v48, v54
	v_fma_f32 v50, -v53, v49, v48
	v_fmac_f32_e32 v49, v50, v54
	v_fma_f32 v48, -v53, v49, v48
	v_div_fmas_f32 v48, v48, v54, v49
	v_div_fixup_f32 v90, v48, v52, 1.0
	v_pk_mul_f32 v[48:49], v[60:61], v[90:91] op_sel_hi:[1,0]
	v_pk_mul_f32 v[50:51], v[62:63], v[90:91] op_sel_hi:[1,0]
	v_pk_mul_f32 v[88:89], v[200:201], v[48:49]
	v_pk_mul_f32 v[86:87], v[198:199], v[50:51]
	v_pk_mul_f32 v[48:49], v[56:57], v[90:91] op_sel_hi:[1,0]
	v_pk_mul_f32 v[50:51], v[58:59], v[90:91] op_sel_hi:[1,0]
	v_pk_mul_f32 v[94:95], v[204:205], v[48:49]
	v_pk_mul_f32 v[92:93], v[202:203], v[50:51]
	ds_bpermute_b32 v102, v176, v88
	ds_bpermute_b32 v100, v176, v94
	ds_bpermute_b32 v103, v176, v89
	ds_bpermute_b32 v101, v176, v95
	ds_bpermute_b32 v98, v176, v86
	ds_bpermute_b32 v96, v176, v92
	ds_bpermute_b32 v99, v176, v87
	ds_bpermute_b32 v97, v176, v93
	v_lshl_add_u64 v[70:71], v[84:85], 0, s[42:43]
	s_and_saveexec_b64 s[8:9], s[6:7]
	s_cbranch_execz .LBB0_689
	global_load_dwordx4 v[60:63], v[68:69], off offset:32
	global_load_dwordx4 v[52:55], v[68:69], off offset:48
	global_load_dwordx4 v[56:59], v[68:69], off
	global_load_dwordx4 v[48:51], v[68:69], off offset:16
	s_waitcnt vmcnt(0) lgkmcnt(0)
	v_pk_mul_f32 v[60:61], v[60:61], v[102:103]
	v_pk_mul_f32 v[52:53], v[52:53], v[100:101]
	s_and_saveexec_b64 s[52:53], s[4:5]
	s_xor_b64 s[52:53], exec, s[52:53]
	v_pk_mul_f32 v[62:63], v[62:63], v[98:99]
	v_pk_mul_f32 v[54:55], v[54:55], v[96:97]
	v_pk_fma_f32 v[86:87], v[58:59], v[86:87], v[62:63]
	v_pk_fma_f32 v[88:89], v[56:57], v[88:89], v[60:61]
	v_pk_fma_f32 v[92:93], v[50:51], v[92:93], v[54:55]
	v_pk_fma_f32 v[94:95], v[48:49], v[94:95], v[52:53]
	s_andn2_saveexec_b64 s[52:53], s[52:53]
	v_pk_mul_f32 v[62:63], v[62:63], v[98:99]
	v_pk_mul_f32 v[54:55], v[54:55], v[96:97]
	v_pk_fma_f32 v[86:87], v[58:59], v[86:87], v[62:63] neg_lo:[0,0,1] neg_hi:[0,0,1]
	v_pk_fma_f32 v[88:89], v[56:57], v[88:89], v[60:61] neg_lo:[0,0,1] neg_hi:[0,0,1]
	v_pk_fma_f32 v[92:93], v[50:51], v[92:93], v[54:55] neg_lo:[0,0,1] neg_hi:[0,0,1]
	v_pk_fma_f32 v[94:95], v[48:49], v[94:95], v[52:53] neg_lo:[0,0,1] neg_hi:[0,0,1]
	s_or_b64 exec, exec, s[52:53]
; __device__ __forceinline__ u32x4 pack8(const f32x4& v0, const f32x4& v1) { u32x4 w; w.x = cvt_pk_bf16(v0[0], v0[1]); w.y = cvt_pk_bf16(v0[2], v0[3]); w.z = cvt_pk_bf16(v1[0], v1[1]); w.w = cvt_pk_bf16(v1[2], v1[3]); return w; }
;     __device__ __forceinline__ void operator()(const f32x4 (&acc)[2][2][4][2], const Unit& u, int wr, int wc, int fr_, int fq_) const {
;     ...
;                     asm volatile("" : "+v"(rp), "+v"(cp), "+v"(sp));
;                     const float rs = rsv[ai * 4 + m];
;                     f32x4 v00 = acc[ai][0][m][0] * rs + b00, v01 = acc[ai][0][m][1] * rs + b01, v10 = acc[ai][1][m][0] * rs + b10, v11 = acc[ai][1][m][1] * rs + b11;
;                     float ss = 0.f;
; #pragma unroll
;                     for (int k = 0; k < 4; ++k) ss += v00[k] * v00[k] + v01[k] * v01[k] + v10[k] * v10[k] + v11[k] * v11[k];
;                     ss += __shfl_xor(ss, 16); ss += __shfl_xor(ss, 32);
;                     const float rstd = 1.0f / sqrtf(ss * (1.0f / 64.0f) + 1e-6f);
;                     v00 = v00 * rstd * g[0][0]; v01 = v01 * rstd * g[0][1]; v10 = v10 * rstd * g[1][0]; v11 = v11 * rstd * g[1][1];
;                     f32x4 p0, p1;
; #pragma unroll
;                     for (int k = 0; k < 4; ++k) { p0[k] = __shfl_xor(v00[k], 16); p1[k] = __shfl_xor(v01[k], 16); }
;                     const f32x4 c0 = *(const f32x4*)(cp), c1 = *(const f32x4*)(cp + 4), s0 = *(const f32x4*)(cp + 8), s1 = *(const f32x4*)(cp + 12);
;                     if (fq < 2) {
;                         if (fq == 0) { v00 = v00 * c0 - p0 * s0; v01 = v01 * c1 - p1 * s1; } else { v00 = p0 * s0 + v00 * c0; v01 = p1 * s1 + v01 * c1; } }
;                     v00 = v00 * sc; v01 = v01 * sc; v10 = v10 * sc; v11 = v11 * sc;
;                     *(u32x4*)rp = pack8(v00, v01); *(u32x4*)(rp + 32) = pack8(v10, v11);
;                     const int adv = (m == 3) ? (128 - 48) : 16; rp += (size_t)adv * 1024; cp += (size_t)adv * 16; sp += adv; }
.LBB0_689:
	s_or_b64 exec, exec, s[8:9]
	v_mov_b32_e32 v91, v90
	v_pk_mul_f32 v[54:55], v[78:79], v[90:91]
	v_pk_fma_f32 v[40:41], v[40:41], v[190:191], v[136:137] op_sel_hi:[1,0,1]
	v_pk_mul_f32 v[62:63], v[120:121], v[54:55]
	v_pk_fma_f32 v[44:45], v[44:45], v[190:191], v[140:141] op_sel_hi:[1,0,1]
	v_pk_fma_f32 v[42:43], v[42:43], v[190:191], v[138:139] op_sel_hi:[1,0,1]
	v_pk_fma_f32 v[54:55], v[34:35], v[190:191], v[130:131] op_sel_hi:[1,0,1]
	v_pk_mul_f32 v[34:35], v[40:41], v[40:41]
	v_pk_fma_f32 v[46:47], v[46:47], v[190:191], v[142:143] op_sel_hi:[1,0,1]
	v_pk_fma_f32 v[60:61], v[36:37], v[190:191], v[132:133] op_sel_hi:[1,0,1]
	v_pk_fma_f32 v[58:59], v[32:33], v[190:191], v[128:129] op_sel_hi:[1,0,1]
	v_pk_mul_f32 v[32:33], v[42:43], v[42:43]
	v_pk_fma_f32 v[34:35], v[44:45], v[44:45], v[34:35]
	v_pk_fma_f32 v[56:57], v[38:39], v[190:191], v[134:135] op_sel_hi:[1,0,1]
	v_pk_fma_f32 v[32:33], v[46:47], v[46:47], v[32:33]
	v_pk_fma_f32 v[34:35], v[60:61], v[60:61], v[34:35]
	v_pk_fma_f32 v[32:33], v[56:57], v[56:57], v[32:33]
	v_pk_fma_f32 v[34:35], v[58:59], v[58:59], v[34:35]
	v_pk_fma_f32 v[32:33], v[54:55], v[54:55], v[32:33]
	v_add_f32_e32 v34, v34, v35
	v_add_f32_e32 v32, v32, v34
	v_add_f32_e32 v32, v33, v32
	ds_bpermute_b32 v33, v176, v32
	v_pk_mul_f32 v[52:53], v[74:75], v[90:91]
	v_mov_b32_e32 v48, v90
	v_pk_mul_f32 v[52:53], v[116:117], v[52:53]
	v_mov_b32_e32 v49, v90
	v_pk_mul_f32 v[38:39], v[112:113], v[52:53]
	s_waitcnt lgkmcnt(0)
	v_add_f32_e32 v52, v32, v33
	ds_bpermute_b32 v53, v187, v52
	v_pk_mul_f32 v[50:51], v[72:73], v[48:49]
	v_pk_mul_f32 v[72:73], v[64:65], v[86:87]
	v_pk_mul_f32 v[74:75], v[112:113], v[88:89]
	v_pk_mul_f32 v[78:79], v[112:113], v[94:95]
	s_waitcnt lgkmcnt(0)
	v_add_f32_e32 v52, v52, v53
	v_fmamk_f32 v52, v52, 0x3c800000, v240
	v_mul_f32_e32 v53, 0x4f800000, v52
	v_cmp_gt_f32_e32 vcc, s83, v52
	v_cvt_pk_bf16_f32 v32, v74, v75
	v_cvt_pk_bf16_f32 v33, v72, v73
	v_cvt_pk_bf16_f32 v34, v78, v79
	v_pk_mul_f32 v[48:49], v[76:77], v[48:49]
	v_pk_mul_f32 v[76:77], v[64:65], v[92:93]
	v_cndmask_b32_e32 v52, v52, v53, vcc
	v_sqrt_f32_e32 v53, v52
	v_cvt_pk_bf16_f32 v35, v76, v77
	global_store_dwordx4 v[66:67], v[32:35], off
	v_pk_mul_f32 v[50:51], v[114:115], v[50:51]
	v_pk_mul_f32 v[48:49], v[118:119], v[48:49]
	v_add_u32_e32 v34, -1, v53
	v_fma_f32 v35, -v34, v53, v52
	v_pk_mul_f32 v[36:37], v[64:65], v[50:51]
	v_cmp_ge_f32_e64 s[8:9], 0, v35
	v_add_u32_e32 v35, 1, v53
	v_cvt_pk_bf16_f32 v32, v38, v39
	v_cvt_pk_bf16_f32 v33, v36, v37
	v_fma_f32 v36, -v35, v53, v52
	v_cndmask_b32_e64 v34, v53, v34, s[8:9]
	v_cmp_lt_f32_e64 s[8:9], 0, v36
	v_pk_mul_f32 v[48:49], v[64:65], v[48:49]
	v_pk_mul_f32 v[50:51], v[112:113], v[62:63]
	v_cndmask_b32_e64 v34, v34, v35, s[8:9]
	v_mul_f32_e32 v35, 0x37800000, v34
	v_cndmask_b32_e32 v34, v34, v35, vcc
	v_cmp_class_f32_e32 vcc, v52, v241
	s_nop 1
	v_cndmask_b32_e32 v36, v34, v52, vcc
	v_div_scale_f32 v37, s[8:9], v36, v36, 1.0
	v_rcp_f32_e32 v38, v37
	v_cvt_pk_bf16_f32 v34, v50, v51
	v_cvt_pk_bf16_f32 v35, v48, v49
	global_store_dwordx4 v[66:67], v[32:35], off offset:64
	v_lshl_add_u64 v[48:49], v[66:67], 0, s[36:37]
	v_lshl_add_u64 v[50:51], v[68:69], 0, s[34:35]
	v_fma_f32 v32, -v37, v38, 1.0
	v_fmac_f32_e32 v38, v32, v38
	v_div_scale_f32 v32, vcc, 1.0, v36, 1.0
	v_mul_f32_e32 v33, v32, v38
	v_fma_f32 v34, -v37, v33, v32
	v_fmac_f32_e32 v33, v34, v38
	v_fma_f32 v32, -v37, v33, v32
	v_div_fmas_f32 v32, v32, v38, v33
	v_div_fixup_f32 v76, v32, v36, 1.0
	v_pk_mul_f32 v[32:33], v[44:45], v[76:77] op_sel_hi:[1,0]
	v_pk_mul_f32 v[34:35], v[46:47], v[76:77] op_sel_hi:[1,0]
	v_pk_mul_f32 v[64:65], v[200:201], v[32:33]
	v_pk_mul_f32 v[62:63], v[198:199], v[34:35]
	v_pk_mul_f32 v[32:33], v[40:41], v[76:77] op_sel_hi:[1,0]
	v_pk_mul_f32 v[34:35], v[42:43], v[76:77] op_sel_hi:[1,0]
	v_pk_mul_f32 v[74:75], v[204:205], v[32:33]
	v_pk_mul_f32 v[72:73], v[202:203], v[34:35]
	ds_bpermute_b32 v84, v176, v64
	ds_bpermute_b32 v82, v176, v74
	ds_bpermute_b32 v85, v176, v65
	ds_bpermute_b32 v83, v176, v75
	ds_bpermute_b32 v80, v176, v62
	ds_bpermute_b32 v78, v176, v72
	ds_bpermute_b32 v81, v176, v63
	ds_bpermute_b32 v79, v176, v73
	v_lshl_add_u64 v[52:53], v[70:71], 0, s[26:27]
	s_and_saveexec_b64 s[8:9], s[6:7]
	s_cbranch_execz .LBB0_695
	global_load_dwordx4 v[44:47], v[50:51], off offset:32
	global_load_dwordx4 v[36:39], v[50:51], off offset:48
	global_load_dwordx4 v[40:43], v[50:51], off
	global_load_dwordx4 v[32:35], v[50:51], off offset:16
	s_waitcnt vmcnt(0) lgkmcnt(0)
	v_pk_mul_f32 v[44:45], v[44:45], v[84:85]
	v_pk_mul_f32 v[36:37], v[36:37], v[82:83]
	s_and_saveexec_b64 s[52:53], s[4:5]
	s_xor_b64 s[52:53], exec, s[52:53]
	v_pk_mul_f32 v[46:47], v[46:47], v[80:81]
	v_pk_mul_f32 v[38:39], v[38:39], v[78:79]
	v_pk_fma_f32 v[62:63], v[42:43], v[62:63], v[46:47]
	v_pk_fma_f32 v[64:65], v[40:41], v[64:65], v[44:45]
	v_pk_fma_f32 v[72:73], v[34:35], v[72:73], v[38:39]
	v_pk_fma_f32 v[74:75], v[32:33], v[74:75], v[36:37]
	s_andn2_saveexec_b64 s[52:53], s[52:53]
	v_pk_mul_f32 v[46:47], v[46:47], v[80:81]
	v_pk_mul_f32 v[38:39], v[38:39], v[78:79]
	v_pk_fma_f32 v[62:63], v[42:43], v[62:63], v[46:47] neg_lo:[0,0,1] neg_hi:[0,0,1]
	v_pk_fma_f32 v[64:65], v[40:41], v[64:65], v[44:45] neg_lo:[0,0,1] neg_hi:[0,0,1]
	v_pk_fma_f32 v[72:73], v[34:35], v[72:73], v[38:39] neg_lo:[0,0,1] neg_hi:[0,0,1]
	v_pk_fma_f32 v[74:75], v[32:33], v[74:75], v[36:37] neg_lo:[0,0,1] neg_hi:[0,0,1]
	s_or_b64 exec, exec, s[52:53]
; __device__ __forceinline__ u32x4 pack8(const f32x4& v0, const f32x4& v1) { u32x4 w; w.x = cvt_pk_bf16(v0[0], v0[1]); w.y = cvt_pk_bf16(v0[2], v0[3]); w.z = cvt_pk_bf16(v1[0], v1[1]); w.w = cvt_pk_bf16(v1[2], v1[3]); return w; }
;     __device__ __forceinline__ void operator()(const f32x4 (&acc)[2][2][4][2], const Unit& u, int wr, int wc, int fr_, int fq_) const {
;     ...
;                     asm volatile("" : "+v"(rp), "+v"(cp), "+v"(sp));
;                     const float rs = rsv[ai * 4 + m];
;                     f32x4 v00 = acc[ai][0][m][0] * rs + b00, v01 = acc[ai][0][m][1] * rs + b01, v10 = acc[ai][1][m][0] * rs + b10, v11 = acc[ai][1][m][1] * rs + b11;
;                     float ss = 0.f;
; #pragma unroll
;                     for (int k = 0; k < 4; ++k) ss += v00[k] * v00[k] + v01[k] * v01[k] + v10[k] * v10[k] + v11[k] * v11[k];
;                     ss += __shfl_xor(ss, 16); ss += __shfl_xor(ss, 32);
;                     const float rstd = 1.0f / sqrtf(ss * (1.0f / 64.0f) + 1e-6f);
;                     v00 = v00 * rstd * g[0][0]; v01 = v01 * rstd * g[0][1]; v10 = v10 * rstd * g[1][0]; v11 = v11 * rstd * g[1][1];
;                     f32x4 p0, p1;
; #pragma unroll
;                     for (int k = 0; k < 4; ++k) { p0[k] = __shfl_xor(v00[k], 16); p1[k] = __shfl_xor(v01[k], 16); }
;                     const f32x4 c0 = *(const f32x4*)(cp), c1 = *(const f32x4*)(cp + 4), s0 = *(const f32x4*)(cp + 8), s1 = *(const f32x4*)(cp + 12);
;                     if (fq < 2) {
;                         if (fq == 0) { v00 = v00 * c0 - p0 * s0; v01 = v01 * c1 - p1 * s1; } else { v00 = p0 * s0 + v00 * c0; v01 = p1 * s1 + v01 * c1; } }
;                     v00 = v00 * sc; v01 = v01 * sc; v10 = v10 * sc; v11 = v11 * sc;
;                     *(u32x4*)rp = pack8(v00, v01); *(u32x4*)(rp + 32) = pack8(v10, v11);
;                     const int adv = (m == 3) ? (128 - 48) : 16; rp += (size_t)adv * 1024; cp += (size_t)adv * 16; sp += adv; }
.LBB0_695:
	s_or_b64 exec, exec, s[8:9]
	v_pk_fma_f32 v[24:25], v[24:25], v[188:189], v[136:137] op_sel_hi:[1,0,1]
	v_pk_fma_f32 v[28:29], v[28:29], v[188:189], v[140:141] op_sel_hi:[1,0,1]
	v_pk_fma_f32 v[26:27], v[26:27], v[188:189], v[138:139] op_sel_hi:[1,0,1]
	v_pk_fma_f32 v[44:45], v[18:19], v[188:189], v[130:131] op_sel_hi:[1,0,1]
	v_pk_mul_f32 v[18:19], v[24:25], v[24:25]
	v_pk_fma_f32 v[30:31], v[30:31], v[188:189], v[142:143] op_sel_hi:[1,0,1]
	v_pk_fma_f32 v[42:43], v[20:21], v[188:189], v[132:133] op_sel_hi:[1,0,1]
	v_pk_fma_f32 v[46:47], v[16:17], v[188:189], v[128:129] op_sel_hi:[1,0,1]
	v_pk_mul_f32 v[16:17], v[26:27], v[26:27]
	v_pk_fma_f32 v[18:19], v[28:29], v[28:29], v[18:19]
	v_pk_fma_f32 v[40:41], v[22:23], v[188:189], v[134:135] op_sel_hi:[1,0,1]
	v_pk_fma_f32 v[16:17], v[30:31], v[30:31], v[16:17]
	v_pk_fma_f32 v[18:19], v[42:43], v[42:43], v[18:19]
	v_pk_fma_f32 v[16:17], v[40:41], v[40:41], v[16:17]
	v_pk_fma_f32 v[18:19], v[46:47], v[46:47], v[18:19]
	v_pk_fma_f32 v[16:17], v[44:45], v[44:45], v[16:17]
	v_add_f32_e32 v18, v18, v19
	v_add_f32_e32 v16, v16, v18
	v_add_f32_e32 v16, v17, v16
	ds_bpermute_b32 v17, v176, v16
	v_mov_b32_e32 v77, v76
	v_pk_mul_f32 v[36:37], v[60:61], v[76:77]
	v_pk_mul_f32 v[38:39], v[58:59], v[76:77]
	v_pk_mul_f32 v[36:37], v[116:117], v[36:37]
	v_pk_mul_f32 v[38:39], v[120:121], v[38:39]
	v_pk_mul_f32 v[22:23], v[112:113], v[36:37]
	v_pk_mul_f32 v[36:37], v[112:113], v[38:39]
	s_waitcnt lgkmcnt(0)
	v_add_f32_e32 v38, v16, v17
	ds_bpermute_b32 v39, v187, v38
	v_mov_b32_e32 v32, v76
	v_mov_b32_e32 v33, v76
	v_pk_mul_f32 v[34:35], v[56:57], v[32:33]
	v_pk_mul_f32 v[32:33], v[54:55], v[32:33]
	s_waitcnt lgkmcnt(0)
	v_add_f32_e32 v38, v38, v39
	v_fmamk_f32 v38, v38, 0x3c800000, v240
	v_mul_f32_e32 v39, 0x4f800000, v38
	v_cmp_gt_f32_e32 vcc, s83, v38
	v_pk_mul_f32 v[54:55], v[118:119], v[32:33]
	v_mov_b32_e32 v32, v112
	v_cndmask_b32_e32 v38, v38, v39, vcc
	v_sqrt_f32_e32 v39, v38
	v_mov_b32_e32 v33, v112
	v_pk_mul_f32 v[56:57], v[32:33], v[62:63]
	v_pk_mul_f32 v[58:59], v[112:113], v[64:65]
	v_pk_mul_f32 v[62:63], v[112:113], v[74:75]
	v_cvt_pk_bf16_f32 v16, v58, v59
	v_cvt_pk_bf16_f32 v17, v56, v57
	v_pk_mul_f32 v[60:61], v[32:33], v[72:73]
	v_cvt_pk_bf16_f32 v18, v62, v63
	v_pk_mul_f32 v[34:35], v[114:115], v[34:35]
	v_cvt_pk_bf16_f32 v19, v60, v61
	global_store_dwordx4 v[48:49], v[16:19], off
	v_pk_mul_f32 v[20:21], v[32:33], v[34:35]
	v_pk_mul_f32 v[34:35], v[32:33], v[54:55]
	v_add_u32_e32 v18, -1, v39
	v_fma_f32 v19, -v18, v39, v38
	v_cmp_ge_f32_e64 s[8:9], 0, v19
	v_add_u32_e32 v19, 1, v39
	v_cvt_pk_bf16_f32 v16, v22, v23
	v_cvt_pk_bf16_f32 v17, v20, v21
	v_fma_f32 v20, -v19, v39, v38
	v_cndmask_b32_e64 v18, v39, v18, s[8:9]
	v_cmp_lt_f32_e64 s[8:9], 0, v20
	s_nop 1
	v_cndmask_b32_e64 v18, v18, v19, s[8:9]
	v_mul_f32_e32 v19, 0x37800000, v18
	v_cndmask_b32_e32 v18, v18, v19, vcc
	v_cmp_class_f32_e32 vcc, v38, v241
	s_nop 1
	v_cndmask_b32_e32 v20, v18, v38, vcc
	v_div_scale_f32 v21, s[8:9], v20, v20, 1.0
	v_rcp_f32_e32 v22, v21
	v_cvt_pk_bf16_f32 v18, v36, v37
	v_cvt_pk_bf16_f32 v19, v34, v35
	global_store_dwordx4 v[48:49], v[16:19], off offset:64
	v_lshl_add_u64 v[34:35], v[48:49], 0, s[36:37]
	v_lshl_add_u64 v[36:37], v[50:51], 0, s[34:35]
	v_fma_f32 v16, -v21, v22, 1.0
	v_fmac_f32_e32 v22, v16, v22
	v_div_scale_f32 v16, vcc, 1.0, v20, 1.0
	v_mul_f32_e32 v17, v16, v22
	v_fma_f32 v18, -v21, v17, v16
	v_fmac_f32_e32 v17, v18, v22
	v_fma_f32 v16, -v21, v17, v16
	v_div_fmas_f32 v16, v16, v22, v17
	v_div_fixup_f32 v58, v16, v20, 1.0
	v_pk_mul_f32 v[16:17], v[28:29], v[58:59] op_sel_hi:[1,0]
	v_pk_mul_f32 v[18:19], v[30:31], v[58:59] op_sel_hi:[1,0]
	v_pk_mul_f32 v[56:57], v[200:201], v[16:17]
	v_pk_mul_f32 v[54:55], v[198:199], v[18:19]
	v_pk_mul_f32 v[16:17], v[24:25], v[58:59] op_sel_hi:[1,0]
	v_pk_mul_f32 v[18:19], v[26:27], v[58:59] op_sel_hi:[1,0]
	v_pk_mul_f32 v[62:63], v[204:205], v[16:17]
	v_pk_mul_f32 v[60:61], v[202:203], v[18:19]
	ds_bpermute_b32 v70, v176, v56
	ds_bpermute_b32 v68, v176, v62
	ds_bpermute_b32 v71, v176, v57
	ds_bpermute_b32 v69, v176, v63
	ds_bpermute_b32 v66, v176, v54
	ds_bpermute_b32 v64, v176, v60
	ds_bpermute_b32 v67, v176, v55
	ds_bpermute_b32 v65, v176, v61
	v_lshl_add_u64 v[38:39], v[52:53], 0, s[26:27]
	s_and_saveexec_b64 s[8:9], s[6:7]
	s_cbranch_execz .LBB0_701
	global_load_dwordx4 v[28:31], v[36:37], off offset:32
	global_load_dwordx4 v[20:23], v[36:37], off offset:48
	global_load_dwordx4 v[24:27], v[36:37], off
	global_load_dwordx4 v[16:19], v[36:37], off offset:16
	s_waitcnt vmcnt(0) lgkmcnt(0)
	v_pk_mul_f32 v[28:29], v[28:29], v[70:71]
	v_pk_mul_f32 v[20:21], v[20:21], v[68:69]
	s_and_saveexec_b64 s[52:53], s[4:5]
	s_xor_b64 s[52:53], exec, s[52:53]
	v_pk_mul_f32 v[30:31], v[30:31], v[66:67]
	v_pk_mul_f32 v[22:23], v[22:23], v[64:65]
	v_pk_fma_f32 v[54:55], v[26:27], v[54:55], v[30:31]
	v_pk_fma_f32 v[56:57], v[24:25], v[56:57], v[28:29]
	v_pk_fma_f32 v[60:61], v[18:19], v[60:61], v[22:23]
	v_pk_fma_f32 v[62:63], v[16:17], v[62:63], v[20:21]
	s_andn2_saveexec_b64 s[52:53], s[52:53]
	v_pk_mul_f32 v[30:31], v[30:31], v[66:67]
	v_pk_mul_f32 v[22:23], v[22:23], v[64:65]
	v_pk_fma_f32 v[54:55], v[26:27], v[54:55], v[30:31] neg_lo:[0,0,1] neg_hi:[0,0,1]
	v_pk_fma_f32 v[56:57], v[24:25], v[56:57], v[28:29] neg_lo:[0,0,1] neg_hi:[0,0,1]
	v_pk_fma_f32 v[60:61], v[18:19], v[60:61], v[22:23] neg_lo:[0,0,1] neg_hi:[0,0,1]
	v_pk_fma_f32 v[62:63], v[16:17], v[62:63], v[20:21] neg_lo:[0,0,1] neg_hi:[0,0,1]
	s_or_b64 exec, exec, s[52:53]
; __device__ __forceinline__ u32x4 pack8(const f32x4& v0, const f32x4& v1) { u32x4 w; w.x = cvt_pk_bf16(v0[0], v0[1]); w.y = cvt_pk_bf16(v0[2], v0[3]); w.z = cvt_pk_bf16(v1[0], v1[1]); w.w = cvt_pk_bf16(v1[2], v1[3]); return w; }
;     __device__ __forceinline__ void operator()(const f32x4 (&acc)[2][2][4][2], const Unit& u, int wr, int wc, int fr_, int fq_) const {
;     ...
;                     asm volatile("" : "+v"(rp), "+v"(cp), "+v"(sp));
;                     const float rs = rsv[ai * 4 + m];
;                     f32x4 v00 = acc[ai][0][m][0] * rs + b00, v01 = acc[ai][0][m][1] * rs + b01, v10 = acc[ai][1][m][0] * rs + b10, v11 = acc[ai][1][m][1] * rs + b11;
;                     float ss = 0.f;
; #pragma unroll
;                     for (int k = 0; k < 4; ++k) ss += v00[k] * v00[k] + v01[k] * v01[k] + v10[k] * v10[k] + v11[k] * v11[k];
;                     ss += __shfl_xor(ss, 16); ss += __shfl_xor(ss, 32);
;                     const float rstd = 1.0f / sqrtf(ss * (1.0f / 64.0f) + 1e-6f);
;                     v00 = v00 * rstd * g[0][0]; v01 = v01 * rstd * g[0][1]; v10 = v10 * rstd * g[1][0]; v11 = v11 * rstd * g[1][1];
;                     f32x4 p0, p1;
; #pragma unroll
;                     for (int k = 0; k < 4; ++k) { p0[k] = __shfl_xor(v00[k], 16); p1[k] = __shfl_xor(v01[k], 16); }
;                     const f32x4 c0 = *(const f32x4*)(cp), c1 = *(const f32x4*)(cp + 4), s0 = *(const f32x4*)(cp + 8), s1 = *(const f32x4*)(cp + 12);
;                     if (fq < 2) {
;                         if (fq == 0) { v00 = v00 * c0 - p0 * s0; v01 = v01 * c1 - p1 * s1; } else { v00 = p0 * s0 + v00 * c0; v01 = p1 * s1 + v01 * c1; } }
;                     v00 = v00 * sc; v01 = v01 * sc; v10 = v10 * sc; v11 = v11 * sc;
;                     *(u32x4*)rp = pack8(v00, v01); *(u32x4*)(rp + 32) = pack8(v10, v11);
;                     const int adv = (m == 3) ? (128 - 48) : 16; rp += (size_t)adv * 1024; cp += (size_t)adv * 16; sp += adv; }
.LBB0_701:
	s_or_b64 exec, exec, s[8:9]
	v_mov_b32_e32 v16, v58
	v_mov_b32_e32 v17, v58
	v_mov_b32_e32 v59, v58
	v_pk_mul_f32 v[18:19], v[40:41], v[16:17]
	v_pk_mul_f32 v[16:17], v[44:45], v[16:17]
	v_pk_fma_f32 v[8:9], v[8:9], v[186:187], v[136:137] op_sel_hi:[1,0,1]
	v_pk_mul_f32 v[20:21], v[42:43], v[58:59]
	v_pk_mul_f32 v[22:23], v[46:47], v[58:59]
	v_pk_mul_f32 v[28:29], v[118:119], v[16:17]
	v_pk_fma_f32 v[12:13], v[12:13], v[186:187], v[140:141] op_sel_hi:[1,0,1]
	v_pk_fma_f32 v[10:11], v[10:11], v[186:187], v[138:139] op_sel_hi:[1,0,1]
	v_pk_fma_f32 v[16:17], v[2:3], v[186:187], v[130:131] op_sel_hi:[1,0,1]
	v_pk_mul_f32 v[2:3], v[8:9], v[8:9]
	v_pk_mul_f32 v[26:27], v[116:117], v[20:21]
	v_pk_mul_f32 v[30:31], v[120:121], v[22:23]
	v_pk_fma_f32 v[14:15], v[14:15], v[186:187], v[142:143] op_sel_hi:[1,0,1]
	v_pk_fma_f32 v[22:23], v[4:5], v[186:187], v[132:133] op_sel_hi:[1,0,1]
	v_pk_fma_f32 v[20:21], v[0:1], v[186:187], v[128:129] op_sel_hi:[1,0,1]
	v_pk_mul_f32 v[0:1], v[10:11], v[10:11]
	v_pk_fma_f32 v[2:3], v[12:13], v[12:13], v[2:3]
	v_pk_mul_f32 v[24:25], v[114:115], v[18:19]
	v_pk_fma_f32 v[18:19], v[6:7], v[186:187], v[134:135] op_sel_hi:[1,0,1]
	v_pk_fma_f32 v[0:1], v[14:15], v[14:15], v[0:1]
	v_pk_fma_f32 v[2:3], v[22:23], v[22:23], v[2:3]
	v_pk_fma_f32 v[0:1], v[18:19], v[18:19], v[0:1]
	v_pk_fma_f32 v[2:3], v[20:21], v[20:21], v[2:3]
	v_pk_fma_f32 v[0:1], v[16:17], v[16:17], v[0:1]
	v_add_f32_e32 v2, v2, v3
	v_add_f32_e32 v0, v0, v2
	v_add_f32_e32 v0, v1, v0
	ds_bpermute_b32 v1, v176, v0
	v_pk_mul_f32 v[4:5], v[32:33], v[24:25]
	v_pk_mul_f32 v[24:25], v[32:33], v[28:29]
	v_pk_mul_f32 v[40:41], v[32:33], v[54:55]
	v_pk_mul_f32 v[42:43], v[112:113], v[56:57]
	s_waitcnt lgkmcnt(0)
	v_add_f32_e32 v28, v0, v1
	ds_bpermute_b32 v29, v187, v28
	v_pk_mul_f32 v[46:47], v[112:113], v[62:63]
	v_cvt_pk_bf16_f32 v0, v42, v43
	v_cvt_pk_bf16_f32 v1, v40, v41
	v_pk_mul_f32 v[44:45], v[32:33], v[60:61]
	s_waitcnt lgkmcnt(0)
	v_add_f32_e32 v28, v28, v29
	v_fmamk_f32 v28, v28, 0x3c800000, v240
	v_mul_f32_e32 v29, 0x4f800000, v28
	v_cmp_gt_f32_e32 vcc, s83, v28
	v_cvt_pk_bf16_f32 v2, v46, v47
	v_cvt_pk_bf16_f32 v3, v44, v45
	global_store_dwordx4 v[34:35], v[0:3], off
	v_pk_mul_f32 v[6:7], v[112:113], v[26:27]
	v_cndmask_b32_e32 v28, v28, v29, vcc
	v_sqrt_f32_e32 v29, v28
	v_cvt_pk_bf16_f32 v0, v6, v7
	v_cvt_pk_bf16_f32 v1, v4, v5
	v_pk_mul_f32 v[26:27], v[112:113], v[30:31]
	v_add_u32_e32 v2, -1, v29
	v_fma_f32 v3, -v2, v29, v28
	v_cmp_ge_f32_e64 s[8:9], 0, v3
	v_add_u32_e32 v3, 1, v29
	v_fma_f32 v4, -v3, v29, v28
	v_cndmask_b32_e64 v2, v29, v2, s[8:9]
	v_cmp_lt_f32_e64 s[8:9], 0, v4
	s_nop 1
	v_cndmask_b32_e64 v2, v2, v3, s[8:9]
	v_mul_f32_e32 v3, 0x37800000, v2
	v_cndmask_b32_e32 v2, v2, v3, vcc
	v_cmp_class_f32_e32 vcc, v28, v241
	s_nop 1
	v_cndmask_b32_e32 v4, v2, v28, vcc
	v_div_scale_f32 v5, s[8:9], v4, v4, 1.0
	v_rcp_f32_e32 v6, v5
	v_cvt_pk_bf16_f32 v2, v26, v27
	v_cvt_pk_bf16_f32 v3, v24, v25
	global_store_dwordx4 v[34:35], v[0:3], off offset:64
	v_lshl_add_u64 v[24:25], v[34:35], 0, s[36:37]
	s_nop 0
	v_fma_f32 v0, -v5, v6, 1.0
	v_fmac_f32_e32 v6, v0, v6
	v_div_scale_f32 v0, vcc, 1.0, v4, 1.0
	v_mul_f32_e32 v1, v0, v6
	v_fma_f32 v2, -v5, v1, v0
	v_fmac_f32_e32 v1, v2, v6
	v_fma_f32 v0, -v5, v1, v0
	v_div_fmas_f32 v0, v0, v6, v1
	v_div_fixup_f32 v40, v0, v4, 1.0
	v_pk_mul_f32 v[0:1], v[12:13], v[40:41] op_sel_hi:[1,0]
	v_pk_mul_f32 v[2:3], v[14:15], v[40:41] op_sel_hi:[1,0]
	v_pk_mul_f32 v[28:29], v[200:201], v[0:1]
	v_pk_mul_f32 v[26:27], v[198:199], v[2:3]
	v_pk_mul_f32 v[0:1], v[8:9], v[40:41] op_sel_hi:[1,0]
	v_pk_mul_f32 v[2:3], v[10:11], v[40:41] op_sel_hi:[1,0]
	v_pk_mul_f32 v[32:33], v[204:205], v[0:1]
	v_pk_mul_f32 v[30:31], v[202:203], v[2:3]
	ds_bpermute_b32 v48, v176, v28
	ds_bpermute_b32 v46, v176, v32
	ds_bpermute_b32 v49, v176, v29
	ds_bpermute_b32 v47, v176, v33
	ds_bpermute_b32 v44, v176, v26
	ds_bpermute_b32 v42, v176, v30
	ds_bpermute_b32 v45, v176, v27
	ds_bpermute_b32 v43, v176, v31
	v_lshl_add_u64 v[0:1], v[36:37], 0, s[34:35]
	v_lshl_add_u64 v[2:3], v[38:39], 0, s[26:27]
	s_and_saveexec_b64 s[8:9], s[6:7]
	s_cbranch_execz .LBB0_707
	global_load_dwordx4 v[12:15], v[0:1], off offset:32
	global_load_dwordx4 v[4:7], v[0:1], off offset:48
	global_load_dwordx4 v[8:11], v[0:1], off
	s_nop 0
	global_load_dwordx4 v[0:3], v[0:1], off offset:16
	s_waitcnt vmcnt(0) lgkmcnt(0)
	v_pk_mul_f32 v[12:13], v[12:13], v[48:49]
	v_pk_mul_f32 v[4:5], v[4:5], v[46:47]
	s_and_saveexec_b64 s[6:7], s[4:5]
	s_xor_b64 s[4:5], exec, s[6:7]
	v_pk_mul_f32 v[14:15], v[14:15], v[44:45]
	v_pk_mul_f32 v[6:7], v[6:7], v[42:43]
	v_pk_fma_f32 v[26:27], v[10:11], v[26:27], v[14:15]
	v_pk_fma_f32 v[28:29], v[8:9], v[28:29], v[12:13]
	v_pk_fma_f32 v[30:31], v[2:3], v[30:31], v[6:7]
	v_pk_fma_f32 v[32:33], v[0:1], v[32:33], v[4:5]
	s_andn2_saveexec_b64 s[4:5], s[4:5]
	v_pk_mul_f32 v[14:15], v[14:15], v[44:45]
	v_pk_mul_f32 v[6:7], v[6:7], v[42:43]
	v_pk_fma_f32 v[26:27], v[10:11], v[26:27], v[14:15] neg_lo:[0,0,1] neg_hi:[0,0,1]
	v_pk_fma_f32 v[28:29], v[8:9], v[28:29], v[12:13] neg_lo:[0,0,1] neg_hi:[0,0,1]
	v_pk_fma_f32 v[30:31], v[2:3], v[30:31], v[6:7] neg_lo:[0,0,1] neg_hi:[0,0,1]
	v_pk_fma_f32 v[32:33], v[0:1], v[32:33], v[4:5] neg_lo:[0,0,1] neg_hi:[0,0,1]
	s_or_b64 exec, exec, s[4:5]
.LBB0_707:
	s_or_b64 exec, exec, s[8:9]
	v_mov_b32_e32 v0, v40
	v_mov_b32_e32 v1, v40
	v_mov_b32_e32 v41, v40
	v_pk_mul_f32 v[2:3], v[18:19], v[0:1]
	v_pk_mul_f32 v[0:1], v[16:17], v[0:1]
	v_pk_mul_f32 v[4:5], v[22:23], v[40:41]
	v_pk_mul_f32 v[6:7], v[20:21], v[40:41]
	v_pk_mul_f32 v[2:3], v[114:115], v[2:3]
	v_pk_mul_f32 v[0:1], v[118:119], v[0:1]
	v_mov_b32_e32 v8, v112
	v_mov_b32_e32 v9, v112
	v_pk_mul_f32 v[4:5], v[116:117], v[4:5]
	v_pk_mul_f32 v[6:7], v[120:121], v[6:7]
	v_pk_mul_f32 v[10:11], v[8:9], v[26:27]
	v_pk_mul_f32 v[12:13], v[112:113], v[28:29]
	v_pk_mul_f32 v[14:15], v[8:9], v[30:31]
	v_pk_mul_f32 v[16:17], v[112:113], v[32:33]
	v_pk_mul_f32 v[18:19], v[8:9], v[2:3]
	v_pk_mul_f32 v[8:9], v[8:9], v[0:1]
	v_cvt_pk_bf16_f32 v0, v12, v13
	v_cvt_pk_bf16_f32 v1, v10, v11
	v_cvt_pk_bf16_f32 v2, v16, v17
	v_cvt_pk_bf16_f32 v3, v14, v15
	v_pk_mul_f32 v[4:5], v[112:113], v[4:5]
	v_pk_mul_f32 v[6:7], v[112:113], v[6:7]
	global_store_dwordx4 v[24:25], v[0:3], off
	s_nop 1
	v_cvt_pk_bf16_f32 v0, v4, v5
	v_cvt_pk_bf16_f32 v1, v18, v19
	v_cvt_pk_bf16_f32 v2, v6, v7
	v_cvt_pk_bf16_f32 v3, v8, v9
	global_store_dwordx4 v[24:25], v[0:3], off offset:64
	s_andn2_b64 vcc, exec, s[0:1]
	s_mov_b64 s[0:1], -1
	s_cbranch_vccnz .LBB0_580

; #define PG8_BAR __builtin_amdgcn_s_barrier()
;     __device__ __forceinline__ void operator()(const f32x4 (&acc)[2][2][4][2], const Unit& u, int wr, int wc, int fr, int fq) const {
;         const int row0 = u.pm * BM + wr * 64 + fr, col0 = u.pz * BM + wc * 32 + 4 * fq;
; #pragma unroll
;         for (int ai = 0; ai < 2; ++ai)
; #pragma unroll
;             for (int m = 0; m < 4; ++m) { const size_t off = (size_t)(row0 + ai * HALF + m * 16) * ldc + col0;
; #pragma unroll
;                 for (int bj = 0; bj < 2; ++bj)
; #pragma unroll
;                     for (int n = 0; n < 2; ++n) *(f32x4*)(out + off + bj * HALF + n * 16) = acc[ai][bj][m][n]; }
;     }
; template <class Epi, class Sched, bool ALIGN_EPI = false, bool SP2 = false>
; __device__ __forceinline__ void gemm_phase(PG8_LAS unsigned char* lds, const Gemm g, const Sched& S, const Epi& E, const int wid) {
;     ...
;         if (!has_next) break;
; #pragma unroll
;         for (int a = 0; a < 2; ++a)
; #pragma unroll
;             for (int b = 0; b < 2; ++b)
; #pragma unroll
;                 for (int m = 0; m < 4; ++m)
; #pragma unroll
;                     for (int n = 0; n < 2; ++n) acc[a][b][m][n] = (f32x4){0.f, 0.f, 0.f, 0.f};
;         cur = nxt; cA = nA; cB = nB; ++ui;
;         if constexpr (ALIGN_EPI) { if (wr == 1) PG8_BAR; }
.LBB0_776:
	v_lshl_add_u32 v150, s45, 8, v144
	v_lshl_add_u32 v152, s44, 8, v146
	v_ashrrev_i32_e32 v151, 31, v150
	v_ashrrev_i32_e32 v153, 31, v152
	v_lshlrev_b64 v[154:155], 15, v[150:151]
	v_lshl_add_u64 v[154:155], s[10:11], 0, v[154:155]
	v_lshlrev_b64 v[152:153], 2, v[152:153]
	v_lshl_add_u64 v[154:155], v[154:155], 0, v[152:153]
	global_store_dwordx4 v[154:155], v[124:127], off
	global_store_dwordx4 v[154:155], v[120:123], off offset:64
	global_store_dwordx4 v[154:155], v[108:111], off offset:512
	global_store_dwordx4 v[154:155], v[100:103], off offset:576
	s_nop 1
	v_or_b32_e32 v100, 16, v150
	v_ashrrev_i32_e32 v101, 31, v100
	v_lshlrev_b64 v[100:101], 15, v[100:101]
	v_lshl_add_u64 v[100:101], s[10:11], 0, v[100:101]
	v_lshl_add_u64 v[100:101], v[100:101], 0, v[152:153]
	global_store_dwordx4 v[100:101], v[116:119], off
	global_store_dwordx4 v[100:101], v[112:115], off offset:64
	global_store_dwordx4 v[100:101], v[92:95], off offset:512
	global_store_dwordx4 v[100:101], v[84:87], off offset:576
	s_nop 1
	v_or_b32_e32 v84, 32, v150
	v_ashrrev_i32_e32 v85, 31, v84
	v_lshlrev_b64 v[84:85], 15, v[84:85]
	v_lshl_add_u64 v[84:85], s[10:11], 0, v[84:85]
	v_lshl_add_u64 v[84:85], v[84:85], 0, v[152:153]
	global_store_dwordx4 v[84:85], v[104:107], off
	global_store_dwordx4 v[84:85], v[96:99], off offset:64
	global_store_dwordx4 v[84:85], v[76:79], off offset:512
	global_store_dwordx4 v[84:85], v[72:75], off offset:576
	s_nop 1
	v_or_b32_e32 v72, 48, v150
	v_ashrrev_i32_e32 v73, 31, v72
	v_lshlrev_b64 v[72:73], 15, v[72:73]
	v_lshl_add_u64 v[72:73], s[10:11], 0, v[72:73]
	v_lshl_add_u64 v[72:73], v[72:73], 0, v[152:153]
	global_store_dwordx4 v[72:73], v[88:91], off
	global_store_dwordx4 v[72:73], v[80:83], off offset:64
	global_store_dwordx4 v[72:73], v[68:71], off offset:512
	global_store_dwordx4 v[72:73], v[64:67], off offset:576
	s_nop 1
	v_add_co_u32_e32 v66, vcc, s53, v154
	v_lshl_add_u64 v[64:65], v[154:155], 0, s[16:17]
	s_nop 0
	v_addc_co_u32_e32 v67, vcc, 0, v155, vcc
	global_store_dwordx4 v[66:67], v[60:63], off
	global_store_dwordx4 v[64:65], v[56:59], off offset:64
	global_store_dwordx4 v[64:65], v[44:47], off offset:512
	global_store_dwordx4 v[64:65], v[36:39], off offset:576
	s_nop 1
	v_add_co_u32_e32 v38, vcc, s54, v154
	v_lshl_add_u64 v[36:37], v[154:155], 0, s[18:19]
	s_nop 0
	v_addc_co_u32_e32 v39, vcc, 0, v155, vcc
	global_store_dwordx4 v[38:39], v[52:55], off
	global_store_dwordx4 v[36:37], v[48:51], off offset:64
	global_store_dwordx4 v[36:37], v[28:31], off offset:512
	global_store_dwordx4 v[36:37], v[20:23], off offset:576
	s_nop 1
	v_add_co_u32_e32 v22, vcc, s55, v154
	v_lshl_add_u64 v[20:21], v[154:155], 0, s[20:21]
	s_nop 0
	v_addc_co_u32_e32 v23, vcc, 0, v155, vcc
	global_store_dwordx4 v[22:23], v[40:43], off
	global_store_dwordx4 v[20:21], v[32:35], off offset:64
	global_store_dwordx4 v[20:21], v[12:15], off offset:512
	global_store_dwordx4 v[20:21], v[8:11], off offset:576
	s_nop 1
	v_add_co_u32_e32 v10, vcc, 0x580000, v154
	v_lshl_add_u64 v[8:9], v[154:155], 0, s[22:23]
	s_nop 0
	v_addc_co_u32_e32 v11, vcc, 0, v155, vcc
	s_and_b64 vcc, exec, s[0:1]
	s_mov_b64 s[0:1], -1
	global_store_dwordx4 v[10:11], v[24:27], off
	global_store_dwordx4 v[8:9], v[16:19], off offset:64
	global_store_dwordx4 v[8:9], v[4:7], off offset:512
	global_store_dwordx4 v[8:9], v[0:3], off offset:576
	s_cbranch_vccnz .LBB0_765
	s_andn2_b64 vcc, exec, s[8:9]
	s_cbranch_vccnz .LBB0_764
	s_barrier
	s_branch .LBB0_764

; __global__ void __launch_bounds__(NTHR, 2) mk_fwd(Args args) {
;     ...
;             float ir = 0.f, ii = 0.f;
;             for (int w2 = 0; w2 < 32; ++w2) { if (w2 < sg) { const float lr = sl[(w2 * 2) * 16 + (lane & 15)], li = sl[(w2 * 2 + 1) * 16 + (lane & 15)]; const float nr = pr * ir - pi * ii + lr, ni = pr * ii + pi * ir + li; ir = nr; ii = ni; } }
;             sr = ir; si = ii;
;             bf16* Ug = p_UGS + (size_t)g * 384 + 256 + p + (size_t)(sg * 32) * (64 * 384);
; #pragma unroll
;             for (int cb = 0; cb < 32; cb += 16) { float er[16], ei[16];
; #pragma unroll
;                 for (int k = 0; k < 16; ++k) { er[k] = Eg[(size_t)(cb + k) * 8192]; ei[k] = Eg[(size_t)(cb + k) * 8192 + 64]; }
.LBB0_831:
	s_or_b64 exec, exec, s[76:77]
	s_mov_b64 s[76:77], 0x19608000
	v_lshl_add_u64 v[70:71], v[10:11], 0, s[76:77]
	s_mov_b64 s[76:77], 0x19608100
	v_lshl_add_u64 v[72:73], v[10:11], 0, s[76:77]
	s_mov_b64 s[76:77], 0x19610000
	v_lshl_add_u64 v[80:81], v[10:11], 0, s[76:77]
	s_mov_b64 s[76:77], 0x19610100
	v_lshl_add_u64 v[76:77], v[10:11], 0, s[76:77]
	s_mov_b64 s[76:77], 0x19618000
	v_lshl_add_u64 v[74:75], v[10:11], 0, s[76:77]
	s_mov_b64 s[76:77], 0x19618100
	v_lshl_add_u64 v[78:79], v[10:11], 0, s[76:77]
	s_mov_b64 s[76:77], 0x19620000
	v_lshl_add_u64 v[82:83], v[10:11], 0, s[76:77]
	s_mov_b64 s[76:77], 0x19620100
	v_lshl_add_u64 v[84:85], v[10:11], 0, s[76:77]
	s_mov_b64 s[76:77], 0x19628000
	v_lshl_add_u64 v[86:87], v[10:11], 0, s[76:77]
	s_mov_b64 s[76:77], 0x19628100
	v_lshl_add_u64 v[88:89], v[10:11], 0, s[76:77]
	s_mov_b64 s[76:77], 0x19630000
	v_lshl_add_u64 v[90:91], v[10:11], 0, s[76:77]
	s_mov_b64 s[76:77], 0x19630100
	v_lshl_add_u64 v[92:93], v[10:11], 0, s[76:77]
	s_mov_b64 s[76:77], 0x19638000
	v_lshl_add_u64 v[94:95], v[10:11], 0, s[76:77]
	s_mov_b64 s[76:77], 0x19638100
	v_lshl_add_u64 v[96:97], v[10:11], 0, s[76:77]
	s_mov_b64 s[76:77], 0x19640000
	v_lshl_add_u64 v[98:99], v[10:11], 0, s[76:77]
	s_mov_b64 s[76:77], 0x19640100
	v_lshl_add_u64 v[100:101], v[10:11], 0, s[76:77]
	s_mov_b64 s[76:77], 0x19648000
	v_lshl_add_u64 v[102:103], v[10:11], 0, s[76:77]
	s_mov_b64 s[76:77], 0x19648100
	v_lshl_add_u64 v[104:105], v[10:11], 0, s[76:77]
	s_mov_b64 s[76:77], 0x19650000
	v_lshl_add_u64 v[106:107], v[10:11], 0, s[76:77]
	s_mov_b64 s[76:77], 0x19650100
	v_lshl_add_u64 v[108:109], v[10:11], 0, s[76:77]
	s_mov_b64 s[76:77], 0x19658000
	v_lshl_add_u64 v[110:111], v[10:11], 0, s[76:77]
	s_mov_b64 s[76:77], 0x19658100
	v_lshl_add_u64 v[112:113], v[10:11], 0, s[76:77]
	s_mov_b64 s[76:77], 0x19660000
	v_lshl_add_u64 v[114:115], v[10:11], 0, s[76:77]
	s_mov_b64 s[76:77], 0x19660100
	v_lshl_add_u64 v[116:117], v[10:11], 0, s[76:77]
	s_mov_b64 s[76:77], 0x19668000
	v_lshl_add_u64 v[118:119], v[10:11], 0, s[76:77]
	s_mov_b64 s[76:77], 0x19668100
	v_lshl_add_u64 v[120:121], v[10:11], 0, s[76:77]
	s_mov_b64 s[76:77], 0x19670000
	v_lshl_add_u64 v[122:123], v[10:11], 0, s[76:77]
	s_mov_b64 s[76:77], 0x19670100
	v_lshl_add_u64 v[124:125], v[10:11], 0, s[76:77]
	s_mov_b64 s[76:77], 0x19678000
	v_lshl_add_u64 v[126:127], v[10:11], 0, s[76:77]
	s_mov_b64 s[76:77], 0x19678100
	v_lshl_add_u64 v[128:129], v[10:11], 0, s[76:77]
	s_mov_b64 s[76:77], 0x19680000
	v_lshl_add_u64 v[60:61], v[10:11], 0, s[76:77]
	s_mov_b64 s[76:77], 0x19680100
	v_lshl_add_u64 v[58:59], v[10:11], 0, s[76:77]
	s_mov_b64 s[76:77], 0x19688000
	v_lshl_add_u64 v[56:57], v[10:11], 0, s[76:77]
	s_mov_b64 s[76:77], 0x19688100
	v_lshl_add_u64 v[52:53], v[10:11], 0, s[76:77]
	s_mov_b64 s[76:77], 0x19690000
	v_lshl_add_u64 v[32:33], v[10:11], 0, s[76:77]
	s_mov_b64 s[76:77], 0x19690100
	v_lshl_add_u64 v[28:29], v[10:11], 0, s[76:77]
	s_mov_b64 s[76:77], 0x19698000
	v_lshl_add_u64 v[14:15], v[10:11], 0, s[76:77]
	s_mov_b64 s[76:77], 0x19698100
	v_lshl_add_u64 v[16:17], v[10:11], 0, s[76:77]
	s_mov_b64 s[76:77], 0x196a0000
	v_lshl_add_u64 v[20:21], v[10:11], 0, s[76:77]
	s_mov_b64 s[76:77], 0x196a0100
	v_lshl_add_u64 v[22:23], v[10:11], 0, s[76:77]
	s_mov_b64 s[76:77], 0x196a8000
	v_lshl_add_u64 v[24:25], v[10:11], 0, s[76:77]
	s_mov_b64 s[76:77], 0x196a8100
	v_lshl_add_u64 v[26:27], v[10:11], 0, s[76:77]
	s_mov_b64 s[76:77], 0x196b0000
	v_lshl_add_u64 v[30:31], v[10:11], 0, s[76:77]
	s_mov_b64 s[76:77], 0x196b0100
	global_load_dword v138, v[12:13], off
	global_load_dword v139, v[12:13], off offset:256
	global_load_dword v140, v[70:71], off
	global_load_dword v141, v[72:73], off
	v_lshl_add_u64 v[34:35], v[10:11], 0, s[76:77]
	s_mov_b64 s[76:77], 0x196b8000
	v_lshl_add_u64 v[36:37], v[10:11], 0, s[76:77]
	s_mov_b64 s[76:77], 0x196b8100
	v_lshl_add_u64 v[38:39], v[10:11], 0, s[76:77]
	s_mov_b64 s[76:77], 0x196c0000
	v_lshl_add_u64 v[40:41], v[10:11], 0, s[76:77]
	s_mov_b64 s[76:77], 0x196c0100
	v_lshl_add_u64 v[42:43], v[10:11], 0, s[76:77]
	s_mov_b64 s[76:77], 0x196c8000
	v_lshl_add_u64 v[44:45], v[10:11], 0, s[76:77]
	s_mov_b64 s[76:77], 0x196c8100
	v_lshl_add_u64 v[46:47], v[10:11], 0, s[76:77]
	s_mov_b64 s[76:77], 0x196d0000
	v_lshl_add_u64 v[48:49], v[10:11], 0, s[76:77]
	s_mov_b64 s[76:77], 0x196d0100
	v_lshl_add_u64 v[50:51], v[10:11], 0, s[76:77]
	s_mov_b64 s[76:77], 0x196d8000
	v_lshl_add_u64 v[54:55], v[10:11], 0, s[76:77]
	s_mov_b64 s[76:77], 0x196d8100
	v_lshl_add_u64 v[12:13], v[10:11], 0, s[76:77]
	s_mov_b64 s[76:77], 0x196e0000
	v_mov_b32_e32 v2, s73
	v_lshl_add_u64 v[62:63], v[10:11], 0, s[76:77]
	s_mov_b64 s[76:77], 0x196e0100
	ds_read_b64 v[136:137], v2
	v_lshl_add_u64 v[64:65], v[10:11], 0, s[76:77]
	s_mov_b64 s[76:77], 0x196e8000
	v_lshl_add_u64 v[66:67], v[10:11], 0, s[76:77]
	s_mov_b64 s[76:77], 0x196e8100
	v_lshl_add_u64 v[68:69], v[10:11], 0, s[76:77]
	s_mov_b64 s[76:77], 0x196f0000
	v_lshl_add_u64 v[70:71], v[10:11], 0, s[76:77]
	s_mov_b64 s[76:77], 0x196f0100
	v_lshl_add_u64 v[72:73], v[10:11], 0, s[76:77]
	s_waitcnt lgkmcnt(0)
; __device__ __forceinline__ unsigned f2bf(float f) { unsigned u = __builtin_bit_cast(unsigned, f); return (u + 0x7fffu + ((u >> 16) & 1u)) >> 16; }
; __global__ void __launch_bounds__(NTHR, 2) mk_fwd(Args args) {
;     ...
;             bf16* Ug = p_UGS + (size_t)g * 384 + 256 + p + (size_t)(sg * 32) * (64 * 384);
; #pragma unroll
;             for (int cb = 0; cb < 32; cb += 16) { float er[16], ei[16];
; #pragma unroll
;                 for (int k = 0; k < 16; ++k) { er[k] = Eg[(size_t)(cb + k) * 8192]; ei[k] = Eg[(size_t)(cb + k) * 8192 + 64]; }
; #pragma unroll
;                 for (int k = 0; k < 16; ++k) { const size_t o = (size_t)(cb + k) * (64 * 384); Ug[o] = (bf16)f2bf(sr); Ug[o + 64] = (bf16)f2bf(si);
;                     const float nr = ar * sr - ai * si + er[k], ni = ar * si + ai * sr + ei[k]; sr = nr; si = ni; } }
	v_readfirstlane_b32 s76, v136
	global_load_dword v136, v[80:81], off
	v_readfirstlane_b32 s77, v137
	global_load_dword v137, v[76:77], off
	s_mul_hi_i32 s96, s95, 0x300
	s_mulk_i32 s95, 0x300
	s_add_u32 s76, s76, s95
	s_addc_u32 s77, s77, s96
	v_lshlrev_b32_e32 v2, 1, v134
	v_lshl_add_u64 v[10:11], s[76:77], 0, v[2:3]
	global_load_dword v142, v[74:75], off
	global_load_dword v143, v[78:79], off
	global_load_dword v144, v[82:83], off
	global_load_dword v145, v[84:85], off
	global_load_dword v146, v[86:87], off
	global_load_dword v147, v[88:89], off
	global_load_dword v148, v[90:91], off
	s_nop 0
	global_load_dword v92, v[92:93], off
	s_nop 0
	global_load_dword v89, v[94:95], off
	global_load_dword v88, v[96:97], off
	global_load_dword v87, v[98:99], off
	global_load_dword v86, v[100:101], off
	global_load_dword v85, v[102:103], off
	global_load_dword v84, v[104:105], off
	global_load_dword v83, v[106:107], off
	global_load_dword v82, v[108:109], off
	global_load_dword v81, v[110:111], off
	global_load_dword v80, v[112:113], off
	global_load_dword v79, v[114:115], off
	global_load_dword v78, v[116:117], off
	global_load_dword v77, v[118:119], off
	global_load_dword v76, v[120:121], off
	global_load_dword v75, v[122:123], off
	global_load_dword v74, v[124:125], off
	global_load_dword v6, v[126:127], off
	global_load_dword v2, v[128:129], off
	v_lshl_add_u64 v[10:11], v[10:11], 0, v[4:5]
	s_mov_b64 s[76:77], 0x16600200
	v_lshl_add_u64 v[134:135], v[10:11], 0, s[76:77]
	v_bfe_u32 v90, v19, 16, 1
	s_mov_b32 s76, 0x16600000
	v_add3_u32 v93, v19, v90, s78
	v_add_co_u32_e32 v90, vcc, s76, v10
	s_mov_b32 s76, 0x1660c000
	s_nop 0
	v_addc_co_u32_e32 v91, vcc, 0, v11, vcc
	global_store_short_d16_hi v[90:91], v93, off offset:512
	v_bfe_u32 v90, v18, 16, 1
	v_add3_u32 v90, v18, v90, s78
	global_store_short_d16_hi v[134:135], v90, off offset:128
	v_mul_f32_e32 v90, v8, v19
	v_fma_f32 v90, -v9, v18, v90
	v_pk_mul_f32 v[18:19], v[8:9], v[18:19]
	global_load_dword v60, v[60:61], off
	v_add_f32_e32 v18, v18, v19
	global_load_dword v58, v[58:59], off
	s_add_i32 s94, s94, s70
	global_load_dword v56, v[56:57], off
	s_add_i32 s3, s3, s33
	global_load_dword v52, v[52:53], off
	s_cmpk_lt_i32 s94, 0x100
	global_load_dword v32, v[32:33], off
	s_waitcnt vmcnt(0)
	v_add_f32_e32 v90, v90, v138
	v_add_f32_e32 v91, v18, v139
	v_bfe_u32 v18, v90, 16, 1
	v_add3_u32 v93, v90, v18, s78
	v_add_co_u32_e32 v18, vcc, s76, v10
	s_mov_b32 s76, 0x16618000
	s_nop 0
	v_addc_co_u32_e32 v19, vcc, 0, v11, vcc
	global_store_short_d16_hi v[18:19], v93, off offset:512
	v_bfe_u32 v93, v91, 16, 1
	v_add3_u32 v93, v91, v93, s78
	global_store_short_d16_hi v[18:19], v93, off offset:640
	v_mul_f32_e32 v18, v9, v91
	v_fma_f32 v18, v8, v90, -v18
	v_add_f32_e32 v93, v18, v140
	v_mul_f32_e32 v18, v9, v90
	v_fmac_f32_e32 v18, v8, v91
	v_add_f32_e32 v90, v18, v141
	v_bfe_u32 v18, v93, 16, 1
	v_add3_u32 v91, v93, v18, s78
	v_add_co_u32_e32 v18, vcc, s76, v10
	s_mov_b32 s76, 0x16624000
	s_nop 0
	v_addc_co_u32_e32 v19, vcc, 0, v11, vcc
	global_store_short_d16_hi v[18:19], v91, off offset:512
	v_bfe_u32 v91, v90, 16, 1
	v_add3_u32 v91, v90, v91, s78
	global_store_short_d16_hi v[18:19], v91, off offset:640
	v_mul_f32_e32 v18, v9, v90
	v_fma_f32 v18, v8, v93, -v18
	global_load_dword v28, v[28:29], off
	s_waitcnt lgkmcnt(0)
	v_add_f32_e32 v91, v18, v136
	v_mul_f32_e32 v18, v9, v93
	v_fmac_f32_e32 v18, v8, v90
	v_add_f32_e32 v90, v18, v137
	v_bfe_u32 v18, v91, 16, 1
	v_add3_u32 v93, v91, v18, s78
	v_add_co_u32_e32 v18, vcc, s76, v10
	s_mov_b32 s76, 0x16630000
	s_nop 0
	v_addc_co_u32_e32 v19, vcc, 0, v11, vcc
	global_store_short_d16_hi v[18:19], v93, off offset:512
	v_bfe_u32 v93, v90, 16, 1
	v_add3_u32 v93, v90, v93, s78
	global_store_short_d16_hi v[18:19], v93, off offset:640
	v_mul_f32_e32 v18, v9, v90
	v_fma_f32 v18, v8, v91, -v18
	v_add_f32_e32 v93, v18, v142
	v_mul_f32_e32 v18, v9, v91
	v_fmac_f32_e32 v18, v8, v90
	v_add_f32_e32 v90, v18, v143
	v_bfe_u32 v18, v93, 16, 1
	v_add3_u32 v91, v93, v18, s78
	v_add_co_u32_e32 v18, vcc, s76, v10
	s_mov_b32 s76, 0x1663c000
	s_nop 0
	v_addc_co_u32_e32 v19, vcc, 0, v11, vcc
	global_store_short_d16_hi v[18:19], v91, off offset:512
	v_bfe_u32 v91, v90, 16, 1
	v_add3_u32 v91, v90, v91, s78
	global_store_short_d16_hi v[18:19], v91, off offset:640
	v_mul_f32_e32 v18, v9, v90
	v_fma_f32 v18, v8, v93, -v18
	v_add_f32_e32 v91, v18, v144
	v_mul_f32_e32 v18, v9, v93
	v_fmac_f32_e32 v18, v8, v90
	v_add_f32_e32 v90, v18, v145
	v_bfe_u32 v18, v91, 16, 1
	v_add3_u32 v93, v91, v18, s78
	v_add_co_u32_e32 v18, vcc, s76, v10
	s_mov_b32 s76, 0x16648000
	s_nop 0
	v_addc_co_u32_e32 v19, vcc, 0, v11, vcc
	global_store_short_d16_hi v[18:19], v93, off offset:512
	v_bfe_u32 v93, v90, 16, 1
	v_add3_u32 v93, v90, v93, s78
	global_store_short_d16_hi v[18:19], v93, off offset:640
	v_mul_f32_e32 v18, v9, v90
	v_fma_f32 v18, v8, v91, -v18
	v_add_f32_e32 v93, v18, v146
	v_mul_f32_e32 v18, v9, v91
	v_fmac_f32_e32 v18, v8, v90
	v_add_f32_e32 v90, v18, v147
	v_bfe_u32 v18, v93, 16, 1
	v_add3_u32 v91, v93, v18, s78
	v_add_co_u32_e32 v18, vcc, s76, v10
	s_mov_b32 s76, 0x16654000
	s_nop 0
	v_addc_co_u32_e32 v19, vcc, 0, v11, vcc
	global_store_short_d16_hi v[18:19], v91, off offset:512
	v_bfe_u32 v91, v90, 16, 1
	v_add3_u32 v91, v90, v91, s78
	global_store_short_d16_hi v[18:19], v91, off offset:640
	v_mul_f32_e32 v18, v9, v90
	v_fma_f32 v18, v8, v93, -v18
	v_add_f32_e32 v91, v18, v148
	v_mul_f32_e32 v18, v9, v93
	v_fmac_f32_e32 v18, v8, v90
	v_add_f32_e32 v90, v18, v92
	v_bfe_u32 v18, v91, 16, 1
	v_add3_u32 v92, v91, v18, s78
	v_add_co_u32_e32 v18, vcc, s76, v10
	s_mov_b32 s76, 0x16660000
	s_nop 0
; __device__ __forceinline__ unsigned f2bf(float f) { unsigned u = __builtin_bit_cast(unsigned, f); return (u + 0x7fffu + ((u >> 16) & 1u)) >> 16; }
; __global__ void __launch_bounds__(NTHR, 2) mk_fwd(Args args) {
;     ...
;             bf16* Ug = p_UGS + (size_t)g * 384 + 256 + p + (size_t)(sg * 32) * (64 * 384);
; #pragma unroll
;             for (int cb = 0; cb < 32; cb += 16) { float er[16], ei[16];
; #pragma unroll
;                 for (int k = 0; k < 16; ++k) { er[k] = Eg[(size_t)(cb + k) * 8192]; ei[k] = Eg[(size_t)(cb + k) * 8192 + 64]; }
; #pragma unroll
;                 for (int k = 0; k < 16; ++k) { const size_t o = (size_t)(cb + k) * (64 * 384); Ug[o] = (bf16)f2bf(sr); Ug[o + 64] = (bf16)f2bf(si);
;                     const float nr = ar * sr - ai * si + er[k], ni = ar * si + ai * sr + ei[k]; sr = nr; si = ni; } }
	v_addc_co_u32_e32 v19, vcc, 0, v11, vcc
	global_store_short_d16_hi v[18:19], v92, off offset:512
	v_bfe_u32 v92, v90, 16, 1
	v_add3_u32 v92, v90, v92, s78
	global_store_short_d16_hi v[18:19], v92, off offset:640
	v_mul_f32_e32 v18, v9, v90
	v_fma_f32 v18, v8, v91, -v18
	v_add_f32_e32 v89, v18, v89
	v_mul_f32_e32 v18, v9, v91
	v_fmac_f32_e32 v18, v8, v90
	v_add_f32_e32 v88, v18, v88
	v_bfe_u32 v18, v89, 16, 1
	v_add3_u32 v90, v89, v18, s78
	v_add_co_u32_e32 v18, vcc, s76, v10
	s_mov_b32 s76, 0x1666c000
	s_nop 0
	v_addc_co_u32_e32 v19, vcc, 0, v11, vcc
	global_store_short_d16_hi v[18:19], v90, off offset:512
	v_bfe_u32 v90, v88, 16, 1
	v_add3_u32 v90, v88, v90, s78
	global_store_short_d16_hi v[18:19], v90, off offset:640
	v_mul_f32_e32 v18, v9, v88
	v_fma_f32 v18, v8, v89, -v18
	v_add_f32_e32 v87, v18, v87
	v_mul_f32_e32 v18, v9, v89
	v_fmac_f32_e32 v18, v8, v88
	v_add_f32_e32 v86, v18, v86
	v_bfe_u32 v18, v87, 16, 1
	v_add3_u32 v88, v87, v18, s78
	v_add_co_u32_e32 v18, vcc, s76, v10
	s_mov_b32 s76, 0x16678000
	s_nop 0
	v_addc_co_u32_e32 v19, vcc, 0, v11, vcc
	global_store_short_d16_hi v[18:19], v88, off offset:512
	v_bfe_u32 v88, v86, 16, 1
	v_add3_u32 v88, v86, v88, s78
	global_store_short_d16_hi v[18:19], v88, off offset:640
	v_mul_f32_e32 v18, v9, v86
	v_fma_f32 v18, v8, v87, -v18
	v_add_f32_e32 v85, v18, v85
	v_mul_f32_e32 v18, v9, v87
	v_fmac_f32_e32 v18, v8, v86
	v_add_f32_e32 v84, v18, v84
	v_bfe_u32 v18, v85, 16, 1
	v_add3_u32 v86, v85, v18, s78
	v_add_co_u32_e32 v18, vcc, s76, v10
	s_mov_b32 s76, 0x16684000
	s_nop 0
	v_addc_co_u32_e32 v19, vcc, 0, v11, vcc
	global_store_short_d16_hi v[18:19], v86, off offset:512
	v_bfe_u32 v86, v84, 16, 1
	v_add3_u32 v86, v84, v86, s78
	global_store_short_d16_hi v[18:19], v86, off offset:640
	v_mul_f32_e32 v18, v9, v84
	v_fma_f32 v18, v8, v85, -v18
	v_add_f32_e32 v83, v18, v83
	v_mul_f32_e32 v18, v9, v85
	v_fmac_f32_e32 v18, v8, v84
	v_add_f32_e32 v82, v18, v82
	v_bfe_u32 v18, v83, 16, 1
	v_add3_u32 v84, v83, v18, s78
	v_add_co_u32_e32 v18, vcc, s76, v10
	s_mov_b32 s76, 0x16690000
	s_nop 0
	v_addc_co_u32_e32 v19, vcc, 0, v11, vcc
	global_store_short_d16_hi v[18:19], v84, off offset:512
	v_bfe_u32 v84, v82, 16, 1
	v_add3_u32 v84, v82, v84, s78
	global_store_short_d16_hi v[18:19], v84, off offset:640
	v_mul_f32_e32 v18, v9, v82
	v_fma_f32 v18, v8, v83, -v18
	v_add_f32_e32 v81, v18, v81
	v_mul_f32_e32 v18, v9, v83
	v_fmac_f32_e32 v18, v8, v82
	v_add_f32_e32 v80, v18, v80
	v_bfe_u32 v18, v81, 16, 1
	v_add3_u32 v82, v81, v18, s78
	v_add_co_u32_e32 v18, vcc, s76, v10
	s_mov_b32 s76, 0x1669c000
	s_nop 0
	v_addc_co_u32_e32 v19, vcc, 0, v11, vcc
	global_store_short_d16_hi v[18:19], v82, off offset:512
	v_bfe_u32 v82, v80, 16, 1
	v_add3_u32 v82, v80, v82, s78
	global_store_short_d16_hi v[18:19], v82, off offset:640
	v_mul_f32_e32 v18, v9, v80
	v_fma_f32 v18, v8, v81, -v18
	v_add_f32_e32 v79, v18, v79
	v_mul_f32_e32 v18, v9, v81
	v_fmac_f32_e32 v18, v8, v80
	v_add_f32_e32 v78, v18, v78
	v_bfe_u32 v18, v79, 16, 1
	v_add3_u32 v80, v79, v18, s78
	v_add_co_u32_e32 v18, vcc, s76, v10
	s_mov_b32 s76, 0x166a8000
	s_nop 0
	v_addc_co_u32_e32 v19, vcc, 0, v11, vcc
	global_store_short_d16_hi v[18:19], v80, off offset:512
	v_bfe_u32 v80, v78, 16, 1
	v_add3_u32 v80, v78, v80, s78
	global_store_short_d16_hi v[18:19], v80, off offset:640
	v_mul_f32_e32 v18, v9, v78
	v_fma_f32 v18, v8, v79, -v18
	v_add_f32_e32 v77, v18, v77
	v_mul_f32_e32 v18, v9, v79
	v_fmac_f32_e32 v18, v8, v78
	v_add_f32_e32 v59, v18, v76
	v_bfe_u32 v18, v77, 16, 1
	v_add3_u32 v61, v77, v18, s78
	v_add_co_u32_e32 v18, vcc, s76, v10
	s_mov_b32 s76, 0x166b4000
	s_nop 0
	v_addc_co_u32_e32 v19, vcc, 0, v11, vcc
	global_store_short_d16_hi v[18:19], v61, off offset:512
	v_bfe_u32 v61, v59, 16, 1
	v_add3_u32 v61, v59, v61, s78
	global_store_short_d16_hi v[18:19], v61, off offset:640
	v_mul_f32_e32 v18, v9, v59
	v_fma_f32 v18, v8, v77, -v18
	v_add_f32_e32 v53, v18, v75
	v_mul_f32_e32 v18, v9, v77
	v_fmac_f32_e32 v18, v8, v59
	v_add_f32_e32 v57, v18, v74
	v_bfe_u32 v18, v53, 16, 1
	v_add3_u32 v59, v53, v18, s78
	v_add_co_u32_e32 v18, vcc, s76, v10
	v_bfe_u32 v33, v57, 16, 1
	s_nop 0
	v_addc_co_u32_e32 v19, vcc, 0, v11, vcc
	v_add3_u32 v33, v57, v33, s78
	global_store_short_d16_hi v[18:19], v59, off offset:512
	global_store_short_d16_hi v[18:19], v33, off offset:640
	v_mul_f32_e32 v18, v9, v57
	v_fma_f32 v18, v8, v53, -v18
	v_add_f32_e32 v29, v18, v6
	v_mul_f32_e32 v6, v9, v53
	v_fmac_f32_e32 v6, v8, v57
	v_add_f32_e32 v33, v6, v2
	global_load_dword v53, v[14:15], off
	global_load_dword v57, v[16:17], off
	global_load_dword v59, v[20:21], off
	global_load_dword v61, v[22:23], off
	global_load_dword v74, v[24:25], off
	global_load_dword v75, v[26:27], off
	s_nop 0
	global_load_dword v30, v[30:31], off
	s_nop 0
	global_load_dword v31, v[34:35], off
	global_load_dword v25, v[36:37], off
	global_load_dword v24, v[38:39], off
	global_load_dword v23, v[40:41], off
	global_load_dword v22, v[42:43], off
	global_load_dword v21, v[44:45], off
	global_load_dword v20, v[46:47], off
	global_load_dword v19, v[48:49], off
	global_load_dword v18, v[50:51], off
	global_load_dword v17, v[54:55], off
	global_load_dword v16, v[12:13], off
	global_load_dword v15, v[62:63], off
	global_load_dword v14, v[64:65], off
	s_nop 0
	global_load_dword v13, v[66:67], off
	global_load_dword v12, v[68:69], off
	global_load_dword v6, v[70:71], off
	global_load_dword v2, v[72:73], off
	v_bfe_u32 v26, v29, 16, 1
	s_mov_b32 s76, 0x166c0000
	v_add3_u32 v34, v29, v26, s78
	v_add_co_u32_e32 v26, vcc, s76, v10
	s_nop 1
	v_addc_co_u32_e32 v27, vcc, 0, v11, vcc
	global_store_short_d16_hi v[26:27], v34, off offset:512
	v_bfe_u32 v34, v33, 16, 1
	v_add3_u32 v34, v33, v34, s78
	global_store_short_d16_hi v[26:27], v34, off offset:640
	v_mul_f32_e32 v26, v9, v33
	v_fma_f32 v26, v8, v29, -v26
	v_add_f32_e32 v34, v26, v60
	v_mul_f32_e32 v26, v9, v29
	v_fmac_f32_e32 v26, v8, v33
	v_add_f32_e32 v29, v26, v58
	v_bfe_u32 v26, v34, 16, 1
	v_add3_u32 v33, v34, v26, s78
	v_add_co_u32_e32 v26, vcc, s79, v10
	s_nop 1
	v_addc_co_u32_e32 v27, vcc, 0, v11, vcc
	global_store_short_d16_hi v[26:27], v33, off offset:512
	v_bfe_u32 v33, v29, 16, 1
	v_add3_u32 v33, v29, v33, s78
	global_store_short_d16_hi v[26:27], v33, off offset:640
	v_mul_f32_e32 v26, v9, v29
	v_fma_f32 v26, v8, v34, -v26
	v_add_f32_e32 v33, v26, v56
	v_mul_f32_e32 v26, v9, v34
	v_fmac_f32_e32 v26, v8, v29
	v_add_f32_e32 v29, v26, v52
	v_bfe_u32 v26, v33, 16, 1
	v_add3_u32 v34, v33, v26, s78
	v_add_co_u32_e32 v26, vcc, s81, v10
	s_nop 1
	v_addc_co_u32_e32 v27, vcc, 0, v11, vcc
	global_store_short_d16_hi v[26:27], v34, off offset:512
	v_bfe_u32 v34, v29, 16, 1
	v_add3_u32 v34, v29, v34, s78
	global_store_short_d16_hi v[26:27], v34, off offset:640
	v_mul_f32_e32 v26, v9, v29
	v_fma_f32 v26, v8, v33, -v26
	v_add_f32_e32 v32, v26, v32
	v_mul_f32_e32 v26, v9, v33
	v_fmac_f32_e32 v26, v8, v29
	s_waitcnt vmcnt(0)
; __device__ __forceinline__ unsigned f2bf(float f) { unsigned u = __builtin_bit_cast(unsigned, f); return (u + 0x7fffu + ((u >> 16) & 1u)) >> 16; }
; __global__ void __launch_bounds__(NTHR, 2) mk_fwd(Args args) {
;     ...
;             bf16* Ug = p_UGS + (size_t)g * 384 + 256 + p + (size_t)(sg * 32) * (64 * 384);
; #pragma unroll
;             for (int cb = 0; cb < 32; cb += 16) { float er[16], ei[16];
; #pragma unroll
;                 for (int k = 0; k < 16; ++k) { er[k] = Eg[(size_t)(cb + k) * 8192]; ei[k] = Eg[(size_t)(cb + k) * 8192 + 64]; }
; #pragma unroll
;                 for (int k = 0; k < 16; ++k) { const size_t o = (size_t)(cb + k) * (64 * 384); Ug[o] = (bf16)f2bf(sr); Ug[o + 64] = (bf16)f2bf(si);
;                     const float nr = ar * sr - ai * si + er[k], ni = ar * si + ai * sr + ei[k]; sr = nr; si = ni; } }
;             __syncthreads();
	v_add_f32_e32 v28, v26, v28
	v_bfe_u32 v26, v32, 16, 1
	v_add3_u32 v29, v32, v26, s78
	v_add_co_u32_e32 v26, vcc, s82, v10
	s_nop 1
	v_addc_co_u32_e32 v27, vcc, 0, v11, vcc
	global_store_short_d16_hi v[26:27], v29, off offset:512
	v_bfe_u32 v29, v28, 16, 1
	v_add3_u32 v29, v28, v29, s78
	global_store_short_d16_hi v[26:27], v29, off offset:640
	v_mul_f32_e32 v26, v9, v28
	v_fma_f32 v26, v8, v32, -v26
	s_waitcnt lgkmcnt(0)
	v_add_f32_e32 v29, v26, v53
	v_mul_f32_e32 v26, v9, v32
	v_fmac_f32_e32 v26, v8, v28
	v_add_f32_e32 v28, v26, v57
	v_bfe_u32 v26, v29, 16, 1
	v_add3_u32 v32, v29, v26, s78
	v_add_co_u32_e32 v26, vcc, s83, v10
	s_nop 1
	v_addc_co_u32_e32 v27, vcc, 0, v11, vcc
	global_store_short_d16_hi v[26:27], v32, off offset:512
	v_bfe_u32 v32, v28, 16, 1
	v_add3_u32 v32, v28, v32, s78
	global_store_short_d16_hi v[26:27], v32, off offset:640
	v_mul_f32_e32 v26, v9, v28
	v_fma_f32 v26, v8, v29, -v26
	v_add_f32_e32 v32, v26, v59
	v_mul_f32_e32 v26, v9, v29
	v_fmac_f32_e32 v26, v8, v28
	v_add_f32_e32 v28, v26, v61
	v_bfe_u32 v26, v32, 16, 1
	v_add3_u32 v29, v32, v26, s78
	v_add_co_u32_e32 v26, vcc, s84, v10
	s_nop 1
	v_addc_co_u32_e32 v27, vcc, 0, v11, vcc
	global_store_short_d16_hi v[26:27], v29, off offset:512
	v_bfe_u32 v29, v28, 16, 1
	v_add3_u32 v29, v28, v29, s78
	global_store_short_d16_hi v[26:27], v29, off offset:640
	v_mul_f32_e32 v26, v9, v28
	v_fma_f32 v26, v8, v32, -v26
	v_add_f32_e32 v29, v26, v74
	v_mul_f32_e32 v26, v9, v32
	v_fmac_f32_e32 v26, v8, v28
	v_add_f32_e32 v28, v26, v75
	v_bfe_u32 v26, v29, 16, 1
	v_add3_u32 v32, v29, v26, s78
	v_add_co_u32_e32 v26, vcc, s85, v10
	s_nop 1
	v_addc_co_u32_e32 v27, vcc, 0, v11, vcc
	global_store_short_d16_hi v[26:27], v32, off offset:512
	v_bfe_u32 v32, v28, 16, 1
	v_add3_u32 v32, v28, v32, s78
	global_store_short_d16_hi v[26:27], v32, off offset:640
	v_mul_f32_e32 v26, v9, v28
	v_fma_f32 v26, v8, v29, -v26
	v_add_f32_e32 v30, v26, v30
	v_mul_f32_e32 v26, v9, v29
	v_fmac_f32_e32 v26, v8, v28
	v_add_f32_e32 v28, v26, v31
	v_bfe_u32 v26, v30, 16, 1
	v_add3_u32 v29, v30, v26, s78
	v_add_co_u32_e32 v26, vcc, s86, v10
	s_nop 1
	v_addc_co_u32_e32 v27, vcc, 0, v11, vcc
	global_store_short_d16_hi v[26:27], v29, off offset:512
	v_bfe_u32 v29, v28, 16, 1
	v_add3_u32 v29, v28, v29, s78
	global_store_short_d16_hi v[26:27], v29, off offset:640
	v_mul_f32_e32 v26, v9, v28
	v_fma_f32 v26, v8, v30, -v26
	v_add_f32_e32 v26, v26, v25
	v_mul_f32_e32 v25, v9, v30
	v_fmac_f32_e32 v25, v8, v28
	v_add_f32_e32 v27, v25, v24
	v_bfe_u32 v24, v26, 16, 1
	v_add3_u32 v28, v26, v24, s78
	v_add_co_u32_e32 v24, vcc, s87, v10
	s_nop 1
	v_addc_co_u32_e32 v25, vcc, 0, v11, vcc
	global_store_short_d16_hi v[24:25], v28, off offset:512
	v_bfe_u32 v28, v27, 16, 1
	v_add3_u32 v28, v27, v28, s78
	global_store_short_d16_hi v[24:25], v28, off offset:640
	v_mul_f32_e32 v24, v9, v27
	v_fma_f32 v24, v8, v26, -v24
	v_add_f32_e32 v24, v24, v23
	v_mul_f32_e32 v23, v9, v26
	v_fmac_f32_e32 v23, v8, v27
	v_add_f32_e32 v25, v23, v22
	v_bfe_u32 v22, v24, 16, 1
	v_add3_u32 v26, v24, v22, s78
	v_add_co_u32_e32 v22, vcc, s88, v10
	s_nop 1
	v_addc_co_u32_e32 v23, vcc, 0, v11, vcc
	global_store_short_d16_hi v[22:23], v26, off offset:512
	v_bfe_u32 v26, v25, 16, 1
	v_add3_u32 v26, v25, v26, s78
	global_store_short_d16_hi v[22:23], v26, off offset:640
	v_mul_f32_e32 v22, v9, v25
	v_fma_f32 v22, v8, v24, -v22
	v_add_f32_e32 v22, v22, v21
	v_mul_f32_e32 v21, v9, v24
	v_fmac_f32_e32 v21, v8, v25
	v_add_f32_e32 v23, v21, v20
	v_bfe_u32 v20, v22, 16, 1
	v_add3_u32 v24, v22, v20, s78
	v_add_co_u32_e32 v20, vcc, s89, v10
	s_nop 1
	v_addc_co_u32_e32 v21, vcc, 0, v11, vcc
	global_store_short_d16_hi v[20:21], v24, off offset:512
	v_bfe_u32 v24, v23, 16, 1
	v_add3_u32 v24, v23, v24, s78
	global_store_short_d16_hi v[20:21], v24, off offset:640
	v_mul_f32_e32 v20, v9, v23
	v_fma_f32 v20, v8, v22, -v20
	v_add_f32_e32 v20, v20, v19
	v_mul_f32_e32 v19, v9, v22
	v_fmac_f32_e32 v19, v8, v23
	v_add_f32_e32 v21, v19, v18
	v_bfe_u32 v18, v20, 16, 1
	v_add3_u32 v22, v20, v18, s78
	v_add_co_u32_e32 v18, vcc, s90, v10
	s_nop 1
	v_addc_co_u32_e32 v19, vcc, 0, v11, vcc
	global_store_short_d16_hi v[18:19], v22, off offset:512
	v_bfe_u32 v22, v21, 16, 1
	v_add3_u32 v22, v21, v22, s78
	global_store_short_d16_hi v[18:19], v22, off offset:640
	v_mul_f32_e32 v18, v9, v21
	v_fma_f32 v18, v8, v20, -v18
	v_add_f32_e32 v18, v18, v17
	v_mul_f32_e32 v17, v9, v20
	v_fmac_f32_e32 v17, v8, v21
	v_add_f32_e32 v19, v17, v16
	v_bfe_u32 v16, v18, 16, 1
	v_add3_u32 v20, v18, v16, s78
	v_add_co_u32_e32 v16, vcc, s91, v10
	s_nop 1
	v_addc_co_u32_e32 v17, vcc, 0, v11, vcc
	global_store_short_d16_hi v[16:17], v20, off offset:512
	v_bfe_u32 v20, v19, 16, 1
	v_add3_u32 v20, v19, v20, s78
	global_store_short_d16_hi v[16:17], v20, off offset:640
	v_mul_f32_e32 v16, v9, v19
	v_fma_f32 v16, v8, v18, -v16
	v_add_f32_e32 v16, v16, v15
	v_mul_f32_e32 v15, v9, v18
	v_fmac_f32_e32 v15, v8, v19
	v_add_f32_e32 v17, v15, v14
	v_bfe_u32 v14, v16, 16, 1
	v_add3_u32 v18, v16, v14, s78
	v_add_co_u32_e32 v14, vcc, s92, v10
	s_nop 1
	v_addc_co_u32_e32 v15, vcc, 0, v11, vcc
	global_store_short_d16_hi v[14:15], v18, off offset:512
	v_bfe_u32 v18, v17, 16, 1
	v_add3_u32 v18, v17, v18, s78
	global_store_short_d16_hi v[14:15], v18, off offset:640
	v_mul_f32_e32 v14, v9, v17
	v_fma_f32 v14, v8, v16, -v14
	v_add_f32_e32 v14, v14, v13
	v_mul_f32_e32 v13, v9, v16
	v_fmac_f32_e32 v13, v8, v17
	v_add_f32_e32 v15, v13, v12
	v_bfe_u32 v12, v14, 16, 1
	v_add3_u32 v16, v14, v12, s78
	v_add_co_u32_e32 v12, vcc, s93, v10
	s_nop 1
	v_addc_co_u32_e32 v13, vcc, 0, v11, vcc
	global_store_short_d16_hi v[12:13], v16, off offset:512
	v_bfe_u32 v16, v15, 16, 1
	v_add3_u32 v16, v15, v16, s78
	global_store_short_d16_hi v[12:13], v16, off offset:640
	v_mul_f32_e32 v12, v9, v15
	v_fma_f32 v12, v8, v14, -v12
	v_add_f32_e32 v6, v12, v6
	v_mul_f32_e32 v9, v9, v14
	v_fmac_f32_e32 v9, v8, v15
	v_bfe_u32 v8, v6, 16, 1
	v_add3_u32 v6, v6, v8, s78
	v_add_co_u32_e32 v8, vcc, 0x16774000, v10
	v_add_f32_e32 v2, v9, v2
	s_nop 0
	v_addc_co_u32_e32 v9, vcc, 0, v11, vcc
	global_store_short_d16_hi v[8:9], v6, off offset:512
	v_bfe_u32 v6, v2, 16, 1
	v_add3_u32 v2, v2, v6, s78
	global_store_short_d16_hi v[8:9], v2, off offset:640
	s_waitcnt lgkmcnt(0)
	s_barrier
	s_cbranch_scc0 .LBB0_896
; #define LAS __attribute__((address_space(3)))
; __global__ void __launch_bounds__(NTHR, 2) mk_fwd(Args args) {
;     ...
;         for (int b = bx; b < 256; b += G) { const int g = b >> 2, p = (b & 3) * 16 + (lane & 15), sub = lane >> 4, sg = wave * 4 + sub; LAS float* sl = (LAS float*)L;
;             const float ar = p_A16[(g * 64 + p) * 2], ai = p_A16[(g * 64 + p) * 2 + 1];
;             const float* Eg = p_E + g * 128 + p + (size_t)(sg * 32) * 8192;
;             float sr = 0.f, si = 0.f;
; #pragma unroll
;             for (int cb = 0; cb < 32; cb += 16) { float er[16], ei[16];
; #pragma unroll
;                 for (int k = 0; k < 16; ++k) { er[k] = Eg[(size_t)(cb + k) * 8192]; ei[k] = Eg[(size_t)(cb + k) * 8192 + 64]; }
; #pragma unroll
;                 for (int k = 0; k < 16; ++k) { const float nr = ar * sr - ai * si + er[k], ni = ar * si + ai * sr + ei[k]; sr = nr; si = ni; } }
.LBB0_832:
	ds_read_b64 v[8:9], v133
	s_ashr_i32 s95, s94, 2
	s_lshl_b32 s76, s95, 7
	v_and_or_b32 v134, s3, 48, v130
	s_ashr_i32 s77, s76, 31
	s_waitcnt lgkmcnt(0)
	v_readfirstlane_b32 s96, v8
	v_lshl_or_b32 v8, v134, 1, s76
	s_lshl_b64 s[76:77], s[76:77], 2
	v_readfirstlane_b32 s97, v9
	s_add_u32 s76, s96, s76
	s_addc_u32 s77, s97, s77
	v_lshlrev_b32_e32 v2, 2, v134
	v_lshl_add_u64 v[10:11], s[76:77], 0, v[2:3]
	v_lshl_add_u64 v[10:11], v[10:11], 0, v[0:1]
	s_mov_b64 s[76:77], 0x19600000
	v_lshl_add_u64 v[12:13], v[10:11], 0, s[76:77]
	s_mov_b32 s76, 0x19600000
	v_add_co_u32_e32 v14, vcc, s76, v10
	s_mov_b32 s76, 0x19608000
	s_nop 0
	v_addc_co_u32_e32 v15, vcc, 0, v11, vcc
	v_add_co_u32_e32 v16, vcc, s76, v10
	s_mov_b32 s76, 0x19610000
	s_nop 0
	v_addc_co_u32_e32 v17, vcc, 0, v11, vcc
	v_add_co_u32_e32 v18, vcc, s76, v10
	s_mov_b32 s76, 0x19618000
	s_nop 0
	v_addc_co_u32_e32 v19, vcc, 0, v11, vcc
	v_add_co_u32_e32 v20, vcc, s76, v10
	s_mov_b32 s76, 0x19620000
	s_nop 0
	v_addc_co_u32_e32 v21, vcc, 0, v11, vcc
	global_load_dword v2, v[14:15], off
	global_load_dword v6, v[16:17], off
	global_load_dword v22, v[16:17], off offset:256
	global_load_dword v23, v[18:19], off
	global_load_dword v24, v[18:19], off offset:256
	global_load_dword v25, v[20:21], off
	global_load_dword v26, v[20:21], off offset:256
	global_load_dword v27, v[12:13], off offset:256
	v_add_co_u32_e32 v14, vcc, s76, v10
	s_mov_b32 s76, 0x19628000
	s_nop 0
	v_addc_co_u32_e32 v15, vcc, 0, v11, vcc
	v_add_co_u32_e32 v16, vcc, s76, v10
	s_mov_b32 s76, 0x19630000
	s_nop 0
	v_addc_co_u32_e32 v17, vcc, 0, v11, vcc
	v_add_co_u32_e32 v18, vcc, s76, v10
	s_mov_b32 s76, 0x19638000
	s_nop 0
	v_addc_co_u32_e32 v19, vcc, 0, v11, vcc
	v_add_co_u32_e32 v20, vcc, s76, v10
	s_mov_b32 s76, 0x19640000
	s_nop 0
	v_addc_co_u32_e32 v21, vcc, 0, v11, vcc
	global_load_dword v28, v[14:15], off
	global_load_dword v29, v[14:15], off offset:256
	global_load_dword v30, v[16:17], off
	global_load_dword v31, v[16:17], off offset:256
	s_waitcnt vmcnt(0)
	global_load_dword v32, v[18:19], off
	global_load_dword v33, v[18:19], off offset:256
	global_load_dword v34, v[20:21], off
	global_load_dword v35, v[20:21], off offset:256
	v_add_co_u32_e32 v14, vcc, s76, v10
	s_mov_b32 s76, 0x19648000
	s_nop 0
	v_addc_co_u32_e32 v15, vcc, 0, v11, vcc
	v_add_co_u32_e32 v16, vcc, s76, v10
	s_mov_b32 s76, 0x19650000
	s_nop 0
	v_addc_co_u32_e32 v17, vcc, 0, v11, vcc
	v_add_co_u32_e32 v18, vcc, s76, v10
	s_mov_b32 s76, 0x19658000
	s_nop 0
	v_addc_co_u32_e32 v19, vcc, 0, v11, vcc
	v_add_co_u32_e32 v20, vcc, s76, v10
	s_mov_b32 s76, 0x19660000
	s_nop 0
	v_addc_co_u32_e32 v21, vcc, 0, v11, vcc
	global_load_dword v36, v[14:15], off
	global_load_dword v37, v[14:15], off offset:256
	global_load_dword v38, v[16:17], off
	global_load_dword v39, v[16:17], off offset:256
	global_load_dword v40, v[18:19], off
	global_load_dword v41, v[18:19], off offset:256
	global_load_dword v42, v[20:21], off
	global_load_dword v43, v[20:21], off offset:256
	v_add_co_u32_e32 v14, vcc, s76, v10
	s_mov_b32 s76, 0x19668000
	s_nop 0
	v_addc_co_u32_e32 v15, vcc, 0, v11, vcc
	v_add_co_u32_e32 v16, vcc, s76, v10
	s_mov_b32 s76, 0x19670000
	s_nop 0
	v_addc_co_u32_e32 v17, vcc, 0, v11, vcc
	v_add_co_u32_e32 v18, vcc, s76, v10
	s_mov_b32 s76, 0x19678000
	s_nop 0
	v_addc_co_u32_e32 v19, vcc, 0, v11, vcc
	v_add_co_u32_e32 v20, vcc, s76, v10
	s_mov_b32 s76, 0x19680000
	s_nop 0
	v_addc_co_u32_e32 v21, vcc, 0, v11, vcc
	global_load_dword v44, v[14:15], off
	global_load_dword v45, v[14:15], off offset:256
	global_load_dword v46, v[16:17], off
	global_load_dword v47, v[16:17], off offset:256
	global_load_dword v48, v[18:19], off
	global_load_dword v49, v[18:19], off offset:256
	global_load_dword v50, v[20:21], off
	global_load_dword v51, v[20:21], off offset:256
	v_add_co_u32_e32 v14, vcc, s76, v10
	s_mov_b32 s76, 0x19688000
	s_nop 0
	v_addc_co_u32_e32 v15, vcc, 0, v11, vcc
	v_add_co_u32_e32 v16, vcc, s76, v10
	s_mov_b32 s76, 0x19690000
	s_nop 0
	v_addc_co_u32_e32 v17, vcc, 0, v11, vcc
	v_add_co_u32_e32 v18, vcc, s76, v10
	s_mov_b32 s76, 0x19698000
	s_nop 0
	v_addc_co_u32_e32 v19, vcc, 0, v11, vcc
	v_ashrrev_i32_e32 v9, 31, v8
	v_add_co_u32_e32 v20, vcc, s76, v10
	v_lshl_add_u64 v[8:9], v[8:9], 2, s[96:97]
	s_nop 0
	v_addc_co_u32_e32 v21, vcc, 0, v11, vcc
	s_mov_b32 s76, 0x500000
	v_add_co_u32_e32 v8, vcc, s76, v8
	s_mov_b32 s76, 0x196a0000
	s_nop 0
	v_addc_co_u32_e32 v9, vcc, 0, v9, vcc
	global_load_dwordx2 v[8:9], v[8:9], off
	s_nop 0
	global_load_dword v52, v[14:15], off
	global_load_dword v53, v[14:15], off offset:256
	global_load_dword v54, v[16:17], off
	global_load_dword v55, v[16:17], off offset:256
	global_load_dword v56, v[18:19], off
	global_load_dword v57, v[18:19], off offset:256
	global_load_dword v58, v[20:21], off
	global_load_dword v59, v[20:21], off offset:256
	v_add_co_u32_e32 v14, vcc, s76, v10
	s_mov_b32 s76, 0x196a8000
	s_nop 0
	v_addc_co_u32_e32 v15, vcc, 0, v11, vcc
	v_add_co_u32_e32 v16, vcc, s76, v10
	s_mov_b32 s76, 0x196b0000
	s_nop 0
	v_addc_co_u32_e32 v17, vcc, 0, v11, vcc
	v_add_co_u32_e32 v18, vcc, s76, v10
	s_mov_b32 s76, 0x196b8000
	s_nop 0
	v_addc_co_u32_e32 v19, vcc, 0, v11, vcc
	v_add_co_u32_e32 v20, vcc, s76, v10
	s_mov_b32 s76, 0x196c0000
	s_nop 0
	v_addc_co_u32_e32 v21, vcc, 0, v11, vcc
	global_load_dword v60, v[14:15], off
	global_load_dword v61, v[14:15], off offset:256
	global_load_dword v62, v[16:17], off
	global_load_dword v63, v[16:17], off offset:256
	global_load_dword v64, v[18:19], off
	global_load_dword v65, v[18:19], off offset:256
	global_load_dword v66, v[20:21], off
	global_load_dword v67, v[20:21], off offset:256
; __global__ void __launch_bounds__(NTHR, 2) mk_fwd(Args args) {
;     ...
;             const float* Eg = p_E + g * 128 + p + (size_t)(sg * 32) * 8192;
;             float sr = 0.f, si = 0.f;
; #pragma unroll
;             for (int cb = 0; cb < 32; cb += 16) { float er[16], ei[16];
; #pragma unroll
;                 for (int k = 0; k < 16; ++k) { er[k] = Eg[(size_t)(cb + k) * 8192]; ei[k] = Eg[(size_t)(cb + k) * 8192 + 64]; }
; #pragma unroll
;                 for (int k = 0; k < 16; ++k) { const float nr = ar * sr - ai * si + er[k], ni = ar * si + ai * sr + ei[k]; sr = nr; si = ni; } }
	v_add_co_u32_e32 v14, vcc, s76, v10
	s_mov_b32 s76, 0x196c8000
	s_nop 0
	v_addc_co_u32_e32 v15, vcc, 0, v11, vcc
	v_add_co_u32_e32 v16, vcc, s76, v10
	s_mov_b32 s76, 0x196d0000
	s_nop 0
	v_addc_co_u32_e32 v17, vcc, 0, v11, vcc
	v_add_co_u32_e32 v18, vcc, s76, v10
	s_mov_b32 s76, 0x196d8000
	s_nop 0
	v_addc_co_u32_e32 v19, vcc, 0, v11, vcc
	v_add_co_u32_e32 v20, vcc, s76, v10
	s_mov_b32 s76, 0x196e0000
	s_nop 0
	v_addc_co_u32_e32 v21, vcc, 0, v11, vcc
	global_load_dword v68, v[14:15], off
	global_load_dword v69, v[14:15], off offset:256
	global_load_dword v70, v[16:17], off
	global_load_dword v71, v[16:17], off offset:256
	global_load_dword v72, v[18:19], off
	global_load_dword v73, v[18:19], off offset:256
	global_load_dword v74, v[20:21], off
	global_load_dword v75, v[20:21], off offset:256
	v_add_co_u32_e32 v14, vcc, s76, v10
	s_mov_b32 s76, 0x196e8000
	s_nop 0
	v_addc_co_u32_e32 v15, vcc, 0, v11, vcc
	v_add_co_u32_e32 v16, vcc, s76, v10
	s_mov_b32 s76, 0x196f0000
	s_nop 0
	v_addc_co_u32_e32 v17, vcc, 0, v11, vcc
	v_add_co_u32_e32 v18, vcc, s76, v10
	s_mov_b32 s76, 0x196f8000
	s_nop 0
	v_addc_co_u32_e32 v19, vcc, 0, v11, vcc
	v_add_co_u32_e32 v20, vcc, s76, v10
	s_nop 1
	v_addc_co_u32_e32 v21, vcc, 0, v11, vcc
	global_load_dword v76, v[14:15], off
	s_nop 0
	global_load_dword v14, v[14:15], off offset:256
	s_nop 0
	global_load_dword v15, v[16:17], off
	s_nop 0
	global_load_dword v16, v[16:17], off offset:256
	s_nop 0
	global_load_dword v17, v[18:19], off
	s_nop 0
	global_load_dword v18, v[18:19], off offset:256
	s_nop 0
	global_load_dword v19, v[20:21], off
	s_nop 0
	global_load_dword v20, v[20:21], off offset:256
	s_waitcnt vmcnt(0) lgkmcnt(0)
	v_mul_f32_e32 v21, 0, v9
	v_fma_f32 v77, v8, 0, -v21
	v_fmac_f32_e32 v21, 0, v8
	v_add_f32_e32 v21, v21, v27
	v_add_f32_e32 v2, v77, v2
	v_mul_f32_e32 v27, v9, v21
	v_fma_f32 v27, v8, v2, -v27
	v_mul_f32_e32 v2, v9, v2
	v_fmac_f32_e32 v2, v8, v21
	v_add_f32_e32 v2, v2, v22
	v_add_f32_e32 v6, v27, v6
	v_mul_f32_e32 v21, v9, v2
	v_fma_f32 v21, v8, v6, -v21
	v_mul_f32_e32 v6, v9, v6
	v_fmac_f32_e32 v6, v8, v2
	v_add_f32_e32 v2, v6, v24
	v_add_f32_e32 v21, v21, v23
	v_mul_f32_e32 v6, v9, v2
	v_fma_f32 v6, v8, v21, -v6
	v_mul_f32_e32 v21, v9, v21
	v_fmac_f32_e32 v21, v8, v2
	v_add_f32_e32 v2, v21, v26
	v_add_f32_e32 v6, v6, v25
	v_mul_f32_e32 v21, v9, v2
	v_fma_f32 v21, v8, v6, -v21
	v_mul_f32_e32 v6, v9, v6
	v_fmac_f32_e32 v6, v8, v2
	v_add_f32_e32 v2, v6, v29
	v_add_f32_e32 v21, v21, v28
	v_mul_f32_e32 v6, v9, v2
	v_fma_f32 v6, v8, v21, -v6
	v_mul_f32_e32 v21, v9, v21
	v_fmac_f32_e32 v21, v8, v2
	v_add_f32_e32 v2, v21, v31
	v_add_f32_e32 v6, v6, v30
	v_mul_f32_e32 v21, v9, v2
	v_fma_f32 v21, v8, v6, -v21
	v_mul_f32_e32 v6, v9, v6
	v_fmac_f32_e32 v6, v8, v2
	v_add_f32_e32 v2, v6, v33
	v_add_f32_e32 v21, v21, v32
	v_mul_f32_e32 v6, v9, v2
	v_fma_f32 v6, v8, v21, -v6
	v_mul_f32_e32 v21, v9, v21
	v_fmac_f32_e32 v21, v8, v2
	v_add_f32_e32 v2, v21, v35
	v_add_f32_e32 v6, v6, v34
	v_mul_f32_e32 v21, v9, v2
	v_fma_f32 v21, v8, v6, -v21
	v_mul_f32_e32 v6, v9, v6
	v_fmac_f32_e32 v6, v8, v2
	v_add_f32_e32 v2, v6, v37
	v_add_f32_e32 v21, v21, v36
	v_mul_f32_e32 v6, v9, v2
	v_fma_f32 v6, v8, v21, -v6
	v_mul_f32_e32 v21, v9, v21
	v_fmac_f32_e32 v21, v8, v2
	v_add_f32_e32 v2, v21, v39
	v_add_f32_e32 v6, v6, v38
	v_mul_f32_e32 v21, v9, v2
	v_fma_f32 v21, v8, v6, -v21
	v_mul_f32_e32 v6, v9, v6
	v_fmac_f32_e32 v6, v8, v2
	v_add_f32_e32 v2, v6, v41
	v_add_f32_e32 v21, v21, v40
	v_mul_f32_e32 v6, v9, v2
	v_fma_f32 v6, v8, v21, -v6
	v_mul_f32_e32 v21, v9, v21
	v_fmac_f32_e32 v21, v8, v2
	v_add_f32_e32 v2, v21, v43
	v_add_f32_e32 v6, v6, v42
	v_mul_f32_e32 v21, v9, v2
	v_fma_f32 v21, v8, v6, -v21
	v_mul_f32_e32 v6, v9, v6
	v_fmac_f32_e32 v6, v8, v2
	v_add_f32_e32 v2, v6, v45
	v_add_f32_e32 v21, v21, v44
	v_mul_f32_e32 v6, v9, v2
	v_fma_f32 v6, v8, v21, -v6
	v_mul_f32_e32 v21, v9, v21
	v_fmac_f32_e32 v21, v8, v2
	v_add_f32_e32 v2, v21, v47
	v_add_f32_e32 v6, v6, v46
	v_mul_f32_e32 v21, v9, v2
	v_fma_f32 v21, v8, v6, -v21
	v_mul_f32_e32 v6, v9, v6
	v_fmac_f32_e32 v6, v8, v2
	v_add_f32_e32 v2, v6, v49
	v_add_f32_e32 v21, v21, v48
	v_mul_f32_e32 v6, v9, v2
	v_fma_f32 v6, v8, v21, -v6
	v_mul_f32_e32 v21, v9, v21
	v_fmac_f32_e32 v21, v8, v2
	v_add_f32_e32 v2, v21, v51
	v_add_f32_e32 v6, v6, v50
	v_mul_f32_e32 v21, v9, v2
	v_fma_f32 v21, v8, v6, -v21
	v_mul_f32_e32 v6, v9, v6
	v_fmac_f32_e32 v6, v8, v2
	v_add_f32_e32 v2, v6, v53
	v_add_f32_e32 v21, v21, v52
	v_mul_f32_e32 v6, v9, v2
	v_fma_f32 v6, v8, v21, -v6
	v_mul_f32_e32 v21, v9, v21
; __global__ void __launch_bounds__(NTHR, 2) mk_fwd(Args args) {
;     ...
;                 for (int k = 0; k < 16; ++k) { const float nr = ar * sr - ai * si + er[k], ni = ar * si + ai * sr + ei[k]; sr = nr; si = ni; } }
;             sl[(sg * 2) * 16 + (lane & 15)] = sr; sl[(sg * 2 + 1) * 16 + (lane & 15)] = si;
;             float pr = ar, pi = ai;
; #pragma unroll
;             for (int k = 0; k < 5; ++k) { const float t = pr * pr - pi * pi; pi = 2.0f * pr * pi; pr = t; }
;             __syncthreads();
;             float ir = 0.f, ii = 0.f;
;             for (int w2 = 0; w2 < 32; ++w2) { if (w2 < sg) { const float lr = sl[(w2 * 2) * 16 + (lane & 15)], li = sl[(w2 * 2 + 1) * 16 + (lane & 15)]; const float nr = pr * ir - pi * ii + lr, ni = pr * ii + pi * ir + li; ir = nr; ii = ni; } }
	v_fmac_f32_e32 v21, v8, v2
	v_add_f32_e32 v2, v21, v55
	v_add_f32_e32 v6, v6, v54
	v_mul_f32_e32 v21, v9, v2
	v_fma_f32 v21, v8, v6, -v21
	v_mul_f32_e32 v6, v9, v6
	v_fmac_f32_e32 v6, v8, v2
	v_add_f32_e32 v2, v6, v57
	v_add_f32_e32 v21, v21, v56
	v_mul_f32_e32 v6, v9, v2
	v_fma_f32 v6, v8, v21, -v6
	v_mul_f32_e32 v21, v9, v21
	v_fmac_f32_e32 v21, v8, v2
	v_add_f32_e32 v2, v21, v59
	v_add_f32_e32 v6, v6, v58
	v_mul_f32_e32 v21, v9, v2
	v_fma_f32 v21, v8, v6, -v21
	v_mul_f32_e32 v6, v9, v6
	v_fmac_f32_e32 v6, v8, v2
	v_add_f32_e32 v2, v6, v61
	v_add_f32_e32 v21, v21, v60
	v_mul_f32_e32 v6, v9, v2
	v_fma_f32 v6, v8, v21, -v6
	v_mul_f32_e32 v21, v9, v21
	v_fmac_f32_e32 v21, v8, v2
	v_add_f32_e32 v2, v21, v63
	v_add_f32_e32 v6, v6, v62
	v_mul_f32_e32 v21, v9, v2
	v_fma_f32 v21, v8, v6, -v21
	v_mul_f32_e32 v6, v9, v6
	v_fmac_f32_e32 v6, v8, v2
	v_add_f32_e32 v2, v6, v65
	v_add_f32_e32 v21, v21, v64
	v_mul_f32_e32 v6, v9, v2
	v_fma_f32 v6, v8, v21, -v6
	v_mul_f32_e32 v21, v9, v21
	v_fmac_f32_e32 v21, v8, v2
	v_add_f32_e32 v2, v21, v67
	v_add_f32_e32 v6, v6, v66
	v_mul_f32_e32 v21, v9, v2
	v_fma_f32 v21, v8, v6, -v21
	v_mul_f32_e32 v6, v9, v6
	v_fmac_f32_e32 v6, v8, v2
	v_add_f32_e32 v2, v6, v69
	v_add_f32_e32 v21, v21, v68
	v_mul_f32_e32 v6, v9, v2
	v_fma_f32 v6, v8, v21, -v6
	v_mul_f32_e32 v21, v9, v21
	v_fmac_f32_e32 v21, v8, v2
	v_add_f32_e32 v2, v21, v71
	v_add_f32_e32 v6, v6, v70
	v_mul_f32_e32 v21, v9, v2
	v_fma_f32 v21, v8, v6, -v21
	v_mul_f32_e32 v6, v9, v6
	v_fmac_f32_e32 v6, v8, v2
	v_add_f32_e32 v2, v6, v73
	v_add_f32_e32 v21, v21, v72
	v_mul_f32_e32 v6, v9, v2
	v_fma_f32 v6, v8, v21, -v6
	v_mul_f32_e32 v21, v9, v21
	v_fmac_f32_e32 v21, v8, v2
	v_add_f32_e32 v2, v21, v75
	v_add_f32_e32 v6, v6, v74
	v_mul_f32_e32 v21, v9, v2
	v_fma_f32 v21, v8, v6, -v21
	v_mul_f32_e32 v6, v9, v6
	v_add_f32_e32 v21, v21, v76
	v_fmac_f32_e32 v6, v8, v2
	v_add_f32_e32 v2, v6, v14
	v_mul_f32_e32 v14, v9, v21
	v_mul_f32_e32 v6, v9, v2
	v_fmac_f32_e32 v14, v8, v2
	v_fma_f32 v6, v8, v21, -v6
	v_add_f32_e32 v2, v14, v16
	v_add_f32_e32 v6, v6, v15
	v_mul_f32_e32 v14, v9, v2
	v_fma_f32 v14, v8, v6, -v14
	v_mul_f32_e32 v6, v9, v6
	v_fmac_f32_e32 v6, v8, v2
	v_add_f32_e32 v2, v6, v18
	v_add_f32_e32 v14, v14, v17
	v_mul_f32_e32 v6, v9, v2
	v_fma_f32 v6, v8, v14, -v6
	v_mul_f32_e32 v14, v9, v14
	v_fmac_f32_e32 v14, v8, v2
	v_add_f32_e32 v6, v6, v19
	v_add_f32_e32 v2, v14, v20
	ds_write2_b32 v132, v6, v2 offset1:16
	v_mul_f32_e32 v2, v8, v8
	v_pk_fma_f32 v[14:15], v[8:9], v[8:9], v[2:3] op_sel_hi:[1,1,0] neg_lo:[1,0,0] neg_hi:[1,0,0]
	v_add_f32_e32 v16, v8, v8
	v_mov_b32_e32 v6, v9
	v_mov_b32_e32 v17, v15
	v_pk_mul_f32 v[16:17], v[6:7], v[16:17]
	s_waitcnt lgkmcnt(0)
	v_pk_mov_b32 v[18:19], v[14:15], v[16:17] op_sel:[1,0]
	v_mov_b32_e32 v14, v15
	v_mov_b32_e32 v15, v17
	v_pk_mul_f32 v[14:15], v[18:19], v[14:15]
	v_pk_mul_f32 v[18:19], v[16:17], v[16:17] op_sel_hi:[0,1]
	v_pk_fma_f32 v[16:17], v[16:17], v[16:17], v[14:15] op_sel_hi:[0,1,1] neg_lo:[1,0,0] neg_hi:[1,0,0]
	v_pk_mul_f32 v[18:19], v[14:15], v[18:19]
	v_mov_b32_e32 v6, v16
	v_pk_mul_f32 v[20:21], v[16:17], v[6:7] op_sel_hi:[0,1]
	v_mov_b32_e32 v14, v19
	v_pk_fma_f32 v[16:17], v[16:17], v[6:7], v[14:15] op_sel_hi:[0,1,1] neg_lo:[0,0,1] neg_hi:[0,0,1]
	v_pk_mul_f32 v[14:15], v[20:21], v[14:15]
	v_mul_f32_e32 v2, v16, v16
	v_mov_b32_e32 v17, v15
	v_pk_fma_f32 v[18:19], v[16:17], v[16:17], v[2:3] op_sel_hi:[1,1,0] neg_lo:[1,0,0] neg_hi:[1,0,0]
	v_add_f32_e32 v14, v16, v16
	v_mov_b32_e32 v16, v15
	v_mov_b32_e32 v17, v19
	v_mov_b32_e32 v15, v19
	v_pk_mul_f32 v[16:17], v[16:17], v[14:15]
	v_mov_b32_e32 v2, v3
	v_pk_mov_b32 v[14:15], v[18:19], v[16:17] op_sel:[1,0]
	v_mov_b32_e32 v18, v7
	v_mov_b32_e32 v19, v16
	v_pk_mul_f32 v[20:21], v[14:15], v[18:19]
	v_pk_fma_f32 v[14:15], v[14:15], v[18:19], v[16:17] neg_lo:[1,0,0] neg_hi:[1,0,0]
	v_pk_mul_f32 v[16:17], v[16:17], v[20:21]
	v_mov_b32_e32 v21, v15
	v_mov_b32_e32 v20, v16
	v_mov_b64_e32 v[18:19], v[2:3]
	s_barrier
	s_and_saveexec_b64 s[76:77], s[0:1]
	s_cbranch_execz .LBB0_864
	ds_read2_b32 v[18:19], v131 offset1:16
	v_pk_mul_f32 v[22:23], v[20:21], 0 op_sel_hi:[1,0]
	s_nop 0
	v_pk_fma_f32 v[24:25], v[20:21], 0, v[22:23] op_sel:[0,0,1] op_sel_hi:[1,0,0]
	v_pk_fma_f32 v[22:23], v[20:21], 0, v[22:23] op_sel_hi:[1,0,0] neg_lo:[0,0,1] neg_hi:[0,0,1]
	s_nop 0
	v_mov_b32_e32 v25, v23
	s_waitcnt lgkmcnt(0)
	v_mov_b32_e32 v22, v19
	v_mov_b32_e32 v23, v18
	v_pk_add_f32 v[18:19], v[24:25], v[22:23]
	s_or_b64 exec, exec, s[76:77]
	s_and_saveexec_b64 s[76:77], s[4:5]
	s_cbranch_execnz .LBB0_865

; __device__ __forceinline__ float bf_lo(unsigned w) { return __uint_as_float(w << 16); }
; __device__ __forceinline__ float bf_hi(unsigned w) { return __uint_as_float(w & 0xffff0000u); }
; __device__ __forceinline__ u32x4 pack8(const f32x4& v0, const f32x4& v1) { u32x4 w; w.x = cvt_pk_bf16(v0[0], v0[1]); w.y = cvt_pk_bf16(v0[2], v0[3]); w.z = cvt_pk_bf16(v1[0], v1[1]); w.w = cvt_pk_bf16(v1[2], v1[3]); return w; }
;     __device__ __forceinline__ void operator()(const f32x4 (&acc)[2][2][4][2], const Unit& u, int wr, int wc, int fr_, int fq_) const {
;     ...
;         const int row0 = u.pm * BM + wr * 64 + fr, g = u.pz, col0 = wc * 32 + 8 * fq, co0 = col0 & 15;
;         const f32x4 d0 = *(const f32x4*)(dskip + g * 16 + co0), d1 = *(const f32x4*)(dskip + g * 16 + co0 + 4);
;         const bf16_t* up = U + ((size_t)(row0 * 64 + g) * 384 + col0);
;         bf16_t* yp = YG + ((size_t)row0 * 16 + (col0 >> 4)) * 1024 + g * 16 + co0;
;         u32x4 uwv[2][2];
; #pragma unroll
;         for (int ai = 0; ai < 2; ++ai)
; #pragma unroll
;             for (int m = 0; m < 4; ++m) {
;                 asm volatile("" : "+v"(up), "+v"(yp));
;                 if ((m & 1) == 0) {
;                     uwv[0][0] = *(const u32x4*)(up); uwv[0][1] = *(const u32x4*)(up + 128);
;                     uwv[1][0] = *(const u32x4*)(up + (size_t)16 * 64 * 384); uwv[1][1] = *(const u32x4*)(up + (size_t)16 * 64 * 384 + 128);
;                     asm volatile("" ::: "memory"); }
; #pragma unroll
;                 for (int bj = 0; bj < 2; ++bj) {
;                     const u32x4 uw = uwv[m & 1][bj];
;                     f32x4 v0 = acc[ai][bj][m][0], v1 = acc[ai][bj][m][1];
;                     v0[0] += d0[0] * bf_lo(uw.x); v0[1] += d0[1] * bf_hi(uw.x); v0[2] += d0[2] * bf_lo(uw.y); v0[3] += d0[3] * bf_hi(uw.y);
;                     v1[0] += d1[0] * bf_lo(uw.z); v1[1] += d1[1] * bf_hi(uw.z); v1[2] += d1[2] * bf_lo(uw.w); v1[3] += d1[3] * bf_hi(uw.w);
; #pragma unroll
;                     for (int k = 0; k < 4; ++k) { v0[k] = gelu_tanh_f(v0[k]); v1[k] = gelu_tanh_f(v1[k]); }
;                     *(u32x4*)(yp + bj * 8 * 1024) = pack8(v0, v1); }
.LBB0_960:
	s_lshl_b32 s40, s64, 8
	s_add_i32 s40, s40, s51
	v_mbcnt_lo_u32_b32 v16, -1, 0
	v_mbcnt_hi_u32_b32 v16, -1, v16
	v_mov_b64_e32 v[140:141], s[8:9]
	v_and_or_b32 v120, v16, 15, s40
	s_lshl_b32 s40, s63, 4
	s_ashr_i32 s41, s40, 31
	v_ashrrev_i32_e32 v16, 1, v16
	s_lshl_b64 s[42:43], s[40:41], 2
	v_and_b32_e32 v17, -8, v16
	v_and_b32_e32 v142, 8, v16
	s_add_u32 s42, s7, s42
	v_add_u32_e32 v122, s52, v17
	s_addc_u32 s43, s33, s43
	v_lshlrev_b32_e32 v152, 2, v142
	v_lshl_add_u32 v121, v120, 6, s63
	v_lshl_add_u64 v[16:17], s[42:43], 0, v[152:153]
	v_ashrrev_i32_e32 v123, 31, v122
	v_mad_i64_i32 v[140:141], s[42:43], v121, s59, v[140:141]
	v_lshl_add_u64 v[140:141], v[122:123], 1, v[140:141]
	v_ashrrev_i32_e32 v121, 31, v120
	v_ashrrev_i32_e32 v122, 4, v122
	v_ashrrev_i32_e32 v123, 31, v122
	v_lshlrev_b64 v[120:121], 15, v[120:121]
	v_lshl_add_u64 v[120:121], s[12:13], 0, v[120:121]
	v_lshlrev_b64 v[122:123], 11, v[122:123]
	v_lshl_add_u64 v[120:121], v[120:121], 0, v[122:123]
	v_lshl_add_u64 v[120:121], s[40:41], 1, v[120:121]
	v_lshlrev_b32_e32 v152, 1, v142
	v_lshl_add_u64 v[160:161], v[120:121], 0, v[152:153]
	global_load_dwordx4 v[20:23], v[16:17], off
	s_nop 0
	global_load_dwordx4 v[16:19], v[16:17], off offset:16
	global_load_dwordx4 v[166:169], v[140:141], off
	global_load_dwordx4 v[170:173], v[140:141], off offset:256
	v_add_co_u32_e32 v120, vcc, s60, v140
	v_lshl_add_u64 v[158:159], v[140:141], 0, s[28:29]
	s_nop 0
	v_addc_co_u32_e32 v121, vcc, 0, v141, vcc
	global_load_dwordx4 v[140:143], v[120:121], off
	s_nop 0
	global_load_dwordx4 v[120:123], v[120:121], off offset:256
	s_waitcnt vmcnt(0) lgkmcnt(0)
	v_and_b32_e32 v154, 0xffff0000, v166
	v_lshlrev_b32_e32 v152, 16, v166
	v_lshlrev_b32_e32 v155, 16, v167
	v_and_b32_e32 v166, 0xffff0000, v168
	v_fma_f32 v133, v21, v154, v133
	v_and_b32_e32 v156, 0xffff0000, v167
	v_fma_f32 v134, v22, v155, v134
	v_fma_f32 v137, v17, v166, v137
	v_mul_f32_e32 v155, 0x3d372713, v133
	v_fmac_f32_e32 v135, v23, v156
	v_mul_f32_e32 v156, 0x3d372713, v137
	v_mul_f32_e32 v155, v133, v155
	v_mul_f32_e32 v156, v137, v156
	v_fma_f32 v155, v133, v155, v133
	v_fma_f32 v132, v20, v152, v132
	v_fma_f32 v156, v137, v156, v137
	v_mul_f32_e32 v155, 0x3f4c422a, v155
	v_mul_f32_e32 v152, 0x3d372713, v132
	v_mul_f32_e32 v156, 0x3f4c422a, v156
	v_add_f32_e32 v155, v155, v155
	v_mul_f32_e32 v152, v132, v152
	v_add_f32_e32 v156, v156, v156
	v_mul_f32_e32 v155, 0xbfb8aa3b, v155
	v_fma_f32 v152, v132, v152, v132
	v_mul_f32_e32 v156, 0xbfb8aa3b, v156
	v_exp_f32_e32 v155, v155
	v_mul_f32_e32 v152, 0x3f4c422a, v152
	v_exp_f32_e32 v156, v156
	v_lshlrev_b32_e32 v157, 16, v168
	v_add_f32_e32 v152, v152, v152
	v_fma_f32 v136, v16, v157, v136
	v_mul_f32_e32 v152, 0xbfb8aa3b, v152
	v_mul_f32_e32 v154, 0x3d372713, v136
	v_exp_f32_e32 v152, v152
	v_add_f32_e32 v155, 1.0, v155
	v_mul_f32_e32 v154, v136, v154
	v_add_f32_e32 v156, 1.0, v156
	v_rcp_f32_e32 v155, v155
	v_fma_f32 v154, v136, v154, v136
	v_rcp_f32_e32 v156, v156
	v_mul_f32_e32 v154, 0x3f4c422a, v154
	v_lshlrev_b32_e32 v167, 16, v169
	v_and_b32_e32 v168, 0xffff0000, v169
	v_add_f32_e32 v154, v154, v154
	v_add_f32_e32 v152, 1.0, v152
	v_fma_f32 v138, v18, v167, v138
	v_fmac_f32_e32 v139, v19, v168
	v_mul_f32_e32 v157, 0x3d372713, v134
	v_mul_f32_e32 v154, 0xbfb8aa3b, v154
	v_rcp_f32_e32 v152, v152
	v_mul_f32_e32 v133, v133, v155
	v_mul_f32_e32 v155, 0x3d372713, v135
	v_mul_f32_e32 v166, 0x3d372713, v138
	v_mul_f32_e32 v157, v134, v157
	v_exp_f32_e32 v154, v154
	v_mul_f32_e32 v137, v137, v156
	v_mul_f32_e32 v155, v135, v155
	v_mul_f32_e32 v156, 0x3d372713, v139
	v_mul_f32_e32 v166, v138, v166
	v_fma_f32 v157, v134, v157, v134
	v_fma_f32 v155, v135, v155, v135
	v_mul_f32_e32 v156, v139, v156
	v_fma_f32 v166, v138, v166, v138
	v_mul_f32_e32 v157, 0x3f4c422a, v157
	v_mul_f32_e32 v155, 0x3f4c422a, v155
	v_fma_f32 v156, v139, v156, v139
	v_add_f32_e32 v157, v157, v157
	v_mul_f32_e32 v132, v132, v152
	v_mul_f32_e32 v152, 0x3f4c422a, v166
	v_add_f32_e32 v155, v155, v155
	v_mul_f32_e32 v156, 0x3f4c422a, v156
	v_mul_f32_e32 v157, 0xbfb8aa3b, v157
	v_add_f32_e32 v154, 1.0, v154
	v_add_f32_e32 v152, v152, v152
	v_mul_f32_e32 v155, 0xbfb8aa3b, v155
	v_add_f32_e32 v156, v156, v156
	v_exp_f32_e32 v157, v157
	v_rcp_f32_e32 v154, v154
	v_mul_f32_e32 v152, 0xbfb8aa3b, v152
	v_exp_f32_e32 v155, v155
	v_mul_f32_e32 v156, 0xbfb8aa3b, v156
	v_exp_f32_e32 v152, v152
	v_exp_f32_e32 v156, v156
	v_mul_f32_e32 v136, v136, v154
	v_add_f32_e32 v154, 1.0, v157
	v_add_f32_e32 v155, 1.0, v155
	v_rcp_f32_e32 v154, v154
	v_add_f32_e32 v152, 1.0, v152
	v_rcp_f32_e32 v155, v155
	v_add_f32_e32 v156, 1.0, v156
	v_rcp_f32_e32 v152, v152
	v_rcp_f32_e32 v156, v156
	v_mul_f32_e32 v134, v134, v154
	v_mul_f32_e32 v135, v135, v155
	v_cvt_pk_bf16_f32 v132, v132, v133
	v_mul_f32_e32 v138, v138, v152
	v_mul_f32_e32 v139, v139, v156
	v_cvt_pk_bf16_f32 v133, v134, v135
	v_cvt_pk_bf16_f32 v134, v136, v137
	v_cvt_pk_bf16_f32 v135, v138, v139
	global_store_dwordx4 v[160:161], v[132:135], off
	s_nop 1
	v_lshlrev_b32_e32 v132, 16, v170
	v_fma_f32 v124, v20, v132, v124
	v_mul_f32_e32 v133, 0x3d372713, v124
	v_mul_f32_e32 v133, v124, v133
	v_fma_f32 v133, v124, v133, v124
	v_and_b32_e32 v132, 0xffff0000, v170
	v_mul_f32_e32 v133, 0x3f4c422a, v133
	v_fma_f32 v125, v21, v132, v125
	v_lshlrev_b32_e32 v132, 16, v171
	v_add_f32_e32 v133, v133, v133
	v_fma_f32 v126, v22, v132, v126
	v_and_b32_e32 v132, 0xffff0000, v171
	v_mul_f32_e32 v133, 0xbfb8aa3b, v133
	v_fmac_f32_e32 v127, v23, v132
	v_lshlrev_b32_e32 v132, 16, v172
	v_exp_f32_e32 v133, v133
	v_fma_f32 v128, v16, v132, v128
	v_and_b32_e32 v132, 0xffff0000, v172
; __device__ __forceinline__ float bf_lo(unsigned w) { return __uint_as_float(w << 16); }
; __device__ __forceinline__ float bf_hi(unsigned w) { return __uint_as_float(w & 0xffff0000u); }
; __device__ __forceinline__ u32x4 pack8(const f32x4& v0, const f32x4& v1) { u32x4 w; w.x = cvt_pk_bf16(v0[0], v0[1]); w.y = cvt_pk_bf16(v0[2], v0[3]); w.z = cvt_pk_bf16(v1[0], v1[1]); w.w = cvt_pk_bf16(v1[2], v1[3]); return w; }
;     __device__ __forceinline__ void operator()(const f32x4 (&acc)[2][2][4][2], const Unit& u, int wr, int wc, int fr_, int fq_) const {
;     ...
; #pragma unroll
;                 for (int bj = 0; bj < 2; ++bj) {
;                     const u32x4 uw = uwv[m & 1][bj];
;                     f32x4 v0 = acc[ai][bj][m][0], v1 = acc[ai][bj][m][1];
;                     v0[0] += d0[0] * bf_lo(uw.x); v0[1] += d0[1] * bf_hi(uw.x); v0[2] += d0[2] * bf_lo(uw.y); v0[3] += d0[3] * bf_hi(uw.y);
;                     v1[0] += d1[0] * bf_lo(uw.z); v1[1] += d1[1] * bf_hi(uw.z); v1[2] += d1[2] * bf_lo(uw.w); v1[3] += d1[3] * bf_hi(uw.w);
; #pragma unroll
;                     for (int k = 0; k < 4; ++k) { v0[k] = gelu_tanh_f(v0[k]); v1[k] = gelu_tanh_f(v1[k]); }
;                     *(u32x4*)(yp + bj * 8 * 1024) = pack8(v0, v1); }
	v_fma_f32 v129, v17, v132, v129
	v_lshlrev_b32_e32 v132, 16, v173
	v_fma_f32 v130, v18, v132, v130
	v_and_b32_e32 v132, 0xffff0000, v173
	v_fmac_f32_e32 v131, v19, v132
	v_add_f32_e32 v132, 1.0, v133
	v_mul_f32_e32 v133, 0x3d372713, v128
	v_mul_f32_e32 v134, 0x3d372713, v125
	v_mul_f32_e32 v133, v128, v133
	v_mul_f32_e32 v134, v125, v134
	v_fma_f32 v133, v128, v133, v128
	v_fma_f32 v134, v125, v134, v125
	v_mul_f32_e32 v133, 0x3f4c422a, v133
	v_mul_f32_e32 v134, 0x3f4c422a, v134
	v_add_f32_e32 v133, v133, v133
	v_add_f32_e32 v134, v134, v134
	v_mul_f32_e32 v133, 0xbfb8aa3b, v133
	v_mul_f32_e32 v134, 0xbfb8aa3b, v134
	v_exp_f32_e32 v133, v133
	v_exp_f32_e32 v134, v134
	v_mul_f32_e32 v135, 0x3d372713, v129
	v_mul_f32_e32 v135, v129, v135
	v_add_f32_e32 v133, 1.0, v133
	v_add_f32_e32 v134, 1.0, v134
	v_rcp_f32_e32 v133, v133
	v_rcp_f32_e32 v134, v134
	v_fma_f32 v135, v129, v135, v129
	v_mul_f32_e32 v135, 0x3f4c422a, v135
	v_add_f32_e32 v135, v135, v135
	v_mul_f32_e32 v135, 0xbfb8aa3b, v135
	v_mul_f32_e32 v128, v128, v133
	v_mul_f32_e32 v125, v125, v134
	v_mul_f32_e32 v133, 0x3d372713, v126
	v_mul_f32_e32 v134, 0x3d372713, v130
	v_rcp_f32_e32 v132, v132
	v_exp_f32_e32 v135, v135
	v_mul_f32_e32 v133, v126, v133
	v_mul_f32_e32 v134, v130, v134
	v_fma_f32 v133, v126, v133, v126
	v_fma_f32 v134, v130, v134, v130
	v_mul_f32_e32 v133, 0x3f4c422a, v133
	v_mul_f32_e32 v134, 0x3f4c422a, v134
	v_add_f32_e32 v133, v133, v133
	v_add_f32_e32 v134, v134, v134
	v_mul_f32_e32 v124, v124, v132
	v_add_f32_e32 v132, 1.0, v135
	v_mul_f32_e32 v133, 0xbfb8aa3b, v133
	v_mul_f32_e32 v134, 0xbfb8aa3b, v134
	v_rcp_f32_e32 v132, v132
	v_exp_f32_e32 v133, v133
	v_exp_f32_e32 v134, v134
	v_mul_f32_e32 v135, 0x3d372713, v131
	v_mul_f32_e32 v129, v129, v132
	v_add_f32_e32 v132, 1.0, v133
	v_add_f32_e32 v133, 1.0, v134
	v_mul_f32_e32 v134, 0x3d372713, v127
	v_mul_f32_e32 v134, v127, v134
	v_fma_f32 v134, v127, v134, v127
	v_mul_f32_e32 v134, 0x3f4c422a, v134
	v_mul_f32_e32 v135, v131, v135
	v_add_f32_e32 v134, v134, v134
	v_fma_f32 v135, v131, v135, v131
	v_mul_f32_e32 v134, 0xbfb8aa3b, v134
	v_mul_f32_e32 v135, 0x3f4c422a, v135
	v_exp_f32_e32 v134, v134
	v_add_f32_e32 v135, v135, v135
	v_mul_f32_e32 v135, 0xbfb8aa3b, v135
	v_exp_f32_e32 v135, v135
	v_rcp_f32_e32 v132, v132
	v_add_f32_e32 v134, 1.0, v134
	v_rcp_f32_e32 v134, v134
	v_add_f32_e32 v135, 1.0, v135
	v_rcp_f32_e32 v133, v133
	v_rcp_f32_e32 v135, v135
	v_mul_f32_e32 v126, v126, v132
	v_mul_f32_e32 v127, v127, v134
	v_cvt_pk_bf16_f32 v124, v124, v125
	v_cvt_pk_bf16_f32 v125, v126, v127
	v_cvt_pk_bf16_f32 v126, v128, v129
	v_add_co_u32_e32 v128, vcc, s50, v160
	v_mul_f32_e32 v130, v130, v133
	s_nop 0
	v_addc_co_u32_e32 v129, vcc, 0, v161, vcc
	v_mul_f32_e32 v131, v131, v135
	v_cvt_pk_bf16_f32 v127, v130, v131
	global_store_dwordx4 v[128:129], v[124:127], off
	s_nop 1
	v_lshlrev_b32_e32 v126, 16, v140
	v_fma_f32 v112, v20, v126, v112
	v_mul_f32_e32 v127, 0x3d372713, v112
	v_mul_f32_e32 v127, v112, v127
	v_fma_f32 v127, v112, v127, v112
	v_and_b32_e32 v126, 0xffff0000, v140
	v_mul_f32_e32 v127, 0x3f4c422a, v127
	v_fma_f32 v113, v21, v126, v113
	v_lshlrev_b32_e32 v126, 16, v141
	v_add_f32_e32 v127, v127, v127
	v_fma_f32 v114, v22, v126, v114
	v_and_b32_e32 v126, 0xffff0000, v141
	v_mul_f32_e32 v127, 0xbfb8aa3b, v127
	v_fmac_f32_e32 v115, v23, v126
	v_lshlrev_b32_e32 v126, 16, v142
	v_exp_f32_e32 v127, v127
	v_fma_f32 v116, v16, v126, v116
	v_and_b32_e32 v126, 0xffff0000, v142
	v_fma_f32 v117, v17, v126, v117
	v_lshlrev_b32_e32 v126, 16, v143
	v_fma_f32 v118, v18, v126, v118
	v_and_b32_e32 v126, 0xffff0000, v143
	v_fmac_f32_e32 v119, v19, v126
	v_add_f32_e32 v126, 1.0, v127
	v_mul_f32_e32 v127, 0x3d372713, v116
	v_mul_f32_e32 v128, 0x3d372713, v113
	v_mul_f32_e32 v127, v116, v127
	v_mul_f32_e32 v128, v113, v128
	v_fma_f32 v127, v116, v127, v116
	v_fma_f32 v128, v113, v128, v113
	v_mul_f32_e32 v127, 0x3f4c422a, v127
	v_mul_f32_e32 v128, 0x3f4c422a, v128
	v_add_f32_e32 v127, v127, v127
	v_add_f32_e32 v128, v128, v128
	v_mul_f32_e32 v127, 0xbfb8aa3b, v127
	v_mul_f32_e32 v128, 0xbfb8aa3b, v128
	v_exp_f32_e32 v127, v127
	v_exp_f32_e32 v128, v128
	v_mul_f32_e32 v129, 0x3d372713, v117
	v_mul_f32_e32 v129, v117, v129
	v_add_f32_e32 v127, 1.0, v127
	v_add_f32_e32 v128, 1.0, v128
	v_rcp_f32_e32 v127, v127
	v_rcp_f32_e32 v128, v128
	v_fma_f32 v129, v117, v129, v117
	v_mul_f32_e32 v129, 0x3f4c422a, v129
	v_add_f32_e32 v129, v129, v129
	v_mul_f32_e32 v129, 0xbfb8aa3b, v129
	v_mul_f32_e32 v116, v116, v127
	v_mul_f32_e32 v113, v113, v128
	v_mul_f32_e32 v127, 0x3d372713, v114
	v_mul_f32_e32 v128, 0x3d372713, v118
	v_rcp_f32_e32 v126, v126
	v_exp_f32_e32 v129, v129
	v_mul_f32_e32 v127, v114, v127
	v_mul_f32_e32 v128, v118, v128
	v_fma_f32 v127, v114, v127, v114
	v_fma_f32 v128, v118, v128, v118
	v_mul_f32_e32 v127, 0x3f4c422a, v127
	v_mul_f32_e32 v128, 0x3f4c422a, v128
	v_add_f32_e32 v127, v127, v127
	v_add_f32_e32 v128, v128, v128
	v_mul_f32_e32 v112, v112, v126
	v_add_f32_e32 v126, 1.0, v129
	v_mul_f32_e32 v127, 0xbfb8aa3b, v127
	v_mul_f32_e32 v128, 0xbfb8aa3b, v128
	v_rcp_f32_e32 v126, v126
	v_exp_f32_e32 v127, v127
	v_exp_f32_e32 v128, v128
	v_mul_f32_e32 v129, 0x3d372713, v119
	v_mul_f32_e32 v117, v117, v126
	v_add_f32_e32 v126, 1.0, v127
	v_add_f32_e32 v127, 1.0, v128
	v_mul_f32_e32 v128, 0x3d372713, v115
	v_mul_f32_e32 v128, v115, v128
	v_fma_f32 v128, v115, v128, v115
	v_mul_f32_e32 v129, v119, v129
	v_mul_f32_e32 v128, 0x3f4c422a, v128
	v_fma_f32 v129, v119, v129, v119
	v_add_f32_e32 v128, v128, v128
	v_mul_f32_e32 v129, 0x3f4c422a, v129
	v_mul_f32_e32 v128, 0xbfb8aa3b, v128
	v_add_f32_e32 v129, v129, v129
	v_exp_f32_e32 v128, v128
; __device__ __forceinline__ float bf_lo(unsigned w) { return __uint_as_float(w << 16); }
; __device__ __forceinline__ float bf_hi(unsigned w) { return __uint_as_float(w & 0xffff0000u); }
; __device__ __forceinline__ u32x4 pack8(const f32x4& v0, const f32x4& v1) { u32x4 w; w.x = cvt_pk_bf16(v0[0], v0[1]); w.y = cvt_pk_bf16(v0[2], v0[3]); w.z = cvt_pk_bf16(v1[0], v1[1]); w.w = cvt_pk_bf16(v1[2], v1[3]); return w; }
;     __device__ __forceinline__ void operator()(const f32x4 (&acc)[2][2][4][2], const Unit& u, int wr, int wc, int fr_, int fq_) const {
;     ...
; #pragma unroll
;                 for (int bj = 0; bj < 2; ++bj) {
;                     const u32x4 uw = uwv[m & 1][bj];
;                     f32x4 v0 = acc[ai][bj][m][0], v1 = acc[ai][bj][m][1];
;                     v0[0] += d0[0] * bf_lo(uw.x); v0[1] += d0[1] * bf_hi(uw.x); v0[2] += d0[2] * bf_lo(uw.y); v0[3] += d0[3] * bf_hi(uw.y);
;                     v1[0] += d1[0] * bf_lo(uw.z); v1[1] += d1[1] * bf_hi(uw.z); v1[2] += d1[2] * bf_lo(uw.w); v1[3] += d1[3] * bf_hi(uw.w);
; #pragma unroll
;                     for (int k = 0; k < 4; ++k) { v0[k] = gelu_tanh_f(v0[k]); v1[k] = gelu_tanh_f(v1[k]); }
;                     *(u32x4*)(yp + bj * 8 * 1024) = pack8(v0, v1); }
;                 const int adv = (m == 3) ? (128 - 48) : 16;
;                 up += (size_t)adv * 64 * 384; yp += (size_t)adv * 16 * 1024; }
	v_mul_f32_e32 v129, 0xbfb8aa3b, v129
	v_exp_f32_e32 v129, v129
	v_rcp_f32_e32 v126, v126
	v_add_f32_e32 v128, 1.0, v128
	v_rcp_f32_e32 v128, v128
	v_add_f32_e32 v129, 1.0, v129
	v_rcp_f32_e32 v127, v127
	v_rcp_f32_e32 v129, v129
	v_lshl_add_u64 v[124:125], v[160:161], 0, s[30:31]
	v_mul_f32_e32 v114, v114, v126
	v_mul_f32_e32 v115, v115, v128
	v_cvt_pk_bf16_f32 v112, v112, v113
	v_mul_f32_e32 v118, v118, v127
	v_mul_f32_e32 v119, v119, v129
	v_cvt_pk_bf16_f32 v113, v114, v115
	v_cvt_pk_bf16_f32 v114, v116, v117
	v_cvt_pk_bf16_f32 v115, v118, v119
	global_store_dwordx4 v[124:125], v[112:115], off
	s_nop 1
	v_lshlrev_b32_e32 v112, 16, v120
	v_fma_f32 v104, v20, v112, v104
	v_mul_f32_e32 v113, 0x3d372713, v104
	v_mul_f32_e32 v113, v104, v113
	v_fma_f32 v113, v104, v113, v104
	v_and_b32_e32 v112, 0xffff0000, v120
	v_mul_f32_e32 v113, 0x3f4c422a, v113
	v_fma_f32 v105, v21, v112, v105
	v_lshlrev_b32_e32 v112, 16, v121
	v_add_f32_e32 v113, v113, v113
	v_fma_f32 v106, v22, v112, v106
	v_and_b32_e32 v112, 0xffff0000, v121
	v_mul_f32_e32 v113, 0xbfb8aa3b, v113
	v_fmac_f32_e32 v107, v23, v112
	v_lshlrev_b32_e32 v112, 16, v122
	v_exp_f32_e32 v113, v113
	v_fma_f32 v108, v16, v112, v108
	v_and_b32_e32 v112, 0xffff0000, v122
	v_fma_f32 v109, v17, v112, v109
	v_lshlrev_b32_e32 v112, 16, v123
	v_fma_f32 v110, v18, v112, v110
	v_and_b32_e32 v112, 0xffff0000, v123
	v_fmac_f32_e32 v111, v19, v112
	v_add_f32_e32 v112, 1.0, v113
	v_mul_f32_e32 v113, 0x3d372713, v108
	v_mul_f32_e32 v114, 0x3d372713, v105
	v_mul_f32_e32 v113, v108, v113
	v_mul_f32_e32 v114, v105, v114
	v_fma_f32 v113, v108, v113, v108
	v_fma_f32 v114, v105, v114, v105
	v_mul_f32_e32 v113, 0x3f4c422a, v113
	v_mul_f32_e32 v114, 0x3f4c422a, v114
	v_add_f32_e32 v113, v113, v113
	v_add_f32_e32 v114, v114, v114
	v_mul_f32_e32 v113, 0xbfb8aa3b, v113
	v_mul_f32_e32 v114, 0xbfb8aa3b, v114
	v_exp_f32_e32 v113, v113
	v_exp_f32_e32 v114, v114
	v_mul_f32_e32 v115, 0x3d372713, v109
	v_mul_f32_e32 v115, v109, v115
	v_add_f32_e32 v113, 1.0, v113
	v_add_f32_e32 v114, 1.0, v114
	v_rcp_f32_e32 v113, v113
	v_rcp_f32_e32 v114, v114
	v_fma_f32 v115, v109, v115, v109
	v_mul_f32_e32 v115, 0x3f4c422a, v115
	v_add_f32_e32 v115, v115, v115
	v_mul_f32_e32 v115, 0xbfb8aa3b, v115
	v_mul_f32_e32 v108, v108, v113
	v_mul_f32_e32 v105, v105, v114
	v_mul_f32_e32 v113, 0x3d372713, v106
	v_mul_f32_e32 v114, 0x3d372713, v110
	v_rcp_f32_e32 v112, v112
	v_exp_f32_e32 v115, v115
	v_mul_f32_e32 v113, v106, v113
	v_mul_f32_e32 v114, v110, v114
	v_fma_f32 v113, v106, v113, v106
	v_fma_f32 v114, v110, v114, v110
	v_mul_f32_e32 v113, 0x3f4c422a, v113
	v_mul_f32_e32 v114, 0x3f4c422a, v114
	v_add_f32_e32 v113, v113, v113
	v_add_f32_e32 v114, v114, v114
	v_mul_f32_e32 v104, v104, v112
	v_add_f32_e32 v112, 1.0, v115
	v_mul_f32_e32 v113, 0xbfb8aa3b, v113
	v_mul_f32_e32 v114, 0xbfb8aa3b, v114
	v_rcp_f32_e32 v112, v112
	v_exp_f32_e32 v113, v113
	v_exp_f32_e32 v114, v114
	v_mul_f32_e32 v115, 0x3d372713, v111
	v_mul_f32_e32 v109, v109, v112
	v_add_f32_e32 v112, 1.0, v113
	v_add_f32_e32 v113, 1.0, v114
	v_mul_f32_e32 v114, 0x3d372713, v107
	v_mul_f32_e32 v114, v107, v114
	v_fma_f32 v114, v107, v114, v107
	v_mul_f32_e32 v114, 0x3f4c422a, v114
	v_mul_f32_e32 v115, v111, v115
	v_add_f32_e32 v114, v114, v114
	v_fma_f32 v115, v111, v115, v111
	v_mul_f32_e32 v114, 0xbfb8aa3b, v114
	v_mul_f32_e32 v115, 0x3f4c422a, v115
	v_exp_f32_e32 v114, v114
	v_add_f32_e32 v115, v115, v115
	v_mul_f32_e32 v115, 0xbfb8aa3b, v115
	v_exp_f32_e32 v115, v115
	v_rcp_f32_e32 v112, v112
	v_add_f32_e32 v114, 1.0, v114
	v_rcp_f32_e32 v114, v114
	v_add_f32_e32 v115, 1.0, v115
	v_rcp_f32_e32 v113, v113
	v_rcp_f32_e32 v115, v115
	v_mul_f32_e32 v106, v106, v112
	v_mul_f32_e32 v107, v107, v114
	v_cvt_pk_bf16_f32 v104, v104, v105
	v_cvt_pk_bf16_f32 v105, v106, v107
	v_cvt_pk_bf16_f32 v106, v108, v109
	v_add_co_u32_e32 v108, vcc, s50, v124
	v_mul_f32_e32 v110, v110, v113
	s_nop 0
	v_addc_co_u32_e32 v109, vcc, 0, v125, vcc
	v_mul_f32_e32 v111, v111, v115
	v_cvt_pk_bf16_f32 v107, v110, v111
	global_store_dwordx4 v[108:109], v[104:107], off
	v_lshl_add_u64 v[114:115], v[124:125], 0, s[30:31]
	s_nop 0
	v_lshl_add_u64 v[104:105], v[158:159], 0, s[28:29]
	global_load_dwordx4 v[116:119], v[104:105], off
	global_load_dwordx4 v[120:123], v[104:105], off offset:256
	v_lshl_add_u64 v[112:113], v[104:105], 0, s[28:29]
	v_add_co_u32_e32 v104, vcc, s60, v104
	s_waitcnt vmcnt(0) lgkmcnt(0)
; __device__ __forceinline__ float bf_lo(unsigned w) { return __uint_as_float(w << 16); }
; __device__ __forceinline__ float bf_hi(unsigned w) { return __uint_as_float(w & 0xffff0000u); }
; __device__ __forceinline__ u32x4 pack8(const f32x4& v0, const f32x4& v1) { u32x4 w; w.x = cvt_pk_bf16(v0[0], v0[1]); w.y = cvt_pk_bf16(v0[2], v0[3]); w.z = cvt_pk_bf16(v1[0], v1[1]); w.w = cvt_pk_bf16(v1[2], v1[3]); return w; }
;     __device__ __forceinline__ void operator()(const f32x4 (&acc)[2][2][4][2], const Unit& u, int wr, int wc, int fr_, int fq_) const {
;     ...
;             for (int m = 0; m < 4; ++m) {
;                 asm volatile("" : "+v"(up), "+v"(yp));
;                 if ((m & 1) == 0) {
;                     uwv[0][0] = *(const u32x4*)(up); uwv[0][1] = *(const u32x4*)(up + 128);
;                     uwv[1][0] = *(const u32x4*)(up + (size_t)16 * 64 * 384); uwv[1][1] = *(const u32x4*)(up + (size_t)16 * 64 * 384 + 128);
;                     asm volatile("" ::: "memory"); }
; #pragma unroll
;                 for (int bj = 0; bj < 2; ++bj) {
;                     const u32x4 uw = uwv[m & 1][bj];
;                     f32x4 v0 = acc[ai][bj][m][0], v1 = acc[ai][bj][m][1];
;                     v0[0] += d0[0] * bf_lo(uw.x); v0[1] += d0[1] * bf_hi(uw.x); v0[2] += d0[2] * bf_lo(uw.y); v0[3] += d0[3] * bf_hi(uw.y);
;                     v1[0] += d1[0] * bf_lo(uw.z); v1[1] += d1[1] * bf_hi(uw.z); v1[2] += d1[2] * bf_lo(uw.w); v1[3] += d1[3] * bf_hi(uw.w);
; #pragma unroll
;                     for (int k = 0; k < 4; ++k) { v0[k] = gelu_tanh_f(v0[k]); v1[k] = gelu_tanh_f(v1[k]); }
;                     *(u32x4*)(yp + bj * 8 * 1024) = pack8(v0, v1); }
;                 const int adv = (m == 3) ? (128 - 48) : 16;
;                 up += (size_t)adv * 64 * 384; yp += (size_t)adv * 16 * 1024; }
	v_lshlrev_b32_e32 v124, 16, v116
	v_and_b32_e32 v116, 0xffff0000, v116
	v_fma_f32 v96, v20, v124, v96
	v_fma_f32 v97, v21, v116, v97
	v_lshlrev_b32_e32 v116, 16, v117
	v_fma_f32 v98, v22, v116, v98
	v_and_b32_e32 v116, 0xffff0000, v117
	v_mul_f32_e32 v117, 0x3d372713, v96
	v_mul_f32_e32 v117, v96, v117
	v_fma_f32 v117, v96, v117, v96
	v_mul_f32_e32 v117, 0x3f4c422a, v117
	v_add_f32_e32 v117, v117, v117
	v_mul_f32_e32 v117, 0xbfb8aa3b, v117
	v_fmac_f32_e32 v99, v23, v116
	v_lshlrev_b32_e32 v116, 16, v118
	v_exp_f32_e32 v117, v117
	v_fma_f32 v100, v16, v116, v100
	v_and_b32_e32 v116, 0xffff0000, v118
	v_fma_f32 v101, v17, v116, v101
	v_lshlrev_b32_e32 v116, 16, v119
	v_fma_f32 v102, v18, v116, v102
	v_and_b32_e32 v116, 0xffff0000, v119
	v_fmac_f32_e32 v103, v19, v116
	v_add_f32_e32 v116, 1.0, v117
	v_mul_f32_e32 v117, 0x3d372713, v100
	v_mul_f32_e32 v118, 0x3d372713, v97
	v_mul_f32_e32 v117, v100, v117
	v_mul_f32_e32 v118, v97, v118
	v_fma_f32 v117, v100, v117, v100
	v_fma_f32 v118, v97, v118, v97
	v_mul_f32_e32 v117, 0x3f4c422a, v117
	v_mul_f32_e32 v118, 0x3f4c422a, v118
	v_add_f32_e32 v117, v117, v117
	v_add_f32_e32 v118, v118, v118
	v_mul_f32_e32 v117, 0xbfb8aa3b, v117
	v_mul_f32_e32 v118, 0xbfb8aa3b, v118
	v_exp_f32_e32 v117, v117
	v_exp_f32_e32 v118, v118
	v_mul_f32_e32 v119, 0x3d372713, v101
	v_mul_f32_e32 v119, v101, v119
	v_add_f32_e32 v117, 1.0, v117
	v_add_f32_e32 v118, 1.0, v118
	v_rcp_f32_e32 v117, v117
	v_rcp_f32_e32 v118, v118
	v_fma_f32 v119, v101, v119, v101
	v_mul_f32_e32 v119, 0x3f4c422a, v119
	v_add_f32_e32 v119, v119, v119
	v_addc_co_u32_e32 v105, vcc, 0, v105, vcc
	v_mul_f32_e32 v119, 0xbfb8aa3b, v119
	v_mul_f32_e32 v100, v100, v117
	v_mul_f32_e32 v97, v97, v118
	v_mul_f32_e32 v117, 0x3d372713, v98
	v_mul_f32_e32 v118, 0x3d372713, v102
	global_load_dwordx4 v[108:111], v[104:105], off
	s_nop 0
	global_load_dwordx4 v[104:107], v[104:105], off offset:256
	v_rcp_f32_e32 v116, v116
	v_exp_f32_e32 v119, v119
	v_mul_f32_e32 v117, v98, v117
	v_mul_f32_e32 v118, v102, v118
	v_fma_f32 v117, v98, v117, v98
	v_fma_f32 v118, v102, v118, v102
	v_mul_f32_e32 v117, 0x3f4c422a, v117
	v_mul_f32_e32 v118, 0x3f4c422a, v118
	v_add_f32_e32 v117, v117, v117
	v_add_f32_e32 v118, v118, v118
	v_mul_f32_e32 v96, v96, v116
	v_add_f32_e32 v116, 1.0, v119
	v_mul_f32_e32 v117, 0xbfb8aa3b, v117
	v_mul_f32_e32 v118, 0xbfb8aa3b, v118
	v_rcp_f32_e32 v116, v116
	v_exp_f32_e32 v117, v117
	v_exp_f32_e32 v118, v118
	v_mul_f32_e32 v119, 0x3d372713, v103
	v_mul_f32_e32 v101, v101, v116
	v_add_f32_e32 v116, 1.0, v117
	v_add_f32_e32 v117, 1.0, v118
	v_mul_f32_e32 v118, 0x3d372713, v99
	v_mul_f32_e32 v118, v99, v118
	v_fma_f32 v118, v99, v118, v99
	v_mul_f32_e32 v119, v103, v119
	v_mul_f32_e32 v118, 0x3f4c422a, v118
	v_fma_f32 v119, v103, v119, v103
	v_add_f32_e32 v118, v118, v118
	v_mul_f32_e32 v119, 0x3f4c422a, v119
	v_mul_f32_e32 v118, 0xbfb8aa3b, v118
	v_add_f32_e32 v119, v119, v119
	v_exp_f32_e32 v118, v118
	v_mul_f32_e32 v119, 0xbfb8aa3b, v119
	v_exp_f32_e32 v119, v119
	v_rcp_f32_e32 v116, v116
	v_add_f32_e32 v118, 1.0, v118
	v_rcp_f32_e32 v118, v118
	v_add_f32_e32 v119, 1.0, v119
	v_rcp_f32_e32 v117, v117
	v_rcp_f32_e32 v119, v119
	v_mul_f32_e32 v98, v98, v116
	v_mul_f32_e32 v99, v99, v118
	v_cvt_pk_bf16_f32 v96, v96, v97
	v_mul_f32_e32 v102, v102, v117
	v_mul_f32_e32 v103, v103, v119
	v_cvt_pk_bf16_f32 v97, v98, v99
	v_cvt_pk_bf16_f32 v98, v100, v101
	v_cvt_pk_bf16_f32 v99, v102, v103
	global_store_dwordx4 v[114:115], v[96:99], off
	s_nop 1
	v_lshlrev_b32_e32 v96, 16, v120
	v_fma_f32 v88, v20, v96, v88
	v_mul_f32_e32 v97, 0x3d372713, v88
	v_mul_f32_e32 v97, v88, v97
	v_fma_f32 v97, v88, v97, v88
	v_and_b32_e32 v96, 0xffff0000, v120
	v_mul_f32_e32 v97, 0x3f4c422a, v97
	v_fma_f32 v89, v21, v96, v89
	v_lshlrev_b32_e32 v96, 16, v121
	v_add_f32_e32 v97, v97, v97
	v_fma_f32 v90, v22, v96, v90
	v_and_b32_e32 v96, 0xffff0000, v121
	v_mul_f32_e32 v97, 0xbfb8aa3b, v97
	v_fmac_f32_e32 v91, v23, v96
	v_lshlrev_b32_e32 v96, 16, v122
	v_exp_f32_e32 v97, v97
	v_fma_f32 v92, v16, v96, v92
	v_and_b32_e32 v96, 0xffff0000, v122
	v_fma_f32 v93, v17, v96, v93
	v_lshlrev_b32_e32 v96, 16, v123
	v_fma_f32 v94, v18, v96, v94
	v_and_b32_e32 v96, 0xffff0000, v123
	v_fmac_f32_e32 v95, v19, v96
	v_add_f32_e32 v96, 1.0, v97
	v_mul_f32_e32 v97, 0x3d372713, v92
	v_mul_f32_e32 v98, 0x3d372713, v89
	v_mul_f32_e32 v97, v92, v97
	v_mul_f32_e32 v98, v89, v98
	v_fma_f32 v97, v92, v97, v92
	v_fma_f32 v98, v89, v98, v89
	v_mul_f32_e32 v97, 0x3f4c422a, v97
	v_mul_f32_e32 v98, 0x3f4c422a, v98
	v_add_f32_e32 v97, v97, v97
	v_add_f32_e32 v98, v98, v98
	v_mul_f32_e32 v97, 0xbfb8aa3b, v97
	v_mul_f32_e32 v98, 0xbfb8aa3b, v98
	v_exp_f32_e32 v97, v97
	v_exp_f32_e32 v98, v98
	v_mul_f32_e32 v99, 0x3d372713, v93
	v_mul_f32_e32 v99, v93, v99
	v_add_f32_e32 v97, 1.0, v97
	v_add_f32_e32 v98, 1.0, v98
	v_rcp_f32_e32 v97, v97
	v_rcp_f32_e32 v98, v98
	v_fma_f32 v99, v93, v99, v93
	v_mul_f32_e32 v99, 0x3f4c422a, v99
	v_add_f32_e32 v99, v99, v99
	v_mul_f32_e32 v99, 0xbfb8aa3b, v99
	v_mul_f32_e32 v92, v92, v97
	v_mul_f32_e32 v89, v89, v98
	v_mul_f32_e32 v97, 0x3d372713, v90
	v_mul_f32_e32 v98, 0x3d372713, v94
	v_rcp_f32_e32 v96, v96
	v_exp_f32_e32 v99, v99
	v_mul_f32_e32 v97, v90, v97
	v_mul_f32_e32 v98, v94, v98
	v_fma_f32 v97, v90, v97, v90
	v_fma_f32 v98, v94, v98, v94
	v_mul_f32_e32 v97, 0x3f4c422a, v97
	v_mul_f32_e32 v98, 0x3f4c422a, v98
	v_add_f32_e32 v97, v97, v97
	v_add_f32_e32 v98, v98, v98
	v_mul_f32_e32 v88, v88, v96
	v_add_f32_e32 v96, 1.0, v99
	v_mul_f32_e32 v97, 0xbfb8aa3b, v97
	v_mul_f32_e32 v98, 0xbfb8aa3b, v98
	v_rcp_f32_e32 v96, v96
	v_exp_f32_e32 v97, v97
	v_exp_f32_e32 v98, v98
	v_mul_f32_e32 v99, 0x3d372713, v95
	v_mul_f32_e32 v93, v93, v96
	v_add_f32_e32 v96, 1.0, v97
	v_add_f32_e32 v97, 1.0, v98
	v_mul_f32_e32 v98, 0x3d372713, v91
	v_mul_f32_e32 v98, v91, v98
	v_fma_f32 v98, v91, v98, v91
	v_mul_f32_e32 v98, 0x3f4c422a, v98
	v_mul_f32_e32 v99, v95, v99
	v_add_f32_e32 v98, v98, v98
	v_fma_f32 v99, v95, v99, v95
	v_mul_f32_e32 v98, 0xbfb8aa3b, v98
	v_mul_f32_e32 v99, 0x3f4c422a, v99
	v_exp_f32_e32 v98, v98
	v_add_f32_e32 v99, v99, v99
	v_mul_f32_e32 v99, 0xbfb8aa3b, v99
	v_exp_f32_e32 v99, v99
	v_rcp_f32_e32 v96, v96
	v_add_f32_e32 v98, 1.0, v98
	v_rcp_f32_e32 v98, v98
	v_add_f32_e32 v99, 1.0, v99
	v_rcp_f32_e32 v97, v97
	v_rcp_f32_e32 v99, v99
	v_mul_f32_e32 v90, v90, v96
	v_mul_f32_e32 v91, v91, v98
	v_cvt_pk_bf16_f32 v88, v88, v89
	v_cvt_pk_bf16_f32 v89, v90, v91
	v_cvt_pk_bf16_f32 v90, v92, v93
	v_add_co_u32_e32 v92, vcc, s50, v114
	v_mul_f32_e32 v94, v94, v97
	s_nop 0
	v_addc_co_u32_e32 v93, vcc, 0, v115, vcc
	v_mul_f32_e32 v95, v95, v99
	v_cvt_pk_bf16_f32 v91, v94, v95
	global_store_dwordx4 v[92:93], v[88:91], off
	s_waitcnt vmcnt(0) lgkmcnt(0)
; __device__ __forceinline__ float bf_lo(unsigned w) { return __uint_as_float(w << 16); }
; __device__ __forceinline__ float bf_hi(unsigned w) { return __uint_as_float(w & 0xffff0000u); }
; __device__ __forceinline__ u32x4 pack8(const f32x4& v0, const f32x4& v1) { u32x4 w; w.x = cvt_pk_bf16(v0[0], v0[1]); w.y = cvt_pk_bf16(v0[2], v0[3]); w.z = cvt_pk_bf16(v1[0], v1[1]); w.w = cvt_pk_bf16(v1[2], v1[3]); return w; }
;     __device__ __forceinline__ void operator()(const f32x4 (&acc)[2][2][4][2], const Unit& u, int wr, int wc, int fr_, int fq_) const {
;     ...
;             for (int m = 0; m < 4; ++m) {
;                 asm volatile("" : "+v"(up), "+v"(yp));
;                 if ((m & 1) == 0) {
;                     uwv[0][0] = *(const u32x4*)(up); uwv[0][1] = *(const u32x4*)(up + 128);
;                     uwv[1][0] = *(const u32x4*)(up + (size_t)16 * 64 * 384); uwv[1][1] = *(const u32x4*)(up + (size_t)16 * 64 * 384 + 128);
;                     asm volatile("" ::: "memory"); }
; #pragma unroll
;                 for (int bj = 0; bj < 2; ++bj) {
;                     const u32x4 uw = uwv[m & 1][bj];
;                     f32x4 v0 = acc[ai][bj][m][0], v1 = acc[ai][bj][m][1];
;                     v0[0] += d0[0] * bf_lo(uw.x); v0[1] += d0[1] * bf_hi(uw.x); v0[2] += d0[2] * bf_lo(uw.y); v0[3] += d0[3] * bf_hi(uw.y);
;                     v1[0] += d1[0] * bf_lo(uw.z); v1[1] += d1[1] * bf_hi(uw.z); v1[2] += d1[2] * bf_lo(uw.w); v1[3] += d1[3] * bf_hi(uw.w);
; #pragma unroll
;                     for (int k = 0; k < 4; ++k) { v0[k] = gelu_tanh_f(v0[k]); v1[k] = gelu_tanh_f(v1[k]); }
;                     *(u32x4*)(yp + bj * 8 * 1024) = pack8(v0, v1); }
;                 const int adv = (m == 3) ? (128 - 48) : 16;
;                 up += (size_t)adv * 64 * 384; yp += (size_t)adv * 16 * 1024; }
	s_nop 0
	v_lshlrev_b32_e32 v90, 16, v108
	v_fma_f32 v80, v20, v90, v80
	v_mul_f32_e32 v91, 0x3d372713, v80
	v_mul_f32_e32 v91, v80, v91
	v_fma_f32 v91, v80, v91, v80
	v_and_b32_e32 v90, 0xffff0000, v108
	v_mul_f32_e32 v91, 0x3f4c422a, v91
	v_fma_f32 v81, v21, v90, v81
	v_lshlrev_b32_e32 v90, 16, v109
	v_add_f32_e32 v91, v91, v91
	v_fma_f32 v82, v22, v90, v82
	v_and_b32_e32 v90, 0xffff0000, v109
	v_mul_f32_e32 v91, 0xbfb8aa3b, v91
	v_fmac_f32_e32 v83, v23, v90
	v_lshlrev_b32_e32 v90, 16, v110
	v_exp_f32_e32 v91, v91
	v_fma_f32 v84, v16, v90, v84
	v_and_b32_e32 v90, 0xffff0000, v110
	v_fma_f32 v85, v17, v90, v85
	v_lshlrev_b32_e32 v90, 16, v111
	v_fma_f32 v86, v18, v90, v86
	v_and_b32_e32 v90, 0xffff0000, v111
	v_fmac_f32_e32 v87, v19, v90
	v_add_f32_e32 v90, 1.0, v91
	v_mul_f32_e32 v91, 0x3d372713, v84
	v_mul_f32_e32 v92, 0x3d372713, v81
	v_mul_f32_e32 v91, v84, v91
	v_mul_f32_e32 v92, v81, v92
	v_fma_f32 v91, v84, v91, v84
	v_fma_f32 v92, v81, v92, v81
	v_mul_f32_e32 v91, 0x3f4c422a, v91
	v_mul_f32_e32 v92, 0x3f4c422a, v92
	v_add_f32_e32 v91, v91, v91
	v_add_f32_e32 v92, v92, v92
	v_mul_f32_e32 v91, 0xbfb8aa3b, v91
	v_mul_f32_e32 v92, 0xbfb8aa3b, v92
	v_exp_f32_e32 v91, v91
	v_exp_f32_e32 v92, v92
	v_mul_f32_e32 v93, 0x3d372713, v85
	v_mul_f32_e32 v93, v85, v93
	v_add_f32_e32 v91, 1.0, v91
	v_add_f32_e32 v92, 1.0, v92
	v_rcp_f32_e32 v91, v91
	v_rcp_f32_e32 v92, v92
	v_fma_f32 v93, v85, v93, v85
	v_mul_f32_e32 v93, 0x3f4c422a, v93
	v_add_f32_e32 v93, v93, v93
	v_mul_f32_e32 v93, 0xbfb8aa3b, v93
	v_mul_f32_e32 v84, v84, v91
	v_mul_f32_e32 v81, v81, v92
	v_mul_f32_e32 v91, 0x3d372713, v82
	v_mul_f32_e32 v92, 0x3d372713, v86
	v_rcp_f32_e32 v90, v90
	v_exp_f32_e32 v93, v93
	v_mul_f32_e32 v91, v82, v91
	v_mul_f32_e32 v92, v86, v92
	v_fma_f32 v91, v82, v91, v82
	v_fma_f32 v92, v86, v92, v86
	v_mul_f32_e32 v91, 0x3f4c422a, v91
	v_mul_f32_e32 v92, 0x3f4c422a, v92
	v_add_f32_e32 v91, v91, v91
	v_add_f32_e32 v92, v92, v92
	v_mul_f32_e32 v80, v80, v90
	v_add_f32_e32 v90, 1.0, v93
	v_mul_f32_e32 v91, 0xbfb8aa3b, v91
	v_mul_f32_e32 v92, 0xbfb8aa3b, v92
	v_rcp_f32_e32 v90, v90
	v_exp_f32_e32 v91, v91
	v_exp_f32_e32 v92, v92
	v_mul_f32_e32 v93, 0x3d372713, v87
	v_mul_f32_e32 v85, v85, v90
	v_add_f32_e32 v90, 1.0, v91
	v_add_f32_e32 v91, 1.0, v92
	v_mul_f32_e32 v92, 0x3d372713, v83
	v_mul_f32_e32 v92, v83, v92
	v_fma_f32 v92, v83, v92, v83
	v_mul_f32_e32 v93, v87, v93
	v_mul_f32_e32 v92, 0x3f4c422a, v92
	v_fma_f32 v93, v87, v93, v87
	v_add_f32_e32 v92, v92, v92
	v_mul_f32_e32 v93, 0x3f4c422a, v93
	v_mul_f32_e32 v92, 0xbfb8aa3b, v92
	v_add_f32_e32 v93, v93, v93
	v_exp_f32_e32 v92, v92
	v_mul_f32_e32 v93, 0xbfb8aa3b, v93
	v_exp_f32_e32 v93, v93
	v_rcp_f32_e32 v90, v90
	v_add_f32_e32 v92, 1.0, v92
	v_rcp_f32_e32 v92, v92
	v_add_f32_e32 v93, 1.0, v93
	v_rcp_f32_e32 v91, v91
	v_rcp_f32_e32 v93, v93
	v_lshl_add_u64 v[88:89], v[114:115], 0, s[30:31]
	v_mul_f32_e32 v82, v82, v90
	v_mul_f32_e32 v83, v83, v92
	v_cvt_pk_bf16_f32 v80, v80, v81
	v_mul_f32_e32 v86, v86, v91
	v_mul_f32_e32 v87, v87, v93
	v_cvt_pk_bf16_f32 v81, v82, v83
	v_cvt_pk_bf16_f32 v82, v84, v85
	v_cvt_pk_bf16_f32 v83, v86, v87
	global_store_dwordx4 v[88:89], v[80:83], off
	s_nop 1
	v_lshlrev_b32_e32 v80, 16, v104
	v_fma_f32 v72, v20, v80, v72
	v_mul_f32_e32 v81, 0x3d372713, v72
	v_mul_f32_e32 v81, v72, v81
	v_fma_f32 v81, v72, v81, v72
	v_and_b32_e32 v80, 0xffff0000, v104
	v_mul_f32_e32 v81, 0x3f4c422a, v81
	v_fma_f32 v73, v21, v80, v73
	v_lshlrev_b32_e32 v80, 16, v105
	v_add_f32_e32 v81, v81, v81
	v_fma_f32 v74, v22, v80, v74
	v_and_b32_e32 v80, 0xffff0000, v105
	v_mul_f32_e32 v81, 0xbfb8aa3b, v81
	v_fmac_f32_e32 v75, v23, v80
	v_lshlrev_b32_e32 v80, 16, v106
	v_exp_f32_e32 v81, v81
	v_fma_f32 v76, v16, v80, v76
	v_and_b32_e32 v80, 0xffff0000, v106
	v_fma_f32 v77, v17, v80, v77
	v_lshlrev_b32_e32 v80, 16, v107
	v_fma_f32 v78, v18, v80, v78
	v_and_b32_e32 v80, 0xffff0000, v107
	v_fmac_f32_e32 v79, v19, v80
	v_add_f32_e32 v80, 1.0, v81
	v_mul_f32_e32 v81, 0x3d372713, v76
	v_mul_f32_e32 v82, 0x3d372713, v73
	v_mul_f32_e32 v81, v76, v81
	v_mul_f32_e32 v82, v73, v82
	v_fma_f32 v81, v76, v81, v76
	v_fma_f32 v82, v73, v82, v73
	v_mul_f32_e32 v81, 0x3f4c422a, v81
	v_mul_f32_e32 v82, 0x3f4c422a, v82
	v_add_f32_e32 v81, v81, v81
	v_add_f32_e32 v82, v82, v82
	v_mul_f32_e32 v81, 0xbfb8aa3b, v81
	v_mul_f32_e32 v82, 0xbfb8aa3b, v82
	v_exp_f32_e32 v81, v81
	v_exp_f32_e32 v82, v82
	v_mul_f32_e32 v83, 0x3d372713, v77
	v_mul_f32_e32 v83, v77, v83
	v_add_f32_e32 v81, 1.0, v81
	v_add_f32_e32 v82, 1.0, v82
	v_rcp_f32_e32 v81, v81
	v_rcp_f32_e32 v82, v82
	v_fma_f32 v83, v77, v83, v77
	v_mul_f32_e32 v83, 0x3f4c422a, v83
	v_add_f32_e32 v83, v83, v83
	v_mul_f32_e32 v83, 0xbfb8aa3b, v83
	v_mul_f32_e32 v76, v76, v81
	v_mul_f32_e32 v73, v73, v82
	v_mul_f32_e32 v81, 0x3d372713, v74
	v_mul_f32_e32 v82, 0x3d372713, v78
	v_rcp_f32_e32 v80, v80
	v_exp_f32_e32 v83, v83
	v_mul_f32_e32 v81, v74, v81
	v_mul_f32_e32 v82, v78, v82
	v_fma_f32 v81, v74, v81, v74
	v_fma_f32 v82, v78, v82, v78
	v_mul_f32_e32 v81, 0x3f4c422a, v81
	v_mul_f32_e32 v82, 0x3f4c422a, v82
	v_add_f32_e32 v81, v81, v81
	v_add_f32_e32 v82, v82, v82
	v_mul_f32_e32 v72, v72, v80
	v_add_f32_e32 v80, 1.0, v83
	v_mul_f32_e32 v81, 0xbfb8aa3b, v81
	v_mul_f32_e32 v82, 0xbfb8aa3b, v82
	v_rcp_f32_e32 v80, v80
	v_exp_f32_e32 v81, v81
	v_exp_f32_e32 v82, v82
	v_mul_f32_e32 v83, 0x3d372713, v79
	v_mul_f32_e32 v77, v77, v80
	v_add_f32_e32 v80, 1.0, v81
	v_add_f32_e32 v81, 1.0, v82
	v_mul_f32_e32 v82, 0x3d372713, v75
	v_mul_f32_e32 v82, v75, v82
	v_fma_f32 v82, v75, v82, v75
	v_mul_f32_e32 v82, 0x3f4c422a, v82
	v_mul_f32_e32 v83, v79, v83
	v_add_f32_e32 v82, v82, v82
	v_fma_f32 v83, v79, v83, v79
	v_mul_f32_e32 v82, 0xbfb8aa3b, v82
	v_mul_f32_e32 v83, 0x3f4c422a, v83
	v_exp_f32_e32 v82, v82
	v_add_f32_e32 v83, v83, v83
	v_mul_f32_e32 v83, 0xbfb8aa3b, v83
	v_exp_f32_e32 v83, v83
	v_rcp_f32_e32 v80, v80
	v_add_f32_e32 v82, 1.0, v82
	v_rcp_f32_e32 v82, v82
	v_add_f32_e32 v83, 1.0, v83
	v_rcp_f32_e32 v81, v81
	v_rcp_f32_e32 v83, v83
	v_mul_f32_e32 v74, v74, v80
	v_mul_f32_e32 v75, v75, v82
	v_cvt_pk_bf16_f32 v72, v72, v73
	v_cvt_pk_bf16_f32 v73, v74, v75
	v_cvt_pk_bf16_f32 v74, v76, v77
	v_add_co_u32_e32 v76, vcc, s50, v88
	v_mul_f32_e32 v78, v78, v81
	s_nop 0
	v_addc_co_u32_e32 v77, vcc, 0, v89, vcc
	v_mul_f32_e32 v79, v79, v83
	v_cvt_pk_bf16_f32 v75, v78, v79
	global_store_dwordx4 v[76:77], v[72:75], off
	v_lshl_add_u64 v[82:83], v[88:89], 0, s[36:37]
	s_nop 0
	v_lshl_add_u64 v[72:73], v[112:113], 0, s[34:35]
	global_load_dwordx4 v[84:87], v[72:73], off
	global_load_dwordx4 v[88:91], v[72:73], off offset:256
	v_lshl_add_u64 v[80:81], v[72:73], 0, s[28:29]
	v_add_co_u32_e32 v72, vcc, s60, v72
	s_waitcnt vmcnt(0) lgkmcnt(0)
; __device__ __forceinline__ float bf_lo(unsigned w) { return __uint_as_float(w << 16); }
; __device__ __forceinline__ float bf_hi(unsigned w) { return __uint_as_float(w & 0xffff0000u); }
; __device__ __forceinline__ u32x4 pack8(const f32x4& v0, const f32x4& v1) { u32x4 w; w.x = cvt_pk_bf16(v0[0], v0[1]); w.y = cvt_pk_bf16(v0[2], v0[3]); w.z = cvt_pk_bf16(v1[0], v1[1]); w.w = cvt_pk_bf16(v1[2], v1[3]); return w; }
;     __device__ __forceinline__ void operator()(const f32x4 (&acc)[2][2][4][2], const Unit& u, int wr, int wc, int fr_, int fq_) const {
;     ...
;             for (int m = 0; m < 4; ++m) {
;                 asm volatile("" : "+v"(up), "+v"(yp));
;                 if ((m & 1) == 0) {
;                     uwv[0][0] = *(const u32x4*)(up); uwv[0][1] = *(const u32x4*)(up + 128);
;                     uwv[1][0] = *(const u32x4*)(up + (size_t)16 * 64 * 384); uwv[1][1] = *(const u32x4*)(up + (size_t)16 * 64 * 384 + 128);
;                     asm volatile("" ::: "memory"); }
; #pragma unroll
;                 for (int bj = 0; bj < 2; ++bj) {
;                     const u32x4 uw = uwv[m & 1][bj];
;                     f32x4 v0 = acc[ai][bj][m][0], v1 = acc[ai][bj][m][1];
;                     v0[0] += d0[0] * bf_lo(uw.x); v0[1] += d0[1] * bf_hi(uw.x); v0[2] += d0[2] * bf_lo(uw.y); v0[3] += d0[3] * bf_hi(uw.y);
;                     v1[0] += d1[0] * bf_lo(uw.z); v1[1] += d1[1] * bf_hi(uw.z); v1[2] += d1[2] * bf_lo(uw.w); v1[3] += d1[3] * bf_hi(uw.w);
; #pragma unroll
;                     for (int k = 0; k < 4; ++k) { v0[k] = gelu_tanh_f(v0[k]); v1[k] = gelu_tanh_f(v1[k]); }
;                     *(u32x4*)(yp + bj * 8 * 1024) = pack8(v0, v1); }
;                 const int adv = (m == 3) ? (128 - 48) : 16;
;                 up += (size_t)adv * 64 * 384; yp += (size_t)adv * 16 * 1024; }
	v_lshlrev_b32_e32 v92, 16, v84
	v_and_b32_e32 v84, 0xffff0000, v84
	v_fma_f32 v64, v20, v92, v64
	v_fma_f32 v65, v21, v84, v65
	v_lshlrev_b32_e32 v84, 16, v85
	v_fma_f32 v66, v22, v84, v66
	v_and_b32_e32 v84, 0xffff0000, v85
	v_mul_f32_e32 v85, 0x3d372713, v64
	v_mul_f32_e32 v85, v64, v85
	v_fma_f32 v85, v64, v85, v64
	v_mul_f32_e32 v85, 0x3f4c422a, v85
	v_add_f32_e32 v85, v85, v85
	v_mul_f32_e32 v85, 0xbfb8aa3b, v85
	v_fmac_f32_e32 v67, v23, v84
	v_lshlrev_b32_e32 v84, 16, v86
	v_exp_f32_e32 v85, v85
	v_fma_f32 v68, v16, v84, v68
	v_and_b32_e32 v84, 0xffff0000, v86
	v_fma_f32 v69, v17, v84, v69
	v_lshlrev_b32_e32 v84, 16, v87
	v_fma_f32 v70, v18, v84, v70
	v_and_b32_e32 v84, 0xffff0000, v87
	v_fmac_f32_e32 v71, v19, v84
	v_add_f32_e32 v84, 1.0, v85
	v_mul_f32_e32 v85, 0x3d372713, v68
	v_mul_f32_e32 v86, 0x3d372713, v65
	v_mul_f32_e32 v85, v68, v85
	v_mul_f32_e32 v86, v65, v86
	v_fma_f32 v85, v68, v85, v68
	v_fma_f32 v86, v65, v86, v65
	v_mul_f32_e32 v85, 0x3f4c422a, v85
	v_mul_f32_e32 v86, 0x3f4c422a, v86
	v_add_f32_e32 v85, v85, v85
	v_add_f32_e32 v86, v86, v86
	v_mul_f32_e32 v85, 0xbfb8aa3b, v85
	v_mul_f32_e32 v86, 0xbfb8aa3b, v86
	v_exp_f32_e32 v85, v85
	v_exp_f32_e32 v86, v86
	v_mul_f32_e32 v87, 0x3d372713, v69
	v_mul_f32_e32 v87, v69, v87
	v_add_f32_e32 v85, 1.0, v85
	v_add_f32_e32 v86, 1.0, v86
	v_rcp_f32_e32 v85, v85
	v_rcp_f32_e32 v86, v86
	v_fma_f32 v87, v69, v87, v69
	v_mul_f32_e32 v87, 0x3f4c422a, v87
	v_add_f32_e32 v87, v87, v87
	v_addc_co_u32_e32 v73, vcc, 0, v73, vcc
	v_mul_f32_e32 v87, 0xbfb8aa3b, v87
	v_mul_f32_e32 v68, v68, v85
	v_mul_f32_e32 v65, v65, v86
	v_mul_f32_e32 v85, 0x3d372713, v66
	v_mul_f32_e32 v86, 0x3d372713, v70
	global_load_dwordx4 v[76:79], v[72:73], off
	s_nop 0
	global_load_dwordx4 v[72:75], v[72:73], off offset:256
	v_rcp_f32_e32 v84, v84
	v_exp_f32_e32 v87, v87
	v_mul_f32_e32 v85, v66, v85
	v_mul_f32_e32 v86, v70, v86
	v_fma_f32 v85, v66, v85, v66
	v_fma_f32 v86, v70, v86, v70
	v_mul_f32_e32 v85, 0x3f4c422a, v85
	v_mul_f32_e32 v86, 0x3f4c422a, v86
	v_add_f32_e32 v85, v85, v85
	v_add_f32_e32 v86, v86, v86
	v_mul_f32_e32 v64, v64, v84
	v_add_f32_e32 v84, 1.0, v87
	v_mul_f32_e32 v85, 0xbfb8aa3b, v85
	v_mul_f32_e32 v86, 0xbfb8aa3b, v86
	v_rcp_f32_e32 v84, v84
	v_exp_f32_e32 v85, v85
	v_exp_f32_e32 v86, v86
	v_mul_f32_e32 v87, 0x3d372713, v71
	v_mul_f32_e32 v69, v69, v84
	v_add_f32_e32 v84, 1.0, v85
	v_add_f32_e32 v85, 1.0, v86
	v_mul_f32_e32 v86, 0x3d372713, v67
	v_mul_f32_e32 v86, v67, v86
	v_fma_f32 v86, v67, v86, v67
	v_mul_f32_e32 v87, v71, v87
	v_mul_f32_e32 v86, 0x3f4c422a, v86
	v_fma_f32 v87, v71, v87, v71
	v_add_f32_e32 v86, v86, v86
	v_mul_f32_e32 v87, 0x3f4c422a, v87
	v_mul_f32_e32 v86, 0xbfb8aa3b, v86
	v_add_f32_e32 v87, v87, v87
	v_exp_f32_e32 v86, v86
	v_mul_f32_e32 v87, 0xbfb8aa3b, v87
	v_exp_f32_e32 v87, v87
	v_rcp_f32_e32 v84, v84
	v_add_f32_e32 v86, 1.0, v86
	v_rcp_f32_e32 v86, v86
	v_add_f32_e32 v87, 1.0, v87
	v_rcp_f32_e32 v85, v85
	v_rcp_f32_e32 v87, v87
	v_mul_f32_e32 v66, v66, v84
	v_mul_f32_e32 v67, v67, v86
	v_cvt_pk_bf16_f32 v64, v64, v65
	v_mul_f32_e32 v70, v70, v85
	v_mul_f32_e32 v71, v71, v87
	v_cvt_pk_bf16_f32 v65, v66, v67
	v_cvt_pk_bf16_f32 v66, v68, v69
	v_cvt_pk_bf16_f32 v67, v70, v71
	global_store_dwordx4 v[82:83], v[64:67], off
	s_nop 1
	v_lshlrev_b32_e32 v64, 16, v88
	v_fma_f32 v56, v20, v64, v56
	v_mul_f32_e32 v65, 0x3d372713, v56
	v_mul_f32_e32 v65, v56, v65
	v_fma_f32 v65, v56, v65, v56
	v_and_b32_e32 v64, 0xffff0000, v88
	v_mul_f32_e32 v65, 0x3f4c422a, v65
	v_fma_f32 v57, v21, v64, v57
	v_lshlrev_b32_e32 v64, 16, v89
	v_add_f32_e32 v65, v65, v65
	v_fma_f32 v58, v22, v64, v58
	v_and_b32_e32 v64, 0xffff0000, v89
	v_mul_f32_e32 v65, 0xbfb8aa3b, v65
	v_fmac_f32_e32 v59, v23, v64
	v_lshlrev_b32_e32 v64, 16, v90
	v_exp_f32_e32 v65, v65
	v_fma_f32 v60, v16, v64, v60
	v_and_b32_e32 v64, 0xffff0000, v90
	v_fma_f32 v61, v17, v64, v61
	v_lshlrev_b32_e32 v64, 16, v91
	v_fma_f32 v62, v18, v64, v62
	v_and_b32_e32 v64, 0xffff0000, v91
	v_fmac_f32_e32 v63, v19, v64
	v_add_f32_e32 v64, 1.0, v65
	v_mul_f32_e32 v65, 0x3d372713, v60
	v_mul_f32_e32 v66, 0x3d372713, v57
	v_mul_f32_e32 v65, v60, v65
	v_mul_f32_e32 v66, v57, v66
	v_fma_f32 v65, v60, v65, v60
	v_fma_f32 v66, v57, v66, v57
	v_mul_f32_e32 v65, 0x3f4c422a, v65
	v_mul_f32_e32 v66, 0x3f4c422a, v66
	v_add_f32_e32 v65, v65, v65
	v_add_f32_e32 v66, v66, v66
	v_mul_f32_e32 v65, 0xbfb8aa3b, v65
	v_mul_f32_e32 v66, 0xbfb8aa3b, v66
	v_exp_f32_e32 v65, v65
	v_exp_f32_e32 v66, v66
	v_mul_f32_e32 v67, 0x3d372713, v61
	v_mul_f32_e32 v67, v61, v67
	v_add_f32_e32 v65, 1.0, v65
	v_add_f32_e32 v66, 1.0, v66
	v_rcp_f32_e32 v65, v65
	v_rcp_f32_e32 v66, v66
	v_fma_f32 v67, v61, v67, v61
	v_mul_f32_e32 v67, 0x3f4c422a, v67
	v_add_f32_e32 v67, v67, v67
	v_mul_f32_e32 v67, 0xbfb8aa3b, v67
	v_mul_f32_e32 v60, v60, v65
	v_mul_f32_e32 v57, v57, v66
	v_mul_f32_e32 v65, 0x3d372713, v58
	v_mul_f32_e32 v66, 0x3d372713, v62
	v_rcp_f32_e32 v64, v64
	v_exp_f32_e32 v67, v67
	v_mul_f32_e32 v65, v58, v65
	v_mul_f32_e32 v66, v62, v66
	v_fma_f32 v65, v58, v65, v58
	v_fma_f32 v66, v62, v66, v62
	v_mul_f32_e32 v65, 0x3f4c422a, v65
	v_mul_f32_e32 v66, 0x3f4c422a, v66
	v_add_f32_e32 v65, v65, v65
	v_add_f32_e32 v66, v66, v66
	v_mul_f32_e32 v56, v56, v64
	v_add_f32_e32 v64, 1.0, v67
	v_mul_f32_e32 v65, 0xbfb8aa3b, v65
	v_mul_f32_e32 v66, 0xbfb8aa3b, v66
	v_rcp_f32_e32 v64, v64
	v_exp_f32_e32 v65, v65
	v_exp_f32_e32 v66, v66
	v_mul_f32_e32 v67, 0x3d372713, v63
	v_mul_f32_e32 v61, v61, v64
	v_add_f32_e32 v64, 1.0, v65
	v_add_f32_e32 v65, 1.0, v66
	v_mul_f32_e32 v66, 0x3d372713, v59
	v_mul_f32_e32 v66, v59, v66
	v_fma_f32 v66, v59, v66, v59
	v_mul_f32_e32 v66, 0x3f4c422a, v66
	v_mul_f32_e32 v67, v63, v67
	v_add_f32_e32 v66, v66, v66
	v_fma_f32 v67, v63, v67, v63
	v_mul_f32_e32 v66, 0xbfb8aa3b, v66
	v_mul_f32_e32 v67, 0x3f4c422a, v67
	v_exp_f32_e32 v66, v66
	v_add_f32_e32 v67, v67, v67
	v_mul_f32_e32 v67, 0xbfb8aa3b, v67
	v_exp_f32_e32 v67, v67
	v_rcp_f32_e32 v64, v64
	v_add_f32_e32 v66, 1.0, v66
	v_rcp_f32_e32 v66, v66
	v_add_f32_e32 v67, 1.0, v67
	v_rcp_f32_e32 v65, v65
	v_rcp_f32_e32 v67, v67
	v_mul_f32_e32 v58, v58, v64
	v_mul_f32_e32 v59, v59, v66
	v_cvt_pk_bf16_f32 v56, v56, v57
	v_cvt_pk_bf16_f32 v57, v58, v59
	v_cvt_pk_bf16_f32 v58, v60, v61
	v_add_co_u32_e32 v60, vcc, s50, v82
	v_mul_f32_e32 v62, v62, v65
	s_nop 0
	v_addc_co_u32_e32 v61, vcc, 0, v83, vcc
	v_mul_f32_e32 v63, v63, v67
	v_cvt_pk_bf16_f32 v59, v62, v63
	global_store_dwordx4 v[60:61], v[56:59], off
	s_waitcnt vmcnt(0) lgkmcnt(0)
; __device__ __forceinline__ float bf_lo(unsigned w) { return __uint_as_float(w << 16); }
; __device__ __forceinline__ float bf_hi(unsigned w) { return __uint_as_float(w & 0xffff0000u); }
; __device__ __forceinline__ u32x4 pack8(const f32x4& v0, const f32x4& v1) { u32x4 w; w.x = cvt_pk_bf16(v0[0], v0[1]); w.y = cvt_pk_bf16(v0[2], v0[3]); w.z = cvt_pk_bf16(v1[0], v1[1]); w.w = cvt_pk_bf16(v1[2], v1[3]); return w; }
;     __device__ __forceinline__ void operator()(const f32x4 (&acc)[2][2][4][2], const Unit& u, int wr, int wc, int fr_, int fq_) const {
;     ...
;             for (int m = 0; m < 4; ++m) {
;                 asm volatile("" : "+v"(up), "+v"(yp));
;                 if ((m & 1) == 0) {
;                     uwv[0][0] = *(const u32x4*)(up); uwv[0][1] = *(const u32x4*)(up + 128);
;                     uwv[1][0] = *(const u32x4*)(up + (size_t)16 * 64 * 384); uwv[1][1] = *(const u32x4*)(up + (size_t)16 * 64 * 384 + 128);
;                     asm volatile("" ::: "memory"); }
; #pragma unroll
;                 for (int bj = 0; bj < 2; ++bj) {
;                     const u32x4 uw = uwv[m & 1][bj];
;                     f32x4 v0 = acc[ai][bj][m][0], v1 = acc[ai][bj][m][1];
;                     v0[0] += d0[0] * bf_lo(uw.x); v0[1] += d0[1] * bf_hi(uw.x); v0[2] += d0[2] * bf_lo(uw.y); v0[3] += d0[3] * bf_hi(uw.y);
;                     v1[0] += d1[0] * bf_lo(uw.z); v1[1] += d1[1] * bf_hi(uw.z); v1[2] += d1[2] * bf_lo(uw.w); v1[3] += d1[3] * bf_hi(uw.w);
; #pragma unroll
;                     for (int k = 0; k < 4; ++k) { v0[k] = gelu_tanh_f(v0[k]); v1[k] = gelu_tanh_f(v1[k]); }
;                     *(u32x4*)(yp + bj * 8 * 1024) = pack8(v0, v1); }
;                 const int adv = (m == 3) ? (128 - 48) : 16;
;                 up += (size_t)adv * 64 * 384; yp += (size_t)adv * 16 * 1024; }
	s_nop 0
	v_lshlrev_b32_e32 v58, 16, v76
	v_fma_f32 v48, v20, v58, v48
	v_mul_f32_e32 v59, 0x3d372713, v48
	v_mul_f32_e32 v59, v48, v59
	v_fma_f32 v59, v48, v59, v48
	v_and_b32_e32 v58, 0xffff0000, v76
	v_mul_f32_e32 v59, 0x3f4c422a, v59
	v_fma_f32 v49, v21, v58, v49
	v_lshlrev_b32_e32 v58, 16, v77
	v_add_f32_e32 v59, v59, v59
	v_fma_f32 v50, v22, v58, v50
	v_and_b32_e32 v58, 0xffff0000, v77
	v_mul_f32_e32 v59, 0xbfb8aa3b, v59
	v_fmac_f32_e32 v51, v23, v58
	v_lshlrev_b32_e32 v58, 16, v78
	v_exp_f32_e32 v59, v59
	v_fma_f32 v52, v16, v58, v52
	v_and_b32_e32 v58, 0xffff0000, v78
	v_fma_f32 v53, v17, v58, v53
	v_lshlrev_b32_e32 v58, 16, v79
	v_fma_f32 v54, v18, v58, v54
	v_and_b32_e32 v58, 0xffff0000, v79
	v_fmac_f32_e32 v55, v19, v58
	v_add_f32_e32 v58, 1.0, v59
	v_mul_f32_e32 v59, 0x3d372713, v52
	v_mul_f32_e32 v60, 0x3d372713, v49
	v_mul_f32_e32 v59, v52, v59
	v_mul_f32_e32 v60, v49, v60
	v_fma_f32 v59, v52, v59, v52
	v_fma_f32 v60, v49, v60, v49
	v_mul_f32_e32 v59, 0x3f4c422a, v59
	v_mul_f32_e32 v60, 0x3f4c422a, v60
	v_add_f32_e32 v59, v59, v59
	v_add_f32_e32 v60, v60, v60
	v_mul_f32_e32 v59, 0xbfb8aa3b, v59
	v_mul_f32_e32 v60, 0xbfb8aa3b, v60
	v_exp_f32_e32 v59, v59
	v_exp_f32_e32 v60, v60
	v_mul_f32_e32 v61, 0x3d372713, v53
	v_mul_f32_e32 v61, v53, v61
	v_add_f32_e32 v59, 1.0, v59
	v_add_f32_e32 v60, 1.0, v60
	v_rcp_f32_e32 v59, v59
	v_rcp_f32_e32 v60, v60
	v_fma_f32 v61, v53, v61, v53
	v_mul_f32_e32 v61, 0x3f4c422a, v61
	v_add_f32_e32 v61, v61, v61
	v_mul_f32_e32 v61, 0xbfb8aa3b, v61
	v_mul_f32_e32 v52, v52, v59
	v_mul_f32_e32 v49, v49, v60
	v_mul_f32_e32 v59, 0x3d372713, v50
	v_mul_f32_e32 v60, 0x3d372713, v54
	v_rcp_f32_e32 v58, v58
	v_exp_f32_e32 v61, v61
	v_mul_f32_e32 v59, v50, v59
	v_mul_f32_e32 v60, v54, v60
	v_fma_f32 v59, v50, v59, v50
	v_fma_f32 v60, v54, v60, v54
	v_mul_f32_e32 v59, 0x3f4c422a, v59
	v_mul_f32_e32 v60, 0x3f4c422a, v60
	v_add_f32_e32 v59, v59, v59
	v_add_f32_e32 v60, v60, v60
	v_mul_f32_e32 v48, v48, v58
	v_add_f32_e32 v58, 1.0, v61
	v_mul_f32_e32 v59, 0xbfb8aa3b, v59
	v_mul_f32_e32 v60, 0xbfb8aa3b, v60
	v_rcp_f32_e32 v58, v58
	v_exp_f32_e32 v59, v59
	v_exp_f32_e32 v60, v60
	v_mul_f32_e32 v61, 0x3d372713, v55
	v_mul_f32_e32 v53, v53, v58
	v_add_f32_e32 v58, 1.0, v59
	v_add_f32_e32 v59, 1.0, v60
	v_mul_f32_e32 v60, 0x3d372713, v51
	v_mul_f32_e32 v60, v51, v60
	v_fma_f32 v60, v51, v60, v51
	v_mul_f32_e32 v61, v55, v61
	v_mul_f32_e32 v60, 0x3f4c422a, v60
	v_fma_f32 v61, v55, v61, v55
	v_add_f32_e32 v60, v60, v60
	v_mul_f32_e32 v61, 0x3f4c422a, v61
	v_mul_f32_e32 v60, 0xbfb8aa3b, v60
	v_add_f32_e32 v61, v61, v61
	v_exp_f32_e32 v60, v60
	v_mul_f32_e32 v61, 0xbfb8aa3b, v61
	v_exp_f32_e32 v61, v61
	v_rcp_f32_e32 v58, v58
	v_add_f32_e32 v60, 1.0, v60
	v_rcp_f32_e32 v60, v60
	v_add_f32_e32 v61, 1.0, v61
	v_rcp_f32_e32 v59, v59
	v_rcp_f32_e32 v61, v61
	v_lshl_add_u64 v[56:57], v[82:83], 0, s[30:31]
	v_mul_f32_e32 v50, v50, v58
	v_mul_f32_e32 v51, v51, v60
	v_cvt_pk_bf16_f32 v48, v48, v49
	v_mul_f32_e32 v54, v54, v59
	v_mul_f32_e32 v55, v55, v61
	v_cvt_pk_bf16_f32 v49, v50, v51
	v_cvt_pk_bf16_f32 v50, v52, v53
	v_cvt_pk_bf16_f32 v51, v54, v55
	global_store_dwordx4 v[56:57], v[48:51], off
	s_nop 1
	v_lshlrev_b32_e32 v48, 16, v72
	v_fma_f32 v40, v20, v48, v40
	v_mul_f32_e32 v49, 0x3d372713, v40
	v_mul_f32_e32 v49, v40, v49
	v_fma_f32 v49, v40, v49, v40
	v_and_b32_e32 v48, 0xffff0000, v72
	v_mul_f32_e32 v49, 0x3f4c422a, v49
	v_fma_f32 v41, v21, v48, v41
	v_lshlrev_b32_e32 v48, 16, v73
	v_add_f32_e32 v49, v49, v49
	v_fma_f32 v42, v22, v48, v42
	v_and_b32_e32 v48, 0xffff0000, v73
	v_mul_f32_e32 v49, 0xbfb8aa3b, v49
	v_fmac_f32_e32 v43, v23, v48
	v_lshlrev_b32_e32 v48, 16, v74
	v_exp_f32_e32 v49, v49
	v_fma_f32 v44, v16, v48, v44
	v_and_b32_e32 v48, 0xffff0000, v74
	v_fma_f32 v45, v17, v48, v45
	v_lshlrev_b32_e32 v48, 16, v75
	v_fma_f32 v46, v18, v48, v46
	v_and_b32_e32 v48, 0xffff0000, v75
	v_fmac_f32_e32 v47, v19, v48
	v_add_f32_e32 v48, 1.0, v49
	v_mul_f32_e32 v49, 0x3d372713, v44
	v_mul_f32_e32 v50, 0x3d372713, v41
	v_mul_f32_e32 v49, v44, v49
	v_mul_f32_e32 v50, v41, v50
	v_fma_f32 v49, v44, v49, v44
	v_fma_f32 v50, v41, v50, v41
	v_mul_f32_e32 v49, 0x3f4c422a, v49
	v_mul_f32_e32 v50, 0x3f4c422a, v50
	v_add_f32_e32 v49, v49, v49
	v_add_f32_e32 v50, v50, v50
	v_mul_f32_e32 v49, 0xbfb8aa3b, v49
	v_mul_f32_e32 v50, 0xbfb8aa3b, v50
	v_exp_f32_e32 v49, v49
	v_exp_f32_e32 v50, v50
	v_mul_f32_e32 v51, 0x3d372713, v45
	v_mul_f32_e32 v51, v45, v51
	v_add_f32_e32 v49, 1.0, v49
	v_add_f32_e32 v50, 1.0, v50
	v_rcp_f32_e32 v49, v49
	v_rcp_f32_e32 v50, v50
	v_fma_f32 v51, v45, v51, v45
	v_mul_f32_e32 v51, 0x3f4c422a, v51
	v_add_f32_e32 v51, v51, v51
	v_mul_f32_e32 v51, 0xbfb8aa3b, v51
	v_mul_f32_e32 v44, v44, v49
	v_mul_f32_e32 v41, v41, v50
	v_mul_f32_e32 v49, 0x3d372713, v42
	v_mul_f32_e32 v50, 0x3d372713, v46
	v_rcp_f32_e32 v48, v48
	v_exp_f32_e32 v51, v51
	v_mul_f32_e32 v49, v42, v49
	v_mul_f32_e32 v50, v46, v50
	v_fma_f32 v49, v42, v49, v42
	v_fma_f32 v50, v46, v50, v46
	v_mul_f32_e32 v49, 0x3f4c422a, v49
	v_mul_f32_e32 v50, 0x3f4c422a, v50
	v_add_f32_e32 v49, v49, v49
	v_add_f32_e32 v50, v50, v50
	v_mul_f32_e32 v40, v40, v48
	v_add_f32_e32 v48, 1.0, v51
	v_mul_f32_e32 v49, 0xbfb8aa3b, v49
	v_mul_f32_e32 v50, 0xbfb8aa3b, v50
	v_rcp_f32_e32 v48, v48
	v_exp_f32_e32 v49, v49
	v_exp_f32_e32 v50, v50
	v_mul_f32_e32 v51, 0x3d372713, v47
	v_mul_f32_e32 v45, v45, v48
	v_add_f32_e32 v48, 1.0, v49
	v_add_f32_e32 v49, 1.0, v50
	v_mul_f32_e32 v50, 0x3d372713, v43
	v_mul_f32_e32 v50, v43, v50
	v_fma_f32 v50, v43, v50, v43
	v_mul_f32_e32 v50, 0x3f4c422a, v50
	v_mul_f32_e32 v51, v47, v51
	v_add_f32_e32 v50, v50, v50
	v_fma_f32 v51, v47, v51, v47
	v_mul_f32_e32 v50, 0xbfb8aa3b, v50
	v_mul_f32_e32 v51, 0x3f4c422a, v51
	v_exp_f32_e32 v50, v50
	v_add_f32_e32 v51, v51, v51
	v_mul_f32_e32 v51, 0xbfb8aa3b, v51
	v_exp_f32_e32 v51, v51
	v_rcp_f32_e32 v48, v48
	v_add_f32_e32 v50, 1.0, v50
	v_rcp_f32_e32 v50, v50
	v_add_f32_e32 v51, 1.0, v51
	v_rcp_f32_e32 v49, v49
	v_rcp_f32_e32 v51, v51
	v_mul_f32_e32 v42, v42, v48
	v_mul_f32_e32 v43, v43, v50
	v_cvt_pk_bf16_f32 v40, v40, v41
	v_cvt_pk_bf16_f32 v41, v42, v43
	v_cvt_pk_bf16_f32 v42, v44, v45
	v_add_co_u32_e32 v44, vcc, s50, v56
	v_mul_f32_e32 v46, v46, v49
	s_nop 0
	v_addc_co_u32_e32 v45, vcc, 0, v57, vcc
	v_mul_f32_e32 v47, v47, v51
	v_cvt_pk_bf16_f32 v43, v46, v47
	global_store_dwordx4 v[44:45], v[40:43], off
	v_lshl_add_u64 v[48:49], v[56:57], 0, s[30:31]
	s_nop 0
	v_lshl_add_u64 v[40:41], v[80:81], 0, s[28:29]
	global_load_dwordx4 v[52:55], v[40:41], off
	global_load_dwordx4 v[56:59], v[40:41], off offset:256
	v_lshl_add_u64 v[50:51], v[40:41], 0, s[28:29]
	v_add_co_u32_e32 v40, vcc, s60, v40
	s_waitcnt vmcnt(0) lgkmcnt(0)
; __device__ __forceinline__ float bf_lo(unsigned w) { return __uint_as_float(w << 16); }
; __device__ __forceinline__ float bf_hi(unsigned w) { return __uint_as_float(w & 0xffff0000u); }
; __device__ __forceinline__ u32x4 pack8(const f32x4& v0, const f32x4& v1) { u32x4 w; w.x = cvt_pk_bf16(v0[0], v0[1]); w.y = cvt_pk_bf16(v0[2], v0[3]); w.z = cvt_pk_bf16(v1[0], v1[1]); w.w = cvt_pk_bf16(v1[2], v1[3]); return w; }
;     __device__ __forceinline__ void operator()(const f32x4 (&acc)[2][2][4][2], const Unit& u, int wr, int wc, int fr_, int fq_) const {
;     ...
;             for (int m = 0; m < 4; ++m) {
;                 asm volatile("" : "+v"(up), "+v"(yp));
;                 if ((m & 1) == 0) {
;                     uwv[0][0] = *(const u32x4*)(up); uwv[0][1] = *(const u32x4*)(up + 128);
;                     uwv[1][0] = *(const u32x4*)(up + (size_t)16 * 64 * 384); uwv[1][1] = *(const u32x4*)(up + (size_t)16 * 64 * 384 + 128);
;                     asm volatile("" ::: "memory"); }
; #pragma unroll
;                 for (int bj = 0; bj < 2; ++bj) {
;                     const u32x4 uw = uwv[m & 1][bj];
;                     f32x4 v0 = acc[ai][bj][m][0], v1 = acc[ai][bj][m][1];
;                     v0[0] += d0[0] * bf_lo(uw.x); v0[1] += d0[1] * bf_hi(uw.x); v0[2] += d0[2] * bf_lo(uw.y); v0[3] += d0[3] * bf_hi(uw.y);
;                     v1[0] += d1[0] * bf_lo(uw.z); v1[1] += d1[1] * bf_hi(uw.z); v1[2] += d1[2] * bf_lo(uw.w); v1[3] += d1[3] * bf_hi(uw.w);
; #pragma unroll
;                     for (int k = 0; k < 4; ++k) { v0[k] = gelu_tanh_f(v0[k]); v1[k] = gelu_tanh_f(v1[k]); }
;                     *(u32x4*)(yp + bj * 8 * 1024) = pack8(v0, v1); }
;                 const int adv = (m == 3) ? (128 - 48) : 16;
;                 up += (size_t)adv * 64 * 384; yp += (size_t)adv * 16 * 1024; }
	v_lshlrev_b32_e32 v60, 16, v52
	v_and_b32_e32 v52, 0xffff0000, v52
	v_fma_f32 v32, v20, v60, v32
	v_fma_f32 v33, v21, v52, v33
	v_lshlrev_b32_e32 v52, 16, v53
	v_fma_f32 v34, v22, v52, v34
	v_and_b32_e32 v52, 0xffff0000, v53
	v_mul_f32_e32 v53, 0x3d372713, v32
	v_mul_f32_e32 v53, v32, v53
	v_fma_f32 v53, v32, v53, v32
	v_mul_f32_e32 v53, 0x3f4c422a, v53
	v_add_f32_e32 v53, v53, v53
	v_mul_f32_e32 v53, 0xbfb8aa3b, v53
	v_fmac_f32_e32 v35, v23, v52
	v_lshlrev_b32_e32 v52, 16, v54
	v_exp_f32_e32 v53, v53
	v_fma_f32 v36, v16, v52, v36
	v_and_b32_e32 v52, 0xffff0000, v54
	v_fma_f32 v37, v17, v52, v37
	v_lshlrev_b32_e32 v52, 16, v55
	v_fma_f32 v38, v18, v52, v38
	v_and_b32_e32 v52, 0xffff0000, v55
	v_fmac_f32_e32 v39, v19, v52
	v_add_f32_e32 v52, 1.0, v53
	v_mul_f32_e32 v53, 0x3d372713, v36
	v_mul_f32_e32 v54, 0x3d372713, v33
	v_mul_f32_e32 v53, v36, v53
	v_mul_f32_e32 v54, v33, v54
	v_fma_f32 v53, v36, v53, v36
	v_fma_f32 v54, v33, v54, v33
	v_mul_f32_e32 v53, 0x3f4c422a, v53
	v_mul_f32_e32 v54, 0x3f4c422a, v54
	v_add_f32_e32 v53, v53, v53
	v_add_f32_e32 v54, v54, v54
	v_mul_f32_e32 v53, 0xbfb8aa3b, v53
	v_mul_f32_e32 v54, 0xbfb8aa3b, v54
	v_exp_f32_e32 v53, v53
	v_exp_f32_e32 v54, v54
	v_mul_f32_e32 v55, 0x3d372713, v37
	v_mul_f32_e32 v55, v37, v55
	v_add_f32_e32 v53, 1.0, v53
	v_add_f32_e32 v54, 1.0, v54
	v_rcp_f32_e32 v53, v53
	v_rcp_f32_e32 v54, v54
	v_fma_f32 v55, v37, v55, v37
	v_mul_f32_e32 v55, 0x3f4c422a, v55
	v_add_f32_e32 v55, v55, v55
	v_addc_co_u32_e32 v41, vcc, 0, v41, vcc
	v_mul_f32_e32 v55, 0xbfb8aa3b, v55
	v_mul_f32_e32 v36, v36, v53
	v_mul_f32_e32 v33, v33, v54
	v_mul_f32_e32 v53, 0x3d372713, v34
	v_mul_f32_e32 v54, 0x3d372713, v38
	global_load_dwordx4 v[44:47], v[40:41], off
	s_nop 0
	global_load_dwordx4 v[40:43], v[40:41], off offset:256
	v_rcp_f32_e32 v52, v52
	v_exp_f32_e32 v55, v55
	v_mul_f32_e32 v53, v34, v53
	v_mul_f32_e32 v54, v38, v54
	v_fma_f32 v53, v34, v53, v34
	v_fma_f32 v54, v38, v54, v38
	v_mul_f32_e32 v53, 0x3f4c422a, v53
	v_mul_f32_e32 v54, 0x3f4c422a, v54
	v_add_f32_e32 v53, v53, v53
	v_add_f32_e32 v54, v54, v54
	v_mul_f32_e32 v32, v32, v52
	v_add_f32_e32 v52, 1.0, v55
	v_mul_f32_e32 v53, 0xbfb8aa3b, v53
	v_mul_f32_e32 v54, 0xbfb8aa3b, v54
	v_rcp_f32_e32 v52, v52
	v_exp_f32_e32 v53, v53
	v_exp_f32_e32 v54, v54
	v_mul_f32_e32 v55, 0x3d372713, v39
	v_mul_f32_e32 v37, v37, v52
	v_add_f32_e32 v52, 1.0, v53
	v_add_f32_e32 v53, 1.0, v54
	v_mul_f32_e32 v54, 0x3d372713, v35
	v_mul_f32_e32 v54, v35, v54
	v_fma_f32 v54, v35, v54, v35
	v_mul_f32_e32 v55, v39, v55
	v_mul_f32_e32 v54, 0x3f4c422a, v54
	v_fma_f32 v55, v39, v55, v39
	v_add_f32_e32 v54, v54, v54
	v_mul_f32_e32 v55, 0x3f4c422a, v55
	v_mul_f32_e32 v54, 0xbfb8aa3b, v54
	v_add_f32_e32 v55, v55, v55
	v_exp_f32_e32 v54, v54
	v_mul_f32_e32 v55, 0xbfb8aa3b, v55
	v_exp_f32_e32 v55, v55
	v_rcp_f32_e32 v52, v52
	v_add_f32_e32 v54, 1.0, v54
	v_rcp_f32_e32 v54, v54
	v_add_f32_e32 v55, 1.0, v55
	v_rcp_f32_e32 v53, v53
	v_rcp_f32_e32 v55, v55
	v_mul_f32_e32 v34, v34, v52
	v_mul_f32_e32 v35, v35, v54
	v_cvt_pk_bf16_f32 v32, v32, v33
	v_mul_f32_e32 v38, v38, v53
	v_mul_f32_e32 v39, v39, v55
	v_cvt_pk_bf16_f32 v33, v34, v35
	v_cvt_pk_bf16_f32 v34, v36, v37
	v_cvt_pk_bf16_f32 v35, v38, v39
	global_store_dwordx4 v[48:49], v[32:35], off
	s_nop 1
	v_lshlrev_b32_e32 v32, 16, v56
	v_fma_f32 v24, v20, v32, v24
	v_mul_f32_e32 v33, 0x3d372713, v24
	v_mul_f32_e32 v33, v24, v33
	v_fma_f32 v33, v24, v33, v24
	v_and_b32_e32 v32, 0xffff0000, v56
	v_mul_f32_e32 v33, 0x3f4c422a, v33
	v_fma_f32 v25, v21, v32, v25
	v_lshlrev_b32_e32 v32, 16, v57
	v_add_f32_e32 v33, v33, v33
	v_fma_f32 v26, v22, v32, v26
	v_and_b32_e32 v32, 0xffff0000, v57
	v_mul_f32_e32 v33, 0xbfb8aa3b, v33
	v_fmac_f32_e32 v27, v23, v32
	v_lshlrev_b32_e32 v32, 16, v58
	v_exp_f32_e32 v33, v33
	v_fma_f32 v28, v16, v32, v28
	v_and_b32_e32 v32, 0xffff0000, v58
	v_fma_f32 v29, v17, v32, v29
	v_lshlrev_b32_e32 v32, 16, v59
	v_fma_f32 v30, v18, v32, v30
	v_and_b32_e32 v32, 0xffff0000, v59
	v_fmac_f32_e32 v31, v19, v32
	v_add_f32_e32 v32, 1.0, v33
	v_mul_f32_e32 v33, 0x3d372713, v28
	v_mul_f32_e32 v34, 0x3d372713, v25
	v_mul_f32_e32 v33, v28, v33
	v_mul_f32_e32 v34, v25, v34
	v_fma_f32 v33, v28, v33, v28
	v_fma_f32 v34, v25, v34, v25
	v_mul_f32_e32 v33, 0x3f4c422a, v33
	v_mul_f32_e32 v34, 0x3f4c422a, v34
	v_add_f32_e32 v33, v33, v33
	v_add_f32_e32 v34, v34, v34
	v_mul_f32_e32 v33, 0xbfb8aa3b, v33
	v_mul_f32_e32 v34, 0xbfb8aa3b, v34
	v_exp_f32_e32 v33, v33
	v_exp_f32_e32 v34, v34
	v_mul_f32_e32 v35, 0x3d372713, v29
	v_mul_f32_e32 v35, v29, v35
	v_add_f32_e32 v33, 1.0, v33
	v_add_f32_e32 v34, 1.0, v34
	v_rcp_f32_e32 v33, v33
	v_rcp_f32_e32 v34, v34
	v_fma_f32 v35, v29, v35, v29
	v_mul_f32_e32 v35, 0x3f4c422a, v35
	v_add_f32_e32 v35, v35, v35
	v_mul_f32_e32 v35, 0xbfb8aa3b, v35
	v_mul_f32_e32 v28, v28, v33
	v_mul_f32_e32 v25, v25, v34
	v_mul_f32_e32 v33, 0x3d372713, v26
	v_mul_f32_e32 v34, 0x3d372713, v30
	v_rcp_f32_e32 v32, v32
	v_exp_f32_e32 v35, v35
	v_mul_f32_e32 v33, v26, v33
	v_mul_f32_e32 v34, v30, v34
	v_fma_f32 v33, v26, v33, v26
	v_fma_f32 v34, v30, v34, v30
	v_mul_f32_e32 v33, 0x3f4c422a, v33
	v_mul_f32_e32 v34, 0x3f4c422a, v34
	v_add_f32_e32 v33, v33, v33
	v_add_f32_e32 v34, v34, v34
	v_mul_f32_e32 v24, v24, v32
	v_add_f32_e32 v32, 1.0, v35
	v_mul_f32_e32 v33, 0xbfb8aa3b, v33
	v_mul_f32_e32 v34, 0xbfb8aa3b, v34
	v_rcp_f32_e32 v32, v32
	v_exp_f32_e32 v33, v33
	v_exp_f32_e32 v34, v34
	v_mul_f32_e32 v35, 0x3d372713, v31
	v_mul_f32_e32 v29, v29, v32
	v_add_f32_e32 v32, 1.0, v33
	v_add_f32_e32 v33, 1.0, v34
	v_mul_f32_e32 v34, 0x3d372713, v27
	v_mul_f32_e32 v34, v27, v34
	v_fma_f32 v34, v27, v34, v27
	v_mul_f32_e32 v34, 0x3f4c422a, v34
	v_mul_f32_e32 v35, v31, v35
	v_add_f32_e32 v34, v34, v34
	v_fma_f32 v35, v31, v35, v31
	v_mul_f32_e32 v34, 0xbfb8aa3b, v34
	v_mul_f32_e32 v35, 0x3f4c422a, v35
	v_exp_f32_e32 v34, v34
	v_add_f32_e32 v35, v35, v35
	v_mul_f32_e32 v35, 0xbfb8aa3b, v35
	v_exp_f32_e32 v35, v35
	v_rcp_f32_e32 v32, v32
	v_add_f32_e32 v34, 1.0, v34
	v_rcp_f32_e32 v34, v34
	v_add_f32_e32 v35, 1.0, v35
	v_rcp_f32_e32 v33, v33
	v_rcp_f32_e32 v35, v35
	v_mul_f32_e32 v26, v26, v32
	v_mul_f32_e32 v27, v27, v34
	v_cvt_pk_bf16_f32 v24, v24, v25
	v_cvt_pk_bf16_f32 v25, v26, v27
	v_cvt_pk_bf16_f32 v26, v28, v29
	v_add_co_u32_e32 v28, vcc, s50, v48
	v_mul_f32_e32 v30, v30, v33
	s_nop 0
	v_addc_co_u32_e32 v29, vcc, 0, v49, vcc
	v_mul_f32_e32 v31, v31, v35
	v_cvt_pk_bf16_f32 v27, v30, v31
	global_store_dwordx4 v[28:29], v[24:27], off
	s_waitcnt vmcnt(0) lgkmcnt(0)
; __device__ __forceinline__ float bf_lo(unsigned w) { return __uint_as_float(w << 16); }
; __device__ __forceinline__ float bf_hi(unsigned w) { return __uint_as_float(w & 0xffff0000u); }
; #define PG8_BAR __builtin_amdgcn_s_barrier()
;     __device__ __forceinline__ void operator()(const f32x4 (&acc)[2][2][4][2], const Unit& u, int wr, int wc, int fr_, int fq_) const {
;     ...
;             for (int m = 0; m < 4; ++m) {
;                 asm volatile("" : "+v"(up), "+v"(yp));
;                 if ((m & 1) == 0) {
;                     uwv[0][0] = *(const u32x4*)(up); uwv[0][1] = *(const u32x4*)(up + 128);
;                     uwv[1][0] = *(const u32x4*)(up + (size_t)16 * 64 * 384); uwv[1][1] = *(const u32x4*)(up + (size_t)16 * 64 * 384 + 128);
;                     asm volatile("" ::: "memory"); }
; #pragma unroll
;                 for (int bj = 0; bj < 2; ++bj) {
;                     const u32x4 uw = uwv[m & 1][bj];
;                     f32x4 v0 = acc[ai][bj][m][0], v1 = acc[ai][bj][m][1];
;                     v0[0] += d0[0] * bf_lo(uw.x); v0[1] += d0[1] * bf_hi(uw.x); v0[2] += d0[2] * bf_lo(uw.y); v0[3] += d0[3] * bf_hi(uw.y);
;                     v1[0] += d1[0] * bf_lo(uw.z); v1[1] += d1[1] * bf_hi(uw.z); v1[2] += d1[2] * bf_lo(uw.w); v1[3] += d1[3] * bf_hi(uw.w);
; #pragma unroll
;                     for (int k = 0; k < 4; ++k) { v0[k] = gelu_tanh_f(v0[k]); v1[k] = gelu_tanh_f(v1[k]); }
;                     *(u32x4*)(yp + bj * 8 * 1024) = pack8(v0, v1); }
;                 const int adv = (m == 3) ? (128 - 48) : 16;
;                 up += (size_t)adv * 64 * 384; yp += (size_t)adv * 16 * 1024; }
; template <class Epi, class Sched, bool ALIGN_EPI = false, bool SP2 = false>
; __device__ __forceinline__ void gemm_phase(PG8_LAS unsigned char* lds, const Gemm g, const Sched& S, const Epi& E, const int wid) {
;     ...
;         if constexpr (ALIGN_EPI) { if (wr == 0) PG8_BAR; }
;         E(acc, cur, wr, wc, fr, fq);
;         if (!has_next) break;
; #pragma unroll
;         for (int a = 0; a < 2; ++a)
; #pragma unroll
;             for (int b = 0; b < 2; ++b)
; #pragma unroll
;                 for (int m = 0; m < 4; ++m)
; #pragma unroll
;                     for (int n = 0; n < 2; ++n) acc[a][b][m][n] = (f32x4){0.f, 0.f, 0.f, 0.f};
;         cur = nxt; cA = nA; cB = nB; ++ui;
;         if constexpr (ALIGN_EPI) { if (wr == 1) PG8_BAR; }
;     }
	s_nop 0
	v_lshlrev_b32_e32 v26, 16, v44
	v_fma_f32 v8, v20, v26, v8
	v_mul_f32_e32 v27, 0x3d372713, v8
	v_mul_f32_e32 v27, v8, v27
	v_fma_f32 v27, v8, v27, v8
	v_and_b32_e32 v26, 0xffff0000, v44
	v_mul_f32_e32 v27, 0x3f4c422a, v27
	v_fma_f32 v9, v21, v26, v9
	v_lshlrev_b32_e32 v26, 16, v45
	v_add_f32_e32 v27, v27, v27
	v_fma_f32 v10, v22, v26, v10
	v_and_b32_e32 v26, 0xffff0000, v45
	v_mul_f32_e32 v27, 0xbfb8aa3b, v27
	v_fmac_f32_e32 v11, v23, v26
	v_lshlrev_b32_e32 v26, 16, v46
	v_exp_f32_e32 v27, v27
	v_fma_f32 v12, v16, v26, v12
	v_and_b32_e32 v26, 0xffff0000, v46
	v_fma_f32 v13, v17, v26, v13
	v_lshlrev_b32_e32 v26, 16, v47
	v_fma_f32 v14, v18, v26, v14
	v_and_b32_e32 v26, 0xffff0000, v47
	v_fmac_f32_e32 v15, v19, v26
	v_add_f32_e32 v26, 1.0, v27
	v_mul_f32_e32 v27, 0x3d372713, v12
	v_mul_f32_e32 v28, 0x3d372713, v9
	v_mul_f32_e32 v27, v12, v27
	v_mul_f32_e32 v28, v9, v28
	v_fma_f32 v27, v12, v27, v12
	v_fma_f32 v28, v9, v28, v9
	v_mul_f32_e32 v27, 0x3f4c422a, v27
	v_mul_f32_e32 v28, 0x3f4c422a, v28
	v_add_f32_e32 v27, v27, v27
	v_add_f32_e32 v28, v28, v28
	v_mul_f32_e32 v27, 0xbfb8aa3b, v27
	v_mul_f32_e32 v28, 0xbfb8aa3b, v28
	v_exp_f32_e32 v27, v27
	v_exp_f32_e32 v28, v28
	v_mul_f32_e32 v29, 0x3d372713, v13
	v_mul_f32_e32 v29, v13, v29
	v_add_f32_e32 v27, 1.0, v27
	v_add_f32_e32 v28, 1.0, v28
	v_rcp_f32_e32 v27, v27
	v_rcp_f32_e32 v28, v28
	v_fma_f32 v29, v13, v29, v13
	v_mul_f32_e32 v29, 0x3f4c422a, v29
	v_add_f32_e32 v29, v29, v29
	v_mul_f32_e32 v29, 0xbfb8aa3b, v29
	v_mul_f32_e32 v12, v12, v27
	v_mul_f32_e32 v9, v9, v28
	v_mul_f32_e32 v27, 0x3d372713, v10
	v_mul_f32_e32 v28, 0x3d372713, v14
	v_rcp_f32_e32 v26, v26
	v_exp_f32_e32 v29, v29
	v_mul_f32_e32 v27, v10, v27
	v_mul_f32_e32 v28, v14, v28
	v_fma_f32 v27, v10, v27, v10
	v_fma_f32 v28, v14, v28, v14
	v_mul_f32_e32 v27, 0x3f4c422a, v27
	v_mul_f32_e32 v28, 0x3f4c422a, v28
	v_add_f32_e32 v27, v27, v27
	v_add_f32_e32 v28, v28, v28
	v_mul_f32_e32 v8, v8, v26
	v_add_f32_e32 v26, 1.0, v29
	v_mul_f32_e32 v27, 0xbfb8aa3b, v27
	v_mul_f32_e32 v28, 0xbfb8aa3b, v28
	v_rcp_f32_e32 v26, v26
	v_exp_f32_e32 v27, v27
	v_exp_f32_e32 v28, v28
	v_mul_f32_e32 v29, 0x3d372713, v15
	v_mul_f32_e32 v13, v13, v26
	v_add_f32_e32 v26, 1.0, v27
	v_add_f32_e32 v27, 1.0, v28
	v_mul_f32_e32 v28, 0x3d372713, v11
	v_mul_f32_e32 v28, v11, v28
	v_fma_f32 v28, v11, v28, v11
	v_mul_f32_e32 v29, v15, v29
	v_mul_f32_e32 v28, 0x3f4c422a, v28
	v_fma_f32 v29, v15, v29, v15
	v_add_f32_e32 v28, v28, v28
	v_mul_f32_e32 v29, 0x3f4c422a, v29
	v_mul_f32_e32 v28, 0xbfb8aa3b, v28
	v_add_f32_e32 v29, v29, v29
	v_exp_f32_e32 v28, v28
	v_mul_f32_e32 v29, 0xbfb8aa3b, v29
	v_exp_f32_e32 v29, v29
	v_rcp_f32_e32 v26, v26
	v_add_f32_e32 v28, 1.0, v28
	v_rcp_f32_e32 v28, v28
	v_add_f32_e32 v29, 1.0, v29
	v_rcp_f32_e32 v27, v27
	v_rcp_f32_e32 v29, v29
	v_lshl_add_u64 v[24:25], v[48:49], 0, s[30:31]
	v_mul_f32_e32 v10, v10, v26
	v_mul_f32_e32 v11, v11, v28
	v_cvt_pk_bf16_f32 v8, v8, v9
	v_mul_f32_e32 v14, v14, v27
	v_mul_f32_e32 v15, v15, v29
	v_cvt_pk_bf16_f32 v9, v10, v11
	v_cvt_pk_bf16_f32 v10, v12, v13
	v_cvt_pk_bf16_f32 v11, v14, v15
	global_store_dwordx4 v[24:25], v[8:11], off
	s_nop 1
	v_lshlrev_b32_e32 v8, 16, v40
	v_fma_f32 v0, v20, v8, v0
	v_mul_f32_e32 v9, 0x3d372713, v0
	v_mul_f32_e32 v9, v0, v9
	v_fma_f32 v9, v0, v9, v0
	v_and_b32_e32 v8, 0xffff0000, v40
	v_mul_f32_e32 v9, 0x3f4c422a, v9
	v_fma_f32 v1, v21, v8, v1
	v_lshlrev_b32_e32 v8, 16, v41
	v_add_f32_e32 v9, v9, v9
	v_fma_f32 v2, v22, v8, v2
	v_and_b32_e32 v8, 0xffff0000, v41
	v_mul_f32_e32 v9, 0xbfb8aa3b, v9
	v_fmac_f32_e32 v3, v23, v8
	v_lshlrev_b32_e32 v8, 16, v42
	v_exp_f32_e32 v9, v9
	v_fma_f32 v4, v16, v8, v4
	v_and_b32_e32 v8, 0xffff0000, v42
	v_fma_f32 v5, v17, v8, v5
	v_lshlrev_b32_e32 v8, 16, v43
	v_fma_f32 v6, v18, v8, v6
	v_and_b32_e32 v8, 0xffff0000, v43
	v_fmac_f32_e32 v7, v19, v8
	v_add_f32_e32 v8, 1.0, v9
	v_mul_f32_e32 v9, 0x3d372713, v4
	v_mul_f32_e32 v10, 0x3d372713, v1
	v_mul_f32_e32 v9, v4, v9
	v_mul_f32_e32 v10, v1, v10
	v_fma_f32 v9, v4, v9, v4
	v_fma_f32 v10, v1, v10, v1
	v_mul_f32_e32 v9, 0x3f4c422a, v9
	v_mul_f32_e32 v10, 0x3f4c422a, v10
	v_add_f32_e32 v9, v9, v9
	v_add_f32_e32 v10, v10, v10
	v_mul_f32_e32 v9, 0xbfb8aa3b, v9
	v_mul_f32_e32 v10, 0xbfb8aa3b, v10
	v_exp_f32_e32 v9, v9
	v_exp_f32_e32 v10, v10
	v_mul_f32_e32 v11, 0x3d372713, v5
	v_mul_f32_e32 v11, v5, v11
	v_add_f32_e32 v9, 1.0, v9
	v_add_f32_e32 v10, 1.0, v10
	v_rcp_f32_e32 v9, v9
	v_rcp_f32_e32 v10, v10
	v_fma_f32 v11, v5, v11, v5
	v_mul_f32_e32 v11, 0x3f4c422a, v11
	v_add_f32_e32 v11, v11, v11
	v_mul_f32_e32 v11, 0xbfb8aa3b, v11
	v_mul_f32_e32 v4, v4, v9
	v_mul_f32_e32 v1, v1, v10
	v_mul_f32_e32 v9, 0x3d372713, v2
	v_mul_f32_e32 v10, 0x3d372713, v6
	v_rcp_f32_e32 v8, v8
	v_exp_f32_e32 v11, v11
	v_mul_f32_e32 v9, v2, v9
	v_mul_f32_e32 v10, v6, v10
	v_fma_f32 v9, v2, v9, v2
	v_fma_f32 v10, v6, v10, v6
	v_mul_f32_e32 v9, 0x3f4c422a, v9
	v_mul_f32_e32 v10, 0x3f4c422a, v10
	v_add_f32_e32 v9, v9, v9
	v_add_f32_e32 v10, v10, v10
	v_mul_f32_e32 v0, v0, v8
	v_add_f32_e32 v8, 1.0, v11
	v_mul_f32_e32 v9, 0xbfb8aa3b, v9
	v_mul_f32_e32 v10, 0xbfb8aa3b, v10
	v_rcp_f32_e32 v8, v8
	v_exp_f32_e32 v9, v9
	v_exp_f32_e32 v10, v10
	v_mul_f32_e32 v11, 0x3d372713, v7
	v_mul_f32_e32 v5, v5, v8
	v_add_f32_e32 v8, 1.0, v9
	v_add_f32_e32 v9, 1.0, v10
	v_mul_f32_e32 v10, 0x3d372713, v3
	v_mul_f32_e32 v10, v3, v10
	v_fma_f32 v10, v3, v10, v3
	v_mul_f32_e32 v10, 0x3f4c422a, v10
	v_add_f32_e32 v10, v10, v10
	v_mul_f32_e32 v11, v7, v11
	v_mul_f32_e32 v10, 0xbfb8aa3b, v10
	v_fma_f32 v11, v7, v11, v7
	v_exp_f32_e32 v10, v10
	v_mul_f32_e32 v11, 0x3f4c422a, v11
	v_add_f32_e32 v11, v11, v11
	v_mul_f32_e32 v11, 0xbfb8aa3b, v11
	v_exp_f32_e32 v11, v11
	v_rcp_f32_e32 v8, v8
	v_add_f32_e32 v10, 1.0, v10
	v_rcp_f32_e32 v10, v10
	v_add_f32_e32 v11, 1.0, v11
	v_rcp_f32_e32 v9, v9
	v_rcp_f32_e32 v11, v11
	v_mul_f32_e32 v2, v2, v8
	v_mul_f32_e32 v3, v3, v10
	v_cvt_pk_bf16_f32 v0, v0, v1
	v_cvt_pk_bf16_f32 v1, v2, v3
	v_cvt_pk_bf16_f32 v2, v4, v5
	v_add_co_u32_e32 v4, vcc, 0x4000, v24
	v_mul_f32_e32 v6, v6, v9
	s_nop 0
	v_addc_co_u32_e32 v5, vcc, 0, v25, vcc
	s_and_b64 vcc, exec, s[0:1]
	s_mov_b64 s[0:1], -1
	v_mul_f32_e32 v7, v7, v11
	v_cvt_pk_bf16_f32 v3, v6, v7
	global_store_dwordx4 v[4:5], v[0:3], off
	s_cbranch_vccnz .LBB0_951
	s_andn2_b64 vcc, exec, s[10:11]
	s_cbranch_vccnz .LBB0_950
	s_barrier
	s_branch .LBB0_950

; __device__ __forceinline__ int lane_asm() { int l; asm volatile("v_mbcnt_lo_u32_b32 %0, -1, 0\n\tv_mbcnt_hi_u32_b32 %0, -1, %0" : "=v"(l)); return l; }
;     __host__ __device__ bool next(int i, Unit& u) const { const long L = (long)i * G + c; if (L >= nun) return false; u.pz = (int)L / nM; u.pm = (int)L % nM; u.pn = 0; return true; }
;   __device__ __forceinline__ bool next(int i,AttnUnit&u)const{ const int v=vcu+(i>>2)*G; if(v>=256)return false; const int s=v&15,k=i&3; u.bh=v>>4; u.qb=(k&1)?(32*(k>>1)+31-s):(32*(k>>1)+s); return true; }
;   bool fixed; { const int l=lane_asm(); float gq=__builtin_fabsf(T.qn[l]),gk=__builtin_fabsf(T.kn[l]);
;     #pragma unroll
;     for(int o_=1;o_<64;o_<<=1){gq=__builtin_fmaxf(gq,__shfl_xor(gq,o_));gk=__builtin_fmaxf(gk,__shfl_xor(gk,o_));}
;     const float bound=C2*64.0f*1.03f*gq*gk; fixed=__builtin_amdgcn_readfirstlane((int)(bound<=60.0f))!=0; }
;   AttnUnit u;
;   for(int i=0;S.next(i,u);++i){ const int h=u.bh>>1,c=u.bh&1;
.LBB0_966:
	v_mbcnt_lo_u32_b32 v0, -1, 0
	v_mbcnt_hi_u32_b32 v0, -1, v0
	s_add_u32 s82, s8, 0x10600000
	v_ashrrev_i32_e32 v1, 31, v0
	v_lshlrev_b64 v[0:1], 2, v[0:1]
	v_lshl_add_u64 v[2:3], s[4:5], 0, v[0:1]
	global_load_dword v2, v[2:3], off
	v_lshl_add_u64 v[0:1], s[0:1], 0, v[0:1]
	global_load_dword v0, v[0:1], off
	v_mbcnt_lo_u32_b32 v3, -1, 0
	v_mbcnt_hi_u32_b32 v3, -1, v3
	v_and_b32_e32 v4, 64, v3
	v_xor_b32_e32 v5, 1, v3
	v_add_u32_e32 v4, 64, v4
	v_cmp_lt_i32_e32 vcc, v5, v4
	v_xor_b32_e32 v6, 2, v3
	v_xor_b32_e32 v7, 4, v3
	v_cndmask_b32_e32 v5, v3, v5, vcc
	v_lshlrev_b32_e32 v5, 2, v5
	v_cmp_lt_i32_e32 vcc, v6, v4
	v_xor_b32_e32 v8, 8, v3
	v_xor_b32_e32 v9, 16, v3
	v_cndmask_b32_e32 v6, v3, v6, vcc
	v_lshlrev_b32_e32 v6, 2, v6
	v_cmp_lt_i32_e32 vcc, v7, v4
	v_xor_b32_e32 v10, 32, v3
	s_addc_u32 s85, s9, 0
	v_cndmask_b32_e32 v7, v3, v7, vcc
	v_lshlrev_b32_e32 v7, 2, v7
	v_cmp_lt_i32_e32 vcc, v8, v4
	s_add_u32 s86, s8, 0x12600000
	s_addc_u32 s87, s9, 0
	v_cndmask_b32_e32 v8, v3, v8, vcc
	v_lshlrev_b32_e32 v8, 2, v8
	v_cmp_lt_i32_e32 vcc, v9, v4
	s_add_u32 s88, s8, 0x14600000
	s_addc_u32 s89, s9, 0
	s_add_u32 s90, s8, 0xc600000
	s_mov_b32 s0, 0x42700000
	s_addc_u32 s91, s9, 0
	s_add_u32 s4, s8, 0x480000
	s_addc_u32 s5, s9, 0
	v_writelane_b32 v254, s4, 5
	s_mov_b32 s6, s92
	s_mov_b32 s11, 0
	v_writelane_b32 v254, s5, 6
	s_mov_b32 s5, s93
	v_writelane_b32 v254, s5, 2
	v_writelane_b32 v254, s6, 1
	s_mov_b32 s13, s11
	v_mov_b32_e32 v1, 0
	s_mov_b64 s[64:65], 0x80
	s_mov_b64 s[14:15], 0x20000
	s_mov_b64 s[16:17], 0x40000
	s_mov_b64 s[66:67], 0x60000
	s_mov_b64 s[74:75], 0x20080
	s_mov_b64 s[22:23], 0x12680000
	s_mov_b64 s[24:25], 0x14640000
	s_mov_b64 s[26:27], 0x14640080
	s_mov_b32 s84, 0x41000000
	s_mov_b64 s[28:29], 0x126a0000
	s_mov_b64 s[38:39], 0x14660000
	s_mov_b64 s[40:41], 0x14660080
	s_mov_b64 s[42:43], 0x12660000
	s_mov_b64 s[44:45], 0x14620000
	s_mov_b64 s[46:47], 0x14620080
	v_mov_b32_e32 v232, 0xff800000
	s_mov_b32 s19, 0
	s_waitcnt vmcnt(0) lgkmcnt(0)
	v_and_b32_e32 v11, 0x7fffffff, v2
	ds_bpermute_b32 v11, v5, v11
	v_and_b32_e32 v12, 0x7fffffff, v0
	ds_bpermute_b32 v5, v5, v12
	v_max_f32_e64 v2, |v2|, |v2|
	v_max_f32_e64 v0, |v0|, |v0|
	s_waitcnt lgkmcnt(1)
	v_max_f32_e32 v11, v11, v11
	v_max_f32_e32 v2, v2, v11
	s_waitcnt lgkmcnt(0)
	v_max_f32_e32 v5, v5, v5
	v_max_f32_e32 v0, v0, v5
	ds_bpermute_b32 v5, v6, v2
	ds_bpermute_b32 v6, v6, v0
	s_waitcnt lgkmcnt(1)
	v_max_f32_e32 v5, v5, v5
	s_waitcnt lgkmcnt(0)
	v_max_f32_e32 v6, v6, v6
	v_max_f32_e32 v2, v2, v5
	v_max_f32_e32 v0, v0, v6
	ds_bpermute_b32 v5, v7, v2
	ds_bpermute_b32 v6, v7, v0
	v_cndmask_b32_e32 v7, v3, v9, vcc
	v_cmp_lt_i32_e32 vcc, v10, v4
	v_lshlrev_b32_e32 v4, 2, v7
	s_waitcnt lgkmcnt(1)
	v_max_f32_e32 v5, v5, v5
	s_waitcnt lgkmcnt(0)
	v_max_f32_e32 v6, v6, v6
	v_max_f32_e32 v2, v2, v5
	v_max_f32_e32 v0, v0, v6
	ds_bpermute_b32 v5, v8, v2
	ds_bpermute_b32 v6, v8, v0
	v_cndmask_b32_e32 v3, v3, v10, vcc
	v_lshlrev_b32_e32 v3, 2, v3
	s_waitcnt lgkmcnt(1)
	v_max_f32_e32 v5, v5, v5
	s_waitcnt lgkmcnt(0)
	v_max_f32_e32 v6, v6, v6
	v_max_f32_e32 v2, v2, v5
	v_max_f32_e32 v0, v0, v6
	ds_bpermute_b32 v5, v4, v2
	ds_bpermute_b32 v4, v4, v0
	s_waitcnt lgkmcnt(1)
	v_max_f32_e32 v5, v5, v5
	s_waitcnt lgkmcnt(0)
	v_max_f32_e32 v4, v4, v4
	v_max_f32_e32 v2, v2, v5
	v_max_f32_e32 v0, v0, v4
	ds_bpermute_b32 v4, v3, v2
	ds_bpermute_b32 v3, v3, v0
	s_waitcnt lgkmcnt(1)
	v_max_f32_e32 v4, v4, v4
	s_waitcnt lgkmcnt(0)
	v_max_f32_e32 v3, v3, v3
	v_max_f32_e32 v2, v2, v4
	v_max_f32_e32 v0, v0, v3
	v_mul_f32_e32 v2, 0x413e3475, v2
	v_mul_f32_e32 v0, v0, v2
	v_cmp_ge_f32_e32 vcc, s0, v0
	s_nop 1
	v_cndmask_b32_e64 v0, 0, 1, vcc
	s_nop 0
	v_readfirstlane_b32 s0, v0
	s_bitcmp1_b32 s0, 0
	s_cselect_b64 s[0:1], -1, 0
	s_lshl_b32 s93, s93, 3
	s_lshl_b32 s4, s5, 4
	s_andn2_b32 s92, s92, 63
	s_xor_b64 s[36:37], s[0:1], -1
	s_and_b32 s94, s4, 48
	s_and_b32 s95, s93, 0x1fffffe0
	s_cmp_lg_u32 0, -1
	s_cselect_b32 s0, 0, 0
	s_lshl_b32 s1, s92, 2
	s_lshl_b32 s4, s73, 2
	s_lshl_b32 s5, s5, 12
	s_lshr_b32 s6, s6, 2
	s_add_i32 s96, s3, s0
	s_add_i32 s78, s1, 0
	s_add_i32 s0, s4, 0
	s_add_i32 s7, s5, 0
	s_and_b32 s12, s6, 0x3fffffc0
	s_and_b32 s1, s6, 0x3ffffff0
	s_add_i32 s79, s96, 0x6000
	s_add_i32 s78, s78, 0x12000
	s_add_i32 s6, s0, 0x1a800
	s_add_i32 s7, s7, 0x12800
	v_writelane_b32 v254, s1, 7
	s_add_u32 s0, s8, s1
	v_writelane_b32 v254, s0, 8
	s_addc_u32 s0, s9, 0
	v_writelane_b32 v254, s0, 9
	v_writelane_b32 v254, s12, 10
	s_add_u32 s0, s8, s12
	s_nop 0
	v_writelane_b32 v254, s13, 11
	v_writelane_b32 v254, s0, 12
	s_addc_u32 s0, s9, 0
	v_writelane_b32 v254, s0, 13
	s_add_i32 s0, 0, 0x1ac00
	v_writelane_b32 v254, s0, 14
	s_branch .LBB0_970
; __device__ __forceinline__ int crow(int r,int hi){return (r&3)+8*(r>>2)+4*hi;}
; template<int THRL,bool FIXED> __device__ __forceinline__ void attn_unit(int qb,const bf16*Q,const bf16*__restrict__ Kh,const bf16*__restrict__ Vh,bf16*O,const int*__restrict__ cid,char*shm,const int wid){
;     ...
;   float rli[16];
;   #pragma unroll
;   for(int r=0;r<16;++r)rli[r]=__builtin_amdgcn_rcpf(wsf[32+crow(r,hi)]);
;   bf16*Ow=O+(long)(q0+wid*QBLK)*DM;
;   { bf16*stg=(bf16*)(shm+LDS_OST)+wid*2048;
;     #pragma unroll
;     for(int e=0;e<2;++e){
;       #pragma unroll
;       for(int r=0;r<16;++r){const int orow=crow(r,hi);
;         #pragma unroll
;         for(int d0=0;d0<2;++d0)stg[orow*64+d0*32+r32]=__float2bfloat16(o[2*e+d0][r]*rli[r]);}
;       asm volatile("s_waitcnt lgkmcnt(0)":::"memory");
.LBB0_967:
	s_or_b64 exec, exec, s[0:1]
	s_waitcnt lgkmcnt(0)
	v_add_u32_e32 v0, s78, v67
	ds_read_b128 v[66:69], v0 offset:128
	ds_read_b128 v[70:73], v0 offset:160
	s_lshl_b64 s[0:1], s[48:49], 1
	s_add_u32 s0, s33, s0
	s_addc_u32 s1, s83, s1
	s_waitcnt lgkmcnt(1)
	v_rcp_f32_e32 v74, v66
	v_rcp_f32_e32 v75, v67
	v_rcp_f32_e32 v76, v68
	v_rcp_f32_e32 v77, v69
	ds_read_b128 v[66:69], v0 offset:192
	s_waitcnt lgkmcnt(1)
	v_rcp_f32_e32 v78, v70
	v_rcp_f32_e32 v79, v71
	v_rcp_f32_e32 v80, v72
	v_rcp_f32_e32 v81, v73
	ds_read_b128 v[70:73], v0 offset:224
	s_waitcnt lgkmcnt(1)
	v_rcp_f32_e32 v82, v66
	v_lshlrev_b32_e32 v0, 9, v234
	v_lshlrev_b32_e32 v66, 1, v233
	v_mul_f32_e32 v34, v34, v74
	v_add3_u32 v84, s7, v0, v66
	v_cvt_pk_bf16_f32 v34, v34, s0
	ds_write_b16 v84, v34
	v_mul_f32_e32 v34, v50, v74
	v_cvt_pk_bf16_f32 v34, v34, s0
	ds_write_b16 v84, v34 offset:64
	v_mul_f32_e32 v34, v35, v75
	v_cvt_pk_bf16_f32 v34, v34, s0
	ds_write_b16 v84, v34 offset:128
	v_mul_f32_e32 v34, v51, v75
	v_cvt_pk_bf16_f32 v34, v34, s0
	ds_write_b16 v84, v34 offset:192
	v_mul_f32_e32 v34, v36, v76
	v_cvt_pk_bf16_f32 v34, v34, s0
	ds_write_b16 v84, v34 offset:256
	v_mul_f32_e32 v34, v52, v76
	v_cvt_pk_bf16_f32 v34, v34, s0
	ds_write_b16 v84, v34 offset:320
	v_mul_f32_e32 v34, v37, v77
	v_cvt_pk_bf16_f32 v34, v34, s0
	ds_write_b16 v84, v34 offset:384
	v_mul_f32_e32 v34, v53, v77
	v_cvt_pk_bf16_f32 v34, v34, s0
	ds_write_b16 v84, v34 offset:448
	v_mul_f32_e32 v34, v38, v78
	v_cvt_pk_bf16_f32 v34, v34, s0
	ds_write_b16 v84, v34 offset:1024
	v_mul_f32_e32 v34, v54, v78
	v_cvt_pk_bf16_f32 v34, v34, s0
	ds_write_b16 v84, v34 offset:1088
	v_mul_f32_e32 v34, v39, v79
	v_cvt_pk_bf16_f32 v34, v34, s0
	ds_write_b16 v84, v34 offset:1152
	v_mul_f32_e32 v34, v55, v79
	v_cvt_pk_bf16_f32 v34, v34, s0
	ds_write_b16 v84, v34 offset:1216
	v_mul_f32_e32 v34, v40, v80
	v_cvt_pk_bf16_f32 v34, v34, s0
	ds_write_b16 v84, v34 offset:1280
	v_mul_f32_e32 v34, v56, v80
	v_cvt_pk_bf16_f32 v34, v34, s0
	ds_write_b16 v84, v34 offset:1344
	v_mul_f32_e32 v34, v41, v81
	v_cvt_pk_bf16_f32 v34, v34, s0
	ds_write_b16 v84, v34 offset:1408
	v_mul_f32_e32 v34, v57, v81
	v_cvt_pk_bf16_f32 v34, v34, s0
	v_rcp_f32_e32 v83, v67
	ds_write_b16 v84, v34 offset:1472
	v_mul_f32_e32 v34, v42, v82
	v_cvt_pk_bf16_f32 v34, v34, s0
	ds_write_b16 v84, v34 offset:2048
	v_mul_f32_e32 v34, v58, v82
	v_cvt_pk_bf16_f32 v34, v34, s0
	v_rcp_f32_e32 v68, v68
	ds_write_b16 v84, v34 offset:2112
	v_mul_f32_e32 v34, v43, v83
	v_cvt_pk_bf16_f32 v34, v34, s0
	ds_write_b16 v84, v34 offset:2176
	v_mul_f32_e32 v34, v59, v83
	v_cvt_pk_bf16_f32 v34, v34, s0
	v_rcp_f32_e32 v69, v69
	ds_write_b16 v84, v34 offset:2240
	v_mul_f32_e32 v34, v44, v68
	v_cvt_pk_bf16_f32 v34, v34, s0
	ds_write_b16 v84, v34 offset:2304
	v_mul_f32_e32 v34, v60, v68
	v_cvt_pk_bf16_f32 v34, v34, s0
	s_waitcnt lgkmcnt(14)
	v_rcp_f32_e32 v70, v70
	ds_write_b16 v84, v34 offset:2368
	v_mul_f32_e32 v34, v45, v69
	v_cvt_pk_bf16_f32 v34, v34, s0
	ds_write_b16 v84, v34 offset:2432
	v_mul_f32_e32 v34, v61, v69
	v_cvt_pk_bf16_f32 v34, v34, s0
	v_rcp_f32_e32 v71, v71
	ds_write_b16 v84, v34 offset:2496
	v_mul_f32_e32 v34, v46, v70
	v_cvt_pk_bf16_f32 v34, v34, s0
	ds_write_b16 v84, v34 offset:3072
	v_mul_f32_e32 v34, v62, v70
	v_cvt_pk_bf16_f32 v34, v34, s0
	v_rcp_f32_e32 v72, v72
	ds_write_b16 v84, v34 offset:3136
	v_mul_f32_e32 v34, v47, v71
	v_cvt_pk_bf16_f32 v34, v34, s0
	ds_write_b16 v84, v34 offset:3200
	v_mul_f32_e32 v34, v63, v71
	v_cvt_pk_bf16_f32 v34, v34, s0
	v_rcp_f32_e32 v73, v73
	ds_write_b16 v84, v34 offset:3264
	v_mul_f32_e32 v34, v48, v72
	v_cvt_pk_bf16_f32 v34, v34, s0
	ds_write_b16 v84, v34 offset:3328
	v_mul_f32_e32 v34, v64, v72
	v_cvt_pk_bf16_f32 v34, v34, s0
	ds_write_b16 v84, v34 offset:3392
	v_mul_f32_e32 v34, v49, v73
	v_cvt_pk_bf16_f32 v34, v34, s0
	v_lshlrev_b32_e32 v0, 1, v223
	ds_write_b16 v84, v34 offset:3456
	v_mul_f32_e32 v34, v65, v73
	v_and_b32_e32 v0, 0x70, v0
	v_cvt_pk_bf16_f32 v34, v34, s0
	v_ashrrev_i32_e32 v66, 3, v222
	v_add_u32_e32 v85, s7, v0
	ds_write_b16 v84, v34 offset:3520
	v_lshl_add_u32 v86, v66, 7, v85
	s_waitcnt lgkmcnt(0)
	ds_read_b128 v[34:37], v86
	v_ashrrev_i32_e32 v67, 31, v66
	v_lshl_add_u64 v[38:39], s[0:1], 0, v[0:1]
	v_lshlrev_b64 v[40:41], 11, v[66:67]
	v_lshl_add_u64 v[40:41], v[38:39], 0, v[40:41]
	v_add_u32_e32 v42, 8, v66
	s_waitcnt lgkmcnt(0)
; template<int THRL,bool FIXED> __device__ __forceinline__ void attn_unit(int qb,const bf16*Q,const bf16*__restrict__ Kh,const bf16*__restrict__ Vh,bf16*O,const int*__restrict__ cid,char*shm,const int wid){
;     ...
;       asm volatile("s_waitcnt lgkmcnt(0)":::"memory");
;       #pragma unroll
;       for(int i=0;i<4;++i){const int row=i*8+(lane>>3),ch=lane&7; const u32x4 v=*(const u32x4*)(stg+row*64+ch*8); ATTN_STORE16(Ow+(long)row*DM+e*64+ch*8,v);}
;       asm volatile("s_waitcnt lgkmcnt(0)":::"memory"); } }
;   asm volatile("s_waitcnt lgkmcnt(0)\n\ts_barrier":::"memory");
	global_store_dwordx4 v[40:41], v[34:37], off
	v_lshl_add_u32 v0, v42, 7, v85
	ds_read_b128 v[34:37], v0
	v_ashrrev_i32_e32 v43, 31, v42
	v_lshlrev_b64 v[42:43], 11, v[42:43]
	v_lshl_add_u64 v[42:43], v[38:39], 0, v[42:43]
	v_add_u32_e32 v44, 16, v66
	s_waitcnt lgkmcnt(0)
	global_store_dwordx4 v[42:43], v[34:37], off
	v_lshl_add_u32 v48, v44, 7, v85
	ds_read_b128 v[34:37], v48
	v_ashrrev_i32_e32 v45, 31, v44
	v_lshlrev_b64 v[44:45], 11, v[44:45]
	v_lshl_add_u64 v[44:45], v[38:39], 0, v[44:45]
	v_add_u32_e32 v46, 24, v66
	s_waitcnt lgkmcnt(0)
	global_store_dwordx4 v[44:45], v[34:37], off
	v_lshl_add_u32 v49, v46, 7, v85
	ds_read_b128 v[34:37], v49
	v_ashrrev_i32_e32 v47, 31, v46
	v_lshlrev_b64 v[46:47], 11, v[46:47]
	v_lshl_add_u64 v[38:39], v[38:39], 0, v[46:47]
	v_mul_f32_e32 v2, v2, v74
	s_waitcnt lgkmcnt(0)
	global_store_dwordx4 v[38:39], v[34:37], off
	v_cvt_pk_bf16_f32 v2, v2, s0
	s_waitcnt lgkmcnt(0)
	ds_write_b16 v84, v2
	v_mul_f32_e32 v2, v18, v74
	v_cvt_pk_bf16_f32 v2, v2, s0
	ds_write_b16 v84, v2 offset:64
	v_mul_f32_e32 v2, v3, v75
	v_cvt_pk_bf16_f32 v2, v2, s0
	ds_write_b16 v84, v2 offset:128
	v_mul_f32_e32 v2, v19, v75
	v_cvt_pk_bf16_f32 v2, v2, s0
	ds_write_b16 v84, v2 offset:192
	v_mul_f32_e32 v2, v4, v76
	v_cvt_pk_bf16_f32 v2, v2, s0
	ds_write_b16 v84, v2 offset:256
	v_mul_f32_e32 v2, v20, v76
	v_cvt_pk_bf16_f32 v2, v2, s0
	ds_write_b16 v84, v2 offset:320
	v_mul_f32_e32 v2, v5, v77
	v_cvt_pk_bf16_f32 v2, v2, s0
	ds_write_b16 v84, v2 offset:384
	v_mul_f32_e32 v2, v21, v77
	v_cvt_pk_bf16_f32 v2, v2, s0
	ds_write_b16 v84, v2 offset:448
	v_mul_f32_e32 v2, v6, v78
	v_cvt_pk_bf16_f32 v2, v2, s0
	ds_write_b16 v84, v2 offset:1024
	v_mul_f32_e32 v2, v22, v78
	v_cvt_pk_bf16_f32 v2, v2, s0
	ds_write_b16 v84, v2 offset:1088
	v_mul_f32_e32 v2, v7, v79
	v_cvt_pk_bf16_f32 v2, v2, s0
	ds_write_b16 v84, v2 offset:1152
	v_mul_f32_e32 v2, v23, v79
	v_cvt_pk_bf16_f32 v2, v2, s0
	ds_write_b16 v84, v2 offset:1216
	v_mul_f32_e32 v2, v8, v80
	v_cvt_pk_bf16_f32 v2, v2, s0
	ds_write_b16 v84, v2 offset:1280
	v_mul_f32_e32 v2, v24, v80
	v_cvt_pk_bf16_f32 v2, v2, s0
	ds_write_b16 v84, v2 offset:1344
	v_mul_f32_e32 v2, v9, v81
	v_cvt_pk_bf16_f32 v2, v2, s0
	ds_write_b16 v84, v2 offset:1408
	v_mul_f32_e32 v2, v25, v81
	v_cvt_pk_bf16_f32 v2, v2, s0
	ds_write_b16 v84, v2 offset:1472
	v_mul_f32_e32 v2, v10, v82
	v_cvt_pk_bf16_f32 v2, v2, s0
	ds_write_b16 v84, v2 offset:2048
	v_mul_f32_e32 v2, v26, v82
	v_cvt_pk_bf16_f32 v2, v2, s0
	ds_write_b16 v84, v2 offset:2112
	v_mul_f32_e32 v2, v11, v83
	v_cvt_pk_bf16_f32 v2, v2, s0
	ds_write_b16 v84, v2 offset:2176
	v_mul_f32_e32 v2, v27, v83
	v_cvt_pk_bf16_f32 v2, v2, s0
	ds_write_b16 v84, v2 offset:2240
	v_mul_f32_e32 v2, v12, v68
	v_cvt_pk_bf16_f32 v2, v2, s0
	ds_write_b16 v84, v2 offset:2304
	v_mul_f32_e32 v2, v28, v68
	v_cvt_pk_bf16_f32 v2, v2, s0
	ds_write_b16 v84, v2 offset:2368
	v_mul_f32_e32 v2, v13, v69
	v_cvt_pk_bf16_f32 v2, v2, s0
	ds_write_b16 v84, v2 offset:2432
	v_mul_f32_e32 v2, v29, v69
	v_cvt_pk_bf16_f32 v2, v2, s0
	ds_write_b16 v84, v2 offset:2496
	v_mul_f32_e32 v2, v14, v70
	v_cvt_pk_bf16_f32 v2, v2, s0
	ds_write_b16 v84, v2 offset:3072
	v_mul_f32_e32 v2, v30, v70
	v_cvt_pk_bf16_f32 v2, v2, s0
	ds_write_b16 v84, v2 offset:3136
	v_mul_f32_e32 v2, v15, v71
	v_cvt_pk_bf16_f32 v2, v2, s0
	ds_write_b16 v84, v2 offset:3200
	v_mul_f32_e32 v2, v31, v71
	v_cvt_pk_bf16_f32 v2, v2, s0
	ds_write_b16 v84, v2 offset:3264
	v_mul_f32_e32 v2, v16, v72
	v_cvt_pk_bf16_f32 v2, v2, s0
	ds_write_b16 v84, v2 offset:3328
	v_mul_f32_e32 v2, v32, v72
	v_cvt_pk_bf16_f32 v2, v2, s0
	ds_write_b16 v84, v2 offset:3392
	v_mul_f32_e32 v2, v17, v73
	v_cvt_pk_bf16_f32 v2, v2, s0
	ds_write_b16 v84, v2 offset:3456
	v_mul_f32_e32 v2, v33, v73
	v_cvt_pk_bf16_f32 v2, v2, s0
	ds_write_b16 v84, v2 offset:3520
	s_waitcnt lgkmcnt(0)
	ds_read_b128 v[2:5], v86
	s_waitcnt lgkmcnt(0)
	global_store_dwordx4 v[40:41], v[2:5], off offset:128
	ds_read_b128 v[2:5], v0
	s_waitcnt lgkmcnt(0)
	global_store_dwordx4 v[42:43], v[2:5], off offset:128
	ds_read_b128 v[2:5], v48
	s_waitcnt lgkmcnt(0)
	global_store_dwordx4 v[44:45], v[2:5], off offset:128
	ds_read_b128 v[2:5], v49
	s_waitcnt lgkmcnt(0)
	global_store_dwordx4 v[38:39], v[2:5], off offset:128
	s_waitcnt lgkmcnt(0)
	s_waitcnt lgkmcnt(0)
	s_barrier

; __device__ __forceinline__ int lane_asm() { int l; asm volatile("v_mbcnt_lo_u32_b32 %0, -1, 0\n\tv_mbcnt_hi_u32_b32 %0, -1, %0" : "=v"(l)); return l; }
;     __host__ __device__ bool next(int i, Unit& u) const { const long L = (long)i * G + c; if (L >= nun) return false; u.pz = (int)L / nM; u.pm = (int)L % nM; u.pn = 0; return true; }
;   __device__ __forceinline__ bool next(int i,AttnUnit&u)const{ const int v=vcu+(i>>2)*G; if(v>=256)return false; const int s=v&15,k=i&3; u.bh=v>>4; u.qb=(k&1)?(32*(k>>1)+31-s):(32*(k>>1)+s); return true; }
; template<int THRL,bool FIXED> __device__ __forceinline__ void attn_unit(int qb,const bf16*Q,const bf16*__restrict__ Kh,const bf16*__restrict__ Vh,bf16*O,const int*__restrict__ cid,char*shm,const int wid){
;   const int lane=lane_asm(),tid=wid*64+lane,r32=lane&31,hi=lane>>5;
;   const int q0=qb*QB;
;   const bf16*Qw=Q+(long)(q0+wid*QBLK)*DM;
;   { __attribute__((address_space(3))) int* cw=(__attribute__((address_space(3))) int*)((__attribute__((address_space(3))) char*)shm+LDS_CID); if(tid<256)cw[tid]=cid[q0+tid]; }
;     ...
;   for(int i=0;S.next(i,u);++i){ const int h=u.bh>>1,c=u.bh&1;
;     if(fixed) attn_unit<THRL,true>(u.qb,T.Q+u.bh*64,T.K+u.bh*64,T.V+h*128,T.O+(long)c*SEQ*DM+h*128,T.cid,lds,wid);
.LBB0_973:
	s_lshl_b32 s0, s20, 6
	s_ashr_i32 s1, s0, 31
	s_lshl_b64 s[52:53], s[0:1], 1
	s_add_u32 s4, s82, s52
	s_addc_u32 s5, s85, s53
	s_add_u32 s60, s86, s52
	s_addc_u32 s61, s87, s53
	s_and_b32 s54, s0, 0xffffff80
	s_ashr_i32 s55, s54, 31
	s_lshl_b64 s[50:51], s[54:55], 1
	s_add_u32 s58, s88, s50
	s_addc_u32 s59, s89, s51
	s_lshl_b32 s0, s20, 25
	s_and_b32 s0, s0, 0x2000000
	s_add_u32 s0, s90, s0
	s_addc_u32 s1, s91, 0
	s_add_u32 s33, s0, s50
	s_addc_u32 s83, s1, s51
	s_lshl_b32 s12, s21, 8
	s_add_i32 s0, s12, s73
	s_ashr_i32 s1, s0, 31
	s_lshl_b64 s[48:49], s[0:1], 10
	s_lshl_b64 s[0:1], s[0:1], 11
	s_add_u32 s56, s4, s0
	s_addc_u32 s57, s5, s1
	s_mov_b64 s[0:1], -1
	s_and_b64 vcc, exec, s[36:37]
	s_cbranch_vccz .LBB0_1055
	v_mbcnt_lo_u32_b32 v220, -1, 0
	v_mbcnt_hi_u32_b32 v220, -1, v220
	s_movk_i32 s0, 0x100
	v_add_u32_e32 v0, s92, v220
	v_cmp_gt_i32_e32 vcc, s0, v0
	s_and_saveexec_b64 s[0:1], vcc
	s_cbranch_execz .LBB0_976
	v_add_u32_e32 v2, s12, v0
	v_readlane_b32 s4, v254, 5
	v_ashrrev_i32_e32 v3, 31, v2
	v_readlane_b32 s5, v254, 6
	v_lshl_add_u32 v0, v0, 2, 0
	v_add_u32_e32 v0, 0x1a800, v0
	v_lshl_add_u64 v[2:3], v[2:3], 2, s[4:5]
	global_load_dword v2, v[2:3], off
	s_waitcnt vmcnt(0) lgkmcnt(0)
	ds_write_b32 v0, v2
; #define WAIT_BAR(N) asm volatile("s_waitcnt vmcnt(" #N ") lgkmcnt(0)\n\ts_barrier":::"memory")
;   #define DMA_K(t,slot) glds16(ksrc+(long)(t)*KVBLK*DM,(unsigned)__builtin_amdgcn_readfirstlane(kdst+(slot)))
;   #define DMA_V(t,slot) do{ glds16(vsrc+(long)(t)*KVBLK*DM,(unsigned)__builtin_amdgcn_readfirstlane(vdst+2*(slot))); glds16(vsrc+64+(long)(t)*KVBLK*DM,(unsigned)__builtin_amdgcn_readfirstlane(vdst+2*(slot)+8192)); }while(0)
;   #define CMASK(P0,P1,t) do{int jb_=(t)-(NT-4); if(jb_>=0)cmask(P0,P1,cidl+64*jb_,qc,hi);}while(0)
;   #define CMASK(P0,P1,t) do{}while(0)
;   #define CMASK(P0,P1,t) do{int jb_=(t)-(NT-4); if(jb_>=0)cmask(P0,P1,cidl+64*jb_,qc,hi);}while(0)
; __device__ __forceinline__ void cmask(f32x16&p0,f32x16&p1,lds_iptr ck,int qc,int hi){
;   const float NEG=-INFINITY;
;   #pragma unroll
;   for(int r=0;r<16;++r){int kv=4*hi+(r&3)+8*(r>>2); if(ck[kv]>qc)p0[r]=NEG; if(ck[kv+32]>qc)p1[r]=NEG;}
; }
; template<int THRL,bool FIXED> __device__ __forceinline__ void attn_unit(int qb,const bf16*Q,const bf16*__restrict__ Kh,const bf16*__restrict__ Vh,bf16*O,const int*__restrict__ cid,char*shm,const int wid){
;     ...
;   const int vb0=(int)(lds0+LDS_V)+((lane>>4)&1)*32+(lane&3)*8+(4*hi+((lane&15)>>2))*64;
;   const char*Kbase=shm+LDS_K; bf16x8 kf[8];
;   const lds_cptr shm3=(lds_cptr)shm; const lds_cptr kp0=shm3+LDS_K+hi*1024+r32*16; const lds_cptr vp0=shm3+LDS_V+((lane>>4)&1)*32+(lane&3)*8+(4*hi+((lane&15)>>2))*64;
;   const int NT=(q0+QB)/KVBLK;
;   DMA_K(0,0);DMA_V(0,0);DMA_K(1,SLOTB);
;   bf16x8 qr[4];
;   #pragma unroll
;   for(int d0=0;d0<4;++d0)qr[d0]=*reinterpret_cast<const bf16x8*>(&Qw[(long)r32*DM+d0*16+hi*8]);
;   float mhat=0.f,l_reg=0.f;f32x16 o[4];o[0]=f32x16{};o[1]=f32x16{};o[2]=f32x16{};o[3]=f32x16{};
;   const int qrel=wid*QBLK+r32;
;     ...
;   bool resc=false;
;     ...
;   f32x16 pA0,pA1,pB0,pB1;
;   int sl_prev=0,sl_cur=0,sl_next=SLOTB;
;     ...
;   DMA_K(2,2*SLOTB);
;   WAIT_BAR(4);
;   const int qc=cidl[qrel];
;   qkt(pA0,pA1,Kbase,qr,r32,hi);asm volatile("s_nop 15\n\ts_nop 7":"+v"(pA0),"+v"(pA1));CMASK(pA0,pA1,0);
.LBB0_976:
	s_or_b64 exec, exec, s[0:1]
	v_ashrrev_i32_e32 v221, 31, v220
	v_lshlrev_b64 v[212:213], 11, v[220:221]
	v_lshl_add_u64 v[2:3], s[60:61], 0, v[212:213]
	s_lshl_b32 s10, s93, 1
	v_ashrrev_i32_e32 v0, 2, v220
	v_lshl_add_u64 v[34:35], v[2:3], 0, s[10:11]
	v_add_u32_e32 v2, s94, v0
	v_ashrrev_i32_e32 v3, 31, v2
	v_lshlrev_b64 v[214:215], 11, v[2:3]
	v_lshlrev_b32_e32 v221, 3, v220
	v_lshl_add_u64 v[2:3], s[58:59], 0, v[214:215]
	s_lshl_b32 s10, s95, 1
	v_and_b32_e32 v230, 24, v221
	v_lshl_add_u64 v[2:3], v[2:3], 0, s[10:11]
	v_lshlrev_b32_e32 v0, 1, v230
	s_add_i32 s0, s12, 0x100
	s_mov_b32 s1, m0
	s_mov_b32 m0, s96
	s_nop 0
	global_load_lds_dwordx4 v[34:35], off
	s_mov_b32 m0, s1
	v_lshl_add_u64 v[36:37], v[2:3], 0, v[0:1]
	s_mov_b32 s1, m0
	s_mov_b32 m0, s79
	s_nop 0
	global_load_lds_dwordx4 v[36:37], off
	s_mov_b32 m0, s1
	s_cmp_lg_u32 0, -1
	s_cselect_b32 s1, 0, 0
	v_lshl_add_u64 v[2:3], v[36:37], 0, s[64:65]
	s_add_i32 s1, s1, s3
	v_ashrrev_i32_e32 v229, 5, v220
	s_add_i32 s4, s1, 0x8000
	s_mov_b32 s5, m0
	s_mov_b32 m0, s4
	s_nop 0
	global_load_lds_dwordx4 v[2:3], off
	s_mov_b32 m0, s5
	v_lshl_add_u64 v[2:3], v[34:35], 0, s[14:15]
	s_add_i32 s4, s1, 0x2000
	s_mov_b32 s5, m0
	s_mov_b32 m0, s4
	s_nop 0
	global_load_lds_dwordx4 v[2:3], off
	s_mov_b32 m0, s5
	v_lshlrev_b32_e32 v2, 3, v229
	v_and_b32_e32 v228, 31, v220
	v_ashrrev_i32_e32 v3, 31, v2
	v_lshl_add_u64 v[2:3], v[2:3], 1, s[56:57]
	v_lshlrev_b32_e32 v0, 11, v228
	v_lshl_add_u64 v[2:3], v[2:3], 0, v[0:1]
	global_load_dwordx4 v[172:175], v[2:3], off
	global_load_dwordx4 v[164:167], v[2:3], off offset:32
	global_load_dwordx4 v[156:159], v[2:3], off offset:64
	global_load_dwordx4 v[144:147], v[2:3], off offset:96
	v_lshlrev_b32_e32 v0, 10, v229
	v_lshlrev_b32_e32 v2, 4, v228
	v_add3_u32 v237, 0, v0, v2
	v_lshl_add_u64 v[2:3], v[34:35], 0, s[16:17]
	s_addk_i32 s1, 0x4000
	s_mov_b32 s4, m0
	s_mov_b32 m0, s1
	s_nop 0
	global_load_lds_dwordx4 v[2:3], off
	s_mov_b32 m0, s4
	s_waitcnt vmcnt(4) lgkmcnt(0)
	s_barrier
	ds_read_b128 v[2:5], v237
	v_lshl_add_u32 v0, v228, 2, s6
	ds_read_b32 v236, v0
	s_ashr_i32 s13, s0, 6
	s_cmp_gt_i32 s13, 4
	s_waitcnt vmcnt(0) lgkmcnt(0)
	v_mfma_f32_32x32x16_bf16 v[18:33], v[2:5], v[172:175], 0
	ds_read_b128 v[2:5], v237 offset:512
	ds_read_b128 v[38:41], v237 offset:2048
	s_waitcnt lgkmcnt(0)
	v_mfma_f32_32x32x16_bf16 v[18:33], v[38:41], v[164:167], v[18:33]
	ds_read_b128 v[38:41], v237 offset:2560
	v_mfma_f32_32x32x16_bf16 v[2:17], v[2:5], v[172:175], 0
	s_waitcnt lgkmcnt(0)
	v_mfma_f32_32x32x16_bf16 v[2:17], v[38:41], v[164:167], v[2:17]
	ds_read_b128 v[38:41], v237 offset:4096
	s_waitcnt lgkmcnt(0)
	v_mfma_f32_32x32x16_bf16 v[18:33], v[38:41], v[156:159], v[18:33]
	ds_read_b128 v[38:41], v237 offset:4608
	s_waitcnt lgkmcnt(0)
	v_mfma_f32_32x32x16_bf16 v[2:17], v[38:41], v[156:159], v[2:17]
	ds_read_b128 v[38:41], v237 offset:6144
	s_waitcnt lgkmcnt(0)
	v_mfma_f32_32x32x16_bf16 v[18:33], v[38:41], v[144:147], v[18:33]
	ds_read_b128 v[38:41], v237 offset:6656
	s_waitcnt lgkmcnt(0)
	v_mfma_f32_32x32x16_bf16 v[2:17], v[38:41], v[144:147], v[2:17]
	s_nop 15
	s_nop 7
	s_cbranch_scc1 .LBB0_978
	s_lshl_b32 s0, s12, 2
	s_sub_i32 s0, 0, s0
	v_lshl_add_u32 v0, v229, 4, s0
	v_add_u32_e32 v0, 0x1a800, v0
	ds_read_b128 v[38:41], v0
	ds_read_b128 v[42:45], v0 offset:128
	ds_read_b128 v[46:49], v0 offset:32
	ds_read_b128 v[50:53], v0 offset:160
	s_waitcnt lgkmcnt(3)
	v_cmp_le_i32_e32 vcc, v38, v236
	s_nop 1
	v_cndmask_b32_e32 v18, v232, v18, vcc
	s_waitcnt lgkmcnt(2)
	v_cmp_le_i32_e32 vcc, v42, v236
	s_nop 1
	v_cndmask_b32_e32 v2, v232, v2, vcc
	v_cmp_le_i32_e32 vcc, v39, v236
	s_nop 1
	v_cndmask_b32_e32 v19, v232, v19, vcc
	v_cmp_le_i32_e32 vcc, v43, v236
	s_nop 1
	v_cndmask_b32_e32 v3, v232, v3, vcc
	v_cmp_le_i32_e32 vcc, v40, v236
	s_nop 1
	v_cndmask_b32_e32 v20, v232, v20, vcc
	v_cmp_le_i32_e32 vcc, v44, v236
	s_nop 1
	v_cndmask_b32_e32 v4, v232, v4, vcc
	v_cmp_le_i32_e32 vcc, v41, v236
	ds_read_b128 v[38:41], v0 offset:64
	s_nop 0
	v_cndmask_b32_e32 v21, v232, v21, vcc
	v_cmp_le_i32_e32 vcc, v45, v236
	s_nop 1
	v_cndmask_b32_e32 v5, v232, v5, vcc
	s_waitcnt lgkmcnt(2)
	v_cmp_le_i32_e32 vcc, v46, v236
	s_nop 1
	v_cndmask_b32_e32 v22, v232, v22, vcc
	s_waitcnt lgkmcnt(1)
	v_cmp_le_i32_e32 vcc, v50, v236
	s_nop 1
	v_cndmask_b32_e32 v6, v232, v6, vcc
	v_cmp_le_i32_e32 vcc, v47, v236
	s_nop 1
	v_cndmask_b32_e32 v23, v232, v23, vcc
	v_cmp_le_i32_e32 vcc, v51, v236
	s_nop 1
	v_cndmask_b32_e32 v7, v232, v7, vcc
	v_cmp_le_i32_e32 vcc, v48, v236
	s_nop 1
	v_cndmask_b32_e32 v24, v232, v24, vcc
	v_cmp_le_i32_e32 vcc, v52, v236
	s_nop 1
	v_cndmask_b32_e32 v8, v232, v8, vcc
	v_cmp_le_i32_e32 vcc, v49, v236
	ds_read_b128 v[42:45], v0 offset:192
	ds_read_b128 v[46:49], v0 offset:96
	v_cndmask_b32_e32 v25, v232, v25, vcc
	v_cmp_le_i32_e32 vcc, v53, v236
	ds_read_b128 v[50:53], v0 offset:224
	s_nop 0
	v_cndmask_b32_e32 v9, v232, v9, vcc
	s_waitcnt lgkmcnt(3)
	v_cmp_le_i32_e32 vcc, v38, v236
	s_nop 1
	v_cndmask_b32_e32 v26, v232, v26, vcc
	s_waitcnt lgkmcnt(2)
	v_cmp_le_i32_e32 vcc, v42, v236
	s_nop 1
	v_cndmask_b32_e32 v10, v232, v10, vcc
	v_cmp_le_i32_e32 vcc, v39, v236
	s_nop 1
	v_cndmask_b32_e32 v27, v232, v27, vcc
	v_cmp_le_i32_e32 vcc, v43, v236
	s_nop 1
	v_cndmask_b32_e32 v11, v232, v11, vcc
	v_cmp_le_i32_e32 vcc, v40, v236
	s_nop 1
	v_cndmask_b32_e32 v28, v232, v28, vcc
	v_cmp_le_i32_e32 vcc, v44, v236
	s_nop 1
	v_cndmask_b32_e32 v12, v232, v12, vcc
	v_cmp_le_i32_e32 vcc, v41, v236
	s_nop 1
	v_cndmask_b32_e32 v29, v232, v29, vcc
	v_cmp_le_i32_e32 vcc, v45, v236
	s_nop 1
	v_cndmask_b32_e32 v13, v232, v13, vcc
	s_waitcnt lgkmcnt(1)
	v_cmp_le_i32_e32 vcc, v46, v236
	s_nop 1
	v_cndmask_b32_e32 v30, v232, v30, vcc
	s_waitcnt lgkmcnt(0)
	v_cmp_le_i32_e32 vcc, v50, v236
	s_nop 1
	v_cndmask_b32_e32 v14, v232, v14, vcc
	v_cmp_le_i32_e32 vcc, v47, v236
	s_nop 1
	v_cndmask_b32_e32 v31, v232, v31, vcc
	v_cmp_le_i32_e32 vcc, v51, v236
	s_nop 1
	v_cndmask_b32_e32 v15, v232, v15, vcc
	v_cmp_le_i32_e32 vcc, v48, v236
	s_nop 1
	v_cndmask_b32_e32 v32, v232, v32, vcc
	v_cmp_le_i32_e32 vcc, v52, v236
	s_nop 1
	v_cndmask_b32_e32 v16, v232, v16, vcc
	v_cmp_le_i32_e32 vcc, v49, v236
	s_nop 1
	v_cndmask_b32_e32 v33, v232, v33, vcc
	v_cmp_le_i32_e32 vcc, v53, v236
	s_nop 1
	v_cndmask_b32_e32 v17, v232, v17, vcc

; __device__ __forceinline__ int crow(int r,int hi){return (r&3)+8*(r>>2)+4*hi;}
; #define SBAR() __builtin_amdgcn_sched_barrier(0)
;   #define PKW(P,B) cvtpk_s(P[B],P[B+1])
; template<int THRL,bool FIXED> __device__ __forceinline__ void attn_unit(int qb,const bf16*Q,const bf16*__restrict__ Kh,const bf16*__restrict__ Vh,bf16*O,const int*__restrict__ cid,char*shm,const int wid){
;     ...
;   { float sacc=pB0[0]+pB0[1]; _Pragma("unroll") for(int r=2;r<16;++r)sacc+=pB0[r]; _Pragma("unroll") for(int r=0;r<16;++r)sacc+=pB1[r]; l_reg+=sacc;
;     pw0=(u32x4){PKW(pB0,0),PKW(pB0,2),PKW(pB0,4),PKW(pB0,6)};pw1=(u32x4){PKW(pB0,8),PKW(pB0,10),PKW(pB0,12),PKW(pB0,14)};pw2=(u32x4){PKW(pB1,0),PKW(pB1,2),PKW(pB1,4),PKW(pB1,6)};pw3=(u32x4){PKW(pB1,8),PKW(pB1,10),PKW(pB1,12),PKW(pB1,14)};
;     SBAR(); pv(o,vb0+2*sl_cur,PAF(0),PAF(1),PAF(2),PAF(3)); pv(o+2,vb0+2*sl_cur+8192,PAF(0),PAF(1),PAF(2),PAF(3)); }
;     ...
;   {auto rr=__builtin_amdgcn_permlane32_swap(__float_as_uint(l_reg),__float_as_uint(l_reg),false,false);l_reg=__uint_as_float(rr[0])+__uint_as_float(rr[1]);}
;   if(hi==0)wsf[32+r32]=l_reg;asm volatile("s_waitcnt lgkmcnt(0)":::"memory");
;   float rli[16];
;   #pragma unroll
;   for(int r=0;r<16;++r)rli[r]=__builtin_amdgcn_rcpf(wsf[32+crow(r,hi)]);
;   bf16*Ow=O+(long)(q0+wid*QBLK)*DM;
;   { bf16*stg=(bf16*)(shm+LDS_OST)+wid*2048;
;     #pragma unroll
;     for(int e=0;e<2;++e){
;       #pragma unroll
;       for(int r=0;r<16;++r){const int orow=crow(r,hi);
;         #pragma unroll
;         for(int d0=0;d0<2;++d0)stg[orow*64+d0*32+r32]=__float2bfloat16(o[2*e+d0][r]*rli[r]);}
.LBB0_1052:
	v_add_f32_e32 v4, v96, v97
	v_add_f32_e32 v4, v98, v4
	v_add_f32_e32 v4, v99, v4
	v_add_f32_e32 v4, v100, v4
	v_add_f32_e32 v4, v101, v4
	v_add_f32_e32 v4, v102, v4
	v_add_f32_e32 v4, v103, v4
	v_add_f32_e32 v4, v104, v4
	v_add_f32_e32 v4, v105, v4
	v_add_f32_e32 v4, v106, v4
	v_add_f32_e32 v4, v107, v4
	v_add_f32_e32 v4, v108, v4
	v_add_f32_e32 v4, v109, v4
	v_add_f32_e32 v4, v110, v4
	v_add_f32_e32 v4, v111, v4
	v_add_f32_e32 v4, v4, v80
	v_add_f32_e32 v4, v81, v4
	v_add_f32_e32 v4, v82, v4
	v_add_f32_e32 v4, v83, v4
	v_add_f32_e32 v4, v84, v4
	v_add_f32_e32 v4, v85, v4
	v_add_f32_e32 v4, v86, v4
	v_add_f32_e32 v4, v87, v4
	v_add_f32_e32 v4, v88, v4
	v_add_f32_e32 v4, v89, v4
	v_add_f32_e32 v4, v90, v4
	v_add_f32_e32 v4, v91, v4
	v_add_f32_e32 v4, v92, v4
	s_cmp_lg_u32 0, -1
	v_add_f32_e32 v4, v93, v4
	s_cselect_b32 s0, 0, 0
	v_add_f32_e32 v4, v94, v4
	s_addk_i32 s0, 0x6000
	v_add_f32_e32 v4, v95, v4
	v_add3_u32 v3, v233, s0, v230
	v_add_f32_e32 v0, v0, v4
	v_cvt_pk_bf16_f32 v4, v96, v97
	v_cvt_pk_bf16_f32 v5, v98, v99
	v_cvt_pk_bf16_f32 v6, v100, v101
	v_cvt_pk_bf16_f32 v7, v102, v103
	v_cvt_pk_bf16_f32 v8, v104, v105
	v_cvt_pk_bf16_f32 v9, v106, v107
	v_cvt_pk_bf16_f32 v10, v108, v109
	v_cvt_pk_bf16_f32 v11, v110, v111
	v_cvt_pk_bf16_f32 v12, v80, v81
	v_cvt_pk_bf16_f32 v13, v82, v83
	v_cvt_pk_bf16_f32 v14, v84, v85
	v_cvt_pk_bf16_f32 v15, v86, v87
	v_cvt_pk_bf16_f32 v80, v88, v89
	v_cvt_pk_bf16_f32 v81, v90, v91
	v_cvt_pk_bf16_f32 v82, v92, v93
	v_cvt_pk_bf16_f32 v83, v94, v95
	s_lshl_b32 s0, s18, 1
	v_add3_u32 v3, v3, v231, s0
	ds_read_b64_tr_b16 v[84:85],v3 offset:0
	ds_read_b64_tr_b16 v[86:87],v3 offset:512
	ds_read_b64_tr_b16 v[88:89],v3 offset:1024
	ds_read_b64_tr_b16 v[90:91],v3 offset:1536
	ds_read_b64_tr_b16 v[92:93],v3 offset:2048
	ds_read_b64_tr_b16 v[94:95],v3 offset:2560
	ds_read_b64_tr_b16 v[96:97],v3 offset:3072
	ds_read_b64_tr_b16 v[98:99],v3 offset:3584
	s_waitcnt lgkmcnt(0)
	s_nop 0
	v_mfma_f32_32x32x16_bf16 v[64:79], v[4:7], v[84:87], v[64:79]
	ds_read_b64_tr_b16 v[84:85],v3 offset:4096
	ds_read_b64_tr_b16 v[86:87],v3 offset:4608
	v_mfma_f32_32x32x16_bf16 v[64:79], v[8:11], v[88:91], v[64:79]
	ds_read_b64_tr_b16 v[88:89],v3 offset:5120
	ds_read_b64_tr_b16 v[90:91],v3 offset:5632
	v_mfma_f32_32x32x16_bf16 v[64:79], v[12:15], v[92:95], v[64:79]
	ds_read_b64_tr_b16 v[92:93],v3 offset:6144
	ds_read_b64_tr_b16 v[94:95],v3 offset:6656
	ds_read_b64_tr_b16 v[100:101],v3 offset:7168
	ds_read_b64_tr_b16 v[102:103],v3 offset:7680
	s_waitcnt lgkmcnt(0)
	v_mfma_f32_32x32x16_bf16 v[64:79], v[80:83], v[96:99], v[64:79]
	v_mfma_f32_32x32x16_bf16 v[48:63], v[4:7], v[84:87], v[48:63]
	v_add_u32_e32 v3, 0x2000, v3
	ds_read_b64_tr_b16 v[84:85],v3 offset:0
	ds_read_b64_tr_b16 v[86:87],v3 offset:512
	v_mfma_f32_32x32x16_bf16 v[48:63], v[8:11], v[88:91], v[48:63]
	ds_read_b64_tr_b16 v[88:89],v3 offset:1024
	ds_read_b64_tr_b16 v[90:91],v3 offset:1536
	v_mfma_f32_32x32x16_bf16 v[48:63], v[12:15], v[92:95], v[48:63]
	ds_read_b64_tr_b16 v[92:93],v3 offset:2048
	ds_read_b64_tr_b16 v[94:95],v3 offset:2560
	ds_read_b64_tr_b16 v[96:97],v3 offset:3072
	ds_read_b64_tr_b16 v[98:99],v3 offset:3584
	s_waitcnt lgkmcnt(0)
	v_mfma_f32_32x32x16_bf16 v[48:63], v[80:83], v[100:103], v[48:63]
	v_mfma_f32_32x32x16_bf16 v[32:47], v[4:7], v[84:87], v[32:47]
	ds_read_b64_tr_b16 v[84:85],v3 offset:4096
	ds_read_b64_tr_b16 v[86:87],v3 offset:4608
	v_mfma_f32_32x32x16_bf16 v[32:47], v[8:11], v[88:91], v[32:47]
	ds_read_b64_tr_b16 v[88:89],v3 offset:5120
	ds_read_b64_tr_b16 v[90:91],v3 offset:5632
	v_mfma_f32_32x32x16_bf16 v[32:47], v[12:15], v[92:95], v[32:47]
	ds_read_b64_tr_b16 v[92:93],v3 offset:6144
	ds_read_b64_tr_b16 v[94:95],v3 offset:6656
	ds_read_b64_tr_b16 v[100:101],v3 offset:7168
	ds_read_b64_tr_b16 v[102:103],v3 offset:7680
	s_waitcnt lgkmcnt(0)
	v_mfma_f32_32x32x16_bf16 v[32:47], v[80:83], v[96:99], v[32:47]
	v_mfma_f32_32x32x16_bf16 v[16:31], v[4:7], v[84:87], v[16:31]
	v_mov_b32_e32 v3, v0
	s_nop 1
	v_permlane32_swap_b32_e32 v0, v3
	v_cmp_gt_u32_e32 vcc, 32, v220
	v_mfma_f32_32x32x16_bf16 v[16:31], v[8:11], v[88:91], v[16:31]
	v_mfma_f32_32x32x16_bf16 v[16:31], v[12:15], v[92:95], v[16:31]
	v_mfma_f32_32x32x16_bf16 v[16:31], v[80:83], v[100:103], v[16:31]
	s_and_saveexec_b64 s[0:1], vcc
	v_lshl_add_u32 v4, v220, 2, s78
	v_add_f32_e32 v0, v0, v3
	ds_write_b32 v4, v0 offset:128
	s_or_b64 exec, exec, s[0:1]
	s_waitcnt lgkmcnt(0)
	ds_read_b128 v[4:7], v2 offset:128
	ds_read_b128 v[8:11], v2 offset:160
	s_lshl_b64 s[0:1], s[48:49], 1
	v_lshlrev_b32_e32 v0, 9, v229
	s_add_u32 s0, s33, s0
	s_waitcnt lgkmcnt(1)
	v_rcp_f32_e32 v80, v4
	v_rcp_f32_e32 v81, v5
	v_rcp_f32_e32 v82, v6
	v_rcp_f32_e32 v83, v7
	s_waitcnt lgkmcnt(0)
	v_rcp_f32_e32 v84, v8
	ds_read_b128 v[4:7], v2 offset:192
	v_rcp_f32_e32 v85, v9
	v_rcp_f32_e32 v86, v10
	v_rcp_f32_e32 v87, v11
	ds_read_b128 v[8:11], v2 offset:224
	v_lshlrev_b32_e32 v2, 1, v228
	v_add3_u32 v96, s7, v0, v2
	v_mul_f32_e32 v2, v64, v80
	v_cvt_pk_bf16_f32 v2, v2, s0
	ds_write_b16 v96, v2
	v_mul_f32_e32 v2, v48, v80
	v_cvt_pk_bf16_f32 v2, v2, s0
	ds_write_b16 v96, v2 offset:64
	v_mul_f32_e32 v2, v65, v81
	v_cvt_pk_bf16_f32 v2, v2, s0
	ds_write_b16 v96, v2 offset:128
	v_mul_f32_e32 v2, v49, v81
	v_cvt_pk_bf16_f32 v2, v2, s0
	ds_write_b16 v96, v2 offset:192
	v_mul_f32_e32 v2, v66, v82
	v_cvt_pk_bf16_f32 v2, v2, s0
	ds_write_b16 v96, v2 offset:256
	v_mul_f32_e32 v2, v50, v82
	v_cvt_pk_bf16_f32 v2, v2, s0
	ds_write_b16 v96, v2 offset:320
	v_mul_f32_e32 v2, v67, v83
	v_cvt_pk_bf16_f32 v2, v2, s0
	ds_write_b16 v96, v2 offset:384
	v_mul_f32_e32 v2, v51, v83
	v_cvt_pk_bf16_f32 v2, v2, s0
	ds_write_b16 v96, v2 offset:448
	v_mul_f32_e32 v2, v68, v84
	v_cvt_pk_bf16_f32 v2, v2, s0
	ds_write_b16 v96, v2 offset:1024
	v_mul_f32_e32 v2, v52, v84
	v_cvt_pk_bf16_f32 v2, v2, s0
	ds_write_b16 v96, v2 offset:1088
	v_mul_f32_e32 v2, v69, v85
	v_cvt_pk_bf16_f32 v2, v2, s0
	ds_write_b16 v96, v2 offset:1152
	v_mul_f32_e32 v2, v53, v85
	v_cvt_pk_bf16_f32 v2, v2, s0
	ds_write_b16 v96, v2 offset:1216
	v_mul_f32_e32 v2, v70, v86
	v_cvt_pk_bf16_f32 v2, v2, s0
	ds_write_b16 v96, v2 offset:1280
	v_mul_f32_e32 v2, v54, v86
	v_cvt_pk_bf16_f32 v2, v2, s0
	s_waitcnt lgkmcnt(14)
; __device__ __forceinline__ int crow(int r,int hi){return (r&3)+8*(r>>2)+4*hi;}
; template<int THRL,bool FIXED> __device__ __forceinline__ void attn_unit(int qb,const bf16*Q,const bf16*__restrict__ Kh,const bf16*__restrict__ Vh,bf16*O,const int*__restrict__ cid,char*shm,const int wid){
;     ...
;   { bf16*stg=(bf16*)(shm+LDS_OST)+wid*2048;
;     #pragma unroll
;     for(int e=0;e<2;++e){
;       #pragma unroll
;       for(int r=0;r<16;++r){const int orow=crow(r,hi);
;         #pragma unroll
;         for(int d0=0;d0<2;++d0)stg[orow*64+d0*32+r32]=__float2bfloat16(o[2*e+d0][r]*rli[r]);}
;       asm volatile("s_waitcnt lgkmcnt(0)":::"memory");
;       #pragma unroll
;       for(int i=0;i<4;++i){const int row=i*8+(lane>>3),ch=lane&7; const u32x4 v=*(const u32x4*)(stg+row*64+ch*8); ATTN_STORE16(Ow+(long)row*DM+e*64+ch*8,v);}
;       asm volatile("s_waitcnt lgkmcnt(0)":::"memory"); } }
;   asm volatile("s_waitcnt lgkmcnt(0)\n\ts_barrier":::"memory");
	v_rcp_f32_e32 v88, v4
	ds_write_b16 v96, v2 offset:1344
	v_mul_f32_e32 v2, v71, v87
	v_cvt_pk_bf16_f32 v2, v2, s0
	ds_write_b16 v96, v2 offset:1408
	v_mul_f32_e32 v2, v55, v87
	v_cvt_pk_bf16_f32 v2, v2, s0
	v_rcp_f32_e32 v89, v5
	ds_write_b16 v96, v2 offset:1472
	v_mul_f32_e32 v2, v72, v88
	v_cvt_pk_bf16_f32 v2, v2, s0
	ds_write_b16 v96, v2 offset:2048
	v_mul_f32_e32 v2, v56, v88
	v_cvt_pk_bf16_f32 v2, v2, s0
	v_rcp_f32_e32 v90, v6
	ds_write_b16 v96, v2 offset:2112
	v_mul_f32_e32 v2, v73, v89
	v_cvt_pk_bf16_f32 v2, v2, s0
	ds_write_b16 v96, v2 offset:2176
	v_mul_f32_e32 v2, v57, v89
	v_cvt_pk_bf16_f32 v2, v2, s0
	v_rcp_f32_e32 v91, v7
	ds_write_b16 v96, v2 offset:2240
	v_mul_f32_e32 v2, v74, v90
	v_cvt_pk_bf16_f32 v2, v2, s0
	ds_write_b16 v96, v2 offset:2304
	v_mul_f32_e32 v2, v58, v90
	v_cvt_pk_bf16_f32 v2, v2, s0
	s_waitcnt lgkmcnt(14)
	v_rcp_f32_e32 v92, v8
	ds_write_b16 v96, v2 offset:2368
	v_mul_f32_e32 v2, v75, v91
	v_cvt_pk_bf16_f32 v2, v2, s0
	ds_write_b16 v96, v2 offset:2432
	v_mul_f32_e32 v2, v59, v91
	v_cvt_pk_bf16_f32 v2, v2, s0
	v_rcp_f32_e32 v93, v9
	ds_write_b16 v96, v2 offset:2496
	v_mul_f32_e32 v2, v76, v92
	v_cvt_pk_bf16_f32 v2, v2, s0
	ds_write_b16 v96, v2 offset:3072
	v_mul_f32_e32 v2, v60, v92
	v_cvt_pk_bf16_f32 v2, v2, s0
	v_rcp_f32_e32 v94, v10
	ds_write_b16 v96, v2 offset:3136
	v_mul_f32_e32 v2, v77, v93
	v_cvt_pk_bf16_f32 v2, v2, s0
	ds_write_b16 v96, v2 offset:3200
	v_mul_f32_e32 v2, v61, v93
	v_cvt_pk_bf16_f32 v2, v2, s0
	v_rcp_f32_e32 v95, v11
	ds_write_b16 v96, v2 offset:3264
	v_mul_f32_e32 v2, v78, v94
	v_cvt_pk_bf16_f32 v2, v2, s0
	ds_write_b16 v96, v2 offset:3328
	v_mul_f32_e32 v2, v62, v94
	v_cvt_pk_bf16_f32 v2, v2, s0
	ds_write_b16 v96, v2 offset:3392
	v_mul_f32_e32 v2, v79, v95
	v_cvt_pk_bf16_f32 v2, v2, s0
	v_lshlrev_b32_e32 v0, 1, v221
	ds_write_b16 v96, v2 offset:3456
	v_mul_f32_e32 v2, v63, v95
	v_and_b32_e32 v0, 0x70, v0
	v_cvt_pk_bf16_f32 v2, v2, s0
	v_ashrrev_i32_e32 v6, 3, v220
	v_add_u32_e32 v97, s7, v0
	ds_write_b16 v96, v2 offset:3520
	v_lshl_add_u32 v98, v6, 7, v97
	s_waitcnt lgkmcnt(0)
	ds_read_b128 v[2:5], v98
	s_addc_u32 s1, s83, s1
	v_ashrrev_i32_e32 v7, 31, v6
	v_lshl_add_u64 v[8:9], s[0:1], 0, v[0:1]
	v_lshlrev_b64 v[10:11], 11, v[6:7]
	v_lshl_add_u64 v[10:11], v[8:9], 0, v[10:11]
	v_add_u32_e32 v12, 8, v6
	s_waitcnt lgkmcnt(0)
	global_store_dwordx4 v[10:11], v[2:5], off
	v_lshl_add_u32 v0, v12, 7, v97
	ds_read_b128 v[2:5], v0
	v_ashrrev_i32_e32 v13, 31, v12
	v_lshlrev_b64 v[12:13], 11, v[12:13]
	v_lshl_add_u64 v[12:13], v[8:9], 0, v[12:13]
	v_add_u32_e32 v14, 16, v6
	s_waitcnt lgkmcnt(0)
	global_store_dwordx4 v[12:13], v[2:5], off
	v_lshl_add_u32 v48, v14, 7, v97
	ds_read_b128 v[2:5], v48
	v_ashrrev_i32_e32 v15, 31, v14
	v_lshlrev_b64 v[14:15], 11, v[14:15]
	v_lshl_add_u64 v[14:15], v[8:9], 0, v[14:15]
	v_add_u32_e32 v6, 24, v6
	s_waitcnt lgkmcnt(0)
	global_store_dwordx4 v[14:15], v[2:5], off
	v_lshl_add_u32 v49, v6, 7, v97
	ds_read_b128 v[2:5], v49
	v_ashrrev_i32_e32 v7, 31, v6
	v_lshlrev_b64 v[6:7], 11, v[6:7]
	v_lshl_add_u64 v[6:7], v[8:9], 0, v[6:7]
	s_waitcnt lgkmcnt(0)
	global_store_dwordx4 v[6:7], v[2:5], off
	s_waitcnt lgkmcnt(0)
	s_nop 1
	v_mul_f32_e32 v2, v32, v80
	v_cvt_pk_bf16_f32 v2, v2, s0
	ds_write_b16 v96, v2
	v_mul_f32_e32 v2, v16, v80
	v_cvt_pk_bf16_f32 v2, v2, s0
	ds_write_b16 v96, v2 offset:64
	v_mul_f32_e32 v2, v33, v81
	v_cvt_pk_bf16_f32 v2, v2, s0
	ds_write_b16 v96, v2 offset:128
	v_mul_f32_e32 v2, v17, v81
	v_cvt_pk_bf16_f32 v2, v2, s0
	ds_write_b16 v96, v2 offset:192
	v_mul_f32_e32 v2, v34, v82
	v_cvt_pk_bf16_f32 v2, v2, s0
	ds_write_b16 v96, v2 offset:256
	v_mul_f32_e32 v2, v18, v82
	v_cvt_pk_bf16_f32 v2, v2, s0
	ds_write_b16 v96, v2 offset:320
	v_mul_f32_e32 v2, v35, v83
	v_cvt_pk_bf16_f32 v2, v2, s0
	ds_write_b16 v96, v2 offset:384
	v_mul_f32_e32 v2, v19, v83
	v_cvt_pk_bf16_f32 v2, v2, s0
	ds_write_b16 v96, v2 offset:448
	v_mul_f32_e32 v2, v36, v84
	v_cvt_pk_bf16_f32 v2, v2, s0
	ds_write_b16 v96, v2 offset:1024
	v_mul_f32_e32 v2, v20, v84
	v_cvt_pk_bf16_f32 v2, v2, s0
	ds_write_b16 v96, v2 offset:1088
	v_mul_f32_e32 v2, v37, v85
	v_cvt_pk_bf16_f32 v2, v2, s0
	ds_write_b16 v96, v2 offset:1152
	v_mul_f32_e32 v2, v21, v85
	v_cvt_pk_bf16_f32 v2, v2, s0
	ds_write_b16 v96, v2 offset:1216
	v_mul_f32_e32 v2, v38, v86
	v_cvt_pk_bf16_f32 v2, v2, s0
	ds_write_b16 v96, v2 offset:1280
	v_mul_f32_e32 v2, v22, v86
	v_cvt_pk_bf16_f32 v2, v2, s0
	ds_write_b16 v96, v2 offset:1344
	v_mul_f32_e32 v2, v39, v87
	v_cvt_pk_bf16_f32 v2, v2, s0
	ds_write_b16 v96, v2 offset:1408
	v_mul_f32_e32 v2, v23, v87
	v_cvt_pk_bf16_f32 v2, v2, s0
	ds_write_b16 v96, v2 offset:1472
	v_mul_f32_e32 v2, v40, v88
	v_cvt_pk_bf16_f32 v2, v2, s0
	ds_write_b16 v96, v2 offset:2048
	v_mul_f32_e32 v2, v24, v88
	v_cvt_pk_bf16_f32 v2, v2, s0
	ds_write_b16 v96, v2 offset:2112
	v_mul_f32_e32 v2, v41, v89
	v_cvt_pk_bf16_f32 v2, v2, s0
	ds_write_b16 v96, v2 offset:2176
	v_mul_f32_e32 v2, v25, v89
	v_cvt_pk_bf16_f32 v2, v2, s0
	ds_write_b16 v96, v2 offset:2240
	v_mul_f32_e32 v2, v42, v90
	v_cvt_pk_bf16_f32 v2, v2, s0
	ds_write_b16 v96, v2 offset:2304
	v_mul_f32_e32 v2, v26, v90
	v_cvt_pk_bf16_f32 v2, v2, s0
	ds_write_b16 v96, v2 offset:2368
	v_mul_f32_e32 v2, v43, v91
	v_cvt_pk_bf16_f32 v2, v2, s0
	ds_write_b16 v96, v2 offset:2432
	v_mul_f32_e32 v2, v27, v91
	v_cvt_pk_bf16_f32 v2, v2, s0
	ds_write_b16 v96, v2 offset:2496
	v_mul_f32_e32 v2, v44, v92
	v_cvt_pk_bf16_f32 v2, v2, s0
	ds_write_b16 v96, v2 offset:3072
	v_mul_f32_e32 v2, v28, v92
	v_cvt_pk_bf16_f32 v2, v2, s0
	ds_write_b16 v96, v2 offset:3136
	v_mul_f32_e32 v2, v45, v93
	v_cvt_pk_bf16_f32 v2, v2, s0
	ds_write_b16 v96, v2 offset:3200
	v_mul_f32_e32 v2, v29, v93
	v_cvt_pk_bf16_f32 v2, v2, s0
	ds_write_b16 v96, v2 offset:3264
	v_mul_f32_e32 v2, v46, v94
	v_cvt_pk_bf16_f32 v2, v2, s0
	ds_write_b16 v96, v2 offset:3328
	v_mul_f32_e32 v2, v30, v94
	v_cvt_pk_bf16_f32 v2, v2, s0
	ds_write_b16 v96, v2 offset:3392
	v_mul_f32_e32 v2, v47, v95
	v_cvt_pk_bf16_f32 v2, v2, s0
	ds_write_b16 v96, v2 offset:3456
	v_mul_f32_e32 v2, v31, v95
	v_cvt_pk_bf16_f32 v2, v2, s0
	ds_write_b16 v96, v2 offset:3520
	s_waitcnt lgkmcnt(0)
	ds_read_b128 v[2:5], v98
	s_mov_b64 s[0:1], 0
	s_waitcnt lgkmcnt(0)
	global_store_dwordx4 v[10:11], v[2:5], off offset:128
	ds_read_b128 v[2:5], v0
	s_waitcnt lgkmcnt(0)
	global_store_dwordx4 v[12:13], v[2:5], off offset:128
	ds_read_b128 v[2:5], v48
	s_waitcnt lgkmcnt(0)
	global_store_dwordx4 v[14:15], v[2:5], off offset:128
	ds_read_b128 v[2:5], v49
	s_waitcnt lgkmcnt(0)
	global_store_dwordx4 v[6:7], v[2:5], off offset:128
	s_waitcnt lgkmcnt(0)
	s_waitcnt lgkmcnt(0)
	s_barrier
; __device__ __forceinline__ int lane_asm() { int l; asm volatile("v_mbcnt_lo_u32_b32 %0, -1, 0\n\tv_mbcnt_hi_u32_b32 %0, -1, %0" : "=v"(l)); return l; }
; #define WAIT_BAR(N) asm volatile("s_waitcnt vmcnt(" #N ") lgkmcnt(0)\n\ts_barrier":::"memory")
;   #define CMASK(P0,P1,t) do{}while(0)
; __device__ __forceinline__ void cmask(f32x16&p0,f32x16&p1,lds_iptr ck,int qc,int hi){
;   const float NEG=-INFINITY;
;   #pragma unroll
;   for(int r=0;r<16;++r){int kv=4*hi+(r&3)+8*(r>>2); if(ck[kv]>qc)p0[r]=NEG; if(ck[kv+32]>qc)p1[r]=NEG;}
; }
; template<int THRL,bool FIXED> __device__ __forceinline__ void attn_unit(int qb,const bf16*Q,const bf16*__restrict__ Kh,const bf16*__restrict__ Vh,bf16*O,const int*__restrict__ cid,char*shm,const int wid){
;   const int lane=lane_asm(),tid=wid*64+lane,r32=lane&31,hi=lane>>5;
;   const int q0=qb*QB;
;   const bf16*Qw=Q+(long)(q0+wid*QBLK)*DM;
;   { __attribute__((address_space(3))) int* cw=(__attribute__((address_space(3))) int*)((__attribute__((address_space(3))) char*)shm+LDS_CID); if(tid<256)cw[tid]=cid[q0+tid]; }
;   const lds_iptr cidl=(lds_iptr)((__attribute__((address_space(3))) const char*)shm+LDS_CID);
;   const unsigned lds0=(unsigned)(uintptr_t)shm;
;   float*wsf=(float*)(shm+LDS_WS)+wid*64;
;   const bf16*ksrc=Kh+(long)lane*DM+wid*8;
;   const bf16*vsrc=Vh+(long)(16*(wid&3)+(lane>>2))*DM+(wid>>2)*32+(lane&3)*8;
;   const unsigned kdst=lds0+LDS_K+wid*1024, vdst=lds0+LDS_V+wid*1024;
;     ...
;   const int vb0=(int)(lds0+LDS_V)+((lane>>4)&1)*32+(lane&3)*8+(4*hi+((lane&15)>>2))*64;
;   const char*Kbase=shm+LDS_K; bf16x8 kf[8];
;   const lds_cptr shm3=(lds_cptr)shm; const lds_cptr kp0=shm3+LDS_K+hi*1024+r32*16; const lds_cptr vp0=shm3+LDS_V+((lane>>4)&1)*32+(lane&3)*8+(4*hi+((lane&15)>>2))*64;
;   const int NT=(q0+QB)/KVBLK;
;   DMA_K(0,0);DMA_V(0,0);DMA_K(1,SLOTB);
;   bf16x8 qr[4];
;   #pragma unroll
;   for(int d0=0;d0<4;++d0)qr[d0]=*reinterpret_cast<const bf16x8*>(&Qw[(long)r32*DM+d0*16+hi*8]);
;   float mhat=0.f,l_reg=0.f;f32x16 o[4];o[0]=f32x16{};o[1]=f32x16{};o[2]=f32x16{};o[3]=f32x16{};
;   const int qrel=wid*QBLK+r32;
;     ...
;   bool resc=false;
;     ...
;   f32x16 pA0,pA1,pB0,pB1;
;   int sl_prev=0,sl_cur=0,sl_next=SLOTB;
;     ...
;   DMA_K(2,2*SLOTB);
;   WAIT_BAR(4);
;   const int qc=cidl[qrel];
;   qkt(pA0,pA1,Kbase,qr,r32,hi);asm volatile("s_nop 15\n\ts_nop 7":"+v"(pA0),"+v"(pA1));CMASK(pA0,pA1,0);
.LBB0_1055:
	s_and_b64 vcc, exec, s[0:1]
	s_cbranch_vccz .LBB0_968
	v_mbcnt_lo_u32_b32 v222, -1, 0
	v_mbcnt_hi_u32_b32 v222, -1, v222
	s_movk_i32 s0, 0x100
	v_add_u32_e32 v0, s92, v222
	v_cmp_gt_i32_e32 vcc, s0, v0
	s_and_saveexec_b64 s[0:1], vcc
	s_cbranch_execz .LBB0_1058
	v_add_u32_e32 v2, s12, v0
	v_readlane_b32 s4, v254, 5
	v_ashrrev_i32_e32 v3, 31, v2
	v_readlane_b32 s5, v254, 6
	v_lshl_add_u32 v0, v0, 2, 0
	v_add_u32_e32 v0, 0x1a800, v0
	v_lshl_add_u64 v[2:3], v[2:3], 2, s[4:5]
	global_load_dword v2, v[2:3], off
	s_waitcnt vmcnt(0) lgkmcnt(0)
	ds_write_b32 v0, v2
.LBB0_1058:
	s_or_b64 exec, exec, s[0:1]
	v_ashrrev_i32_e32 v223, 31, v222
	v_lshlrev_b64 v[210:211], 11, v[222:223]
	v_lshl_add_u64 v[2:3], s[60:61], 0, v[210:211]
	s_lshl_b32 s10, s93, 1
	v_ashrrev_i32_e32 v0, 2, v222
	v_lshl_add_u64 v[34:35], v[2:3], 0, s[10:11]
	v_add_u32_e32 v2, s94, v0
	v_ashrrev_i32_e32 v3, 31, v2
	v_lshlrev_b64 v[212:213], 11, v[2:3]
	v_lshlrev_b32_e32 v223, 3, v222
	v_lshl_add_u64 v[2:3], s[58:59], 0, v[212:213]
	s_lshl_b32 s10, s95, 1
	v_and_b32_e32 v237, 24, v223
	v_lshl_add_u64 v[2:3], v[2:3], 0, s[10:11]
	v_lshlrev_b32_e32 v0, 1, v237
	s_add_i32 s0, s12, 0x100
	s_mov_b32 s1, m0
	s_mov_b32 m0, s96
	s_nop 0
	global_load_lds_dwordx4 v[34:35], off
	s_mov_b32 m0, s1
	v_lshl_add_u64 v[36:37], v[2:3], 0, v[0:1]
	s_mov_b32 s1, m0
	s_mov_b32 m0, s79
	s_nop 0
	global_load_lds_dwordx4 v[36:37], off
	s_mov_b32 m0, s1
	s_cmp_lg_u32 0, -1
	s_cselect_b32 s1, 0, 0
	v_lshl_add_u64 v[2:3], v[36:37], 0, s[64:65]
	s_add_i32 s1, s1, s3
	v_ashrrev_i32_e32 v234, 5, v222
	s_add_i32 s4, s1, 0x8000
	s_mov_b32 s5, m0
	s_mov_b32 m0, s4
	s_nop 0
	global_load_lds_dwordx4 v[2:3], off
	s_mov_b32 m0, s5
	v_lshl_add_u64 v[2:3], v[34:35], 0, s[14:15]
	s_add_i32 s4, s1, 0x2000
	s_mov_b32 s5, m0
	s_mov_b32 m0, s4
	s_nop 0
	global_load_lds_dwordx4 v[2:3], off
	s_mov_b32 m0, s5
	v_lshlrev_b32_e32 v2, 3, v234
	v_and_b32_e32 v233, 31, v222
	v_ashrrev_i32_e32 v3, 31, v2
	v_lshl_add_u64 v[2:3], v[2:3], 1, s[56:57]
	v_lshlrev_b32_e32 v0, 11, v233
	v_lshl_add_u64 v[2:3], v[2:3], 0, v[0:1]
	global_load_dwordx4 v[174:177], v[2:3], off
	global_load_dwordx4 v[170:173], v[2:3], off offset:32
	global_load_dwordx4 v[166:169], v[2:3], off offset:64
	global_load_dwordx4 v[154:157], v[2:3], off offset:96
	v_lshlrev_b32_e32 v0, 10, v234
	v_lshlrev_b32_e32 v2, 4, v233
	v_add3_u32 v238, 0, v0, v2
	v_lshl_add_u64 v[2:3], v[34:35], 0, s[16:17]
	s_addk_i32 s1, 0x4000
	s_mov_b32 s4, m0
	s_mov_b32 m0, s1
	s_nop 0
	global_load_lds_dwordx4 v[2:3], off
	s_mov_b32 m0, s4
	s_waitcnt vmcnt(4) lgkmcnt(0)
	s_barrier
	ds_read_b128 v[2:5], v238
	v_lshl_add_u32 v0, v233, 2, s6
	ds_read_b32 v236, v0
	s_ashr_i32 s13, s0, 6
	s_cmp_gt_i32 s13, 4
	s_waitcnt vmcnt(0) lgkmcnt(0)
	v_mfma_f32_32x32x16_bf16 v[18:33], v[2:5], v[174:177], 0
	ds_read_b128 v[2:5], v238 offset:512
	ds_read_b128 v[38:41], v238 offset:2048
	s_waitcnt lgkmcnt(0)
	v_mfma_f32_32x32x16_bf16 v[18:33], v[38:41], v[170:173], v[18:33]
	ds_read_b128 v[38:41], v238 offset:2560
	v_mfma_f32_32x32x16_bf16 v[2:17], v[2:5], v[174:177], 0
	s_waitcnt lgkmcnt(0)
	v_mfma_f32_32x32x16_bf16 v[2:17], v[38:41], v[170:173], v[2:17]
	ds_read_b128 v[38:41], v238 offset:4096
	s_waitcnt lgkmcnt(0)
	v_mfma_f32_32x32x16_bf16 v[18:33], v[38:41], v[166:169], v[18:33]
	ds_read_b128 v[38:41], v238 offset:4608
	s_waitcnt lgkmcnt(0)
	v_mfma_f32_32x32x16_bf16 v[2:17], v[38:41], v[166:169], v[2:17]
	ds_read_b128 v[38:41], v238 offset:6144
	s_waitcnt lgkmcnt(0)
	v_mfma_f32_32x32x16_bf16 v[18:33], v[38:41], v[154:157], v[18:33]
	ds_read_b128 v[38:41], v238 offset:6656
	s_waitcnt lgkmcnt(0)
	v_mfma_f32_32x32x16_bf16 v[2:17], v[38:41], v[154:157], v[2:17]
	s_nop 15
	s_nop 7
	s_cbranch_scc1 .LBB0_1060
	s_lshl_b32 s0, s12, 2
	s_sub_i32 s0, 0, s0
	v_lshl_add_u32 v0, v234, 4, s0
	v_add_u32_e32 v0, 0x1a800, v0
	ds_read_b128 v[38:41], v0
	ds_read_b128 v[42:45], v0 offset:128
	ds_read_b128 v[46:49], v0 offset:32
	ds_read_b128 v[50:53], v0 offset:160
	s_waitcnt lgkmcnt(3)
	v_cmp_le_i32_e32 vcc, v38, v236
	s_nop 1
	v_cndmask_b32_e32 v18, v232, v18, vcc
	s_waitcnt lgkmcnt(2)
	v_cmp_le_i32_e32 vcc, v42, v236
	s_nop 1
	v_cndmask_b32_e32 v2, v232, v2, vcc
	v_cmp_le_i32_e32 vcc, v39, v236
	s_nop 1
	v_cndmask_b32_e32 v19, v232, v19, vcc
	v_cmp_le_i32_e32 vcc, v43, v236
	s_nop 1
	v_cndmask_b32_e32 v3, v232, v3, vcc
	v_cmp_le_i32_e32 vcc, v40, v236
	s_nop 1
	v_cndmask_b32_e32 v20, v232, v20, vcc
	v_cmp_le_i32_e32 vcc, v44, v236
	s_nop 1
	v_cndmask_b32_e32 v4, v232, v4, vcc
	v_cmp_le_i32_e32 vcc, v41, v236
	ds_read_b128 v[38:41], v0 offset:64
	s_nop 0
	v_cndmask_b32_e32 v21, v232, v21, vcc
	v_cmp_le_i32_e32 vcc, v45, v236
	s_nop 1
	v_cndmask_b32_e32 v5, v232, v5, vcc
	s_waitcnt lgkmcnt(2)
	v_cmp_le_i32_e32 vcc, v46, v236
	s_nop 1
	v_cndmask_b32_e32 v22, v232, v22, vcc
	s_waitcnt lgkmcnt(1)
	v_cmp_le_i32_e32 vcc, v50, v236
	s_nop 1
	v_cndmask_b32_e32 v6, v232, v6, vcc
	v_cmp_le_i32_e32 vcc, v47, v236
	s_nop 1
	v_cndmask_b32_e32 v23, v232, v23, vcc
	v_cmp_le_i32_e32 vcc, v51, v236
	s_nop 1
	v_cndmask_b32_e32 v7, v232, v7, vcc
	v_cmp_le_i32_e32 vcc, v48, v236
	s_nop 1
	v_cndmask_b32_e32 v24, v232, v24, vcc
	v_cmp_le_i32_e32 vcc, v52, v236
	s_nop 1
	v_cndmask_b32_e32 v8, v232, v8, vcc
	v_cmp_le_i32_e32 vcc, v49, v236
	ds_read_b128 v[42:45], v0 offset:192
	ds_read_b128 v[46:49], v0 offset:96
	v_cndmask_b32_e32 v25, v232, v25, vcc
	v_cmp_le_i32_e32 vcc, v53, v236
	ds_read_b128 v[50:53], v0 offset:224
	s_nop 0
	v_cndmask_b32_e32 v9, v232, v9, vcc
	s_waitcnt lgkmcnt(3)
	v_cmp_le_i32_e32 vcc, v38, v236
	s_nop 1
	v_cndmask_b32_e32 v26, v232, v26, vcc
	s_waitcnt lgkmcnt(2)
	v_cmp_le_i32_e32 vcc, v42, v236
	s_nop 1
	v_cndmask_b32_e32 v10, v232, v10, vcc
	v_cmp_le_i32_e32 vcc, v39, v236
	s_nop 1
	v_cndmask_b32_e32 v27, v232, v27, vcc
	v_cmp_le_i32_e32 vcc, v43, v236
	s_nop 1
	v_cndmask_b32_e32 v11, v232, v11, vcc
	v_cmp_le_i32_e32 vcc, v40, v236
	s_nop 1
	v_cndmask_b32_e32 v28, v232, v28, vcc
	v_cmp_le_i32_e32 vcc, v44, v236
	s_nop 1
	v_cndmask_b32_e32 v12, v232, v12, vcc
	v_cmp_le_i32_e32 vcc, v41, v236
	s_nop 1
	v_cndmask_b32_e32 v29, v232, v29, vcc
	v_cmp_le_i32_e32 vcc, v45, v236
	s_nop 1
	v_cndmask_b32_e32 v13, v232, v13, vcc
	s_waitcnt lgkmcnt(1)
	v_cmp_le_i32_e32 vcc, v46, v236
	s_nop 1
	v_cndmask_b32_e32 v30, v232, v30, vcc
	s_waitcnt lgkmcnt(0)
	v_cmp_le_i32_e32 vcc, v50, v236
	s_nop 1
	v_cndmask_b32_e32 v14, v232, v14, vcc
	v_cmp_le_i32_e32 vcc, v47, v236
	s_nop 1
	v_cndmask_b32_e32 v31, v232, v31, vcc
	v_cmp_le_i32_e32 vcc, v51, v236
	s_nop 1
	v_cndmask_b32_e32 v15, v232, v15, vcc
	v_cmp_le_i32_e32 vcc, v48, v236
	s_nop 1
	v_cndmask_b32_e32 v32, v232, v32, vcc
	v_cmp_le_i32_e32 vcc, v52, v236
	s_nop 1
	v_cndmask_b32_e32 v16, v232, v16, vcc
	v_cmp_le_i32_e32 vcc, v49, v236
	s_nop 1
	v_cndmask_b32_e32 v33, v232, v33, vcc
	v_cmp_le_i32_e32 vcc, v53, v236
	s_nop 1
	v_cndmask_b32_e32 v17, v232, v17, vcc

; __device__ __forceinline__ float bf_lo(unsigned w) { return __uint_as_float(w << 16); }
; __device__ __forceinline__ float bf_hi(unsigned w) { return __uint_as_float(w & 0xffff0000u); }
; __device__ __forceinline__ float sigmoid_f(float a) { return __builtin_amdgcn_rcpf(1.0f + __builtin_amdgcn_exp2f(-1.4426950408889634f * a)); }
; __device__ __forceinline__ u32x4 pack8(const f32x4& v0, const f32x4& v1) { u32x4 w; w.x = cvt_pk_bf16(v0[0], v0[1]); w.y = cvt_pk_bf16(v0[2], v0[3]); w.z = cvt_pk_bf16(v1[0], v1[1]); w.w = cvt_pk_bf16(v1[2], v1[3]); return w; }
;     __device__ __forceinline__ void operator()(const f32x4 (&acc)[2][2][4][2], const Unit& u, int wr, int wc, int fr, int fq) const {
;         const int row0 = u.pm * BM + wr * 64 + fr, col0 = u.pn * BM + wc * 32 + 8 * fq;
; #pragma unroll
;         for (int bj = 0; bj < 2; ++bj) { const int col = col0 + bj * HALF;
;             const f32x4 b0 = *(const f32x4*)(bias + col), b1 = *(const f32x4*)(bias + col + 4);
;             u32x4 ywv[8];
; #pragma unroll
;             for (int i = 0; i < 8; ++i) ywv[i] = *(const u32x4*)(YG + (size_t)(row0 + (i >> 2) * HALF + (i & 3) * 16) * 1024 + col);
;             asm volatile("" ::: "memory");
; #pragma unroll
;             for (int ai = 0; ai < 2; ++ai)
; #pragma unroll
;                 for (int m = 0; m < 4; ++m) { const size_t off = (size_t)(row0 + ai * HALF + m * 16) * 1024 + col;
;                     const u32x4 yw = ywv[ai * 4 + m];
;                     f32x4 v0 = acc[ai][bj][m][0] + b0, v1 = acc[ai][bj][m][1] + b1;
;                     v0[0] = bf_lo(yw.x) * sigmoid_f(v0[0]); v0[1] = bf_hi(yw.x) * sigmoid_f(v0[1]); v0[2] = bf_lo(yw.y) * sigmoid_f(v0[2]); v0[3] = bf_hi(yw.y) * sigmoid_f(v0[3]);
;                     v1[0] = bf_lo(yw.z) * sigmoid_f(v1[0]); v1[1] = bf_hi(yw.z) * sigmoid_f(v1[1]); v1[2] = bf_lo(yw.w) * sigmoid_f(v1[2]); v1[3] = bf_hi(yw.w) * sigmoid_f(v1[3]);
;                     *(u32x4*)(Y2 + off) = pack8(v0, v1); }
.LBB0_1180:
	v_lshl_add_u32 v136, s59, 8, v204
	v_ashrrev_i32_e32 v137, 31, v136
	v_lshl_add_u64 v[176:177], v[136:137], 2, s[6:7]
	global_load_dwordx4 v[132:135], v[176:177], off
	global_load_dwordx4 v[128:131], v[176:177], off offset:16
	v_lshl_add_u32 v138, s36, 8, v202
	v_ashrrev_i32_e32 v139, 31, v138
	v_lshlrev_b64 v[194:195], 1, v[136:137]
	v_lshlrev_b64 v[216:217], 11, v[138:139]
	v_lshl_add_u64 v[136:137], s[8:9], 0, v[194:195]
	v_lshl_add_u64 v[178:179], v[136:137], 0, v[216:217]
	global_load_dwordx4 v[208:211], v[178:179], off
	v_or_b32_e32 v140, 16, v138
	v_ashrrev_i32_e32 v141, 31, v140
	v_lshlrev_b64 v[218:219], 11, v[140:141]
	v_lshl_add_u64 v[192:193], v[136:137], 0, v[218:219]
	global_load_dwordx4 v[212:215], v[192:193], off
	v_or_b32_e32 v142, 32, v138
	v_or_b32_e32 v144, 48, v138
	v_add_u32_e32 v146, 0x90, v138
	v_add_u32_e32 v148, 0xa0, v138
	v_add_u32_e32 v138, 0xb0, v138
	v_ashrrev_i32_e32 v143, 31, v142
	v_ashrrev_i32_e32 v145, 31, v144
	v_ashrrev_i32_e32 v147, 31, v146
	v_ashrrev_i32_e32 v149, 31, v148
	v_ashrrev_i32_e32 v139, 31, v138
	v_lshlrev_b64 v[200:201], 11, v[142:143]
	v_lshl_add_u64 v[196:197], v[216:217], 0, s[10:11]
	v_lshlrev_b64 v[198:199], 11, v[144:145]
	v_lshlrev_b64 v[140:141], 11, v[146:147]
	v_lshlrev_b64 v[142:143], 11, v[148:149]
	v_lshlrev_b64 v[138:139], 11, v[138:139]
	v_lshl_add_u64 v[180:181], v[136:137], 0, v[200:201]
	v_lshl_add_u64 v[182:183], v[136:137], 0, v[198:199]
	v_lshl_add_u64 v[184:185], v[136:137], 0, v[196:197]
	v_lshl_add_u64 v[186:187], v[136:137], 0, v[140:141]
	v_lshl_add_u64 v[188:189], v[136:137], 0, v[142:143]
	v_lshl_add_u64 v[190:191], v[136:137], 0, v[138:139]
	global_load_dwordx4 v[156:159], v[180:181], off
	global_load_dwordx4 v[152:155], v[182:183], off
	global_load_dwordx4 v[148:151], v[184:185], off
	global_load_dwordx4 v[144:147], v[186:187], off
	global_load_dwordx4 v[140:143], v[188:189], off
	global_load_dwordx4 v[136:139], v[190:191], off
	s_waitcnt vmcnt(0) lgkmcnt(0)
	v_pk_add_f32 v[124:125], v[124:125], v[132:133]
	v_pk_add_f32 v[122:123], v[122:123], v[130:131]
	v_pk_add_f32 v[120:121], v[120:121], v[128:129]
	v_pk_add_f32 v[126:127], v[126:127], v[134:135]
	v_mul_f32_e32 v124, 0xbfb8aa3b, v124
	v_mul_f32_e32 v125, 0xbfb8aa3b, v125
	v_mul_f32_e32 v120, 0xbfb8aa3b, v120
	v_mul_f32_e32 v121, 0xbfb8aa3b, v121
	v_mul_f32_e32 v122, 0xbfb8aa3b, v122
	v_mul_f32_e32 v126, 0xbfb8aa3b, v126
	v_mul_f32_e32 v127, 0xbfb8aa3b, v127
	v_mul_f32_e32 v123, 0xbfb8aa3b, v123
	v_exp_f32_e32 v124, v124
	v_exp_f32_e32 v125, v125
	v_exp_f32_e32 v120, v120
	v_exp_f32_e32 v121, v121
	v_exp_f32_e32 v122, v122
	v_exp_f32_e32 v126, v126
	v_exp_f32_e32 v127, v127
	v_exp_f32_e32 v123, v123
	v_pk_add_f32 v[116:117], v[116:117], v[132:133]
	v_add_f32_e32 v124, 1.0, v124
	v_mul_f32_e32 v116, 0xbfb8aa3b, v116
	v_add_f32_e32 v125, 1.0, v125
	v_add_f32_e32 v120, 1.0, v120
	v_add_f32_e32 v121, 1.0, v121
	v_add_f32_e32 v122, 1.0, v122
	v_pk_add_f32 v[118:119], v[118:119], v[134:135]
	v_exp_f32_e32 v116, v116
	v_mul_f32_e32 v117, 0xbfb8aa3b, v117
	v_add_f32_e32 v126, 1.0, v126
	v_add_f32_e32 v127, 1.0, v127
	v_add_f32_e32 v123, 1.0, v123
	v_rcp_f32_e32 v124, v124
	v_rcp_f32_e32 v125, v125
	v_rcp_f32_e32 v120, v120
	v_rcp_f32_e32 v121, v121
	v_rcp_f32_e32 v122, v122
	v_exp_f32_e32 v117, v117
	v_mul_f32_e32 v118, 0xbfb8aa3b, v118
	v_rcp_f32_e32 v126, v126
	v_rcp_f32_e32 v127, v127
	v_rcp_f32_e32 v123, v123
	v_pk_add_f32 v[112:113], v[112:113], v[128:129]
	v_exp_f32_e32 v118, v118
	v_mul_f32_e32 v119, 0xbfb8aa3b, v119
	v_exp_f32_e32 v119, v119
	v_mul_f32_e32 v112, 0xbfb8aa3b, v112
	v_lshlrev_b32_e32 v220, 16, v208
	v_and_b32_e32 v208, 0xffff0000, v208
	v_lshlrev_b32_e32 v222, 16, v210
	v_and_b32_e32 v210, 0xffff0000, v210
	v_lshlrev_b32_e32 v223, 16, v211
	v_pk_add_f32 v[114:115], v[114:115], v[130:131]
	v_add_f32_e32 v116, 1.0, v116
	v_exp_f32_e32 v112, v112
	v_mul_f32_e32 v113, 0xbfb8aa3b, v113
	v_lshlrev_b32_e32 v221, 16, v209
	v_and_b32_e32 v209, 0xffff0000, v209
	v_mul_f32_e32 v124, v124, v220
	v_mul_f32_e32 v125, v125, v208
	v_mul_f32_e32 v120, v120, v222
	v_mul_f32_e32 v121, v121, v210
	v_mul_f32_e32 v208, v122, v223
	v_and_b32_e32 v122, 0xffff0000, v211
	v_rcp_f32_e32 v116, v116
	v_add_f32_e32 v117, 1.0, v117
	v_exp_f32_e32 v113, v113
	v_mul_f32_e32 v114, 0xbfb8aa3b, v114
	v_mul_f32_e32 v126, v126, v221
	v_mul_f32_e32 v127, v127, v209
	v_mul_f32_e32 v209, v123, v122
	v_cvt_pk_bf16_f32 v122, v124, v125
	v_cvt_pk_bf16_f32 v123, v126, v127
	v_cvt_pk_bf16_f32 v124, v120, v121
	v_lshl_add_u64 v[120:121], s[14:15], 0, v[216:217]
	v_rcp_f32_e32 v117, v117
	v_add_f32_e32 v118, 1.0, v118
	v_exp_f32_e32 v114, v114
	v_mul_f32_e32 v115, 0xbfb8aa3b, v115
	v_lshl_add_u64 v[120:121], v[120:121], 0, v[194:195]
	v_rcp_f32_e32 v118, v118
	v_add_f32_e32 v119, 1.0, v119
	v_exp_f32_e32 v115, v115
	v_cvt_pk_bf16_f32 v125, v208, v209
	global_store_dwordx4 v[120:121], v[122:125], off
	v_rcp_f32_e32 v119, v119
	v_add_f32_e32 v112, 1.0, v112
	v_lshlrev_b32_e32 v122, 16, v212
	v_pk_add_f32 v[108:109], v[108:109], v[132:133]
	v_mul_f32_e32 v116, v116, v122
	v_and_b32_e32 v122, 0xffff0000, v212
	v_rcp_f32_e32 v112, v112
	v_add_f32_e32 v113, 1.0, v113
	v_mul_f32_e32 v108, 0xbfb8aa3b, v108
	v_mul_f32_e32 v117, v117, v122
	v_lshlrev_b32_e32 v122, 16, v213
	v_rcp_f32_e32 v113, v113
	v_add_f32_e32 v114, 1.0, v114
	v_pk_add_f32 v[110:111], v[110:111], v[134:135]
	v_exp_f32_e32 v108, v108
	v_mul_f32_e32 v109, 0xbfb8aa3b, v109
	v_mul_f32_e32 v118, v118, v122
	v_and_b32_e32 v122, 0xffff0000, v213
	v_rcp_f32_e32 v114, v114
	v_add_f32_e32 v115, 1.0, v115
	v_exp_f32_e32 v109, v109
	v_mul_f32_e32 v110, 0xbfb8aa3b, v110
; __device__ __forceinline__ float bf_lo(unsigned w) { return __uint_as_float(w << 16); }
; __device__ __forceinline__ float bf_hi(unsigned w) { return __uint_as_float(w & 0xffff0000u); }
; __device__ __forceinline__ float sigmoid_f(float a) { return __builtin_amdgcn_rcpf(1.0f + __builtin_amdgcn_exp2f(-1.4426950408889634f * a)); }
; __device__ __forceinline__ u32x4 pack8(const f32x4& v0, const f32x4& v1) { u32x4 w; w.x = cvt_pk_bf16(v0[0], v0[1]); w.y = cvt_pk_bf16(v0[2], v0[3]); w.z = cvt_pk_bf16(v1[0], v1[1]); w.w = cvt_pk_bf16(v1[2], v1[3]); return w; }
;     __device__ __forceinline__ void operator()(const f32x4 (&acc)[2][2][4][2], const Unit& u, int wr, int wc, int fr, int fq) const {
;     ...
;                 for (int m = 0; m < 4; ++m) { const size_t off = (size_t)(row0 + ai * HALF + m * 16) * 1024 + col;
;                     const u32x4 yw = ywv[ai * 4 + m];
;                     f32x4 v0 = acc[ai][bj][m][0] + b0, v1 = acc[ai][bj][m][1] + b1;
;                     v0[0] = bf_lo(yw.x) * sigmoid_f(v0[0]); v0[1] = bf_hi(yw.x) * sigmoid_f(v0[1]); v0[2] = bf_lo(yw.y) * sigmoid_f(v0[2]); v0[3] = bf_hi(yw.y) * sigmoid_f(v0[3]);
;                     v1[0] = bf_lo(yw.z) * sigmoid_f(v1[0]); v1[1] = bf_hi(yw.z) * sigmoid_f(v1[1]); v1[2] = bf_lo(yw.w) * sigmoid_f(v1[2]); v1[3] = bf_hi(yw.w) * sigmoid_f(v1[3]);
;                     *(u32x4*)(Y2 + off) = pack8(v0, v1); }
	v_mul_f32_e32 v119, v119, v122
	v_lshlrev_b32_e32 v122, 16, v214
	v_rcp_f32_e32 v115, v115
	v_pk_add_f32 v[104:105], v[104:105], v[128:129]
	v_exp_f32_e32 v110, v110
	v_mul_f32_e32 v111, 0xbfb8aa3b, v111
	v_mul_f32_e32 v112, v112, v122
	v_and_b32_e32 v122, 0xffff0000, v214
	v_exp_f32_e32 v111, v111
	v_mul_f32_e32 v104, 0xbfb8aa3b, v104
	v_mul_f32_e32 v113, v113, v122
	v_lshlrev_b32_e32 v122, 16, v215
	v_pk_add_f32 v[106:107], v[106:107], v[130:131]
	v_add_f32_e32 v108, 1.0, v108
	v_exp_f32_e32 v104, v104
	v_mul_f32_e32 v105, 0xbfb8aa3b, v105
	v_mul_f32_e32 v122, v114, v122
	v_and_b32_e32 v114, 0xffff0000, v215
	v_rcp_f32_e32 v108, v108
	v_add_f32_e32 v109, 1.0, v109
	v_exp_f32_e32 v105, v105
	v_mul_f32_e32 v106, 0xbfb8aa3b, v106
	v_mul_f32_e32 v123, v115, v114
	v_cvt_pk_bf16_f32 v114, v116, v117
	v_cvt_pk_bf16_f32 v115, v118, v119
	v_cvt_pk_bf16_f32 v116, v112, v113
	v_lshl_add_u64 v[112:113], s[14:15], 0, v[218:219]
	v_rcp_f32_e32 v109, v109
	v_add_f32_e32 v110, 1.0, v110
	v_exp_f32_e32 v106, v106
	v_mul_f32_e32 v107, 0xbfb8aa3b, v107
	v_lshl_add_u64 v[112:113], v[112:113], 0, v[194:195]
	v_rcp_f32_e32 v110, v110
	v_add_f32_e32 v111, 1.0, v111
	v_exp_f32_e32 v107, v107
	v_cvt_pk_bf16_f32 v117, v122, v123
	global_store_dwordx4 v[112:113], v[114:117], off
	v_rcp_f32_e32 v111, v111
	v_add_f32_e32 v104, 1.0, v104
	v_lshlrev_b32_e32 v114, 16, v156
	v_pk_add_f32 v[100:101], v[100:101], v[132:133]
	v_mul_f32_e32 v108, v108, v114
	v_and_b32_e32 v114, 0xffff0000, v156
	v_rcp_f32_e32 v104, v104
	v_add_f32_e32 v105, 1.0, v105
	v_mul_f32_e32 v100, 0xbfb8aa3b, v100
	v_mul_f32_e32 v109, v109, v114
	v_lshlrev_b32_e32 v114, 16, v157
	v_rcp_f32_e32 v105, v105
	v_add_f32_e32 v106, 1.0, v106
	v_pk_add_f32 v[102:103], v[102:103], v[134:135]
	v_exp_f32_e32 v100, v100
	v_mul_f32_e32 v101, 0xbfb8aa3b, v101
	v_mul_f32_e32 v110, v110, v114
	v_and_b32_e32 v114, 0xffff0000, v157
	v_rcp_f32_e32 v106, v106
	v_add_f32_e32 v107, 1.0, v107
	v_exp_f32_e32 v101, v101
	v_mul_f32_e32 v102, 0xbfb8aa3b, v102
	v_mul_f32_e32 v111, v111, v114
	v_lshlrev_b32_e32 v114, 16, v158
	v_rcp_f32_e32 v107, v107
	v_pk_add_f32 v[96:97], v[96:97], v[128:129]
	v_exp_f32_e32 v102, v102
	v_mul_f32_e32 v103, 0xbfb8aa3b, v103
	v_mul_f32_e32 v104, v104, v114
	v_and_b32_e32 v114, 0xffff0000, v158
	v_exp_f32_e32 v103, v103
	v_mul_f32_e32 v96, 0xbfb8aa3b, v96
	v_mul_f32_e32 v105, v105, v114
	v_lshlrev_b32_e32 v114, 16, v159
	v_pk_add_f32 v[98:99], v[98:99], v[130:131]
	v_add_f32_e32 v100, 1.0, v100
	v_exp_f32_e32 v96, v96
	v_mul_f32_e32 v97, 0xbfb8aa3b, v97
	v_mul_f32_e32 v114, v106, v114
	v_and_b32_e32 v106, 0xffff0000, v159
	v_rcp_f32_e32 v100, v100
	v_add_f32_e32 v101, 1.0, v101
	v_exp_f32_e32 v97, v97
	v_mul_f32_e32 v98, 0xbfb8aa3b, v98
	v_mul_f32_e32 v115, v107, v106
	v_cvt_pk_bf16_f32 v106, v108, v109
	v_cvt_pk_bf16_f32 v107, v110, v111
	v_cvt_pk_bf16_f32 v108, v104, v105
	v_lshl_add_u64 v[104:105], s[14:15], 0, v[200:201]
	v_rcp_f32_e32 v101, v101
	v_add_f32_e32 v102, 1.0, v102
	v_exp_f32_e32 v98, v98
	v_mul_f32_e32 v99, 0xbfb8aa3b, v99
	v_lshl_add_u64 v[104:105], v[104:105], 0, v[194:195]
	v_rcp_f32_e32 v102, v102
	v_add_f32_e32 v103, 1.0, v103
	v_exp_f32_e32 v99, v99
	v_cvt_pk_bf16_f32 v109, v114, v115
	global_store_dwordx4 v[104:105], v[106:109], off
	v_rcp_f32_e32 v103, v103
	v_add_f32_e32 v96, 1.0, v96
	v_lshlrev_b32_e32 v106, 16, v152
	v_pk_add_f32 v[92:93], v[92:93], v[132:133]
	v_mul_f32_e32 v100, v100, v106
	v_and_b32_e32 v106, 0xffff0000, v152
	v_rcp_f32_e32 v96, v96
	v_add_f32_e32 v97, 1.0, v97
	v_mul_f32_e32 v92, 0xbfb8aa3b, v92
	v_mul_f32_e32 v101, v101, v106
	v_lshlrev_b32_e32 v106, 16, v153
	v_rcp_f32_e32 v97, v97
	v_add_f32_e32 v98, 1.0, v98
	v_pk_add_f32 v[94:95], v[94:95], v[134:135]
	v_exp_f32_e32 v92, v92
	v_mul_f32_e32 v93, 0xbfb8aa3b, v93
	v_mul_f32_e32 v102, v102, v106
	v_and_b32_e32 v106, 0xffff0000, v153
	v_rcp_f32_e32 v98, v98
	v_add_f32_e32 v99, 1.0, v99
	v_exp_f32_e32 v93, v93
	v_mul_f32_e32 v94, 0xbfb8aa3b, v94
	v_mul_f32_e32 v103, v103, v106
	v_lshlrev_b32_e32 v106, 16, v154
	v_rcp_f32_e32 v99, v99
	v_pk_add_f32 v[88:89], v[88:89], v[128:129]
	v_exp_f32_e32 v94, v94
	v_mul_f32_e32 v95, 0xbfb8aa3b, v95
	v_mul_f32_e32 v96, v96, v106
	v_and_b32_e32 v106, 0xffff0000, v154
	v_exp_f32_e32 v95, v95
	v_mul_f32_e32 v88, 0xbfb8aa3b, v88
	v_mul_f32_e32 v97, v97, v106
	v_lshlrev_b32_e32 v106, 16, v155
	v_add_f32_e32 v92, 1.0, v92
	v_exp_f32_e32 v88, v88
	v_mul_f32_e32 v89, 0xbfb8aa3b, v89
	v_mul_f32_e32 v106, v98, v106
	v_and_b32_e32 v98, 0xffff0000, v155
	v_rcp_f32_e32 v92, v92
	v_add_f32_e32 v93, 1.0, v93
	v_exp_f32_e32 v89, v89
	v_mul_f32_e32 v107, v99, v98
	v_cvt_pk_bf16_f32 v98, v100, v101
	v_cvt_pk_bf16_f32 v99, v102, v103
	v_cvt_pk_bf16_f32 v100, v96, v97
	v_lshl_add_u64 v[96:97], s[14:15], 0, v[198:199]
	v_rcp_f32_e32 v93, v93
	v_add_f32_e32 v94, 1.0, v94
	v_lshl_add_u64 v[96:97], v[96:97], 0, v[194:195]
	v_rcp_f32_e32 v94, v94
	v_add_f32_e32 v95, 1.0, v95
	v_cvt_pk_bf16_f32 v101, v106, v107
	global_store_dwordx4 v[96:97], v[98:101], off
	v_pk_add_f32 v[90:91], v[90:91], v[130:131]
	v_rcp_f32_e32 v95, v95
	v_lshlrev_b32_e32 v98, 16, v148
	v_add_f32_e32 v88, 1.0, v88
	v_mul_f32_e32 v92, v92, v98
	v_and_b32_e32 v98, 0xffff0000, v148
	v_rcp_f32_e32 v88, v88
	v_add_f32_e32 v89, 1.0, v89
	v_mul_f32_e32 v90, 0xbfb8aa3b, v90
	v_mul_f32_e32 v93, v93, v98
	v_lshlrev_b32_e32 v98, 16, v149
	v_rcp_f32_e32 v89, v89
	v_exp_f32_e32 v90, v90
	v_mul_f32_e32 v91, 0xbfb8aa3b, v91
	v_mul_f32_e32 v94, v94, v98
	v_and_b32_e32 v98, 0xffff0000, v149
	v_exp_f32_e32 v91, v91
	v_mul_f32_e32 v95, v95, v98
	v_lshlrev_b32_e32 v98, 16, v150
	v_pk_add_f32 v[84:85], v[84:85], v[132:133]
; __device__ __forceinline__ float bf_lo(unsigned w) { return __uint_as_float(w << 16); }
; __device__ __forceinline__ float bf_hi(unsigned w) { return __uint_as_float(w & 0xffff0000u); }
; __device__ __forceinline__ float sigmoid_f(float a) { return __builtin_amdgcn_rcpf(1.0f + __builtin_amdgcn_exp2f(-1.4426950408889634f * a)); }
; __device__ __forceinline__ u32x4 pack8(const f32x4& v0, const f32x4& v1) { u32x4 w; w.x = cvt_pk_bf16(v0[0], v0[1]); w.y = cvt_pk_bf16(v0[2], v0[3]); w.z = cvt_pk_bf16(v1[0], v1[1]); w.w = cvt_pk_bf16(v1[2], v1[3]); return w; }
;     __device__ __forceinline__ void operator()(const f32x4 (&acc)[2][2][4][2], const Unit& u, int wr, int wc, int fr, int fq) const {
;     ...
;             for (int i = 0; i < 8; ++i) ywv[i] = *(const u32x4*)(YG + (size_t)(row0 + (i >> 2) * HALF + (i & 3) * 16) * 1024 + col);
;             asm volatile("" ::: "memory");
; #pragma unroll
;             for (int ai = 0; ai < 2; ++ai)
; #pragma unroll
;                 for (int m = 0; m < 4; ++m) { const size_t off = (size_t)(row0 + ai * HALF + m * 16) * 1024 + col;
;                     const u32x4 yw = ywv[ai * 4 + m];
;                     f32x4 v0 = acc[ai][bj][m][0] + b0, v1 = acc[ai][bj][m][1] + b1;
;                     v0[0] = bf_lo(yw.x) * sigmoid_f(v0[0]); v0[1] = bf_hi(yw.x) * sigmoid_f(v0[1]); v0[2] = bf_lo(yw.y) * sigmoid_f(v0[2]); v0[3] = bf_hi(yw.y) * sigmoid_f(v0[3]);
;                     v1[0] = bf_lo(yw.z) * sigmoid_f(v1[0]); v1[1] = bf_hi(yw.z) * sigmoid_f(v1[1]); v1[2] = bf_lo(yw.w) * sigmoid_f(v1[2]); v1[3] = bf_hi(yw.w) * sigmoid_f(v1[3]);
;                     *(u32x4*)(Y2 + off) = pack8(v0, v1); }
	v_mul_f32_e32 v98, v88, v98
	v_and_b32_e32 v88, 0xffff0000, v150
	v_mul_f32_e32 v84, 0xbfb8aa3b, v84
	v_mul_f32_e32 v99, v89, v88
	v_add_f32_e32 v88, 1.0, v90
	v_pk_add_f32 v[86:87], v[86:87], v[134:135]
	v_exp_f32_e32 v84, v84
	v_mul_f32_e32 v85, 0xbfb8aa3b, v85
	v_rcp_f32_e32 v88, v88
	v_add_f32_e32 v89, 1.0, v91
	v_exp_f32_e32 v85, v85
	v_mul_f32_e32 v86, 0xbfb8aa3b, v86
	v_rcp_f32_e32 v89, v89
	v_pk_add_f32 v[80:81], v[80:81], v[128:129]
	v_exp_f32_e32 v86, v86
	v_mul_f32_e32 v87, 0xbfb8aa3b, v87
	v_exp_f32_e32 v87, v87
	v_mul_f32_e32 v80, 0xbfb8aa3b, v80
	v_lshlrev_b32_e32 v90, 16, v151
	v_add_f32_e32 v84, 1.0, v84
	v_exp_f32_e32 v80, v80
	v_mul_f32_e32 v81, 0xbfb8aa3b, v81
	v_mul_f32_e32 v91, v88, v90
	v_and_b32_e32 v88, 0xffff0000, v151
	v_rcp_f32_e32 v84, v84
	v_add_f32_e32 v85, 1.0, v85
	v_exp_f32_e32 v81, v81
	v_mul_f32_e32 v100, v89, v88
	v_cvt_pk_bf16_f32 v88, v92, v93
	v_lshl_add_u64 v[92:93], s[14:15], 0, v[196:197]
	v_rcp_f32_e32 v85, v85
	v_add_f32_e32 v86, 1.0, v86
	v_cvt_pk_bf16_f32 v89, v94, v95
	v_cvt_pk_bf16_f32 v90, v98, v99
	v_lshl_add_u64 v[98:99], v[92:93], 0, v[194:195]
	v_rcp_f32_e32 v86, v86
	v_add_f32_e32 v87, 1.0, v87
	v_cvt_pk_bf16_f32 v91, v91, v100
	global_store_dwordx4 v[98:99], v[88:91], off
	v_pk_add_f32 v[82:83], v[82:83], v[130:131]
	v_rcp_f32_e32 v87, v87
	v_lshlrev_b32_e32 v88, 16, v144
	v_add_f32_e32 v80, 1.0, v80
	v_mul_f32_e32 v84, v84, v88
	v_and_b32_e32 v88, 0xffff0000, v144
	v_rcp_f32_e32 v80, v80
	v_add_f32_e32 v81, 1.0, v81
	v_mul_f32_e32 v82, 0xbfb8aa3b, v82
	v_mul_f32_e32 v85, v85, v88
	v_lshlrev_b32_e32 v88, 16, v145
	v_rcp_f32_e32 v81, v81
	v_exp_f32_e32 v82, v82
	v_mul_f32_e32 v83, 0xbfb8aa3b, v83
	v_mul_f32_e32 v86, v86, v88
	v_and_b32_e32 v88, 0xffff0000, v145
	v_exp_f32_e32 v83, v83
	v_mul_f32_e32 v87, v87, v88
	v_lshlrev_b32_e32 v88, 16, v146
	v_pk_add_f32 v[76:77], v[76:77], v[132:133]
	v_mul_f32_e32 v88, v80, v88
	v_and_b32_e32 v80, 0xffff0000, v146
	v_mul_f32_e32 v76, 0xbfb8aa3b, v76
	v_mul_f32_e32 v89, v81, v80
	v_add_f32_e32 v80, 1.0, v82
	v_pk_add_f32 v[78:79], v[78:79], v[134:135]
	v_exp_f32_e32 v76, v76
	v_mul_f32_e32 v77, 0xbfb8aa3b, v77
	v_rcp_f32_e32 v80, v80
	v_add_f32_e32 v81, 1.0, v83
	v_exp_f32_e32 v77, v77
	v_mul_f32_e32 v78, 0xbfb8aa3b, v78
	v_rcp_f32_e32 v81, v81
	v_pk_add_f32 v[72:73], v[72:73], v[128:129]
	v_exp_f32_e32 v78, v78
	v_mul_f32_e32 v79, 0xbfb8aa3b, v79
	v_exp_f32_e32 v79, v79
	v_mul_f32_e32 v72, 0xbfb8aa3b, v72
	v_lshlrev_b32_e32 v82, 16, v147
	v_add_f32_e32 v76, 1.0, v76
	v_exp_f32_e32 v72, v72
	v_mul_f32_e32 v73, 0xbfb8aa3b, v73
	v_mul_f32_e32 v83, v80, v82
	v_and_b32_e32 v80, 0xffff0000, v147
	v_rcp_f32_e32 v76, v76
	v_add_f32_e32 v77, 1.0, v77
	v_exp_f32_e32 v73, v73
	v_mul_f32_e32 v90, v81, v80
	v_cvt_pk_bf16_f32 v80, v84, v85
	v_add_co_u32_e32 v84, vcc, s56, v120
	v_rcp_f32_e32 v77, v77
	v_add_f32_e32 v78, 1.0, v78
	v_addc_co_u32_e32 v85, vcc, 0, v121, vcc
	v_rcp_f32_e32 v78, v78
	v_add_f32_e32 v79, 1.0, v79
	v_cvt_pk_bf16_f32 v81, v86, v87
	v_cvt_pk_bf16_f32 v82, v88, v89
	v_cvt_pk_bf16_f32 v83, v83, v90
	global_store_dwordx4 v[84:85], v[80:83], off
	v_pk_add_f32 v[74:75], v[74:75], v[130:131]
	v_rcp_f32_e32 v79, v79
	v_lshlrev_b32_e32 v80, 16, v140
	v_add_f32_e32 v72, 1.0, v72
	v_mul_f32_e32 v76, v76, v80
	v_and_b32_e32 v80, 0xffff0000, v140
	v_rcp_f32_e32 v72, v72
	v_add_f32_e32 v73, 1.0, v73
	v_mul_f32_e32 v74, 0xbfb8aa3b, v74
	v_mul_f32_e32 v77, v77, v80
	v_lshlrev_b32_e32 v80, 16, v141
	v_rcp_f32_e32 v73, v73
	v_exp_f32_e32 v74, v74
	v_mul_f32_e32 v75, 0xbfb8aa3b, v75
	v_mul_f32_e32 v78, v78, v80
	v_and_b32_e32 v80, 0xffff0000, v141
	v_exp_f32_e32 v75, v75
	v_mul_f32_e32 v79, v79, v80
	v_lshlrev_b32_e32 v80, 16, v142
	v_pk_add_f32 v[68:69], v[68:69], v[132:133]
	v_mul_f32_e32 v80, v72, v80
	v_and_b32_e32 v72, 0xffff0000, v142
	v_mul_f32_e32 v68, 0xbfb8aa3b, v68
	v_mul_f32_e32 v81, v73, v72
	v_add_f32_e32 v72, 1.0, v74
	v_pk_add_f32 v[70:71], v[70:71], v[134:135]
	v_exp_f32_e32 v68, v68
	v_mul_f32_e32 v69, 0xbfb8aa3b, v69
	v_rcp_f32_e32 v72, v72
	v_add_f32_e32 v73, 1.0, v75
	v_exp_f32_e32 v69, v69
	v_mul_f32_e32 v70, 0xbfb8aa3b, v70
	v_rcp_f32_e32 v73, v73
	v_pk_add_f32 v[64:65], v[64:65], v[128:129]
	v_exp_f32_e32 v70, v70
	v_mul_f32_e32 v71, 0xbfb8aa3b, v71
	v_exp_f32_e32 v71, v71
	v_mul_f32_e32 v64, 0xbfb8aa3b, v64
	v_lshlrev_b32_e32 v74, 16, v143
	v_add_f32_e32 v68, 1.0, v68
	v_exp_f32_e32 v64, v64
	v_mul_f32_e32 v65, 0xbfb8aa3b, v65
	v_mul_f32_e32 v75, v72, v74
	v_and_b32_e32 v72, 0xffff0000, v143
	v_rcp_f32_e32 v68, v68
	v_add_f32_e32 v69, 1.0, v69
	v_exp_f32_e32 v65, v65
	v_mul_f32_e32 v82, v73, v72
	v_cvt_pk_bf16_f32 v72, v76, v77
	v_add_co_u32_e32 v76, vcc, s57, v120
	v_rcp_f32_e32 v69, v69
	v_add_f32_e32 v70, 1.0, v70
	v_addc_co_u32_e32 v77, vcc, 0, v121, vcc
	v_rcp_f32_e32 v70, v70
	v_add_f32_e32 v71, 1.0, v71
	v_cvt_pk_bf16_f32 v73, v78, v79
	v_cvt_pk_bf16_f32 v74, v80, v81
	v_cvt_pk_bf16_f32 v75, v75, v82
	global_store_dwordx4 v[76:77], v[72:75], off
	v_pk_add_f32 v[66:67], v[66:67], v[130:131]
	v_rcp_f32_e32 v71, v71
	v_lshlrev_b32_e32 v72, 16, v136
	v_add_f32_e32 v64, 1.0, v64
	v_mul_f32_e32 v68, v68, v72
	v_and_b32_e32 v72, 0xffff0000, v136
	v_rcp_f32_e32 v64, v64
	v_add_f32_e32 v65, 1.0, v65
	v_mul_f32_e32 v66, 0xbfb8aa3b, v66
	v_mul_f32_e32 v69, v69, v72
	v_lshlrev_b32_e32 v72, 16, v137
	v_rcp_f32_e32 v65, v65
	v_exp_f32_e32 v66, v66
	v_mul_f32_e32 v67, 0xbfb8aa3b, v67
	v_mul_f32_e32 v70, v70, v72
	v_and_b32_e32 v72, 0xffff0000, v137
	v_exp_f32_e32 v67, v67
	v_mul_f32_e32 v71, v71, v72
	v_lshlrev_b32_e32 v72, 16, v138
	v_mul_f32_e32 v72, v64, v72
	v_and_b32_e32 v64, 0xffff0000, v138
	v_mul_f32_e32 v73, v65, v64
	v_add_f32_e32 v64, 1.0, v66
	v_rcp_f32_e32 v64, v64
	v_add_f32_e32 v65, 1.0, v67
	v_rcp_f32_e32 v65, v65
	v_lshlrev_b32_e32 v66, 16, v139
	v_mul_f32_e32 v67, v64, v66
	v_and_b32_e32 v64, 0xffff0000, v139
	v_mul_f32_e32 v74, v65, v64
	v_cvt_pk_bf16_f32 v64, v68, v69
	v_add_co_u32_e32 v68, vcc, s58, v120
	v_cvt_pk_bf16_f32 v65, v70, v71
	v_cvt_pk_bf16_f32 v66, v72, v73
	v_cvt_pk_bf16_f32 v67, v67, v74
	v_lshl_add_u64 v[106:107], v[120:121], 0, s[20:21]
	s_nop 0
	v_addc_co_u32_e32 v69, vcc, 0, v121, vcc
	global_store_dwordx4 v[68:69], v[64:67], off
	global_load_dwordx4 v[72:75], v[176:177], off offset:512
	global_load_dwordx4 v[68:71], v[176:177], off offset:528
	global_load_dwordx4 v[108:111], v[178:179], off offset:256
	global_load_dwordx4 v[114:117], v[192:193], off offset:256
	global_load_dwordx4 v[92:95], v[180:181], off offset:256
	global_load_dwordx4 v[88:91], v[182:183], off offset:256
	global_load_dwordx4 v[84:87], v[184:185], off offset:256
	global_load_dwordx4 v[80:83], v[186:187], off offset:256
	global_load_dwordx4 v[76:79], v[188:189], off offset:256
	global_load_dwordx4 v[64:67], v[190:191], off offset:256
	v_lshl_add_u64 v[102:103], v[120:121], 0, s[22:23]
	v_lshl_add_u64 v[100:101], v[120:121], 0, s[24:25]
	s_andn2_b64 vcc, exec, s[0:1]
	s_mov_b64 s[0:1], -1
	s_waitcnt vmcnt(0) lgkmcnt(0)
; __device__ __forceinline__ float bf_lo(unsigned w) { return __uint_as_float(w << 16); }
; __device__ __forceinline__ float bf_hi(unsigned w) { return __uint_as_float(w & 0xffff0000u); }
; __device__ __forceinline__ float sigmoid_f(float a) { return __builtin_amdgcn_rcpf(1.0f + __builtin_amdgcn_exp2f(-1.4426950408889634f * a)); }
; __device__ __forceinline__ u32x4 pack8(const f32x4& v0, const f32x4& v1) { u32x4 w; w.x = cvt_pk_bf16(v0[0], v0[1]); w.y = cvt_pk_bf16(v0[2], v0[3]); w.z = cvt_pk_bf16(v1[0], v1[1]); w.w = cvt_pk_bf16(v1[2], v1[3]); return w; }
;     __device__ __forceinline__ void operator()(const f32x4 (&acc)[2][2][4][2], const Unit& u, int wr, int wc, int fr, int fq) const {
;     ...
;                 for (int m = 0; m < 4; ++m) { const size_t off = (size_t)(row0 + ai * HALF + m * 16) * 1024 + col;
;                     const u32x4 yw = ywv[ai * 4 + m];
;                     f32x4 v0 = acc[ai][bj][m][0] + b0, v1 = acc[ai][bj][m][1] + b1;
;                     v0[0] = bf_lo(yw.x) * sigmoid_f(v0[0]); v0[1] = bf_hi(yw.x) * sigmoid_f(v0[1]); v0[2] = bf_lo(yw.y) * sigmoid_f(v0[2]); v0[3] = bf_hi(yw.y) * sigmoid_f(v0[3]);
;                     v1[0] = bf_lo(yw.z) * sigmoid_f(v1[0]); v1[1] = bf_hi(yw.z) * sigmoid_f(v1[1]); v1[2] = bf_lo(yw.w) * sigmoid_f(v1[2]); v1[3] = bf_hi(yw.w) * sigmoid_f(v1[3]);
;                     *(u32x4*)(Y2 + off) = pack8(v0, v1); }
	v_pk_add_f32 v[60:61], v[60:61], v[72:73]
	v_pk_add_f32 v[62:63], v[62:63], v[74:75]
	v_mul_f32_e32 v61, 0xbfb8aa3b, v61
	v_exp_f32_e32 v61, v61
	v_mul_f32_e32 v62, 0xbfb8aa3b, v62
	v_pk_add_f32 v[56:57], v[56:57], v[68:69]
	v_exp_f32_e32 v62, v62
	v_mul_f32_e32 v63, 0xbfb8aa3b, v63
	v_exp_f32_e32 v63, v63
	v_mul_f32_e32 v56, 0xbfb8aa3b, v56
	v_exp_f32_e32 v56, v56
	v_mul_f32_e32 v57, 0xbfb8aa3b, v57
	v_add_f32_e32 v61, 1.0, v61
	v_exp_f32_e32 v57, v57
	v_rcp_f32_e32 v61, v61
	v_add_f32_e32 v62, 1.0, v62
	v_rcp_f32_e32 v62, v62
	v_add_f32_e32 v63, 1.0, v63
	v_pk_add_f32 v[58:59], v[58:59], v[70:71]
	v_rcp_f32_e32 v63, v63
	v_add_f32_e32 v56, 1.0, v56
	v_lshlrev_b32_e32 v118, 16, v108
	v_and_b32_e32 v108, 0xffff0000, v108
	v_rcp_f32_e32 v56, v56
	v_add_f32_e32 v57, 1.0, v57
	v_mul_f32_e32 v58, 0xbfb8aa3b, v58
	v_mul_f32_e32 v60, 0xbfb8aa3b, v60
	v_mul_f32_e32 v61, v61, v108
	v_lshlrev_b32_e32 v108, 16, v109
	v_rcp_f32_e32 v57, v57
	v_exp_f32_e32 v58, v58
	v_mul_f32_e32 v59, 0xbfb8aa3b, v59
	v_exp_f32_e32 v60, v60
	v_mul_f32_e32 v62, v62, v108
	v_and_b32_e32 v108, 0xffff0000, v109
	v_exp_f32_e32 v59, v59
	v_pk_add_f32 v[52:53], v[52:53], v[72:73]
	v_mul_f32_e32 v63, v63, v108
	v_lshlrev_b32_e32 v108, 16, v110
	v_mul_f32_e32 v52, 0xbfb8aa3b, v52
	v_mul_f32_e32 v108, v56, v108
	v_and_b32_e32 v56, 0xffff0000, v110
	v_pk_add_f32 v[54:55], v[54:55], v[74:75]
	v_exp_f32_e32 v52, v52
	v_mul_f32_e32 v53, 0xbfb8aa3b, v53
	v_mul_f32_e32 v109, v57, v56
	v_add_f32_e32 v56, 1.0, v58
	v_exp_f32_e32 v53, v53
	v_mul_f32_e32 v54, 0xbfb8aa3b, v54
	v_add_f32_e32 v60, 1.0, v60
	v_rcp_f32_e32 v56, v56
	v_add_f32_e32 v57, 1.0, v59
	v_pk_add_f32 v[48:49], v[48:49], v[68:69]
	v_exp_f32_e32 v54, v54
	v_mul_f32_e32 v55, 0xbfb8aa3b, v55
	v_rcp_f32_e32 v60, v60
	v_rcp_f32_e32 v57, v57
	v_exp_f32_e32 v55, v55
	v_mul_f32_e32 v48, 0xbfb8aa3b, v48
	v_add_f32_e32 v52, 1.0, v52
	v_exp_f32_e32 v48, v48
	v_mul_f32_e32 v49, 0xbfb8aa3b, v49
	v_lshlrev_b32_e32 v58, 16, v111
	v_rcp_f32_e32 v52, v52
	v_add_f32_e32 v53, 1.0, v53
	v_exp_f32_e32 v49, v49
	v_mul_f32_e32 v59, v56, v58
	v_and_b32_e32 v56, 0xffff0000, v111
	v_rcp_f32_e32 v53, v53
	v_add_f32_e32 v54, 1.0, v54
	v_mul_f32_e32 v60, v60, v118
	v_mul_f32_e32 v110, v57, v56
	v_cvt_pk_bf16_f32 v56, v60, v61
	v_rcp_f32_e32 v54, v54
	v_add_f32_e32 v55, 1.0, v55
	v_cvt_pk_bf16_f32 v57, v62, v63
	v_cvt_pk_bf16_f32 v58, v108, v109
	v_cvt_pk_bf16_f32 v59, v59, v110
	global_store_dwordx4 v[120:121], v[56:59], off offset:256
	v_pk_add_f32 v[50:51], v[50:51], v[70:71]
	v_rcp_f32_e32 v55, v55
	v_lshlrev_b32_e32 v56, 16, v114
	v_add_f32_e32 v48, 1.0, v48
	v_mul_f32_e32 v52, v52, v56
	v_and_b32_e32 v56, 0xffff0000, v114
	v_rcp_f32_e32 v48, v48
	v_add_f32_e32 v49, 1.0, v49
	v_mul_f32_e32 v50, 0xbfb8aa3b, v50
	v_mul_f32_e32 v53, v53, v56
	v_lshlrev_b32_e32 v56, 16, v115
	v_rcp_f32_e32 v49, v49
	v_exp_f32_e32 v50, v50
	v_mul_f32_e32 v51, 0xbfb8aa3b, v51
	v_mul_f32_e32 v54, v54, v56
	v_and_b32_e32 v56, 0xffff0000, v115
	v_exp_f32_e32 v51, v51
	v_pk_add_f32 v[44:45], v[44:45], v[72:73]
	v_mul_f32_e32 v55, v55, v56
	v_lshlrev_b32_e32 v56, 16, v116
	v_mul_f32_e32 v44, 0xbfb8aa3b, v44
	v_mul_f32_e32 v56, v48, v56
	v_and_b32_e32 v48, 0xffff0000, v116
	v_pk_add_f32 v[46:47], v[46:47], v[74:75]
	v_exp_f32_e32 v44, v44
	v_mul_f32_e32 v45, 0xbfb8aa3b, v45
	v_mul_f32_e32 v57, v49, v48
	v_add_f32_e32 v48, 1.0, v50
	v_exp_f32_e32 v45, v45
	v_mul_f32_e32 v46, 0xbfb8aa3b, v46
	v_rcp_f32_e32 v48, v48
	v_add_f32_e32 v49, 1.0, v51
	v_pk_add_f32 v[40:41], v[40:41], v[68:69]
	v_exp_f32_e32 v46, v46
	v_mul_f32_e32 v47, 0xbfb8aa3b, v47
	v_rcp_f32_e32 v49, v49
	v_exp_f32_e32 v47, v47
	v_mul_f32_e32 v40, 0xbfb8aa3b, v40
	v_add_f32_e32 v44, 1.0, v44
	v_exp_f32_e32 v40, v40
	v_mul_f32_e32 v41, 0xbfb8aa3b, v41
	v_lshlrev_b32_e32 v50, 16, v117
	v_rcp_f32_e32 v44, v44
	v_add_f32_e32 v45, 1.0, v45
	v_exp_f32_e32 v41, v41
	v_mul_f32_e32 v51, v48, v50
	v_and_b32_e32 v48, 0xffff0000, v117
	v_rcp_f32_e32 v45, v45
	v_add_f32_e32 v46, 1.0, v46
	v_mul_f32_e32 v58, v49, v48
	v_cvt_pk_bf16_f32 v48, v52, v53
	v_rcp_f32_e32 v46, v46
	v_add_f32_e32 v47, 1.0, v47
	v_cvt_pk_bf16_f32 v49, v54, v55
	v_cvt_pk_bf16_f32 v50, v56, v57
	v_cvt_pk_bf16_f32 v51, v51, v58
	global_store_dwordx4 v[112:113], v[48:51], off offset:256
	v_pk_add_f32 v[42:43], v[42:43], v[70:71]
	v_rcp_f32_e32 v47, v47
	v_lshlrev_b32_e32 v48, 16, v92
	v_add_f32_e32 v40, 1.0, v40
	v_mul_f32_e32 v44, v44, v48
	v_and_b32_e32 v48, 0xffff0000, v92
	v_rcp_f32_e32 v40, v40
	v_add_f32_e32 v41, 1.0, v41
	v_mul_f32_e32 v42, 0xbfb8aa3b, v42
	v_mul_f32_e32 v45, v45, v48
	v_lshlrev_b32_e32 v48, 16, v93
	v_rcp_f32_e32 v41, v41
	v_exp_f32_e32 v42, v42
	v_mul_f32_e32 v43, 0xbfb8aa3b, v43
	v_mul_f32_e32 v46, v46, v48
	v_and_b32_e32 v48, 0xffff0000, v93
	v_exp_f32_e32 v43, v43
	v_pk_add_f32 v[36:37], v[36:37], v[72:73]
	v_mul_f32_e32 v47, v47, v48
	v_lshlrev_b32_e32 v48, 16, v94
	v_mul_f32_e32 v36, 0xbfb8aa3b, v36
	v_mul_f32_e32 v48, v40, v48
	v_and_b32_e32 v40, 0xffff0000, v94
	v_pk_add_f32 v[38:39], v[38:39], v[74:75]
	v_exp_f32_e32 v36, v36
	v_mul_f32_e32 v37, 0xbfb8aa3b, v37
	v_mul_f32_e32 v49, v41, v40
	v_add_f32_e32 v40, 1.0, v42
	v_exp_f32_e32 v37, v37
	v_mul_f32_e32 v38, 0xbfb8aa3b, v38
	v_rcp_f32_e32 v40, v40
	v_add_f32_e32 v41, 1.0, v43
	v_pk_add_f32 v[32:33], v[32:33], v[68:69]
	v_exp_f32_e32 v38, v38
	v_mul_f32_e32 v39, 0xbfb8aa3b, v39
	v_rcp_f32_e32 v41, v41
	v_exp_f32_e32 v39, v39
	v_mul_f32_e32 v32, 0xbfb8aa3b, v32
	v_add_f32_e32 v36, 1.0, v36
	v_exp_f32_e32 v32, v32
	v_mul_f32_e32 v33, 0xbfb8aa3b, v33
	v_lshlrev_b32_e32 v42, 16, v95
	v_rcp_f32_e32 v36, v36
	v_add_f32_e32 v37, 1.0, v37
	v_exp_f32_e32 v33, v33
; __device__ __forceinline__ float bf_lo(unsigned w) { return __uint_as_float(w << 16); }
; __device__ __forceinline__ float bf_hi(unsigned w) { return __uint_as_float(w & 0xffff0000u); }
; __device__ __forceinline__ float sigmoid_f(float a) { return __builtin_amdgcn_rcpf(1.0f + __builtin_amdgcn_exp2f(-1.4426950408889634f * a)); }
; __device__ __forceinline__ u32x4 pack8(const f32x4& v0, const f32x4& v1) { u32x4 w; w.x = cvt_pk_bf16(v0[0], v0[1]); w.y = cvt_pk_bf16(v0[2], v0[3]); w.z = cvt_pk_bf16(v1[0], v1[1]); w.w = cvt_pk_bf16(v1[2], v1[3]); return w; }
;     __device__ __forceinline__ void operator()(const f32x4 (&acc)[2][2][4][2], const Unit& u, int wr, int wc, int fr, int fq) const {
;     ...
;                 for (int m = 0; m < 4; ++m) { const size_t off = (size_t)(row0 + ai * HALF + m * 16) * 1024 + col;
;                     const u32x4 yw = ywv[ai * 4 + m];
;                     f32x4 v0 = acc[ai][bj][m][0] + b0, v1 = acc[ai][bj][m][1] + b1;
;                     v0[0] = bf_lo(yw.x) * sigmoid_f(v0[0]); v0[1] = bf_hi(yw.x) * sigmoid_f(v0[1]); v0[2] = bf_lo(yw.y) * sigmoid_f(v0[2]); v0[3] = bf_hi(yw.y) * sigmoid_f(v0[3]);
;                     v1[0] = bf_lo(yw.z) * sigmoid_f(v1[0]); v1[1] = bf_hi(yw.z) * sigmoid_f(v1[1]); v1[2] = bf_lo(yw.w) * sigmoid_f(v1[2]); v1[3] = bf_hi(yw.w) * sigmoid_f(v1[3]);
;                     *(u32x4*)(Y2 + off) = pack8(v0, v1); }
	v_mul_f32_e32 v43, v40, v42
	v_and_b32_e32 v40, 0xffff0000, v95
	v_rcp_f32_e32 v37, v37
	v_add_f32_e32 v38, 1.0, v38
	v_mul_f32_e32 v50, v41, v40
	v_cvt_pk_bf16_f32 v40, v44, v45
	v_rcp_f32_e32 v38, v38
	v_add_f32_e32 v39, 1.0, v39
	v_cvt_pk_bf16_f32 v41, v46, v47
	v_cvt_pk_bf16_f32 v42, v48, v49
	v_cvt_pk_bf16_f32 v43, v43, v50
	global_store_dwordx4 v[104:105], v[40:43], off offset:256
	v_pk_add_f32 v[34:35], v[34:35], v[70:71]
	v_rcp_f32_e32 v39, v39
	v_lshlrev_b32_e32 v40, 16, v88
	v_add_f32_e32 v32, 1.0, v32
	v_mul_f32_e32 v36, v36, v40
	v_and_b32_e32 v40, 0xffff0000, v88
	v_rcp_f32_e32 v32, v32
	v_add_f32_e32 v33, 1.0, v33
	v_mul_f32_e32 v34, 0xbfb8aa3b, v34
	v_mul_f32_e32 v37, v37, v40
	v_lshlrev_b32_e32 v40, 16, v89
	v_rcp_f32_e32 v33, v33
	v_exp_f32_e32 v34, v34
	v_mul_f32_e32 v35, 0xbfb8aa3b, v35
	v_mul_f32_e32 v38, v38, v40
	v_and_b32_e32 v40, 0xffff0000, v89
	v_exp_f32_e32 v35, v35
	v_pk_add_f32 v[28:29], v[28:29], v[72:73]
	v_mul_f32_e32 v39, v39, v40
	v_lshlrev_b32_e32 v40, 16, v90
	v_mul_f32_e32 v28, 0xbfb8aa3b, v28
	v_mul_f32_e32 v40, v32, v40
	v_and_b32_e32 v32, 0xffff0000, v90
	v_pk_add_f32 v[30:31], v[30:31], v[74:75]
	v_exp_f32_e32 v28, v28
	v_mul_f32_e32 v29, 0xbfb8aa3b, v29
	v_mul_f32_e32 v41, v33, v32
	v_add_f32_e32 v32, 1.0, v34
	v_exp_f32_e32 v29, v29
	v_mul_f32_e32 v30, 0xbfb8aa3b, v30
	v_rcp_f32_e32 v32, v32
	v_add_f32_e32 v33, 1.0, v35
	v_pk_add_f32 v[24:25], v[24:25], v[68:69]
	v_exp_f32_e32 v30, v30
	v_mul_f32_e32 v31, 0xbfb8aa3b, v31
	v_rcp_f32_e32 v33, v33
	v_exp_f32_e32 v31, v31
	v_mul_f32_e32 v24, 0xbfb8aa3b, v24
	v_add_f32_e32 v28, 1.0, v28
	v_exp_f32_e32 v24, v24
	v_mul_f32_e32 v25, 0xbfb8aa3b, v25
	v_lshlrev_b32_e32 v34, 16, v91
	v_rcp_f32_e32 v28, v28
	v_add_f32_e32 v29, 1.0, v29
	v_exp_f32_e32 v25, v25
	v_mul_f32_e32 v35, v32, v34
	v_and_b32_e32 v32, 0xffff0000, v91
	v_rcp_f32_e32 v29, v29
	v_add_f32_e32 v30, 1.0, v30
	v_mul_f32_e32 v42, v33, v32
	v_cvt_pk_bf16_f32 v32, v36, v37
	v_rcp_f32_e32 v30, v30
	v_add_f32_e32 v31, 1.0, v31
	v_cvt_pk_bf16_f32 v33, v38, v39
	v_cvt_pk_bf16_f32 v34, v40, v41
	v_cvt_pk_bf16_f32 v35, v35, v42
	global_store_dwordx4 v[96:97], v[32:35], off offset:256
	v_pk_add_f32 v[26:27], v[26:27], v[70:71]
	v_rcp_f32_e32 v31, v31
	v_lshlrev_b32_e32 v32, 16, v84
	v_add_f32_e32 v24, 1.0, v24
	v_mul_f32_e32 v28, v28, v32
	v_and_b32_e32 v32, 0xffff0000, v84
	v_rcp_f32_e32 v24, v24
	v_add_f32_e32 v25, 1.0, v25
	v_mul_f32_e32 v26, 0xbfb8aa3b, v26
	v_mul_f32_e32 v29, v29, v32
	v_lshlrev_b32_e32 v32, 16, v85
	v_rcp_f32_e32 v25, v25
	v_exp_f32_e32 v26, v26
	v_mul_f32_e32 v27, 0xbfb8aa3b, v27
	v_mul_f32_e32 v30, v30, v32
	v_and_b32_e32 v32, 0xffff0000, v85
	v_exp_f32_e32 v27, v27
	v_pk_add_f32 v[20:21], v[20:21], v[72:73]
	v_mul_f32_e32 v31, v31, v32
	v_lshlrev_b32_e32 v32, 16, v86
	v_mul_f32_e32 v20, 0xbfb8aa3b, v20
	v_mul_f32_e32 v32, v24, v32
	v_and_b32_e32 v24, 0xffff0000, v86
	v_pk_add_f32 v[22:23], v[22:23], v[74:75]
	v_exp_f32_e32 v20, v20
	v_mul_f32_e32 v21, 0xbfb8aa3b, v21
	v_mul_f32_e32 v33, v25, v24
	v_add_f32_e32 v24, 1.0, v26
	v_exp_f32_e32 v21, v21
	v_mul_f32_e32 v22, 0xbfb8aa3b, v22
	v_rcp_f32_e32 v24, v24
	v_add_f32_e32 v25, 1.0, v27
	v_pk_add_f32 v[16:17], v[16:17], v[68:69]
	v_exp_f32_e32 v22, v22
	v_mul_f32_e32 v23, 0xbfb8aa3b, v23
	v_rcp_f32_e32 v25, v25
	v_exp_f32_e32 v23, v23
	v_mul_f32_e32 v16, 0xbfb8aa3b, v16
	v_add_f32_e32 v20, 1.0, v20
	v_exp_f32_e32 v16, v16
	v_mul_f32_e32 v17, 0xbfb8aa3b, v17
	v_lshlrev_b32_e32 v26, 16, v87
	v_rcp_f32_e32 v20, v20
	v_add_f32_e32 v21, 1.0, v21
	v_exp_f32_e32 v17, v17
	v_mul_f32_e32 v27, v24, v26
	v_and_b32_e32 v24, 0xffff0000, v87
	v_rcp_f32_e32 v21, v21
	v_add_f32_e32 v22, 1.0, v22
	v_mul_f32_e32 v34, v25, v24
	v_cvt_pk_bf16_f32 v24, v28, v29
	v_rcp_f32_e32 v22, v22
	v_add_f32_e32 v23, 1.0, v23
	v_cvt_pk_bf16_f32 v25, v30, v31
	v_cvt_pk_bf16_f32 v26, v32, v33
	v_cvt_pk_bf16_f32 v27, v27, v34
	global_store_dwordx4 v[98:99], v[24:27], off offset:256
	v_pk_add_f32 v[18:19], v[18:19], v[70:71]
	v_rcp_f32_e32 v23, v23
	v_lshlrev_b32_e32 v24, 16, v80
	v_add_f32_e32 v16, 1.0, v16
	v_mul_f32_e32 v20, v20, v24
	v_and_b32_e32 v24, 0xffff0000, v80
	v_rcp_f32_e32 v16, v16
	v_add_f32_e32 v17, 1.0, v17
	v_mul_f32_e32 v18, 0xbfb8aa3b, v18
	v_mul_f32_e32 v21, v21, v24
	v_lshlrev_b32_e32 v24, 16, v81
; __device__ __forceinline__ float bf_lo(unsigned w) { return __uint_as_float(w << 16); }
; __device__ __forceinline__ float bf_hi(unsigned w) { return __uint_as_float(w & 0xffff0000u); }
; __device__ __forceinline__ float sigmoid_f(float a) { return __builtin_amdgcn_rcpf(1.0f + __builtin_amdgcn_exp2f(-1.4426950408889634f * a)); }
; __device__ __forceinline__ u32x4 pack8(const f32x4& v0, const f32x4& v1) { u32x4 w; w.x = cvt_pk_bf16(v0[0], v0[1]); w.y = cvt_pk_bf16(v0[2], v0[3]); w.z = cvt_pk_bf16(v1[0], v1[1]); w.w = cvt_pk_bf16(v1[2], v1[3]); return w; }
; #define PG8_BAR __builtin_amdgcn_s_barrier()
;     __device__ __forceinline__ void operator()(const f32x4 (&acc)[2][2][4][2], const Unit& u, int wr, int wc, int fr, int fq) const {
;     ...
;                 for (int m = 0; m < 4; ++m) { const size_t off = (size_t)(row0 + ai * HALF + m * 16) * 1024 + col;
;                     const u32x4 yw = ywv[ai * 4 + m];
;                     f32x4 v0 = acc[ai][bj][m][0] + b0, v1 = acc[ai][bj][m][1] + b1;
;                     v0[0] = bf_lo(yw.x) * sigmoid_f(v0[0]); v0[1] = bf_hi(yw.x) * sigmoid_f(v0[1]); v0[2] = bf_lo(yw.y) * sigmoid_f(v0[2]); v0[3] = bf_hi(yw.y) * sigmoid_f(v0[3]);
;                     v1[0] = bf_lo(yw.z) * sigmoid_f(v1[0]); v1[1] = bf_hi(yw.z) * sigmoid_f(v1[1]); v1[2] = bf_lo(yw.w) * sigmoid_f(v1[2]); v1[3] = bf_hi(yw.w) * sigmoid_f(v1[3]);
;                     *(u32x4*)(Y2 + off) = pack8(v0, v1); }
;             asm volatile("" ::: "memory"); }
; template <class Epi, class Sched, bool ALIGN_EPI = false, bool SP2 = false>
; __device__ __forceinline__ void gemm_phase(PG8_LAS unsigned char* lds, const Gemm g, const Sched& S, const Epi& E, const int wid) {
;     ...
;         if constexpr (ALIGN_EPI) { if (wr == 0) PG8_BAR; }
;         E(acc, cur, wr, wc, fr, fq);
;         if (!has_next) break;
; #pragma unroll
;         for (int a = 0; a < 2; ++a)
; #pragma unroll
;             for (int b = 0; b < 2; ++b)
; #pragma unroll
;                 for (int m = 0; m < 4; ++m)
; #pragma unroll
;                     for (int n = 0; n < 2; ++n) acc[a][b][m][n] = (f32x4){0.f, 0.f, 0.f, 0.f};
;         cur = nxt; cA = nA; cB = nB; ++ui;
;         if constexpr (ALIGN_EPI) { if (wr == 1) PG8_BAR; }
;     }
	v_rcp_f32_e32 v17, v17
	v_exp_f32_e32 v18, v18
	v_mul_f32_e32 v19, 0xbfb8aa3b, v19
	v_mul_f32_e32 v22, v22, v24
	v_and_b32_e32 v24, 0xffff0000, v81
	v_exp_f32_e32 v19, v19
	v_pk_add_f32 v[12:13], v[12:13], v[72:73]
	v_mul_f32_e32 v23, v23, v24
	v_lshlrev_b32_e32 v24, 16, v82
	v_mul_f32_e32 v12, 0xbfb8aa3b, v12
	v_mul_f32_e32 v24, v16, v24
	v_and_b32_e32 v16, 0xffff0000, v82
	v_pk_add_f32 v[14:15], v[14:15], v[74:75]
	v_exp_f32_e32 v12, v12
	v_mul_f32_e32 v13, 0xbfb8aa3b, v13
	v_mul_f32_e32 v25, v17, v16
	v_add_f32_e32 v16, 1.0, v18
	v_exp_f32_e32 v13, v13
	v_mul_f32_e32 v14, 0xbfb8aa3b, v14
	v_rcp_f32_e32 v16, v16
	v_add_f32_e32 v17, 1.0, v19
	v_pk_add_f32 v[8:9], v[8:9], v[68:69]
	v_exp_f32_e32 v14, v14
	v_mul_f32_e32 v15, 0xbfb8aa3b, v15
	v_rcp_f32_e32 v17, v17
	v_exp_f32_e32 v15, v15
	v_mul_f32_e32 v8, 0xbfb8aa3b, v8
	v_add_f32_e32 v12, 1.0, v12
	v_exp_f32_e32 v8, v8
	v_mul_f32_e32 v9, 0xbfb8aa3b, v9
	v_lshlrev_b32_e32 v18, 16, v83
	v_rcp_f32_e32 v12, v12
	v_add_f32_e32 v13, 1.0, v13
	v_exp_f32_e32 v9, v9
	v_mul_f32_e32 v19, v16, v18
	v_and_b32_e32 v16, 0xffff0000, v83
	v_rcp_f32_e32 v13, v13
	v_add_f32_e32 v14, 1.0, v14
	v_mul_f32_e32 v26, v17, v16
	v_cvt_pk_bf16_f32 v16, v20, v21
	v_rcp_f32_e32 v14, v14
	v_add_f32_e32 v15, 1.0, v15
	v_cvt_pk_bf16_f32 v17, v22, v23
	v_cvt_pk_bf16_f32 v18, v24, v25
	v_cvt_pk_bf16_f32 v19, v19, v26
	global_store_dwordx4 v[106:107], v[16:19], off offset:256
	v_pk_add_f32 v[10:11], v[10:11], v[70:71]
	v_rcp_f32_e32 v15, v15
	v_lshlrev_b32_e32 v16, 16, v76
	v_add_f32_e32 v8, 1.0, v8
	v_mul_f32_e32 v12, v12, v16
	v_and_b32_e32 v16, 0xffff0000, v76
	v_rcp_f32_e32 v8, v8
	v_add_f32_e32 v9, 1.0, v9
	v_mul_f32_e32 v10, 0xbfb8aa3b, v10
	v_mul_f32_e32 v13, v13, v16
	v_lshlrev_b32_e32 v16, 16, v77
	v_rcp_f32_e32 v9, v9
	v_exp_f32_e32 v10, v10
	v_mul_f32_e32 v11, 0xbfb8aa3b, v11
	v_mul_f32_e32 v14, v14, v16
	v_and_b32_e32 v16, 0xffff0000, v77
	v_exp_f32_e32 v11, v11
	v_pk_add_f32 v[4:5], v[4:5], v[72:73]
	v_mul_f32_e32 v15, v15, v16
	v_lshlrev_b32_e32 v16, 16, v78
	v_mul_f32_e32 v4, 0xbfb8aa3b, v4
	v_mul_f32_e32 v16, v8, v16
	v_and_b32_e32 v8, 0xffff0000, v78
	v_pk_add_f32 v[6:7], v[6:7], v[74:75]
	v_exp_f32_e32 v4, v4
	v_mul_f32_e32 v5, 0xbfb8aa3b, v5
	v_mul_f32_e32 v17, v9, v8
	v_add_f32_e32 v8, 1.0, v10
	v_exp_f32_e32 v5, v5
	v_mul_f32_e32 v6, 0xbfb8aa3b, v6
	v_rcp_f32_e32 v8, v8
	v_add_f32_e32 v9, 1.0, v11
	v_pk_add_f32 v[0:1], v[0:1], v[68:69]
	v_exp_f32_e32 v6, v6
	v_mul_f32_e32 v7, 0xbfb8aa3b, v7
	v_rcp_f32_e32 v9, v9
	v_exp_f32_e32 v7, v7
	v_mul_f32_e32 v0, 0xbfb8aa3b, v0
	v_add_f32_e32 v4, 1.0, v4
	v_exp_f32_e32 v0, v0
	v_mul_f32_e32 v1, 0xbfb8aa3b, v1
	v_lshlrev_b32_e32 v10, 16, v79
	v_rcp_f32_e32 v4, v4
	v_add_f32_e32 v5, 1.0, v5
	v_exp_f32_e32 v1, v1
	v_mul_f32_e32 v11, v8, v10
	v_and_b32_e32 v8, 0xffff0000, v79
	v_rcp_f32_e32 v5, v5
	v_add_f32_e32 v6, 1.0, v6
	v_mul_f32_e32 v18, v9, v8
	v_cvt_pk_bf16_f32 v8, v12, v13
	v_rcp_f32_e32 v6, v6
	v_add_f32_e32 v7, 1.0, v7
	v_cvt_pk_bf16_f32 v9, v14, v15
	v_cvt_pk_bf16_f32 v10, v16, v17
	v_cvt_pk_bf16_f32 v11, v11, v18
	global_store_dwordx4 v[102:103], v[8:11], off offset:256
	v_pk_add_f32 v[2:3], v[2:3], v[70:71]
	v_rcp_f32_e32 v7, v7
	v_lshlrev_b32_e32 v8, 16, v64
	v_add_f32_e32 v0, 1.0, v0
	v_mul_f32_e32 v4, v4, v8
	v_and_b32_e32 v8, 0xffff0000, v64
	v_rcp_f32_e32 v0, v0
	v_add_f32_e32 v1, 1.0, v1
	v_mul_f32_e32 v2, 0xbfb8aa3b, v2
	v_mul_f32_e32 v5, v5, v8
	v_lshlrev_b32_e32 v8, 16, v65
	v_rcp_f32_e32 v1, v1
	v_exp_f32_e32 v2, v2
	v_mul_f32_e32 v3, 0xbfb8aa3b, v3
	v_mul_f32_e32 v6, v6, v8
	v_and_b32_e32 v8, 0xffff0000, v65
	v_exp_f32_e32 v3, v3
	v_mul_f32_e32 v7, v7, v8
	v_lshlrev_b32_e32 v8, 16, v66
	v_mul_f32_e32 v8, v0, v8
	v_and_b32_e32 v0, 0xffff0000, v66
	v_mul_f32_e32 v9, v1, v0
	v_add_f32_e32 v0, 1.0, v2
	v_rcp_f32_e32 v0, v0
	v_add_f32_e32 v1, 1.0, v3
	v_rcp_f32_e32 v1, v1
	v_lshlrev_b32_e32 v2, 16, v67
	v_mul_f32_e32 v3, v0, v2
	v_and_b32_e32 v0, 0xffff0000, v67
	v_mul_f32_e32 v10, v1, v0
	v_cvt_pk_bf16_f32 v0, v4, v5
	v_cvt_pk_bf16_f32 v1, v6, v7
	v_cvt_pk_bf16_f32 v2, v8, v9
	v_cvt_pk_bf16_f32 v3, v3, v10
	global_store_dwordx4 v[100:101], v[0:3], off offset:256
	s_cbranch_vccnz .LBB0_1169
	s_andn2_b64 vcc, exec, s[12:13]
	s_cbranch_vccnz .LBB0_1168
	s_barrier
	s_branch .LBB0_1168

; __device__ __forceinline__ int lane_asm() { int l; asm volatile("v_mbcnt_lo_u32_b32 %0, -1, 0\n\tv_mbcnt_hi_u32_b32 %0, -1, %0" : "=v"(l)); return l; }
; #define INP(k) ((const float*)ldptr(L, (k)))
; __global__ void __launch_bounds__(NTHR, 2) mk_fwd(Args args) {
;     ...
;     if (IN(11)) { const int lane = lane_asm(), tid = wave * 64 + lane; (void)tid;
;         const float s1 = wave_sum((INP(13))[lane] * (INP(14))[lane]), s2 = wave_sum((INP(15))[lane] * (INP(16))[lane]);
;         const float lam_init = 0.2f, lam = expf(s1) - expf(s2) + lam_init;
;         float subln[16], ogn[16];
;         { const float* sp_ = INP(17) + (lane & 7) * 16; const float* gp_ = INP(28) + lane * 16;
; #pragma unroll
;           for (int i = 0; i < 16; ++i) { subln[i] = sp_[i]; ogn[i] = gp_[i]; } }
.LBB0_1232:
	s_cmp_lt_i32 s68, 12
	s_cselect_b64 s[0:1], -1, 0
	s_and_b64 s[8:9], s[0:1], s[34:35]
	s_andn2_b64 vcc, exec, s[8:9]
	s_cbranch_vccnz .LBB0_1236
	s_add_i32 s0, 0, 0x20068
	v_mov_b32_e32 v0, s0
	v_mbcnt_lo_u32_b32 v16, -1, 0
	v_mbcnt_hi_u32_b32 v16, -1, v16
	s_waitcnt lgkmcnt(0)
	ds_read2_b64 v[0:3], v0 offset1:1
	s_add_i32 s0, 0, 0x20078
	v_mov_b32_e32 v4, s0
	ds_read2_b64 v[4:7], v4 offset1:1
	v_ashrrev_i32_e32 v17, 31, v16
	s_waitcnt lgkmcnt(0)
	v_readfirstlane_b32 s0, v0
	v_readfirstlane_b32 s1, v1
	v_lshlrev_b64 v[0:1], 2, v[16:17]
	s_nop 0
	v_lshl_add_u64 v[8:9], s[0:1], 0, v[0:1]
	v_readfirstlane_b32 s0, v2
	v_readfirstlane_b32 s1, v3
	global_load_dword v8, v[8:9], off
	s_nop 0
	v_lshl_add_u64 v[2:3], s[0:1], 0, v[0:1]
	v_readfirstlane_b32 s0, v4
	v_readfirstlane_b32 s1, v5
	global_load_dword v9, v[2:3], off
	s_nop 0
	v_lshl_add_u64 v[2:3], s[0:1], 0, v[0:1]
	v_readfirstlane_b32 s0, v6
	v_readfirstlane_b32 s1, v7
	global_load_dword v4, v[2:3], off
	s_nop 0
	v_lshl_add_u64 v[0:1], s[0:1], 0, v[0:1]
	global_load_dword v5, v[0:1], off
	v_mbcnt_lo_u32_b32 v0, -1, 0
	v_mbcnt_hi_u32_b32 v6, -1, v0
	v_and_b32_e32 v7, 64, v6
	v_xor_b32_e32 v10, 1, v6
	v_add_u32_e32 v7, 64, v7
	v_cmp_lt_i32_e32 vcc, v10, v7
	v_xor_b32_e32 v11, 2, v6
	v_xor_b32_e32 v12, 4, v6
	v_cndmask_b32_e32 v10, v6, v10, vcc
	v_lshlrev_b32_e32 v130, 2, v10
	v_cmp_lt_i32_e32 vcc, v11, v7
	v_xor_b32_e32 v13, 8, v6
	v_xor_b32_e32 v14, 16, v6
	v_cndmask_b32_e32 v11, v6, v11, vcc
	v_lshlrev_b32_e32 v131, 2, v11
	v_cmp_lt_i32_e32 vcc, v12, v7
	v_xor_b32_e32 v15, 32, v6
	s_add_i32 s0, 0, 0x20088
	s_add_i32 s1, 0, 0x200e0
	v_mov_b32_e32 v0, s0
	v_mov_b32_e32 v2, s1
	ds_read_b64 v[0:1], v0
	ds_read_b64 v[2:3], v2
	s_cmpk_gt_i32 s72, 0x3fff
	s_waitcnt lgkmcnt(0)
	v_readfirstlane_b32 s0, v0
	v_readfirstlane_b32 s1, v1
	v_readfirstlane_b32 s3, v2
	v_readfirstlane_b32 s4, v3
	s_waitcnt vmcnt(0)
	v_mul_f32_e32 v10, v8, v9
	ds_bpermute_b32 v10, v130, v10
	s_waitcnt lgkmcnt(0)
	v_fmac_f32_e32 v10, v8, v9
	v_cndmask_b32_e32 v8, v6, v12, vcc
	v_mul_f32_e32 v17, v4, v5
	ds_bpermute_b32 v17, v130, v17
	v_lshlrev_b32_e32 v132, 2, v8
	v_cmp_lt_i32_e32 vcc, v13, v7
	s_waitcnt lgkmcnt(0)
	v_fmac_f32_e32 v17, v4, v5
	ds_bpermute_b32 v4, v131, v10
	ds_bpermute_b32 v5, v131, v17
	s_waitcnt lgkmcnt(1)
	v_add_f32_e32 v4, v10, v4
	s_waitcnt lgkmcnt(0)
	v_add_f32_e32 v5, v17, v5
	ds_bpermute_b32 v8, v132, v4
	ds_bpermute_b32 v9, v132, v5
	v_cndmask_b32_e32 v10, v6, v13, vcc
	v_lshlrev_b32_e32 v133, 2, v10
	v_cmp_lt_i32_e32 vcc, v14, v7
	s_waitcnt lgkmcnt(1)
	v_add_f32_e32 v4, v4, v8
	s_waitcnt lgkmcnt(0)
	v_add_f32_e32 v5, v5, v9
	ds_bpermute_b32 v8, v133, v4
	ds_bpermute_b32 v9, v133, v5
	v_cndmask_b32_e32 v10, v6, v14, vcc
	v_lshlrev_b32_e32 v134, 2, v10
	v_cmp_lt_i32_e32 vcc, v15, v7
	s_waitcnt lgkmcnt(1)
	v_add_f32_e32 v4, v4, v8
	s_waitcnt lgkmcnt(0)
	v_add_f32_e32 v5, v5, v9
	ds_bpermute_b32 v8, v134, v4
	ds_bpermute_b32 v9, v134, v5
	v_cndmask_b32_e32 v6, v6, v15, vcc
	v_lshlrev_b32_e32 v135, 2, v6
	s_waitcnt lgkmcnt(1)
	v_add_f32_e32 v34, v4, v8
	s_waitcnt lgkmcnt(0)
	v_add_f32_e32 v32, v5, v9
	ds_bpermute_b32 v35, v135, v34
	ds_bpermute_b32 v33, v135, v32
	s_cbranch_scc1 .LBB0_1236
	v_lshlrev_b32_e32 v0, 6, v16
	v_lshlrev_b32_e32 v38, 4, v16
	v_and_b32_e32 v0, 0x1c0, v0
	v_mov_b32_e32 v1, 0
	v_mov_b32_e32 v16, s3
	v_mov_b32_e32 v17, s4
	v_ashrrev_i32_e32 v39, 31, v38
	v_lshl_add_u64 v[18:19], s[0:1], 0, v[0:1]
	v_lshl_add_u64 v[36:37], v[38:39], 2, v[16:17]
	global_load_dwordx4 v[0:3], v[18:19], off offset:32
	global_load_dwordx4 v[4:7], v[18:19], off offset:48
	global_load_dwordx4 v[8:11], v[18:19], off offset:16
	global_load_dwordx4 v[12:15], v[18:19], off
	s_nop 0
	global_load_dwordx4 v[16:19], v[36:37], off offset:32
	global_load_dwordx4 v[20:23], v[36:37], off offset:48
	global_load_dwordx4 v[24:27], v[36:37], off
	global_load_dwordx4 v[28:31], v[36:37], off offset:16
	s_waitcnt lgkmcnt(0)
	v_add_f32_e32 v34, v34, v35
	s_mov_b32 s0, 0x3fb8aa3b
	v_add_f32_e32 v32, v32, v33
	v_mul_f32_e32 v33, 0x3fb8aa3b, v34
	v_mul_f32_e32 v36, 0x3fb8aa3b, v32
	v_fma_f32 v37, v34, s0, -v33
	v_rndne_f32_e32 v42, v33
	v_fma_f32 v43, v32, s0, -v36
	v_rndne_f32_e32 v44, v36
	v_fmac_f32_e32 v37, 0x32a5705f, v34
	v_sub_f32_e32 v33, v33, v42
	v_fmac_f32_e32 v43, 0x32a5705f, v32
	v_sub_f32_e32 v36, v36, v44
	v_add_f32_e32 v33, v33, v37
	v_cvt_i32_f32_e32 v42, v42
	v_add_f32_e32 v36, v36, v43
	v_exp_f32_e32 v33, v33
	v_cvt_i32_f32_e32 v44, v44
	v_exp_f32_e32 v36, v36
	s_mov_b32 s1, 0xc2ce8ed0
	v_ldexp_f32 v33, v33, v42
	v_cmp_ngt_f32_e32 vcc, s1, v34
	s_mov_b32 s3, 0x42b17218
	v_ldexp_f32 v36, v36, v44
	v_cndmask_b32_e32 v33, 0, v33, vcc
	v_cmp_ngt_f32_e32 vcc, s1, v32
	v_mov_b32_e32 v35, 0x7f800000
	s_lshl_b32 s10, s70, 4
	v_cndmask_b32_e32 v36, 0, v36, vcc
	v_cmp_nlt_f32_e32 vcc, s3, v34
	s_ashr_i32 s73, s72, 31
	s_ashr_i32 s11, s10, 31
	v_cndmask_b32_e32 v33, v35, v33, vcc
	v_cmp_nlt_f32_e32 vcc, s3, v32
	s_lshl_b64 s[12:13], s[72:73], 12
	s_lshl_b64 s[14:15], s[72:73], 11
	v_cndmask_b32_e32 v32, v35, v36, vcc
	v_sub_f32_e32 v32, v33, v32
	v_add_f32_e32 v42, 0x3e4ccccd, v32
	v_lshlrev_b64 v[40:41], 1, v[38:39]
	s_lshl_b64 s[16:17], s[10:11], 12
	s_lshl_b64 s[18:19], s[10:11], 11
	v_mov_b32_e32 v43, v42
	s_add_i32 s3, 0, 0x20118
	s_mov_b32 s11, 0xc600000
	s_mov_b32 s26, 0xe600000
	s_mov_b32 s27, 0x10600000
	s_mov_b32 s28, 0xffff0000
	v_mov_b32_e32 v136, 0x358637bd
	s_mov_b32 s29, 0xf800000
	v_mov_b32_e32 v137, 0x260
	s_mov_b32 s30, 0x3f4ccccd
	s_movk_i32 s31, 0x7fff
	s_mov_b32 s33, 0x12600000
	s_mov_b64 s[20:21], 0x12600000
	s_mov_b64 s[22:23], 0x12600800
	s_waitcnt vmcnt(0)
	v_mov_b32_e32 v44, v1
	v_mov_b32_e32 v45, v3
	v_mov_b32_e32 v1, v2
	v_mov_b32_e32 v2, v5
	v_mov_b32_e32 v3, v7
	v_mov_b32_e32 v5, v6
	v_mov_b32_e32 v6, v13
	v_mov_b32_e32 v7, v15
	v_mov_b32_e32 v13, v14
	v_mov_b32_e32 v14, v9
	v_mov_b32_e32 v15, v11
	v_mov_b32_e32 v9, v10
	v_mov_b32_e32 v10, v17
	v_mov_b32_e32 v11, v19
	v_mov_b32_e32 v17, v18
	v_mov_b32_e32 v18, v21
	v_mov_b32_e32 v19, v23
	v_mov_b32_e32 v21, v22
	v_mov_b32_e32 v22, v25
	v_mov_b32_e32 v23, v27
	v_mov_b32_e32 v25, v26
	v_mov_b32_e32 v26, v29
	v_mov_b32_e32 v27, v31
	v_mov_b32_e32 v29, v30
; __global__ void __launch_bounds__(NTHR, 2) mk_fwd(Args args) {
;     ...
;         for (int row = gw; row < M; row += 2 * NGW) {
;             const int r1 = (row + NGW < M) ? row + NGW : row;
;             v4u w[2][6];
; #pragma unroll
;             for (int q = 0; q < 2; ++q) { const size_t ro = (size_t)(q == 0 ? row : r1) * 1024 + lane * 16;
;                 w[q][0] = *(const v4u*)(p_O32 + ro); w[q][1] = *(const v4u*)(p_O32 + ro + 8);
;                 w[q][2] = *(const v4u*)(p_O32 + (size_t)M * 1024 + ro); w[q][3] = *(const v4u*)(p_O32 + (size_t)M * 1024 + ro + 8);
;                 w[q][4] = *(const v4u*)(p_Y2 + ro); w[q][5] = *(const v4u*)(p_Y2 + ro + 8); }
; #pragma unroll
;             for (int q = 0; q < 2; ++q) { const int r = (q == 0 ? row : r1);
;                 float a[16], b[16];
;     ...
;                 UNP(a, w[q][0], w[q][1]); UNP(b, w[q][2], w[q][3]);
;                 float ss = 0.f;
; #pragma unroll
;                 for (int i = 0; i < 16; ++i) { a[i] = a[i] - lam * b[i]; ss += a[i] * a[i]; }
.LBB0_1235:
	v_mov_b32_e32 v138, s3
	ds_read_b64 v[30:31], v138
	s_add_i32 s0, s80, s72
	s_cmpk_lt_i32 s0, 0x4000
	s_cselect_b32 s0, s0, s72
	s_ashr_i32 s1, s0, 31
	s_lshl_b64 s[4:5], s[0:1], 10
	s_lshl_b64 s[24:25], s[0:1], 12
	s_waitcnt lgkmcnt(0)
	v_readfirstlane_b32 s0, v30
	v_readfirstlane_b32 s1, v31
	v_lshl_add_u64 v[32:33], s[4:5], 0, v[38:39]
	s_nop 0
	v_lshl_add_u64 v[30:31], s[0:1], 0, v[40:41]
	v_lshl_add_u64 v[34:35], v[30:31], 0, s[14:15]
	v_add_co_u32_e32 v36, vcc, 0xc600000, v34
	v_lshl_add_u64 v[30:31], v[30:31], 0, s[12:13]
	s_nop 0
	v_addc_co_u32_e32 v37, vcc, 0, v35, vcc
	v_lshl_add_u64 v[32:33], v[32:33], 1, s[0:1]
	v_add_co_u32_e64 v46, s[0:1], s33, v30
	v_add_co_u32_e32 v30, vcc, 0xe600000, v34
	s_nop 0
	v_addc_co_u32_e64 v47, s[0:1], 0, v31, s[0:1]
	v_addc_co_u32_e32 v31, vcc, 0, v35, vcc
	v_add_co_u32_e32 v34, vcc, 0x10600000, v34
	global_load_dwordx4 v[48:51], v[36:37], off offset:16
	global_load_dwordx4 v[52:55], v[36:37], off
	v_addc_co_u32_e32 v35, vcc, 0, v35, vcc
	global_load_dwordx4 v[56:59], v[30:31], off offset:16
	global_load_dwordx4 v[60:63], v[30:31], off
	v_add_co_u32_e32 v30, vcc, s11, v32
	global_load_dwordx4 v[72:75], v[34:35], off offset:16
	global_load_dwordx4 v[76:79], v[34:35], off
	v_addc_co_u32_e32 v31, vcc, 0, v33, vcc
	v_add_co_u32_e32 v34, vcc, s26, v32
	global_load_dwordx4 v[88:91], v[30:31], off
	global_load_dwordx4 v[92:95], v[30:31], off offset:16
	v_addc_co_u32_e32 v35, vcc, 0, v33, vcc
	global_load_dwordx4 v[96:99], v[34:35], off
	global_load_dwordx4 v[100:103], v[34:35], off offset:16
	v_add_co_u32_e32 v64, vcc, s27, v32
	s_waitcnt vmcnt(0) lgkmcnt(0)
	v_lshlrev_b32_e32 v69, 16, v51
	v_addc_co_u32_e32 v65, vcc, 0, v33, vcc
	global_load_dwordx4 v[30:33], v[64:65], off
	global_load_dwordx4 v[34:37], v[64:65], off offset:16
	v_lshlrev_b32_e32 v81, 16, v53
	v_lshlrev_b32_e32 v80, 16, v52
	v_and_b32_e32 v53, 0xffff0000, v53
	v_and_b32_e32 v52, 0xffff0000, v52
	v_lshlrev_b32_e32 v83, 16, v61
	v_lshlrev_b32_e32 v82, 16, v60
	v_and_b32_e32 v61, 0xffff0000, v61
	v_and_b32_e32 v60, 0xffff0000, v60
	v_lshlrev_b32_e32 v65, 16, v49
	v_lshlrev_b32_e32 v64, 16, v48
	v_and_b32_e32 v49, 0xffff0000, v49
	v_and_b32_e32 v48, 0xffff0000, v48
	v_lshlrev_b32_e32 v68, 16, v50
	v_and_b32_e32 v51, 0xffff0000, v51
	v_and_b32_e32 v50, 0xffff0000, v50
	v_lshlrev_b32_e32 v85, 16, v55
	v_lshlrev_b32_e32 v84, 16, v54
	v_and_b32_e32 v55, 0xffff0000, v55
	v_and_b32_e32 v54, 0xffff0000, v54
	v_lshlrev_b32_e32 v67, 16, v57
	v_lshlrev_b32_e32 v66, 16, v56
	v_and_b32_e32 v57, 0xffff0000, v57
	v_and_b32_e32 v56, 0xffff0000, v56
	v_lshlrev_b32_e32 v71, 16, v59
	v_lshlrev_b32_e32 v70, 16, v58
	v_and_b32_e32 v59, 0xffff0000, v59
	v_and_b32_e32 v58, 0xffff0000, v58
	v_lshlrev_b32_e32 v87, 16, v63
	v_lshlrev_b32_e32 v86, 16, v62
	v_and_b32_e32 v63, 0xffff0000, v63
	v_and_b32_e32 v62, 0xffff0000, v62
	v_pk_fma_f32 v[80:81], v[42:43], v[82:83], v[80:81] neg_lo:[1,0,0] neg_hi:[1,0,0]
	v_pk_fma_f32 v[82:83], v[42:43], v[60:61], v[52:53] neg_lo:[1,0,0] neg_hi:[1,0,0]
	v_pk_fma_f32 v[64:65], v[42:43], v[66:67], v[64:65] neg_lo:[1,0,0] neg_hi:[1,0,0]
	v_pk_fma_f32 v[66:67], v[42:43], v[56:57], v[48:49] neg_lo:[1,0,0] neg_hi:[1,0,0]
	v_pk_fma_f32 v[68:69], v[42:43], v[70:71], v[68:69] neg_lo:[1,0,0] neg_hi:[1,0,0]
	v_pk_fma_f32 v[70:71], v[42:43], v[58:59], v[50:51] neg_lo:[1,0,0] neg_hi:[1,0,0]
	v_pk_fma_f32 v[84:85], v[42:43], v[86:87], v[84:85] neg_lo:[1,0,0] neg_hi:[1,0,0]
	v_pk_fma_f32 v[86:87], v[42:43], v[62:63], v[54:55] neg_lo:[1,0,0] neg_hi:[1,0,0]
	v_lshlrev_b32_e32 v53, 16, v75
	v_and_b32_e32 v55, 0xffff0000, v75
	v_lshlrev_b32_e32 v57, 16, v77
	v_lshlrev_b32_e32 v56, 16, v76
	v_and_b32_e32 v59, 0xffff0000, v77
	v_and_b32_e32 v58, 0xffff0000, v76
	v_pk_mul_f32 v[76:77], v[80:81], v[80:81]
	v_pk_mul_f32 v[120:121], v[82:83], v[82:83]
	v_lshlrev_b32_e32 v61, 16, v79
	v_lshlrev_b32_e32 v60, 16, v78
	v_and_b32_e32 v63, 0xffff0000, v79
	v_and_b32_e32 v62, 0xffff0000, v78
	v_mov_b32_e32 v78, v53
	v_mov_b32_e32 v79, v55
	v_pk_mul_f32 v[140:141], v[56:57], v[56:57]
	v_pk_mul_f32 v[122:123], v[58:59], v[58:59]
	v_add_f32_e32 v76, v76, v120
	v_lshlrev_b32_e32 v49, 16, v73
	v_lshlrev_b32_e32 v48, 16, v72
	v_and_b32_e32 v51, 0xffff0000, v73
	v_and_b32_e32 v50, 0xffff0000, v72
	v_lshlrev_b32_e32 v52, 16, v74
	v_and_b32_e32 v54, 0xffff0000, v74
	v_mov_b32_e32 v72, v68
	v_mov_b32_e32 v73, v70
	v_mov_b32_e32 v74, v69
	v_mov_b32_e32 v75, v71
	v_lshlrev_b32_e32 v145, 16, v95
	v_lshlrev_b32_e32 v144, 16, v94
	v_and_b32_e32 v95, 0xffff0000, v95
	v_and_b32_e32 v94, 0xffff0000, v94
	v_lshlrev_b32_e32 v147, 16, v89
	v_lshlrev_b32_e32 v146, 16, v88
	v_and_b32_e32 v149, 0xffff0000, v89
	v_and_b32_e32 v148, 0xffff0000, v88
	v_lshlrev_b32_e32 v151, 16, v91
	v_lshlrev_b32_e32 v150, 16, v90
	v_and_b32_e32 v153, 0xffff0000, v91
	v_and_b32_e32 v152, 0xffff0000, v90
	v_pk_mul_f32 v[126:127], v[78:79], v[78:79]
	v_add_f32_e32 v120, v140, v122
	v_lshlrev_b32_e32 v79, 16, v103
	v_lshlrev_b32_e32 v78, 16, v102
	v_and_b32_e32 v89, 0xffff0000, v103
	v_and_b32_e32 v88, 0xffff0000, v102
	v_lshlrev_b32_e32 v91, 16, v97
	v_lshlrev_b32_e32 v90, 16, v96
	v_and_b32_e32 v97, 0xffff0000, v97
	v_and_b32_e32 v96, 0xffff0000, v96
	v_add_f32_e32 v122, v76, v77
	v_pk_mul_f32 v[114:115], v[84:85], v[84:85]
	v_lshlrev_b32_e32 v143, 16, v93
	v_lshlrev_b32_e32 v142, 16, v92
	v_and_b32_e32 v93, 0xffff0000, v93
	v_and_b32_e32 v92, 0xffff0000, v92
	v_pk_mul_f32 v[128:129], v[72:73], v[72:73]
	v_pk_mul_f32 v[124:125], v[74:75], v[74:75]
	v_lshlrev_b32_e32 v73, 16, v101
	v_lshlrev_b32_e32 v72, 16, v100
	v_and_b32_e32 v75, 0xffff0000, v101
	v_and_b32_e32 v74, 0xffff0000, v100
	v_lshlrev_b32_e32 v101, 16, v99
	v_lshlrev_b32_e32 v100, 16, v98
	v_add_f32_e32 v120, v120, v141
	v_pk_fma_f32 v[76:77], v[42:43], v[78:79], v[144:145] neg_lo:[1,0,0] neg_hi:[1,0,0]
	v_pk_fma_f32 v[78:79], v[42:43], v[88:89], v[94:95] neg_lo:[1,0,0] neg_hi:[1,0,0]
	v_pk_fma_f32 v[88:89], v[42:43], v[90:91], v[146:147] neg_lo:[1,0,0] neg_hi:[1,0,0]
	v_pk_fma_f32 v[90:91], v[42:43], v[96:97], v[148:149] neg_lo:[1,0,0] neg_hi:[1,0,0]
	v_add_f32_e32 v139, v122, v121
	v_pk_mul_f32 v[112:113], v[86:87], v[86:87]
	v_pk_mul_f32 v[118:119], v[60:61], v[60:61]
	v_pk_fma_f32 v[74:75], v[42:43], v[74:75], v[92:93] neg_lo:[1,0,0] neg_hi:[1,0,0]
	v_pk_fma_f32 v[92:93], v[42:43], v[100:101], v[150:151] neg_lo:[1,0,0] neg_hi:[1,0,0]
	s_waitcnt vmcnt(0) lgkmcnt(0)
; __global__ void __launch_bounds__(NTHR, 2) mk_fwd(Args args) {
;     ...
;                 float ss = 0.f;
; #pragma unroll
;                 for (int i = 0; i < 16; ++i) { a[i] = a[i] - lam * b[i]; ss += a[i] * a[i]; }
;                 ss += __shfl_xor(ss, 1); ss += __shfl_xor(ss, 2); ss += __shfl_xor(ss, 4);
;                 const float rstd = (1.0f - lam_init) / sqrtf(ss * (1.0f / 128.0f) + 1e-6f);
; #pragma unroll
;                 for (int i = 0; i < 16; ++i) a[i] = a[i] * rstd * subln[i];
;                 pack16(p_MIX + (size_t)r * DMODEL + lane * 16, a);
;                 UNP(b, w[q][4], w[q][5]); float s3 = 0.f;
;     ...
; #pragma unroll
;                 for (int i = 0; i < 16; ++i) s3 += b[i] * b[i];
;                 const float r2 = 1.0f / sqrtf(wave_sum(s3) * (1.0f / 1024.0f) + 1e-6f);
	v_lshlrev_b32_e32 v101, 16, v31
	v_lshlrev_b32_e32 v100, 16, v30
	v_and_b32_e32 v31, 0xffff0000, v31
	v_and_b32_e32 v30, 0xffff0000, v30
	v_add_f32_e32 v166, v120, v123
	v_pk_mul_f32 v[144:145], v[88:89], v[88:89]
	v_pk_mul_f32 v[146:147], v[90:91], v[90:91]
	v_add_f32_e32 v114, v139, v114
	v_pk_mul_f32 v[116:117], v[62:63], v[62:63]
	v_pk_mul_f32 v[158:159], v[100:101], v[100:101]
	v_pk_mul_f32 v[160:161], v[30:31], v[30:31]
	v_add_f32_e32 v118, v166, v118
	v_add_f32_e32 v139, v144, v146
	v_add_f32_e32 v112, v114, v112
	v_and_b32_e32 v99, 0xffff0000, v99
	v_and_b32_e32 v98, 0xffff0000, v98
	v_add_f32_e32 v144, v158, v160
	v_add_f32_e32 v114, v118, v116
	v_add_f32_e32 v116, v139, v145
	v_add_f32_e32 v112, v112, v115
	v_pk_mul_f32 v[106:107], v[64:65], v[64:65]
	v_pk_fma_f32 v[94:95], v[42:43], v[98:99], v[152:153] neg_lo:[1,0,0] neg_hi:[1,0,0]
	v_lshlrev_b32_e32 v103, 16, v33
	v_lshlrev_b32_e32 v102, 16, v32
	v_pk_mul_f32 v[148:149], v[92:93], v[92:93]
	v_add_f32_e32 v118, v144, v159
	v_add_f32_e32 v114, v114, v119
	v_add_f32_e32 v115, v116, v147
	v_add_f32_e32 v112, v112, v113
	v_pk_mul_f32 v[104:105], v[66:67], v[66:67]
	v_pk_mul_f32 v[110:111], v[48:49], v[48:49]
	v_and_b32_e32 v33, 0xffff0000, v33
	v_and_b32_e32 v32, 0xffff0000, v32
	v_pk_mul_f32 v[150:151], v[94:95], v[94:95]
	v_pk_mul_f32 v[162:163], v[102:103], v[102:103]
	v_add_f32_e32 v116, v118, v161
	v_add_f32_e32 v113, v114, v117
	v_add_f32_e32 v114, v115, v148
	v_add_f32_e32 v106, v112, v106
	v_pk_mul_f32 v[108:109], v[50:51], v[50:51]
	v_pk_mul_f32 v[164:165], v[32:33], v[32:33]
	v_add_f32_e32 v115, v116, v162
	v_add_f32_e32 v110, v113, v110
	v_add_f32_e32 v112, v114, v150
	v_add_f32_e32 v104, v106, v104
	v_pk_fma_f32 v[72:73], v[42:43], v[72:73], v[142:143] neg_lo:[1,0,0] neg_hi:[1,0,0]
	v_add_f32_e32 v113, v115, v164
	v_add_f32_e32 v106, v110, v108
	v_add_f32_e32 v108, v112, v149
	v_add_f32_e32 v104, v104, v107
	v_lshlrev_b32_e32 v97, 16, v35
	v_lshlrev_b32_e32 v96, 16, v34
	v_pk_mul_f32 v[120:121], v[72:73], v[72:73]
	v_add_f32_e32 v110, v113, v163
	v_add_f32_e32 v106, v106, v111
	v_add_f32_e32 v107, v108, v151
	v_add_f32_e32 v104, v104, v105
	v_and_b32_e32 v35, 0xffff0000, v35
	v_and_b32_e32 v34, 0xffff0000, v34
	v_pk_mul_f32 v[122:123], v[74:75], v[74:75]
	v_pk_mul_f32 v[152:153], v[96:97], v[96:97]
	v_add_f32_e32 v108, v110, v165
	v_add_f32_e32 v105, v106, v109
	v_add_f32_e32 v106, v107, v120
	v_add_f32_e32 v104, v104, v128
	v_pk_mul_f32 v[154:155], v[34:35], v[34:35]
	v_add_f32_e32 v107, v108, v152
	v_fmac_f32_e32 v105, v52, v52
	v_add_f32_e32 v106, v106, v122
	v_add_f32_e32 v104, v104, v129
	v_mov_b32_e32 v140, v76
	v_mov_b32_e32 v141, v78
	v_add_f32_e32 v107, v107, v154
	v_fmac_f32_e32 v105, v54, v54
	v_add_f32_e32 v106, v106, v121
	v_add_f32_e32 v104, v104, v124
	v_pk_mul_f32 v[140:141], v[140:141], v[140:141]
	v_add_f32_e32 v107, v107, v153
	v_add_f32_e32 v105, v105, v126
	v_add_f32_e32 v106, v106, v123
	v_add_f32_e32 v104, v104, v125
	v_lshlrev_b32_e32 v99, 16, v37
	v_lshlrev_b32_e32 v98, 16, v36
	v_and_b32_e32 v37, 0xffff0000, v37
	v_mov_b32_e32 v142, v77
	v_mov_b32_e32 v143, v79
	v_add_f32_e32 v107, v107, v155
	v_add_f32_e32 v105, v105, v127
	v_add_f32_e32 v106, v106, v140
	ds_bpermute_b32 v108, v130, v104
	v_and_b32_e32 v36, 0xffff0000, v36
	v_mov_b32_e32 v156, v99
	v_mov_b32_e32 v157, v37
	v_pk_mul_f32 v[142:143], v[142:143], v[142:143]
	v_fmac_f32_e32 v107, v98, v98
	ds_bpermute_b32 v109, v130, v105
	v_add_f32_e32 v106, v106, v141
	v_pk_mul_f32 v[156:157], v[156:157], v[156:157]
	v_fmac_f32_e32 v107, v36, v36
	v_add_f32_e32 v106, v106, v142
	v_add_f32_e32 v107, v107, v156
	v_add_f32_e32 v106, v106, v143
	v_add_f32_e32 v107, v107, v157
	ds_bpermute_b32 v110, v130, v106
	ds_bpermute_b32 v111, v130, v107
	s_waitcnt lgkmcnt(3)
	v_add_f32_e32 v104, v104, v108
	s_waitcnt lgkmcnt(2)
	v_add_f32_e32 v105, v105, v109
	ds_bpermute_b32 v108, v131, v104
	ds_bpermute_b32 v109, v131, v105
	s_waitcnt lgkmcnt(3)
	v_add_f32_e32 v106, v106, v110
	s_waitcnt lgkmcnt(2)
	v_add_f32_e32 v107, v107, v111
	ds_bpermute_b32 v110, v131, v106
	ds_bpermute_b32 v111, v131, v107
	s_waitcnt lgkmcnt(3)
	v_add_f32_e32 v104, v104, v108
	s_waitcnt lgkmcnt(2)
	v_add_f32_e32 v105, v105, v109
	ds_bpermute_b32 v108, v132, v104
	ds_bpermute_b32 v109, v132, v105
	s_waitcnt lgkmcnt(3)
	v_add_f32_e32 v106, v106, v110
	s_waitcnt lgkmcnt(2)
	v_add_f32_e32 v107, v107, v111
	ds_bpermute_b32 v110, v132, v106
	ds_bpermute_b32 v111, v132, v107
	s_waitcnt lgkmcnt(3)
	v_add_f32_e32 v104, v104, v108
	s_waitcnt lgkmcnt(2)
	v_add_f32_e32 v105, v105, v109
	v_fmamk_f32 v104, v104, 0x3c000000, v136
	ds_bpermute_b32 v108, v133, v105
	v_mul_f32_e32 v109, 0x4f800000, v104
	v_cmp_gt_f32_e32 vcc, s29, v104
	s_waitcnt lgkmcnt(2)
	v_add_f32_e32 v106, v106, v110
	s_waitcnt lgkmcnt(1)
	v_add_f32_e32 v107, v107, v111
	v_cndmask_b32_e32 v104, v104, v109, vcc
	v_sqrt_f32_e32 v109, v104
	v_fmamk_f32 v106, v106, 0x3c000000, v136
	ds_bpermute_b32 v110, v133, v107
	v_mul_f32_e32 v111, 0x4f800000, v106
	v_cmp_gt_f32_e64 s[0:1], s29, v106
	s_waitcnt lgkmcnt(1)
	v_add_f32_e32 v105, v105, v108
	ds_bpermute_b32 v108, v134, v105
	v_cndmask_b32_e64 v106, v106, v111, s[0:1]
	v_sqrt_f32_e32 v111, v106
	v_add_u32_e32 v112, -1, v109
	v_add_u32_e32 v113, 1, v109
	v_fma_f32 v114, -v112, v109, v104
	v_fma_f32 v115, -v113, v109, v104
	v_cmp_ge_f32_e64 s[4:5], 0, v114
	s_waitcnt lgkmcnt(1)
	v_add_f32_e32 v107, v107, v110
	ds_bpermute_b32 v110, v134, v107
	v_cndmask_b32_e64 v109, v109, v112, s[4:5]
	v_cmp_lt_f32_e64 s[4:5], 0, v115
	v_add_u32_e32 v112, -1, v111
	s_waitcnt lgkmcnt(1)
; __global__ void __launch_bounds__(NTHR, 2) mk_fwd(Args args) {
;     ...
;                 for (int i = 0; i < 16; ++i) { a[i] = a[i] - lam * b[i]; ss += a[i] * a[i]; }
;                 ss += __shfl_xor(ss, 1); ss += __shfl_xor(ss, 2); ss += __shfl_xor(ss, 4);
;                 const float rstd = (1.0f - lam_init) / sqrtf(ss * (1.0f / 128.0f) + 1e-6f);
; #pragma unroll
;                 for (int i = 0; i < 16; ++i) a[i] = a[i] * rstd * subln[i];
;                 pack16(p_MIX + (size_t)r * DMODEL + lane * 16, a);
	v_add_f32_e32 v105, v105, v108
	v_cndmask_b32_e64 v109, v109, v113, s[4:5]
	v_add_u32_e32 v113, 1, v111
	v_mul_f32_e32 v114, 0x37800000, v109
	v_fma_f32 v108, -v112, v111, v106
	v_fma_f32 v115, -v113, v111, v106
	v_cndmask_b32_e32 v109, v109, v114, vcc
	ds_bpermute_b32 v114, v135, v105
	v_cmp_ge_f32_e32 vcc, 0, v108
	v_cmp_class_f32_e64 s[4:5], v104, v137
	s_waitcnt lgkmcnt(1)
	v_add_f32_e32 v107, v107, v110
	v_cndmask_b32_e32 v108, v111, v112, vcc
	v_cmp_lt_f32_e32 vcc, 0, v115
	v_cndmask_b32_e64 v104, v109, v104, s[4:5]
	v_div_scale_f32 v109, s[4:5], v104, v104, s30
	v_cndmask_b32_e32 v108, v108, v113, vcc
	v_mul_f32_e32 v112, 0x37800000, v108
	v_rcp_f32_e32 v110, v109
	v_cndmask_b32_e64 v108, v108, v112, s[0:1]
	ds_bpermute_b32 v112, v135, v107
	s_waitcnt lgkmcnt(1)
	v_add_f32_e32 v105, v105, v114
	v_cmp_class_f32_e64 s[0:1], v106, v137
	v_fmamk_f32 v105, v105, 0x3a800000, v136
	v_fma_f32 v115, -v109, v110, 1.0
	v_cndmask_b32_e64 v106, v108, v106, s[0:1]
	v_mul_f32_e32 v116, 0x4f800000, v105
	v_cmp_gt_f32_e64 s[6:7], s29, v105
	v_div_scale_f32 v111, vcc, s30, v104, s30
	v_div_scale_f32 v108, s[0:1], v106, v106, s30
	v_fmac_f32_e32 v110, v115, v110
	v_cndmask_b32_e64 v105, v105, v116, s[6:7]
	v_rcp_f32_e32 v114, v108
	s_waitcnt lgkmcnt(0)
	v_add_f32_e32 v107, v107, v112
	v_mul_f32_e32 v112, v111, v110
	v_sqrt_f32_e32 v115, v105
	v_fmamk_f32 v107, v107, 0x3a800000, v136
	v_fma_f32 v116, -v109, v112, v111
	v_mul_f32_e32 v118, 0x4f800000, v107
	v_cmp_gt_f32_e64 s[4:5], s29, v107
	v_fmac_f32_e32 v112, v116, v110
	v_fma_f32 v109, -v109, v112, v111
	v_cndmask_b32_e64 v107, v107, v118, s[4:5]
	v_fma_f32 v117, -v108, v114, 1.0
	v_sqrt_f32_e32 v116, v107
	v_div_fmas_f32 v109, v109, v110, v112
	v_add_u32_e32 v110, -1, v115
	v_div_scale_f32 v113, s[0:1], s30, v106, s30
	v_fmac_f32_e32 v114, v117, v114
	v_add_u32_e32 v112, 1, v115
	v_div_fixup_f32 v104, v109, v104, s30
	v_fma_f32 v109, -v110, v115, v105
	v_mul_f32_e32 v111, v113, v114
	v_fma_f32 v118, -v112, v115, v105
	v_cmp_ge_f32_e32 vcc, 0, v109
	v_fma_f32 v117, -v108, v111, v113
	v_pk_mul_f32 v[80:81], v[104:105], v[80:81] op_sel_hi:[0,1]
	v_pk_mul_f32 v[82:83], v[104:105], v[82:83] op_sel_hi:[0,1]
	v_pk_mul_f32 v[84:85], v[104:105], v[84:85] op_sel_hi:[0,1]
	v_pk_mul_f32 v[86:87], v[104:105], v[86:87] op_sel_hi:[0,1]
	v_pk_mul_f32 v[64:65], v[104:105], v[64:65] op_sel_hi:[0,1]
	v_pk_mul_f32 v[66:67], v[104:105], v[66:67] op_sel_hi:[0,1]
	v_pk_mul_f32 v[68:69], v[104:105], v[68:69] op_sel_hi:[0,1]
	v_pk_mul_f32 v[70:71], v[104:105], v[70:71] op_sel_hi:[0,1]
	v_cndmask_b32_e32 v104, v115, v110, vcc
	v_cmp_lt_f32_e32 vcc, 0, v118
	v_fmac_f32_e32 v111, v117, v114
	v_pk_mul_f32 v[80:81], v[80:81], v[12:13]
	v_pk_mul_f32 v[84:85], v[84:85], v[8:9]
	v_pk_mul_f32 v[86:87], v[86:87], v[14:15]
	v_pk_mul_f32 v[66:67], v[66:67], v[44:45]
	v_pk_mul_f32 v[68:69], v[68:69], v[4:5]
	v_cndmask_b32_e32 v104, v104, v112, vcc
	v_add_u32_e32 v109, -1, v116
	v_fma_f32 v108, -v108, v111, v113
	v_pk_mul_f32 v[82:83], v[82:83], v[6:7]
	v_pk_mul_f32 v[64:65], v[64:65], v[0:1]
	v_add_u32_e32 v110, 1, v116
	v_bfe_u32 v113, v86, 16, 1
	v_bfe_u32 v118, v80, 16, 1
	v_bfe_u32 v119, v81, 16, 1
	v_bfe_u32 v120, v84, 16, 1
	v_bfe_u32 v121, v85, 16, 1
	v_bfe_u32 v124, v67, 16, 1
	v_bfe_u32 v128, v68, 16, 1
	v_mul_f32_e32 v139, 0x37800000, v104
	v_fma_f32 v140, -v109, v116, v107
	v_pk_mul_f32 v[70:71], v[70:71], v[2:3]
	v_bfe_u32 v112, v87, 16, 1
	v_bfe_u32 v115, v83, 16, 1
	v_bfe_u32 v117, v82, 16, 1
	v_bfe_u32 v125, v66, 16, 1
	v_bfe_u32 v126, v64, 16, 1
	v_bfe_u32 v127, v65, 16, 1
	v_bfe_u32 v129, v69, 16, 1
	v_fma_f32 v141, -v110, v116, v107
	v_add3_u32 v86, v86, v113, s31
	v_add3_u32 v85, v85, v121, s31
	v_add3_u32 v84, v84, v120, s31
	v_add3_u32 v81, v81, v119, s31
	v_add3_u32 v80, v80, v118, s31
	v_add3_u32 v113, v67, v124, s31
	v_add3_u32 v67, v68, v128, s31
	v_cndmask_b32_e64 v68, v104, v139, s[6:7]
	v_cmp_class_f32_e32 vcc, v105, v137
	v_cmp_ge_f32_e64 s[6:7], 0, v140
	v_bfe_u32 v122, v71, 16, 1
	v_bfe_u32 v123, v70, 16, 1
	v_add3_u32 v82, v82, v117, s31
	v_add3_u32 v83, v83, v115, s31
	v_add3_u32 v87, v87, v112, s31
	v_add3_u32 v112, v66, v125, s31
	v_add3_u32 v66, v69, v129, s31
	v_add3_u32 v65, v65, v127, s31
	v_add3_u32 v64, v64, v126, s31
	v_cndmask_b32_e64 v69, v116, v109, s[6:7]
	v_cmp_lt_f32_e64 s[6:7], 0, v141
	v_lshrrev_b32_e32 v80, 16, v80
	v_lshrrev_b32_e32 v81, 16, v81
	v_lshrrev_b32_e32 v84, 16, v84
	v_lshrrev_b32_e32 v85, 16, v85
	v_cndmask_b32_e32 v105, v68, v105, vcc
	v_add3_u32 v70, v70, v123, s31
	v_add3_u32 v71, v71, v122, s31
	v_lshrrev_b32_e32 v104, 16, v64
	v_lshrrev_b32_e32 v109, 16, v65
	v_lshrrev_b32_e32 v115, 16, v67
	v_lshrrev_b32_e32 v116, 16, v66
	v_cndmask_b32_e64 v110, v69, v110, s[6:7]
	v_and_or_b32 v67, v87, s28, v85
	v_and_or_b32 v66, v86, s28, v84
	v_and_or_b32 v65, v83, s28, v81
	v_and_or_b32 v64, v82, s28, v80
	v_div_scale_f32 v80, s[6:7], v105, v105, 1.0
	v_and_or_b32 v71, v71, s28, v116
	v_and_or_b32 v70, v70, s28, v115
	v_and_or_b32 v69, v113, s28, v109
	v_and_or_b32 v68, v112, s28, v104
	v_mul_f32_e32 v82, 0x37800000, v110
	global_store_dwordx4 v[46:47], v[64:67], off
	global_store_dwordx4 v[46:47], v[68:71], off offset:16
	v_div_scale_f32 v81, vcc, 1.0, v105, 1.0
	v_rcp_f32_e32 v64, v80
	v_cndmask_b32_e64 v65, v110, v82, s[4:5]
	v_cmp_class_f32_e64 s[4:5], v107, v137
	ds_read_b64 v[46:47], v138
	v_fma_f32 v67, -v80, v64, 1.0
	v_cndmask_b32_e64 v82, v65, v107, s[4:5]
	v_div_scale_f32 v65, s[4:5], v82, v82, 1.0
	v_rcp_f32_e32 v83, v65
	v_fmac_f32_e32 v64, v67, v64
	v_mul_f32_e32 v67, v81, v64
	v_fma_f32 v68, -v80, v67, v81
	v_fma_f32 v69, -v65, v83, 1.0
	v_fmac_f32_e32 v67, v68, v64
	v_div_scale_f32 v66, s[4:5], 1.0, v82, 1.0
	v_fmac_f32_e32 v83, v69, v83
	v_fma_f32 v68, -v80, v67, v81
	v_mul_f32_e32 v84, v66, v83
	v_div_fmas_f32 v64, v68, v64, v67
	v_fma_f32 v67, -v65, v84, v66
	v_div_fixup_f32 v64, v64, v105, 1.0
	s_mov_b64 vcc, s[0:1]
	v_div_fmas_f32 v68, v108, v114, v111
	v_fmac_f32_e32 v84, v67, v83
	v_pk_mul_f32 v[56:57], v[64:65], v[56:57] op_sel_hi:[0,1]
	v_pk_mul_f32 v[58:59], v[64:65], v[58:59] op_sel_hi:[0,1]
	v_pk_mul_f32 v[60:61], v[64:65], v[60:61] op_sel_hi:[0,1]
	s_waitcnt lgkmcnt(0)
; __global__ void __launch_bounds__(NTHR, 2) mk_fwd(Args args) {
;     ...
;                 const float rstd = (1.0f - lam_init) / sqrtf(ss * (1.0f / 128.0f) + 1e-6f);
; #pragma unroll
;                 for (int i = 0; i < 16; ++i) a[i] = a[i] * rstd * subln[i];
;                 pack16(p_MIX + (size_t)r * DMODEL + lane * 16, a);
;                 UNP(b, w[q][4], w[q][5]); float s3 = 0.f;
;     ...
; #pragma unroll
;                 for (int i = 0; i < 16; ++i) s3 += b[i] * b[i];
;                 const float r2 = 1.0f / sqrtf(wave_sum(s3) * (1.0f / 1024.0f) + 1e-6f);
; #pragma unroll
;                 for (int i = 0; i < 16; ++i) b[i] = b[i] * r2 * ogn[i];
;                 pack16(p_MIX + (size_t)r * DMODEL + 1024 + lane * 16, b); }
	v_readfirstlane_b32 s6, v46
	v_readfirstlane_b32 s7, v47
	v_pk_mul_f32 v[62:63], v[64:65], v[62:63] op_sel_hi:[0,1]
	v_pk_mul_f32 v[48:49], v[64:65], v[48:49] op_sel_hi:[0,1]
	v_pk_mul_f32 v[50:51], v[64:65], v[50:51] op_sel_hi:[0,1]
	v_pk_mul_f32 v[52:53], v[64:65], v[52:53] op_sel_hi:[0,1]
	v_pk_mul_f32 v[54:55], v[64:65], v[54:55] op_sel_hi:[0,1]
	v_div_fixup_f32 v64, v68, v106, s30
	v_fma_f32 v85, -v65, v84, v66
	v_pk_mul_f32 v[56:57], v[56:57], v[24:25]
	v_pk_mul_f32 v[58:59], v[58:59], v[22:23]
	v_pk_mul_f32 v[60:61], v[60:61], v[28:29]
	s_mov_b64 vcc, s[4:5]
	v_lshl_add_u64 v[46:47], s[6:7], 0, v[40:41]
	v_pk_mul_f32 v[62:63], v[62:63], v[26:27]
	v_pk_mul_f32 v[48:49], v[48:49], v[16:17]
	v_pk_mul_f32 v[50:51], v[50:51], v[10:11]
	v_pk_mul_f32 v[52:53], v[52:53], v[20:21]
	v_pk_mul_f32 v[54:55], v[54:55], v[18:19]
	v_pk_mul_f32 v[66:67], v[64:65], v[88:89] op_sel_hi:[0,1]
	v_pk_mul_f32 v[68:69], v[64:65], v[90:91] op_sel_hi:[0,1]
	v_pk_mul_f32 v[80:81], v[64:65], v[94:95] op_sel_hi:[0,1]
	v_div_fmas_f32 v83, v85, v83, v84
	v_bfe_u32 v86, v59, 16, 1
	v_bfe_u32 v87, v58, 16, 1
	v_bfe_u32 v88, v56, 16, 1
	v_bfe_u32 v89, v57, 16, 1
	v_bfe_u32 v90, v60, 16, 1
	v_bfe_u32 v91, v61, 16, 1
	v_lshl_add_u64 v[46:47], v[46:47], 0, s[12:13]
	v_pk_mul_f32 v[70:71], v[64:65], v[92:93] op_sel_hi:[0,1]
	v_pk_mul_f32 v[72:73], v[64:65], v[72:73] op_sel_hi:[0,1]
	v_pk_mul_f32 v[74:75], v[64:65], v[74:75] op_sel_hi:[0,1]
	v_pk_mul_f32 v[76:77], v[64:65], v[76:77] op_sel_hi:[0,1]
	v_pk_mul_f32 v[64:65], v[64:65], v[78:79] op_sel_hi:[0,1]
	v_bfe_u32 v84, v63, 16, 1
	v_bfe_u32 v85, v62, 16, 1
	v_bfe_u32 v92, v55, 16, 1
	v_bfe_u32 v93, v54, 16, 1
	v_bfe_u32 v94, v51, 16, 1
	v_bfe_u32 v95, v50, 16, 1
	v_bfe_u32 v104, v48, 16, 1
	v_bfe_u32 v105, v49, 16, 1
	v_bfe_u32 v106, v52, 16, 1
	v_bfe_u32 v107, v53, 16, 1
	v_pk_mul_f32 v[78:79], v[80:81], v[14:15]
	v_div_fixup_f32 v80, v83, v82, 1.0
	v_add3_u32 v81, v58, v87, s31
	v_add3_u32 v82, v59, v86, s31
	v_add3_u32 v58, v61, v91, s31
	v_add3_u32 v59, v60, v90, s31
	v_add3_u32 v57, v57, v89, s31
	v_add3_u32 v56, v56, v88, s31
	v_add_co_u32_e64 v46, s[6:7], s33, v46
	v_pk_mul_f32 v[66:67], v[66:67], v[12:13]
	v_pk_mul_f32 v[68:69], v[68:69], v[6:7]
	v_pk_mul_f32 v[70:71], v[70:71], v[8:9]
	v_add3_u32 v83, v62, v85, s31
	v_add3_u32 v84, v63, v84, s31
	v_add3_u32 v85, v50, v95, s31
	v_add3_u32 v86, v51, v94, s31
	v_add3_u32 v87, v54, v93, s31
	v_add3_u32 v88, v55, v92, s31
	v_add3_u32 v60, v53, v107, s31
	v_add3_u32 v61, v52, v106, s31
	v_add3_u32 v62, v49, v105, s31
	v_add3_u32 v63, v48, v104, s31
	v_pk_mul_f32 v[48:49], v[80:81], v[100:101] op_sel_hi:[0,1]
	v_pk_mul_f32 v[30:31], v[80:81], v[30:31] op_sel_hi:[0,1]
	v_pk_mul_f32 v[50:51], v[80:81], v[102:103] op_sel_hi:[0,1]
	v_pk_mul_f32 v[32:33], v[80:81], v[32:33] op_sel_hi:[0,1]
	v_pk_mul_f32 v[52:53], v[80:81], v[96:97] op_sel_hi:[0,1]
	v_pk_mul_f32 v[34:35], v[80:81], v[34:35] op_sel_hi:[0,1]
	v_pk_mul_f32 v[54:55], v[80:81], v[98:99] op_sel_hi:[0,1]
	v_pk_mul_f32 v[36:37], v[80:81], v[36:37] op_sel_hi:[0,1]
	v_lshrrev_b32_e32 v80, 16, v56
	v_lshrrev_b32_e32 v96, 16, v57
	v_lshrrev_b32_e32 v97, 16, v59
	v_lshrrev_b32_e32 v98, 16, v58
	v_addc_co_u32_e64 v47, s[6:7], 0, v47, s[6:7]
	v_bfe_u32 v89, v79, 16, 1
	v_bfe_u32 v90, v78, 16, 1
	v_bfe_u32 v91, v69, 16, 1
	v_bfe_u32 v94, v67, 16, 1
	v_bfe_u32 v95, v70, 16, 1
	v_lshrrev_b32_e32 v99, 16, v63
	v_lshrrev_b32_e32 v100, 16, v62
	v_lshrrev_b32_e32 v101, 16, v61
	v_lshrrev_b32_e32 v102, 16, v60
	v_pk_mul_f32 v[56:57], v[30:31], v[22:23]
	v_pk_mul_f32 v[58:59], v[32:33], v[26:27]
	v_pk_mul_f32 v[60:61], v[34:35], v[10:11]
	v_pk_mul_f32 v[54:55], v[54:55], v[20:21]
	v_pk_mul_f32 v[62:63], v[36:37], v[18:19]
	v_and_or_b32 v33, v84, s28, v98
	v_and_or_b32 v32, v83, s28, v97
	v_and_or_b32 v31, v82, s28, v96
	v_and_or_b32 v30, v81, s28, v80
	v_add3_u32 v69, v69, v91, s31
	v_add3_u32 v78, v78, v90, s31
	v_add3_u32 v79, v79, v89, s31
	v_add3_u32 v70, v70, v95, s31
	v_add3_u32 v67, v67, v94, s31
	v_and_or_b32 v37, v88, s28, v102
	v_and_or_b32 v36, v87, s28, v101
	v_and_or_b32 v35, v86, s28, v100
	v_and_or_b32 v34, v85, s28, v99
	v_bfe_u32 v80, v59, 16, 1
	v_bfe_u32 v81, v58, 16, 1
	v_bfe_u32 v82, v57, 16, 1
	v_bfe_u32 v83, v56, 16, 1
	v_bfe_u32 v88, v63, 16, 1
	v_bfe_u32 v89, v62, 16, 1
	v_bfe_u32 v90, v61, 16, 1
	v_bfe_u32 v91, v60, 16, 1
	v_bfe_u32 v94, v54, 16, 1
	v_bfe_u32 v95, v55, 16, 1
	global_store_dwordx4 v[46:47], v[30:33], off offset:2048
	global_store_dwordx4 v[46:47], v[34:37], off offset:2064
	v_add3_u32 v46, v56, v83, s31
	v_add3_u32 v47, v57, v82, s31
	v_add3_u32 v56, v58, v81, s31
	v_add3_u32 v57, v59, v80, s31
	v_add3_u32 v58, v60, v91, s31
	v_add3_u32 v59, v61, v90, s31
	v_add3_u32 v60, v62, v89, s31
	v_add3_u32 v61, v63, v88, s31
	v_add3_u32 v62, v55, v95, s31
	v_add3_u32 v63, v54, v94, s31
	ds_read_b64 v[54:55], v138
	v_pk_mul_f32 v[76:77], v[76:77], v[4:5]
	v_pk_mul_f32 v[64:65], v[64:65], v[2:3]
	v_bfe_u32 v111, v76, 16, 1
	v_bfe_u32 v112, v77, 16, 1
	v_pk_mul_f32 v[48:49], v[48:49], v[24:25]
	v_pk_mul_f32 v[50:51], v[50:51], v[28:29]
	s_waitcnt lgkmcnt(0)
; __global__ void __launch_bounds__(NTHR, 2) mk_fwd(Args args) {
;     ...
; #pragma unroll
;                 for (int i = 0; i < 16; ++i) a[i] = a[i] * rstd * subln[i];
;                 pack16(p_MIX + (size_t)r * DMODEL + lane * 16, a);
;                 UNP(b, w[q][4], w[q][5]); float s3 = 0.f;
;     ...
; #pragma unroll
;                 for (int i = 0; i < 16; ++i) s3 += b[i] * b[i];
;                 const float r2 = 1.0f / sqrtf(wave_sum(s3) * (1.0f / 1024.0f) + 1e-6f);
; #pragma unroll
;                 for (int i = 0; i < 16; ++i) b[i] = b[i] * r2 * ogn[i];
;                 pack16(p_MIX + (size_t)r * DMODEL + 1024 + lane * 16, b); }
;         }
	v_readfirstlane_b32 s0, v54
	v_bfe_u32 v105, v65, 16, 1
	v_bfe_u32 v106, v64, 16, 1
	v_add3_u32 v77, v77, v112, s31
	v_add3_u32 v76, v76, v111, s31
	v_bfe_u32 v84, v48, 16, 1
	v_bfe_u32 v85, v49, 16, 1
	v_bfe_u32 v86, v50, 16, 1
	v_bfe_u32 v87, v51, 16, 1
	v_readfirstlane_b32 s1, v55
	s_add_u32 s0, s0, s24
	v_pk_mul_f32 v[72:73], v[72:73], v[0:1]
	v_bfe_u32 v93, v66, 16, 1
	v_bfe_u32 v104, v71, 16, 1
	v_add3_u32 v64, v64, v106, s31
	v_add3_u32 v65, v65, v105, s31
	v_lshrrev_b32_e32 v76, 16, v76
	v_lshrrev_b32_e32 v77, 16, v77
	v_add3_u32 v51, v51, v87, s31
	v_add3_u32 v50, v50, v86, s31
	v_add3_u32 v49, v49, v85, s31
	v_add3_u32 v48, v48, v84, s31
	s_addc_u32 s1, s1, s25
	v_pk_mul_f32 v[74:75], v[74:75], v[44:45]
	v_bfe_u32 v92, v68, 16, 1
	v_bfe_u32 v109, v72, 16, 1
	v_bfe_u32 v110, v73, 16, 1
	v_add3_u32 v71, v71, v104, s31
	v_add3_u32 v66, v66, v93, s31
	v_and_or_b32 v37, v65, s28, v77
	v_and_or_b32 v36, v64, s28, v76
	v_lshrrev_b32_e32 v64, 16, v48
	v_lshrrev_b32_e32 v65, 16, v49
	v_lshrrev_b32_e32 v48, 16, v50
	v_lshrrev_b32_e32 v49, 16, v51
	v_lshl_add_u64 v[54:55], s[0:1], 0, v[40:41]
	v_bfe_u32 v107, v75, 16, 1
	v_bfe_u32 v108, v74, 16, 1
	v_add3_u32 v68, v68, v92, s31
	v_add3_u32 v73, v73, v110, s31
	v_add3_u32 v72, v72, v109, s31
	v_lshrrev_b32_e32 v66, 16, v66
	v_lshrrev_b32_e32 v67, 16, v67
	v_lshrrev_b32_e32 v70, 16, v70
	v_lshrrev_b32_e32 v71, 16, v71
	v_and_or_b32 v49, v57, s28, v49
	v_and_or_b32 v48, v56, s28, v48
	v_lshl_add_u64 v[56:57], v[54:55], 0, s[20:21]
	v_add_co_u32_e32 v54, vcc, s33, v54
	v_add3_u32 v74, v74, v108, s31
	v_add3_u32 v75, v75, v107, s31
	v_lshrrev_b32_e32 v72, 16, v72
	v_lshrrev_b32_e32 v73, 16, v73
	v_and_or_b32 v33, v79, s28, v71
	v_and_or_b32 v32, v78, s28, v70
	v_and_or_b32 v31, v69, s28, v67
	v_and_or_b32 v30, v68, s28, v66
	v_addc_co_u32_e32 v55, vcc, 0, v55, vcc
	v_and_or_b32 v35, v75, s28, v73
	v_and_or_b32 v34, v74, s28, v72
	global_store_dwordx4 v[54:55], v[30:33], off
	global_store_dwordx4 v[56:57], v[34:37], off offset:16
	ds_read_b64 v[30:31], v138
	v_pk_mul_f32 v[52:53], v[52:53], v[16:17]
	v_and_or_b32 v47, v47, s28, v65
	v_bfe_u32 v92, v52, 16, 1
	v_bfe_u32 v93, v53, 16, 1
	s_waitcnt lgkmcnt(0)
	v_readfirstlane_b32 s0, v30
	v_readfirstlane_b32 s1, v31
	s_add_u32 s0, s0, s24
	s_addc_u32 s1, s1, s25
	s_add_i32 s72, s72, s10
	s_add_u32 s12, s12, s16
	s_addc_u32 s13, s13, s17
	v_add3_u32 v53, v53, v93, s31
	v_add3_u32 v52, v52, v92, s31
	v_lshl_add_u64 v[30:31], s[0:1], 0, v[40:41]
	s_add_u32 s14, s14, s18
	v_lshrrev_b32_e32 v50, 16, v52
	v_lshrrev_b32_e32 v51, 16, v53
	v_lshrrev_b32_e32 v52, 16, v63
	v_lshrrev_b32_e32 v53, 16, v62
	v_lshl_add_u64 v[32:33], v[30:31], 0, s[22:23]
	v_add_co_u32_e32 v30, vcc, s33, v30
	s_addc_u32 s15, s15, s19
	v_and_or_b32 v46, v46, s28, v64
	v_and_or_b32 v53, v61, s28, v53
	v_and_or_b32 v52, v60, s28, v52
	v_and_or_b32 v51, v59, s28, v51
	v_and_or_b32 v50, v58, s28, v50
	v_addc_co_u32_e32 v31, vcc, 0, v31, vcc
	s_cmpk_lt_i32 s72, 0x4000
	global_store_dwordx4 v[32:33], v[50:53], off offset:16
	global_store_dwordx4 v[30:31], v[46:49], off offset:2048
	s_cbranch_scc1 .LBB0_1235

; __device__ __forceinline__ unsigned cvt_pk_bf16(float lo, float hi) { unsigned r; asm volatile("v_cvt_pk_bf16_f32 %0, %1, %2" : "=v"(r) : "v"(lo), "v"(hi)); return r; }
;     __device__ __forceinline__ void operator()(const f32x4 (&acc)[2][2][4][2], const Unit& u, int wr, int wc, int fr_, int fq_) const {
;     ...
;         for (int mh = 0; mh < 2; ++mh) {
;             f32x4 bs[2][2][2];
; #pragma unroll
;             for (int m = 0; m < 2; ++m) { const size_t off = (size_t)(row0 + ai * HALF + (2 * mh + m) * 16) * ldc + col0;
; #pragma unroll
;                 for (int bj = 0; bj < 2; ++bj)
; #pragma unroll
;                     for (int n = 0; n < 2; ++n) bs[m][bj][n] = *(const f32x4*)(base + off + bj * HALF + n * 16); }
;             asm volatile("" ::: "memory");
; #pragma unroll
;             for (int m = 0; m < 2; ++m) { const int row = row0 + ai * HALF + (2 * mh + m) * 16; const size_t off = (size_t)row * ldc + col0; float ss = 0.f;
; #pragma unroll
;                 for (int bj = 0; bj < 2; ++bj)
; #pragma unroll
;                     for (int n = 0; n < 2; ++n) { const f32x4 o = bs[m][bj][n] + gv[bj][n] * acc[ai][bj][2 * mh + m][n]; *(f32x4*)(out + off + bj * HALF + n * 16) = o;
;                         if constexpr (EMIT) { ss += (o[0] * o[0] + o[1] * o[1]) + (o[2] * o[2] + o[3] * o[3]); const f32x4 y = o * gm[bj][n];
;                             typedef unsigned u32x2_t __attribute__((ext_vector_type(2))); u32x2_t w; w.x = cvt_pk_bf16(y[0], y[1]); w.y = cvt_pk_bf16(y[2], y[3]); *(u32x2_t*)(A2 + off + bj * HALF + n * 16) = w; } }
;                 if constexpr (EMIT) { ss += __shfl_xor(ss, 16); ss += __shfl_xor(ss, 32); if (fq == 0) atomicAdd(ssq + row, (unsigned long long)(ss * 16777216.0f)); } }
.LBB0_1307:
	v_mbcnt_lo_u32_b32 v203, -1, 0
	v_mbcnt_hi_u32_b32 v203, -1, v203
	s_lshl_b32 s4, s4, 8
	v_ashrrev_i32_e32 v64, 2, v203
	s_lshl_b32 s5, s34, 8
	s_or_b32 s4, s4, s50
	v_and_b32_e32 v64, -4, v64
	s_add_i32 s5, s5, s49
	v_add_u32_e32 v188, s4, v64
	v_ashrrev_i32_e32 v189, 31, v188
	v_and_or_b32 v192, v203, 15, s5
	v_lshlrev_b64 v[64:65], 2, v[188:189]
	v_ashrrev_i32_e32 v193, 31, v192
	v_lshl_add_u64 v[190:191], s[8:9], 0, v[64:65]
	v_lshlrev_b64 v[72:73], 13, v[192:193]
	v_lshl_add_u64 v[220:221], v[190:191], 0, v[72:73]
	v_lshl_add_u64 v[66:67], s[12:13], 0, v[64:65]
	global_load_dwordx4 v[204:207], v[220:221], off
	global_load_dwordx4 v[104:107], v[66:67], off
	global_load_dwordx4 v[92:95], v[66:67], off offset:64
	global_load_dwordx4 v[208:211], v[220:221], off offset:64
	global_load_dwordx4 v[212:215], v[220:221], off offset:512
	global_load_dwordx4 v[84:87], v[66:67], off offset:512
	global_load_dwordx4 v[72:75], v[66:67], off offset:576
	global_load_dwordx4 v[216:219], v[220:221], off offset:576
	v_lshl_add_u64 v[64:65], s[16:17], 0, v[64:65]
	global_load_dwordx4 v[100:103], v[64:65], off
	global_load_dwordx4 v[88:91], v[64:65], off offset:64
	global_load_dwordx4 v[80:83], v[64:65], off offset:512
	s_nop 0
	global_load_dwordx4 v[64:67], v[64:65], off offset:576
	v_or_b32_e32 v194, 16, v192
	v_ashrrev_i32_e32 v195, 31, v194
	v_lshlrev_b64 v[160:161], 13, v[194:195]
	v_lshl_add_u64 v[196:197], v[190:191], 0, v[160:161]
	global_load_dwordx4 v[172:175], v[196:197], off
	global_load_dwordx4 v[168:171], v[196:197], off offset:64
	global_load_dwordx4 v[164:167], v[196:197], off offset:512
	global_load_dwordx4 v[160:163], v[196:197], off offset:576
	v_and_b32_e32 v223, 64, v202
	v_xor_b32_e32 v222, 16, v202
	v_add_u32_e32 v224, 64, v223
	v_cmp_lt_i32_e64 s[4:5], v222, v224
	v_cmp_gt_u32_e32 vcc, 16, v203
	s_waitcnt vmcnt(0) lgkmcnt(0)
	v_pk_fma_f32 v[158:159], v[158:159], v[106:107], v[206:207]
	v_cndmask_b32_e64 v203, v202, v222, s[4:5]
	v_lshlrev_b64 v[222:223], 11, v[192:193]
	v_pk_fma_f32 v[156:157], v[156:157], v[104:105], v[204:205]
	v_pk_fma_f32 v[154:155], v[154:155], v[94:95], v[210:211]
	v_pk_fma_f32 v[152:153], v[152:153], v[92:93], v[208:209]
	v_lshl_add_u64 v[222:223], v[222:223], 0, v[188:189]
	v_pk_fma_f32 v[150:151], v[150:151], v[86:87], v[214:215]
	v_pk_fma_f32 v[148:149], v[148:149], v[84:85], v[212:213]
	v_pk_fma_f32 v[206:207], v[146:147], v[74:75], v[218:219]
	v_pk_fma_f32 v[204:205], v[144:145], v[72:73], v[216:217]
	global_store_dwordx4 v[220:221], v[156:159], off
	v_mul_f32_e32 v218, v157, v157
	v_mul_f32_e32 v219, v159, v159
	v_pk_mul_f32 v[144:145], v[102:103], v[158:159]
	v_pk_mul_f32 v[146:147], v[100:101], v[156:157]
	v_mul_f32_e32 v157, v153, v153
	v_mul_f32_e32 v159, v155, v155
	v_lshl_add_u64 v[222:223], v[222:223], 1, s[14:15]
	v_mul_f32_e32 v225, v149, v149
	v_mul_f32_e32 v226, v151, v151
	v_fmac_f32_e32 v218, v156, v156
	v_fmac_f32_e32 v219, v158, v158
	v_cvt_pk_bf16_f32 v146, v146, v147
	v_cvt_pk_bf16_f32 v147, v144, v145
	v_fmac_f32_e32 v157, v152, v152
	v_fmac_f32_e32 v159, v154, v154
	v_mul_f32_e32 v227, v205, v205
	v_mul_f32_e32 v228, v207, v207
	v_fmac_f32_e32 v225, v148, v148
	v_fmac_f32_e32 v226, v150, v150
	v_add_f32_e32 v156, v218, v219
	global_store_dwordx2 v[222:223], v[146:147], off
	global_store_dwordx4 v[220:221], v[152:155], off offset:64
	v_add_f32_e32 v146, v157, v159
	v_pk_mul_f32 v[208:209], v[90:91], v[154:155]
	v_pk_mul_f32 v[210:211], v[88:89], v[152:153]
	v_fmac_f32_e32 v227, v204, v204
	v_fmac_f32_e32 v228, v206, v206
	v_cvt_pk_bf16_f32 v144, v210, v211
	v_cvt_pk_bf16_f32 v145, v208, v209
	v_add_f32_e32 v147, v225, v226
	v_add_f32_e32 v146, v156, v146
	v_add_f32_e32 v152, v227, v228
	global_store_dwordx2 v[222:223], v[144:145], off offset:32
	global_store_dwordx4 v[220:221], v[148:151], off offset:512
	v_add_f32_e32 v144, v146, v147
	v_lshlrev_b32_e32 v203, 2, v203
	v_add_f32_e32 v146, v144, v152
	ds_bpermute_b32 v147, v203, v146
	v_pk_mul_f32 v[212:213], v[82:83], v[150:151]
	v_pk_mul_f32 v[214:215], v[80:81], v[148:149]
	v_pk_mul_f32 v[216:217], v[66:67], v[206:207]
	v_cvt_pk_bf16_f32 v144, v214, v215
	v_cvt_pk_bf16_f32 v145, v212, v213
	global_store_dwordx2 v[222:223], v[144:145], off offset:256
	global_store_dwordx4 v[220:221], v[204:207], off offset:576
	v_xor_b32_e32 v145, 32, v202
	v_cmp_lt_i32_e64 s[4:5], v145, v224
	s_waitcnt lgkmcnt(0)
	v_add_f32_e32 v144, v146, v147
	v_pk_mul_f32 v[146:147], v[64:65], v[204:205]
	v_cndmask_b32_e64 v145, v202, v145, s[4:5]
	v_lshlrev_b32_e32 v150, 2, v145
	ds_bpermute_b32 v145, v150, v144
	v_cvt_pk_bf16_f32 v146, v146, v147
	v_cvt_pk_bf16_f32 v147, v216, v217
	global_store_dwordx2 v[222:223], v[146:147], off offset:288
	s_and_saveexec_b64 s[4:5], vcc
	s_cbranch_execz .LBB0_1309
	s_waitcnt lgkmcnt(0)
	v_add_f32_e32 v144, v144, v145
	v_mul_f32_e32 v144, 0x4b800000, v144
	v_trunc_f32_e32 v144, v144
	v_mul_f32_e32 v145, 0x2f800000, v144
	v_floor_f32_e32 v145, v145
	v_fmac_f32_e32 v144, 0xcf800000, v145
	v_cvt_u32_f32_e32 v144, v144
	v_cvt_u32_f32_e32 v145, v145
	v_lshl_add_u64 v[146:147], v[192:193], 3, s[18:19]
	global_atomic_add_x2 v[146:147], v[144:145], off
; __device__ __forceinline__ unsigned cvt_pk_bf16(float lo, float hi) { unsigned r; asm volatile("v_cvt_pk_bf16_f32 %0, %1, %2" : "=v"(r) : "v"(lo), "v"(hi)); return r; }
;     __device__ __forceinline__ void operator()(const f32x4 (&acc)[2][2][4][2], const Unit& u, int wr, int wc, int fr_, int fq_) const {
;     ...
;             for (int m = 0; m < 2; ++m) { const size_t off = (size_t)(row0 + ai * HALF + (2 * mh + m) * 16) * ldc + col0;
; #pragma unroll
;                 for (int bj = 0; bj < 2; ++bj)
; #pragma unroll
;                     for (int n = 0; n < 2; ++n) bs[m][bj][n] = *(const f32x4*)(base + off + bj * HALF + n * 16); }
;             asm volatile("" ::: "memory");
; #pragma unroll
;             for (int m = 0; m < 2; ++m) { const int row = row0 + ai * HALF + (2 * mh + m) * 16; const size_t off = (size_t)row * ldc + col0; float ss = 0.f;
; #pragma unroll
;                 for (int bj = 0; bj < 2; ++bj)
; #pragma unroll
;                     for (int n = 0; n < 2; ++n) { const f32x4 o = bs[m][bj][n] + gv[bj][n] * acc[ai][bj][2 * mh + m][n]; *(f32x4*)(out + off + bj * HALF + n * 16) = o;
;                         if constexpr (EMIT) { ss += (o[0] * o[0] + o[1] * o[1]) + (o[2] * o[2] + o[3] * o[3]); const f32x4 y = o * gm[bj][n];
;                             typedef unsigned u32x2_t __attribute__((ext_vector_type(2))); u32x2_t w; w.x = cvt_pk_bf16(y[0], y[1]); w.y = cvt_pk_bf16(y[2], y[3]); *(u32x2_t*)(A2 + off + bj * HALF + n * 16) = w; } }
;                 if constexpr (EMIT) { ss += __shfl_xor(ss, 16); ss += __shfl_xor(ss, 32); if (fq == 0) atomicAdd(ssq + row, (unsigned long long)(ss * 16777216.0f)); } }
.LBB0_1309:
	s_or_b64 exec, exec, s[4:5]
	v_pk_fma_f32 v[142:143], v[142:143], v[106:107], v[174:175]
	v_pk_fma_f32 v[140:141], v[140:141], v[104:105], v[172:173]
	s_waitcnt lgkmcnt(0)
	v_lshlrev_b64 v[144:145], 11, v[194:195]
	v_mul_f32_e32 v146, v141, v141
	v_mul_f32_e32 v147, v143, v143
	v_lshl_add_u64 v[144:145], v[144:145], 0, v[188:189]
	global_store_dwordx4 v[196:197], v[140:143], off
	v_fmac_f32_e32 v146, v140, v140
	v_fmac_f32_e32 v147, v142, v142
	v_pk_mul_f32 v[142:143], v[102:103], v[142:143]
	v_pk_mul_f32 v[140:141], v[100:101], v[140:141]
	v_pk_fma_f32 v[136:137], v[136:137], v[92:93], v[168:169]
	v_cvt_pk_bf16_f32 v140, v140, v141
	v_cvt_pk_bf16_f32 v141, v142, v143
	v_lshl_add_u64 v[142:143], v[144:145], 1, s[14:15]
	global_store_dwordx2 v[142:143], v[140:141], off
	v_pk_fma_f32 v[138:139], v[138:139], v[94:95], v[170:171]
	v_mul_f32_e32 v140, v137, v137
	global_store_dwordx4 v[196:197], v[136:139], off offset:64
	v_fmac_f32_e32 v140, v136, v136
	v_mul_f32_e32 v141, v139, v139
	v_pk_mul_f32 v[136:137], v[88:89], v[136:137]
	v_fmac_f32_e32 v141, v138, v138
	v_pk_mul_f32 v[138:139], v[90:91], v[138:139]
	v_cvt_pk_bf16_f32 v136, v136, v137
	v_pk_fma_f32 v[134:135], v[134:135], v[86:87], v[166:167]
	v_cvt_pk_bf16_f32 v137, v138, v139
	v_pk_fma_f32 v[132:133], v[132:133], v[84:85], v[164:165]
	global_store_dwordx2 v[142:143], v[136:137], off offset:32
	v_mul_f32_e32 v136, v133, v133
	v_mul_f32_e32 v137, v135, v135
	v_add_f32_e32 v146, v146, v147
	v_add_f32_e32 v140, v140, v141
	v_fmac_f32_e32 v136, v132, v132
	v_fmac_f32_e32 v137, v134, v134
	v_add_f32_e32 v140, v146, v140
	global_store_dwordx4 v[196:197], v[132:135], off offset:512
	v_add_f32_e32 v136, v136, v137
	v_add_f32_e32 v137, v140, v136
	v_pk_mul_f32 v[132:133], v[80:81], v[132:133]
	v_pk_mul_f32 v[134:135], v[82:83], v[134:135]
	v_cvt_pk_bf16_f32 v136, v132, v133
	v_pk_fma_f32 v[132:133], v[130:131], v[74:75], v[162:163]
	v_pk_fma_f32 v[130:131], v[128:129], v[72:73], v[160:161]
	v_mul_f32_e32 v129, v133, v133
	v_mul_f32_e32 v128, v131, v131
	v_fmac_f32_e32 v128, v130, v130
	v_fmac_f32_e32 v129, v132, v132
	v_add_f32_e32 v128, v128, v129
	v_add_f32_e32 v128, v137, v128
	ds_bpermute_b32 v129, v203, v128
	v_cvt_pk_bf16_f32 v137, v134, v135
	global_store_dwordx2 v[142:143], v[136:137], off offset:256
	global_store_dwordx4 v[196:197], v[130:133], off offset:576
	s_waitcnt lgkmcnt(0)
	v_add_f32_e32 v128, v128, v129
	ds_bpermute_b32 v129, v150, v128
	v_pk_mul_f32 v[130:131], v[64:65], v[130:131]
	v_pk_mul_f32 v[132:133], v[66:67], v[132:133]
	v_cvt_pk_bf16_f32 v130, v130, v131
	s_nop 0
	v_cvt_pk_bf16_f32 v131, v132, v133
	global_store_dwordx2 v[142:143], v[130:131], off offset:288
	s_and_saveexec_b64 s[4:5], vcc
	s_cbranch_execz .LBB0_1311
	s_waitcnt lgkmcnt(0)
	v_add_f32_e32 v128, v128, v129
	v_mul_f32_e32 v128, 0x4b800000, v128
	v_trunc_f32_e32 v128, v128
	v_mul_f32_e32 v129, 0x2f800000, v128
	v_floor_f32_e32 v129, v129
	v_fmac_f32_e32 v128, 0xcf800000, v129
	v_cvt_u32_f32_e32 v128, v128
	v_cvt_u32_f32_e32 v129, v129
	v_lshl_add_u64 v[130:131], v[194:195], 3, s[18:19]
	global_atomic_add_x2 v[130:131], v[128:129], off
.LBB0_1311:
	s_or_b64 exec, exec, s[4:5]
	v_or_b32_e32 v148, 32, v192
	v_ashrrev_i32_e32 v149, 31, v148
	s_waitcnt lgkmcnt(0)
	v_lshlrev_b64 v[128:129], 13, v[148:149]
	v_lshl_add_u64 v[168:169], v[190:191], 0, v[128:129]
	global_load_dwordx4 v[152:155], v[168:169], off
	global_load_dwordx4 v[156:159], v[168:169], off offset:64
	global_load_dwordx4 v[160:163], v[168:169], off offset:512
	global_load_dwordx4 v[164:167], v[168:169], off offset:576
	v_or_b32_e32 v144, 48, v192
	v_ashrrev_i32_e32 v145, 31, v144
	v_lshlrev_b64 v[128:129], 13, v[144:145]
	v_lshl_add_u64 v[146:147], v[190:191], 0, v[128:129]
	global_load_dwordx4 v[140:143], v[146:147], off
	global_load_dwordx4 v[136:139], v[146:147], off offset:64
	global_load_dwordx4 v[132:135], v[146:147], off offset:512
	global_load_dwordx4 v[128:131], v[146:147], off offset:576
	v_lshlrev_b64 v[170:171], 11, v[148:149]
	v_lshl_add_u64 v[170:171], v[170:171], 0, v[188:189]
	v_lshl_add_u64 v[170:171], v[170:171], 1, s[14:15]
	s_waitcnt vmcnt(0) lgkmcnt(0)
	v_pk_fma_f32 v[126:127], v[126:127], v[106:107], v[154:155]
	v_pk_fma_f32 v[124:125], v[124:125], v[104:105], v[152:153]
	v_pk_fma_f32 v[122:123], v[122:123], v[94:95], v[158:159]
	v_pk_fma_f32 v[120:121], v[120:121], v[92:93], v[156:157]
	v_pk_fma_f32 v[118:119], v[118:119], v[86:87], v[162:163]
	v_pk_fma_f32 v[116:117], v[116:117], v[84:85], v[160:161]
	v_pk_fma_f32 v[154:155], v[114:115], v[74:75], v[166:167]
	v_pk_fma_f32 v[152:153], v[112:113], v[72:73], v[164:165]
	global_store_dwordx4 v[168:169], v[124:127], off
	v_mul_f32_e32 v151, v125, v125
	v_mul_f32_e32 v164, v127, v127
	v_pk_mul_f32 v[112:113], v[102:103], v[126:127]
	v_pk_mul_f32 v[114:115], v[100:101], v[124:125]
	v_mul_f32_e32 v125, v121, v121
	v_mul_f32_e32 v127, v123, v123
	v_mul_f32_e32 v165, v117, v117
	v_mul_f32_e32 v166, v119, v119
	v_fmac_f32_e32 v151, v124, v124
	v_fmac_f32_e32 v164, v126, v126
	v_cvt_pk_bf16_f32 v114, v114, v115
	v_cvt_pk_bf16_f32 v115, v112, v113
	v_fmac_f32_e32 v125, v120, v120
	v_fmac_f32_e32 v127, v122, v122
	v_mul_f32_e32 v167, v153, v153
	v_mul_f32_e32 v172, v155, v155
	v_fmac_f32_e32 v165, v116, v116
	v_fmac_f32_e32 v166, v118, v118
	v_add_f32_e32 v124, v151, v164
	global_store_dwordx2 v[170:171], v[114:115], off
	global_store_dwordx4 v[168:169], v[120:123], off offset:64
	v_add_f32_e32 v114, v125, v127
	v_pk_mul_f32 v[156:157], v[90:91], v[122:123]
	v_pk_mul_f32 v[158:159], v[88:89], v[120:121]
	v_fmac_f32_e32 v167, v152, v152
	v_fmac_f32_e32 v172, v154, v154
	v_cvt_pk_bf16_f32 v112, v158, v159
	v_cvt_pk_bf16_f32 v113, v156, v157
	v_add_f32_e32 v115, v165, v166
	v_add_f32_e32 v114, v124, v114
	global_store_dwordx2 v[170:171], v[112:113], off offset:32
	global_store_dwordx4 v[168:169], v[116:119], off offset:512
	v_add_f32_e32 v113, v114, v115
	v_add_f32_e32 v114, v167, v172
	v_pk_mul_f32 v[162:163], v[80:81], v[116:117]
	v_add_f32_e32 v116, v113, v114
	ds_bpermute_b32 v117, v203, v116
	v_pk_mul_f32 v[160:161], v[82:83], v[118:119]
	v_cvt_pk_bf16_f32 v112, v162, v163
	v_pk_mul_f32 v[114:115], v[66:67], v[154:155]
	v_cvt_pk_bf16_f32 v113, v160, v161
	global_store_dwordx2 v[170:171], v[112:113], off offset:256
	global_store_dwordx4 v[168:169], v[152:155], off offset:576
	s_waitcnt lgkmcnt(0)
	v_add_f32_e32 v112, v116, v117
	ds_bpermute_b32 v113, v150, v112
	v_pk_mul_f32 v[116:117], v[64:65], v[152:153]
	s_nop 0
	v_cvt_pk_bf16_f32 v116, v116, v117
	v_cvt_pk_bf16_f32 v117, v114, v115
	global_store_dwordx2 v[170:171], v[116:117], off offset:288
	s_and_saveexec_b64 s[4:5], vcc
	s_cbranch_execz .LBB0_1313
; __device__ __forceinline__ unsigned cvt_pk_bf16(float lo, float hi) { unsigned r; asm volatile("v_cvt_pk_bf16_f32 %0, %1, %2" : "=v"(r) : "v"(lo), "v"(hi)); return r; }
;     __device__ __forceinline__ void operator()(const f32x4 (&acc)[2][2][4][2], const Unit& u, int wr, int wc, int fr_, int fq_) const {
;     ...
;             for (int m = 0; m < 2; ++m) { const size_t off = (size_t)(row0 + ai * HALF + (2 * mh + m) * 16) * ldc + col0;
; #pragma unroll
;                 for (int bj = 0; bj < 2; ++bj)
; #pragma unroll
;                     for (int n = 0; n < 2; ++n) bs[m][bj][n] = *(const f32x4*)(base + off + bj * HALF + n * 16); }
;             asm volatile("" ::: "memory");
; #pragma unroll
;             for (int m = 0; m < 2; ++m) { const int row = row0 + ai * HALF + (2 * mh + m) * 16; const size_t off = (size_t)row * ldc + col0; float ss = 0.f;
; #pragma unroll
;                 for (int bj = 0; bj < 2; ++bj)
; #pragma unroll
;                     for (int n = 0; n < 2; ++n) { const f32x4 o = bs[m][bj][n] + gv[bj][n] * acc[ai][bj][2 * mh + m][n]; *(f32x4*)(out + off + bj * HALF + n * 16) = o;
;                         if constexpr (EMIT) { ss += (o[0] * o[0] + o[1] * o[1]) + (o[2] * o[2] + o[3] * o[3]); const f32x4 y = o * gm[bj][n];
;                             typedef unsigned u32x2_t __attribute__((ext_vector_type(2))); u32x2_t w; w.x = cvt_pk_bf16(y[0], y[1]); w.y = cvt_pk_bf16(y[2], y[3]); *(u32x2_t*)(A2 + off + bj * HALF + n * 16) = w; } }
;                 if constexpr (EMIT) { ss += __shfl_xor(ss, 16); ss += __shfl_xor(ss, 32); if (fq == 0) atomicAdd(ssq + row, (unsigned long long)(ss * 16777216.0f)); } }
	s_waitcnt lgkmcnt(0)
	v_add_f32_e32 v112, v112, v113
	v_mul_f32_e32 v112, 0x4b800000, v112
	v_trunc_f32_e32 v112, v112
	v_mul_f32_e32 v113, 0x2f800000, v112
	v_floor_f32_e32 v113, v113
	v_fmac_f32_e32 v112, 0xcf800000, v113
	v_cvt_u32_f32_e32 v112, v112
	v_cvt_u32_f32_e32 v113, v113
	v_lshl_add_u64 v[114:115], v[148:149], 3, s[18:19]
	global_atomic_add_x2 v[114:115], v[112:113], off
.LBB0_1313:
	s_or_b64 exec, exec, s[4:5]
	v_pk_fma_f32 v[110:111], v[110:111], v[106:107], v[142:143]
	v_pk_fma_f32 v[108:109], v[108:109], v[104:105], v[140:141]
	s_waitcnt lgkmcnt(0)
	v_lshlrev_b64 v[112:113], 11, v[144:145]
	v_mul_f32_e32 v114, v109, v109
	v_mul_f32_e32 v115, v111, v111
	v_lshl_add_u64 v[112:113], v[112:113], 0, v[188:189]
	global_store_dwordx4 v[146:147], v[108:111], off
	v_fmac_f32_e32 v114, v108, v108
	v_fmac_f32_e32 v115, v110, v110
	v_pk_mul_f32 v[110:111], v[102:103], v[110:111]
	v_pk_mul_f32 v[108:109], v[100:101], v[108:109]
	v_pk_fma_f32 v[96:97], v[96:97], v[92:93], v[136:137]
	v_cvt_pk_bf16_f32 v108, v108, v109
	v_cvt_pk_bf16_f32 v109, v110, v111
	v_lshl_add_u64 v[110:111], v[112:113], 1, s[14:15]
	global_store_dwordx2 v[110:111], v[108:109], off
	v_pk_fma_f32 v[98:99], v[98:99], v[94:95], v[138:139]
	v_mul_f32_e32 v108, v97, v97
	global_store_dwordx4 v[146:147], v[96:99], off offset:64
	v_fmac_f32_e32 v108, v96, v96
	v_mul_f32_e32 v109, v99, v99
	v_pk_mul_f32 v[96:97], v[88:89], v[96:97]
	v_fmac_f32_e32 v109, v98, v98
	v_pk_mul_f32 v[98:99], v[90:91], v[98:99]
	v_cvt_pk_bf16_f32 v96, v96, v97
	v_pk_fma_f32 v[78:79], v[78:79], v[86:87], v[134:135]
	v_cvt_pk_bf16_f32 v97, v98, v99
	v_pk_fma_f32 v[76:77], v[76:77], v[84:85], v[132:133]
	global_store_dwordx2 v[110:111], v[96:97], off offset:32
	v_mul_f32_e32 v96, v77, v77
	v_mul_f32_e32 v97, v79, v79
	v_add_f32_e32 v114, v114, v115
	v_add_f32_e32 v108, v108, v109
	v_fmac_f32_e32 v96, v76, v76
	v_fmac_f32_e32 v97, v78, v78
	v_add_f32_e32 v108, v114, v108
	global_store_dwordx4 v[146:147], v[76:79], off offset:512
	v_add_f32_e32 v96, v96, v97
	v_add_f32_e32 v99, v108, v96
	v_pk_mul_f32 v[76:77], v[80:81], v[76:77]
	v_pk_mul_f32 v[96:97], v[82:83], v[78:79]
	v_cvt_pk_bf16_f32 v98, v76, v77
	v_pk_fma_f32 v[78:79], v[70:71], v[74:75], v[130:131]
	v_pk_fma_f32 v[76:77], v[68:69], v[72:73], v[128:129]
	v_mul_f32_e32 v69, v79, v79
	v_mul_f32_e32 v68, v77, v77
	v_fmac_f32_e32 v68, v76, v76
	v_fmac_f32_e32 v69, v78, v78
	v_add_f32_e32 v68, v68, v69
	v_add_f32_e32 v68, v99, v68
	ds_bpermute_b32 v69, v203, v68
	v_cvt_pk_bf16_f32 v99, v96, v97
	global_store_dwordx2 v[110:111], v[98:99], off offset:256
	global_store_dwordx4 v[146:147], v[76:79], off offset:576
	v_pk_mul_f32 v[70:71], v[66:67], v[78:79]
	s_waitcnt lgkmcnt(0)
	v_add_f32_e32 v68, v68, v69
	ds_bpermute_b32 v69, v150, v68
	v_pk_mul_f32 v[76:77], v[64:65], v[76:77]
	s_nop 0
	v_cvt_pk_bf16_f32 v76, v76, v77
	v_cvt_pk_bf16_f32 v77, v70, v71
	global_store_dwordx2 v[110:111], v[76:77], off offset:288
	s_and_saveexec_b64 s[4:5], vcc
	s_cbranch_execz .LBB0_1315
	s_waitcnt lgkmcnt(0)
	v_add_f32_e32 v68, v68, v69
	v_mul_f32_e32 v68, 0x4b800000, v68
	v_trunc_f32_e32 v68, v68
	v_mul_f32_e32 v69, 0x2f800000, v68
	v_floor_f32_e32 v69, v69
	v_fmac_f32_e32 v68, 0xcf800000, v69
	v_cvt_u32_f32_e32 v68, v68
	v_cvt_u32_f32_e32 v69, v69
	v_lshl_add_u64 v[70:71], v[144:145], 3, s[18:19]
	global_atomic_add_x2 v[70:71], v[68:69], off
.LBB0_1315:
	s_or_b64 exec, exec, s[4:5]
	v_add_u32_e32 v116, 0x80, v192
	v_ashrrev_i32_e32 v117, 31, v116
	s_waitcnt lgkmcnt(0)
	v_lshlrev_b64 v[68:69], 13, v[116:117]
	v_lshl_add_u64 v[134:135], v[190:191], 0, v[68:69]
	global_load_dwordx4 v[118:121], v[134:135], off
	global_load_dwordx4 v[122:125], v[134:135], off offset:64
	global_load_dwordx4 v[126:129], v[134:135], off offset:512
	global_load_dwordx4 v[130:133], v[134:135], off offset:576
	v_add_u32_e32 v112, 0x90, v192
	v_ashrrev_i32_e32 v113, 31, v112
	v_lshlrev_b64 v[68:69], 13, v[112:113]
	v_lshl_add_u64 v[114:115], v[190:191], 0, v[68:69]
	global_load_dwordx4 v[108:111], v[114:115], off
	global_load_dwordx4 v[96:99], v[114:115], off offset:64
	global_load_dwordx4 v[76:79], v[114:115], off offset:512
	global_load_dwordx4 v[68:71], v[114:115], off offset:576
	v_lshlrev_b64 v[136:137], 11, v[116:117]
	v_lshl_add_u64 v[136:137], v[136:137], 0, v[188:189]
	v_lshl_add_u64 v[136:137], v[136:137], 1, s[14:15]
	s_waitcnt vmcnt(0) lgkmcnt(0)
	v_pk_fma_f32 v[62:63], v[62:63], v[106:107], v[120:121]
	v_pk_fma_f32 v[60:61], v[60:61], v[104:105], v[118:119]
	v_pk_fma_f32 v[58:59], v[58:59], v[94:95], v[124:125]
	v_pk_fma_f32 v[56:57], v[56:57], v[92:93], v[122:123]
	v_pk_fma_f32 v[54:55], v[54:55], v[86:87], v[128:129]
	v_pk_fma_f32 v[52:53], v[52:53], v[84:85], v[126:127]
	v_pk_fma_f32 v[120:121], v[50:51], v[74:75], v[132:133]
	v_pk_fma_f32 v[118:119], v[48:49], v[72:73], v[130:131]
	global_store_dwordx4 v[134:135], v[60:63], off
	v_mul_f32_e32 v130, v61, v61
	v_mul_f32_e32 v131, v63, v63
	v_pk_mul_f32 v[48:49], v[102:103], v[62:63]
	v_pk_mul_f32 v[50:51], v[100:101], v[60:61]
	v_mul_f32_e32 v61, v57, v57
	v_mul_f32_e32 v63, v59, v59
	v_mul_f32_e32 v132, v53, v53
	v_mul_f32_e32 v133, v55, v55
	v_fmac_f32_e32 v130, v60, v60
	v_fmac_f32_e32 v131, v62, v62
	v_cvt_pk_bf16_f32 v50, v50, v51
	v_cvt_pk_bf16_f32 v51, v48, v49
	v_fmac_f32_e32 v61, v56, v56
	v_fmac_f32_e32 v63, v58, v58
	v_mul_f32_e32 v138, v119, v119
	v_mul_f32_e32 v139, v121, v121
	v_fmac_f32_e32 v132, v52, v52
	v_fmac_f32_e32 v133, v54, v54
	v_add_f32_e32 v60, v130, v131
	global_store_dwordx2 v[136:137], v[50:51], off
	global_store_dwordx4 v[134:135], v[56:59], off offset:64
	v_add_f32_e32 v50, v61, v63
	v_pk_mul_f32 v[122:123], v[90:91], v[58:59]
	v_pk_mul_f32 v[124:125], v[88:89], v[56:57]
	v_fmac_f32_e32 v138, v118, v118
	v_fmac_f32_e32 v139, v120, v120
	v_cvt_pk_bf16_f32 v48, v124, v125
	v_cvt_pk_bf16_f32 v49, v122, v123
	v_add_f32_e32 v51, v132, v133
	v_add_f32_e32 v50, v60, v50
	global_store_dwordx2 v[136:137], v[48:49], off offset:32
	global_store_dwordx4 v[134:135], v[52:55], off offset:512
	v_add_f32_e32 v49, v50, v51
	v_add_f32_e32 v50, v138, v139
	v_pk_mul_f32 v[128:129], v[80:81], v[52:53]
	v_add_f32_e32 v52, v49, v50
	ds_bpermute_b32 v53, v203, v52
	v_pk_mul_f32 v[126:127], v[82:83], v[54:55]
	v_cvt_pk_bf16_f32 v48, v128, v129
	v_pk_mul_f32 v[50:51], v[66:67], v[120:121]
	v_cvt_pk_bf16_f32 v49, v126, v127
	global_store_dwordx2 v[136:137], v[48:49], off offset:256
	global_store_dwordx4 v[134:135], v[118:121], off offset:576
	s_waitcnt lgkmcnt(0)
	v_add_f32_e32 v48, v52, v53
	ds_bpermute_b32 v49, v150, v48
	v_pk_mul_f32 v[52:53], v[64:65], v[118:119]
	s_nop 0
	v_cvt_pk_bf16_f32 v52, v52, v53
	v_cvt_pk_bf16_f32 v53, v50, v51
	global_store_dwordx2 v[136:137], v[52:53], off offset:288
	s_and_saveexec_b64 s[4:5], vcc
	s_cbranch_execz .LBB0_1317
; __device__ __forceinline__ unsigned cvt_pk_bf16(float lo, float hi) { unsigned r; asm volatile("v_cvt_pk_bf16_f32 %0, %1, %2" : "=v"(r) : "v"(lo), "v"(hi)); return r; }
;     __device__ __forceinline__ void operator()(const f32x4 (&acc)[2][2][4][2], const Unit& u, int wr, int wc, int fr_, int fq_) const {
;     ...
;             for (int m = 0; m < 2; ++m) { const size_t off = (size_t)(row0 + ai * HALF + (2 * mh + m) * 16) * ldc + col0;
; #pragma unroll
;                 for (int bj = 0; bj < 2; ++bj)
; #pragma unroll
;                     for (int n = 0; n < 2; ++n) bs[m][bj][n] = *(const f32x4*)(base + off + bj * HALF + n * 16); }
;             asm volatile("" ::: "memory");
; #pragma unroll
;             for (int m = 0; m < 2; ++m) { const int row = row0 + ai * HALF + (2 * mh + m) * 16; const size_t off = (size_t)row * ldc + col0; float ss = 0.f;
; #pragma unroll
;                 for (int bj = 0; bj < 2; ++bj)
; #pragma unroll
;                     for (int n = 0; n < 2; ++n) { const f32x4 o = bs[m][bj][n] + gv[bj][n] * acc[ai][bj][2 * mh + m][n]; *(f32x4*)(out + off + bj * HALF + n * 16) = o;
;                         if constexpr (EMIT) { ss += (o[0] * o[0] + o[1] * o[1]) + (o[2] * o[2] + o[3] * o[3]); const f32x4 y = o * gm[bj][n];
;                             typedef unsigned u32x2_t __attribute__((ext_vector_type(2))); u32x2_t w; w.x = cvt_pk_bf16(y[0], y[1]); w.y = cvt_pk_bf16(y[2], y[3]); *(u32x2_t*)(A2 + off + bj * HALF + n * 16) = w; } }
;                 if constexpr (EMIT) { ss += __shfl_xor(ss, 16); ss += __shfl_xor(ss, 32); if (fq == 0) atomicAdd(ssq + row, (unsigned long long)(ss * 16777216.0f)); } }
	s_waitcnt lgkmcnt(0)
	v_add_f32_e32 v48, v48, v49
	v_mul_f32_e32 v48, 0x4b800000, v48
	v_trunc_f32_e32 v48, v48
	v_mul_f32_e32 v49, 0x2f800000, v48
	v_floor_f32_e32 v49, v49
	v_fmac_f32_e32 v48, 0xcf800000, v49
	v_cvt_u32_f32_e32 v48, v48
	v_cvt_u32_f32_e32 v49, v49
	v_lshl_add_u64 v[50:51], v[116:117], 3, s[18:19]
	global_atomic_add_x2 v[50:51], v[48:49], off
.LBB0_1317:
	s_or_b64 exec, exec, s[4:5]
	v_pk_fma_f32 v[46:47], v[46:47], v[106:107], v[110:111]
	v_pk_fma_f32 v[44:45], v[44:45], v[104:105], v[108:109]
	s_waitcnt lgkmcnt(0)
	v_lshlrev_b64 v[48:49], 11, v[112:113]
	v_mul_f32_e32 v50, v45, v45
	v_mul_f32_e32 v51, v47, v47
	v_lshl_add_u64 v[48:49], v[48:49], 0, v[188:189]
	global_store_dwordx4 v[114:115], v[44:47], off
	v_fmac_f32_e32 v50, v44, v44
	v_fmac_f32_e32 v51, v46, v46
	v_pk_mul_f32 v[46:47], v[102:103], v[46:47]
	v_pk_mul_f32 v[44:45], v[100:101], v[44:45]
	v_pk_fma_f32 v[40:41], v[40:41], v[92:93], v[96:97]
	v_cvt_pk_bf16_f32 v44, v44, v45
	v_cvt_pk_bf16_f32 v45, v46, v47
	v_lshl_add_u64 v[46:47], v[48:49], 1, s[14:15]
	global_store_dwordx2 v[46:47], v[44:45], off
	v_pk_fma_f32 v[42:43], v[42:43], v[94:95], v[98:99]
	v_mul_f32_e32 v44, v41, v41
	global_store_dwordx4 v[114:115], v[40:43], off offset:64
	v_fmac_f32_e32 v44, v40, v40
	v_mul_f32_e32 v45, v43, v43
	v_pk_mul_f32 v[40:41], v[88:89], v[40:41]
	v_fmac_f32_e32 v45, v42, v42
	v_pk_mul_f32 v[42:43], v[90:91], v[42:43]
	v_cvt_pk_bf16_f32 v40, v40, v41
	v_pk_fma_f32 v[38:39], v[38:39], v[86:87], v[78:79]
	v_cvt_pk_bf16_f32 v41, v42, v43
	v_pk_fma_f32 v[36:37], v[36:37], v[84:85], v[76:77]
	global_store_dwordx2 v[46:47], v[40:41], off offset:32
	v_mul_f32_e32 v40, v37, v37
	v_mul_f32_e32 v41, v39, v39
	v_add_f32_e32 v50, v50, v51
	v_add_f32_e32 v44, v44, v45
	v_fmac_f32_e32 v40, v36, v36
	v_fmac_f32_e32 v41, v38, v38
	v_add_f32_e32 v44, v50, v44
	global_store_dwordx4 v[114:115], v[36:39], off offset:512
	v_add_f32_e32 v40, v40, v41
	v_add_f32_e32 v41, v44, v40
	v_pk_mul_f32 v[36:37], v[80:81], v[36:37]
	v_pk_mul_f32 v[38:39], v[82:83], v[38:39]
	v_cvt_pk_bf16_f32 v40, v36, v37
	v_pk_fma_f32 v[36:37], v[34:35], v[74:75], v[70:71]
	v_pk_fma_f32 v[34:35], v[32:33], v[72:73], v[68:69]
	v_mul_f32_e32 v33, v37, v37
	v_mul_f32_e32 v32, v35, v35
	v_fmac_f32_e32 v32, v34, v34
	v_fmac_f32_e32 v33, v36, v36
	v_add_f32_e32 v32, v32, v33
	v_add_f32_e32 v32, v41, v32
	ds_bpermute_b32 v33, v203, v32
	v_cvt_pk_bf16_f32 v41, v38, v39
	global_store_dwordx2 v[46:47], v[40:41], off offset:256
	global_store_dwordx4 v[114:115], v[34:37], off offset:576
	s_waitcnt lgkmcnt(0)
	v_add_f32_e32 v32, v32, v33
	ds_bpermute_b32 v33, v150, v32
	v_pk_mul_f32 v[34:35], v[64:65], v[34:35]
	v_pk_mul_f32 v[36:37], v[66:67], v[36:37]
	v_cvt_pk_bf16_f32 v34, v34, v35
	s_nop 0
	v_cvt_pk_bf16_f32 v35, v36, v37
	global_store_dwordx2 v[46:47], v[34:35], off offset:288
	s_and_saveexec_b64 s[4:5], vcc
	s_cbranch_execz .LBB0_1319
	s_waitcnt lgkmcnt(0)
	v_add_f32_e32 v32, v32, v33
	v_mul_f32_e32 v32, 0x4b800000, v32
	v_trunc_f32_e32 v32, v32
	v_mul_f32_e32 v33, 0x2f800000, v32
	v_floor_f32_e32 v33, v33
	v_fmac_f32_e32 v32, 0xcf800000, v33
	v_cvt_u32_f32_e32 v32, v32
	v_cvt_u32_f32_e32 v33, v33
	v_lshl_add_u64 v[34:35], v[112:113], 3, s[18:19]
	global_atomic_add_x2 v[34:35], v[32:33], off
; __device__ __forceinline__ unsigned cvt_pk_bf16(float lo, float hi) { unsigned r; asm volatile("v_cvt_pk_bf16_f32 %0, %1, %2" : "=v"(r) : "v"(lo), "v"(hi)); return r; }
;     __device__ __forceinline__ void operator()(const f32x4 (&acc)[2][2][4][2], const Unit& u, int wr, int wc, int fr_, int fq_) const {
;     ...
;             for (int m = 0; m < 2; ++m) { const size_t off = (size_t)(row0 + ai * HALF + (2 * mh + m) * 16) * ldc + col0;
; #pragma unroll
;                 for (int bj = 0; bj < 2; ++bj)
; #pragma unroll
;                     for (int n = 0; n < 2; ++n) bs[m][bj][n] = *(const f32x4*)(base + off + bj * HALF + n * 16); }
;             asm volatile("" ::: "memory");
; #pragma unroll
;             for (int m = 0; m < 2; ++m) { const int row = row0 + ai * HALF + (2 * mh + m) * 16; const size_t off = (size_t)row * ldc + col0; float ss = 0.f;
; #pragma unroll
;                 for (int bj = 0; bj < 2; ++bj)
; #pragma unroll
;                     for (int n = 0; n < 2; ++n) { const f32x4 o = bs[m][bj][n] + gv[bj][n] * acc[ai][bj][2 * mh + m][n]; *(f32x4*)(out + off + bj * HALF + n * 16) = o;
;                         if constexpr (EMIT) { ss += (o[0] * o[0] + o[1] * o[1]) + (o[2] * o[2] + o[3] * o[3]); const f32x4 y = o * gm[bj][n];
;                             typedef unsigned u32x2_t __attribute__((ext_vector_type(2))); u32x2_t w; w.x = cvt_pk_bf16(y[0], y[1]); w.y = cvt_pk_bf16(y[2], y[3]); *(u32x2_t*)(A2 + off + bj * HALF + n * 16) = w; } }
;                 if constexpr (EMIT) { ss += __shfl_xor(ss, 16); ss += __shfl_xor(ss, 32); if (fq == 0) atomicAdd(ssq + row, (unsigned long long)(ss * 16777216.0f)); } }
.LBB0_1319:
	s_or_b64 exec, exec, s[4:5]
	v_add_u32_e32 v52, 0xa0, v192
	v_ashrrev_i32_e32 v53, 31, v52
	s_waitcnt lgkmcnt(0)
	v_lshlrev_b64 v[32:33], 13, v[52:53]
	v_lshl_add_u64 v[62:63], v[190:191], 0, v[32:33]
	global_load_dwordx4 v[54:57], v[62:63], off
	global_load_dwordx4 v[58:61], v[62:63], off offset:64
	global_load_dwordx4 v[68:71], v[62:63], off offset:512
	global_load_dwordx4 v[76:79], v[62:63], off offset:576
	v_add_u32_e32 v48, 0xb0, v192
	v_ashrrev_i32_e32 v49, 31, v48
	v_lshlrev_b64 v[32:33], 13, v[48:49]
	v_lshl_add_u64 v[50:51], v[190:191], 0, v[32:33]
	global_load_dwordx4 v[44:47], v[50:51], off
	global_load_dwordx4 v[40:43], v[50:51], off offset:64
	global_load_dwordx4 v[36:39], v[50:51], off offset:512
	global_load_dwordx4 v[32:35], v[50:51], off offset:576
	v_lshlrev_b64 v[96:97], 11, v[52:53]
	v_lshl_add_u64 v[96:97], v[96:97], 0, v[188:189]
	v_lshl_add_u64 v[96:97], v[96:97], 1, s[14:15]
	s_waitcnt vmcnt(0) lgkmcnt(0)
	v_pk_fma_f32 v[30:31], v[30:31], v[106:107], v[56:57]
	v_pk_fma_f32 v[28:29], v[28:29], v[104:105], v[54:55]
	v_pk_fma_f32 v[26:27], v[26:27], v[94:95], v[60:61]
	v_pk_fma_f32 v[24:25], v[24:25], v[92:93], v[58:59]
	v_pk_fma_f32 v[22:23], v[22:23], v[86:87], v[70:71]
	v_pk_fma_f32 v[20:21], v[20:21], v[84:85], v[68:69]
	v_pk_fma_f32 v[56:57], v[18:19], v[74:75], v[78:79]
	v_pk_fma_f32 v[54:55], v[16:17], v[72:73], v[76:77]
	global_store_dwordx4 v[62:63], v[28:31], off
	v_mul_f32_e32 v76, v29, v29
	v_mul_f32_e32 v77, v31, v31
	v_pk_mul_f32 v[16:17], v[102:103], v[30:31]
	v_pk_mul_f32 v[18:19], v[100:101], v[28:29]
	v_mul_f32_e32 v29, v25, v25
	v_mul_f32_e32 v31, v27, v27
	v_mul_f32_e32 v78, v21, v21
	v_mul_f32_e32 v79, v23, v23
	v_fmac_f32_e32 v76, v28, v28
	v_fmac_f32_e32 v77, v30, v30
	v_cvt_pk_bf16_f32 v18, v18, v19
	v_cvt_pk_bf16_f32 v19, v16, v17
	v_fmac_f32_e32 v29, v24, v24
	v_fmac_f32_e32 v31, v26, v26
	v_mul_f32_e32 v98, v55, v55
	v_mul_f32_e32 v99, v57, v57
	v_fmac_f32_e32 v78, v20, v20
	v_fmac_f32_e32 v79, v22, v22
	v_add_f32_e32 v28, v76, v77
	global_store_dwordx2 v[96:97], v[18:19], off
	global_store_dwordx4 v[62:63], v[24:27], off offset:64
	v_add_f32_e32 v18, v29, v31
	v_pk_mul_f32 v[58:59], v[90:91], v[26:27]
	v_pk_mul_f32 v[60:61], v[88:89], v[24:25]
	v_fmac_f32_e32 v98, v54, v54
	v_fmac_f32_e32 v99, v56, v56
	v_cvt_pk_bf16_f32 v16, v60, v61
	v_cvt_pk_bf16_f32 v17, v58, v59
	v_add_f32_e32 v19, v78, v79
	v_add_f32_e32 v18, v28, v18
	global_store_dwordx2 v[96:97], v[16:17], off offset:32
	global_store_dwordx4 v[62:63], v[20:23], off offset:512
	v_add_f32_e32 v17, v18, v19
	v_add_f32_e32 v18, v98, v99
	v_pk_mul_f32 v[70:71], v[80:81], v[20:21]
	v_add_f32_e32 v20, v17, v18
	ds_bpermute_b32 v21, v203, v20
	v_pk_mul_f32 v[68:69], v[82:83], v[22:23]
	v_cvt_pk_bf16_f32 v16, v70, v71
	v_pk_mul_f32 v[18:19], v[66:67], v[56:57]
	v_cvt_pk_bf16_f32 v17, v68, v69
	global_store_dwordx2 v[96:97], v[16:17], off offset:256
	global_store_dwordx4 v[62:63], v[54:57], off offset:576
	s_waitcnt lgkmcnt(0)
	v_add_f32_e32 v16, v20, v21
	ds_bpermute_b32 v17, v150, v16
	v_pk_mul_f32 v[20:21], v[64:65], v[54:55]
	s_nop 0
	v_cvt_pk_bf16_f32 v20, v20, v21
	v_cvt_pk_bf16_f32 v21, v18, v19
	global_store_dwordx2 v[96:97], v[20:21], off offset:288
	s_and_saveexec_b64 s[4:5], vcc
	s_cbranch_execz .LBB0_1321
	s_waitcnt lgkmcnt(0)
	v_add_f32_e32 v16, v16, v17
	v_mul_f32_e32 v16, 0x4b800000, v16
	v_trunc_f32_e32 v16, v16
	v_mul_f32_e32 v17, 0x2f800000, v16
	v_floor_f32_e32 v17, v17
	v_fmac_f32_e32 v16, 0xcf800000, v17
	v_cvt_u32_f32_e32 v16, v16
	v_cvt_u32_f32_e32 v17, v17
	v_lshl_add_u64 v[18:19], v[52:53], 3, s[18:19]
	global_atomic_add_x2 v[18:19], v[16:17], off
.LBB0_1321:
	s_or_b64 exec, exec, s[4:5]
	v_pk_fma_f32 v[14:15], v[14:15], v[106:107], v[46:47]
	v_pk_fma_f32 v[12:13], v[12:13], v[104:105], v[44:45]
	s_waitcnt lgkmcnt(0)
	v_lshlrev_b64 v[16:17], 11, v[48:49]
	v_mul_f32_e32 v18, v13, v13
	v_mul_f32_e32 v19, v15, v15
	v_lshl_add_u64 v[16:17], v[16:17], 0, v[188:189]
	global_store_dwordx4 v[50:51], v[12:15], off
	v_fmac_f32_e32 v18, v12, v12
	v_fmac_f32_e32 v19, v14, v14
	v_pk_mul_f32 v[14:15], v[102:103], v[14:15]
	v_pk_mul_f32 v[12:13], v[100:101], v[12:13]
	v_pk_fma_f32 v[8:9], v[8:9], v[92:93], v[40:41]
	v_cvt_pk_bf16_f32 v12, v12, v13
	v_cvt_pk_bf16_f32 v13, v14, v15
	v_lshl_add_u64 v[14:15], v[16:17], 1, s[14:15]
	global_store_dwordx2 v[14:15], v[12:13], off
	v_pk_fma_f32 v[10:11], v[10:11], v[94:95], v[42:43]
	v_mul_f32_e32 v12, v9, v9
	global_store_dwordx4 v[50:51], v[8:11], off offset:64
	v_fmac_f32_e32 v12, v8, v8
	v_mul_f32_e32 v13, v11, v11
	v_pk_mul_f32 v[8:9], v[88:89], v[8:9]
	v_fmac_f32_e32 v13, v10, v10
	v_pk_mul_f32 v[10:11], v[90:91], v[10:11]
	v_cvt_pk_bf16_f32 v8, v8, v9
	v_pk_fma_f32 v[6:7], v[6:7], v[86:87], v[38:39]
	v_cvt_pk_bf16_f32 v9, v10, v11
	v_pk_fma_f32 v[4:5], v[4:5], v[84:85], v[36:37]
	global_store_dwordx2 v[14:15], v[8:9], off offset:32
	v_mul_f32_e32 v8, v5, v5
	v_mul_f32_e32 v9, v7, v7
	v_add_f32_e32 v18, v18, v19
	v_add_f32_e32 v12, v12, v13
	v_fmac_f32_e32 v8, v4, v4
	v_fmac_f32_e32 v9, v6, v6
	v_add_f32_e32 v12, v18, v12
	global_store_dwordx4 v[50:51], v[4:7], off offset:512
	v_add_f32_e32 v8, v8, v9
	v_add_f32_e32 v9, v12, v8
	v_pk_mul_f32 v[4:5], v[80:81], v[4:5]
	v_pk_mul_f32 v[6:7], v[82:83], v[6:7]
	v_cvt_pk_bf16_f32 v8, v4, v5
	v_pk_fma_f32 v[4:5], v[2:3], v[74:75], v[34:35]
	v_pk_fma_f32 v[2:3], v[0:1], v[72:73], v[32:33]
	v_mul_f32_e32 v1, v5, v5
	v_mul_f32_e32 v0, v3, v3
	v_fmac_f32_e32 v0, v2, v2
	v_fmac_f32_e32 v1, v4, v4
	v_add_f32_e32 v0, v0, v1
	v_add_f32_e32 v0, v9, v0
	ds_bpermute_b32 v1, v203, v0
	v_cvt_pk_bf16_f32 v9, v6, v7
	global_store_dwordx2 v[14:15], v[8:9], off offset:256
	global_store_dwordx4 v[50:51], v[2:5], off offset:576
	s_waitcnt lgkmcnt(0)
	v_add_f32_e32 v0, v0, v1
	ds_bpermute_b32 v1, v150, v0
	v_pk_mul_f32 v[2:3], v[64:65], v[2:3]
	v_pk_mul_f32 v[4:5], v[66:67], v[4:5]
	v_cvt_pk_bf16_f32 v2, v2, v3
	s_nop 0
	v_cvt_pk_bf16_f32 v3, v4, v5
	global_store_dwordx2 v[14:15], v[2:3], off offset:288
	s_and_saveexec_b64 s[4:5], vcc
	s_cbranch_execz .LBB0_1323
	s_waitcnt lgkmcnt(0)
	v_add_f32_e32 v0, v0, v1
	v_mul_f32_e32 v0, 0x4b800000, v0
	v_trunc_f32_e32 v0, v0
	v_mul_f32_e32 v1, 0x2f800000, v0
	v_floor_f32_e32 v1, v1
	v_fmac_f32_e32 v0, 0xcf800000, v1
	v_cvt_u32_f32_e32 v0, v0
	v_cvt_u32_f32_e32 v1, v1
	v_lshl_add_u64 v[2:3], v[48:49], 3, s[18:19]
	global_atomic_add_x2 v[2:3], v[0:1], off

; __device__ __forceinline__ int lane_asm() { int l; asm volatile("v_mbcnt_lo_u32_b32 %0, -1, 0\n\tv_mbcnt_hi_u32_b32 %0, -1, %0" : "=v"(l)); return l; }
; __device__ __forceinline__ float rstd_from_ssq(const unsigned long long* ssq, int row) {
;     return 1.0f / sqrtf((float)ssq[row] * (1.0f / 16777216.0f) * (1.0f / 2048.0f) + 1e-6f);
; }
;     __device__ __forceinline__ void operator()(const f32x4 (&acc)[2][2][4][2], const Unit& u, int wr, int wc, int fr_, int fq_) const {
;         const int l_ = lane_asm(); const int fr = l_ & 15, fq = l_ >> 4; (void)fr_; (void)fq_;
;         const int row0 = u.pm * BM + wr * 64 + fr, col0 = u.pn * HALF + wc * 32 + 8 * fq;
;         f32x4 ba0 = {0.f, 0.f, 0.f, 0.f}, ba1 = ba0, bb0 = ba0, bb1 = ba0;
;         if constexpr (DEFER) { const float* bp = bv + u.pn * BM + wc * 32 + 8 * fq; ba0 = *(const f32x4*)bp; ba1 = *(const f32x4*)(bp + 4); bb0 = *(const f32x4*)(bp + HALF); bb1 = *(const f32x4*)(bp + HALF + 4); }
;         float rsv[8];
;         if constexpr (DEFER) {
; #pragma unroll
;             for (int i = 0; i < 8; ++i) rsv[i] = rstd_from_ssq(ssq, row0 + (i >> 2) * HALF + (i & 3) * 16);
;             asm volatile("" ::: "memory"); }
.LBB0_1388:
	s_lshl_b32 s4, s4, 8
	s_add_i32 s4, s4, s43
	v_mbcnt_lo_u32_b32 v128, -1, 0
	v_mbcnt_hi_u32_b32 v128, -1, v128
	s_nop 0
	v_and_or_b32 v160, v128, 15, s4
	v_ashrrev_i32_e32 v161, 31, v160
	v_lshl_add_u64 v[162:163], v[160:161], 3, s[16:17]
	global_load_dwordx2 v[180:181], v[162:163], off
	global_load_dwordx2 v[182:183], v[162:163], off offset:128
	global_load_dwordx2 v[184:185], v[162:163], off offset:256
	s_lshl_b32 s4, s56, 8
	s_ashr_i32 s5, s4, 31
	v_ashrrev_i32_e32 v128, 1, v128
	s_lshl_b64 s[4:5], s[4:5], 2
	v_and_b32_e32 v164, -8, v128
	s_add_u32 s4, s50, s4
	v_ashrrev_i32_e32 v165, 31, v164
	s_addc_u32 s5, s51, s5
	v_lshl_add_u64 v[128:129], v[164:165], 2, s[4:5]
	global_load_dwordx2 v[186:187], v[162:163], off offset:384
	global_load_dwordx2 v[166:167], v[162:163], off offset:1024
	global_load_dwordx4 v[140:143], v[128:129], off
	global_load_dwordx4 v[132:135], v[128:129], off offset:16
	global_load_dwordx4 v[136:139], v[128:129], off offset:512
	s_nop 0
	global_load_dwordx4 v[128:131], v[128:129], off offset:528
	s_waitcnt vmcnt(0) lgkmcnt(0)
	v_ffbh_u32_e32 v161, v181
	v_ffbh_u32_e32 v165, v183
	v_min_u32_e32 v161, 32, v161
	v_ffbh_u32_e32 v168, v185
	v_min_u32_e32 v165, 32, v165
	v_lshlrev_b64 v[180:181], v161, v[180:181]
	v_min_u32_e32 v168, 32, v168
	v_lshlrev_b64 v[182:183], v165, v[182:183]
	v_min_u32_e32 v170, 1, v180
	v_lshlrev_b64 v[184:185], v168, v[184:185]
	v_min_u32_e32 v172, 1, v182
	v_or_b32_e32 v170, v181, v170
	v_min_u32_e32 v174, 1, v184
	v_or_b32_e32 v172, v183, v172
	v_cvt_f32_u32_e32 v170, v170
	v_or_b32_e32 v174, v185, v174
	v_cvt_f32_u32_e32 v172, v172
	v_cvt_f32_u32_e32 v174, v174
	v_sub_u32_e32 v161, 32, v161
	v_sub_u32_e32 v165, 32, v165
	v_ldexp_f32 v161, v170, v161
	v_sub_u32_e32 v168, 32, v168
	v_ldexp_f32 v165, v172, v165
	v_mul_f32_e32 v161, 0x33800000, v161
	v_ldexp_f32 v168, v174, v168
	v_mul_f32_e32 v165, 0x33800000, v165
	v_fmamk_f32 v161, v161, 0x3a000000, v177
	v_mul_f32_e32 v168, 0x33800000, v168
	v_fmamk_f32 v165, v165, 0x3a000000, v177
	v_mul_f32_e32 v170, 0x4f800000, v161
	v_cmp_gt_f32_e32 vcc, s54, v161
	v_fmamk_f32 v168, v168, 0x3a000000, v177
	v_mul_f32_e32 v172, 0x4f800000, v165
	v_cndmask_b32_e32 v161, v161, v170, vcc
	v_cmp_gt_f32_e64 s[4:5], s54, v165
	v_mul_f32_e32 v174, 0x4f800000, v168
	v_sqrt_f32_e32 v170, v161
	v_cndmask_b32_e64 v165, v165, v172, s[4:5]
	v_cmp_gt_f32_e64 s[6:7], s54, v168
	v_sqrt_f32_e32 v172, v165
	v_add_u32_e32 v176, -1, v170
	v_cndmask_b32_e64 v168, v168, v174, s[6:7]
	v_sqrt_f32_e32 v174, v168
	v_add_u32_e32 v180, -1, v172
	v_fma_f32 v184, -v176, v170, v161
	v_add_u32_e32 v178, 1, v170
	v_add_u32_e32 v182, -1, v174
	v_fma_f32 v188, -v180, v172, v165
	v_cmp_ge_f32_e64 s[8:9], 0, v184
	v_add_u32_e32 v181, 1, v172
	v_fma_f32 v185, -v178, v170, v161
	v_fma_f32 v190, -v182, v174, v168
	v_cndmask_b32_e64 v170, v170, v176, s[8:9]
	v_cmp_ge_f32_e64 s[8:9], 0, v188
	v_add_u32_e32 v183, 1, v174
	v_fma_f32 v189, -v181, v172, v165
	v_cndmask_b32_e64 v172, v172, v180, s[8:9]
	v_cmp_ge_f32_e64 s[8:9], 0, v190
	v_fma_f32 v191, -v183, v174, v168
	s_nop 0
	v_cndmask_b32_e64 v174, v174, v182, s[8:9]
	v_cmp_lt_f32_e64 s[8:9], 0, v185
	s_nop 1
	v_cndmask_b32_e64 v170, v170, v178, s[8:9]
	v_cmp_lt_f32_e64 s[8:9], 0, v189
	v_mul_f32_e32 v176, 0x37800000, v170
	v_cndmask_b32_e32 v170, v170, v176, vcc
	v_cndmask_b32_e64 v172, v172, v181, s[8:9]
	v_cmp_class_f32_e32 vcc, v161, v179
	v_mul_f32_e32 v178, 0x37800000, v172
	v_cndmask_b32_e64 v172, v172, v178, s[4:5]
	v_cndmask_b32_e32 v161, v170, v161, vcc
	v_div_scale_f32 v170, s[4:5], v161, v161, 1.0
	v_rcp_f32_e32 v178, v170
	v_cmp_class_f32_e32 vcc, v165, v179
	v_cmp_lt_f32_e64 s[8:9], 0, v191
	v_fma_f32 v182, -v170, v178, 1.0
	v_cndmask_b32_e32 v165, v172, v165, vcc
	v_div_scale_f32 v176, s[4:5], v165, v165, 1.0
	v_rcp_f32_e32 v180, v176
	v_div_scale_f32 v172, vcc, 1.0, v161, 1.0
	v_fmac_f32_e32 v178, v182, v178
	v_mul_f32_e32 v182, v172, v178
	v_fma_f32 v184, -v170, v182, v172
	v_cndmask_b32_e64 v174, v174, v183, s[8:9]
	v_fma_f32 v183, -v176, v180, 1.0
	v_fmac_f32_e32 v182, v184, v178
	v_div_scale_f32 v181, s[4:5], 1.0, v165, 1.0
	v_fmac_f32_e32 v180, v183, v180
	v_fma_f32 v170, -v170, v182, v172
	v_mul_f32_e32 v183, v181, v180
	v_div_fmas_f32 v170, v170, v178, v182
	v_fma_f32 v185, -v176, v183, v181
	v_div_fixup_f32 v178, v170, v161, 1.0
	v_mul_f32_e32 v161, 0x37800000, v174
	v_fmac_f32_e32 v183, v185, v180
	v_cndmask_b32_e64 v161, v174, v161, s[6:7]
	v_cmp_class_f32_e32 vcc, v168, v179
	v_fma_f32 v172, -v176, v183, v181
	v_pk_fma_f32 v[126:127], v[126:127], v[178:179], v[142:143] op_sel_hi:[1,0,1]
	v_cndmask_b32_e32 v161, v161, v168, vcc
	s_mov_b64 vcc, s[4:5]
	v_div_fmas_f32 v172, v172, v180, v183
	global_load_dwordx2 v[182:183], v[162:163], off offset:1152
	v_div_scale_f32 v168, s[6:7], v161, v161, 1.0
	v_rcp_f32_e32 v170, v168
	v_div_fixup_f32 v174, v172, v165, 1.0
	v_div_scale_f32 v176, vcc, 1.0, v161, 1.0
	v_fma_f32 v165, -v168, v170, 1.0
	v_fmac_f32_e32 v170, v165, v170
	v_ffbh_u32_e32 v165, v187
	v_min_u32_e32 v165, 32, v165
	v_lshlrev_b64 v[180:181], v165, v[186:187]
	v_min_u32_e32 v172, 1, v180
	v_or_b32_e32 v172, v181, v172
	v_cvt_f32_u32_e32 v172, v172
	v_sub_u32_e32 v165, 32, v165
	v_mul_f32_e32 v180, v176, v170
	v_fma_f32 v181, -v168, v180, v176
	v_ldexp_f32 v165, v172, v165
	v_mul_f32_e32 v165, 0x33800000, v165
	v_fmamk_f32 v165, v165, 0x3a000000, v177
	v_mul_f32_e32 v172, 0x4f800000, v165
	v_cmp_gt_f32_e64 s[4:5], s54, v165
	v_fmac_f32_e32 v180, v181, v170
	v_fma_f32 v168, -v168, v180, v176
	v_cndmask_b32_e64 v165, v165, v172, s[4:5]
	v_sqrt_f32_e32 v172, v165
	v_div_fmas_f32 v168, v168, v170, v180
; __device__ __forceinline__ int lane_asm() { int l; asm volatile("v_mbcnt_lo_u32_b32 %0, -1, 0\n\tv_mbcnt_hi_u32_b32 %0, -1, %0" : "=v"(l)); return l; }
; __device__ __forceinline__ float rstd_from_ssq(const unsigned long long* ssq, int row) {
;     return 1.0f / sqrtf((float)ssq[row] * (1.0f / 16777216.0f) * (1.0f / 2048.0f) + 1e-6f);
; }
; __device__ __forceinline__ f32x4 swiglu4(const f32x4 a, const f32x4 b) {
;     const f32x4 t = a * (-1.4426950408889634f); f32x4 e;
; #pragma unroll
;     for (int k = 0; k < 4; ++k) e[k] = __builtin_amdgcn_exp2f(t[k]);
;     e = e + 1.0f;
; #pragma unroll
;     for (int k = 0; k < 4; ++k) e[k] = __builtin_amdgcn_rcpf(e[k]);
;     return (a * e) * b;
; }
;     __device__ __forceinline__ void operator()(const f32x4 (&acc)[2][2][4][2], const Unit& u, int wr, int wc, int fr_, int fq_) const {
;         const int l_ = lane_asm(); const int fr = l_ & 15, fq = l_ >> 4; (void)fr_; (void)fq_;
;         const int row0 = u.pm * BM + wr * 64 + fr, col0 = u.pn * HALF + wc * 32 + 8 * fq;
;         f32x4 ba0 = {0.f, 0.f, 0.f, 0.f}, ba1 = ba0, bb0 = ba0, bb1 = ba0;
;         if constexpr (DEFER) { const float* bp = bv + u.pn * BM + wc * 32 + 8 * fq; ba0 = *(const f32x4*)bp; ba1 = *(const f32x4*)(bp + 4); bb0 = *(const f32x4*)(bp + HALF); bb1 = *(const f32x4*)(bp + HALF + 4); }
;         float rsv[8];
;         if constexpr (DEFER) {
; #pragma unroll
;             for (int i = 0; i < 8; ++i) rsv[i] = rstd_from_ssq(ssq, row0 + (i >> 2) * HALF + (i & 3) * 16);
;             asm volatile("" ::: "memory"); }
; #pragma unroll
;         for (int ai = 0; ai < 2; ++ai)
; #pragma unroll
;             for (int m = 0; m < 4; ++m) { const int row = row0 + ai * HALF + m * 16; bf16_t* rowp = O + (size_t)row * ldc + col0;
;                 f32x4 v0, v1;
;                 if constexpr (DEFER) { const float rs = rsv[ai * 4 + m];
;                     v0 = swiglu4(acc[ai][0][m][0] * rs + ba0, acc[ai][1][m][0] * rs + bb0); v1 = swiglu4(acc[ai][0][m][1] * rs + ba1, acc[ai][1][m][1] * rs + bb1); }
;                 else { v0 = swiglu4(acc[ai][0][m][0], acc[ai][1][m][0]); v1 = swiglu4(acc[ai][0][m][1], acc[ai][1][m][1]); }
;                 *(u32x4*)rowp = pack8(v0, v1); }
;     }
	v_pk_fma_f32 v[122:123], v[122:123], v[178:179], v[134:135] op_sel_hi:[1,0,1]
	v_pk_fma_f32 v[120:121], v[120:121], v[178:179], v[132:133] op_sel_hi:[1,0,1]
	v_add_u32_e32 v176, -1, v172
	v_fma_f32 v181, -v176, v172, v165
	v_cmp_ge_f32_e64 s[6:7], 0, v181
	v_add_u32_e32 v181, 1, v172
	v_pk_fma_f32 v[118:119], v[118:119], v[178:179], v[138:139] op_sel_hi:[1,0,1]
	v_cndmask_b32_e64 v176, v172, v176, s[6:7]
	v_fma_f32 v172, -v181, v172, v165
	v_cmp_lt_f32_e64 s[6:7], 0, v172
	v_pk_fma_f32 v[112:113], v[112:113], v[178:179], v[128:129] op_sel_hi:[1,0,1]
	v_pk_fma_f32 v[114:115], v[114:115], v[178:179], v[130:131] op_sel_hi:[1,0,1]
	v_cndmask_b32_e64 v172, v176, v181, s[6:7]
	global_load_dwordx2 v[180:181], v[162:163], off offset:1280
	s_nop 0
	global_load_dwordx2 v[162:163], v[162:163], off offset:1408
	v_mul_f32_e32 v176, 0x37800000, v172
	v_cndmask_b32_e64 v172, v172, v176, s[4:5]
	v_cmp_class_f32_e64 s[4:5], v165, v179
	v_pk_fma_f32 v[116:117], v[116:117], v[178:179], v[136:137] op_sel_hi:[1,0,1]
	v_pk_fma_f32 v[110:111], v[110:111], v[174:175], v[142:143] op_sel_hi:[1,0,1]
	v_cndmask_b32_e64 v165, v172, v165, s[4:5]
	v_div_scale_f32 v176, s[4:5], v165, v165, 1.0
	v_rcp_f32_e32 v184, v176
	v_div_fixup_f32 v172, v168, v161, 1.0
	v_pk_fma_f32 v[108:109], v[108:109], v[174:175], v[140:141] op_sel_hi:[1,0,1]
	v_pk_fma_f32 v[106:107], v[106:107], v[174:175], v[134:135] op_sel_hi:[1,0,1]
	v_fma_f32 v161, -v176, v184, 1.0
	v_fmac_f32_e32 v184, v161, v184
	v_ffbh_u32_e32 v161, v167
	v_min_u32_e32 v161, 32, v161
	v_lshlrev_b64 v[166:167], v161, v[166:167]
	v_min_u32_e32 v166, 1, v166
	v_or_b32_e32 v166, v167, v166
	v_cvt_f32_u32_e32 v166, v166
	v_sub_u32_e32 v161, 32, v161
	v_div_scale_f32 v167, vcc, 1.0, v165, 1.0
	v_ldexp_f32 v161, v166, v161
	v_mul_f32_e32 v161, 0x33800000, v161
	v_fmamk_f32 v161, v161, 0x3a000000, v177
	v_mul_f32_e32 v166, 0x4f800000, v161
	v_cmp_gt_f32_e64 s[4:5], s54, v161
	v_mul_f32_e32 v168, v167, v184
	v_fma_f32 v170, -v176, v168, v167
	v_cndmask_b32_e64 v161, v161, v166, s[4:5]
	v_sqrt_f32_e32 v166, v161
	v_fmac_f32_e32 v168, v170, v184
	v_fma_f32 v167, -v176, v168, v167
	v_pk_fma_f32 v[104:105], v[104:105], v[174:175], v[132:133] op_sel_hi:[1,0,1]
	v_add_u32_e32 v170, -1, v166
	v_fma_f32 v176, -v170, v166, v161
	v_cmp_ge_f32_e64 s[6:7], 0, v176
	v_add_u32_e32 v176, 1, v166
	v_pk_fma_f32 v[100:101], v[100:101], v[174:175], v[136:137] op_sel_hi:[1,0,1]
	v_cndmask_b32_e64 v170, v166, v170, s[6:7]
	v_fma_f32 v166, -v176, v166, v161
	v_cmp_lt_f32_e64 s[6:7], 0, v166
	v_pk_fma_f32 v[102:103], v[102:103], v[174:175], v[138:139] op_sel_hi:[1,0,1]
	v_pk_fma_f32 v[96:97], v[96:97], v[174:175], v[128:129] op_sel_hi:[1,0,1]
	v_cndmask_b32_e64 v166, v170, v176, s[6:7]
	v_mul_f32_e32 v170, 0x37800000, v166
	v_cndmask_b32_e64 v166, v166, v170, s[4:5]
	v_cmp_class_f32_e64 s[4:5], v161, v179
	v_pk_fma_f32 v[98:99], v[98:99], v[174:175], v[130:131] op_sel_hi:[1,0,1]
	v_pk_fma_f32 v[94:95], v[94:95], v[172:173], v[142:143] op_sel_hi:[1,0,1]
	v_cndmask_b32_e64 v170, v166, v161, s[4:5]
	v_div_scale_f32 v185, s[4:5], v170, v170, 1.0
	v_rcp_f32_e32 v186, v185
	v_div_fmas_f32 v161, v167, v184, v168
	v_div_fixup_f32 v176, v161, v165, 1.0
	v_pk_fma_f32 v[92:93], v[92:93], v[172:173], v[140:141] op_sel_hi:[1,0,1]
	v_fma_f32 v165, -v185, v186, 1.0
	v_fmac_f32_e32 v186, v165, v186
	s_waitcnt vmcnt(0) lgkmcnt(0)
	v_ffbh_u32_e32 v165, v183
	v_min_u32_e32 v165, 32, v165
	v_lshlrev_b64 v[166:167], v165, v[182:183]
	v_min_u32_e32 v166, 1, v166
	v_or_b32_e32 v166, v167, v166
	v_cvt_f32_u32_e32 v166, v166
	v_sub_u32_e32 v165, 32, v165
	v_div_scale_f32 v167, vcc, 1.0, v170, 1.0
	v_ldexp_f32 v165, v166, v165
	v_mul_f32_e32 v165, 0x33800000, v165
	v_fmamk_f32 v165, v165, 0x3a000000, v177
	v_mul_f32_e32 v166, 0x4f800000, v165
	v_cmp_gt_f32_e64 s[4:5], s54, v165
	v_mul_f32_e32 v168, v167, v186
	v_fma_f32 v182, -v185, v168, v167
	v_cndmask_b32_e64 v165, v165, v166, s[4:5]
	v_sqrt_f32_e32 v166, v165
	v_fmac_f32_e32 v168, v182, v186
	v_fma_f32 v167, -v185, v168, v167
	v_pk_fma_f32 v[184:185], v[124:125], v[178:179], v[140:141] op_sel_hi:[1,0,1]
	v_add_u32_e32 v182, -1, v166
	v_fma_f32 v183, -v182, v166, v165
	v_cmp_ge_f32_e64 s[6:7], 0, v183
	v_add_u32_e32 v183, 1, v166
	v_mul_f32_e32 v124, 0xbfb8aa3b, v184
	v_cndmask_b32_e64 v182, v166, v182, s[6:7]
	v_fma_f32 v166, -v183, v166, v165
	v_cmp_lt_f32_e64 s[6:7], 0, v166
	v_mul_f32_e32 v125, 0xbfb8aa3b, v126
	v_exp_f32_e32 v188, v125
	v_cndmask_b32_e64 v166, v182, v183, s[6:7]
	v_mul_f32_e32 v182, 0x37800000, v166
	v_cndmask_b32_e64 v166, v166, v182, s[4:5]
	v_cmp_class_f32_e64 s[4:5], v165, v179
	v_mul_f32_e32 v125, 0xbfb8aa3b, v127
	v_exp_f32_e32 v189, v125
	v_cndmask_b32_e64 v165, v166, v165, s[4:5]
	v_div_scale_f32 v182, s[4:5], v165, v165, 1.0
	v_rcp_f32_e32 v183, v182
	v_div_fmas_f32 v166, v167, v186, v168
	v_div_fixup_f32 v170, v166, v170, 1.0
	v_exp_f32_e32 v186, v124
	v_fma_f32 v166, -v182, v183, 1.0
	v_fmac_f32_e32 v183, v166, v183
	v_ffbh_u32_e32 v166, v181
	v_min_u32_e32 v168, 32, v166
	v_lshlrev_b64 v[166:167], v168, v[180:181]
	v_min_u32_e32 v166, 1, v166
	v_or_b32_e32 v166, v167, v166
	v_cvt_f32_u32_e32 v166, v166
	v_sub_u32_e32 v168, 32, v168
	v_div_scale_f32 v167, vcc, 1.0, v165, 1.0
	v_ldexp_f32 v166, v166, v168
	v_mul_f32_e32 v166, 0x33800000, v166
	v_fmamk_f32 v166, v166, 0x3a000000, v177
	v_mul_f32_e32 v168, 0x4f800000, v166
	v_cmp_gt_f32_e64 s[4:5], s54, v166
	v_mul_f32_e32 v180, v167, v183
	v_fma_f32 v181, -v182, v180, v167
	v_cndmask_b32_e64 v166, v166, v168, s[4:5]
	v_sqrt_f32_e32 v168, v166
	v_fmac_f32_e32 v180, v181, v183
	v_fma_f32 v167, -v182, v180, v167
	v_div_fmas_f32 v167, v167, v183, v180
; __device__ __forceinline__ int lane_asm() { int l; asm volatile("v_mbcnt_lo_u32_b32 %0, -1, 0\n\tv_mbcnt_hi_u32_b32 %0, -1, %0" : "=v"(l)); return l; }
; __device__ __forceinline__ u32x4 pack8(const f32x4& v0, const f32x4& v1) { u32x4 w; w.x = cvt_pk_bf16(v0[0], v0[1]); w.y = cvt_pk_bf16(v0[2], v0[3]); w.z = cvt_pk_bf16(v1[0], v1[1]); w.w = cvt_pk_bf16(v1[2], v1[3]); return w; }
; __device__ __forceinline__ f32x4 swiglu4(const f32x4 a, const f32x4 b) {
;     const f32x4 t = a * (-1.4426950408889634f); f32x4 e;
; #pragma unroll
;     for (int k = 0; k < 4; ++k) e[k] = __builtin_amdgcn_exp2f(t[k]);
;     e = e + 1.0f;
; #pragma unroll
;     for (int k = 0; k < 4; ++k) e[k] = __builtin_amdgcn_rcpf(e[k]);
;     return (a * e) * b;
; }
;     __device__ __forceinline__ void operator()(const f32x4 (&acc)[2][2][4][2], const Unit& u, int wr, int wc, int fr_, int fq_) const {
;         const int l_ = lane_asm(); const int fr = l_ & 15, fq = l_ >> 4; (void)fr_; (void)fq_;
;         const int row0 = u.pm * BM + wr * 64 + fr, col0 = u.pn * HALF + wc * 32 + 8 * fq;
;         f32x4 ba0 = {0.f, 0.f, 0.f, 0.f}, ba1 = ba0, bb0 = ba0, bb1 = ba0;
;         if constexpr (DEFER) { const float* bp = bv + u.pn * BM + wc * 32 + 8 * fq; ba0 = *(const f32x4*)bp; ba1 = *(const f32x4*)(bp + 4); bb0 = *(const f32x4*)(bp + HALF); bb1 = *(const f32x4*)(bp + HALF + 4); }
;         float rsv[8];
;         if constexpr (DEFER) {
; #pragma unroll
;             for (int i = 0; i < 8; ++i) rsv[i] = rstd_from_ssq(ssq, row0 + (i >> 2) * HALF + (i & 3) * 16);
;             asm volatile("" ::: "memory"); }
; #pragma unroll
;         for (int ai = 0; ai < 2; ++ai)
; #pragma unroll
;             for (int m = 0; m < 4; ++m) { const int row = row0 + ai * HALF + m * 16; bf16_t* rowp = O + (size_t)row * ldc + col0;
;                 f32x4 v0, v1;
;                 if constexpr (DEFER) { const float rs = rsv[ai * 4 + m];
;                     v0 = swiglu4(acc[ai][0][m][0] * rs + ba0, acc[ai][1][m][0] * rs + bb0); v1 = swiglu4(acc[ai][0][m][1] * rs + ba1, acc[ai][1][m][1] * rs + bb1); }
;                 else { v0 = swiglu4(acc[ai][0][m][0], acc[ai][1][m][0]); v1 = swiglu4(acc[ai][0][m][1], acc[ai][1][m][1]); }
;                 *(u32x4*)rowp = pack8(v0, v1); }
	v_add_u32_e32 v181, -1, v168
	v_fma_f32 v182, -v181, v168, v166
	v_cmp_ge_f32_e64 s[6:7], 0, v182
	v_add_u32_e32 v182, 1, v168
	v_mul_f32_e32 v124, 0xbfb8aa3b, v185
	v_cndmask_b32_e64 v181, v168, v181, s[6:7]
	v_fma_f32 v168, -v182, v168, v166
	v_cmp_lt_f32_e64 s[6:7], 0, v168
	v_exp_f32_e32 v187, v124
	v_pk_fma_f32 v[90:91], v[90:91], v[172:173], v[134:135] op_sel_hi:[1,0,1]
	v_cndmask_b32_e64 v168, v181, v182, s[6:7]
	v_mul_f32_e32 v181, 0x37800000, v168
	v_cndmask_b32_e64 v168, v168, v181, s[4:5]
	v_cmp_class_f32_e64 s[4:5], v166, v179
	v_pk_add_f32 v[186:187], v[186:187], 1.0 op_sel_hi:[1,0]
	v_pk_fma_f32 v[88:89], v[88:89], v[172:173], v[132:133] op_sel_hi:[1,0,1]
	v_cndmask_b32_e64 v166, v168, v166, s[4:5]
	v_div_scale_f32 v181, s[4:5], v166, v166, 1.0
	v_rcp_f32_e32 v182, v181
	v_div_fixup_f32 v168, v167, v165, 1.0
	v_rcp_f32_e32 v186, v186
	v_rcp_f32_e32 v187, v187
	v_fma_f32 v165, -v181, v182, 1.0
	v_fmac_f32_e32 v182, v165, v182
	v_ffbh_u32_e32 v165, v163
	v_min_u32_e32 v165, 32, v165
	v_lshlrev_b64 v[162:163], v165, v[162:163]
	v_min_u32_e32 v162, 1, v162
	v_or_b32_e32 v162, v163, v162
	v_cvt_f32_u32_e32 v162, v162
	v_sub_u32_e32 v165, 32, v165
	v_div_scale_f32 v163, vcc, 1.0, v166, 1.0
	v_ldexp_f32 v162, v162, v165
	v_mul_f32_e32 v162, 0x33800000, v162
	v_fmamk_f32 v162, v162, 0x3a000000, v177
	v_mul_f32_e32 v165, 0x4f800000, v162
	v_cmp_gt_f32_e64 s[4:5], s54, v162
	v_mul_f32_e32 v167, v163, v182
	v_fma_f32 v180, -v181, v167, v163
	v_cndmask_b32_e64 v162, v162, v165, s[4:5]
	v_sqrt_f32_e32 v165, v162
	v_fmac_f32_e32 v167, v180, v182
	v_fma_f32 v163, -v181, v167, v163
	v_div_fmas_f32 v163, v163, v182, v167
	v_add_u32_e32 v180, -1, v165
	v_fma_f32 v181, -v180, v165, v162
	v_cmp_ge_f32_e64 s[6:7], 0, v181
	v_add_u32_e32 v181, 1, v165
	v_div_fixup_f32 v166, v163, v166, 1.0
	v_cndmask_b32_e64 v180, v165, v180, s[6:7]
	v_fma_f32 v165, -v181, v165, v162
	v_cmp_lt_f32_e64 s[6:7], 0, v165
	v_pk_mul_f32 v[184:185], v[184:185], v[186:187]
	v_pk_fma_f32 v[84:85], v[84:85], v[172:173], v[136:137] op_sel_hi:[1,0,1]
	v_cndmask_b32_e64 v165, v180, v181, s[6:7]
	v_mul_f32_e32 v180, 0x37800000, v165
	v_cndmask_b32_e64 v165, v165, v180, s[4:5]
	v_cmp_class_f32_e64 s[4:5], v162, v179
	v_pk_mul_f32 v[116:117], v[116:117], v[184:185]
	v_pk_fma_f32 v[86:87], v[86:87], v[172:173], v[138:139] op_sel_hi:[1,0,1]
	v_cndmask_b32_e64 v162, v165, v162, s[4:5]
	v_div_scale_f32 v165, s[4:5], v162, v162, 1.0
	v_rcp_f32_e32 v180, v165
	s_lshl_b32 s4, s56, 7
	s_or_b32 s4, s4, s44
	v_pk_fma_f32 v[80:81], v[80:81], v[172:173], v[128:129] op_sel_hi:[1,0,1]
	v_fma_f32 v163, -v165, v180, 1.0
	v_fmac_f32_e32 v180, v163, v180
	v_div_scale_f32 v163, vcc, 1.0, v162, 1.0
	v_mul_f32_e32 v167, v163, v180
	v_fma_f32 v181, -v165, v167, v163
	v_fmac_f32_e32 v167, v181, v180
	v_fma_f32 v163, -v165, v167, v163
	v_div_fmas_f32 v163, v163, v180, v167
	v_add_u32_e32 v180, s4, v164
	v_ashrrev_i32_e32 v181, 31, v180
	v_mov_b64_e32 v[164:165], s[14:15]
	v_mad_i64_i32 v[182:183], s[4:5], v160, s55, v[164:165]
	v_lshlrev_b64 v[124:125], 1, v[180:181]
	v_lshl_add_u64 v[180:181], v[182:183], 0, v[124:125]
	v_pk_add_f32 v[182:183], v[188:189], 1.0 op_sel_hi:[1,0]
	v_div_fixup_f32 v162, v163, v162, 1.0
	v_rcp_f32_e32 v182, v182
	v_rcp_f32_e32 v183, v183
	v_mul_f32_e32 v163, 0xbfb8aa3b, v120
	v_mul_f32_e32 v167, 0xbfb8aa3b, v122
	v_exp_f32_e32 v186, v167
	v_pk_mul_f32 v[126:127], v[126:127], v[182:183]
	v_exp_f32_e32 v182, v163
	v_mul_f32_e32 v163, 0xbfb8aa3b, v121
	v_mul_f32_e32 v167, 0xbfb8aa3b, v123
	v_exp_f32_e32 v187, v167
	v_exp_f32_e32 v183, v163
	v_pk_mul_f32 v[118:119], v[118:119], v[126:127]
	v_pk_fma_f32 v[82:83], v[82:83], v[172:173], v[130:131] op_sel_hi:[1,0,1]
	v_pk_add_f32 v[126:127], v[186:187], 1.0 op_sel_hi:[1,0]
	v_pk_add_f32 v[182:183], v[182:183], 1.0 op_sel_hi:[1,0]
	v_rcp_f32_e32 v126, v126
	v_rcp_f32_e32 v182, v182
	v_rcp_f32_e32 v183, v183
	v_rcp_f32_e32 v127, v127
	v_pk_fma_f32 v[78:79], v[78:79], v[176:177], v[142:143] op_sel_hi:[1,0,1]
	v_pk_fma_f32 v[76:77], v[76:77], v[176:177], v[140:141] op_sel_hi:[1,0,1]
	v_pk_mul_f32 v[120:121], v[120:121], v[182:183]
	v_pk_mul_f32 v[122:123], v[122:123], v[126:127]
	v_pk_fma_f32 v[74:75], v[74:75], v[176:177], v[134:135] op_sel_hi:[1,0,1]
	v_pk_mul_f32 v[122:123], v[114:115], v[122:123]
	v_pk_mul_f32 v[114:115], v[112:113], v[120:121]
	v_cvt_pk_bf16_f32 v112, v116, v117
	v_cvt_pk_bf16_f32 v113, v118, v119
	v_or_b32_e32 v116, 16, v160
	v_cvt_pk_bf16_f32 v114, v114, v115
	v_cvt_pk_bf16_f32 v115, v122, v123
	global_store_dwordx4 v[180:181], v[112:115], off
	v_mad_i64_i32 v[116:117], s[4:5], v116, s55, v[164:165]
	s_nop 0
	v_mul_f32_e32 v112, 0xbfb8aa3b, v108
	v_mul_f32_e32 v113, 0xbfb8aa3b, v109
	v_mul_f32_e32 v114, 0xbfb8aa3b, v110
	v_mul_f32_e32 v115, 0xbfb8aa3b, v111
	v_exp_f32_e32 v112, v112
	v_exp_f32_e32 v113, v113
	v_exp_f32_e32 v114, v114
	v_exp_f32_e32 v115, v115
	v_lshl_add_u64 v[116:117], v[116:117], 0, v[124:125]
	v_pk_add_f32 v[112:113], v[112:113], 1.0 op_sel_hi:[1,0]
	v_pk_fma_f32 v[72:73], v[72:73], v[176:177], v[132:133] op_sel_hi:[1,0,1]
	v_pk_add_f32 v[114:115], v[114:115], 1.0 op_sel_hi:[1,0]
	v_rcp_f32_e32 v112, v112
	v_rcp_f32_e32 v113, v113
	v_rcp_f32_e32 v114, v114
	v_rcp_f32_e32 v115, v115
	v_pk_fma_f32 v[68:69], v[68:69], v[176:177], v[136:137] op_sel_hi:[1,0,1]
	v_pk_mul_f32 v[108:109], v[108:109], v[112:113]
	v_mul_f32_e32 v112, 0xbfb8aa3b, v104
	v_pk_mul_f32 v[110:111], v[110:111], v[114:115]
	v_mul_f32_e32 v113, 0xbfb8aa3b, v105
	v_mul_f32_e32 v114, 0xbfb8aa3b, v106
	v_mul_f32_e32 v115, 0xbfb8aa3b, v107
	v_exp_f32_e32 v112, v112
	v_exp_f32_e32 v114, v114
	v_exp_f32_e32 v115, v115
; __device__ __forceinline__ int lane_asm() { int l; asm volatile("v_mbcnt_lo_u32_b32 %0, -1, 0\n\tv_mbcnt_hi_u32_b32 %0, -1, %0" : "=v"(l)); return l; }
; __device__ __forceinline__ u32x4 pack8(const f32x4& v0, const f32x4& v1) { u32x4 w; w.x = cvt_pk_bf16(v0[0], v0[1]); w.y = cvt_pk_bf16(v0[2], v0[3]); w.z = cvt_pk_bf16(v1[0], v1[1]); w.w = cvt_pk_bf16(v1[2], v1[3]); return w; }
; __device__ __forceinline__ f32x4 swiglu4(const f32x4 a, const f32x4 b) {
;     const f32x4 t = a * (-1.4426950408889634f); f32x4 e;
; #pragma unroll
;     for (int k = 0; k < 4; ++k) e[k] = __builtin_amdgcn_exp2f(t[k]);
;     e = e + 1.0f;
; #pragma unroll
;     for (int k = 0; k < 4; ++k) e[k] = __builtin_amdgcn_rcpf(e[k]);
;     return (a * e) * b;
; }
;     __device__ __forceinline__ void operator()(const f32x4 (&acc)[2][2][4][2], const Unit& u, int wr, int wc, int fr_, int fq_) const {
;         const int l_ = lane_asm(); const int fr = l_ & 15, fq = l_ >> 4; (void)fr_; (void)fq_;
;         const int row0 = u.pm * BM + wr * 64 + fr, col0 = u.pn * HALF + wc * 32 + 8 * fq;
;         f32x4 ba0 = {0.f, 0.f, 0.f, 0.f}, ba1 = ba0, bb0 = ba0, bb1 = ba0;
;         if constexpr (DEFER) { const float* bp = bv + u.pn * BM + wc * 32 + 8 * fq; ba0 = *(const f32x4*)bp; ba1 = *(const f32x4*)(bp + 4); bb0 = *(const f32x4*)(bp + HALF); bb1 = *(const f32x4*)(bp + HALF + 4); }
;         float rsv[8];
;         if constexpr (DEFER) {
; #pragma unroll
;             for (int i = 0; i < 8; ++i) rsv[i] = rstd_from_ssq(ssq, row0 + (i >> 2) * HALF + (i & 3) * 16);
;             asm volatile("" ::: "memory"); }
; #pragma unroll
;         for (int ai = 0; ai < 2; ++ai)
; #pragma unroll
;             for (int m = 0; m < 4; ++m) { const int row = row0 + ai * HALF + m * 16; bf16_t* rowp = O + (size_t)row * ldc + col0;
;                 f32x4 v0, v1;
;                 if constexpr (DEFER) { const float rs = rsv[ai * 4 + m];
;                     v0 = swiglu4(acc[ai][0][m][0] * rs + ba0, acc[ai][1][m][0] * rs + bb0); v1 = swiglu4(acc[ai][0][m][1] * rs + ba1, acc[ai][1][m][1] * rs + bb1); }
;                 else { v0 = swiglu4(acc[ai][0][m][0], acc[ai][1][m][0]); v1 = swiglu4(acc[ai][0][m][1], acc[ai][1][m][1]); }
;                 *(u32x4*)rowp = pack8(v0, v1); }
	v_exp_f32_e32 v113, v113
	v_pk_mul_f32 v[102:103], v[102:103], v[110:111]
	v_pk_mul_f32 v[100:101], v[100:101], v[108:109]
	v_pk_add_f32 v[108:109], v[114:115], 1.0 op_sel_hi:[1,0]
	v_pk_add_f32 v[110:111], v[112:113], 1.0 op_sel_hi:[1,0]
	v_rcp_f32_e32 v108, v108
	v_rcp_f32_e32 v110, v110
	v_rcp_f32_e32 v111, v111
	v_rcp_f32_e32 v109, v109
	v_pk_fma_f32 v[70:71], v[70:71], v[176:177], v[138:139] op_sel_hi:[1,0,1]
	v_pk_fma_f32 v[64:65], v[64:65], v[176:177], v[128:129] op_sel_hi:[1,0,1]
	v_pk_mul_f32 v[104:105], v[104:105], v[110:111]
	v_pk_mul_f32 v[106:107], v[106:107], v[108:109]
	v_pk_fma_f32 v[66:67], v[66:67], v[176:177], v[130:131] op_sel_hi:[1,0,1]
	v_pk_mul_f32 v[106:107], v[98:99], v[106:107]
	v_pk_mul_f32 v[98:99], v[96:97], v[104:105]
	v_cvt_pk_bf16_f32 v96, v100, v101
	v_cvt_pk_bf16_f32 v97, v102, v103
	v_or_b32_e32 v100, 32, v160
	v_cvt_pk_bf16_f32 v98, v98, v99
	v_cvt_pk_bf16_f32 v99, v106, v107
	global_store_dwordx4 v[116:117], v[96:99], off
	v_mad_i64_i32 v[100:101], s[4:5], v100, s55, v[164:165]
	s_nop 0
	v_mul_f32_e32 v96, 0xbfb8aa3b, v92
	v_mul_f32_e32 v97, 0xbfb8aa3b, v93
	v_mul_f32_e32 v98, 0xbfb8aa3b, v94
	v_mul_f32_e32 v99, 0xbfb8aa3b, v95
	v_exp_f32_e32 v96, v96
	v_exp_f32_e32 v97, v97
	v_exp_f32_e32 v98, v98
	v_exp_f32_e32 v99, v99
	v_lshl_add_u64 v[100:101], v[100:101], 0, v[124:125]
	v_pk_add_f32 v[96:97], v[96:97], 1.0 op_sel_hi:[1,0]
	v_pk_fma_f32 v[62:63], v[62:63], v[170:171], v[142:143] op_sel_hi:[1,0,1]
	v_pk_add_f32 v[98:99], v[98:99], 1.0 op_sel_hi:[1,0]
	v_rcp_f32_e32 v96, v96
	v_rcp_f32_e32 v97, v97
	v_rcp_f32_e32 v98, v98
	v_rcp_f32_e32 v99, v99
	v_pk_fma_f32 v[60:61], v[60:61], v[170:171], v[140:141] op_sel_hi:[1,0,1]
	v_pk_mul_f32 v[92:93], v[92:93], v[96:97]
	v_mul_f32_e32 v96, 0xbfb8aa3b, v88
	v_pk_mul_f32 v[94:95], v[94:95], v[98:99]
	v_mul_f32_e32 v97, 0xbfb8aa3b, v89
	v_mul_f32_e32 v98, 0xbfb8aa3b, v90
	v_mul_f32_e32 v99, 0xbfb8aa3b, v91
	v_exp_f32_e32 v96, v96
	v_exp_f32_e32 v98, v98
	v_exp_f32_e32 v99, v99
	v_exp_f32_e32 v97, v97
	v_pk_mul_f32 v[86:87], v[86:87], v[94:95]
	v_pk_mul_f32 v[84:85], v[84:85], v[92:93]
	v_pk_add_f32 v[92:93], v[98:99], 1.0 op_sel_hi:[1,0]
	v_pk_add_f32 v[94:95], v[96:97], 1.0 op_sel_hi:[1,0]
	v_rcp_f32_e32 v92, v92
	v_rcp_f32_e32 v94, v94
	v_rcp_f32_e32 v95, v95
	v_rcp_f32_e32 v93, v93
	v_pk_fma_f32 v[58:59], v[58:59], v[170:171], v[134:135] op_sel_hi:[1,0,1]
	v_pk_fma_f32 v[56:57], v[56:57], v[170:171], v[132:133] op_sel_hi:[1,0,1]
	v_pk_mul_f32 v[88:89], v[88:89], v[94:95]
	v_pk_mul_f32 v[90:91], v[90:91], v[92:93]
	v_pk_fma_f32 v[52:53], v[52:53], v[170:171], v[136:137] op_sel_hi:[1,0,1]
	v_pk_mul_f32 v[90:91], v[82:83], v[90:91]
	v_pk_mul_f32 v[82:83], v[80:81], v[88:89]
	v_cvt_pk_bf16_f32 v80, v84, v85
	v_cvt_pk_bf16_f32 v81, v86, v87
	v_or_b32_e32 v84, 48, v160
	v_cvt_pk_bf16_f32 v82, v82, v83
	v_cvt_pk_bf16_f32 v83, v90, v91
	global_store_dwordx4 v[100:101], v[80:83], off
	v_mad_i64_i32 v[84:85], s[4:5], v84, s55, v[164:165]
	s_nop 0
	v_mul_f32_e32 v80, 0xbfb8aa3b, v76
	v_mul_f32_e32 v81, 0xbfb8aa3b, v77
	v_mul_f32_e32 v82, 0xbfb8aa3b, v78
	v_mul_f32_e32 v83, 0xbfb8aa3b, v79
	v_exp_f32_e32 v80, v80
	v_exp_f32_e32 v81, v81
	v_exp_f32_e32 v82, v82
	v_exp_f32_e32 v83, v83
	v_lshl_add_u64 v[84:85], v[84:85], 0, v[124:125]
	v_pk_add_f32 v[80:81], v[80:81], 1.0 op_sel_hi:[1,0]
	v_pk_fma_f32 v[54:55], v[54:55], v[170:171], v[138:139] op_sel_hi:[1,0,1]
	v_pk_add_f32 v[82:83], v[82:83], 1.0 op_sel_hi:[1,0]
	v_rcp_f32_e32 v80, v80
	v_rcp_f32_e32 v81, v81
	v_rcp_f32_e32 v82, v82
	v_rcp_f32_e32 v83, v83
	v_add_u32_e32 v161, 0x80, v160
	v_pk_mul_f32 v[76:77], v[76:77], v[80:81]
	v_mul_f32_e32 v80, 0xbfb8aa3b, v72
	v_pk_mul_f32 v[78:79], v[78:79], v[82:83]
	v_mul_f32_e32 v81, 0xbfb8aa3b, v73
	v_mul_f32_e32 v82, 0xbfb8aa3b, v74
	v_mul_f32_e32 v83, 0xbfb8aa3b, v75
	v_exp_f32_e32 v80, v80
	v_exp_f32_e32 v82, v82
	v_exp_f32_e32 v83, v83
	v_exp_f32_e32 v81, v81
	v_pk_mul_f32 v[70:71], v[70:71], v[78:79]
	v_pk_mul_f32 v[68:69], v[68:69], v[76:77]
	v_pk_add_f32 v[76:77], v[82:83], 1.0 op_sel_hi:[1,0]
	v_pk_add_f32 v[78:79], v[80:81], 1.0 op_sel_hi:[1,0]
	v_rcp_f32_e32 v76, v76
	v_rcp_f32_e32 v78, v78
	v_rcp_f32_e32 v79, v79
	v_rcp_f32_e32 v77, v77
	v_pk_fma_f32 v[48:49], v[48:49], v[170:171], v[128:129] op_sel_hi:[1,0,1]
	v_pk_fma_f32 v[50:51], v[50:51], v[170:171], v[130:131] op_sel_hi:[1,0,1]
	v_pk_mul_f32 v[72:73], v[72:73], v[78:79]
	v_pk_mul_f32 v[74:75], v[74:75], v[76:77]
	v_pk_fma_f32 v[46:47], v[46:47], v[168:169], v[142:143] op_sel_hi:[1,0,1]
	v_pk_mul_f32 v[74:75], v[66:67], v[74:75]
	v_pk_mul_f32 v[66:67], v[64:65], v[72:73]
	v_cvt_pk_bf16_f32 v64, v68, v69
	v_cvt_pk_bf16_f32 v65, v70, v71
	v_mad_i64_i32 v[68:69], s[4:5], v161, s55, v[164:165]
	v_cvt_pk_bf16_f32 v66, v66, v67
	v_cvt_pk_bf16_f32 v67, v74, v75
	global_store_dwordx4 v[84:85], v[64:67], off
	v_lshl_add_u64 v[68:69], v[68:69], 0, v[124:125]
	v_pk_fma_f32 v[44:45], v[44:45], v[168:169], v[140:141] op_sel_hi:[1,0,1]
	v_mul_f32_e32 v64, 0xbfb8aa3b, v60
	v_mul_f32_e32 v65, 0xbfb8aa3b, v61
	v_mul_f32_e32 v66, 0xbfb8aa3b, v62
	v_mul_f32_e32 v67, 0xbfb8aa3b, v63
	v_exp_f32_e32 v64, v64
	v_exp_f32_e32 v65, v65
	v_exp_f32_e32 v66, v66
	v_exp_f32_e32 v67, v67
	v_pk_fma_f32 v[42:43], v[42:43], v[168:169], v[134:135] op_sel_hi:[1,0,1]
	v_pk_add_f32 v[64:65], v[64:65], 1.0 op_sel_hi:[1,0]
	v_pk_fma_f32 v[40:41], v[40:41], v[168:169], v[132:133] op_sel_hi:[1,0,1]
	v_pk_add_f32 v[66:67], v[66:67], 1.0 op_sel_hi:[1,0]
	v_rcp_f32_e32 v64, v64
	v_rcp_f32_e32 v65, v65
	v_rcp_f32_e32 v66, v66
	v_rcp_f32_e32 v67, v67
	v_pk_fma_f32 v[36:37], v[36:37], v[168:169], v[136:137] op_sel_hi:[1,0,1]
	v_pk_mul_f32 v[60:61], v[60:61], v[64:65]
; __device__ __forceinline__ int lane_asm() { int l; asm volatile("v_mbcnt_lo_u32_b32 %0, -1, 0\n\tv_mbcnt_hi_u32_b32 %0, -1, %0" : "=v"(l)); return l; }
; __device__ __forceinline__ u32x4 pack8(const f32x4& v0, const f32x4& v1) { u32x4 w; w.x = cvt_pk_bf16(v0[0], v0[1]); w.y = cvt_pk_bf16(v0[2], v0[3]); w.z = cvt_pk_bf16(v1[0], v1[1]); w.w = cvt_pk_bf16(v1[2], v1[3]); return w; }
; __device__ __forceinline__ f32x4 swiglu4(const f32x4 a, const f32x4 b) {
;     const f32x4 t = a * (-1.4426950408889634f); f32x4 e;
; #pragma unroll
;     for (int k = 0; k < 4; ++k) e[k] = __builtin_amdgcn_exp2f(t[k]);
;     e = e + 1.0f;
; #pragma unroll
;     for (int k = 0; k < 4; ++k) e[k] = __builtin_amdgcn_rcpf(e[k]);
;     return (a * e) * b;
; }
;     __device__ __forceinline__ void operator()(const f32x4 (&acc)[2][2][4][2], const Unit& u, int wr, int wc, int fr_, int fq_) const {
;         const int l_ = lane_asm(); const int fr = l_ & 15, fq = l_ >> 4; (void)fr_; (void)fq_;
;         const int row0 = u.pm * BM + wr * 64 + fr, col0 = u.pn * HALF + wc * 32 + 8 * fq;
;         f32x4 ba0 = {0.f, 0.f, 0.f, 0.f}, ba1 = ba0, bb0 = ba0, bb1 = ba0;
;         if constexpr (DEFER) { const float* bp = bv + u.pn * BM + wc * 32 + 8 * fq; ba0 = *(const f32x4*)bp; ba1 = *(const f32x4*)(bp + 4); bb0 = *(const f32x4*)(bp + HALF); bb1 = *(const f32x4*)(bp + HALF + 4); }
;         float rsv[8];
;         if constexpr (DEFER) {
; #pragma unroll
;             for (int i = 0; i < 8; ++i) rsv[i] = rstd_from_ssq(ssq, row0 + (i >> 2) * HALF + (i & 3) * 16);
;             asm volatile("" ::: "memory"); }
; #pragma unroll
;         for (int ai = 0; ai < 2; ++ai)
; #pragma unroll
;             for (int m = 0; m < 4; ++m) { const int row = row0 + ai * HALF + m * 16; bf16_t* rowp = O + (size_t)row * ldc + col0;
;                 f32x4 v0, v1;
;                 if constexpr (DEFER) { const float rs = rsv[ai * 4 + m];
;                     v0 = swiglu4(acc[ai][0][m][0] * rs + ba0, acc[ai][1][m][0] * rs + bb0); v1 = swiglu4(acc[ai][0][m][1] * rs + ba1, acc[ai][1][m][1] * rs + bb1); }
;                 else { v0 = swiglu4(acc[ai][0][m][0], acc[ai][1][m][0]); v1 = swiglu4(acc[ai][0][m][1], acc[ai][1][m][1]); }
;                 *(u32x4*)rowp = pack8(v0, v1); }
	v_mul_f32_e32 v64, 0xbfb8aa3b, v56
	v_pk_mul_f32 v[62:63], v[62:63], v[66:67]
	v_mul_f32_e32 v65, 0xbfb8aa3b, v57
	v_mul_f32_e32 v66, 0xbfb8aa3b, v58
	v_mul_f32_e32 v67, 0xbfb8aa3b, v59
	v_exp_f32_e32 v64, v64
	v_exp_f32_e32 v66, v66
	v_exp_f32_e32 v67, v67
	v_exp_f32_e32 v65, v65
	v_pk_mul_f32 v[54:55], v[54:55], v[62:63]
	v_pk_mul_f32 v[52:53], v[52:53], v[60:61]
	v_pk_add_f32 v[60:61], v[66:67], 1.0 op_sel_hi:[1,0]
	v_pk_add_f32 v[62:63], v[64:65], 1.0 op_sel_hi:[1,0]
	v_rcp_f32_e32 v60, v60
	v_rcp_f32_e32 v62, v62
	v_rcp_f32_e32 v63, v63
	v_rcp_f32_e32 v61, v61
	v_pk_fma_f32 v[38:39], v[38:39], v[168:169], v[138:139] op_sel_hi:[1,0,1]
	v_pk_fma_f32 v[32:33], v[32:33], v[168:169], v[128:129] op_sel_hi:[1,0,1]
	v_pk_mul_f32 v[56:57], v[56:57], v[62:63]
	v_pk_mul_f32 v[58:59], v[58:59], v[60:61]
	v_pk_fma_f32 v[34:35], v[34:35], v[168:169], v[130:131] op_sel_hi:[1,0,1]
	v_pk_mul_f32 v[58:59], v[50:51], v[58:59]
	v_pk_mul_f32 v[50:51], v[48:49], v[56:57]
	v_cvt_pk_bf16_f32 v48, v52, v53
	v_cvt_pk_bf16_f32 v49, v54, v55
	v_add_u32_e32 v52, 0x90, v160
	v_cvt_pk_bf16_f32 v50, v50, v51
	v_cvt_pk_bf16_f32 v51, v58, v59
	global_store_dwordx4 v[68:69], v[48:51], off
	v_mad_i64_i32 v[52:53], s[4:5], v52, s55, v[164:165]
	s_nop 0
	v_mul_f32_e32 v48, 0xbfb8aa3b, v44
	v_mul_f32_e32 v49, 0xbfb8aa3b, v45
	v_mul_f32_e32 v50, 0xbfb8aa3b, v46
	v_mul_f32_e32 v51, 0xbfb8aa3b, v47
	v_exp_f32_e32 v48, v48
	v_exp_f32_e32 v49, v49
	v_exp_f32_e32 v50, v50
	v_exp_f32_e32 v51, v51
	v_lshl_add_u64 v[52:53], v[52:53], 0, v[124:125]
	v_pk_add_f32 v[48:49], v[48:49], 1.0 op_sel_hi:[1,0]
	v_pk_fma_f32 v[30:31], v[30:31], v[166:167], v[142:143] op_sel_hi:[1,0,1]
	v_pk_add_f32 v[50:51], v[50:51], 1.0 op_sel_hi:[1,0]
	v_rcp_f32_e32 v48, v48
	v_rcp_f32_e32 v49, v49
	v_rcp_f32_e32 v50, v50
	v_rcp_f32_e32 v51, v51
	v_pk_fma_f32 v[28:29], v[28:29], v[166:167], v[140:141] op_sel_hi:[1,0,1]
	v_pk_mul_f32 v[44:45], v[44:45], v[48:49]
	v_mul_f32_e32 v48, 0xbfb8aa3b, v40
	v_pk_mul_f32 v[46:47], v[46:47], v[50:51]
	v_mul_f32_e32 v49, 0xbfb8aa3b, v41
	v_mul_f32_e32 v50, 0xbfb8aa3b, v42
	v_mul_f32_e32 v51, 0xbfb8aa3b, v43
	v_exp_f32_e32 v48, v48
	v_exp_f32_e32 v50, v50
	v_exp_f32_e32 v51, v51
	v_exp_f32_e32 v49, v49
	v_pk_mul_f32 v[38:39], v[38:39], v[46:47]
	v_pk_mul_f32 v[36:37], v[36:37], v[44:45]
	v_pk_add_f32 v[44:45], v[50:51], 1.0 op_sel_hi:[1,0]
	v_pk_add_f32 v[46:47], v[48:49], 1.0 op_sel_hi:[1,0]
	v_rcp_f32_e32 v44, v44
	v_rcp_f32_e32 v46, v46
	v_rcp_f32_e32 v47, v47
	v_rcp_f32_e32 v45, v45
	v_pk_fma_f32 v[26:27], v[26:27], v[166:167], v[134:135] op_sel_hi:[1,0,1]
	v_pk_fma_f32 v[24:25], v[24:25], v[166:167], v[132:133] op_sel_hi:[1,0,1]
	v_pk_mul_f32 v[40:41], v[40:41], v[46:47]
	v_pk_mul_f32 v[42:43], v[42:43], v[44:45]
	v_pk_fma_f32 v[20:21], v[20:21], v[166:167], v[136:137] op_sel_hi:[1,0,1]
	v_pk_mul_f32 v[42:43], v[34:35], v[42:43]
	v_pk_mul_f32 v[34:35], v[32:33], v[40:41]
	v_cvt_pk_bf16_f32 v32, v36, v37
	v_cvt_pk_bf16_f32 v33, v38, v39
	v_pk_fma_f32 v[22:23], v[22:23], v[166:167], v[138:139] op_sel_hi:[1,0,1]
	v_cvt_pk_bf16_f32 v34, v34, v35
	v_cvt_pk_bf16_f32 v35, v42, v43
	global_store_dwordx4 v[52:53], v[32:35], off
	v_add_u32_e32 v36, 0xa0, v160
	v_pk_fma_f32 v[16:17], v[16:17], v[166:167], v[128:129] op_sel_hi:[1,0,1]
	v_mul_f32_e32 v32, 0xbfb8aa3b, v28
	v_mul_f32_e32 v33, 0xbfb8aa3b, v29
	v_mul_f32_e32 v34, 0xbfb8aa3b, v30
	v_mul_f32_e32 v35, 0xbfb8aa3b, v31
	v_exp_f32_e32 v32, v32
	v_exp_f32_e32 v33, v33
	v_exp_f32_e32 v34, v34
	v_exp_f32_e32 v35, v35
	v_pk_fma_f32 v[18:19], v[18:19], v[166:167], v[130:131] op_sel_hi:[1,0,1]
	v_pk_add_f32 v[32:33], v[32:33], 1.0 op_sel_hi:[1,0]
	v_mad_i64_i32 v[36:37], s[4:5], v36, s55, v[164:165]
	v_pk_add_f32 v[34:35], v[34:35], 1.0 op_sel_hi:[1,0]
	v_rcp_f32_e32 v32, v32
	v_rcp_f32_e32 v33, v33
	v_rcp_f32_e32 v34, v34
	v_rcp_f32_e32 v35, v35
	v_lshl_add_u64 v[36:37], v[36:37], 0, v[124:125]
	v_pk_mul_f32 v[28:29], v[28:29], v[32:33]
	v_mul_f32_e32 v32, 0xbfb8aa3b, v24
	v_pk_mul_f32 v[30:31], v[30:31], v[34:35]
	v_mul_f32_e32 v33, 0xbfb8aa3b, v25
	v_mul_f32_e32 v34, 0xbfb8aa3b, v26
	v_mul_f32_e32 v35, 0xbfb8aa3b, v27
	v_exp_f32_e32 v32, v32
	v_exp_f32_e32 v34, v34
	v_exp_f32_e32 v35, v35
	v_exp_f32_e32 v33, v33
	v_pk_mul_f32 v[22:23], v[22:23], v[30:31]
	v_pk_mul_f32 v[20:21], v[20:21], v[28:29]
	v_pk_add_f32 v[28:29], v[34:35], 1.0 op_sel_hi:[1,0]
	v_pk_add_f32 v[30:31], v[32:33], 1.0 op_sel_hi:[1,0]
	v_rcp_f32_e32 v28, v28
	v_rcp_f32_e32 v30, v30
	v_rcp_f32_e32 v31, v31
	v_rcp_f32_e32 v29, v29
	v_pk_fma_f32 v[14:15], v[14:15], v[162:163], v[142:143] op_sel_hi:[1,0,1]
	v_pk_fma_f32 v[12:13], v[12:13], v[162:163], v[140:141] op_sel_hi:[1,0,1]
	v_pk_mul_f32 v[24:25], v[24:25], v[30:31]
	v_pk_mul_f32 v[26:27], v[26:27], v[28:29]
	v_pk_fma_f32 v[10:11], v[10:11], v[162:163], v[134:135] op_sel_hi:[1,0,1]
	v_pk_mul_f32 v[26:27], v[18:19], v[26:27]
	v_pk_mul_f32 v[18:19], v[16:17], v[24:25]
	v_cvt_pk_bf16_f32 v16, v20, v21
	v_cvt_pk_bf16_f32 v17, v22, v23
	v_pk_fma_f32 v[8:9], v[8:9], v[162:163], v[132:133] op_sel_hi:[1,0,1]
	v_cvt_pk_bf16_f32 v18, v18, v19
	v_cvt_pk_bf16_f32 v19, v26, v27
	global_store_dwordx4 v[36:37], v[16:19], off
	v_pk_fma_f32 v[4:5], v[4:5], v[162:163], v[136:137] op_sel_hi:[1,0,1]
	v_pk_fma_f32 v[6:7], v[6:7], v[162:163], v[138:139] op_sel_hi:[1,0,1]
	v_mul_f32_e32 v16, 0xbfb8aa3b, v12
	v_mul_f32_e32 v17, 0xbfb8aa3b, v13
	v_mul_f32_e32 v18, 0xbfb8aa3b, v14
	v_mul_f32_e32 v19, 0xbfb8aa3b, v15
	v_exp_f32_e32 v16, v16
	v_exp_f32_e32 v17, v17
	v_exp_f32_e32 v18, v18
	v_exp_f32_e32 v19, v19
	v_add_u32_e32 v20, 0xb0, v160
	v_pk_add_f32 v[16:17], v[16:17], 1.0 op_sel_hi:[1,0]
	v_mad_i64_i32 v[20:21], s[4:5], v20, s55, v[164:165]
	v_pk_add_f32 v[18:19], v[18:19], 1.0 op_sel_hi:[1,0]
	v_rcp_f32_e32 v16, v16
	v_rcp_f32_e32 v17, v17
	v_rcp_f32_e32 v18, v18
	v_rcp_f32_e32 v19, v19
	v_pk_fma_f32 v[0:1], v[0:1], v[162:163], v[128:129] op_sel_hi:[1,0,1]
	v_pk_mul_f32 v[12:13], v[12:13], v[16:17]
	v_mul_f32_e32 v16, 0xbfb8aa3b, v8
	v_pk_mul_f32 v[14:15], v[14:15], v[18:19]
	v_mul_f32_e32 v17, 0xbfb8aa3b, v9
	v_mul_f32_e32 v18, 0xbfb8aa3b, v10
	v_mul_f32_e32 v19, 0xbfb8aa3b, v11
	v_exp_f32_e32 v16, v16
	v_exp_f32_e32 v18, v18
	v_exp_f32_e32 v19, v19
	v_exp_f32_e32 v17, v17
	v_pk_mul_f32 v[6:7], v[6:7], v[14:15]
	v_pk_mul_f32 v[4:5], v[4:5], v[12:13]
	v_pk_add_f32 v[12:13], v[18:19], 1.0 op_sel_hi:[1,0]
	v_pk_add_f32 v[14:15], v[16:17], 1.0 op_sel_hi:[1,0]
	v_rcp_f32_e32 v12, v12
	v_rcp_f32_e32 v14, v14
	v_rcp_f32_e32 v15, v15
	v_rcp_f32_e32 v13, v13
	v_pk_fma_f32 v[2:3], v[2:3], v[162:163], v[130:131] op_sel_hi:[1,0,1]
	v_lshl_add_u64 v[20:21], v[20:21], 0, v[124:125]
	v_pk_mul_f32 v[8:9], v[8:9], v[14:15]
	v_pk_mul_f32 v[10:11], v[10:11], v[12:13]
	s_andn2_b64 vcc, exec, s[0:1]
	v_pk_mul_f32 v[10:11], v[2:3], v[10:11]
	v_pk_mul_f32 v[2:3], v[0:1], v[8:9]
	s_mov_b64 s[0:1], -1
	v_cvt_pk_bf16_f32 v0, v4, v5
	v_cvt_pk_bf16_f32 v1, v6, v7
	v_cvt_pk_bf16_f32 v2, v2, v3
	v_cvt_pk_bf16_f32 v3, v10, v11
	global_store_dwordx4 v[20:21], v[0:3], off
	s_cbranch_vccnz .LBB0_1381
; #define PG8_BAR __builtin_amdgcn_s_barrier()
; template <class Epi, class Sched, bool ALIGN_EPI = false, bool SP2 = false>
; __device__ __forceinline__ void gemm_phase(PG8_LAS unsigned char* lds, const Gemm g, const Sched& S, const Epi& E, const int wid) {
;     ...
;         if constexpr (ALIGN_EPI) { if (wr == 0) PG8_BAR; }
;         E(acc, cur, wr, wc, fr, fq);
;         if (!has_next) break;
; #pragma unroll
;         for (int a = 0; a < 2; ++a)
; #pragma unroll
;             for (int b = 0; b < 2; ++b)
; #pragma unroll
;                 for (int m = 0; m < 4; ++m)
; #pragma unroll
;                     for (int n = 0; n < 2; ++n) acc[a][b][m][n] = (f32x4){0.f, 0.f, 0.f, 0.f};
;         cur = nxt; cA = nA; cB = nB; ++ui;
;         if constexpr (ALIGN_EPI) { if (wr == 1) PG8_BAR; }
;     }
	s_andn2_b64 vcc, exec, s[12:13]
	s_cbranch_vccnz .LBB0_1380
	s_barrier
	s_branch .LBB0_1380

; __device__ __forceinline__ unsigned cvt_pk_bf16(float lo, float hi) { unsigned r; asm volatile("v_cvt_pk_bf16_f32 %0, %1, %2" : "=v"(r) : "v"(lo), "v"(hi)); return r; }
;     __device__ __forceinline__ void operator()(const f32x4 (&acc)[2][2][4][2], const Unit& u, int wr, int wc, int fr_, int fq_) const {
;     ...
;         for (int ai = 0; ai < 2; ++ai)
; #pragma unroll
;         for (int mh = 0; mh < 2; ++mh) {
;             f32x4 bs[2][2][2];
; #pragma unroll
;             for (int m = 0; m < 2; ++m) { const size_t off = (size_t)(row0 + ai * HALF + (2 * mh + m) * 16) * ldc + col0;
; #pragma unroll
;                 for (int bj = 0; bj < 2; ++bj)
; #pragma unroll
;                     for (int n = 0; n < 2; ++n) bs[m][bj][n] = *(const f32x4*)(base + off + bj * HALF + n * 16); }
;             asm volatile("" ::: "memory");
; #pragma unroll
;             for (int m = 0; m < 2; ++m) { const int row = row0 + ai * HALF + (2 * mh + m) * 16; const size_t off = (size_t)row * ldc + col0; float ss = 0.f;
; #pragma unroll
;                 for (int bj = 0; bj < 2; ++bj)
; #pragma unroll
;                     for (int n = 0; n < 2; ++n) { const f32x4 o = bs[m][bj][n] + gv[bj][n] * acc[ai][bj][2 * mh + m][n]; *(f32x4*)(out + off + bj * HALF + n * 16) = o;
;                         if constexpr (EMIT) { ss += (o[0] * o[0] + o[1] * o[1]) + (o[2] * o[2] + o[3] * o[3]); const f32x4 y = o * gm[bj][n];
;                             typedef unsigned u32x2_t __attribute__((ext_vector_type(2))); u32x2_t w; w.x = cvt_pk_bf16(y[0], y[1]); w.y = cvt_pk_bf16(y[2], y[3]); *(u32x2_t*)(A2 + off + bj * HALF + n * 16) = w; } }
;                 if constexpr (EMIT) { ss += __shfl_xor(ss, 16); ss += __shfl_xor(ss, 32); if (fq == 0) atomicAdd(ssq + row, (unsigned long long)(ss * 16777216.0f)); } }
;             asm volatile("" ::: "memory");
;         }
.LBB0_1465:
	v_mbcnt_lo_u32_b32 v158, -1, 0
	v_mbcnt_hi_u32_b32 v158, -1, v158
	s_lshl_b32 s26, s54, 8
	s_lshl_b32 s27, s55, 8
	v_ashrrev_i32_e32 v128, 2, v158
	s_add_i32 s26, s26, s45
	s_or_b32 s27, s27, s46
	v_and_b32_e32 v128, -4, v128
	v_add_u32_e32 v128, s27, v128
	v_and_or_b32 v198, v158, 15, s26
	v_ashrrev_i32_e32 v129, 31, v128
	v_or_b32_e32 v182, 16, v198
	v_lshlrev_b64 v[156:157], 2, v[128:129]
	v_ashrrev_i32_e32 v199, 31, v198
	v_ashrrev_i32_e32 v183, 31, v182
	v_lshl_add_u64 v[158:159], s[6:7], 0, v[156:157]
	v_lshlrev_b64 v[160:161], 13, v[198:199]
	v_lshlrev_b64 v[200:201], 13, v[182:183]
	v_lshl_add_u64 v[128:129], s[12:13], 0, v[156:157]
	v_lshl_add_u64 v[178:179], v[158:159], 0, v[160:161]
	v_lshl_add_u64 v[194:195], v[158:159], 0, v[200:201]
	global_load_dwordx4 v[140:143], v[128:129], off
	global_load_dwordx4 v[136:139], v[128:129], off offset:64
	global_load_dwordx4 v[132:135], v[128:129], off offset:512
	s_nop 0
	global_load_dwordx4 v[128:131], v[128:129], off offset:576
	s_nop 0
	global_load_dwordx4 v[166:169], v[178:179], off
	global_load_dwordx4 v[170:173], v[178:179], off offset:64
	global_load_dwordx4 v[174:177], v[178:179], off offset:512
	s_nop 0
	global_load_dwordx4 v[178:181], v[178:179], off offset:576
	s_nop 0
	global_load_dwordx4 v[182:185], v[194:195], off
	global_load_dwordx4 v[186:189], v[194:195], off offset:64
	global_load_dwordx4 v[190:193], v[194:195], off offset:512
	s_nop 0
	global_load_dwordx4 v[194:197], v[194:195], off offset:576
	v_lshl_add_u64 v[204:205], s[6:7], 0, v[160:161]
	v_or_b32_e32 v202, 32, v198
	v_lshl_add_u64 v[204:205], v[204:205], 0, v[156:157]
	v_lshl_add_u64 v[200:201], s[6:7], 0, v[200:201]
	v_ashrrev_i32_e32 v203, 31, v202
	v_lshl_add_u64 v[200:201], v[200:201], 0, v[156:157]
	v_lshlrev_b64 v[202:203], 13, v[202:203]
	v_lshl_add_u64 v[206:207], v[158:159], 0, v[202:203]
	s_and_b64 vcc, exec, s[0:1]
	s_mov_b64 s[0:1], -1
	s_waitcnt vmcnt(0) lgkmcnt(0)
	v_pk_fma_f32 v[126:127], v[126:127], v[142:143], v[168:169]
	v_pk_fma_f32 v[124:125], v[124:125], v[140:141], v[166:167]
	v_pk_fma_f32 v[108:109], v[108:109], v[132:133], v[174:175]
	v_pk_fma_f32 v[122:123], v[122:123], v[138:139], v[172:173]
	v_pk_fma_f32 v[120:121], v[120:121], v[136:137], v[170:171]
	v_pk_fma_f32 v[110:111], v[110:111], v[134:135], v[176:177]
	v_pk_fma_f32 v[106:107], v[106:107], v[130:131], v[180:181]
	v_pk_fma_f32 v[104:105], v[104:105], v[128:129], v[178:179]
	v_pk_fma_f32 v[118:119], v[118:119], v[142:143], v[184:185]
	v_pk_fma_f32 v[116:117], v[116:117], v[140:141], v[182:183]
	v_pk_fma_f32 v[114:115], v[114:115], v[138:139], v[188:189]
	v_pk_fma_f32 v[112:113], v[112:113], v[136:137], v[186:187]
	v_pk_fma_f32 v[102:103], v[102:103], v[134:135], v[192:193]
	v_pk_fma_f32 v[100:101], v[100:101], v[132:133], v[190:191]
	v_pk_fma_f32 v[98:99], v[98:99], v[130:131], v[196:197]
	v_pk_fma_f32 v[96:97], v[96:97], v[128:129], v[194:195]
	global_store_dwordx4 v[204:205], v[124:127], off
	global_store_dwordx4 v[204:205], v[120:123], off offset:64
	global_store_dwordx4 v[204:205], v[108:111], off offset:512
	global_store_dwordx4 v[204:205], v[104:107], off offset:576
	global_store_dwordx4 v[200:201], v[116:119], off
	global_store_dwordx4 v[200:201], v[112:115], off offset:64
	global_store_dwordx4 v[200:201], v[100:103], off offset:512
	global_store_dwordx4 v[200:201], v[96:99], off offset:576
	v_or_b32_e32 v108, 48, v198
	v_ashrrev_i32_e32 v109, 31, v108
	v_lshlrev_b64 v[166:167], 13, v[108:109]
	global_load_dwordx4 v[96:99], v[206:207], off
	global_load_dwordx4 v[100:103], v[206:207], off offset:64
	v_lshl_add_u64 v[124:125], v[158:159], 0, v[166:167]
	global_load_dwordx4 v[104:107], v[206:207], off offset:512
	global_load_dwordx4 v[108:111], v[206:207], off offset:576
	global_load_dwordx4 v[112:115], v[124:125], off
	global_load_dwordx4 v[116:119], v[124:125], off offset:64
	global_load_dwordx4 v[120:123], v[124:125], off offset:512
	s_nop 0
	global_load_dwordx4 v[124:127], v[124:125], off offset:576
	v_lshl_add_u64 v[170:171], s[6:7], 0, v[202:203]
	v_lshl_add_u64 v[166:167], s[6:7], 0, v[166:167]
	v_lshl_add_u64 v[170:171], v[170:171], 0, v[156:157]
	v_lshl_add_u64 v[168:169], v[160:161], 0, s[18:19]
	v_lshl_add_u64 v[166:167], v[166:167], 0, v[156:157]
	v_lshl_add_u64 v[172:173], v[158:159], 0, v[168:169]
	s_waitcnt vmcnt(0) lgkmcnt(0)
; __device__ __forceinline__ unsigned cvt_pk_bf16(float lo, float hi) { unsigned r; asm volatile("v_cvt_pk_bf16_f32 %0, %1, %2" : "=v"(r) : "v"(lo), "v"(hi)); return r; }
;     __device__ __forceinline__ void operator()(const f32x4 (&acc)[2][2][4][2], const Unit& u, int wr, int wc, int fr_, int fq_) const {
;     ...
;         for (int ai = 0; ai < 2; ++ai)
; #pragma unroll
;         for (int mh = 0; mh < 2; ++mh) {
;             f32x4 bs[2][2][2];
; #pragma unroll
;             for (int m = 0; m < 2; ++m) { const size_t off = (size_t)(row0 + ai * HALF + (2 * mh + m) * 16) * ldc + col0;
; #pragma unroll
;                 for (int bj = 0; bj < 2; ++bj)
; #pragma unroll
;                     for (int n = 0; n < 2; ++n) bs[m][bj][n] = *(const f32x4*)(base + off + bj * HALF + n * 16); }
;             asm volatile("" ::: "memory");
; #pragma unroll
;             for (int m = 0; m < 2; ++m) { const int row = row0 + ai * HALF + (2 * mh + m) * 16; const size_t off = (size_t)row * ldc + col0; float ss = 0.f;
; #pragma unroll
;                 for (int bj = 0; bj < 2; ++bj)
; #pragma unroll
;                     for (int n = 0; n < 2; ++n) { const f32x4 o = bs[m][bj][n] + gv[bj][n] * acc[ai][bj][2 * mh + m][n]; *(f32x4*)(out + off + bj * HALF + n * 16) = o;
;                         if constexpr (EMIT) { ss += (o[0] * o[0] + o[1] * o[1]) + (o[2] * o[2] + o[3] * o[3]); const f32x4 y = o * gm[bj][n];
;                             typedef unsigned u32x2_t __attribute__((ext_vector_type(2))); u32x2_t w; w.x = cvt_pk_bf16(y[0], y[1]); w.y = cvt_pk_bf16(y[2], y[3]); *(u32x2_t*)(A2 + off + bj * HALF + n * 16) = w; } }
;                 if constexpr (EMIT) { ss += __shfl_xor(ss, 16); ss += __shfl_xor(ss, 32); if (fq == 0) atomicAdd(ssq + row, (unsigned long long)(ss * 16777216.0f)); } }
;             asm volatile("" ::: "memory");
;         }
	v_pk_fma_f32 v[94:95], v[94:95], v[142:143], v[98:99]
	v_pk_fma_f32 v[92:93], v[92:93], v[140:141], v[96:97]
	v_pk_fma_f32 v[90:91], v[90:91], v[138:139], v[102:103]
	v_pk_fma_f32 v[88:89], v[88:89], v[136:137], v[100:101]
	v_pk_fma_f32 v[78:79], v[78:79], v[134:135], v[106:107]
	v_pk_fma_f32 v[76:77], v[76:77], v[132:133], v[104:105]
	v_pk_fma_f32 v[74:75], v[74:75], v[130:131], v[110:111]
	v_pk_fma_f32 v[72:73], v[72:73], v[128:129], v[108:109]
	v_pk_fma_f32 v[86:87], v[86:87], v[142:143], v[114:115]
	v_pk_fma_f32 v[84:85], v[84:85], v[140:141], v[112:113]
	v_pk_fma_f32 v[82:83], v[82:83], v[138:139], v[118:119]
	v_pk_fma_f32 v[80:81], v[80:81], v[136:137], v[116:117]
	v_pk_fma_f32 v[70:71], v[70:71], v[134:135], v[122:123]
	v_pk_fma_f32 v[68:69], v[68:69], v[132:133], v[120:121]
	v_pk_fma_f32 v[66:67], v[66:67], v[130:131], v[126:127]
	v_pk_fma_f32 v[64:65], v[64:65], v[128:129], v[124:125]
	global_store_dwordx4 v[170:171], v[92:95], off
	global_store_dwordx4 v[170:171], v[88:91], off offset:64
	global_store_dwordx4 v[170:171], v[76:79], off offset:512
	global_store_dwordx4 v[170:171], v[72:75], off offset:576
	global_store_dwordx4 v[166:167], v[84:87], off
	global_store_dwordx4 v[166:167], v[80:83], off offset:64
	global_store_dwordx4 v[166:167], v[68:71], off offset:512
	global_store_dwordx4 v[166:167], v[64:67], off offset:576
	v_lshl_add_u64 v[96:97], v[160:161], 0, s[20:21]
	v_lshl_add_u64 v[92:93], v[158:159], 0, v[96:97]
	global_load_dwordx4 v[64:67], v[172:173], off
	global_load_dwordx4 v[68:71], v[172:173], off offset:64
	global_load_dwordx4 v[72:75], v[172:173], off offset:512
	global_load_dwordx4 v[76:79], v[172:173], off offset:576
	global_load_dwordx4 v[80:83], v[92:93], off
	global_load_dwordx4 v[84:87], v[92:93], off offset:64
	global_load_dwordx4 v[88:91], v[92:93], off offset:512
	s_nop 0
	global_load_dwordx4 v[92:95], v[92:93], off offset:576
	v_lshl_add_u64 v[100:101], s[6:7], 0, v[168:169]
	v_lshl_add_u64 v[96:97], s[6:7], 0, v[96:97]
	v_lshl_add_u64 v[100:101], v[100:101], 0, v[156:157]
	v_lshl_add_u64 v[98:99], v[160:161], 0, s[22:23]
	v_lshl_add_u64 v[96:97], v[96:97], 0, v[156:157]
	v_lshl_add_u64 v[102:103], v[158:159], 0, v[98:99]
	s_waitcnt vmcnt(0) lgkmcnt(0)
	v_pk_fma_f32 v[62:63], v[62:63], v[142:143], v[66:67]
	v_pk_fma_f32 v[60:61], v[60:61], v[140:141], v[64:65]
	v_pk_fma_f32 v[58:59], v[58:59], v[138:139], v[70:71]
	v_pk_fma_f32 v[56:57], v[56:57], v[136:137], v[68:69]
	v_pk_fma_f32 v[46:47], v[46:47], v[134:135], v[74:75]
	v_pk_fma_f32 v[44:45], v[44:45], v[132:133], v[72:73]
	v_pk_fma_f32 v[42:43], v[42:43], v[130:131], v[78:79]
	v_pk_fma_f32 v[40:41], v[40:41], v[128:129], v[76:77]
	v_pk_fma_f32 v[54:55], v[54:55], v[142:143], v[82:83]
	v_pk_fma_f32 v[52:53], v[52:53], v[140:141], v[80:81]
	v_pk_fma_f32 v[50:51], v[50:51], v[138:139], v[86:87]
	v_pk_fma_f32 v[48:49], v[48:49], v[136:137], v[84:85]
	v_pk_fma_f32 v[38:39], v[38:39], v[134:135], v[90:91]
	v_pk_fma_f32 v[36:37], v[36:37], v[132:133], v[88:89]
	v_pk_fma_f32 v[34:35], v[34:35], v[130:131], v[94:95]
	v_pk_fma_f32 v[32:33], v[32:33], v[128:129], v[92:93]
	global_store_dwordx4 v[100:101], v[60:63], off
	global_store_dwordx4 v[100:101], v[56:59], off offset:64
	global_store_dwordx4 v[100:101], v[44:47], off offset:512
	global_store_dwordx4 v[100:101], v[40:43], off offset:576
	global_store_dwordx4 v[96:97], v[52:55], off
	global_store_dwordx4 v[96:97], v[48:51], off offset:64
	global_store_dwordx4 v[96:97], v[36:39], off offset:512
	global_store_dwordx4 v[96:97], v[32:35], off offset:576
	v_lshl_add_u64 v[64:65], v[160:161], 0, s[8:9]
	v_lshl_add_u64 v[66:67], v[158:159], 0, v[64:65]
	global_load_dwordx4 v[32:35], v[102:103], off
	global_load_dwordx4 v[36:39], v[102:103], off offset:64
	global_load_dwordx4 v[40:43], v[102:103], off offset:512
	global_load_dwordx4 v[44:47], v[102:103], off offset:576
	global_load_dwordx4 v[48:51], v[66:67], off
	global_load_dwordx4 v[52:55], v[66:67], off offset:64
	global_load_dwordx4 v[56:59], v[66:67], off offset:512
	global_load_dwordx4 v[60:63], v[66:67], off offset:576
	v_lshl_add_u64 v[66:67], s[6:7], 0, v[98:99]
	v_lshl_add_u64 v[64:65], s[6:7], 0, v[64:65]
	v_lshl_add_u64 v[66:67], v[66:67], 0, v[156:157]
	v_lshl_add_u64 v[64:65], v[64:65], 0, v[156:157]
	s_waitcnt vmcnt(0) lgkmcnt(0)
	v_pk_fma_f32 v[30:31], v[30:31], v[142:143], v[34:35]
	v_pk_fma_f32 v[28:29], v[28:29], v[140:141], v[32:33]
	v_pk_fma_f32 v[26:27], v[26:27], v[138:139], v[38:39]
	v_pk_fma_f32 v[24:25], v[24:25], v[136:137], v[36:37]
	v_pk_fma_f32 v[14:15], v[14:15], v[134:135], v[42:43]
	v_pk_fma_f32 v[12:13], v[12:13], v[132:133], v[40:41]
	v_pk_fma_f32 v[10:11], v[10:11], v[130:131], v[46:47]
	v_pk_fma_f32 v[8:9], v[8:9], v[128:129], v[44:45]
	v_pk_fma_f32 v[22:23], v[22:23], v[142:143], v[50:51]
	v_pk_fma_f32 v[20:21], v[20:21], v[140:141], v[48:49]
	v_pk_fma_f32 v[18:19], v[18:19], v[138:139], v[54:55]
	v_pk_fma_f32 v[16:17], v[16:17], v[136:137], v[52:53]
	v_pk_fma_f32 v[6:7], v[6:7], v[134:135], v[58:59]
	v_pk_fma_f32 v[4:5], v[4:5], v[132:133], v[56:57]
	v_pk_fma_f32 v[2:3], v[2:3], v[130:131], v[62:63]
	v_pk_fma_f32 v[0:1], v[0:1], v[128:129], v[60:61]
	global_store_dwordx4 v[66:67], v[28:31], off
	global_store_dwordx4 v[66:67], v[24:27], off offset:64
	global_store_dwordx4 v[66:67], v[12:15], off offset:512
	global_store_dwordx4 v[66:67], v[8:11], off offset:576
	global_store_dwordx4 v[64:65], v[20:23], off
	global_store_dwordx4 v[64:65], v[16:19], off offset:64
	global_store_dwordx4 v[64:65], v[4:7], off offset:512
	global_store_dwordx4 v[64:65], v[0:3], off offset:576
	s_cbranch_vccnz .LBB0_1450
	s_andn2_b64 vcc, exec, s[10:11]
	s_cbranch_vccnz .LBB0_1449
	s_barrier
	s_branch .LBB0_1449
